# GEMM K-loops: LDS fragment base addresses precomputed outside the loop
# speedup vs baseline: 1.0085x; 1.0017x over previous
; #define PG8_STAGE(bufoff, gbase, voff) do { _Pragma("unroll") for (int _i = 0; _i < 2; ++_i) \
;         __builtin_amdgcn_global_load_lds((const unsigned*)((const char*)(gbase) + (voff)[_i]), (PG8_LAS unsigned*)(lds + (bufoff) + ldsw + _i * 8192), 16, 0, 0); } while (0)
; #define PG8_LDA(dst, b, h) do { _Pragma("unroll") for (int m = 0; m < 4; ++m) _Pragma("unroll") for (int k = 0; k < 2; ++k) dst[m][k] = *(const PG8_LAS bf16x8*)(lds + PG8_SA(b, h) + aoff + m * 2048 + k * 1024); } while (0)
; #define PG8_LDB(dst, b, h) do { _Pragma("unroll") for (int n = 0; n < 2; ++n) _Pragma("unroll") for (int k = 0; k < 2; ++k) dst[n][k] = *(const PG8_LAS bf16x8*)(lds + PG8_SB(b, h) + boff + n * 2048 + k * 1024); } while (0)
; #define PG8_WAIT_L(n) asm volatile("s_waitcnt lgkmcnt(" #n ")" ::: "memory")
; #define PG8_BAR __builtin_amdgcn_s_barrier()
; #define PG8_SCHED __builtin_amdgcn_sched_barrier(0)
;     __device__ bool next(int i, pg8::Unit& u) const { if (i != 0 || !valid) return false; u.pm = pm; u.pn = pn; return true; }
; template <class Epi, class Sched, bool STAMP = false>
; __device__ __forceinline__ void gemm_phase(PG8_LAS unsigned char* lds, const Gemm g, const Sched& S, const Epi& E, unsigned long long* stamps) {
;     ...
;         const bool has_next = S.next(ui + 1, nxt);
;         const char* nA = has_next ? (const char*)g.A + (size_t)nxt.pm * tstep : cA; const char* nB = has_next ? (const char*)g.Bt + (size_t)nxt.pn * tstep : cB;
;         for (int t = 0; t < nt; t += 2) {
;             const bool last = (t == nt - 2);
;             const char* a1 = cA + (size_t)(t + 1) * kstep;
;             const char* a2 = last ? nA : cA + (size_t)(t + 2) * kstep; const char* b2 = last ? nB : cB + (size_t)(t + 2) * kstep;
;             const char* a3 = a2 + kstep; const char* b3 = b2 + kstep;
;             if (last && has_next) S.a_ready(nxt);
;             PG8_LDB(B0, 0, 0); PG8_SCHED; PG8_LDA(At, 0, 0); PG8_STAGE(PG8_SA(1, 1), a1 + hstep, voffA);
;             PG8_WAIT_L(8); PG8_BAR; PG8_WAIT_L(0); PG8_MMA(0, 0, At, B0); PG8_BAR; PG8_SCHED;
;     ...
; #pragma unroll
;         for (int a = 0; a < 2; ++a)
; #pragma unroll
;             for (int b = 0; b < 2; ++b)
; #pragma unroll
;                 for (int m = 0; m < 4; ++m)
; #pragma unroll
;                     for (int n = 0; n < 2; ++n) acc[a][b][m][n] = (f32x4){0.f, 0.f, 0.f, 0.f};
;         cur = nxt; cA = nA; cB = nB; ++ui;
.LBB0_43:
	s_ashr_i32 s7, s6, 31
	v_cmp_lt_i64_e32 vcc, s[12:13], v[132:133]
	s_lshl_b64 s[12:13], s[6:7], 19
	s_add_u32 s12, s37, s12
	s_addc_u32 s13, s40, s13
	s_and_b64 s[14:15], vcc, exec
	s_cselect_b32 s7, s13, s25
	s_cselect_b32 s57, s12, s24
	s_ashr_i32 s5, s4, 31
	s_lshl_b64 s[14:15], s[4:5], 19
	s_add_u32 s20, s41, s14
	s_addc_u32 s21, s42, s15
	s_and_b64 s[14:15], vcc, exec
	s_cselect_b32 s5, s21, s27
	s_cselect_b32 s58, s20, s26
	s_add_u32 s24, s24, 0x40080
	s_addc_u32 s25, s25, 0
	s_add_u32 s59, s26, 0x100
	v_mov_b32_e32 v0, 0
	s_addc_u32 s60, s27, 0
	s_mov_b32 s61, -2
	v_mov_b32_e32 v1, v0
	v_mov_b32_e32 v2, v0
	v_mov_b32_e32 v3, v0
	v_mov_b32_e32 v4, v0
	v_mov_b32_e32 v5, v0
	v_mov_b32_e32 v6, v0
	v_mov_b32_e32 v7, v0
	v_mov_b32_e32 v16, v0
	v_mov_b32_e32 v17, v0
	v_mov_b32_e32 v18, v0
	v_mov_b32_e32 v19, v0
	v_mov_b32_e32 v20, v0
	v_mov_b32_e32 v21, v0
	v_mov_b32_e32 v22, v0
	v_mov_b32_e32 v23, v0
	v_mov_b32_e32 v32, v0
	v_mov_b32_e32 v33, v0
	v_mov_b32_e32 v34, v0
	v_mov_b32_e32 v35, v0
	v_mov_b32_e32 v36, v0
	v_mov_b32_e32 v37, v0
	v_mov_b32_e32 v38, v0
	v_mov_b32_e32 v39, v0
	v_mov_b32_e32 v48, v0
	v_mov_b32_e32 v49, v0
	v_mov_b32_e32 v50, v0
	v_mov_b32_e32 v51, v0
	v_mov_b32_e32 v52, v0
	v_mov_b32_e32 v53, v0
	v_mov_b32_e32 v54, v0
	v_mov_b32_e32 v55, v0
	v_mov_b32_e32 v8, v0
	v_mov_b32_e32 v9, v0
	v_mov_b32_e32 v10, v0
	v_mov_b32_e32 v11, v0
	v_mov_b32_e32 v12, v0
	v_mov_b32_e32 v13, v0
	v_mov_b32_e32 v14, v0
	v_mov_b32_e32 v15, v0
	v_mov_b32_e32 v24, v0
	v_mov_b32_e32 v25, v0
	v_mov_b32_e32 v26, v0
	v_mov_b32_e32 v27, v0
	v_mov_b32_e32 v28, v0
	v_mov_b32_e32 v29, v0
	v_mov_b32_e32 v30, v0
	v_mov_b32_e32 v31, v0
	v_mov_b32_e32 v40, v0
	v_mov_b32_e32 v41, v0
	v_mov_b32_e32 v42, v0
	v_mov_b32_e32 v43, v0
	v_mov_b32_e32 v44, v0
	v_mov_b32_e32 v45, v0
	v_mov_b32_e32 v46, v0
	v_mov_b32_e32 v47, v0
	v_mov_b32_e32 v56, v0
	v_mov_b32_e32 v57, v0
	v_mov_b32_e32 v58, v0
	v_mov_b32_e32 v59, v0
	v_mov_b32_e32 v60, v0
	v_mov_b32_e32 v61, v0
	v_mov_b32_e32 v62, v0
	v_mov_b32_e32 v63, v0
	v_mov_b32_e32 v64, v0
	v_mov_b32_e32 v65, v0
	v_mov_b32_e32 v66, v0
	v_mov_b32_e32 v67, v0
	v_mov_b32_e32 v68, v0
	v_mov_b32_e32 v69, v0
	v_mov_b32_e32 v70, v0
	v_mov_b32_e32 v71, v0
	v_mov_b32_e32 v80, v0
	v_mov_b32_e32 v81, v0
	v_mov_b32_e32 v82, v0
	v_mov_b32_e32 v83, v0
	v_mov_b32_e32 v84, v0
	v_mov_b32_e32 v85, v0
	v_mov_b32_e32 v86, v0
	v_mov_b32_e32 v87, v0
	v_mov_b32_e32 v96, v0
	v_mov_b32_e32 v97, v0
	v_mov_b32_e32 v98, v0
	v_mov_b32_e32 v99, v0
	v_mov_b32_e32 v100, v0
	v_mov_b32_e32 v101, v0
	v_mov_b32_e32 v102, v0
	v_mov_b32_e32 v103, v0
	v_mov_b32_e32 v112, v0
	v_mov_b32_e32 v113, v0
	v_mov_b32_e32 v114, v0
	v_mov_b32_e32 v115, v0
	v_mov_b32_e32 v116, v0
	v_mov_b32_e32 v117, v0
	v_mov_b32_e32 v118, v0
	v_mov_b32_e32 v119, v0
	v_mov_b32_e32 v72, v0
	v_mov_b32_e32 v73, v0
	v_mov_b32_e32 v74, v0
	v_mov_b32_e32 v75, v0
	v_mov_b32_e32 v76, v0
	v_mov_b32_e32 v77, v0
	v_mov_b32_e32 v78, v0
	v_mov_b32_e32 v79, v0
	v_mov_b32_e32 v88, v0
	v_mov_b32_e32 v89, v0
	v_mov_b32_e32 v90, v0
	v_mov_b32_e32 v91, v0
	v_mov_b32_e32 v92, v0
	v_mov_b32_e32 v93, v0
	v_mov_b32_e32 v94, v0
	v_mov_b32_e32 v95, v0
	v_mov_b32_e32 v104, v0
	v_mov_b32_e32 v105, v0
	v_mov_b32_e32 v106, v0
	v_mov_b32_e32 v107, v0
	v_mov_b32_e32 v108, v0
	v_mov_b32_e32 v109, v0
	v_mov_b32_e32 v110, v0
	v_mov_b32_e32 v111, v0
	v_mov_b32_e32 v120, v0
	v_mov_b32_e32 v121, v0
	v_mov_b32_e32 v122, v0
	v_mov_b32_e32 v123, v0
	v_mov_b32_e32 v124, v0
	v_mov_b32_e32 v125, v0
	v_mov_b32_e32 v126, v0
	v_mov_b32_e32 v127, v0
	v_add_u32_e32 v244, 0x80, v128
	v_add_u32_e32 v245, 0x80, v148
	v_add_u32_e32 v246, 0x80, v152
	v_add_u32_e32 v247, 0x80, v150
	v_add_u32_e32 v248, 0x10000, v166
	v_add_u32_e32 v249, 0x14000, v166
	v_add_u32_e32 v250, 0x18000, v166
	v_add_u32_e32 v251, 0x1c000, v166
.LBB0_44:
	s_add_u32 s14, s24, 0xfffc0080
	s_addc_u32 s15, s25, -1
	s_add_i32 s16, 0, 0x10000
	ds_read_b128 v[158:161], v248
	ds_read_b128 v[162:165], v248 offset:1024
	ds_read_b128 v[170:173], v248 offset:2048
	ds_read_b128 v[174:177], v248 offset:3072
	s_cmp_eq_u32 s61, 12
	s_cselect_b32 s31, s7, s15
	s_cselect_b32 s30, s57, s14
	s_cselect_b32 s27, s5, s60
	s_cselect_b32 s26, s58, s59
	s_add_i32 m0, s23, 0xc000
	ds_read_b128 v[178:181], v168
	ds_read_b128 v[192:195], v168 offset:1024
	ds_read_b128 v[196:199], v168 offset:2048
	ds_read_b128 v[200:203], v168 offset:3072
	ds_read_b128 v[204:207], v168 offset:4096
	ds_read_b128 v[208:211], v168 offset:5120
	ds_read_b128 v[212:215], v168 offset:6144
	ds_read_b128 v[216:219], v168 offset:7168
	global_load_lds_dwordx4 v154, s[24:25]
	s_add_i32 m0, s23, 0xe000
	s_nop 0
	global_load_lds_dwordx4 v156, s[24:25]
	s_waitcnt lgkmcnt(8)
	s_barrier
	s_waitcnt lgkmcnt(0)
	v_mfma_f32_16x16x32_bf16 v[124:127], v[158:161], v[178:181], v[124:127]
	v_mfma_f32_16x16x32_bf16 v[120:123], v[170:173], v[178:181], v[120:123]
	v_mfma_f32_16x16x32_bf16 v[108:111], v[158:161], v[196:199], v[108:111]
	v_mfma_f32_16x16x32_bf16 v[104:107], v[170:173], v[196:199], v[104:107]
	v_mfma_f32_16x16x32_bf16 v[92:95], v[158:161], v[204:207], v[92:95]
	v_mfma_f32_16x16x32_bf16 v[88:91], v[170:173], v[204:207], v[88:91]
	v_mfma_f32_16x16x32_bf16 v[76:79], v[158:161], v[212:215], v[76:79]
	v_mfma_f32_16x16x32_bf16 v[72:75], v[170:173], v[212:215], v[72:75]
	v_mfma_f32_16x16x32_bf16 v[124:127], v[162:165], v[192:195], v[124:127]
	v_mfma_f32_16x16x32_bf16 v[120:123], v[174:177], v[192:195], v[120:123]
	v_mfma_f32_16x16x32_bf16 v[108:111], v[162:165], v[200:203], v[108:111]
	v_mfma_f32_16x16x32_bf16 v[104:107], v[174:177], v[200:203], v[104:107]
	v_mfma_f32_16x16x32_bf16 v[92:95], v[162:165], v[208:211], v[92:95]
	v_mfma_f32_16x16x32_bf16 v[88:91], v[174:177], v[208:211], v[88:91]
	v_mfma_f32_16x16x32_bf16 v[76:79], v[162:165], v[216:219], v[76:79]
	v_mfma_f32_16x16x32_bf16 v[72:75], v[174:177], v[216:219], v[72:75]
	s_barrier
; #define PG8_STAGE(bufoff, gbase, voff) do { _Pragma("unroll") for (int _i = 0; _i < 2; ++_i) \
;         __builtin_amdgcn_global_load_lds((const unsigned*)((const char*)(gbase) + (voff)[_i]), (PG8_LAS unsigned*)(lds + (bufoff) + ldsw + _i * 8192), 16, 0, 0); } while (0)
; #define PG8_LDA(dst, b, h) do { _Pragma("unroll") for (int m = 0; m < 4; ++m) _Pragma("unroll") for (int k = 0; k < 2; ++k) dst[m][k] = *(const PG8_LAS bf16x8*)(lds + PG8_SA(b, h) + aoff + m * 2048 + k * 1024); } while (0)
; #define PG8_LDB(dst, b, h) do { _Pragma("unroll") for (int n = 0; n < 2; ++n) _Pragma("unroll") for (int k = 0; k < 2; ++k) dst[n][k] = *(const PG8_LAS bf16x8*)(lds + PG8_SB(b, h) + boff + n * 2048 + k * 1024); } while (0)
; #define PG8_MMA(ai, bj, At, Bt) do { __builtin_amdgcn_s_setprio(1); _Pragma("unroll") for (int m = 0; m < 4; ++m) _Pragma("unroll") for (int n = 0; n < 2; ++n) _Pragma("unroll") for (int k = 0; k < 2; ++k) \
;         acc[ai][bj][m][n] = __builtin_amdgcn_mfma_f32_16x16x32_bf16(Bt[n][k], At[m][k], acc[ai][bj][m][n], 0, 0, 0); __builtin_amdgcn_s_setprio(0); } while (0)
; #define PG8_WAIT_V(n) asm volatile("s_waitcnt vmcnt(" #n ")" ::: "memory")
; #define PG8_WAIT_L(n) asm volatile("s_waitcnt lgkmcnt(" #n ")" ::: "memory")
; #define PG8_BAR __builtin_amdgcn_s_barrier()
; #define PG8_SCHED __builtin_amdgcn_sched_barrier(0)
; template <class Epi, class Sched, bool STAMP = false>
; __device__ __forceinline__ void gemm_phase(PG8_LAS unsigned char* lds, const Gemm g, const Sched& S, const Epi& E, unsigned long long* stamps) {
;     ...
;             PG8_LDB(B1, 0, 1); PG8_STAGE(PG8_SB(0, 0), b2, voffB);
;             PG8_BAR; PG8_WAIT_L(0); PG8_MMA(0, 1, At, B1); PG8_BAR;
;             PG8_LDA(At, 0, 1); PG8_STAGE(PG8_SA(0, 0), a2, voffA);
;             PG8_BAR; PG8_WAIT_L(0); PG8_MMA(1, 0, At, B0); PG8_BAR; PG8_SCHED;
;             PG8_STAGE(PG8_SB(0, 1), b2 + hstep, voffB);
;             PG8_WAIT_V(6); PG8_BAR; PG8_MMA(1, 1, At, B1); PG8_BAR;
;             PG8_LDB(B0, 1, 0); PG8_SCHED; PG8_LDA(At, 1, 0); PG8_STAGE(PG8_SA(0, 1), a2 + hstep, voffA);
;             PG8_WAIT_L(8); PG8_BAR; PG8_WAIT_L(0); PG8_MMA(0, 0, At, B0); PG8_BAR; PG8_SCHED;
	s_add_i32 s17, 0, 0x14000
	s_add_i32 s14, s16, s43
	s_mov_b32 m0, s14
	ds_read_b128 v[220:223], v249
	ds_read_b128 v[224:227], v249 offset:1024
	ds_read_b128 v[228:231], v249 offset:2048
	ds_read_b128 v[232:235], v249 offset:3072
	global_load_lds_dwordx4 v128, s[26:27]
	s_add_i32 m0, s14, 0x2000
	s_nop 0
	global_load_lds_dwordx4 v148, s[26:27]
	s_barrier
	s_waitcnt lgkmcnt(0)
	v_mfma_f32_16x16x32_bf16 v[116:119], v[220:223], v[178:181], v[116:119]
	v_mfma_f32_16x16x32_bf16 v[112:115], v[228:231], v[178:181], v[112:115]
	v_mfma_f32_16x16x32_bf16 v[100:103], v[220:223], v[196:199], v[100:103]
	v_mfma_f32_16x16x32_bf16 v[96:99], v[228:231], v[196:199], v[96:99]
	v_mfma_f32_16x16x32_bf16 v[84:87], v[220:223], v[204:207], v[84:87]
	v_mfma_f32_16x16x32_bf16 v[80:83], v[228:231], v[204:207], v[80:83]
	v_mfma_f32_16x16x32_bf16 v[68:71], v[220:223], v[212:215], v[68:71]
	v_mfma_f32_16x16x32_bf16 v[64:67], v[228:231], v[212:215], v[64:67]
	v_mfma_f32_16x16x32_bf16 v[116:119], v[224:227], v[192:195], v[116:119]
	v_mfma_f32_16x16x32_bf16 v[112:115], v[232:235], v[192:195], v[112:115]
	v_mfma_f32_16x16x32_bf16 v[100:103], v[224:227], v[200:203], v[100:103]
	v_mfma_f32_16x16x32_bf16 v[96:99], v[232:235], v[200:203], v[96:99]
	v_mfma_f32_16x16x32_bf16 v[84:87], v[224:227], v[208:211], v[84:87]
	v_mfma_f32_16x16x32_bf16 v[80:83], v[232:235], v[208:211], v[80:83]
	v_mfma_f32_16x16x32_bf16 v[68:71], v[224:227], v[216:219], v[68:71]
	v_mfma_f32_16x16x32_bf16 v[64:67], v[232:235], v[216:219], v[64:67]
	s_mov_b32 m0, s23
	s_barrier
	ds_read_b128 v[178:181], v168 offset:16384
	ds_read_b128 v[192:195], v168 offset:17408
	ds_read_b128 v[196:199], v168 offset:18432
	ds_read_b128 v[200:203], v168 offset:19456
	ds_read_b128 v[204:207], v168 offset:20480
	ds_read_b128 v[208:211], v168 offset:21504
	ds_read_b128 v[212:215], v168 offset:22528
	ds_read_b128 v[216:219], v168 offset:23552
	global_load_lds_dwordx4 v152, s[30:31]
	s_mov_b32 m0, s45
	s_nop 0
	global_load_lds_dwordx4 v150, s[30:31]
	s_barrier
	s_waitcnt lgkmcnt(0)
	v_mfma_f32_16x16x32_bf16 v[60:63], v[158:161], v[178:181], v[60:63]
	v_mfma_f32_16x16x32_bf16 v[56:59], v[170:173], v[178:181], v[56:59]
	v_mfma_f32_16x16x32_bf16 v[44:47], v[158:161], v[196:199], v[44:47]
	v_mfma_f32_16x16x32_bf16 v[40:43], v[170:173], v[196:199], v[40:43]
	v_mfma_f32_16x16x32_bf16 v[28:31], v[158:161], v[204:207], v[28:31]
	v_mfma_f32_16x16x32_bf16 v[24:27], v[170:173], v[204:207], v[24:27]
	v_mfma_f32_16x16x32_bf16 v[12:15], v[158:161], v[212:215], v[12:15]
	v_mfma_f32_16x16x32_bf16 v[8:11], v[170:173], v[212:215], v[8:11]
	v_mfma_f32_16x16x32_bf16 v[60:63], v[162:165], v[192:195], v[60:63]
	v_mfma_f32_16x16x32_bf16 v[56:59], v[174:177], v[192:195], v[56:59]
	v_mfma_f32_16x16x32_bf16 v[44:47], v[162:165], v[200:203], v[44:47]
	v_mfma_f32_16x16x32_bf16 v[40:43], v[174:177], v[200:203], v[40:43]
	v_mfma_f32_16x16x32_bf16 v[28:31], v[162:165], v[208:211], v[28:31]
	v_mfma_f32_16x16x32_bf16 v[24:27], v[174:177], v[208:211], v[24:27]
	v_mfma_f32_16x16x32_bf16 v[12:15], v[162:165], v[216:219], v[12:15]
	v_mfma_f32_16x16x32_bf16 v[8:11], v[174:177], v[216:219], v[8:11]
	s_barrier
	s_add_u32 s14, s26, 0x40000
	s_addc_u32 s15, s27, 0
	s_add_i32 s16, s17, s43
	s_mov_b32 m0, s16
	s_nop 0
	global_load_lds_dwordx4 v128, s[14:15]
	s_add_i32 m0, s16, 0x2000
	s_nop 0
	global_load_lds_dwordx4 v148, s[14:15]
	s_waitcnt vmcnt(6)
	s_barrier
	v_mfma_f32_16x16x32_bf16 v[52:55], v[220:223], v[178:181], v[52:55]
	v_mfma_f32_16x16x32_bf16 v[48:51], v[228:231], v[178:181], v[48:51]
	v_mfma_f32_16x16x32_bf16 v[36:39], v[220:223], v[196:199], v[36:39]
	v_mfma_f32_16x16x32_bf16 v[32:35], v[228:231], v[196:199], v[32:35]
	v_mfma_f32_16x16x32_bf16 v[20:23], v[220:223], v[204:207], v[20:23]
	v_mfma_f32_16x16x32_bf16 v[16:19], v[228:231], v[204:207], v[16:19]
	v_mfma_f32_16x16x32_bf16 v[4:7], v[220:223], v[212:215], v[4:7]
	v_mfma_f32_16x16x32_bf16 v[0:3], v[228:231], v[212:215], v[0:3]
	v_mfma_f32_16x16x32_bf16 v[52:55], v[224:227], v[192:195], v[52:55]
	v_mfma_f32_16x16x32_bf16 v[48:51], v[232:235], v[192:195], v[48:51]
	v_mfma_f32_16x16x32_bf16 v[36:39], v[224:227], v[200:203], v[36:39]
	v_mfma_f32_16x16x32_bf16 v[32:35], v[232:235], v[200:203], v[32:35]
	v_mfma_f32_16x16x32_bf16 v[20:23], v[224:227], v[208:211], v[20:23]
	v_mfma_f32_16x16x32_bf16 v[16:19], v[232:235], v[208:211], v[16:19]
	v_mfma_f32_16x16x32_bf16 v[4:7], v[224:227], v[216:219], v[4:7]
	v_mfma_f32_16x16x32_bf16 v[0:3], v[232:235], v[216:219], v[0:3]
	s_add_i32 s16, 0, 0x18000
	s_barrier
	ds_read_b128 v[158:161], v250
	ds_read_b128 v[162:165], v250 offset:1024
	ds_read_b128 v[170:173], v250 offset:2048
	ds_read_b128 v[174:177], v250 offset:3072
	s_add_u32 s14, s30, 0x40000
	s_addc_u32 s15, s31, 0
	s_mov_b32 m0, s46
	ds_read_b128 v[178:181], v168 offset:32768
	ds_read_b128 v[192:195], v168 offset:33792
	ds_read_b128 v[196:199], v168 offset:34816
	ds_read_b128 v[200:203], v168 offset:35840
	ds_read_b128 v[204:207], v168 offset:36864
	ds_read_b128 v[208:211], v168 offset:37888
	ds_read_b128 v[212:215], v168 offset:38912
	ds_read_b128 v[216:219], v168 offset:39936
	global_load_lds_dwordx4 v152, s[14:15]
	s_mov_b32 m0, s47
	s_nop 0
	global_load_lds_dwordx4 v150, s[14:15]
	s_waitcnt lgkmcnt(8)
	s_barrier
; #define PG8_STAGE(bufoff, gbase, voff) do { _Pragma("unroll") for (int _i = 0; _i < 2; ++_i) \
;         __builtin_amdgcn_global_load_lds((const unsigned*)((const char*)(gbase) + (voff)[_i]), (PG8_LAS unsigned*)(lds + (bufoff) + ldsw + _i * 8192), 16, 0, 0); } while (0)
; #define PG8_LDA(dst, b, h) do { _Pragma("unroll") for (int m = 0; m < 4; ++m) _Pragma("unroll") for (int k = 0; k < 2; ++k) dst[m][k] = *(const PG8_LAS bf16x8*)(lds + PG8_SA(b, h) + aoff + m * 2048 + k * 1024); } while (0)
; #define PG8_LDB(dst, b, h) do { _Pragma("unroll") for (int n = 0; n < 2; ++n) _Pragma("unroll") for (int k = 0; k < 2; ++k) dst[n][k] = *(const PG8_LAS bf16x8*)(lds + PG8_SB(b, h) + boff + n * 2048 + k * 1024); } while (0)
; #define PG8_MMA(ai, bj, At, Bt) do { __builtin_amdgcn_s_setprio(1); _Pragma("unroll") for (int m = 0; m < 4; ++m) _Pragma("unroll") for (int n = 0; n < 2; ++n) _Pragma("unroll") for (int k = 0; k < 2; ++k) \
;         acc[ai][bj][m][n] = __builtin_amdgcn_mfma_f32_16x16x32_bf16(Bt[n][k], At[m][k], acc[ai][bj][m][n], 0, 0, 0); __builtin_amdgcn_s_setprio(0); } while (0)
; #define PG8_WAIT_V(n) asm volatile("s_waitcnt vmcnt(" #n ")" ::: "memory")
; #define PG8_WAIT_L(n) asm volatile("s_waitcnt lgkmcnt(" #n ")" ::: "memory")
; #define PG8_BAR __builtin_amdgcn_s_barrier()
; #define PG8_SCHED __builtin_amdgcn_sched_barrier(0)
; template <class Epi, class Sched, bool STAMP = false>
; __device__ __forceinline__ void gemm_phase(PG8_LAS unsigned char* lds, const Gemm g, const Sched& S, const Epi& E, unsigned long long* stamps) {
;     ...
;             PG8_WAIT_L(8); PG8_BAR; PG8_WAIT_L(0); PG8_MMA(0, 0, At, B0); PG8_BAR; PG8_SCHED;
;             PG8_LDB(B1, 1, 1); PG8_STAGE(PG8_SB(1, 0), b3, voffB);
;             PG8_BAR; PG8_WAIT_L(0); PG8_MMA(0, 1, At, B1); PG8_BAR;
;             PG8_LDA(At, 1, 1); PG8_STAGE(PG8_SA(1, 0), a3, voffA);
;             PG8_BAR; PG8_WAIT_L(0); PG8_MMA(1, 0, At, B0); PG8_BAR; PG8_SCHED;
;             PG8_STAGE(PG8_SB(1, 1), b3 + hstep, voffB);
;             PG8_WAIT_V(6); PG8_BAR; PG8_MMA(1, 1, At, B1); PG8_BAR;
	s_waitcnt lgkmcnt(0)
	v_mfma_f32_16x16x32_bf16 v[124:127], v[158:161], v[178:181], v[124:127]
	v_mfma_f32_16x16x32_bf16 v[120:123], v[170:173], v[178:181], v[120:123]
	v_mfma_f32_16x16x32_bf16 v[108:111], v[158:161], v[196:199], v[108:111]
	v_mfma_f32_16x16x32_bf16 v[104:107], v[170:173], v[196:199], v[104:107]
	v_mfma_f32_16x16x32_bf16 v[92:95], v[158:161], v[204:207], v[92:95]
	v_mfma_f32_16x16x32_bf16 v[88:91], v[170:173], v[204:207], v[88:91]
	v_mfma_f32_16x16x32_bf16 v[76:79], v[158:161], v[212:215], v[76:79]
	v_mfma_f32_16x16x32_bf16 v[72:75], v[170:173], v[212:215], v[72:75]
	v_mfma_f32_16x16x32_bf16 v[124:127], v[162:165], v[192:195], v[124:127]
	v_mfma_f32_16x16x32_bf16 v[120:123], v[174:177], v[192:195], v[120:123]
	v_mfma_f32_16x16x32_bf16 v[108:111], v[162:165], v[200:203], v[108:111]
	v_mfma_f32_16x16x32_bf16 v[104:107], v[174:177], v[200:203], v[104:107]
	v_mfma_f32_16x16x32_bf16 v[92:95], v[162:165], v[208:211], v[92:95]
	v_mfma_f32_16x16x32_bf16 v[88:91], v[174:177], v[208:211], v[88:91]
	v_mfma_f32_16x16x32_bf16 v[76:79], v[162:165], v[216:219], v[76:79]
	v_mfma_f32_16x16x32_bf16 v[72:75], v[174:177], v[216:219], v[72:75]
	s_barrier
	s_add_i32 s17, 0, 0x1c000
	s_add_i32 s14, s16, s43
	s_mov_b32 m0, s14
	ds_read_b128 v[220:223], v251
	ds_read_b128 v[224:227], v251 offset:1024
	ds_read_b128 v[228:231], v251 offset:2048
	ds_read_b128 v[232:235], v251 offset:3072
	global_load_lds_dwordx4 v244, s[26:27]
	s_add_i32 m0, s14, 0x2000
	s_nop 0
	global_load_lds_dwordx4 v245, s[26:27]
	s_barrier
	s_waitcnt lgkmcnt(0)
	v_mfma_f32_16x16x32_bf16 v[116:119], v[220:223], v[178:181], v[116:119]
	v_mfma_f32_16x16x32_bf16 v[112:115], v[228:231], v[178:181], v[112:115]
	v_mfma_f32_16x16x32_bf16 v[100:103], v[220:223], v[196:199], v[100:103]
	v_mfma_f32_16x16x32_bf16 v[96:99], v[228:231], v[196:199], v[96:99]
	v_mfma_f32_16x16x32_bf16 v[84:87], v[220:223], v[204:207], v[84:87]
	v_mfma_f32_16x16x32_bf16 v[80:83], v[228:231], v[204:207], v[80:83]
	v_mfma_f32_16x16x32_bf16 v[68:71], v[220:223], v[212:215], v[68:71]
	v_mfma_f32_16x16x32_bf16 v[64:67], v[228:231], v[212:215], v[64:67]
	v_mfma_f32_16x16x32_bf16 v[116:119], v[224:227], v[192:195], v[116:119]
	v_mfma_f32_16x16x32_bf16 v[112:115], v[232:235], v[192:195], v[112:115]
	v_mfma_f32_16x16x32_bf16 v[100:103], v[224:227], v[200:203], v[100:103]
	v_mfma_f32_16x16x32_bf16 v[96:99], v[232:235], v[200:203], v[96:99]
	v_mfma_f32_16x16x32_bf16 v[84:87], v[224:227], v[208:211], v[84:87]
	v_mfma_f32_16x16x32_bf16 v[80:83], v[232:235], v[208:211], v[80:83]
	v_mfma_f32_16x16x32_bf16 v[68:71], v[224:227], v[216:219], v[68:71]
	v_mfma_f32_16x16x32_bf16 v[64:67], v[232:235], v[216:219], v[64:67]
	s_mov_b32 m0, s49
	s_barrier
	ds_read_b128 v[178:181], v168 offset:49152
	ds_read_b128 v[192:195], v168 offset:50176
	ds_read_b128 v[196:199], v168 offset:51200
	ds_read_b128 v[200:203], v168 offset:52224
	ds_read_b128 v[204:207], v168 offset:53248
	ds_read_b128 v[208:211], v168 offset:54272
	ds_read_b128 v[212:215], v168 offset:55296
	ds_read_b128 v[216:219], v168 offset:56320
	global_load_lds_dwordx4 v246, s[30:31]
	s_mov_b32 m0, s53
	s_nop 0
	global_load_lds_dwordx4 v247, s[30:31]
	s_barrier
	s_waitcnt lgkmcnt(0)
	v_mfma_f32_16x16x32_bf16 v[60:63], v[158:161], v[178:181], v[60:63]
	v_mfma_f32_16x16x32_bf16 v[56:59], v[170:173], v[178:181], v[56:59]
	v_mfma_f32_16x16x32_bf16 v[44:47], v[158:161], v[196:199], v[44:47]
	v_mfma_f32_16x16x32_bf16 v[40:43], v[170:173], v[196:199], v[40:43]
	v_mfma_f32_16x16x32_bf16 v[28:31], v[158:161], v[204:207], v[28:31]
	v_mfma_f32_16x16x32_bf16 v[24:27], v[170:173], v[204:207], v[24:27]
	v_mfma_f32_16x16x32_bf16 v[12:15], v[158:161], v[212:215], v[12:15]
	v_mfma_f32_16x16x32_bf16 v[8:11], v[170:173], v[212:215], v[8:11]
	v_mfma_f32_16x16x32_bf16 v[60:63], v[162:165], v[192:195], v[60:63]
	v_mfma_f32_16x16x32_bf16 v[56:59], v[174:177], v[192:195], v[56:59]
	v_mfma_f32_16x16x32_bf16 v[44:47], v[162:165], v[200:203], v[44:47]
	v_mfma_f32_16x16x32_bf16 v[40:43], v[174:177], v[200:203], v[40:43]
	v_mfma_f32_16x16x32_bf16 v[28:31], v[162:165], v[208:211], v[28:31]
	v_mfma_f32_16x16x32_bf16 v[24:27], v[174:177], v[208:211], v[24:27]
	v_mfma_f32_16x16x32_bf16 v[12:15], v[162:165], v[216:219], v[12:15]
	v_mfma_f32_16x16x32_bf16 v[8:11], v[174:177], v[216:219], v[8:11]
	s_barrier
	s_add_u32 s14, s26, 0x40080
	s_addc_u32 s15, s27, 0
	s_add_i32 s16, s17, s43
	s_mov_b32 m0, s16
	s_nop 0
	global_load_lds_dwordx4 v128, s[14:15]
	s_add_i32 m0, s16, 0x2000
	s_nop 0
	global_load_lds_dwordx4 v148, s[14:15]
	s_waitcnt vmcnt(6)
	s_barrier
	v_mfma_f32_16x16x32_bf16 v[52:55], v[220:223], v[178:181], v[52:55]
	v_mfma_f32_16x16x32_bf16 v[48:51], v[228:231], v[178:181], v[48:51]
	v_mfma_f32_16x16x32_bf16 v[36:39], v[220:223], v[196:199], v[36:39]
	v_mfma_f32_16x16x32_bf16 v[32:35], v[228:231], v[196:199], v[32:35]
	v_mfma_f32_16x16x32_bf16 v[20:23], v[220:223], v[204:207], v[20:23]
	v_mfma_f32_16x16x32_bf16 v[16:19], v[228:231], v[204:207], v[16:19]
	v_mfma_f32_16x16x32_bf16 v[4:7], v[220:223], v[212:215], v[4:7]
	v_mfma_f32_16x16x32_bf16 v[0:3], v[228:231], v[212:215], v[0:3]
	v_mfma_f32_16x16x32_bf16 v[52:55], v[224:227], v[192:195], v[52:55]
	v_mfma_f32_16x16x32_bf16 v[48:51], v[232:235], v[192:195], v[48:51]
	v_mfma_f32_16x16x32_bf16 v[36:39], v[224:227], v[200:203], v[36:39]
	v_mfma_f32_16x16x32_bf16 v[32:35], v[232:235], v[200:203], v[32:35]
	v_mfma_f32_16x16x32_bf16 v[20:23], v[224:227], v[208:211], v[20:23]
	v_mfma_f32_16x16x32_bf16 v[16:19], v[232:235], v[208:211], v[16:19]
	v_mfma_f32_16x16x32_bf16 v[4:7], v[224:227], v[216:219], v[4:7]
	v_mfma_f32_16x16x32_bf16 v[0:3], v[232:235], v[216:219], v[0:3]
	s_add_i32 s61, s61, 2
	s_add_u32 s24, s24, 0x100
	s_addc_u32 s25, s25, 0
	s_add_u32 s59, s59, 0x100
	s_addc_u32 s60, s60, 0
	s_cmp_gt_u32 s61, 13
	s_barrier
; __device__ __forceinline__ unsigned cvt_pk_bf16(float lo, float hi) { const f32x2_cv v = {lo, hi}; const bf16x2_cv b = __builtin_convertvector(v, bf16x2_cv); return __builtin_bit_cast(unsigned, b); }
; #define PG8_MMA(ai, bj, At, Bt) do { __builtin_amdgcn_s_setprio(1); _Pragma("unroll") for (int m = 0; m < 4; ++m) _Pragma("unroll") for (int n = 0; n < 2; ++n) _Pragma("unroll") for (int k = 0; k < 2; ++k) \
;         acc[ai][bj][m][n] = __builtin_amdgcn_mfma_f32_16x16x32_bf16(Bt[n][k], At[m][k], acc[ai][bj][m][n], 0, 0, 0); __builtin_amdgcn_s_setprio(0); } while (0)
; #define PG8_WAIT_V(n) asm volatile("s_waitcnt vmcnt(" #n ")" ::: "memory")
; #define PG8_BAR __builtin_amdgcn_s_barrier()
; __device__ __forceinline__ float rstd_of(const float* rowss, int row) { return rsqrtf(rowss[row] * (1.0f / 1024.0f) + 1e-6f); }
; template <class Epi, class Sched, bool STAMP = false>
; __device__ __forceinline__ void gemm_phase(PG8_LAS unsigned char* lds, const Gemm g, const Sched& S, const Epi& E, unsigned long long* stamps) {
;     ...
;             PG8_WAIT_V(6); PG8_BAR; PG8_MMA(1, 1, At, B1); PG8_BAR;
;         }
;     __device__ __forceinline__ void operator()(const f32x4 (&acc)[2][2][4][2], const pg8::Unit& u, int wr, int wc, int fr, int fq) const {
;         const int row0 = u.pm * 256 + wr * 64 + fr, col0 = u.pn * 256 + wc * 32 + 8 * fq;
; #pragma unroll
;         for (int ai = 0; ai < 2; ++ai)
; #pragma unroll
;             for (int m = 0; m < 4; ++m) {
;                 const int row = row0 + ai * 128 + m * 16;
;                 const float s = (MODE == 2) ? 1.0f : rstd_of(rowss, row);
;                 bf16_t* rowp = O + (size_t)row * ldc + col0;
; #pragma unroll
;                 for (int bj = 0; bj < 2; ++bj) {
;                     f32x4 v0 = acc[ai][bj][m][0] * s, v1 = acc[ai][bj][m][1] * s;
;                     if (MODE == 1) {
; #pragma unroll
;                         for (int j = 0; j < 4; ++j) { const float a = fmaxf(v0[j], 0.f), b = fmaxf(v1[j], 0.f); v0[j] = a * a; v1[j] = b * b; } }
;                     u32x4 w; w.x = cvt_pk_bf16(v0[0], v0[1]); w.y = cvt_pk_bf16(v0[2], v0[3]); w.z = cvt_pk_bf16(v1[0], v1[1]); w.w = cvt_pk_bf16(v1[2], v1[3]);
;                     *(u32x4*)(rowp + bj * 128) = w; } }
	s_cbranch_scc0 .LBB0_44
	v_lshl_add_u32 v162, s22, 8, v139
	v_ashrrev_i32_e32 v163, 31, v162
	v_lshl_add_u64 v[158:159], v[162:163], 2, s[0:1]
	global_load_dword v164, v[158:159], off
	global_load_dword v193, v[158:159], off offset:64
	global_load_dword v194, v[158:159], off offset:128
	global_load_dword v195, v[158:159], off offset:192
	global_load_dword v196, v[158:159], off offset:512
	global_load_dword v197, v[158:159], off offset:576
	global_load_dword v198, v[158:159], off offset:640
	global_load_dword v199, v[158:159], off offset:704
	v_lshl_or_b32 v160, s56, 8, v167
	v_ashrrev_i32_e32 v161, 31, v160
	s_mov_b32 s5, 0x100000
	s_mov_b64 s[14:15], 0x100000
	s_mov_b32 s56, s4
	s_mov_b32 s22, s6
	s_mov_b64 s[26:27], s[20:21]
	s_mov_b64 s[24:25], s[12:13]
	s_waitcnt vmcnt(0)
	v_fmamk_f32 v164, v164, 0x3a800000, v187
	v_cmp_gt_f32_e32 vcc, s67, v164
	v_mul_f32_e32 v165, 0x4b800000, v164
	s_nop 0
	v_cndmask_b32_e32 v164, v164, v165, vcc
	v_rsq_f32_e32 v164, v164
	s_nop 0
	v_mul_f32_e32 v165, 0x45800000, v164
	v_cndmask_b32_e32 v170, v164, v165, vcc
	v_lshlrev_b64 v[164:165], 13, v[162:163]
	v_pk_mul_f32 v[120:121], v[120:121], v[170:171] op_sel_hi:[1,0]
	v_lshl_add_u64 v[172:173], s[2:3], 0, v[164:165]
	v_lshlrev_b64 v[164:165], 1, v[160:161]
	v_pk_mul_f32 v[126:127], v[126:127], v[170:171] op_sel_hi:[1,0]
	v_pk_mul_f32 v[124:125], v[124:125], v[170:171] op_sel_hi:[1,0]
	v_pk_mul_f32 v[122:123], v[122:123], v[170:171] op_sel_hi:[1,0]
	v_max_f32_e32 v120, 0, v120
	v_max_f32_e32 v121, 0, v121
	v_lshl_add_u64 v[160:161], v[172:173], 0, v[164:165]
	v_max_f32_e32 v124, 0, v124
	v_max_f32_e32 v125, 0, v125
	v_pk_mul_f32 v[172:173], v[120:121], v[120:121]
	v_max_f32_e32 v120, 0, v126
	v_max_f32_e32 v122, 0, v122
	v_max_f32_e32 v121, 0, v127
	v_max_f32_e32 v123, 0, v123
	v_pk_mul_f32 v[124:125], v[124:125], v[124:125]
	v_pk_mul_f32 v[126:127], v[120:121], v[120:121]
	v_pk_mul_f32 v[174:175], v[122:123], v[122:123]
	v_pk_mul_f32 v[112:113], v[112:113], v[170:171] op_sel_hi:[1,0]
	v_cvt_pk_bf16_f32 v120, v124, v125
	v_cvt_pk_bf16_f32 v121, v126, v127
	v_cvt_pk_bf16_f32 v122, v172, v173
	v_cvt_pk_bf16_f32 v123, v174, v175
	v_pk_mul_f32 v[118:119], v[118:119], v[170:171] op_sel_hi:[1,0]
	v_pk_mul_f32 v[116:117], v[116:117], v[170:171] op_sel_hi:[1,0]
	v_pk_mul_f32 v[114:115], v[114:115], v[170:171] op_sel_hi:[1,0]
	v_max_f32_e32 v112, 0, v112
	v_max_f32_e32 v113, 0, v113
	global_store_dwordx4 v[160:161], v[120:123], off
	v_max_f32_e32 v116, 0, v116
	v_max_f32_e32 v117, 0, v117
	v_pk_mul_f32 v[120:121], v[112:113], v[112:113]
	v_max_f32_e32 v112, 0, v118
	v_max_f32_e32 v114, 0, v114
	v_max_f32_e32 v113, 0, v119
	v_max_f32_e32 v115, 0, v115
	v_pk_mul_f32 v[116:117], v[116:117], v[116:117]
	v_pk_mul_f32 v[118:119], v[112:113], v[112:113]
	v_pk_mul_f32 v[122:123], v[114:115], v[114:115]
	v_cvt_pk_bf16_f32 v112, v116, v117
	v_cvt_pk_bf16_f32 v113, v118, v119
	v_cvt_pk_bf16_f32 v114, v120, v121
	v_cvt_pk_bf16_f32 v115, v122, v123
	global_store_dwordx4 v[160:161], v[112:115], off offset:256
	s_nop 1
	v_mov_b32_e32 v114, v193
	s_nop 0
	v_or_b32_e32 v112, 16, v162
	v_ashrrev_i32_e32 v113, 31, v112
	v_lshlrev_b64 v[112:113], 13, v[112:113]
	v_lshl_add_u64 v[112:113], s[2:3], 0, v[112:113]
	v_lshl_add_u64 v[112:113], v[112:113], 0, v[164:165]
	v_fmamk_f32 v114, v114, 0x3a800000, v187
	v_cmp_gt_f32_e32 vcc, s67, v114
	v_mul_f32_e32 v115, 0x4b800000, v114
	s_nop 0
	v_cndmask_b32_e32 v114, v114, v115, vcc
	v_rsq_f32_e32 v114, v114
	s_nop 0
	v_mul_f32_e32 v115, 0x45800000, v114
	v_cndmask_b32_e32 v114, v114, v115, vcc
	v_pk_mul_f32 v[104:105], v[104:105], v[114:115] op_sel_hi:[1,0]
	v_pk_mul_f32 v[110:111], v[110:111], v[114:115] op_sel_hi:[1,0]
	v_pk_mul_f32 v[108:109], v[108:109], v[114:115] op_sel_hi:[1,0]
	v_pk_mul_f32 v[106:107], v[106:107], v[114:115] op_sel_hi:[1,0]
	v_max_f32_e32 v104, 0, v104
	v_max_f32_e32 v105, 0, v105
	v_max_f32_e32 v108, 0, v108
	v_max_f32_e32 v109, 0, v109
	v_pk_mul_f32 v[116:117], v[104:105], v[104:105]
	v_max_f32_e32 v104, 0, v110
	v_max_f32_e32 v106, 0, v106
	v_max_f32_e32 v105, 0, v111
	v_max_f32_e32 v107, 0, v107
	v_pk_mul_f32 v[108:109], v[108:109], v[108:109]
	v_pk_mul_f32 v[110:111], v[104:105], v[104:105]
	v_pk_mul_f32 v[118:119], v[106:107], v[106:107]
	v_pk_mul_f32 v[96:97], v[96:97], v[114:115] op_sel_hi:[1,0]
	v_cvt_pk_bf16_f32 v104, v108, v109
	v_cvt_pk_bf16_f32 v105, v110, v111
	v_cvt_pk_bf16_f32 v106, v116, v117
	v_cvt_pk_bf16_f32 v107, v118, v119
	v_pk_mul_f32 v[102:103], v[102:103], v[114:115] op_sel_hi:[1,0]
	v_pk_mul_f32 v[100:101], v[100:101], v[114:115] op_sel_hi:[1,0]
	v_pk_mul_f32 v[98:99], v[98:99], v[114:115] op_sel_hi:[1,0]
	v_max_f32_e32 v96, 0, v96
	v_max_f32_e32 v97, 0, v97
	global_store_dwordx4 v[112:113], v[104:107], off
	v_max_f32_e32 v100, 0, v100
	v_max_f32_e32 v101, 0, v101
	v_pk_mul_f32 v[104:105], v[96:97], v[96:97]
	v_max_f32_e32 v96, 0, v102
	v_max_f32_e32 v98, 0, v98
	v_max_f32_e32 v97, 0, v103
	v_max_f32_e32 v99, 0, v99
	v_pk_mul_f32 v[100:101], v[100:101], v[100:101]
	v_pk_mul_f32 v[102:103], v[96:97], v[96:97]
	v_pk_mul_f32 v[106:107], v[98:99], v[98:99]
	v_cvt_pk_bf16_f32 v96, v100, v101
	v_cvt_pk_bf16_f32 v97, v102, v103
	v_cvt_pk_bf16_f32 v98, v104, v105
	v_cvt_pk_bf16_f32 v99, v106, v107
	global_store_dwordx4 v[112:113], v[96:99], off offset:256
	s_nop 1
	v_mov_b32_e32 v98, v194
	s_nop 0
	v_or_b32_e32 v96, 32, v162
	v_ashrrev_i32_e32 v97, 31, v96
	v_lshlrev_b64 v[96:97], 13, v[96:97]
	v_lshl_add_u64 v[96:97], s[2:3], 0, v[96:97]
	v_lshl_add_u64 v[96:97], v[96:97], 0, v[164:165]
	v_fmamk_f32 v98, v98, 0x3a800000, v187
	v_cmp_gt_f32_e32 vcc, s67, v98
	v_mul_f32_e32 v99, 0x4b800000, v98
; __device__ __forceinline__ unsigned cvt_pk_bf16(float lo, float hi) { const f32x2_cv v = {lo, hi}; const bf16x2_cv b = __builtin_convertvector(v, bf16x2_cv); return __builtin_bit_cast(unsigned, b); }
; __device__ __forceinline__ float rstd_of(const float* rowss, int row) { return rsqrtf(rowss[row] * (1.0f / 1024.0f) + 1e-6f); }
;     __device__ __forceinline__ void operator()(const f32x4 (&acc)[2][2][4][2], const pg8::Unit& u, int wr, int wc, int fr, int fq) const {
;     ...
;             for (int m = 0; m < 4; ++m) {
;                 const int row = row0 + ai * 128 + m * 16;
;                 const float s = (MODE == 2) ? 1.0f : rstd_of(rowss, row);
;                 bf16_t* rowp = O + (size_t)row * ldc + col0;
; #pragma unroll
;                 for (int bj = 0; bj < 2; ++bj) {
;                     f32x4 v0 = acc[ai][bj][m][0] * s, v1 = acc[ai][bj][m][1] * s;
;                     if (MODE == 1) {
; #pragma unroll
;                         for (int j = 0; j < 4; ++j) { const float a = fmaxf(v0[j], 0.f), b = fmaxf(v1[j], 0.f); v0[j] = a * a; v1[j] = b * b; } }
;                     u32x4 w; w.x = cvt_pk_bf16(v0[0], v0[1]); w.y = cvt_pk_bf16(v0[2], v0[3]); w.z = cvt_pk_bf16(v1[0], v1[1]); w.w = cvt_pk_bf16(v1[2], v1[3]);
;                     *(u32x4*)(rowp + bj * 128) = w; } }
	s_nop 0
	v_cndmask_b32_e32 v98, v98, v99, vcc
	v_rsq_f32_e32 v98, v98
	s_nop 0
	v_mul_f32_e32 v99, 0x45800000, v98
	v_cndmask_b32_e32 v98, v98, v99, vcc
	v_pk_mul_f32 v[88:89], v[88:89], v[98:99] op_sel_hi:[1,0]
	v_pk_mul_f32 v[94:95], v[94:95], v[98:99] op_sel_hi:[1,0]
	v_pk_mul_f32 v[92:93], v[92:93], v[98:99] op_sel_hi:[1,0]
	v_pk_mul_f32 v[90:91], v[90:91], v[98:99] op_sel_hi:[1,0]
	v_max_f32_e32 v88, 0, v88
	v_max_f32_e32 v89, 0, v89
	v_max_f32_e32 v92, 0, v92
	v_max_f32_e32 v93, 0, v93
	v_pk_mul_f32 v[100:101], v[88:89], v[88:89]
	v_max_f32_e32 v88, 0, v94
	v_max_f32_e32 v90, 0, v90
	v_max_f32_e32 v89, 0, v95
	v_max_f32_e32 v91, 0, v91
	v_pk_mul_f32 v[92:93], v[92:93], v[92:93]
	v_pk_mul_f32 v[94:95], v[88:89], v[88:89]
	v_pk_mul_f32 v[102:103], v[90:91], v[90:91]
	v_pk_mul_f32 v[80:81], v[80:81], v[98:99] op_sel_hi:[1,0]
	v_cvt_pk_bf16_f32 v88, v92, v93
	v_cvt_pk_bf16_f32 v89, v94, v95
	v_cvt_pk_bf16_f32 v90, v100, v101
	v_cvt_pk_bf16_f32 v91, v102, v103
	v_pk_mul_f32 v[86:87], v[86:87], v[98:99] op_sel_hi:[1,0]
	v_pk_mul_f32 v[84:85], v[84:85], v[98:99] op_sel_hi:[1,0]
	v_pk_mul_f32 v[82:83], v[82:83], v[98:99] op_sel_hi:[1,0]
	v_max_f32_e32 v80, 0, v80
	v_max_f32_e32 v81, 0, v81
	global_store_dwordx4 v[96:97], v[88:91], off
	v_max_f32_e32 v84, 0, v84
	v_max_f32_e32 v85, 0, v85
	v_pk_mul_f32 v[88:89], v[80:81], v[80:81]
	v_max_f32_e32 v80, 0, v86
	v_max_f32_e32 v82, 0, v82
	v_max_f32_e32 v81, 0, v87
	v_max_f32_e32 v83, 0, v83
	v_pk_mul_f32 v[84:85], v[84:85], v[84:85]
	v_pk_mul_f32 v[86:87], v[80:81], v[80:81]
	v_pk_mul_f32 v[90:91], v[82:83], v[82:83]
	v_cvt_pk_bf16_f32 v80, v84, v85
	v_cvt_pk_bf16_f32 v81, v86, v87
	v_cvt_pk_bf16_f32 v82, v88, v89
	v_cvt_pk_bf16_f32 v83, v90, v91
	global_store_dwordx4 v[96:97], v[80:83], off offset:256
	s_nop 1
	v_mov_b32_e32 v82, v195
	s_nop 0
	v_or_b32_e32 v80, 48, v162
	v_ashrrev_i32_e32 v81, 31, v80
	v_lshlrev_b64 v[80:81], 13, v[80:81]
	v_lshl_add_u64 v[80:81], s[2:3], 0, v[80:81]
	v_lshl_add_u64 v[80:81], v[80:81], 0, v[164:165]
	v_fmamk_f32 v82, v82, 0x3a800000, v187
	v_cmp_gt_f32_e32 vcc, s67, v82
	v_mul_f32_e32 v83, 0x4b800000, v82
	s_nop 0
	v_cndmask_b32_e32 v82, v82, v83, vcc
	v_rsq_f32_e32 v82, v82
	s_nop 0
	v_mul_f32_e32 v83, 0x45800000, v82
	v_cndmask_b32_e32 v82, v82, v83, vcc
	v_pk_mul_f32 v[72:73], v[72:73], v[82:83] op_sel_hi:[1,0]
	v_pk_mul_f32 v[78:79], v[78:79], v[82:83] op_sel_hi:[1,0]
	v_pk_mul_f32 v[76:77], v[76:77], v[82:83] op_sel_hi:[1,0]
	v_pk_mul_f32 v[74:75], v[74:75], v[82:83] op_sel_hi:[1,0]
	v_max_f32_e32 v72, 0, v72
	v_max_f32_e32 v73, 0, v73
	v_max_f32_e32 v76, 0, v76
	v_max_f32_e32 v77, 0, v77
	v_pk_mul_f32 v[84:85], v[72:73], v[72:73]
	v_max_f32_e32 v72, 0, v78
	v_max_f32_e32 v74, 0, v74
	v_max_f32_e32 v73, 0, v79
	v_max_f32_e32 v75, 0, v75
	v_pk_mul_f32 v[76:77], v[76:77], v[76:77]
	v_pk_mul_f32 v[78:79], v[72:73], v[72:73]
	v_pk_mul_f32 v[86:87], v[74:75], v[74:75]
	v_pk_mul_f32 v[64:65], v[64:65], v[82:83] op_sel_hi:[1,0]
	v_cvt_pk_bf16_f32 v72, v76, v77
	v_cvt_pk_bf16_f32 v73, v78, v79
	v_cvt_pk_bf16_f32 v74, v84, v85
	v_cvt_pk_bf16_f32 v75, v86, v87
	v_pk_mul_f32 v[70:71], v[70:71], v[82:83] op_sel_hi:[1,0]
	v_pk_mul_f32 v[68:69], v[68:69], v[82:83] op_sel_hi:[1,0]
	v_pk_mul_f32 v[66:67], v[66:67], v[82:83] op_sel_hi:[1,0]
	v_max_f32_e32 v64, 0, v64
	v_max_f32_e32 v65, 0, v65
	global_store_dwordx4 v[80:81], v[72:75], off
	v_max_f32_e32 v68, 0, v68
	v_max_f32_e32 v69, 0, v69
	v_pk_mul_f32 v[72:73], v[64:65], v[64:65]
	v_max_f32_e32 v64, 0, v70
	v_max_f32_e32 v66, 0, v66
	v_max_f32_e32 v65, 0, v71
	v_max_f32_e32 v67, 0, v67
	v_pk_mul_f32 v[68:69], v[68:69], v[68:69]
	v_pk_mul_f32 v[70:71], v[64:65], v[64:65]
	v_pk_mul_f32 v[74:75], v[66:67], v[66:67]
	v_cvt_pk_bf16_f32 v64, v68, v69
	v_cvt_pk_bf16_f32 v65, v70, v71
	v_cvt_pk_bf16_f32 v66, v72, v73
	v_cvt_pk_bf16_f32 v67, v74, v75
	global_store_dwordx4 v[80:81], v[64:67], off offset:256
	s_nop 1
	v_mov_b32_e32 v64, v196
	v_fmamk_f32 v64, v64, 0x3a800000, v187
	v_cmp_gt_f32_e32 vcc, s67, v64
	v_mul_f32_e32 v65, 0x4b800000, v64
	s_nop 0
	v_cndmask_b32_e32 v64, v64, v65, vcc
	v_rsq_f32_e32 v64, v64
	s_nop 0
	v_mul_f32_e32 v65, 0x45800000, v64
	v_cndmask_b32_e32 v66, v64, v65, vcc
	v_pk_mul_f32 v[60:61], v[60:61], v[66:67] op_sel_hi:[1,0]
	v_pk_mul_f32 v[56:57], v[56:57], v[66:67] op_sel_hi:[1,0]
	v_pk_mul_f32 v[62:63], v[62:63], v[66:67] op_sel_hi:[1,0]
	v_pk_mul_f32 v[58:59], v[58:59], v[66:67] op_sel_hi:[1,0]
	v_max_f32_e32 v60, 0, v60
	v_max_f32_e32 v56, 0, v56
	v_max_f32_e32 v61, 0, v61
	v_max_f32_e32 v57, 0, v57
	v_pk_mul_f32 v[60:61], v[60:61], v[60:61]
	v_pk_mul_f32 v[68:69], v[56:57], v[56:57]
	v_max_f32_e32 v56, 0, v62
	v_max_f32_e32 v58, 0, v58
	v_max_f32_e32 v57, 0, v63
	v_max_f32_e32 v59, 0, v59
	v_pk_mul_f32 v[62:63], v[56:57], v[56:57]
	v_pk_mul_f32 v[70:71], v[58:59], v[58:59]
	v_cvt_pk_bf16_f32 v56, v60, v61
	v_add_co_u32_e32 v60, vcc, s5, v160
	v_pk_mul_f32 v[48:49], v[48:49], v[66:67] op_sel_hi:[1,0]
	v_cvt_pk_bf16_f32 v57, v62, v63
	v_cvt_pk_bf16_f32 v58, v68, v69
	v_cvt_pk_bf16_f32 v59, v70, v71
	v_addc_co_u32_e32 v61, vcc, 0, v161, vcc
	v_pk_mul_f32 v[54:55], v[54:55], v[66:67] op_sel_hi:[1,0]
	v_pk_mul_f32 v[52:53], v[52:53], v[66:67] op_sel_hi:[1,0]
	v_pk_mul_f32 v[50:51], v[50:51], v[66:67] op_sel_hi:[1,0]
	v_max_f32_e32 v48, 0, v48
	v_max_f32_e32 v49, 0, v49
	global_store_dwordx4 v[60:61], v[56:59], off
	v_max_f32_e32 v52, 0, v52
	v_max_f32_e32 v53, 0, v53
	v_pk_mul_f32 v[56:57], v[48:49], v[48:49]
	v_max_f32_e32 v48, 0, v54
	v_max_f32_e32 v50, 0, v50
	v_max_f32_e32 v49, 0, v55
	v_max_f32_e32 v51, 0, v51
	v_pk_mul_f32 v[52:53], v[52:53], v[52:53]
	v_pk_mul_f32 v[54:55], v[48:49], v[48:49]
; __device__ __forceinline__ unsigned cvt_pk_bf16(float lo, float hi) { const f32x2_cv v = {lo, hi}; const bf16x2_cv b = __builtin_convertvector(v, bf16x2_cv); return __builtin_bit_cast(unsigned, b); }
; __device__ __forceinline__ float rstd_of(const float* rowss, int row) { return rsqrtf(rowss[row] * (1.0f / 1024.0f) + 1e-6f); }
; template <class Epi, class Sched, bool STAMP = false>
; __device__ __forceinline__ void gemm_phase(PG8_LAS unsigned char* lds, const Gemm g, const Sched& S, const Epi& E, unsigned long long* stamps) {
;     ...
;         if constexpr (!Epi::AFTER_DRAIN) { E(acc, cur, wr, wc, fr, fq); S.done(cur); }
;         if (!has_next) break;
;     __device__ __forceinline__ void operator()(const f32x4 (&acc)[2][2][4][2], const pg8::Unit& u, int wr, int wc, int fr, int fq) const {
;     ...
;             for (int m = 0; m < 4; ++m) {
;                 const int row = row0 + ai * 128 + m * 16;
;                 const float s = (MODE == 2) ? 1.0f : rstd_of(rowss, row);
;                 bf16_t* rowp = O + (size_t)row * ldc + col0;
; #pragma unroll
;                 for (int bj = 0; bj < 2; ++bj) {
;                     f32x4 v0 = acc[ai][bj][m][0] * s, v1 = acc[ai][bj][m][1] * s;
;                     if (MODE == 1) {
; #pragma unroll
;                         for (int j = 0; j < 4; ++j) { const float a = fmaxf(v0[j], 0.f), b = fmaxf(v1[j], 0.f); v0[j] = a * a; v1[j] = b * b; } }
;                     u32x4 w; w.x = cvt_pk_bf16(v0[0], v0[1]); w.y = cvt_pk_bf16(v0[2], v0[3]); w.z = cvt_pk_bf16(v1[0], v1[1]); w.w = cvt_pk_bf16(v1[2], v1[3]);
;                     *(u32x4*)(rowp + bj * 128) = w; } }
	v_pk_mul_f32 v[58:59], v[50:51], v[50:51]
	v_lshl_add_u64 v[64:65], v[160:161], 0, s[14:15]
	v_cvt_pk_bf16_f32 v48, v52, v53
	v_cvt_pk_bf16_f32 v49, v54, v55
	v_cvt_pk_bf16_f32 v50, v56, v57
	v_cvt_pk_bf16_f32 v51, v58, v59
	global_store_dwordx4 v[64:65], v[48:51], off offset:256
	s_nop 1
	v_mov_b32_e32 v48, v197
	s_mov_b32 s5, 0x120000
	s_mov_b64 s[14:15], 0x120000
	v_fmamk_f32 v48, v48, 0x3a800000, v187
	v_cmp_gt_f32_e32 vcc, s67, v48
	v_mul_f32_e32 v49, 0x4b800000, v48
	s_nop 0
	v_cndmask_b32_e32 v48, v48, v49, vcc
	v_rsq_f32_e32 v48, v48
	s_nop 0
	v_mul_f32_e32 v49, 0x45800000, v48
	v_cndmask_b32_e32 v50, v48, v49, vcc
	v_pk_mul_f32 v[44:45], v[44:45], v[50:51] op_sel_hi:[1,0]
	v_pk_mul_f32 v[40:41], v[40:41], v[50:51] op_sel_hi:[1,0]
	v_pk_mul_f32 v[46:47], v[46:47], v[50:51] op_sel_hi:[1,0]
	v_pk_mul_f32 v[42:43], v[42:43], v[50:51] op_sel_hi:[1,0]
	v_max_f32_e32 v44, 0, v44
	v_max_f32_e32 v40, 0, v40
	v_max_f32_e32 v45, 0, v45
	v_max_f32_e32 v41, 0, v41
	v_pk_mul_f32 v[44:45], v[44:45], v[44:45]
	v_pk_mul_f32 v[52:53], v[40:41], v[40:41]
	v_max_f32_e32 v40, 0, v46
	v_max_f32_e32 v42, 0, v42
	v_max_f32_e32 v41, 0, v47
	v_max_f32_e32 v43, 0, v43
	v_pk_mul_f32 v[46:47], v[40:41], v[40:41]
	v_pk_mul_f32 v[54:55], v[42:43], v[42:43]
	v_cvt_pk_bf16_f32 v40, v44, v45
	v_add_co_u32_e32 v44, vcc, s5, v160
	v_pk_mul_f32 v[32:33], v[32:33], v[50:51] op_sel_hi:[1,0]
	v_cvt_pk_bf16_f32 v41, v46, v47
	v_cvt_pk_bf16_f32 v42, v52, v53
	v_cvt_pk_bf16_f32 v43, v54, v55
	v_addc_co_u32_e32 v45, vcc, 0, v161, vcc
	v_pk_mul_f32 v[38:39], v[38:39], v[50:51] op_sel_hi:[1,0]
	v_pk_mul_f32 v[36:37], v[36:37], v[50:51] op_sel_hi:[1,0]
	v_pk_mul_f32 v[34:35], v[34:35], v[50:51] op_sel_hi:[1,0]
	v_max_f32_e32 v32, 0, v32
	v_max_f32_e32 v33, 0, v33
	global_store_dwordx4 v[44:45], v[40:43], off
	v_max_f32_e32 v36, 0, v36
	v_max_f32_e32 v37, 0, v37
	v_pk_mul_f32 v[40:41], v[32:33], v[32:33]
	v_max_f32_e32 v32, 0, v38
	v_max_f32_e32 v34, 0, v34
	v_max_f32_e32 v33, 0, v39
	v_max_f32_e32 v35, 0, v35
	v_pk_mul_f32 v[36:37], v[36:37], v[36:37]
	v_pk_mul_f32 v[38:39], v[32:33], v[32:33]
	v_pk_mul_f32 v[42:43], v[34:35], v[34:35]
	v_lshl_add_u64 v[48:49], v[160:161], 0, s[14:15]
	v_cvt_pk_bf16_f32 v32, v36, v37
	v_cvt_pk_bf16_f32 v33, v38, v39
	v_cvt_pk_bf16_f32 v34, v40, v41
	v_cvt_pk_bf16_f32 v35, v42, v43
	global_store_dwordx4 v[48:49], v[32:35], off offset:256
	s_nop 1
	v_mov_b32_e32 v32, v198
	s_mov_b32 s5, 0x140000
	s_mov_b64 s[14:15], 0x140000
	v_fmamk_f32 v32, v32, 0x3a800000, v187
	v_cmp_gt_f32_e32 vcc, s67, v32
	v_mul_f32_e32 v33, 0x4b800000, v32
	s_nop 0
	v_cndmask_b32_e32 v32, v32, v33, vcc
	v_rsq_f32_e32 v32, v32
	s_nop 0
	v_mul_f32_e32 v33, 0x45800000, v32
	v_cndmask_b32_e32 v34, v32, v33, vcc
	v_pk_mul_f32 v[28:29], v[28:29], v[34:35] op_sel_hi:[1,0]
	v_pk_mul_f32 v[24:25], v[24:25], v[34:35] op_sel_hi:[1,0]
	v_pk_mul_f32 v[30:31], v[30:31], v[34:35] op_sel_hi:[1,0]
	v_pk_mul_f32 v[26:27], v[26:27], v[34:35] op_sel_hi:[1,0]
	v_max_f32_e32 v28, 0, v28
	v_max_f32_e32 v24, 0, v24
	v_max_f32_e32 v29, 0, v29
	v_max_f32_e32 v25, 0, v25
	v_pk_mul_f32 v[28:29], v[28:29], v[28:29]
	v_pk_mul_f32 v[36:37], v[24:25], v[24:25]
	v_max_f32_e32 v24, 0, v30
	v_max_f32_e32 v26, 0, v26
	v_max_f32_e32 v25, 0, v31
	v_max_f32_e32 v27, 0, v27
	v_pk_mul_f32 v[30:31], v[24:25], v[24:25]
	v_pk_mul_f32 v[38:39], v[26:27], v[26:27]
	v_cvt_pk_bf16_f32 v24, v28, v29
	v_add_co_u32_e32 v28, vcc, s5, v160
	v_pk_mul_f32 v[16:17], v[16:17], v[34:35] op_sel_hi:[1,0]
	v_cvt_pk_bf16_f32 v25, v30, v31
	v_cvt_pk_bf16_f32 v26, v36, v37
	v_cvt_pk_bf16_f32 v27, v38, v39
	v_addc_co_u32_e32 v29, vcc, 0, v161, vcc
	v_pk_mul_f32 v[22:23], v[22:23], v[34:35] op_sel_hi:[1,0]
	v_pk_mul_f32 v[20:21], v[20:21], v[34:35] op_sel_hi:[1,0]
	v_pk_mul_f32 v[18:19], v[18:19], v[34:35] op_sel_hi:[1,0]
	v_max_f32_e32 v16, 0, v16
	v_max_f32_e32 v17, 0, v17
	global_store_dwordx4 v[28:29], v[24:27], off
	v_max_f32_e32 v20, 0, v20
	v_max_f32_e32 v21, 0, v21
	v_pk_mul_f32 v[24:25], v[16:17], v[16:17]
	v_max_f32_e32 v16, 0, v22
	v_max_f32_e32 v18, 0, v18
	v_max_f32_e32 v17, 0, v23
	v_max_f32_e32 v19, 0, v19
	v_pk_mul_f32 v[20:21], v[20:21], v[20:21]
	v_pk_mul_f32 v[22:23], v[16:17], v[16:17]
	v_pk_mul_f32 v[26:27], v[18:19], v[18:19]
	v_lshl_add_u64 v[32:33], v[160:161], 0, s[14:15]
	v_cvt_pk_bf16_f32 v16, v20, v21
	v_cvt_pk_bf16_f32 v17, v22, v23
	v_cvt_pk_bf16_f32 v18, v24, v25
	v_cvt_pk_bf16_f32 v19, v26, v27
	global_store_dwordx4 v[32:33], v[16:19], off offset:256
	s_nop 1
	v_mov_b32_e32 v16, v199
	s_mov_b32 s5, 0x160000
	s_mov_b64 s[14:15], 0x160000
	v_lshl_add_u64 v[18:19], v[160:161], 0, s[14:15]
	v_fmamk_f32 v16, v16, 0x3a800000, v187
	v_cmp_gt_f32_e32 vcc, s67, v16
	v_mul_f32_e32 v17, 0x4b800000, v16
	s_nop 0
	v_cndmask_b32_e32 v16, v16, v17, vcc
	v_rsq_f32_e32 v16, v16
	s_nop 0
	v_mul_f32_e32 v17, 0x45800000, v16
	v_cndmask_b32_e32 v16, v16, v17, vcc
	v_pk_mul_f32 v[12:13], v[12:13], v[16:17] op_sel_hi:[1,0]
	v_pk_mul_f32 v[8:9], v[8:9], v[16:17] op_sel_hi:[1,0]
	v_pk_mul_f32 v[14:15], v[14:15], v[16:17] op_sel_hi:[1,0]
	v_pk_mul_f32 v[10:11], v[10:11], v[16:17] op_sel_hi:[1,0]
	v_max_f32_e32 v12, 0, v12
	v_max_f32_e32 v8, 0, v8
	v_max_f32_e32 v13, 0, v13
	v_max_f32_e32 v9, 0, v9
	v_pk_mul_f32 v[12:13], v[12:13], v[12:13]
	v_pk_mul_f32 v[20:21], v[8:9], v[8:9]
	v_max_f32_e32 v8, 0, v14
	v_max_f32_e32 v10, 0, v10
	v_max_f32_e32 v9, 0, v15
	v_max_f32_e32 v11, 0, v11
	v_pk_mul_f32 v[14:15], v[8:9], v[8:9]
	v_pk_mul_f32 v[22:23], v[10:11], v[10:11]
	v_cvt_pk_bf16_f32 v8, v12, v13
	v_add_co_u32_e32 v12, vcc, s5, v160
	v_pk_mul_f32 v[0:1], v[0:1], v[16:17] op_sel_hi:[1,0]
	v_cvt_pk_bf16_f32 v9, v14, v15
	v_cvt_pk_bf16_f32 v10, v20, v21
	v_cvt_pk_bf16_f32 v11, v22, v23
	v_addc_co_u32_e32 v13, vcc, 0, v161, vcc
	v_pk_mul_f32 v[6:7], v[6:7], v[16:17] op_sel_hi:[1,0]
	v_pk_mul_f32 v[4:5], v[4:5], v[16:17] op_sel_hi:[1,0]
	v_pk_mul_f32 v[2:3], v[2:3], v[16:17] op_sel_hi:[1,0]
	v_max_f32_e32 v0, 0, v0
	v_max_f32_e32 v1, 0, v1
	global_store_dwordx4 v[12:13], v[8:11], off
	v_max_f32_e32 v4, 0, v4
	v_max_f32_e32 v5, 0, v5
	v_pk_mul_f32 v[8:9], v[0:1], v[0:1]
	v_max_f32_e32 v0, 0, v6
	v_max_f32_e32 v2, 0, v2
	v_max_f32_e32 v1, 0, v7
	v_max_f32_e32 v3, 0, v3
	v_pk_mul_f32 v[4:5], v[4:5], v[4:5]
	v_pk_mul_f32 v[6:7], v[0:1], v[0:1]
	v_pk_mul_f32 v[10:11], v[2:3], v[2:3]
	v_cvt_pk_bf16_f32 v0, v4, v5
	v_cvt_pk_bf16_f32 v1, v6, v7
	v_cvt_pk_bf16_f32 v2, v8, v9
	v_cvt_pk_bf16_f32 v3, v10, v11
	s_and_b64 vcc, exec, s[38:39]
	global_store_dwordx4 v[18:19], v[0:3], off offset:256
	s_cbranch_vccz .LBB0_41
	s_cmpk_gt_u32 s36, 0xff
	s_cbranch_scc1 .LBB0_48
	s_barrier

; #define PG8_STAGE(bufoff, gbase, voff) do { _Pragma("unroll") for (int _i = 0; _i < 2; ++_i) \
;         __builtin_amdgcn_global_load_lds((const unsigned*)((const char*)(gbase) + (voff)[_i]), (PG8_LAS unsigned*)(lds + (bufoff) + ldsw + _i * 8192), 16, 0, 0); } while (0)
; #define PG8_LDA(dst, b, h) do { _Pragma("unroll") for (int m = 0; m < 4; ++m) _Pragma("unroll") for (int k = 0; k < 2; ++k) dst[m][k] = *(const PG8_LAS bf16x8*)(lds + PG8_SA(b, h) + aoff + m * 2048 + k * 1024); } while (0)
; #define PG8_LDB(dst, b, h) do { _Pragma("unroll") for (int n = 0; n < 2; ++n) _Pragma("unroll") for (int k = 0; k < 2; ++k) dst[n][k] = *(const PG8_LAS bf16x8*)(lds + PG8_SB(b, h) + boff + n * 2048 + k * 1024); } while (0)
; #define PG8_WAIT_L(n) asm volatile("s_waitcnt lgkmcnt(" #n ")" ::: "memory")
; #define PG8_BAR __builtin_amdgcn_s_barrier()
; #define PG8_SCHED __builtin_amdgcn_sched_barrier(0)
;     __device__ bool next(int i, pg8::Unit& u) const { if (i != 0 || !valid) return false; u.pm = pm; u.pn = pn; return true; }
; template <class Epi, class Sched, bool STAMP = false>
; __device__ __forceinline__ void gemm_phase(PG8_LAS unsigned char* lds, const Gemm g, const Sched& S, const Epi& E, unsigned long long* stamps) {
;     ...
;         const bool has_next = S.next(ui + 1, nxt);
;         const char* nA = has_next ? (const char*)g.A + (size_t)nxt.pm * tstep : cA; const char* nB = has_next ? (const char*)g.Bt + (size_t)nxt.pn * tstep : cB;
;         for (int t = 0; t < nt; t += 2) {
;             const bool last = (t == nt - 2);
;             const char* a1 = cA + (size_t)(t + 1) * kstep;
;             const char* a2 = last ? nA : cA + (size_t)(t + 2) * kstep; const char* b2 = last ? nB : cB + (size_t)(t + 2) * kstep;
;             const char* a3 = a2 + kstep; const char* b3 = b2 + kstep;
;             if (last && has_next) S.a_ready(nxt);
;             PG8_LDB(B0, 0, 0); PG8_SCHED; PG8_LDA(At, 0, 0); PG8_STAGE(PG8_SA(1, 1), a1 + hstep, voffA);
;             PG8_WAIT_L(8); PG8_BAR; PG8_WAIT_L(0); PG8_MMA(0, 0, At, B0); PG8_BAR; PG8_SCHED;
;     ...
; #pragma unroll
;         for (int a = 0; a < 2; ++a)
; #pragma unroll
;             for (int b = 0; b < 2; ++b)
; #pragma unroll
;                 for (int m = 0; m < 4; ++m)
; #pragma unroll
;                     for (int n = 0; n < 2; ++n) acc[a][b][m][n] = (f32x4){0.f, 0.f, 0.f, 0.f};
.LBB0_140:
	s_ashr_i32 s23, s22, 31
	s_lshl_b64 s[14:15], s[22:23], 19
	v_cmp_lt_i64_e32 vcc, s[24:25], v[136:137]
	s_add_u32 s24, s60, s14
	s_addc_u32 s25, s61, s15
	s_and_b64 s[14:15], vcc, exec
	s_cselect_b32 s23, s25, s45
	s_cselect_b32 s31, s24, s44
	s_ashr_i32 s21, s20, 31
	s_lshl_b64 s[14:15], s[20:21], 19
	s_add_u32 s26, s62, s14
	s_addc_u32 s27, s63, s15
	s_and_b64 s[14:15], vcc, exec
	s_cselect_b32 s21, s27, s49
	s_cselect_b32 vcc_lo, s26, s48
	s_add_u32 vcc_hi, s48, 0x100
	v_mov_b32_e32 v0, 0
	s_addc_u32 s38, s49, 0
	s_mov_b32 s39, -2
	s_waitcnt lgkmcnt(0)
	v_mov_b32_e32 v1, v0
	v_mov_b32_e32 v2, v0
	v_mov_b32_e32 v3, v0
	v_mov_b32_e32 v4, v0
	v_mov_b32_e32 v5, v0
	v_mov_b32_e32 v6, v0
	v_mov_b32_e32 v7, v0
	v_mov_b32_e32 v16, v0
	v_mov_b32_e32 v17, v0
	v_mov_b32_e32 v18, v0
	v_mov_b32_e32 v19, v0
	v_mov_b32_e32 v20, v0
	v_mov_b32_e32 v21, v0
	v_mov_b32_e32 v22, v0
	v_mov_b32_e32 v23, v0
	v_mov_b32_e32 v32, v0
	v_mov_b32_e32 v33, v0
	v_mov_b32_e32 v34, v0
	v_mov_b32_e32 v35, v0
	v_mov_b32_e32 v36, v0
	v_mov_b32_e32 v37, v0
	v_mov_b32_e32 v38, v0
	v_mov_b32_e32 v39, v0
	v_mov_b32_e32 v48, v0
	v_mov_b32_e32 v49, v0
	v_mov_b32_e32 v50, v0
	v_mov_b32_e32 v51, v0
	v_mov_b32_e32 v52, v0
	v_mov_b32_e32 v53, v0
	v_mov_b32_e32 v54, v0
	v_mov_b32_e32 v55, v0
	v_mov_b32_e32 v8, v0
	v_mov_b32_e32 v9, v0
	v_mov_b32_e32 v10, v0
	v_mov_b32_e32 v11, v0
	v_mov_b32_e32 v12, v0
	v_mov_b32_e32 v13, v0
	v_mov_b32_e32 v14, v0
	v_mov_b32_e32 v15, v0
	v_mov_b32_e32 v24, v0
	v_mov_b32_e32 v25, v0
	v_mov_b32_e32 v26, v0
	v_mov_b32_e32 v27, v0
	v_mov_b32_e32 v28, v0
	v_mov_b32_e32 v29, v0
	v_mov_b32_e32 v30, v0
	v_mov_b32_e32 v31, v0
	v_mov_b32_e32 v40, v0
	v_mov_b32_e32 v41, v0
	v_mov_b32_e32 v42, v0
	v_mov_b32_e32 v43, v0
	v_mov_b32_e32 v44, v0
	v_mov_b32_e32 v45, v0
	v_mov_b32_e32 v46, v0
	v_mov_b32_e32 v47, v0
	v_mov_b32_e32 v56, v0
	v_mov_b32_e32 v57, v0
	v_mov_b32_e32 v58, v0
	v_mov_b32_e32 v59, v0
	v_mov_b32_e32 v60, v0
	v_mov_b32_e32 v61, v0
	v_mov_b32_e32 v62, v0
	v_mov_b32_e32 v63, v0
	v_mov_b32_e32 v64, v0
	v_mov_b32_e32 v65, v0
	v_mov_b32_e32 v66, v0
	v_mov_b32_e32 v67, v0
	v_mov_b32_e32 v68, v0
	v_mov_b32_e32 v69, v0
	v_mov_b32_e32 v70, v0
	v_mov_b32_e32 v71, v0
	v_mov_b32_e32 v80, v0
	v_mov_b32_e32 v81, v0
	v_mov_b32_e32 v82, v0
	v_mov_b32_e32 v83, v0
	v_mov_b32_e32 v84, v0
	v_mov_b32_e32 v85, v0
	v_mov_b32_e32 v86, v0
	v_mov_b32_e32 v87, v0
	v_mov_b32_e32 v96, v0
	v_mov_b32_e32 v97, v0
	v_mov_b32_e32 v98, v0
	v_mov_b32_e32 v99, v0
	v_mov_b32_e32 v100, v0
	v_mov_b32_e32 v101, v0
	v_mov_b32_e32 v102, v0
	v_mov_b32_e32 v103, v0
	v_mov_b32_e32 v112, v0
	v_mov_b32_e32 v113, v0
	v_mov_b32_e32 v114, v0
	v_mov_b32_e32 v115, v0
	v_mov_b32_e32 v116, v0
	v_mov_b32_e32 v117, v0
	v_mov_b32_e32 v118, v0
	v_mov_b32_e32 v119, v0
	v_mov_b32_e32 v72, v0
	v_mov_b32_e32 v73, v0
	v_mov_b32_e32 v74, v0
	v_mov_b32_e32 v75, v0
	v_mov_b32_e32 v76, v0
	v_mov_b32_e32 v77, v0
	v_mov_b32_e32 v78, v0
	v_mov_b32_e32 v79, v0
	v_mov_b32_e32 v88, v0
	v_mov_b32_e32 v89, v0
	v_mov_b32_e32 v90, v0
	v_mov_b32_e32 v91, v0
	v_mov_b32_e32 v92, v0
	v_mov_b32_e32 v93, v0
	v_mov_b32_e32 v94, v0
	v_mov_b32_e32 v95, v0
	v_mov_b32_e32 v104, v0
	v_mov_b32_e32 v105, v0
	v_mov_b32_e32 v106, v0
	v_mov_b32_e32 v107, v0
	v_mov_b32_e32 v108, v0
	v_mov_b32_e32 v109, v0
	v_mov_b32_e32 v110, v0
	v_mov_b32_e32 v111, v0
	v_mov_b32_e32 v120, v0
	v_mov_b32_e32 v121, v0
	v_mov_b32_e32 v122, v0
	v_mov_b32_e32 v123, v0
	v_mov_b32_e32 v124, v0
	v_mov_b32_e32 v125, v0
	v_mov_b32_e32 v126, v0
	v_mov_b32_e32 v127, v0
	v_add_u32_e32 v244, 0x80, v148
	v_add_u32_e32 v245, 0x80, v150
	v_add_u32_e32 v248, 0x10000, v166
	v_add_u32_e32 v249, 0x14000, v166
	v_add_u32_e32 v250, 0x18000, v166
	v_add_u32_e32 v251, 0x1c000, v166
.LBB0_141:
	s_add_u32 s48, s44, 0x100
	s_addc_u32 s49, s45, 0
	s_add_i32 s14, 0, 0x10000
	ds_read_b128 v[156:159], v248
	ds_read_b128 v[160:163], v248 offset:1024
	ds_read_b128 v[170:173], v248 offset:2048
	ds_read_b128 v[174:177], v248 offset:3072
	s_cmp_eq_u32 s39, 12
	s_cselect_b32 s59, s23, s49
	s_cselect_b32 s58, s31, s48
	s_cselect_b32 s57, s21, s38
	s_cselect_b32 s56, vcc_lo, vcc_hi
	s_add_i32 m0, s37, 0xc000
	ds_read_b128 v[178:181], v168
	ds_read_b128 v[192:195], v168 offset:1024
	ds_read_b128 v[196:199], v168 offset:2048
	ds_read_b128 v[200:203], v168 offset:3072
	ds_read_b128 v[204:207], v168 offset:4096
	ds_read_b128 v[208:211], v168 offset:5120
	ds_read_b128 v[212:215], v168 offset:6144
	ds_read_b128 v[216:219], v168 offset:7168
	global_load_lds_dwordx4 v152, s[44:45]
	s_add_i32 m0, s37, 0xe000
	s_nop 0
	global_load_lds_dwordx4 v154, s[44:45]
	s_waitcnt lgkmcnt(8)
	s_barrier
	s_waitcnt lgkmcnt(0)
	v_mfma_f32_16x16x32_bf16 v[124:127], v[156:159], v[178:181], v[124:127]
	v_mfma_f32_16x16x32_bf16 v[120:123], v[170:173], v[178:181], v[120:123]
	v_mfma_f32_16x16x32_bf16 v[108:111], v[156:159], v[196:199], v[108:111]
	v_mfma_f32_16x16x32_bf16 v[104:107], v[170:173], v[196:199], v[104:107]
	v_mfma_f32_16x16x32_bf16 v[92:95], v[156:159], v[204:207], v[92:95]
	v_mfma_f32_16x16x32_bf16 v[88:91], v[170:173], v[204:207], v[88:91]
	v_mfma_f32_16x16x32_bf16 v[76:79], v[156:159], v[212:215], v[76:79]
	v_mfma_f32_16x16x32_bf16 v[72:75], v[170:173], v[212:215], v[72:75]
	v_mfma_f32_16x16x32_bf16 v[124:127], v[160:163], v[192:195], v[124:127]
	v_mfma_f32_16x16x32_bf16 v[120:123], v[174:177], v[192:195], v[120:123]
	v_mfma_f32_16x16x32_bf16 v[108:111], v[160:163], v[200:203], v[108:111]
	v_mfma_f32_16x16x32_bf16 v[104:107], v[174:177], v[200:203], v[104:107]
	v_mfma_f32_16x16x32_bf16 v[92:95], v[160:163], v[208:211], v[92:95]
	v_mfma_f32_16x16x32_bf16 v[88:91], v[174:177], v[208:211], v[88:91]
	v_mfma_f32_16x16x32_bf16 v[76:79], v[160:163], v[216:219], v[76:79]
	v_mfma_f32_16x16x32_bf16 v[72:75], v[174:177], v[216:219], v[72:75]
	s_barrier
; #define PG8_STAGE(bufoff, gbase, voff) do { _Pragma("unroll") for (int _i = 0; _i < 2; ++_i) \
;         __builtin_amdgcn_global_load_lds((const unsigned*)((const char*)(gbase) + (voff)[_i]), (PG8_LAS unsigned*)(lds + (bufoff) + ldsw + _i * 8192), 16, 0, 0); } while (0)
; #define PG8_LDA(dst, b, h) do { _Pragma("unroll") for (int m = 0; m < 4; ++m) _Pragma("unroll") for (int k = 0; k < 2; ++k) dst[m][k] = *(const PG8_LAS bf16x8*)(lds + PG8_SA(b, h) + aoff + m * 2048 + k * 1024); } while (0)
; #define PG8_LDB(dst, b, h) do { _Pragma("unroll") for (int n = 0; n < 2; ++n) _Pragma("unroll") for (int k = 0; k < 2; ++k) dst[n][k] = *(const PG8_LAS bf16x8*)(lds + PG8_SB(b, h) + boff + n * 2048 + k * 1024); } while (0)
; #define PG8_MMA(ai, bj, At, Bt) do { __builtin_amdgcn_s_setprio(1); _Pragma("unroll") for (int m = 0; m < 4; ++m) _Pragma("unroll") for (int n = 0; n < 2; ++n) _Pragma("unroll") for (int k = 0; k < 2; ++k) \
;         acc[ai][bj][m][n] = __builtin_amdgcn_mfma_f32_16x16x32_bf16(Bt[n][k], At[m][k], acc[ai][bj][m][n], 0, 0, 0); __builtin_amdgcn_s_setprio(0); } while (0)
; #define PG8_WAIT_V(n) asm volatile("s_waitcnt vmcnt(" #n ")" ::: "memory")
; #define PG8_WAIT_L(n) asm volatile("s_waitcnt lgkmcnt(" #n ")" ::: "memory")
; #define PG8_BAR __builtin_amdgcn_s_barrier()
; #define PG8_SCHED __builtin_amdgcn_sched_barrier(0)
; template <class Epi, class Sched, bool STAMP = false>
; __device__ __forceinline__ void gemm_phase(PG8_LAS unsigned char* lds, const Gemm g, const Sched& S, const Epi& E, unsigned long long* stamps) {
;     ...
;             PG8_LDB(B1, 0, 1); PG8_STAGE(PG8_SB(0, 0), b2, voffB);
;             PG8_BAR; PG8_WAIT_L(0); PG8_MMA(0, 1, At, B1); PG8_BAR;
;             PG8_LDA(At, 0, 1); PG8_STAGE(PG8_SA(0, 0), a2, voffA);
;             PG8_BAR; PG8_WAIT_L(0); PG8_MMA(1, 0, At, B0); PG8_BAR; PG8_SCHED;
;             PG8_STAGE(PG8_SB(0, 1), b2 + hstep, voffB);
;             PG8_WAIT_V(6); PG8_BAR; PG8_MMA(1, 1, At, B1); PG8_BAR;
;             PG8_LDB(B0, 1, 0); PG8_SCHED; PG8_LDA(At, 1, 0); PG8_STAGE(PG8_SA(0, 1), a2 + hstep, voffA);
;             PG8_WAIT_L(8); PG8_BAR; PG8_WAIT_L(0); PG8_MMA(0, 0, At, B0); PG8_BAR; PG8_SCHED;
	s_add_i32 s16, 0, 0x14000
	s_add_i32 s14, s14, s64
	s_mov_b32 m0, s14
	ds_read_b128 v[220:223], v249
	ds_read_b128 v[224:227], v249 offset:1024
	ds_read_b128 v[228:231], v249 offset:2048
	ds_read_b128 v[232:235], v249 offset:3072
	global_load_lds_dwordx4 v148, s[56:57]
	s_add_i32 m0, s14, 0x2000
	s_nop 0
	global_load_lds_dwordx4 v150, s[56:57]
	s_barrier
	s_waitcnt lgkmcnt(0)
	v_mfma_f32_16x16x32_bf16 v[116:119], v[220:223], v[178:181], v[116:119]
	v_mfma_f32_16x16x32_bf16 v[112:115], v[228:231], v[178:181], v[112:115]
	v_mfma_f32_16x16x32_bf16 v[100:103], v[220:223], v[196:199], v[100:103]
	v_mfma_f32_16x16x32_bf16 v[96:99], v[228:231], v[196:199], v[96:99]
	v_mfma_f32_16x16x32_bf16 v[84:87], v[220:223], v[204:207], v[84:87]
	v_mfma_f32_16x16x32_bf16 v[80:83], v[228:231], v[204:207], v[80:83]
	v_mfma_f32_16x16x32_bf16 v[68:71], v[220:223], v[212:215], v[68:71]
	v_mfma_f32_16x16x32_bf16 v[64:67], v[228:231], v[212:215], v[64:67]
	v_mfma_f32_16x16x32_bf16 v[116:119], v[224:227], v[192:195], v[116:119]
	v_mfma_f32_16x16x32_bf16 v[112:115], v[232:235], v[192:195], v[112:115]
	v_mfma_f32_16x16x32_bf16 v[100:103], v[224:227], v[200:203], v[100:103]
	v_mfma_f32_16x16x32_bf16 v[96:99], v[232:235], v[200:203], v[96:99]
	v_mfma_f32_16x16x32_bf16 v[84:87], v[224:227], v[208:211], v[84:87]
	v_mfma_f32_16x16x32_bf16 v[80:83], v[232:235], v[208:211], v[80:83]
	v_mfma_f32_16x16x32_bf16 v[68:71], v[224:227], v[216:219], v[68:71]
	v_mfma_f32_16x16x32_bf16 v[64:67], v[232:235], v[216:219], v[64:67]
	s_mov_b32 m0, s37
	s_barrier
	ds_read_b128 v[178:181], v168 offset:16384
	ds_read_b128 v[192:195], v168 offset:17408
	ds_read_b128 v[196:199], v168 offset:18432
	ds_read_b128 v[200:203], v168 offset:19456
	ds_read_b128 v[204:207], v168 offset:20480
	ds_read_b128 v[208:211], v168 offset:21504
	ds_read_b128 v[212:215], v168 offset:22528
	ds_read_b128 v[216:219], v168 offset:23552
	global_load_lds_dwordx4 v148, s[58:59]
	s_mov_b32 m0, s65
	s_nop 0
	global_load_lds_dwordx4 v150, s[58:59]
	s_barrier
	s_waitcnt lgkmcnt(0)
	v_mfma_f32_16x16x32_bf16 v[60:63], v[156:159], v[178:181], v[60:63]
	v_mfma_f32_16x16x32_bf16 v[56:59], v[170:173], v[178:181], v[56:59]
	v_mfma_f32_16x16x32_bf16 v[44:47], v[156:159], v[196:199], v[44:47]
	v_mfma_f32_16x16x32_bf16 v[40:43], v[170:173], v[196:199], v[40:43]
	v_mfma_f32_16x16x32_bf16 v[28:31], v[156:159], v[204:207], v[28:31]
	v_mfma_f32_16x16x32_bf16 v[24:27], v[170:173], v[204:207], v[24:27]
	v_mfma_f32_16x16x32_bf16 v[12:15], v[156:159], v[212:215], v[12:15]
	v_mfma_f32_16x16x32_bf16 v[8:11], v[170:173], v[212:215], v[8:11]
	v_mfma_f32_16x16x32_bf16 v[60:63], v[160:163], v[192:195], v[60:63]
	v_mfma_f32_16x16x32_bf16 v[56:59], v[174:177], v[192:195], v[56:59]
	v_mfma_f32_16x16x32_bf16 v[44:47], v[160:163], v[200:203], v[44:47]
	v_mfma_f32_16x16x32_bf16 v[40:43], v[174:177], v[200:203], v[40:43]
	v_mfma_f32_16x16x32_bf16 v[28:31], v[160:163], v[208:211], v[28:31]
	v_mfma_f32_16x16x32_bf16 v[24:27], v[174:177], v[208:211], v[24:27]
	v_mfma_f32_16x16x32_bf16 v[12:15], v[160:163], v[216:219], v[12:15]
	v_mfma_f32_16x16x32_bf16 v[8:11], v[174:177], v[216:219], v[8:11]
	s_barrier
	s_add_u32 s14, s56, 0x40000
	s_addc_u32 s15, s57, 0
	s_add_i32 s16, s16, s64
	s_mov_b32 m0, s16
	s_nop 0
	global_load_lds_dwordx4 v148, s[14:15]
	s_add_i32 m0, s16, 0x2000
	s_nop 0
	global_load_lds_dwordx4 v150, s[14:15]
	s_waitcnt vmcnt(6)
	s_barrier
	v_mfma_f32_16x16x32_bf16 v[52:55], v[220:223], v[178:181], v[52:55]
	v_mfma_f32_16x16x32_bf16 v[48:51], v[228:231], v[178:181], v[48:51]
	v_mfma_f32_16x16x32_bf16 v[36:39], v[220:223], v[196:199], v[36:39]
	v_mfma_f32_16x16x32_bf16 v[32:35], v[228:231], v[196:199], v[32:35]
	v_mfma_f32_16x16x32_bf16 v[20:23], v[220:223], v[204:207], v[20:23]
	v_mfma_f32_16x16x32_bf16 v[16:19], v[228:231], v[204:207], v[16:19]
	v_mfma_f32_16x16x32_bf16 v[4:7], v[220:223], v[212:215], v[4:7]
	v_mfma_f32_16x16x32_bf16 v[0:3], v[228:231], v[212:215], v[0:3]
	v_mfma_f32_16x16x32_bf16 v[52:55], v[224:227], v[192:195], v[52:55]
	v_mfma_f32_16x16x32_bf16 v[48:51], v[232:235], v[192:195], v[48:51]
	v_mfma_f32_16x16x32_bf16 v[36:39], v[224:227], v[200:203], v[36:39]
	v_mfma_f32_16x16x32_bf16 v[32:35], v[232:235], v[200:203], v[32:35]
	v_mfma_f32_16x16x32_bf16 v[20:23], v[224:227], v[208:211], v[20:23]
	v_mfma_f32_16x16x32_bf16 v[16:19], v[232:235], v[208:211], v[16:19]
	v_mfma_f32_16x16x32_bf16 v[4:7], v[224:227], v[216:219], v[4:7]
	v_mfma_f32_16x16x32_bf16 v[0:3], v[232:235], v[216:219], v[0:3]
	s_add_i32 s16, 0, 0x18000
	s_barrier
	ds_read_b128 v[156:159], v250
	ds_read_b128 v[160:163], v250 offset:1024
	ds_read_b128 v[170:173], v250 offset:2048
	ds_read_b128 v[174:177], v250 offset:3072
	s_add_u32 s14, s58, 0x40000
	s_addc_u32 s15, s59, 0
	s_mov_b32 m0, s76
	ds_read_b128 v[178:181], v168 offset:32768
	ds_read_b128 v[192:195], v168 offset:33792
	ds_read_b128 v[196:199], v168 offset:34816
	ds_read_b128 v[200:203], v168 offset:35840
	ds_read_b128 v[204:207], v168 offset:36864
	ds_read_b128 v[208:211], v168 offset:37888
	ds_read_b128 v[212:215], v168 offset:38912
	ds_read_b128 v[216:219], v168 offset:39936
	global_load_lds_dwordx4 v148, s[14:15]
	s_mov_b32 m0, s77
	s_nop 0
	global_load_lds_dwordx4 v150, s[14:15]
	s_waitcnt lgkmcnt(8)
	s_barrier
; #define PG8_STAGE(bufoff, gbase, voff) do { _Pragma("unroll") for (int _i = 0; _i < 2; ++_i) \
;         __builtin_amdgcn_global_load_lds((const unsigned*)((const char*)(gbase) + (voff)[_i]), (PG8_LAS unsigned*)(lds + (bufoff) + ldsw + _i * 8192), 16, 0, 0); } while (0)
; #define PG8_LDA(dst, b, h) do { _Pragma("unroll") for (int m = 0; m < 4; ++m) _Pragma("unroll") for (int k = 0; k < 2; ++k) dst[m][k] = *(const PG8_LAS bf16x8*)(lds + PG8_SA(b, h) + aoff + m * 2048 + k * 1024); } while (0)
; #define PG8_LDB(dst, b, h) do { _Pragma("unroll") for (int n = 0; n < 2; ++n) _Pragma("unroll") for (int k = 0; k < 2; ++k) dst[n][k] = *(const PG8_LAS bf16x8*)(lds + PG8_SB(b, h) + boff + n * 2048 + k * 1024); } while (0)
; #define PG8_WAIT_V(n) asm volatile("s_waitcnt vmcnt(" #n ")" ::: "memory")
; #define PG8_WAIT_L(n) asm volatile("s_waitcnt lgkmcnt(" #n ")" ::: "memory")
; #define PG8_BAR __builtin_amdgcn_s_barrier()
; #define PG8_SCHED __builtin_amdgcn_sched_barrier(0)
; template <class Epi, class Sched, bool STAMP = false>
; __device__ __forceinline__ void gemm_phase(PG8_LAS unsigned char* lds, const Gemm g, const Sched& S, const Epi& E, unsigned long long* stamps) {
;     ...
;             PG8_WAIT_L(8); PG8_BAR; PG8_WAIT_L(0); PG8_MMA(0, 0, At, B0); PG8_BAR; PG8_SCHED;
;             PG8_LDB(B1, 1, 1); PG8_STAGE(PG8_SB(1, 0), b3, voffB);
;             PG8_BAR; PG8_WAIT_L(0); PG8_MMA(0, 1, At, B1); PG8_BAR;
;             PG8_LDA(At, 1, 1); PG8_STAGE(PG8_SA(1, 0), a3, voffA);
;             PG8_BAR; PG8_WAIT_L(0); PG8_MMA(1, 0, At, B0); PG8_BAR; PG8_SCHED;
;             PG8_STAGE(PG8_SB(1, 1), b3 + hstep, voffB);
;             PG8_WAIT_V(6); PG8_BAR; PG8_MMA(1, 1, At, B1); PG8_BAR;
;     __device__ __forceinline__ void operator()(const f32x4 (&acc)[2][2][4][2], const pg8::Unit& u, int wr, int wc, int fr, int fq) const {
;         const int row0 = u.pm * 256 + wr * 64 + fr, col0 = u.pn * 256 + wc * 32 + 4 * fq;
; #pragma unroll
;         for (int ai = 0; ai < 2; ++ai)
; #pragma unroll
;             for (int m = 0; m < 4; ++m) {
;                 const int row = row0 + ai * 128 + m * 16;
;                 float* xp = X + (size_t)row * 1024 + col0; bf16_t* bp = XB + (size_t)row * 1024 + col0;
;                 const float* xi = Xp0 ? (row < T_P ? Xp0 + (size_t)row * 1024 + col0 : Xs0 + (size_t)(row - T_P) * 1024 + col0) : xp;
	s_waitcnt lgkmcnt(0)
	v_mfma_f32_16x16x32_bf16 v[124:127], v[156:159], v[178:181], v[124:127]
	v_mfma_f32_16x16x32_bf16 v[120:123], v[170:173], v[178:181], v[120:123]
	v_mfma_f32_16x16x32_bf16 v[108:111], v[156:159], v[196:199], v[108:111]
	v_mfma_f32_16x16x32_bf16 v[104:107], v[170:173], v[196:199], v[104:107]
	v_mfma_f32_16x16x32_bf16 v[92:95], v[156:159], v[204:207], v[92:95]
	v_mfma_f32_16x16x32_bf16 v[88:91], v[170:173], v[204:207], v[88:91]
	v_mfma_f32_16x16x32_bf16 v[76:79], v[156:159], v[212:215], v[76:79]
	v_mfma_f32_16x16x32_bf16 v[72:75], v[170:173], v[212:215], v[72:75]
	v_mfma_f32_16x16x32_bf16 v[124:127], v[160:163], v[192:195], v[124:127]
	v_mfma_f32_16x16x32_bf16 v[120:123], v[174:177], v[192:195], v[120:123]
	v_mfma_f32_16x16x32_bf16 v[108:111], v[160:163], v[200:203], v[108:111]
	v_mfma_f32_16x16x32_bf16 v[104:107], v[174:177], v[200:203], v[104:107]
	v_mfma_f32_16x16x32_bf16 v[92:95], v[160:163], v[208:211], v[92:95]
	v_mfma_f32_16x16x32_bf16 v[88:91], v[174:177], v[208:211], v[88:91]
	v_mfma_f32_16x16x32_bf16 v[76:79], v[160:163], v[216:219], v[76:79]
	v_mfma_f32_16x16x32_bf16 v[72:75], v[174:177], v[216:219], v[72:75]
	s_barrier
	s_add_i32 s17, 0, 0x1c000
	s_add_i32 s14, s16, s64
	s_mov_b32 m0, s14
	ds_read_b128 v[220:223], v251
	ds_read_b128 v[224:227], v251 offset:1024
	ds_read_b128 v[228:231], v251 offset:2048
	ds_read_b128 v[232:235], v251 offset:3072
	global_load_lds_dwordx4 v244, s[56:57]
	s_add_i32 m0, s14, 0x2000
	s_nop 0
	global_load_lds_dwordx4 v245, s[56:57]
	s_barrier
	s_waitcnt lgkmcnt(0)
	v_mfma_f32_16x16x32_bf16 v[116:119], v[220:223], v[178:181], v[116:119]
	v_mfma_f32_16x16x32_bf16 v[112:115], v[228:231], v[178:181], v[112:115]
	v_mfma_f32_16x16x32_bf16 v[100:103], v[220:223], v[196:199], v[100:103]
	v_mfma_f32_16x16x32_bf16 v[96:99], v[228:231], v[196:199], v[96:99]
	v_mfma_f32_16x16x32_bf16 v[84:87], v[220:223], v[204:207], v[84:87]
	v_mfma_f32_16x16x32_bf16 v[80:83], v[228:231], v[204:207], v[80:83]
	v_mfma_f32_16x16x32_bf16 v[68:71], v[220:223], v[212:215], v[68:71]
	v_mfma_f32_16x16x32_bf16 v[64:67], v[228:231], v[212:215], v[64:67]
	v_mfma_f32_16x16x32_bf16 v[116:119], v[224:227], v[192:195], v[116:119]
	v_mfma_f32_16x16x32_bf16 v[112:115], v[232:235], v[192:195], v[112:115]
	v_mfma_f32_16x16x32_bf16 v[100:103], v[224:227], v[200:203], v[100:103]
	v_mfma_f32_16x16x32_bf16 v[96:99], v[232:235], v[200:203], v[96:99]
	v_mfma_f32_16x16x32_bf16 v[84:87], v[224:227], v[208:211], v[84:87]
	v_mfma_f32_16x16x32_bf16 v[80:83], v[232:235], v[208:211], v[80:83]
	v_mfma_f32_16x16x32_bf16 v[68:71], v[224:227], v[216:219], v[68:71]
	v_mfma_f32_16x16x32_bf16 v[64:67], v[232:235], v[216:219], v[64:67]
	s_mov_b32 m0, s88
	s_barrier
	ds_read_b128 v[178:181], v168 offset:49152
	ds_read_b128 v[192:195], v168 offset:50176
	ds_read_b128 v[196:199], v168 offset:51200
	ds_read_b128 v[200:203], v168 offset:52224
	ds_read_b128 v[204:207], v168 offset:53248
	ds_read_b128 v[208:211], v168 offset:54272
	ds_read_b128 v[212:215], v168 offset:55296
	ds_read_b128 v[216:219], v168 offset:56320
	global_load_lds_dwordx4 v244, s[58:59]
	s_mov_b32 m0, s89
	s_nop 0
	global_load_lds_dwordx4 v245, s[58:59]
	s_barrier
	s_waitcnt lgkmcnt(0)
	v_mfma_f32_16x16x32_bf16 v[60:63], v[156:159], v[178:181], v[60:63]
	v_mfma_f32_16x16x32_bf16 v[56:59], v[170:173], v[178:181], v[56:59]
	v_mfma_f32_16x16x32_bf16 v[44:47], v[156:159], v[196:199], v[44:47]
	v_mfma_f32_16x16x32_bf16 v[40:43], v[170:173], v[196:199], v[40:43]
	v_mfma_f32_16x16x32_bf16 v[28:31], v[156:159], v[204:207], v[28:31]
	v_mfma_f32_16x16x32_bf16 v[24:27], v[170:173], v[204:207], v[24:27]
	v_mfma_f32_16x16x32_bf16 v[12:15], v[156:159], v[212:215], v[12:15]
	v_mfma_f32_16x16x32_bf16 v[8:11], v[170:173], v[212:215], v[8:11]
	v_mfma_f32_16x16x32_bf16 v[60:63], v[160:163], v[192:195], v[60:63]
	v_mfma_f32_16x16x32_bf16 v[56:59], v[174:177], v[192:195], v[56:59]
	v_mfma_f32_16x16x32_bf16 v[44:47], v[160:163], v[200:203], v[44:47]
	v_mfma_f32_16x16x32_bf16 v[40:43], v[174:177], v[200:203], v[40:43]
	v_mfma_f32_16x16x32_bf16 v[28:31], v[160:163], v[208:211], v[28:31]
	v_mfma_f32_16x16x32_bf16 v[24:27], v[174:177], v[208:211], v[24:27]
	v_mfma_f32_16x16x32_bf16 v[12:15], v[160:163], v[216:219], v[12:15]
	v_mfma_f32_16x16x32_bf16 v[8:11], v[174:177], v[216:219], v[8:11]
	s_barrier
	s_add_u32 s14, s56, 0x40080
	s_addc_u32 s15, s57, 0
	s_add_i32 s16, s17, s64
	s_mov_b32 m0, s16
	s_nop 0
	global_load_lds_dwordx4 v148, s[14:15]
	s_add_i32 m0, s16, 0x2000
	s_nop 0
	global_load_lds_dwordx4 v150, s[14:15]
	s_waitcnt vmcnt(6)
	s_barrier
	v_mfma_f32_16x16x32_bf16 v[52:55], v[220:223], v[178:181], v[52:55]
	v_mfma_f32_16x16x32_bf16 v[48:51], v[228:231], v[178:181], v[48:51]
	v_mfma_f32_16x16x32_bf16 v[36:39], v[220:223], v[196:199], v[36:39]
	v_mfma_f32_16x16x32_bf16 v[32:35], v[228:231], v[196:199], v[32:35]
	v_mfma_f32_16x16x32_bf16 v[20:23], v[220:223], v[204:207], v[20:23]
	v_mfma_f32_16x16x32_bf16 v[16:19], v[228:231], v[204:207], v[16:19]
	v_mfma_f32_16x16x32_bf16 v[4:7], v[220:223], v[212:215], v[4:7]
	v_mfma_f32_16x16x32_bf16 v[0:3], v[228:231], v[212:215], v[0:3]
	v_mfma_f32_16x16x32_bf16 v[52:55], v[224:227], v[192:195], v[52:55]
	v_mfma_f32_16x16x32_bf16 v[48:51], v[232:235], v[192:195], v[48:51]
	v_mfma_f32_16x16x32_bf16 v[36:39], v[224:227], v[200:203], v[36:39]
	v_mfma_f32_16x16x32_bf16 v[32:35], v[232:235], v[200:203], v[32:35]
	v_mfma_f32_16x16x32_bf16 v[20:23], v[224:227], v[208:211], v[20:23]
	v_mfma_f32_16x16x32_bf16 v[16:19], v[232:235], v[208:211], v[16:19]
	v_mfma_f32_16x16x32_bf16 v[4:7], v[224:227], v[216:219], v[4:7]
	v_mfma_f32_16x16x32_bf16 v[0:3], v[232:235], v[216:219], v[0:3]
	s_add_i32 s39, s39, 2
	s_add_u32 vcc_hi, vcc_hi, 0x100
	s_addc_u32 s38, s38, 0
	s_cmp_gt_u32 s39, 13
	s_mov_b64 s[44:45], s[48:49]
	s_barrier
	s_cbranch_scc0 .LBB0_141
	v_lshl_add_u32 v158, s30, 8, v139
	v_ashrrev_i32_e32 v159, 31, v158
	v_lshl_or_b32 v156, s36, 8, v167
	v_lshlrev_b64 v[160:161], 12, v[158:159]
	v_ashrrev_i32_e32 v157, 31, v156
	v_lshl_add_u64 v[160:161], s[84:85], 0, v[160:161]
	v_lshl_add_u64 v[160:161], v[156:157], 2, v[160:161]
	v_cndmask_b32_e64 v128, 0, 1, s[12:13]
	v_lshlrev_b64 v[164:165], 10, v[158:159]
	v_cmp_ne_u32_e64 s[44:45], 1, v128
	s_andn2_b64 vcc, exec, s[12:13]
	v_mov_b64_e32 v[162:163], v[160:161]
	v_readlane_b32 s39, v242, 28
	s_movk_i32 s21, 0x3fff
	s_mov_b32 s38, 0x1ffff
	s_cbranch_vccnz .LBB0_148
	v_cmp_lt_i32_e32 vcc, s21, v158
	s_and_saveexec_b64 s[14:15], vcc
	s_xor_b64 s[30:31], exec, s[14:15]
	v_add_u32_e32 v128, 0xffffc000, v158
	v_lshlrev_b64 v[162:163], 12, v[128:129]
	v_lshl_add_u64 v[162:163], s[4:5], 0, v[162:163]
	v_lshl_add_u64 v[162:163], v[156:157], 2, v[162:163]
	s_andn2_saveexec_b64 s[30:31], s[30:31]
	v_lshl_add_u64 v[162:163], v[164:165], 2, s[0:1]
	v_lshl_add_u64 v[162:163], v[156:157], 2, v[162:163]
	s_or_b64 exec, exec, s[30:31]

; #define PG8_STAGE(bufoff, gbase, voff) do { _Pragma("unroll") for (int _i = 0; _i < 2; ++_i) \
;         __builtin_amdgcn_global_load_lds((const unsigned*)((const char*)(gbase) + (voff)[_i]), (PG8_LAS unsigned*)(lds + (bufoff) + ldsw + _i * 8192), 16, 0, 0); } while (0)
; #define PG8_WAIT_V(n) asm volatile("s_waitcnt vmcnt(" #n ")" ::: "memory")
; #define PG8_BAR __builtin_amdgcn_s_barrier()
; template <class Epi, class Sched, bool STAMP = false>
; __device__ __forceinline__ void gemm_phase(PG8_LAS unsigned char* lds, const Gemm g, const Sched& S, const Epi& E, unsigned long long* stamps) {
;     ...
;     f32x4 acc[2][2][4][2];
; #pragma unroll
;     for (int a = 0; a < 2; ++a)
; #pragma unroll
;         for (int b = 0; b < 2; ++b)
; #pragma unroll
;             for (int m = 0; m < 4; ++m)
; #pragma unroll
;                 for (int n = 0; n < 2; ++n) acc[a][b][m][n] = (f32x4){0.f, 0.f, 0.f, 0.f};
;     ...
;     PG8_STAGE(PG8_SB(0, 0), cB, voffB); PG8_STAGE(PG8_SA(0, 0), cA, voffA); PG8_STAGE(PG8_SB(0, 1), cB + hstep, voffB); PG8_STAGE(PG8_SA(0, 1), cA + hstep, voffA);
;     if (wr == 1) PG8_BAR;
;     PG8_WAIT_V(4); PG8_BAR;
;     PG8_STAGE(PG8_SB(1, 0), cB + kstep, voffB); PG8_STAGE(PG8_SA(1, 0), cA + kstep, voffA); PG8_STAGE(PG8_SB(1, 1), cB + hstep + kstep, voffB);
;     PG8_WAIT_V(6); PG8_BAR;
.LBB0_212:
	v_bfe_u32 v139, v0, 4, 2
	s_lshl_b32 s12, s12, 5
	v_and_b32_e32 v150, 15, v0
	v_lshlrev_b32_e32 v1, 4, v139
	v_lshlrev_b32_e32 v0, 2, v0
	s_and_b32 s56, s12, 0x60
	v_lshl_add_u64 v[2:3], s[0:1], 0, v[128:129]
	v_mov_b32_e32 v149, v129
	s_lshl_b32 s53, s13, 6
	v_lshl_or_b32 v1, v150, 6, v1
	s_lshl_b32 s13, s13, 13
	v_and_b32_e32 v0, 32, v0
	s_lshl_b32 s12, s56, 7
	v_lshl_add_u64 v[4:5], s[0:1], 0, v[148:149]
	v_bitop3_b32 v10, v1, s13, v0 bitop3:0xde
	v_bitop3_b32 v151, v1, s12, v0 bitop3:0xde
	s_add_i32 m0, s45, 0x18000
	v_lshl_add_u64 v[0:1], v[2:3], 0, s[18:19]
	v_lshl_add_u64 v[6:7], s[4:5], 0, v[128:129]
	s_waitcnt vmcnt(4)
	s_barrier
	global_load_lds_dwordx4 v[0:1], off
	v_lshl_add_u64 v[0:1], v[4:5], 0, s[18:19]
	s_add_i32 m0, s45, 0x1a000
	s_add_i32 s57, s45, 0x8000
	s_add_i32 s58, s45, 0xa000
	v_lshl_add_u64 v[8:9], s[4:5], 0, v[148:149]
	global_load_lds_dwordx4 v[0:1], off
	v_lshl_add_u64 v[0:1], v[6:7], 0, s[18:19]
	s_mov_b32 m0, s57
	s_add_u32 s12, s0, 0x40080
	global_load_lds_dwordx4 v[0:1], off
	v_lshl_add_u64 v[0:1], v[8:9], 0, s[18:19]
	s_mov_b32 m0, s58
	s_addc_u32 s13, s1, 0
	global_load_lds_dwordx4 v[0:1], off
	s_add_i32 m0, s45, 0x1c000
	v_lshl_add_u64 v[0:1], s[12:13], 0, v[128:129]
	global_load_lds_dwordx4 v[0:1], off
	v_lshl_add_u64 v[0:1], s[12:13], 0, v[148:149]
	s_add_i32 m0, s45, 0x1e000
	s_mov_b32 s14, 0
	global_load_lds_dwordx4 v[0:1], off
	s_waitcnt vmcnt(6)
	v_mov_b32_e32 v0, 0
	s_mov_b64 s[12:13], -1
	s_mov_b64 s[20:21], 0
	v_add_u32_e32 v152, 0, v10
	v_mov_b32_e32 v1, v0
	v_mov_b32_e32 v2, v0
	v_mov_b32_e32 v3, v0
	v_mov_b32_e32 v4, v0
	v_mov_b32_e32 v5, v0
	v_mov_b32_e32 v6, v0
	v_mov_b32_e32 v7, v0
	v_mov_b32_e32 v8, v0
	v_mov_b32_e32 v9, v0
	v_mov_b32_e32 v10, v0
	v_mov_b32_e32 v11, v0
	v_mov_b32_e32 v12, v0
	v_mov_b32_e32 v13, v0
	v_mov_b32_e32 v14, v0
	v_mov_b32_e32 v15, v0
	v_mov_b32_e32 v24, v0
	v_mov_b32_e32 v25, v0
	v_mov_b32_e32 v26, v0
	v_mov_b32_e32 v27, v0
	v_mov_b32_e32 v28, v0
	v_mov_b32_e32 v29, v0
	v_mov_b32_e32 v30, v0
	v_mov_b32_e32 v31, v0
	v_mov_b32_e32 v40, v0
	v_mov_b32_e32 v41, v0
	v_mov_b32_e32 v42, v0
	v_mov_b32_e32 v43, v0
	v_mov_b32_e32 v44, v0
	v_mov_b32_e32 v45, v0
	v_mov_b32_e32 v46, v0
	v_mov_b32_e32 v47, v0
	v_mov_b32_e32 v16, v0
	v_mov_b32_e32 v17, v0
	v_mov_b32_e32 v18, v0
	v_mov_b32_e32 v19, v0
	v_mov_b32_e32 v20, v0
	v_mov_b32_e32 v21, v0
	v_mov_b32_e32 v22, v0
	v_mov_b32_e32 v23, v0
	v_mov_b32_e32 v32, v0
	v_mov_b32_e32 v33, v0
	v_mov_b32_e32 v34, v0
	v_mov_b32_e32 v35, v0
	v_mov_b32_e32 v36, v0
	v_mov_b32_e32 v37, v0
	v_mov_b32_e32 v38, v0
	v_mov_b32_e32 v39, v0
	v_mov_b32_e32 v48, v0
	v_mov_b32_e32 v49, v0
	v_mov_b32_e32 v50, v0
	v_mov_b32_e32 v51, v0
	v_mov_b32_e32 v52, v0
	v_mov_b32_e32 v53, v0
	v_mov_b32_e32 v54, v0
	v_mov_b32_e32 v55, v0
	v_mov_b32_e32 v56, v0
	v_mov_b32_e32 v57, v0
	v_mov_b32_e32 v58, v0
	v_mov_b32_e32 v59, v0
	v_mov_b32_e32 v60, v0
	v_mov_b32_e32 v61, v0
	v_mov_b32_e32 v62, v0
	v_mov_b32_e32 v63, v0
	v_mov_b32_e32 v64, v0
	v_mov_b32_e32 v65, v0
	v_mov_b32_e32 v66, v0
	v_mov_b32_e32 v67, v0
	v_mov_b32_e32 v68, v0
	v_mov_b32_e32 v69, v0
	v_mov_b32_e32 v70, v0
	v_mov_b32_e32 v71, v0
	v_mov_b32_e32 v72, v0
	v_mov_b32_e32 v73, v0
	v_mov_b32_e32 v74, v0
	v_mov_b32_e32 v75, v0
	v_mov_b32_e32 v76, v0
	v_mov_b32_e32 v77, v0
	v_mov_b32_e32 v78, v0
	v_mov_b32_e32 v79, v0
	v_mov_b32_e32 v84, v0
	v_mov_b32_e32 v85, v0
	v_mov_b32_e32 v86, v0
	v_mov_b32_e32 v87, v0
	v_mov_b32_e32 v92, v0
	v_mov_b32_e32 v93, v0
	v_mov_b32_e32 v94, v0
	v_mov_b32_e32 v95, v0
	v_mov_b32_e32 v100, v0
	v_mov_b32_e32 v101, v0
	v_mov_b32_e32 v102, v0
	v_mov_b32_e32 v103, v0
	v_mov_b32_e32 v108, v0
	v_mov_b32_e32 v109, v0
	v_mov_b32_e32 v110, v0
	v_mov_b32_e32 v111, v0
	v_mov_b32_e32 v80, v0
	v_mov_b32_e32 v81, v0
	v_mov_b32_e32 v82, v0
	v_mov_b32_e32 v83, v0
	v_mov_b32_e32 v88, v0
	v_mov_b32_e32 v89, v0
	v_mov_b32_e32 v90, v0
	v_mov_b32_e32 v91, v0
	v_mov_b32_e32 v96, v0
	v_mov_b32_e32 v97, v0
	v_mov_b32_e32 v98, v0
	v_mov_b32_e32 v99, v0
	v_mov_b32_e32 v104, v0
	v_mov_b32_e32 v105, v0
	v_mov_b32_e32 v106, v0
	v_mov_b32_e32 v107, v0
	v_mov_b32_e32 v112, v0
	v_mov_b32_e32 v113, v0
	v_mov_b32_e32 v114, v0
	v_mov_b32_e32 v115, v0
	v_mov_b32_e32 v116, v0
	v_mov_b32_e32 v117, v0
	v_mov_b32_e32 v118, v0
	v_mov_b32_e32 v119, v0
	v_mov_b32_e32 v120, v0
	v_mov_b32_e32 v121, v0
	v_mov_b32_e32 v122, v0
	v_mov_b32_e32 v123, v0
	v_mov_b32_e32 v124, v0
	v_mov_b32_e32 v125, v0
	v_mov_b32_e32 v126, v0
	v_mov_b32_e32 v127, v0
	s_barrier
	v_add_u32_e32 v244, 0x80, v128
	v_add_u32_e32 v245, 0x80, v148
	v_add_u32_e32 v248, 0x10000, v151
	v_add_u32_e32 v249, 0x14000, v151
	v_add_u32_e32 v250, 0x18000, v151
	v_add_u32_e32 v251, 0x1c000, v151
; #define PG8_STAGE(bufoff, gbase, voff) do { _Pragma("unroll") for (int _i = 0; _i < 2; ++_i) \
;         __builtin_amdgcn_global_load_lds((const unsigned*)((const char*)(gbase) + (voff)[_i]), (PG8_LAS unsigned*)(lds + (bufoff) + ldsw + _i * 8192), 16, 0, 0); } while (0)
; #define PG8_LDA(dst, b, h) do { _Pragma("unroll") for (int m = 0; m < 4; ++m) _Pragma("unroll") for (int k = 0; k < 2; ++k) dst[m][k] = *(const PG8_LAS bf16x8*)(lds + PG8_SA(b, h) + aoff + m * 2048 + k * 1024); } while (0)
; #define PG8_LDB(dst, b, h) do { _Pragma("unroll") for (int n = 0; n < 2; ++n) _Pragma("unroll") for (int k = 0; k < 2; ++k) dst[n][k] = *(const PG8_LAS bf16x8*)(lds + PG8_SB(b, h) + boff + n * 2048 + k * 1024); } while (0)
; #define PG8_MMA(ai, bj, At, Bt) do { __builtin_amdgcn_s_setprio(1); _Pragma("unroll") for (int m = 0; m < 4; ++m) _Pragma("unroll") for (int n = 0; n < 2; ++n) _Pragma("unroll") for (int k = 0; k < 2; ++k) \
;         acc[ai][bj][m][n] = __builtin_amdgcn_mfma_f32_16x16x32_bf16(Bt[n][k], At[m][k], acc[ai][bj][m][n], 0, 0, 0); __builtin_amdgcn_s_setprio(0); } while (0)
; #define PG8_WAIT_L(n) asm volatile("s_waitcnt lgkmcnt(" #n ")" ::: "memory")
; #define PG8_BAR __builtin_amdgcn_s_barrier()
; #define PG8_SCHED __builtin_amdgcn_sched_barrier(0)
; template <class Epi, class Sched, bool STAMP = false>
; __device__ __forceinline__ void gemm_phase(PG8_LAS unsigned char* lds, const Gemm g, const Sched& S, const Epi& E, unsigned long long* stamps) {
;     ...
;         for (int t = 0; t < nt; t += 2) {
;             const bool last = (t == nt - 2);
;             const char* a1 = cA + (size_t)(t + 1) * kstep;
;             const char* a2 = last ? nA : cA + (size_t)(t + 2) * kstep; const char* b2 = last ? nB : cB + (size_t)(t + 2) * kstep;
;             const char* a3 = a2 + kstep; const char* b3 = b2 + kstep;
;             if (last && has_next) S.a_ready(nxt);
;             PG8_LDB(B0, 0, 0); PG8_SCHED; PG8_LDA(At, 0, 0); PG8_STAGE(PG8_SA(1, 1), a1 + hstep, voffA);
;             PG8_WAIT_L(8); PG8_BAR; PG8_WAIT_L(0); PG8_MMA(0, 0, At, B0); PG8_BAR; PG8_SCHED;
;             PG8_LDB(B1, 0, 1); PG8_STAGE(PG8_SB(0, 0), b2, voffB);
;             PG8_BAR; PG8_WAIT_L(0); PG8_MMA(0, 1, At, B1); PG8_BAR;
;             PG8_LDA(At, 0, 1); PG8_STAGE(PG8_SA(0, 0), a2, voffA);
;             PG8_BAR; PG8_WAIT_L(0); PG8_MMA(1, 0, At, B0); PG8_BAR; PG8_SCHED;
.LBB0_213:
	s_add_i32 s15, s14, 0x100
	s_and_b64 s[16:17], s[20:21], exec
	s_cselect_b32 s15, 0, s15
	s_cselect_b32 s16, 0, 0
	s_add_u32 s26, s4, s15
	s_addc_u32 s27, s5, s16
	s_add_i32 s21, 0, 0x10000
	s_add_u32 s30, s0, s15
	s_addc_u32 s31, s1, s16
	s_add_u32 s36, s6, s14
	s_addc_u32 s37, s7, 0
	s_add_i32 s61, s21, s44
	s_add_i32 m0, s45, 0xc000
	s_add_i32 s62, s45, 0xe000
	s_add_i32 s60, 0, 0x14000
	s_add_i32 s59, s61, 0x2000
	s_add_u32 s24, s30, 0x40000
	s_addc_u32 s25, s31, 0
	s_add_i32 s38, s60, s44
	ds_read_b128 v[154:157], v248
	ds_read_b128 v[158:161], v248 offset:1024
	ds_read_b128 v[162:165], v248 offset:2048
	ds_read_b128 v[166:169], v248 offset:3072
	s_add_i32 s29, s38, 0x2000
	s_add_i32 s17, 0, 0x18000
	s_add_u32 s22, s26, 0x40000
	s_addc_u32 s23, s27, 0
	s_add_i32 s16, s17, s44
	s_add_i32 s15, 0, 0x1c000
	s_add_i32 s14, s16, 0x2000
	s_add_u32 s20, s30, 0x40080
	s_addc_u32 s21, s31, 0
	s_add_i32 s52, s15, s44
	s_add_i32 s39, s52, 0x2000
	v_lshl_add_u64 v[182:183], s[36:37], 0, v[128:129]
	v_lshl_add_u64 v[182:183], v[182:183], 0, s[18:19]
	ds_read_b128 v[170:173], v152
	ds_read_b128 v[174:177], v152 offset:1024
	ds_read_b128 v[178:181], v152 offset:2048
	ds_read_b128 v[192:195], v152 offset:3072
	ds_read_b128 v[196:199], v152 offset:4096
	ds_read_b128 v[200:203], v152 offset:5120
	ds_read_b128 v[204:207], v152 offset:6144
	ds_read_b128 v[208:211], v152 offset:7168
	global_load_lds_dwordx4 v244, s[36:37]
	v_lshl_add_u64 v[182:183], s[36:37], 0, v[148:149]
	v_lshl_add_u64 v[182:183], v[182:183], 0, s[18:19]
	s_mov_b32 m0, s62
	s_nop 0
	global_load_lds_dwordx4 v245, s[36:37]
	s_waitcnt lgkmcnt(8)
	s_barrier
	s_waitcnt lgkmcnt(0)
	v_mfma_f32_16x16x32_bf16 v[124:127], v[154:157], v[170:173], v[124:127]
	v_mfma_f32_16x16x32_bf16 v[120:123], v[162:165], v[170:173], v[120:123]
	v_mfma_f32_16x16x32_bf16 v[116:119], v[154:157], v[178:181], v[116:119]
	v_mfma_f32_16x16x32_bf16 v[112:115], v[162:165], v[178:181], v[112:115]
	v_mfma_f32_16x16x32_bf16 v[104:107], v[154:157], v[196:199], v[104:107]
	v_mfma_f32_16x16x32_bf16 v[96:99], v[162:165], v[196:199], v[96:99]
	v_mfma_f32_16x16x32_bf16 v[88:91], v[154:157], v[204:207], v[88:91]
	v_mfma_f32_16x16x32_bf16 v[80:83], v[162:165], v[204:207], v[80:83]
	v_mfma_f32_16x16x32_bf16 v[124:127], v[158:161], v[174:177], v[124:127]
	v_mfma_f32_16x16x32_bf16 v[120:123], v[166:169], v[174:177], v[120:123]
	v_mfma_f32_16x16x32_bf16 v[116:119], v[158:161], v[192:195], v[116:119]
	v_mfma_f32_16x16x32_bf16 v[112:115], v[166:169], v[192:195], v[112:115]
	v_mfma_f32_16x16x32_bf16 v[104:107], v[158:161], v[200:203], v[104:107]
	v_mfma_f32_16x16x32_bf16 v[96:99], v[166:169], v[200:203], v[96:99]
	v_mfma_f32_16x16x32_bf16 v[88:91], v[158:161], v[208:211], v[88:91]
	v_mfma_f32_16x16x32_bf16 v[80:83], v[166:169], v[208:211], v[80:83]
	s_barrier
	s_mov_b32 m0, s61
	v_lshl_add_u64 v[182:183], s[30:31], 0, v[128:129]
	ds_read_b128 v[212:215], v249
	ds_read_b128 v[216:219], v249 offset:1024
	ds_read_b128 v[220:223], v249 offset:2048
	ds_read_b128 v[224:227], v249 offset:3072
	global_load_lds_dwordx4 v128, s[30:31]
	v_lshl_add_u64 v[228:229], s[30:31], 0, v[148:149]
	s_mov_b32 m0, s59
	s_nop 0
	global_load_lds_dwordx4 v148, s[30:31]
	s_barrier
	s_waitcnt lgkmcnt(0)
	v_mfma_f32_16x16x32_bf16 v[108:111], v[212:215], v[170:173], v[108:111]
	v_mfma_f32_16x16x32_bf16 v[100:103], v[220:223], v[170:173], v[100:103]
	v_mfma_f32_16x16x32_bf16 v[92:95], v[212:215], v[178:181], v[92:95]
	v_mfma_f32_16x16x32_bf16 v[84:87], v[220:223], v[178:181], v[84:87]
	v_mfma_f32_16x16x32_bf16 v[76:79], v[212:215], v[196:199], v[76:79]
	v_mfma_f32_16x16x32_bf16 v[72:75], v[220:223], v[196:199], v[72:75]
	v_mfma_f32_16x16x32_bf16 v[68:71], v[212:215], v[204:207], v[68:71]
	v_mfma_f32_16x16x32_bf16 v[64:67], v[220:223], v[204:207], v[64:67]
	v_mfma_f32_16x16x32_bf16 v[108:111], v[216:219], v[174:177], v[108:111]
	v_mfma_f32_16x16x32_bf16 v[100:103], v[224:227], v[174:177], v[100:103]
	v_mfma_f32_16x16x32_bf16 v[92:95], v[216:219], v[192:195], v[92:95]
	v_mfma_f32_16x16x32_bf16 v[84:87], v[224:227], v[192:195], v[84:87]
	v_mfma_f32_16x16x32_bf16 v[76:79], v[216:219], v[200:203], v[76:79]
	v_mfma_f32_16x16x32_bf16 v[72:75], v[224:227], v[200:203], v[72:75]
	v_mfma_f32_16x16x32_bf16 v[68:71], v[216:219], v[208:211], v[68:71]
	v_mfma_f32_16x16x32_bf16 v[64:67], v[224:227], v[208:211], v[64:67]
	s_mov_b32 m0, s45
	v_lshl_add_u64 v[230:231], s[26:27], 0, v[128:129]
	s_barrier
	ds_read_b128 v[170:173], v152 offset:16384
	ds_read_b128 v[174:177], v152 offset:17408
	ds_read_b128 v[178:181], v152 offset:18432
	ds_read_b128 v[192:195], v152 offset:19456
	ds_read_b128 v[196:199], v152 offset:20480
	ds_read_b128 v[200:203], v152 offset:21504
	ds_read_b128 v[204:207], v152 offset:22528
	ds_read_b128 v[208:211], v152 offset:23552
	global_load_lds_dwordx4 v128, s[26:27]
	v_lshl_add_u64 v[232:233], s[26:27], 0, v[148:149]
	s_mov_b32 m0, s47
	s_nop 0
	global_load_lds_dwordx4 v148, s[26:27]
	s_barrier
	s_waitcnt lgkmcnt(0)
	v_mfma_f32_16x16x32_bf16 v[60:63], v[154:157], v[170:173], v[60:63]
	v_mfma_f32_16x16x32_bf16 v[56:59], v[162:165], v[170:173], v[56:59]
	v_mfma_f32_16x16x32_bf16 v[52:55], v[154:157], v[178:181], v[52:55]
	v_mfma_f32_16x16x32_bf16 v[48:51], v[162:165], v[178:181], v[48:51]
	v_mfma_f32_16x16x32_bf16 v[36:39], v[154:157], v[196:199], v[36:39]
	v_mfma_f32_16x16x32_bf16 v[32:35], v[162:165], v[196:199], v[32:35]
	v_mfma_f32_16x16x32_bf16 v[20:23], v[154:157], v[204:207], v[20:23]
	v_mfma_f32_16x16x32_bf16 v[16:19], v[162:165], v[204:207], v[16:19]
	v_mfma_f32_16x16x32_bf16 v[60:63], v[158:161], v[174:177], v[60:63]
	v_mfma_f32_16x16x32_bf16 v[56:59], v[166:169], v[174:177], v[56:59]
	v_mfma_f32_16x16x32_bf16 v[52:55], v[158:161], v[192:195], v[52:55]
	v_mfma_f32_16x16x32_bf16 v[48:51], v[166:169], v[192:195], v[48:51]
	v_mfma_f32_16x16x32_bf16 v[36:39], v[158:161], v[200:203], v[36:39]
	v_mfma_f32_16x16x32_bf16 v[32:35], v[166:169], v[200:203], v[32:35]
	v_mfma_f32_16x16x32_bf16 v[20:23], v[158:161], v[208:211], v[20:23]
	v_mfma_f32_16x16x32_bf16 v[16:19], v[166:169], v[208:211], v[16:19]
	s_barrier
; #define PG8_STAGE(bufoff, gbase, voff) do { _Pragma("unroll") for (int _i = 0; _i < 2; ++_i) \
;         __builtin_amdgcn_global_load_lds((const unsigned*)((const char*)(gbase) + (voff)[_i]), (PG8_LAS unsigned*)(lds + (bufoff) + ldsw + _i * 8192), 16, 0, 0); } while (0)
; #define PG8_LDA(dst, b, h) do { _Pragma("unroll") for (int m = 0; m < 4; ++m) _Pragma("unroll") for (int k = 0; k < 2; ++k) dst[m][k] = *(const PG8_LAS bf16x8*)(lds + PG8_SA(b, h) + aoff + m * 2048 + k * 1024); } while (0)
; #define PG8_LDB(dst, b, h) do { _Pragma("unroll") for (int n = 0; n < 2; ++n) _Pragma("unroll") for (int k = 0; k < 2; ++k) dst[n][k] = *(const PG8_LAS bf16x8*)(lds + PG8_SB(b, h) + boff + n * 2048 + k * 1024); } while (0)
; #define PG8_MMA(ai, bj, At, Bt) do { __builtin_amdgcn_s_setprio(1); _Pragma("unroll") for (int m = 0; m < 4; ++m) _Pragma("unroll") for (int n = 0; n < 2; ++n) _Pragma("unroll") for (int k = 0; k < 2; ++k) \
;         acc[ai][bj][m][n] = __builtin_amdgcn_mfma_f32_16x16x32_bf16(Bt[n][k], At[m][k], acc[ai][bj][m][n], 0, 0, 0); __builtin_amdgcn_s_setprio(0); } while (0)
; #define PG8_WAIT_V(n) asm volatile("s_waitcnt vmcnt(" #n ")" ::: "memory")
; #define PG8_WAIT_L(n) asm volatile("s_waitcnt lgkmcnt(" #n ")" ::: "memory")
; #define PG8_BAR __builtin_amdgcn_s_barrier()
; #define PG8_SCHED __builtin_amdgcn_sched_barrier(0)
; template <class Epi, class Sched, bool STAMP = false>
; __device__ __forceinline__ void gemm_phase(PG8_LAS unsigned char* lds, const Gemm g, const Sched& S, const Epi& E, unsigned long long* stamps) {
;     ...
;             PG8_BAR; PG8_WAIT_L(0); PG8_MMA(1, 0, At, B0); PG8_BAR; PG8_SCHED;
;             PG8_STAGE(PG8_SB(0, 1), b2 + hstep, voffB);
;             PG8_WAIT_V(6); PG8_BAR; PG8_MMA(1, 1, At, B1); PG8_BAR;
;             PG8_LDB(B0, 1, 0); PG8_SCHED; PG8_LDA(At, 1, 0); PG8_STAGE(PG8_SA(0, 1), a2 + hstep, voffA);
;             PG8_WAIT_L(8); PG8_BAR; PG8_WAIT_L(0); PG8_MMA(0, 0, At, B0); PG8_BAR; PG8_SCHED;
;             PG8_LDB(B1, 1, 1); PG8_STAGE(PG8_SB(1, 0), b3, voffB);
;             PG8_BAR; PG8_WAIT_L(0); PG8_MMA(0, 1, At, B1); PG8_BAR;
;             PG8_LDA(At, 1, 1); PG8_STAGE(PG8_SA(1, 0), a3, voffA);
	s_mov_b32 m0, s38
	s_nop 0
	global_load_lds_dwordx4 v128, s[24:25]
	s_mov_b32 m0, s29
	s_nop 0
	global_load_lds_dwordx4 v148, s[24:25]
	s_waitcnt vmcnt(6)
	s_barrier
	v_mfma_f32_16x16x32_bf16 v[44:47], v[212:215], v[170:173], v[44:47]
	v_mfma_f32_16x16x32_bf16 v[40:43], v[220:223], v[170:173], v[40:43]
	v_mfma_f32_16x16x32_bf16 v[28:31], v[212:215], v[178:181], v[28:31]
	v_mfma_f32_16x16x32_bf16 v[24:27], v[220:223], v[178:181], v[24:27]
	v_mfma_f32_16x16x32_bf16 v[12:15], v[212:215], v[196:199], v[12:15]
	v_mfma_f32_16x16x32_bf16 v[8:11], v[220:223], v[196:199], v[8:11]
	v_mfma_f32_16x16x32_bf16 v[4:7], v[212:215], v[204:207], v[4:7]
	v_mfma_f32_16x16x32_bf16 v[0:3], v[220:223], v[204:207], v[0:3]
	v_mfma_f32_16x16x32_bf16 v[44:47], v[216:219], v[174:177], v[44:47]
	v_mfma_f32_16x16x32_bf16 v[40:43], v[224:227], v[174:177], v[40:43]
	v_mfma_f32_16x16x32_bf16 v[28:31], v[216:219], v[192:195], v[28:31]
	v_mfma_f32_16x16x32_bf16 v[24:27], v[224:227], v[192:195], v[24:27]
	v_mfma_f32_16x16x32_bf16 v[12:15], v[216:219], v[200:203], v[12:15]
	v_mfma_f32_16x16x32_bf16 v[8:11], v[224:227], v[200:203], v[8:11]
	v_mfma_f32_16x16x32_bf16 v[4:7], v[216:219], v[208:211], v[4:7]
	v_mfma_f32_16x16x32_bf16 v[0:3], v[224:227], v[208:211], v[0:3]
	s_barrier
	ds_read_b128 v[154:157], v250
	ds_read_b128 v[158:161], v250 offset:1024
	ds_read_b128 v[162:165], v250 offset:2048
	ds_read_b128 v[166:169], v250 offset:3072
	s_mov_b32 m0, s48
	ds_read_b128 v[170:173], v152 offset:32768
	ds_read_b128 v[174:177], v152 offset:33792
	ds_read_b128 v[178:181], v152 offset:34816
	ds_read_b128 v[192:195], v152 offset:35840
	ds_read_b128 v[196:199], v152 offset:36864
	ds_read_b128 v[200:203], v152 offset:37888
	ds_read_b128 v[204:207], v152 offset:38912
	ds_read_b128 v[208:211], v152 offset:39936
	global_load_lds_dwordx4 v128, s[22:23]
	s_mov_b32 m0, s49
	s_nop 0
	global_load_lds_dwordx4 v148, s[22:23]
	s_waitcnt lgkmcnt(8)
	s_barrier
	s_waitcnt lgkmcnt(0)
	v_mfma_f32_16x16x32_bf16 v[124:127], v[154:157], v[170:173], v[124:127]
	v_mfma_f32_16x16x32_bf16 v[120:123], v[162:165], v[170:173], v[120:123]
	v_mfma_f32_16x16x32_bf16 v[116:119], v[154:157], v[178:181], v[116:119]
	v_mfma_f32_16x16x32_bf16 v[112:115], v[162:165], v[178:181], v[112:115]
	v_mfma_f32_16x16x32_bf16 v[104:107], v[154:157], v[196:199], v[104:107]
	v_mfma_f32_16x16x32_bf16 v[96:99], v[162:165], v[196:199], v[96:99]
	v_mfma_f32_16x16x32_bf16 v[88:91], v[154:157], v[204:207], v[88:91]
	v_mfma_f32_16x16x32_bf16 v[80:83], v[162:165], v[204:207], v[80:83]
	v_mfma_f32_16x16x32_bf16 v[124:127], v[158:161], v[174:177], v[124:127]
	v_mfma_f32_16x16x32_bf16 v[120:123], v[166:169], v[174:177], v[120:123]
	v_mfma_f32_16x16x32_bf16 v[116:119], v[158:161], v[192:195], v[116:119]
	v_mfma_f32_16x16x32_bf16 v[112:115], v[166:169], v[192:195], v[112:115]
	v_mfma_f32_16x16x32_bf16 v[104:107], v[158:161], v[200:203], v[104:107]
	v_mfma_f32_16x16x32_bf16 v[96:99], v[166:169], v[200:203], v[96:99]
	v_mfma_f32_16x16x32_bf16 v[88:91], v[158:161], v[208:211], v[88:91]
	v_mfma_f32_16x16x32_bf16 v[80:83], v[166:169], v[208:211], v[80:83]
	s_barrier
	s_mov_b32 m0, s16
	v_lshl_add_u64 v[182:183], v[182:183], 0, s[18:19]
	ds_read_b128 v[212:215], v251
	ds_read_b128 v[216:219], v251 offset:1024
	ds_read_b128 v[220:223], v251 offset:2048
	ds_read_b128 v[224:227], v251 offset:3072
	global_load_lds_dwordx4 v244, s[30:31]
	v_lshl_add_u64 v[182:183], v[228:229], 0, s[18:19]
	s_mov_b32 m0, s14
	s_nop 0
	global_load_lds_dwordx4 v245, s[30:31]
	s_barrier
	s_waitcnt lgkmcnt(0)
	v_mfma_f32_16x16x32_bf16 v[108:111], v[212:215], v[170:173], v[108:111]
	v_mfma_f32_16x16x32_bf16 v[100:103], v[220:223], v[170:173], v[100:103]
	v_mfma_f32_16x16x32_bf16 v[92:95], v[212:215], v[178:181], v[92:95]
	v_mfma_f32_16x16x32_bf16 v[84:87], v[220:223], v[178:181], v[84:87]
	v_mfma_f32_16x16x32_bf16 v[76:79], v[212:215], v[196:199], v[76:79]
	v_mfma_f32_16x16x32_bf16 v[72:75], v[220:223], v[196:199], v[72:75]
	v_mfma_f32_16x16x32_bf16 v[68:71], v[212:215], v[204:207], v[68:71]
	v_mfma_f32_16x16x32_bf16 v[64:67], v[220:223], v[204:207], v[64:67]
	v_mfma_f32_16x16x32_bf16 v[108:111], v[216:219], v[174:177], v[108:111]
	v_mfma_f32_16x16x32_bf16 v[100:103], v[224:227], v[174:177], v[100:103]
	v_mfma_f32_16x16x32_bf16 v[92:95], v[216:219], v[192:195], v[92:95]
	v_mfma_f32_16x16x32_bf16 v[84:87], v[224:227], v[192:195], v[84:87]
	v_mfma_f32_16x16x32_bf16 v[76:79], v[216:219], v[200:203], v[76:79]
	v_mfma_f32_16x16x32_bf16 v[72:75], v[224:227], v[200:203], v[72:75]
	v_mfma_f32_16x16x32_bf16 v[68:71], v[216:219], v[208:211], v[68:71]
	v_mfma_f32_16x16x32_bf16 v[64:67], v[224:227], v[208:211], v[64:67]
	s_mov_b32 m0, s57
	v_lshl_add_u64 v[182:183], v[230:231], 0, s[18:19]
	s_barrier
	ds_read_b128 v[170:173], v152 offset:49152
	ds_read_b128 v[174:177], v152 offset:50176
	ds_read_b128 v[178:181], v152 offset:51200
	ds_read_b128 v[192:195], v152 offset:52224
	ds_read_b128 v[196:199], v152 offset:53248
	ds_read_b128 v[200:203], v152 offset:54272
	ds_read_b128 v[204:207], v152 offset:55296
	ds_read_b128 v[208:211], v152 offset:56320
	global_load_lds_dwordx4 v244, s[26:27]
	v_lshl_add_u64 v[182:183], v[232:233], 0, s[18:19]
	s_mov_b32 m0, s58
	s_nop 0
	global_load_lds_dwordx4 v245, s[26:27]
	s_barrier
; #define PG8_STAGE(bufoff, gbase, voff) do { _Pragma("unroll") for (int _i = 0; _i < 2; ++_i) \
;         __builtin_amdgcn_global_load_lds((const unsigned*)((const char*)(gbase) + (voff)[_i]), (PG8_LAS unsigned*)(lds + (bufoff) + ldsw + _i * 8192), 16, 0, 0); } while (0)
; #define PG8_MMA(ai, bj, At, Bt) do { __builtin_amdgcn_s_setprio(1); _Pragma("unroll") for (int m = 0; m < 4; ++m) _Pragma("unroll") for (int n = 0; n < 2; ++n) _Pragma("unroll") for (int k = 0; k < 2; ++k) \
;         acc[ai][bj][m][n] = __builtin_amdgcn_mfma_f32_16x16x32_bf16(Bt[n][k], At[m][k], acc[ai][bj][m][n], 0, 0, 0); __builtin_amdgcn_s_setprio(0); } while (0)
; #define PG8_WAIT_V(n) asm volatile("s_waitcnt vmcnt(" #n ")" ::: "memory")
; #define PG8_WAIT_L(n) asm volatile("s_waitcnt lgkmcnt(" #n ")" ::: "memory")
; #define PG8_BAR __builtin_amdgcn_s_barrier()
; #define PG8_SCHED __builtin_amdgcn_sched_barrier(0)
; template <class Epi, class Sched, bool STAMP = false>
; __device__ __forceinline__ void gemm_phase(PG8_LAS unsigned char* lds, const Gemm g, const Sched& S, const Epi& E, unsigned long long* stamps) {
;     ...
;             PG8_BAR; PG8_WAIT_L(0); PG8_MMA(1, 0, At, B0); PG8_BAR; PG8_SCHED;
;             PG8_STAGE(PG8_SB(1, 1), b3 + hstep, voffB);
;             PG8_WAIT_V(6); PG8_BAR; PG8_MMA(1, 1, At, B1); PG8_BAR;
;     __device__ __forceinline__ void operator()(const f32x4 (&acc)[2][2][4][2], const pg8::Unit& u, int wr, int wc, int fr, int fq) const {
;         const int row0 = (u.pm - 64) * 256 + wr * 64 + fr, col0 = u.pn * 256 + wc * 32 + 4 * fq;
; #pragma unroll
;         for (int ai = 0; ai < 2; ++ai)
; #pragma unroll
;             for (int m = 0; m < 4; ++m) { float* xp = PART + (size_t)(row0 + ai * 128 + m * 16) * ldp + col0;
; #pragma unroll
;                 for (int bj = 0; bj < 2; ++bj)
; #pragma unroll
;                     for (int n = 0; n < 2; ++n) *(f32x4*)(xp + bj * 128 + n * 16) = acc[ai][bj][m][n]; }
	s_waitcnt lgkmcnt(0)
	v_mfma_f32_16x16x32_bf16 v[60:63], v[154:157], v[170:173], v[60:63]
	v_mfma_f32_16x16x32_bf16 v[56:59], v[162:165], v[170:173], v[56:59]
	v_mfma_f32_16x16x32_bf16 v[52:55], v[154:157], v[178:181], v[52:55]
	v_mfma_f32_16x16x32_bf16 v[48:51], v[162:165], v[178:181], v[48:51]
	v_mfma_f32_16x16x32_bf16 v[36:39], v[154:157], v[196:199], v[36:39]
	v_mfma_f32_16x16x32_bf16 v[32:35], v[162:165], v[196:199], v[32:35]
	v_mfma_f32_16x16x32_bf16 v[20:23], v[154:157], v[204:207], v[20:23]
	v_mfma_f32_16x16x32_bf16 v[16:19], v[162:165], v[204:207], v[16:19]
	v_mfma_f32_16x16x32_bf16 v[60:63], v[158:161], v[174:177], v[60:63]
	v_mfma_f32_16x16x32_bf16 v[56:59], v[166:169], v[174:177], v[56:59]
	v_mfma_f32_16x16x32_bf16 v[52:55], v[158:161], v[192:195], v[52:55]
	v_mfma_f32_16x16x32_bf16 v[48:51], v[166:169], v[192:195], v[48:51]
	v_mfma_f32_16x16x32_bf16 v[36:39], v[158:161], v[200:203], v[36:39]
	v_mfma_f32_16x16x32_bf16 v[32:35], v[166:169], v[200:203], v[32:35]
	v_mfma_f32_16x16x32_bf16 v[20:23], v[158:161], v[208:211], v[20:23]
	v_mfma_f32_16x16x32_bf16 v[16:19], v[166:169], v[208:211], v[16:19]
	s_barrier
	s_mov_b32 m0, s52
	s_nop 0
	global_load_lds_dwordx4 v128, s[20:21]
	s_mov_b32 m0, s39
	s_nop 0
	global_load_lds_dwordx4 v148, s[20:21]
	s_waitcnt vmcnt(6)
	s_barrier
	v_mfma_f32_16x16x32_bf16 v[44:47], v[212:215], v[170:173], v[44:47]
	v_mfma_f32_16x16x32_bf16 v[40:43], v[220:223], v[170:173], v[40:43]
	v_mfma_f32_16x16x32_bf16 v[28:31], v[212:215], v[178:181], v[28:31]
	v_mfma_f32_16x16x32_bf16 v[24:27], v[220:223], v[178:181], v[24:27]
	v_mfma_f32_16x16x32_bf16 v[12:15], v[212:215], v[196:199], v[12:15]
	v_mfma_f32_16x16x32_bf16 v[8:11], v[220:223], v[196:199], v[8:11]
	v_mfma_f32_16x16x32_bf16 v[4:7], v[212:215], v[204:207], v[4:7]
	v_mfma_f32_16x16x32_bf16 v[0:3], v[220:223], v[204:207], v[0:3]
	v_mfma_f32_16x16x32_bf16 v[44:47], v[216:219], v[174:177], v[44:47]
	v_mfma_f32_16x16x32_bf16 v[40:43], v[224:227], v[174:177], v[40:43]
	v_mfma_f32_16x16x32_bf16 v[28:31], v[216:219], v[192:195], v[28:31]
	v_mfma_f32_16x16x32_bf16 v[24:27], v[224:227], v[192:195], v[24:27]
	v_mfma_f32_16x16x32_bf16 v[12:15], v[216:219], v[200:203], v[12:15]
	v_mfma_f32_16x16x32_bf16 v[8:11], v[224:227], v[200:203], v[8:11]
	v_mfma_f32_16x16x32_bf16 v[4:7], v[216:219], v[208:211], v[4:7]
	v_mfma_f32_16x16x32_bf16 v[0:3], v[224:227], v[208:211], v[0:3]
	s_andn2_b64 vcc, exec, s[12:13]
	s_mov_b64 s[20:21], -1
	s_mov_b64 s[12:13], 0
	s_movk_i32 s14, 0x100
	s_barrier
	s_cbranch_vccz .LBB0_213
	s_lshl_b32 s0, s43, 22
	s_add_u32 s0, s10, s0
	s_addc_u32 s1, s46, 0
	s_add_u32 s0, s0, 0xbb00000
	s_addc_u32 s1, s1, 0
	s_lshl_b32 s4, s42, 8
	s_add_i32 s4, s4, s53
	v_add_u32_e32 v150, s4, v150
	v_add_u32_e32 v148, 0xffffc000, v150
	s_lshl_b32 s4, s41, 8
	v_lshl_or_b32 v128, v139, 2, s4
	v_ashrrev_i32_e32 v149, 31, v148
	v_or_b32_e32 v128, s56, v128
	v_lshlrev_b64 v[148:149], 12, v[148:149]
	v_lshl_add_u64 v[148:149], s[0:1], 0, v[148:149]
	v_lshlrev_b32_e32 v128, 2, v128
	v_lshl_add_u64 v[148:149], v[148:149], 0, v[128:129]
	global_store_dwordx4 v[148:149], v[124:127], off
	global_store_dwordx4 v[148:149], v[120:123], off offset:64
	global_store_dwordx4 v[148:149], v[108:111], off offset:512
	global_store_dwordx4 v[148:149], v[100:103], off offset:576
	s_cmpk_lt_u32 s40, 0x100
	s_movk_i32 s58, 0xff60
	v_add_u32_e32 v100, 0xffffc010, v150
	v_ashrrev_i32_e32 v101, 31, v100
	v_lshlrev_b64 v[100:101], 12, v[100:101]
	v_lshl_add_u64 v[100:101], s[0:1], 0, v[100:101]
	v_lshl_add_u64 v[100:101], v[100:101], 0, v[128:129]
	global_store_dwordx4 v[100:101], v[116:119], off
	global_store_dwordx4 v[100:101], v[112:115], off offset:64
	global_store_dwordx4 v[100:101], v[92:95], off offset:512
	global_store_dwordx4 v[100:101], v[84:87], off offset:576
	s_nop 1
	v_add_u32_e32 v84, 0xffffc020, v150
	v_ashrrev_i32_e32 v85, 31, v84
	v_lshlrev_b64 v[84:85], 12, v[84:85]
	v_lshl_add_u64 v[84:85], s[0:1], 0, v[84:85]
	v_lshl_add_u64 v[84:85], v[84:85], 0, v[128:129]
	global_store_dwordx4 v[84:85], v[104:107], off
	global_store_dwordx4 v[84:85], v[96:99], off offset:64
	global_store_dwordx4 v[84:85], v[76:79], off offset:512
	global_store_dwordx4 v[84:85], v[72:75], off offset:576
	s_nop 1
	v_add_u32_e32 v72, 0xffffc030, v150
	v_ashrrev_i32_e32 v73, 31, v72
	v_lshlrev_b64 v[72:73], 12, v[72:73]
	v_lshl_add_u64 v[72:73], s[0:1], 0, v[72:73]
	v_lshl_add_u64 v[72:73], v[72:73], 0, v[128:129]
	s_mov_b64 s[0:1], 0x80000
	global_store_dwordx4 v[72:73], v[88:91], off
	global_store_dwordx4 v[72:73], v[80:83], off offset:64
	global_store_dwordx4 v[72:73], v[68:71], off offset:512
	global_store_dwordx4 v[72:73], v[64:67], off offset:576
	s_nop 1
	v_lshl_add_u64 v[64:65], v[148:149], 0, s[0:1]
	s_mov_b32 s0, 0x80000
	v_add_co_u32_e32 v66, vcc, s0, v148
	s_mov_b64 s[0:1], 0x90000
	s_nop 0
	v_addc_co_u32_e32 v67, vcc, 0, v149, vcc
	global_store_dwordx4 v[66:67], v[60:63], off
	global_store_dwordx4 v[64:65], v[56:59], off offset:64
	global_store_dwordx4 v[64:65], v[44:47], off offset:512
	global_store_dwordx4 v[64:65], v[40:43], off offset:576
	s_nop 1
	v_lshl_add_u64 v[40:41], v[148:149], 0, s[0:1]
	s_mov_b32 s0, 0x90000
	v_add_co_u32_e32 v42, vcc, s0, v148
	s_mov_b64 s[0:1], 0xa0000
	s_nop 0
	v_addc_co_u32_e32 v43, vcc, 0, v149, vcc
	global_store_dwordx4 v[42:43], v[52:55], off
	global_store_dwordx4 v[40:41], v[48:51], off offset:64
	global_store_dwordx4 v[40:41], v[28:31], off offset:512
	global_store_dwordx4 v[40:41], v[24:27], off offset:576
	s_nop 1
	v_lshl_add_u64 v[24:25], v[148:149], 0, s[0:1]
	s_mov_b32 s0, 0xa0000
	v_add_co_u32_e32 v26, vcc, s0, v148
	s_mov_b64 s[0:1], 0xb0000
	s_nop 0
	v_addc_co_u32_e32 v27, vcc, 0, v149, vcc
	global_store_dwordx4 v[26:27], v[36:39], off
	global_store_dwordx4 v[24:25], v[32:35], off offset:64
	global_store_dwordx4 v[24:25], v[12:15], off offset:512
	global_store_dwordx4 v[24:25], v[8:11], off offset:576
	s_nop 1
	v_add_co_u32_e32 v10, vcc, 0xb0000, v148
	v_lshl_add_u64 v[8:9], v[148:149], 0, s[0:1]
	s_nop 0
	v_addc_co_u32_e32 v11, vcc, 0, v149, vcc
	global_store_dwordx4 v[10:11], v[20:23], off
	global_store_dwordx4 v[8:9], v[16:19], off offset:64
	global_store_dwordx4 v[8:9], v[4:7], off offset:512
	global_store_dwordx4 v[8:9], v[0:3], off offset:576
	s_waitcnt vmcnt(0)
	s_cbranch_scc0 .LBB0_216
	s_barrier

; #define PG8_STAGE(bufoff, gbase, voff) do { _Pragma("unroll") for (int _i = 0; _i < 2; ++_i) \
;         __builtin_amdgcn_global_load_lds((const unsigned*)((const char*)(gbase) + (voff)[_i]), (PG8_LAS unsigned*)(lds + (bufoff) + ldsw + _i * 8192), 16, 0, 0); } while (0)
; #define PG8_LDA(dst, b, h) do { _Pragma("unroll") for (int m = 0; m < 4; ++m) _Pragma("unroll") for (int k = 0; k < 2; ++k) dst[m][k] = *(const PG8_LAS bf16x8*)(lds + PG8_SA(b, h) + aoff + m * 2048 + k * 1024); } while (0)
; #define PG8_LDB(dst, b, h) do { _Pragma("unroll") for (int n = 0; n < 2; ++n) _Pragma("unroll") for (int k = 0; k < 2; ++k) dst[n][k] = *(const PG8_LAS bf16x8*)(lds + PG8_SB(b, h) + boff + n * 2048 + k * 1024); } while (0)
; #define PG8_WAIT_L(n) asm volatile("s_waitcnt lgkmcnt(" #n ")" ::: "memory")
; #define PG8_BAR __builtin_amdgcn_s_barrier()
; #define PG8_SCHED __builtin_amdgcn_sched_barrier(0)
;     __device__ bool next(int i, pg8::Unit& u) const { if (i != 0 || !valid) return false; u.pm = pm; u.pn = pn; return true; }
; template <class Epi, class Sched, bool STAMP = false>
; __device__ __forceinline__ void gemm_phase(PG8_LAS unsigned char* lds, const Gemm g, const Sched& S, const Epi& E, unsigned long long* stamps) {
;     ...
;         const bool has_next = S.next(ui + 1, nxt);
;         const char* nA = has_next ? (const char*)g.A + (size_t)nxt.pm * tstep : cA; const char* nB = has_next ? (const char*)g.Bt + (size_t)nxt.pn * tstep : cB;
;         for (int t = 0; t < nt; t += 2) {
;             const bool last = (t == nt - 2);
;             const char* a1 = cA + (size_t)(t + 1) * kstep;
;             const char* a2 = last ? nA : cA + (size_t)(t + 2) * kstep; const char* b2 = last ? nB : cB + (size_t)(t + 2) * kstep;
;             const char* a3 = a2 + kstep; const char* b3 = b2 + kstep;
;             if (last && has_next) S.a_ready(nxt);
;             PG8_LDB(B0, 0, 0); PG8_SCHED; PG8_LDA(At, 0, 0); PG8_STAGE(PG8_SA(1, 1), a1 + hstep, voffA);
;             PG8_WAIT_L(8); PG8_BAR; PG8_WAIT_L(0); PG8_MMA(0, 0, At, B0); PG8_BAR; PG8_SCHED;
;     ...
; #pragma unroll
;         for (int a = 0; a < 2; ++a)
; #pragma unroll
;             for (int b = 0; b < 2; ++b)
; #pragma unroll
;                 for (int m = 0; m < 4; ++m)
; #pragma unroll
;                     for (int n = 0; n < 2; ++n) acc[a][b][m][n] = (f32x4){0.f, 0.f, 0.f, 0.f};
.LBB0_292:
	s_ashr_i32 s7, s6, 31
	v_cmp_lt_i64_e32 vcc, s[12:13], v[136:137]
	s_lshl_b64 s[12:13], s[6:7], 18
	s_add_u32 s12, s20, s12
	s_addc_u32 s13, s21, s13
	s_and_b64 s[14:15], vcc, exec
	s_cselect_b32 s7, s13, s25
	s_cselect_b32 s53, s12, s24
	s_ashr_i32 s5, s4, 31
	s_lshl_b64 s[14:15], s[4:5], 18
	s_add_u32 s22, s44, s14
	s_addc_u32 s23, s45, s15
	s_and_b64 s[14:15], vcc, exec
	s_cselect_b32 s5, s23, s27
	s_cselect_b32 s56, s22, s26
	s_add_u32 s24, s24, 0x20080
	s_addc_u32 s25, s25, 0
	s_add_u32 s57, s26, 0x100
	v_mov_b32_e32 v0, 0
	s_addc_u32 s58, s27, 0
	s_mov_b32 s59, -2
	v_mov_b32_e32 v1, v0
	v_mov_b32_e32 v2, v0
	v_mov_b32_e32 v3, v0
	v_mov_b32_e32 v4, v0
	v_mov_b32_e32 v5, v0
	v_mov_b32_e32 v6, v0
	v_mov_b32_e32 v7, v0
	v_mov_b32_e32 v8, v0
	v_mov_b32_e32 v9, v0
	v_mov_b32_e32 v10, v0
	v_mov_b32_e32 v11, v0
	v_mov_b32_e32 v12, v0
	v_mov_b32_e32 v13, v0
	v_mov_b32_e32 v14, v0
	v_mov_b32_e32 v15, v0
	v_mov_b32_e32 v24, v0
	v_mov_b32_e32 v25, v0
	v_mov_b32_e32 v26, v0
	v_mov_b32_e32 v27, v0
	v_mov_b32_e32 v28, v0
	v_mov_b32_e32 v29, v0
	v_mov_b32_e32 v30, v0
	v_mov_b32_e32 v31, v0
	v_mov_b32_e32 v40, v0
	v_mov_b32_e32 v41, v0
	v_mov_b32_e32 v42, v0
	v_mov_b32_e32 v43, v0
	v_mov_b32_e32 v44, v0
	v_mov_b32_e32 v45, v0
	v_mov_b32_e32 v46, v0
	v_mov_b32_e32 v47, v0
	v_mov_b32_e32 v16, v0
	v_mov_b32_e32 v17, v0
	v_mov_b32_e32 v18, v0
	v_mov_b32_e32 v19, v0
	v_mov_b32_e32 v20, v0
	v_mov_b32_e32 v21, v0
	v_mov_b32_e32 v22, v0
	v_mov_b32_e32 v23, v0
	v_mov_b32_e32 v32, v0
	v_mov_b32_e32 v33, v0
	v_mov_b32_e32 v34, v0
	v_mov_b32_e32 v35, v0
	v_mov_b32_e32 v36, v0
	v_mov_b32_e32 v37, v0
	v_mov_b32_e32 v38, v0
	v_mov_b32_e32 v39, v0
	v_mov_b32_e32 v48, v0
	v_mov_b32_e32 v49, v0
	v_mov_b32_e32 v50, v0
	v_mov_b32_e32 v51, v0
	v_mov_b32_e32 v52, v0
	v_mov_b32_e32 v53, v0
	v_mov_b32_e32 v54, v0
	v_mov_b32_e32 v55, v0
	v_mov_b32_e32 v56, v0
	v_mov_b32_e32 v57, v0
	v_mov_b32_e32 v58, v0
	v_mov_b32_e32 v59, v0
	v_mov_b32_e32 v60, v0
	v_mov_b32_e32 v61, v0
	v_mov_b32_e32 v62, v0
	v_mov_b32_e32 v63, v0
	v_mov_b32_e32 v64, v0
	v_mov_b32_e32 v65, v0
	v_mov_b32_e32 v66, v0
	v_mov_b32_e32 v67, v0
	v_mov_b32_e32 v68, v0
	v_mov_b32_e32 v69, v0
	v_mov_b32_e32 v70, v0
	v_mov_b32_e32 v71, v0
	v_mov_b32_e32 v72, v0
	v_mov_b32_e32 v73, v0
	v_mov_b32_e32 v74, v0
	v_mov_b32_e32 v75, v0
	v_mov_b32_e32 v76, v0
	v_mov_b32_e32 v77, v0
	v_mov_b32_e32 v78, v0
	v_mov_b32_e32 v79, v0
	v_mov_b32_e32 v88, v0
	v_mov_b32_e32 v89, v0
	v_mov_b32_e32 v90, v0
	v_mov_b32_e32 v91, v0
	v_mov_b32_e32 v92, v0
	v_mov_b32_e32 v93, v0
	v_mov_b32_e32 v94, v0
	v_mov_b32_e32 v95, v0
	v_mov_b32_e32 v104, v0
	v_mov_b32_e32 v105, v0
	v_mov_b32_e32 v106, v0
	v_mov_b32_e32 v107, v0
	v_mov_b32_e32 v108, v0
	v_mov_b32_e32 v109, v0
	v_mov_b32_e32 v110, v0
	v_mov_b32_e32 v111, v0
	v_mov_b32_e32 v80, v0
	v_mov_b32_e32 v81, v0
	v_mov_b32_e32 v82, v0
	v_mov_b32_e32 v83, v0
	v_mov_b32_e32 v84, v0
	v_mov_b32_e32 v85, v0
	v_mov_b32_e32 v86, v0
	v_mov_b32_e32 v87, v0
	v_mov_b32_e32 v96, v0
	v_mov_b32_e32 v97, v0
	v_mov_b32_e32 v98, v0
	v_mov_b32_e32 v99, v0
	v_mov_b32_e32 v100, v0
	v_mov_b32_e32 v101, v0
	v_mov_b32_e32 v102, v0
	v_mov_b32_e32 v103, v0
	v_mov_b32_e32 v112, v0
	v_mov_b32_e32 v113, v0
	v_mov_b32_e32 v114, v0
	v_mov_b32_e32 v115, v0
	v_mov_b32_e32 v116, v0
	v_mov_b32_e32 v117, v0
	v_mov_b32_e32 v118, v0
	v_mov_b32_e32 v119, v0
	v_mov_b32_e32 v120, v0
	v_mov_b32_e32 v121, v0
	v_mov_b32_e32 v122, v0
	v_mov_b32_e32 v123, v0
	v_mov_b32_e32 v124, v0
	v_mov_b32_e32 v125, v0
	v_mov_b32_e32 v126, v0
	v_mov_b32_e32 v127, v0
	v_add_u32_e32 v244, 0x80, v128
	v_add_u32_e32 v245, 0x80, v152
	v_add_u32_e32 v246, 0x80, v148
	v_add_u32_e32 v247, 0x80, v150
	v_add_u32_e32 v248, 0x10000, v158
	v_add_u32_e32 v249, 0x14000, v158
	v_add_u32_e32 v250, 0x18000, v158
	v_add_u32_e32 v251, 0x1c000, v158
.LBB0_293:
	s_add_u32 s14, s24, 0xfffe0080
	s_addc_u32 s15, s25, -1
	s_add_i32 s16, 0, 0x10000
	ds_read_b128 v[162:165], v248
	ds_read_b128 v[166:169], v248 offset:1024
	ds_read_b128 v[170:173], v248 offset:2048
	ds_read_b128 v[174:177], v248 offset:3072
	s_cmp_eq_u32 s59, 4
	s_cselect_b32 s31, s7, s15
	s_cselect_b32 s30, s53, s14
	s_cselect_b32 s27, s5, s58
	s_cselect_b32 s26, s56, s57
	s_add_i32 m0, s3, 0xc000
	ds_read_b128 v[178:181], v160
	ds_read_b128 v[192:195], v160 offset:1024
	ds_read_b128 v[196:199], v160 offset:2048
	ds_read_b128 v[200:203], v160 offset:3072
	ds_read_b128 v[204:207], v160 offset:4096
	ds_read_b128 v[208:211], v160 offset:5120
	ds_read_b128 v[212:215], v160 offset:6144
	ds_read_b128 v[216:219], v160 offset:7168
	global_load_lds_dwordx4 v154, s[24:25]
	s_add_i32 m0, s3, 0xe000
	s_nop 0
	global_load_lds_dwordx4 v156, s[24:25]
	s_waitcnt lgkmcnt(8)
	s_barrier
	s_waitcnt lgkmcnt(0)
	v_mfma_f32_16x16x32_bf16 v[124:127], v[162:165], v[178:181], v[124:127]
	v_mfma_f32_16x16x32_bf16 v[120:123], v[170:173], v[178:181], v[120:123]
	v_mfma_f32_16x16x32_bf16 v[116:119], v[162:165], v[196:199], v[116:119]
	v_mfma_f32_16x16x32_bf16 v[112:115], v[170:173], v[196:199], v[112:115]
	v_mfma_f32_16x16x32_bf16 v[100:103], v[162:165], v[204:207], v[100:103]
	v_mfma_f32_16x16x32_bf16 v[96:99], v[170:173], v[204:207], v[96:99]
	v_mfma_f32_16x16x32_bf16 v[84:87], v[162:165], v[212:215], v[84:87]
	v_mfma_f32_16x16x32_bf16 v[80:83], v[170:173], v[212:215], v[80:83]
	v_mfma_f32_16x16x32_bf16 v[124:127], v[166:169], v[192:195], v[124:127]
	v_mfma_f32_16x16x32_bf16 v[120:123], v[174:177], v[192:195], v[120:123]
	v_mfma_f32_16x16x32_bf16 v[116:119], v[166:169], v[200:203], v[116:119]
	v_mfma_f32_16x16x32_bf16 v[112:115], v[174:177], v[200:203], v[112:115]
	v_mfma_f32_16x16x32_bf16 v[100:103], v[166:169], v[208:211], v[100:103]
	v_mfma_f32_16x16x32_bf16 v[96:99], v[174:177], v[208:211], v[96:99]
	v_mfma_f32_16x16x32_bf16 v[84:87], v[166:169], v[216:219], v[84:87]
	v_mfma_f32_16x16x32_bf16 v[80:83], v[174:177], v[216:219], v[80:83]
	s_barrier
; #define PG8_STAGE(bufoff, gbase, voff) do { _Pragma("unroll") for (int _i = 0; _i < 2; ++_i) \
;         __builtin_amdgcn_global_load_lds((const unsigned*)((const char*)(gbase) + (voff)[_i]), (PG8_LAS unsigned*)(lds + (bufoff) + ldsw + _i * 8192), 16, 0, 0); } while (0)
; #define PG8_LDA(dst, b, h) do { _Pragma("unroll") for (int m = 0; m < 4; ++m) _Pragma("unroll") for (int k = 0; k < 2; ++k) dst[m][k] = *(const PG8_LAS bf16x8*)(lds + PG8_SA(b, h) + aoff + m * 2048 + k * 1024); } while (0)
; #define PG8_LDB(dst, b, h) do { _Pragma("unroll") for (int n = 0; n < 2; ++n) _Pragma("unroll") for (int k = 0; k < 2; ++k) dst[n][k] = *(const PG8_LAS bf16x8*)(lds + PG8_SB(b, h) + boff + n * 2048 + k * 1024); } while (0)
; #define PG8_MMA(ai, bj, At, Bt) do { __builtin_amdgcn_s_setprio(1); _Pragma("unroll") for (int m = 0; m < 4; ++m) _Pragma("unroll") for (int n = 0; n < 2; ++n) _Pragma("unroll") for (int k = 0; k < 2; ++k) \
;         acc[ai][bj][m][n] = __builtin_amdgcn_mfma_f32_16x16x32_bf16(Bt[n][k], At[m][k], acc[ai][bj][m][n], 0, 0, 0); __builtin_amdgcn_s_setprio(0); } while (0)
; #define PG8_WAIT_V(n) asm volatile("s_waitcnt vmcnt(" #n ")" ::: "memory")
; #define PG8_WAIT_L(n) asm volatile("s_waitcnt lgkmcnt(" #n ")" ::: "memory")
; #define PG8_BAR __builtin_amdgcn_s_barrier()
; #define PG8_SCHED __builtin_amdgcn_sched_barrier(0)
; template <class Epi, class Sched, bool STAMP = false>
; __device__ __forceinline__ void gemm_phase(PG8_LAS unsigned char* lds, const Gemm g, const Sched& S, const Epi& E, unsigned long long* stamps) {
;     ...
;             PG8_LDB(B1, 0, 1); PG8_STAGE(PG8_SB(0, 0), b2, voffB);
;             PG8_BAR; PG8_WAIT_L(0); PG8_MMA(0, 1, At, B1); PG8_BAR;
;             PG8_LDA(At, 0, 1); PG8_STAGE(PG8_SA(0, 0), a2, voffA);
;             PG8_BAR; PG8_WAIT_L(0); PG8_MMA(1, 0, At, B0); PG8_BAR; PG8_SCHED;
;             PG8_STAGE(PG8_SB(0, 1), b2 + hstep, voffB);
;             PG8_WAIT_V(6); PG8_BAR; PG8_MMA(1, 1, At, B1); PG8_BAR;
;             PG8_LDB(B0, 1, 0); PG8_SCHED; PG8_LDA(At, 1, 0); PG8_STAGE(PG8_SA(0, 1), a2 + hstep, voffA);
;             PG8_WAIT_L(8); PG8_BAR; PG8_WAIT_L(0); PG8_MMA(0, 0, At, B0); PG8_BAR; PG8_SCHED;
	s_add_i32 s17, 0, 0x14000
	s_add_i32 s14, s16, s40
	s_mov_b32 m0, s14
	ds_read_b128 v[220:223], v249
	ds_read_b128 v[224:227], v249 offset:1024
	ds_read_b128 v[228:231], v249 offset:2048
	ds_read_b128 v[232:235], v249 offset:3072
	global_load_lds_dwordx4 v128, s[26:27]
	s_add_i32 m0, s14, 0x2000
	s_nop 0
	global_load_lds_dwordx4 v152, s[26:27]
	s_barrier
	s_waitcnt lgkmcnt(0)
	v_mfma_f32_16x16x32_bf16 v[108:111], v[220:223], v[178:181], v[108:111]
	v_mfma_f32_16x16x32_bf16 v[104:107], v[228:231], v[178:181], v[104:107]
	v_mfma_f32_16x16x32_bf16 v[92:95], v[220:223], v[196:199], v[92:95]
	v_mfma_f32_16x16x32_bf16 v[88:91], v[228:231], v[196:199], v[88:91]
	v_mfma_f32_16x16x32_bf16 v[76:79], v[220:223], v[204:207], v[76:79]
	v_mfma_f32_16x16x32_bf16 v[72:75], v[228:231], v[204:207], v[72:75]
	v_mfma_f32_16x16x32_bf16 v[68:71], v[220:223], v[212:215], v[68:71]
	v_mfma_f32_16x16x32_bf16 v[64:67], v[228:231], v[212:215], v[64:67]
	v_mfma_f32_16x16x32_bf16 v[108:111], v[224:227], v[192:195], v[108:111]
	v_mfma_f32_16x16x32_bf16 v[104:107], v[232:235], v[192:195], v[104:107]
	v_mfma_f32_16x16x32_bf16 v[92:95], v[224:227], v[200:203], v[92:95]
	v_mfma_f32_16x16x32_bf16 v[88:91], v[232:235], v[200:203], v[88:91]
	v_mfma_f32_16x16x32_bf16 v[76:79], v[224:227], v[208:211], v[76:79]
	v_mfma_f32_16x16x32_bf16 v[72:75], v[232:235], v[208:211], v[72:75]
	v_mfma_f32_16x16x32_bf16 v[68:71], v[224:227], v[216:219], v[68:71]
	v_mfma_f32_16x16x32_bf16 v[64:67], v[232:235], v[216:219], v[64:67]
	s_mov_b32 m0, s3
	s_barrier
	ds_read_b128 v[178:181], v160 offset:16384
	ds_read_b128 v[192:195], v160 offset:17408
	ds_read_b128 v[196:199], v160 offset:18432
	ds_read_b128 v[200:203], v160 offset:19456
	ds_read_b128 v[204:207], v160 offset:20480
	ds_read_b128 v[208:211], v160 offset:21504
	ds_read_b128 v[212:215], v160 offset:22528
	ds_read_b128 v[216:219], v160 offset:23552
	global_load_lds_dwordx4 v148, s[30:31]
	s_mov_b32 m0, s41
	s_nop 0
	global_load_lds_dwordx4 v150, s[30:31]
	s_barrier
	s_waitcnt lgkmcnt(0)
	v_mfma_f32_16x16x32_bf16 v[60:63], v[162:165], v[178:181], v[60:63]
	v_mfma_f32_16x16x32_bf16 v[56:59], v[170:173], v[178:181], v[56:59]
	v_mfma_f32_16x16x32_bf16 v[52:55], v[162:165], v[196:199], v[52:55]
	v_mfma_f32_16x16x32_bf16 v[48:51], v[170:173], v[196:199], v[48:51]
	v_mfma_f32_16x16x32_bf16 v[36:39], v[162:165], v[204:207], v[36:39]
	v_mfma_f32_16x16x32_bf16 v[32:35], v[170:173], v[204:207], v[32:35]
	v_mfma_f32_16x16x32_bf16 v[20:23], v[162:165], v[212:215], v[20:23]
	v_mfma_f32_16x16x32_bf16 v[16:19], v[170:173], v[212:215], v[16:19]
	v_mfma_f32_16x16x32_bf16 v[60:63], v[166:169], v[192:195], v[60:63]
	v_mfma_f32_16x16x32_bf16 v[56:59], v[174:177], v[192:195], v[56:59]
	v_mfma_f32_16x16x32_bf16 v[52:55], v[166:169], v[200:203], v[52:55]
	v_mfma_f32_16x16x32_bf16 v[48:51], v[174:177], v[200:203], v[48:51]
	v_mfma_f32_16x16x32_bf16 v[36:39], v[166:169], v[208:211], v[36:39]
	v_mfma_f32_16x16x32_bf16 v[32:35], v[174:177], v[208:211], v[32:35]
	v_mfma_f32_16x16x32_bf16 v[20:23], v[166:169], v[216:219], v[20:23]
	v_mfma_f32_16x16x32_bf16 v[16:19], v[174:177], v[216:219], v[16:19]
	s_barrier
	s_add_u32 s14, s26, 0x20000
	s_addc_u32 s15, s27, 0
	s_add_i32 s16, s17, s40
	s_mov_b32 m0, s16
	s_nop 0
	global_load_lds_dwordx4 v128, s[14:15]
	s_add_i32 m0, s16, 0x2000
	s_nop 0
	global_load_lds_dwordx4 v152, s[14:15]
	s_waitcnt vmcnt(6)
	s_barrier
	v_mfma_f32_16x16x32_bf16 v[44:47], v[220:223], v[178:181], v[44:47]
	v_mfma_f32_16x16x32_bf16 v[40:43], v[228:231], v[178:181], v[40:43]
	v_mfma_f32_16x16x32_bf16 v[28:31], v[220:223], v[196:199], v[28:31]
	v_mfma_f32_16x16x32_bf16 v[24:27], v[228:231], v[196:199], v[24:27]
	v_mfma_f32_16x16x32_bf16 v[12:15], v[220:223], v[204:207], v[12:15]
	v_mfma_f32_16x16x32_bf16 v[8:11], v[228:231], v[204:207], v[8:11]
	v_mfma_f32_16x16x32_bf16 v[4:7], v[220:223], v[212:215], v[4:7]
	v_mfma_f32_16x16x32_bf16 v[0:3], v[228:231], v[212:215], v[0:3]
	v_mfma_f32_16x16x32_bf16 v[44:47], v[224:227], v[192:195], v[44:47]
	v_mfma_f32_16x16x32_bf16 v[40:43], v[232:235], v[192:195], v[40:43]
	v_mfma_f32_16x16x32_bf16 v[28:31], v[224:227], v[200:203], v[28:31]
	v_mfma_f32_16x16x32_bf16 v[24:27], v[232:235], v[200:203], v[24:27]
	v_mfma_f32_16x16x32_bf16 v[12:15], v[224:227], v[208:211], v[12:15]
	v_mfma_f32_16x16x32_bf16 v[8:11], v[232:235], v[208:211], v[8:11]
	v_mfma_f32_16x16x32_bf16 v[4:7], v[224:227], v[216:219], v[4:7]
	v_mfma_f32_16x16x32_bf16 v[0:3], v[232:235], v[216:219], v[0:3]
	s_add_i32 s16, 0, 0x18000
	s_barrier
	ds_read_b128 v[162:165], v250
	ds_read_b128 v[166:169], v250 offset:1024
	ds_read_b128 v[170:173], v250 offset:2048
	ds_read_b128 v[174:177], v250 offset:3072
	s_add_u32 s14, s30, 0x20000
	s_addc_u32 s15, s31, 0
	s_mov_b32 m0, s42
	ds_read_b128 v[178:181], v160 offset:32768
	ds_read_b128 v[192:195], v160 offset:33792
	ds_read_b128 v[196:199], v160 offset:34816
	ds_read_b128 v[200:203], v160 offset:35840
	ds_read_b128 v[204:207], v160 offset:36864
	ds_read_b128 v[208:211], v160 offset:37888
	ds_read_b128 v[212:215], v160 offset:38912
	ds_read_b128 v[216:219], v160 offset:39936
	global_load_lds_dwordx4 v148, s[14:15]
	s_mov_b32 m0, s43
	s_nop 0
	global_load_lds_dwordx4 v150, s[14:15]
	s_waitcnt lgkmcnt(8)
	s_barrier
; #define PG8_STAGE(bufoff, gbase, voff) do { _Pragma("unroll") for (int _i = 0; _i < 2; ++_i) \
;         __builtin_amdgcn_global_load_lds((const unsigned*)((const char*)(gbase) + (voff)[_i]), (PG8_LAS unsigned*)(lds + (bufoff) + ldsw + _i * 8192), 16, 0, 0); } while (0)
; #define PG8_LDA(dst, b, h) do { _Pragma("unroll") for (int m = 0; m < 4; ++m) _Pragma("unroll") for (int k = 0; k < 2; ++k) dst[m][k] = *(const PG8_LAS bf16x8*)(lds + PG8_SA(b, h) + aoff + m * 2048 + k * 1024); } while (0)
; #define PG8_LDB(dst, b, h) do { _Pragma("unroll") for (int n = 0; n < 2; ++n) _Pragma("unroll") for (int k = 0; k < 2; ++k) dst[n][k] = *(const PG8_LAS bf16x8*)(lds + PG8_SB(b, h) + boff + n * 2048 + k * 1024); } while (0)
; #define PG8_MMA(ai, bj, At, Bt) do { __builtin_amdgcn_s_setprio(1); _Pragma("unroll") for (int m = 0; m < 4; ++m) _Pragma("unroll") for (int n = 0; n < 2; ++n) _Pragma("unroll") for (int k = 0; k < 2; ++k) \
;         acc[ai][bj][m][n] = __builtin_amdgcn_mfma_f32_16x16x32_bf16(Bt[n][k], At[m][k], acc[ai][bj][m][n], 0, 0, 0); __builtin_amdgcn_s_setprio(0); } while (0)
; #define PG8_WAIT_V(n) asm volatile("s_waitcnt vmcnt(" #n ")" ::: "memory")
; #define PG8_WAIT_L(n) asm volatile("s_waitcnt lgkmcnt(" #n ")" ::: "memory")
; #define PG8_BAR __builtin_amdgcn_s_barrier()
; #define PG8_SCHED __builtin_amdgcn_sched_barrier(0)
; template <class Epi, class Sched, bool STAMP = false>
; __device__ __forceinline__ void gemm_phase(PG8_LAS unsigned char* lds, const Gemm g, const Sched& S, const Epi& E, unsigned long long* stamps) {
;     ...
;             PG8_WAIT_L(8); PG8_BAR; PG8_WAIT_L(0); PG8_MMA(0, 0, At, B0); PG8_BAR; PG8_SCHED;
;             PG8_LDB(B1, 1, 1); PG8_STAGE(PG8_SB(1, 0), b3, voffB);
;             PG8_BAR; PG8_WAIT_L(0); PG8_MMA(0, 1, At, B1); PG8_BAR;
;             PG8_LDA(At, 1, 1); PG8_STAGE(PG8_SA(1, 0), a3, voffA);
;             PG8_BAR; PG8_WAIT_L(0); PG8_MMA(1, 0, At, B0); PG8_BAR; PG8_SCHED;
;             PG8_STAGE(PG8_SB(1, 1), b3 + hstep, voffB);
;             PG8_WAIT_V(6); PG8_BAR; PG8_MMA(1, 1, At, B1); PG8_BAR;
	s_waitcnt lgkmcnt(0)
	v_mfma_f32_16x16x32_bf16 v[124:127], v[162:165], v[178:181], v[124:127]
	v_mfma_f32_16x16x32_bf16 v[120:123], v[170:173], v[178:181], v[120:123]
	v_mfma_f32_16x16x32_bf16 v[116:119], v[162:165], v[196:199], v[116:119]
	v_mfma_f32_16x16x32_bf16 v[112:115], v[170:173], v[196:199], v[112:115]
	v_mfma_f32_16x16x32_bf16 v[100:103], v[162:165], v[204:207], v[100:103]
	v_mfma_f32_16x16x32_bf16 v[96:99], v[170:173], v[204:207], v[96:99]
	v_mfma_f32_16x16x32_bf16 v[84:87], v[162:165], v[212:215], v[84:87]
	v_mfma_f32_16x16x32_bf16 v[80:83], v[170:173], v[212:215], v[80:83]
	v_mfma_f32_16x16x32_bf16 v[124:127], v[166:169], v[192:195], v[124:127]
	v_mfma_f32_16x16x32_bf16 v[120:123], v[174:177], v[192:195], v[120:123]
	v_mfma_f32_16x16x32_bf16 v[116:119], v[166:169], v[200:203], v[116:119]
	v_mfma_f32_16x16x32_bf16 v[112:115], v[174:177], v[200:203], v[112:115]
	v_mfma_f32_16x16x32_bf16 v[100:103], v[166:169], v[208:211], v[100:103]
	v_mfma_f32_16x16x32_bf16 v[96:99], v[174:177], v[208:211], v[96:99]
	v_mfma_f32_16x16x32_bf16 v[84:87], v[166:169], v[216:219], v[84:87]
	v_mfma_f32_16x16x32_bf16 v[80:83], v[174:177], v[216:219], v[80:83]
	s_barrier
	s_add_i32 s17, 0, 0x1c000
	s_add_i32 s14, s16, s40
	s_mov_b32 m0, s14
	ds_read_b128 v[220:223], v251
	ds_read_b128 v[224:227], v251 offset:1024
	ds_read_b128 v[228:231], v251 offset:2048
	ds_read_b128 v[232:235], v251 offset:3072
	global_load_lds_dwordx4 v244, s[26:27]
	s_add_i32 m0, s14, 0x2000
	s_nop 0
	global_load_lds_dwordx4 v245, s[26:27]
	s_barrier
	s_waitcnt lgkmcnt(0)
	v_mfma_f32_16x16x32_bf16 v[108:111], v[220:223], v[178:181], v[108:111]
	v_mfma_f32_16x16x32_bf16 v[104:107], v[228:231], v[178:181], v[104:107]
	v_mfma_f32_16x16x32_bf16 v[92:95], v[220:223], v[196:199], v[92:95]
	v_mfma_f32_16x16x32_bf16 v[88:91], v[228:231], v[196:199], v[88:91]
	v_mfma_f32_16x16x32_bf16 v[76:79], v[220:223], v[204:207], v[76:79]
	v_mfma_f32_16x16x32_bf16 v[72:75], v[228:231], v[204:207], v[72:75]
	v_mfma_f32_16x16x32_bf16 v[68:71], v[220:223], v[212:215], v[68:71]
	v_mfma_f32_16x16x32_bf16 v[64:67], v[228:231], v[212:215], v[64:67]
	v_mfma_f32_16x16x32_bf16 v[108:111], v[224:227], v[192:195], v[108:111]
	v_mfma_f32_16x16x32_bf16 v[104:107], v[232:235], v[192:195], v[104:107]
	v_mfma_f32_16x16x32_bf16 v[92:95], v[224:227], v[200:203], v[92:95]
	v_mfma_f32_16x16x32_bf16 v[88:91], v[232:235], v[200:203], v[88:91]
	v_mfma_f32_16x16x32_bf16 v[76:79], v[224:227], v[208:211], v[76:79]
	v_mfma_f32_16x16x32_bf16 v[72:75], v[232:235], v[208:211], v[72:75]
	v_mfma_f32_16x16x32_bf16 v[68:71], v[224:227], v[216:219], v[68:71]
	v_mfma_f32_16x16x32_bf16 v[64:67], v[232:235], v[216:219], v[64:67]
	s_mov_b32 m0, s46
	s_barrier
	ds_read_b128 v[178:181], v160 offset:49152
	ds_read_b128 v[192:195], v160 offset:50176
	ds_read_b128 v[196:199], v160 offset:51200
	ds_read_b128 v[200:203], v160 offset:52224
	ds_read_b128 v[204:207], v160 offset:53248
	ds_read_b128 v[208:211], v160 offset:54272
	ds_read_b128 v[212:215], v160 offset:55296
	ds_read_b128 v[216:219], v160 offset:56320
	global_load_lds_dwordx4 v246, s[30:31]
	s_mov_b32 m0, s47
	s_nop 0
	global_load_lds_dwordx4 v247, s[30:31]
	s_barrier
	s_waitcnt lgkmcnt(0)
	v_mfma_f32_16x16x32_bf16 v[60:63], v[162:165], v[178:181], v[60:63]
	v_mfma_f32_16x16x32_bf16 v[56:59], v[170:173], v[178:181], v[56:59]
	v_mfma_f32_16x16x32_bf16 v[52:55], v[162:165], v[196:199], v[52:55]
	v_mfma_f32_16x16x32_bf16 v[48:51], v[170:173], v[196:199], v[48:51]
	v_mfma_f32_16x16x32_bf16 v[36:39], v[162:165], v[204:207], v[36:39]
	v_mfma_f32_16x16x32_bf16 v[32:35], v[170:173], v[204:207], v[32:35]
	v_mfma_f32_16x16x32_bf16 v[20:23], v[162:165], v[212:215], v[20:23]
	v_mfma_f32_16x16x32_bf16 v[16:19], v[170:173], v[212:215], v[16:19]
	v_mfma_f32_16x16x32_bf16 v[60:63], v[166:169], v[192:195], v[60:63]
	v_mfma_f32_16x16x32_bf16 v[56:59], v[174:177], v[192:195], v[56:59]
	v_mfma_f32_16x16x32_bf16 v[52:55], v[166:169], v[200:203], v[52:55]
	v_mfma_f32_16x16x32_bf16 v[48:51], v[174:177], v[200:203], v[48:51]
	v_mfma_f32_16x16x32_bf16 v[36:39], v[166:169], v[208:211], v[36:39]
	v_mfma_f32_16x16x32_bf16 v[32:35], v[174:177], v[208:211], v[32:35]
	v_mfma_f32_16x16x32_bf16 v[20:23], v[166:169], v[216:219], v[20:23]
	v_mfma_f32_16x16x32_bf16 v[16:19], v[174:177], v[216:219], v[16:19]
	s_barrier
	s_add_u32 s14, s26, 0x20080
	s_addc_u32 s15, s27, 0
	s_add_i32 s16, s17, s40
	s_mov_b32 m0, s16
	s_nop 0
	global_load_lds_dwordx4 v128, s[14:15]
	s_add_i32 m0, s16, 0x2000
	s_nop 0
	global_load_lds_dwordx4 v152, s[14:15]
	s_waitcnt vmcnt(6)
	s_barrier
	v_mfma_f32_16x16x32_bf16 v[44:47], v[220:223], v[178:181], v[44:47]
	v_mfma_f32_16x16x32_bf16 v[40:43], v[228:231], v[178:181], v[40:43]
	v_mfma_f32_16x16x32_bf16 v[28:31], v[220:223], v[196:199], v[28:31]
	v_mfma_f32_16x16x32_bf16 v[24:27], v[228:231], v[196:199], v[24:27]
	v_mfma_f32_16x16x32_bf16 v[12:15], v[220:223], v[204:207], v[12:15]
	v_mfma_f32_16x16x32_bf16 v[8:11], v[228:231], v[204:207], v[8:11]
	v_mfma_f32_16x16x32_bf16 v[4:7], v[220:223], v[212:215], v[4:7]
	v_mfma_f32_16x16x32_bf16 v[0:3], v[228:231], v[212:215], v[0:3]
	v_mfma_f32_16x16x32_bf16 v[44:47], v[224:227], v[192:195], v[44:47]
	v_mfma_f32_16x16x32_bf16 v[40:43], v[232:235], v[192:195], v[40:43]
	v_mfma_f32_16x16x32_bf16 v[28:31], v[224:227], v[200:203], v[28:31]
	v_mfma_f32_16x16x32_bf16 v[24:27], v[232:235], v[200:203], v[24:27]
	v_mfma_f32_16x16x32_bf16 v[12:15], v[224:227], v[208:211], v[12:15]
	v_mfma_f32_16x16x32_bf16 v[8:11], v[232:235], v[208:211], v[8:11]
	v_mfma_f32_16x16x32_bf16 v[4:7], v[224:227], v[216:219], v[4:7]
	v_mfma_f32_16x16x32_bf16 v[0:3], v[232:235], v[216:219], v[0:3]
	s_add_i32 s59, s59, 2
	s_add_u32 s24, s24, 0x100
	s_addc_u32 s25, s25, 0
	s_add_u32 s57, s57, 0x100
	s_addc_u32 s58, s58, 0
	s_cmp_gt_u32 s59, 5
	s_barrier
; __device__ __forceinline__ unsigned cvt_pk_bf16(float lo, float hi) { const f32x2_cv v = {lo, hi}; const bf16x2_cv b = __builtin_convertvector(v, bf16x2_cv); return __builtin_bit_cast(unsigned, b); }
; __device__ __forceinline__ float rstd_of(const float* rowss, int row) { return rsqrtf(rowss[row] * (1.0f / 1024.0f) + 1e-6f); }
;     __device__ __forceinline__ void operator()(const f32x4 (&acc)[2][2][4][2], const pg8::Unit& u, int wr, int wc, int fr, int fq) const {
;         const int row0 = u.pm * 256 + wr * 64 + fr, col0 = u.pn * 256 + wc * 32 + 8 * fq;
; #pragma unroll
;         for (int ai = 0; ai < 2; ++ai)
; #pragma unroll
;             for (int m = 0; m < 4; ++m) {
;                 const int row = row0 + ai * 128 + m * 16;
;                 const float s = (MODE == 2) ? 1.0f : rstd_of(rowss, row);
;                 bf16_t* rowp = O + (size_t)row * ldc + col0;
; #pragma unroll
;                 for (int bj = 0; bj < 2; ++bj) {
;                     f32x4 v0 = acc[ai][bj][m][0] * s, v1 = acc[ai][bj][m][1] * s;
;                     if (MODE == 1) {
; #pragma unroll
;                         for (int j = 0; j < 4; ++j) { const float a = fmaxf(v0[j], 0.f), b = fmaxf(v1[j], 0.f); v0[j] = a * a; v1[j] = b * b; } }
;                     u32x4 w; w.x = cvt_pk_bf16(v0[0], v0[1]); w.y = cvt_pk_bf16(v0[2], v0[3]); w.z = cvt_pk_bf16(v1[0], v1[1]); w.w = cvt_pk_bf16(v1[2], v1[3]);
;                     *(u32x4*)(rowp + bj * 128) = w; } }
	s_cbranch_scc0 .LBB0_293
	v_lshl_add_u32 v162, s2, 8, v139
	v_lshl_or_b32 v164, s49, 8, v159
	v_ashrrev_i32_e32 v163, 31, v162
	v_ashrrev_i32_e32 v165, 31, v164
	v_lshlrev_b64 v[166:167], 11, v[162:163]
	v_lshl_add_u64 v[166:167], s[0:1], 0, v[166:167]
	v_lshlrev_b64 v[164:165], 1, v[164:165]
	v_lshl_add_u64 v[166:167], v[166:167], 0, v[164:165]
	s_mov_b32 s2, 0x40000
	s_mov_b64 s[14:15], 0x40000
	v_cvt_pk_bf16_f32 v60, v60, v61
	v_cvt_pk_bf16_f32 v61, v62, v63
	v_cvt_pk_bf16_f32 v62, v56, v57
	v_add_co_u32_e32 v56, vcc, s2, v166
	v_cvt_pk_bf16_f32 v68, v68, v69
	v_cvt_pk_bf16_f32 v69, v70, v71
	v_cvt_pk_bf16_f32 v70, v64, v65
	v_lshl_add_u64 v[64:65], v[166:167], 0, s[14:15]
	v_addc_co_u32_e32 v57, vcc, 0, v167, vcc
	v_cvt_pk_bf16_f32 v44, v44, v45
	v_cvt_pk_bf16_f32 v45, v46, v47
	v_cvt_pk_bf16_f32 v46, v40, v41
	v_cvt_pk_bf16_f32 v47, v42, v43
	s_mov_b32 s2, 0x48000
	v_cvt_pk_bf16_f32 v108, v108, v109
	v_cvt_pk_bf16_f32 v109, v110, v111
	v_cvt_pk_bf16_f32 v110, v104, v105
	v_or_b32_e32 v104, 16, v162
	global_store_dwordx4 v[64:65], v[44:47], off offset:256
	s_mov_b64 s[14:15], 0x48000
	v_ashrrev_i32_e32 v105, 31, v104
	v_add_co_u32_e32 v46, vcc, s2, v166
	v_cvt_pk_bf16_f32 v92, v92, v93
	v_cvt_pk_bf16_f32 v93, v94, v95
	v_cvt_pk_bf16_f32 v94, v88, v89
	v_or_b32_e32 v88, 32, v162
	v_lshl_add_u64 v[44:45], v[166:167], 0, s[14:15]
	v_addc_co_u32_e32 v47, vcc, 0, v167, vcc
	v_cvt_pk_bf16_f32 v28, v28, v29
	v_cvt_pk_bf16_f32 v29, v30, v31
	v_cvt_pk_bf16_f32 v30, v24, v25
	v_cvt_pk_bf16_f32 v31, v26, v27
	s_mov_b32 s2, 0x50000
	v_lshlrev_b64 v[104:105], 11, v[104:105]
	v_ashrrev_i32_e32 v89, 31, v88
	v_cvt_pk_bf16_f32 v76, v76, v77
	v_cvt_pk_bf16_f32 v77, v78, v79
	v_cvt_pk_bf16_f32 v78, v72, v73
	v_or_b32_e32 v72, 48, v162
	global_store_dwordx4 v[44:45], v[28:31], off offset:256
	s_mov_b64 s[14:15], 0x50000
	v_cvt_pk_bf16_f32 v111, v106, v107
	v_add_co_u32_e32 v30, vcc, s2, v166
	v_lshl_add_u64 v[104:105], s[0:1], 0, v[104:105]
	v_lshlrev_b64 v[88:89], 11, v[88:89]
	v_ashrrev_i32_e32 v73, 31, v72
	v_lshl_add_u64 v[28:29], v[166:167], 0, s[14:15]
	v_addc_co_u32_e32 v31, vcc, 0, v167, vcc
	v_cvt_pk_bf16_f32 v12, v12, v13
	v_cvt_pk_bf16_f32 v13, v14, v15
	v_cvt_pk_bf16_f32 v14, v8, v9
	v_cvt_pk_bf16_f32 v15, v10, v11
	s_mov_b32 s2, 0x58000
	global_store_dwordx4 v[166:167], v[108:111], off offset:256
	v_cvt_pk_bf16_f32 v95, v90, v91
	v_lshl_add_u64 v[88:89], s[0:1], 0, v[88:89]
	v_lshl_add_u64 v[108:109], v[104:105], 0, v[164:165]
	v_lshlrev_b64 v[72:73], 11, v[72:73]
	global_store_dwordx4 v[28:29], v[12:15], off offset:256
	global_store_dwordx4 v[108:109], v[92:95], off offset:256
	v_cvt_pk_bf16_f32 v79, v74, v75
	v_add_co_u32_e32 v14, vcc, s2, v166
	v_lshl_add_u64 v[92:93], v[88:89], 0, v[164:165]
	v_lshl_add_u64 v[72:73], s[0:1], 0, v[72:73]
	s_mov_b64 s[14:15], 0x58000
	v_addc_co_u32_e32 v15, vcc, 0, v167, vcc
	v_cvt_pk_bf16_f32 v124, v124, v125
	v_cvt_pk_bf16_f32 v125, v126, v127
	v_cvt_pk_bf16_f32 v126, v120, v121
	v_cvt_pk_bf16_f32 v127, v122, v123
	v_cvt_pk_bf16_f32 v104, v116, v117
	v_cvt_pk_bf16_f32 v105, v118, v119
	v_cvt_pk_bf16_f32 v106, v112, v113
	v_cvt_pk_bf16_f32 v107, v114, v115
	v_cvt_pk_bf16_f32 v88, v100, v101
	v_cvt_pk_bf16_f32 v89, v102, v103
	v_cvt_pk_bf16_f32 v90, v96, v97
	v_cvt_pk_bf16_f32 v91, v98, v99
	global_store_dwordx4 v[92:93], v[76:79], off offset:256
	v_cvt_pk_bf16_f32 v74, v80, v81
	v_cvt_pk_bf16_f32 v75, v82, v83
	v_lshl_add_u64 v[76:77], v[72:73], 0, v[164:165]
	v_cvt_pk_bf16_f32 v72, v84, v85
	v_cvt_pk_bf16_f32 v73, v86, v87
	v_cvt_pk_bf16_f32 v71, v66, v67
	v_cvt_pk_bf16_f32 v63, v58, v59
	v_cvt_pk_bf16_f32 v40, v52, v53
	v_cvt_pk_bf16_f32 v41, v54, v55
	v_cvt_pk_bf16_f32 v42, v48, v49
	v_cvt_pk_bf16_f32 v43, v50, v51
	v_cvt_pk_bf16_f32 v24, v36, v37
	v_cvt_pk_bf16_f32 v25, v38, v39
	v_cvt_pk_bf16_f32 v26, v32, v33
	v_cvt_pk_bf16_f32 v27, v34, v35
	v_lshl_add_u64 v[12:13], v[166:167], 0, s[14:15]
	v_cvt_pk_bf16_f32 v8, v20, v21
	v_cvt_pk_bf16_f32 v9, v22, v23
	v_cvt_pk_bf16_f32 v10, v16, v17
	v_cvt_pk_bf16_f32 v11, v18, v19
	v_cvt_pk_bf16_f32 v4, v4, v5
	v_cvt_pk_bf16_f32 v5, v6, v7
	v_cvt_pk_bf16_f32 v6, v0, v1
	v_cvt_pk_bf16_f32 v7, v2, v3
	s_and_b64 vcc, exec, s[38:39]
	s_mov_b32 s49, s4
	s_mov_b32 s2, s6
	s_mov_b64 s[26:27], s[22:23]
	s_mov_b64 s[24:25], s[12:13]
	s_movk_i32 s58, 0xff60
	global_store_dwordx4 v[166:167], v[124:127], off
	global_store_dwordx4 v[108:109], v[104:107], off
	global_store_dwordx4 v[92:93], v[88:91], off
	global_store_dwordx4 v[76:77], v[72:75], off
	global_store_dwordx4 v[76:77], v[68:71], off offset:256
	global_store_dwordx4 v[56:57], v[60:63], off
	global_store_dwordx4 v[46:47], v[40:43], off
	global_store_dwordx4 v[30:31], v[24:27], off
	global_store_dwordx4 v[14:15], v[8:11], off
	global_store_dwordx4 v[12:13], v[4:7], off offset:256
	s_cbranch_vccz .LBB0_286
	s_cmpk_gt_u32 s36, 0xff
	s_cbranch_scc1 .LBB0_297
	s_barrier

; #define PG8_STAGE(bufoff, gbase, voff) do { _Pragma("unroll") for (int _i = 0; _i < 2; ++_i) \
;         __builtin_amdgcn_global_load_lds((const unsigned*)((const char*)(gbase) + (voff)[_i]), (PG8_LAS unsigned*)(lds + (bufoff) + ldsw + _i * 8192), 16, 0, 0); } while (0)
; #define PG8_LDA(dst, b, h) do { _Pragma("unroll") for (int m = 0; m < 4; ++m) _Pragma("unroll") for (int k = 0; k < 2; ++k) dst[m][k] = *(const PG8_LAS bf16x8*)(lds + PG8_SA(b, h) + aoff + m * 2048 + k * 1024); } while (0)
; #define PG8_LDB(dst, b, h) do { _Pragma("unroll") for (int n = 0; n < 2; ++n) _Pragma("unroll") for (int k = 0; k < 2; ++k) dst[n][k] = *(const PG8_LAS bf16x8*)(lds + PG8_SB(b, h) + boff + n * 2048 + k * 1024); } while (0)
; #define PG8_WAIT_L(n) asm volatile("s_waitcnt lgkmcnt(" #n ")" ::: "memory")
; #define PG8_BAR __builtin_amdgcn_s_barrier()
; #define PG8_SCHED __builtin_amdgcn_sched_barrier(0)
;     __device__ bool next(int i, pg8::Unit& u) const { if (i != 0 || !valid) return false; u.pm = pm; u.pn = pn; return true; }
; template <class Epi, class Sched, bool STAMP = false>
; __device__ __forceinline__ void gemm_phase(PG8_LAS unsigned char* lds, const Gemm g, const Sched& S, const Epi& E, unsigned long long* stamps) {
;     ...
;         const bool has_next = S.next(ui + 1, nxt);
;         const char* nA = has_next ? (const char*)g.A + (size_t)nxt.pm * tstep : cA; const char* nB = has_next ? (const char*)g.Bt + (size_t)nxt.pn * tstep : cB;
;         for (int t = 0; t < nt; t += 2) {
;             const bool last = (t == nt - 2);
;             const char* a1 = cA + (size_t)(t + 1) * kstep;
;             const char* a2 = last ? nA : cA + (size_t)(t + 2) * kstep; const char* b2 = last ? nB : cB + (size_t)(t + 2) * kstep;
;             const char* a3 = a2 + kstep; const char* b3 = b2 + kstep;
;             if (last && has_next) S.a_ready(nxt);
;             PG8_LDB(B0, 0, 0); PG8_SCHED; PG8_LDA(At, 0, 0); PG8_STAGE(PG8_SA(1, 1), a1 + hstep, voffA);
;             PG8_WAIT_L(8); PG8_BAR; PG8_WAIT_L(0); PG8_MMA(0, 0, At, B0); PG8_BAR; PG8_SCHED;
;     ...
; #pragma unroll
;         for (int a = 0; a < 2; ++a)
; #pragma unroll
;             for (int b = 0; b < 2; ++b)
; #pragma unroll
;                 for (int m = 0; m < 4; ++m)
; #pragma unroll
;                     for (int n = 0; n < 2; ++n) acc[a][b][m][n] = (f32x4){0.f, 0.f, 0.f, 0.f};
.LBB0_312:
	s_ashr_i32 s31, s30, 31
	s_lshl_b64 s[14:15], s[30:31], 19
	s_add_u32 s48, s42, s14
	v_cmp_lt_i64_e32 vcc, s[24:25], v[136:137]
	s_addc_u32 s49, s43, s15
	s_and_b64 s[14:15], vcc, exec
	s_cselect_b32 s31, s49, s5
	s_cselect_b32 s47, s48, s4
	s_ashr_i32 s7, s6, 31
	s_lshl_b64 s[14:15], s[6:7], 19
	s_add_u32 s24, s22, s14
	s_addc_u32 s25, s23, s15
	s_and_b64 s[14:15], vcc, exec
	s_cselect_b32 s7, s25, s13
	s_cselect_b32 s53, s24, s12
	s_add_u32 s4, s4, 0x40080
	s_addc_u32 s5, s5, 0
	s_add_u32 s62, s12, 0x100
	v_mov_b32_e32 v0, 0
	s_addc_u32 s63, s13, 0
	s_mov_b32 s65, -2
	v_mov_b32_e32 v1, v0
	v_mov_b32_e32 v2, v0
	v_mov_b32_e32 v3, v0
	v_mov_b32_e32 v4, v0
	v_mov_b32_e32 v5, v0
	v_mov_b32_e32 v6, v0
	v_mov_b32_e32 v7, v0
	v_mov_b32_e32 v16, v0
	v_mov_b32_e32 v17, v0
	v_mov_b32_e32 v18, v0
	v_mov_b32_e32 v19, v0
	v_mov_b32_e32 v20, v0
	v_mov_b32_e32 v21, v0
	v_mov_b32_e32 v22, v0
	v_mov_b32_e32 v23, v0
	v_mov_b32_e32 v32, v0
	v_mov_b32_e32 v33, v0
	v_mov_b32_e32 v34, v0
	v_mov_b32_e32 v35, v0
	v_mov_b32_e32 v36, v0
	v_mov_b32_e32 v37, v0
	v_mov_b32_e32 v38, v0
	v_mov_b32_e32 v39, v0
	v_mov_b32_e32 v48, v0
	v_mov_b32_e32 v49, v0
	v_mov_b32_e32 v50, v0
	v_mov_b32_e32 v51, v0
	v_mov_b32_e32 v52, v0
	v_mov_b32_e32 v53, v0
	v_mov_b32_e32 v54, v0
	v_mov_b32_e32 v55, v0
	v_mov_b32_e32 v8, v0
	v_mov_b32_e32 v9, v0
	v_mov_b32_e32 v10, v0
	v_mov_b32_e32 v11, v0
	v_mov_b32_e32 v12, v0
	v_mov_b32_e32 v13, v0
	v_mov_b32_e32 v14, v0
	v_mov_b32_e32 v15, v0
	v_mov_b32_e32 v24, v0
	v_mov_b32_e32 v25, v0
	v_mov_b32_e32 v26, v0
	v_mov_b32_e32 v27, v0
	v_mov_b32_e32 v28, v0
	v_mov_b32_e32 v29, v0
	v_mov_b32_e32 v30, v0
	v_mov_b32_e32 v31, v0
	v_mov_b32_e32 v40, v0
	v_mov_b32_e32 v41, v0
	v_mov_b32_e32 v42, v0
	v_mov_b32_e32 v43, v0
	v_mov_b32_e32 v44, v0
	v_mov_b32_e32 v45, v0
	v_mov_b32_e32 v46, v0
	v_mov_b32_e32 v47, v0
	v_mov_b32_e32 v56, v0
	v_mov_b32_e32 v57, v0
	v_mov_b32_e32 v58, v0
	v_mov_b32_e32 v59, v0
	v_mov_b32_e32 v60, v0
	v_mov_b32_e32 v61, v0
	v_mov_b32_e32 v62, v0
	v_mov_b32_e32 v63, v0
	v_mov_b32_e32 v64, v0
	v_mov_b32_e32 v65, v0
	v_mov_b32_e32 v66, v0
	v_mov_b32_e32 v67, v0
	v_mov_b32_e32 v68, v0
	v_mov_b32_e32 v69, v0
	v_mov_b32_e32 v70, v0
	v_mov_b32_e32 v71, v0
	v_mov_b32_e32 v80, v0
	v_mov_b32_e32 v81, v0
	v_mov_b32_e32 v82, v0
	v_mov_b32_e32 v83, v0
	v_mov_b32_e32 v84, v0
	v_mov_b32_e32 v85, v0
	v_mov_b32_e32 v86, v0
	v_mov_b32_e32 v87, v0
	v_mov_b32_e32 v96, v0
	v_mov_b32_e32 v97, v0
	v_mov_b32_e32 v98, v0
	v_mov_b32_e32 v99, v0
	v_mov_b32_e32 v100, v0
	v_mov_b32_e32 v101, v0
	v_mov_b32_e32 v102, v0
	v_mov_b32_e32 v103, v0
	v_mov_b32_e32 v112, v0
	v_mov_b32_e32 v113, v0
	v_mov_b32_e32 v114, v0
	v_mov_b32_e32 v115, v0
	v_mov_b32_e32 v116, v0
	v_mov_b32_e32 v117, v0
	v_mov_b32_e32 v118, v0
	v_mov_b32_e32 v119, v0
	v_mov_b32_e32 v72, v0
	v_mov_b32_e32 v73, v0
	v_mov_b32_e32 v74, v0
	v_mov_b32_e32 v75, v0
	v_mov_b32_e32 v76, v0
	v_mov_b32_e32 v77, v0
	v_mov_b32_e32 v78, v0
	v_mov_b32_e32 v79, v0
	v_mov_b32_e32 v88, v0
	v_mov_b32_e32 v89, v0
	v_mov_b32_e32 v90, v0
	v_mov_b32_e32 v91, v0
	v_mov_b32_e32 v92, v0
	v_mov_b32_e32 v93, v0
	v_mov_b32_e32 v94, v0
	v_mov_b32_e32 v95, v0
	v_mov_b32_e32 v104, v0
	v_mov_b32_e32 v105, v0
	v_mov_b32_e32 v106, v0
	v_mov_b32_e32 v107, v0
	v_mov_b32_e32 v108, v0
	v_mov_b32_e32 v109, v0
	v_mov_b32_e32 v110, v0
	v_mov_b32_e32 v111, v0
	v_mov_b32_e32 v120, v0
	v_mov_b32_e32 v121, v0
	v_mov_b32_e32 v122, v0
	v_mov_b32_e32 v123, v0
	v_mov_b32_e32 v124, v0
	v_mov_b32_e32 v125, v0
	v_mov_b32_e32 v126, v0
	v_mov_b32_e32 v127, v0
	v_add_u32_e32 v244, 0x80, v128
	v_add_u32_e32 v245, 0x80, v152
	v_add_u32_e32 v246, 0x80, v148
	v_add_u32_e32 v247, 0x80, v150
	v_add_u32_e32 v248, 0x10000, v167
	v_add_u32_e32 v249, 0x14000, v167
	v_add_u32_e32 v250, 0x18000, v167
	v_add_u32_e32 v251, 0x1c000, v167
.LBB0_313:
	s_add_u32 s12, s4, 0xfffc0080
	s_addc_u32 s13, s5, -1
	s_add_i32 s14, 0, 0x10000
	ds_read_b128 v[158:161], v248
	ds_read_b128 v[162:165], v248 offset:1024
	ds_read_b128 v[170:173], v248 offset:2048
	ds_read_b128 v[174:177], v248 offset:3072
	s_cmp_eq_u32 s65, 12
	s_cselect_b32 s27, s31, s13
	s_cselect_b32 s26, s47, s12
	s_cselect_b32 s13, s7, s63
	s_cselect_b32 s12, s53, s62
	s_add_i32 m0, s3, 0xc000
	ds_read_b128 v[178:181], v169
	ds_read_b128 v[192:195], v169 offset:1024
	ds_read_b128 v[196:199], v169 offset:2048
	ds_read_b128 v[200:203], v169 offset:3072
	ds_read_b128 v[204:207], v169 offset:4096
	ds_read_b128 v[208:211], v169 offset:5120
	ds_read_b128 v[212:215], v169 offset:6144
	ds_read_b128 v[216:219], v169 offset:7168
	global_load_lds_dwordx4 v154, s[4:5]
	s_add_i32 m0, s3, 0xe000
	s_nop 0
	global_load_lds_dwordx4 v156, s[4:5]
	s_waitcnt lgkmcnt(8)
	s_barrier
	s_waitcnt lgkmcnt(0)
	v_mfma_f32_16x16x32_bf16 v[124:127], v[158:161], v[178:181], v[124:127]
	v_mfma_f32_16x16x32_bf16 v[120:123], v[170:173], v[178:181], v[120:123]
	v_mfma_f32_16x16x32_bf16 v[108:111], v[158:161], v[196:199], v[108:111]
	v_mfma_f32_16x16x32_bf16 v[104:107], v[170:173], v[196:199], v[104:107]
	v_mfma_f32_16x16x32_bf16 v[92:95], v[158:161], v[204:207], v[92:95]
	v_mfma_f32_16x16x32_bf16 v[88:91], v[170:173], v[204:207], v[88:91]
	v_mfma_f32_16x16x32_bf16 v[76:79], v[158:161], v[212:215], v[76:79]
	v_mfma_f32_16x16x32_bf16 v[72:75], v[170:173], v[212:215], v[72:75]
	v_mfma_f32_16x16x32_bf16 v[124:127], v[162:165], v[192:195], v[124:127]
	v_mfma_f32_16x16x32_bf16 v[120:123], v[174:177], v[192:195], v[120:123]
	v_mfma_f32_16x16x32_bf16 v[108:111], v[162:165], v[200:203], v[108:111]
	v_mfma_f32_16x16x32_bf16 v[104:107], v[174:177], v[200:203], v[104:107]
	v_mfma_f32_16x16x32_bf16 v[92:95], v[162:165], v[208:211], v[92:95]
	v_mfma_f32_16x16x32_bf16 v[88:91], v[174:177], v[208:211], v[88:91]
	v_mfma_f32_16x16x32_bf16 v[76:79], v[162:165], v[216:219], v[76:79]
	v_mfma_f32_16x16x32_bf16 v[72:75], v[174:177], v[216:219], v[72:75]
	s_barrier
; #define PG8_STAGE(bufoff, gbase, voff) do { _Pragma("unroll") for (int _i = 0; _i < 2; ++_i) \
;         __builtin_amdgcn_global_load_lds((const unsigned*)((const char*)(gbase) + (voff)[_i]), (PG8_LAS unsigned*)(lds + (bufoff) + ldsw + _i * 8192), 16, 0, 0); } while (0)
; #define PG8_LDA(dst, b, h) do { _Pragma("unroll") for (int m = 0; m < 4; ++m) _Pragma("unroll") for (int k = 0; k < 2; ++k) dst[m][k] = *(const PG8_LAS bf16x8*)(lds + PG8_SA(b, h) + aoff + m * 2048 + k * 1024); } while (0)
; #define PG8_LDB(dst, b, h) do { _Pragma("unroll") for (int n = 0; n < 2; ++n) _Pragma("unroll") for (int k = 0; k < 2; ++k) dst[n][k] = *(const PG8_LAS bf16x8*)(lds + PG8_SB(b, h) + boff + n * 2048 + k * 1024); } while (0)
; #define PG8_MMA(ai, bj, At, Bt) do { __builtin_amdgcn_s_setprio(1); _Pragma("unroll") for (int m = 0; m < 4; ++m) _Pragma("unroll") for (int n = 0; n < 2; ++n) _Pragma("unroll") for (int k = 0; k < 2; ++k) \
;         acc[ai][bj][m][n] = __builtin_amdgcn_mfma_f32_16x16x32_bf16(Bt[n][k], At[m][k], acc[ai][bj][m][n], 0, 0, 0); __builtin_amdgcn_s_setprio(0); } while (0)
; #define PG8_WAIT_V(n) asm volatile("s_waitcnt vmcnt(" #n ")" ::: "memory")
; #define PG8_WAIT_L(n) asm volatile("s_waitcnt lgkmcnt(" #n ")" ::: "memory")
; #define PG8_BAR __builtin_amdgcn_s_barrier()
; #define PG8_SCHED __builtin_amdgcn_sched_barrier(0)
; template <class Epi, class Sched, bool STAMP = false>
; __device__ __forceinline__ void gemm_phase(PG8_LAS unsigned char* lds, const Gemm g, const Sched& S, const Epi& E, unsigned long long* stamps) {
;     ...
;             PG8_LDB(B1, 0, 1); PG8_STAGE(PG8_SB(0, 0), b2, voffB);
;             PG8_BAR; PG8_WAIT_L(0); PG8_MMA(0, 1, At, B1); PG8_BAR;
;             PG8_LDA(At, 0, 1); PG8_STAGE(PG8_SA(0, 0), a2, voffA);
;             PG8_BAR; PG8_WAIT_L(0); PG8_MMA(1, 0, At, B0); PG8_BAR; PG8_SCHED;
;             PG8_STAGE(PG8_SB(0, 1), b2 + hstep, voffB);
;             PG8_WAIT_V(6); PG8_BAR; PG8_MMA(1, 1, At, B1); PG8_BAR;
;             PG8_LDB(B0, 1, 0); PG8_SCHED; PG8_LDA(At, 1, 0); PG8_STAGE(PG8_SA(0, 1), a2 + hstep, voffA);
;             PG8_WAIT_L(8); PG8_BAR; PG8_WAIT_L(0); PG8_MMA(0, 0, At, B0); PG8_BAR; PG8_SCHED;
	s_add_i32 s16, 0, 0x14000
	s_add_i32 s14, s14, s56
	s_mov_b32 m0, s14
	ds_read_b128 v[220:223], v249
	ds_read_b128 v[224:227], v249 offset:1024
	ds_read_b128 v[228:231], v249 offset:2048
	ds_read_b128 v[232:235], v249 offset:3072
	global_load_lds_dwordx4 v128, s[12:13]
	s_add_i32 m0, s14, 0x2000
	s_nop 0
	global_load_lds_dwordx4 v152, s[12:13]
	s_barrier
	s_waitcnt lgkmcnt(0)
	v_mfma_f32_16x16x32_bf16 v[116:119], v[220:223], v[178:181], v[116:119]
	v_mfma_f32_16x16x32_bf16 v[112:115], v[228:231], v[178:181], v[112:115]
	v_mfma_f32_16x16x32_bf16 v[100:103], v[220:223], v[196:199], v[100:103]
	v_mfma_f32_16x16x32_bf16 v[96:99], v[228:231], v[196:199], v[96:99]
	v_mfma_f32_16x16x32_bf16 v[84:87], v[220:223], v[204:207], v[84:87]
	v_mfma_f32_16x16x32_bf16 v[80:83], v[228:231], v[204:207], v[80:83]
	v_mfma_f32_16x16x32_bf16 v[68:71], v[220:223], v[212:215], v[68:71]
	v_mfma_f32_16x16x32_bf16 v[64:67], v[228:231], v[212:215], v[64:67]
	v_mfma_f32_16x16x32_bf16 v[116:119], v[224:227], v[192:195], v[116:119]
	v_mfma_f32_16x16x32_bf16 v[112:115], v[232:235], v[192:195], v[112:115]
	v_mfma_f32_16x16x32_bf16 v[100:103], v[224:227], v[200:203], v[100:103]
	v_mfma_f32_16x16x32_bf16 v[96:99], v[232:235], v[200:203], v[96:99]
	v_mfma_f32_16x16x32_bf16 v[84:87], v[224:227], v[208:211], v[84:87]
	v_mfma_f32_16x16x32_bf16 v[80:83], v[232:235], v[208:211], v[80:83]
	v_mfma_f32_16x16x32_bf16 v[68:71], v[224:227], v[216:219], v[68:71]
	v_mfma_f32_16x16x32_bf16 v[64:67], v[232:235], v[216:219], v[64:67]
	s_mov_b32 m0, s3
	s_barrier
	ds_read_b128 v[178:181], v169 offset:16384
	ds_read_b128 v[192:195], v169 offset:17408
	ds_read_b128 v[196:199], v169 offset:18432
	ds_read_b128 v[200:203], v169 offset:19456
	ds_read_b128 v[204:207], v169 offset:20480
	ds_read_b128 v[208:211], v169 offset:21504
	ds_read_b128 v[212:215], v169 offset:22528
	ds_read_b128 v[216:219], v169 offset:23552
	global_load_lds_dwordx4 v148, s[26:27]
	s_mov_b32 m0, s57
	s_nop 0
	global_load_lds_dwordx4 v150, s[26:27]
	s_barrier
	s_waitcnt lgkmcnt(0)
	v_mfma_f32_16x16x32_bf16 v[60:63], v[158:161], v[178:181], v[60:63]
	v_mfma_f32_16x16x32_bf16 v[56:59], v[170:173], v[178:181], v[56:59]
	v_mfma_f32_16x16x32_bf16 v[44:47], v[158:161], v[196:199], v[44:47]
	v_mfma_f32_16x16x32_bf16 v[40:43], v[170:173], v[196:199], v[40:43]
	v_mfma_f32_16x16x32_bf16 v[28:31], v[158:161], v[204:207], v[28:31]
	v_mfma_f32_16x16x32_bf16 v[24:27], v[170:173], v[204:207], v[24:27]
	v_mfma_f32_16x16x32_bf16 v[12:15], v[158:161], v[212:215], v[12:15]
	v_mfma_f32_16x16x32_bf16 v[8:11], v[170:173], v[212:215], v[8:11]
	v_mfma_f32_16x16x32_bf16 v[60:63], v[162:165], v[192:195], v[60:63]
	v_mfma_f32_16x16x32_bf16 v[56:59], v[174:177], v[192:195], v[56:59]
	v_mfma_f32_16x16x32_bf16 v[44:47], v[162:165], v[200:203], v[44:47]
	v_mfma_f32_16x16x32_bf16 v[40:43], v[174:177], v[200:203], v[40:43]
	v_mfma_f32_16x16x32_bf16 v[28:31], v[162:165], v[208:211], v[28:31]
	v_mfma_f32_16x16x32_bf16 v[24:27], v[174:177], v[208:211], v[24:27]
	v_mfma_f32_16x16x32_bf16 v[12:15], v[162:165], v[216:219], v[12:15]
	v_mfma_f32_16x16x32_bf16 v[8:11], v[174:177], v[216:219], v[8:11]
	s_barrier
	s_add_u32 s14, s12, 0x40000
	s_addc_u32 s15, s13, 0
	s_add_i32 s16, s16, s56
	s_mov_b32 m0, s16
	s_nop 0
	global_load_lds_dwordx4 v128, s[14:15]
	s_add_i32 m0, s16, 0x2000
	s_nop 0
	global_load_lds_dwordx4 v152, s[14:15]
	s_waitcnt vmcnt(6)
	s_barrier
	v_mfma_f32_16x16x32_bf16 v[52:55], v[220:223], v[178:181], v[52:55]
	v_mfma_f32_16x16x32_bf16 v[48:51], v[228:231], v[178:181], v[48:51]
	v_mfma_f32_16x16x32_bf16 v[36:39], v[220:223], v[196:199], v[36:39]
	v_mfma_f32_16x16x32_bf16 v[32:35], v[228:231], v[196:199], v[32:35]
	v_mfma_f32_16x16x32_bf16 v[20:23], v[220:223], v[204:207], v[20:23]
	v_mfma_f32_16x16x32_bf16 v[16:19], v[228:231], v[204:207], v[16:19]
	v_mfma_f32_16x16x32_bf16 v[4:7], v[220:223], v[212:215], v[4:7]
	v_mfma_f32_16x16x32_bf16 v[0:3], v[228:231], v[212:215], v[0:3]
	v_mfma_f32_16x16x32_bf16 v[52:55], v[224:227], v[192:195], v[52:55]
	v_mfma_f32_16x16x32_bf16 v[48:51], v[232:235], v[192:195], v[48:51]
	v_mfma_f32_16x16x32_bf16 v[36:39], v[224:227], v[200:203], v[36:39]
	v_mfma_f32_16x16x32_bf16 v[32:35], v[232:235], v[200:203], v[32:35]
	v_mfma_f32_16x16x32_bf16 v[20:23], v[224:227], v[208:211], v[20:23]
	v_mfma_f32_16x16x32_bf16 v[16:19], v[232:235], v[208:211], v[16:19]
	v_mfma_f32_16x16x32_bf16 v[4:7], v[224:227], v[216:219], v[4:7]
	v_mfma_f32_16x16x32_bf16 v[0:3], v[232:235], v[216:219], v[0:3]
	s_add_i32 s16, 0, 0x18000
	s_barrier
	ds_read_b128 v[158:161], v250
	ds_read_b128 v[162:165], v250 offset:1024
	ds_read_b128 v[170:173], v250 offset:2048
	ds_read_b128 v[174:177], v250 offset:3072
	s_add_u32 s14, s26, 0x40000
	s_addc_u32 s15, s27, 0
	s_mov_b32 m0, s58
	ds_read_b128 v[178:181], v169 offset:32768
	ds_read_b128 v[192:195], v169 offset:33792
	ds_read_b128 v[196:199], v169 offset:34816
	ds_read_b128 v[200:203], v169 offset:35840
	ds_read_b128 v[204:207], v169 offset:36864
	ds_read_b128 v[208:211], v169 offset:37888
	ds_read_b128 v[212:215], v169 offset:38912
	ds_read_b128 v[216:219], v169 offset:39936
	global_load_lds_dwordx4 v148, s[14:15]
	s_mov_b32 m0, s59
	s_nop 0
	global_load_lds_dwordx4 v150, s[14:15]
	s_waitcnt lgkmcnt(8)
	s_barrier
; #define PG8_STAGE(bufoff, gbase, voff) do { _Pragma("unroll") for (int _i = 0; _i < 2; ++_i) \
;         __builtin_amdgcn_global_load_lds((const unsigned*)((const char*)(gbase) + (voff)[_i]), (PG8_LAS unsigned*)(lds + (bufoff) + ldsw + _i * 8192), 16, 0, 0); } while (0)
; #define PG8_LDA(dst, b, h) do { _Pragma("unroll") for (int m = 0; m < 4; ++m) _Pragma("unroll") for (int k = 0; k < 2; ++k) dst[m][k] = *(const PG8_LAS bf16x8*)(lds + PG8_SA(b, h) + aoff + m * 2048 + k * 1024); } while (0)
; #define PG8_LDB(dst, b, h) do { _Pragma("unroll") for (int n = 0; n < 2; ++n) _Pragma("unroll") for (int k = 0; k < 2; ++k) dst[n][k] = *(const PG8_LAS bf16x8*)(lds + PG8_SB(b, h) + boff + n * 2048 + k * 1024); } while (0)
; #define PG8_MMA(ai, bj, At, Bt) do { __builtin_amdgcn_s_setprio(1); _Pragma("unroll") for (int m = 0; m < 4; ++m) _Pragma("unroll") for (int n = 0; n < 2; ++n) _Pragma("unroll") for (int k = 0; k < 2; ++k) \
;         acc[ai][bj][m][n] = __builtin_amdgcn_mfma_f32_16x16x32_bf16(Bt[n][k], At[m][k], acc[ai][bj][m][n], 0, 0, 0); __builtin_amdgcn_s_setprio(0); } while (0)
; #define PG8_WAIT_V(n) asm volatile("s_waitcnt vmcnt(" #n ")" ::: "memory")
; #define PG8_WAIT_L(n) asm volatile("s_waitcnt lgkmcnt(" #n ")" ::: "memory")
; #define PG8_BAR __builtin_amdgcn_s_barrier()
; #define PG8_SCHED __builtin_amdgcn_sched_barrier(0)
; template <class Epi, class Sched, bool STAMP = false>
; __device__ __forceinline__ void gemm_phase(PG8_LAS unsigned char* lds, const Gemm g, const Sched& S, const Epi& E, unsigned long long* stamps) {
;     ...
;             PG8_WAIT_L(8); PG8_BAR; PG8_WAIT_L(0); PG8_MMA(0, 0, At, B0); PG8_BAR; PG8_SCHED;
;             PG8_LDB(B1, 1, 1); PG8_STAGE(PG8_SB(1, 0), b3, voffB);
;             PG8_BAR; PG8_WAIT_L(0); PG8_MMA(0, 1, At, B1); PG8_BAR;
;             PG8_LDA(At, 1, 1); PG8_STAGE(PG8_SA(1, 0), a3, voffA);
;             PG8_BAR; PG8_WAIT_L(0); PG8_MMA(1, 0, At, B0); PG8_BAR; PG8_SCHED;
;             PG8_STAGE(PG8_SB(1, 1), b3 + hstep, voffB);
;             PG8_WAIT_V(6); PG8_BAR; PG8_MMA(1, 1, At, B1); PG8_BAR;
	s_waitcnt lgkmcnt(0)
	v_mfma_f32_16x16x32_bf16 v[124:127], v[158:161], v[178:181], v[124:127]
	v_mfma_f32_16x16x32_bf16 v[120:123], v[170:173], v[178:181], v[120:123]
	v_mfma_f32_16x16x32_bf16 v[108:111], v[158:161], v[196:199], v[108:111]
	v_mfma_f32_16x16x32_bf16 v[104:107], v[170:173], v[196:199], v[104:107]
	v_mfma_f32_16x16x32_bf16 v[92:95], v[158:161], v[204:207], v[92:95]
	v_mfma_f32_16x16x32_bf16 v[88:91], v[170:173], v[204:207], v[88:91]
	v_mfma_f32_16x16x32_bf16 v[76:79], v[158:161], v[212:215], v[76:79]
	v_mfma_f32_16x16x32_bf16 v[72:75], v[170:173], v[212:215], v[72:75]
	v_mfma_f32_16x16x32_bf16 v[124:127], v[162:165], v[192:195], v[124:127]
	v_mfma_f32_16x16x32_bf16 v[120:123], v[174:177], v[192:195], v[120:123]
	v_mfma_f32_16x16x32_bf16 v[108:111], v[162:165], v[200:203], v[108:111]
	v_mfma_f32_16x16x32_bf16 v[104:107], v[174:177], v[200:203], v[104:107]
	v_mfma_f32_16x16x32_bf16 v[92:95], v[162:165], v[208:211], v[92:95]
	v_mfma_f32_16x16x32_bf16 v[88:91], v[174:177], v[208:211], v[88:91]
	v_mfma_f32_16x16x32_bf16 v[76:79], v[162:165], v[216:219], v[76:79]
	v_mfma_f32_16x16x32_bf16 v[72:75], v[174:177], v[216:219], v[72:75]
	s_barrier
	s_add_i32 s14, 0, 0x1c000
	s_add_i32 s15, s16, s56
	s_mov_b32 m0, s15
	ds_read_b128 v[220:223], v251
	ds_read_b128 v[224:227], v251 offset:1024
	ds_read_b128 v[228:231], v251 offset:2048
	ds_read_b128 v[232:235], v251 offset:3072
	global_load_lds_dwordx4 v244, s[12:13]
	s_add_i32 m0, s15, 0x2000
	s_nop 0
	global_load_lds_dwordx4 v245, s[12:13]
	s_barrier
	s_waitcnt lgkmcnt(0)
	v_mfma_f32_16x16x32_bf16 v[116:119], v[220:223], v[178:181], v[116:119]
	v_mfma_f32_16x16x32_bf16 v[112:115], v[228:231], v[178:181], v[112:115]
	v_mfma_f32_16x16x32_bf16 v[100:103], v[220:223], v[196:199], v[100:103]
	v_mfma_f32_16x16x32_bf16 v[96:99], v[228:231], v[196:199], v[96:99]
	v_mfma_f32_16x16x32_bf16 v[84:87], v[220:223], v[204:207], v[84:87]
	v_mfma_f32_16x16x32_bf16 v[80:83], v[228:231], v[204:207], v[80:83]
	v_mfma_f32_16x16x32_bf16 v[68:71], v[220:223], v[212:215], v[68:71]
	v_mfma_f32_16x16x32_bf16 v[64:67], v[228:231], v[212:215], v[64:67]
	v_mfma_f32_16x16x32_bf16 v[116:119], v[224:227], v[192:195], v[116:119]
	v_mfma_f32_16x16x32_bf16 v[112:115], v[232:235], v[192:195], v[112:115]
	v_mfma_f32_16x16x32_bf16 v[100:103], v[224:227], v[200:203], v[100:103]
	v_mfma_f32_16x16x32_bf16 v[96:99], v[232:235], v[200:203], v[96:99]
	v_mfma_f32_16x16x32_bf16 v[84:87], v[224:227], v[208:211], v[84:87]
	v_mfma_f32_16x16x32_bf16 v[80:83], v[232:235], v[208:211], v[80:83]
	v_mfma_f32_16x16x32_bf16 v[68:71], v[224:227], v[216:219], v[68:71]
	v_mfma_f32_16x16x32_bf16 v[64:67], v[232:235], v[216:219], v[64:67]
	s_mov_b32 m0, s60
	s_barrier
	ds_read_b128 v[178:181], v169 offset:49152
	ds_read_b128 v[192:195], v169 offset:50176
	ds_read_b128 v[196:199], v169 offset:51200
	ds_read_b128 v[200:203], v169 offset:52224
	ds_read_b128 v[204:207], v169 offset:53248
	ds_read_b128 v[208:211], v169 offset:54272
	ds_read_b128 v[212:215], v169 offset:55296
	ds_read_b128 v[216:219], v169 offset:56320
	global_load_lds_dwordx4 v246, s[26:27]
	s_mov_b32 m0, s61
	s_nop 0
	global_load_lds_dwordx4 v247, s[26:27]
	s_barrier
	s_waitcnt lgkmcnt(0)
	v_mfma_f32_16x16x32_bf16 v[60:63], v[158:161], v[178:181], v[60:63]
	v_mfma_f32_16x16x32_bf16 v[56:59], v[170:173], v[178:181], v[56:59]
	v_mfma_f32_16x16x32_bf16 v[44:47], v[158:161], v[196:199], v[44:47]
	v_mfma_f32_16x16x32_bf16 v[40:43], v[170:173], v[196:199], v[40:43]
	v_mfma_f32_16x16x32_bf16 v[28:31], v[158:161], v[204:207], v[28:31]
	v_mfma_f32_16x16x32_bf16 v[24:27], v[170:173], v[204:207], v[24:27]
	v_mfma_f32_16x16x32_bf16 v[12:15], v[158:161], v[212:215], v[12:15]
	v_mfma_f32_16x16x32_bf16 v[8:11], v[170:173], v[212:215], v[8:11]
	v_mfma_f32_16x16x32_bf16 v[60:63], v[162:165], v[192:195], v[60:63]
	v_mfma_f32_16x16x32_bf16 v[56:59], v[174:177], v[192:195], v[56:59]
	v_mfma_f32_16x16x32_bf16 v[44:47], v[162:165], v[200:203], v[44:47]
	v_mfma_f32_16x16x32_bf16 v[40:43], v[174:177], v[200:203], v[40:43]
	v_mfma_f32_16x16x32_bf16 v[28:31], v[162:165], v[208:211], v[28:31]
	v_mfma_f32_16x16x32_bf16 v[24:27], v[174:177], v[208:211], v[24:27]
	v_mfma_f32_16x16x32_bf16 v[12:15], v[162:165], v[216:219], v[12:15]
	v_mfma_f32_16x16x32_bf16 v[8:11], v[174:177], v[216:219], v[8:11]
	s_barrier
	s_add_u32 s12, s12, 0x40080
	s_addc_u32 s13, s13, 0
	s_add_i32 s14, s14, s56
	s_mov_b32 m0, s14
	s_nop 0
	global_load_lds_dwordx4 v128, s[12:13]
	s_add_i32 m0, s14, 0x2000
	s_nop 0
	global_load_lds_dwordx4 v152, s[12:13]
	s_waitcnt vmcnt(6)
	s_barrier
	v_mfma_f32_16x16x32_bf16 v[52:55], v[220:223], v[178:181], v[52:55]
	v_mfma_f32_16x16x32_bf16 v[48:51], v[228:231], v[178:181], v[48:51]
	v_mfma_f32_16x16x32_bf16 v[36:39], v[220:223], v[196:199], v[36:39]
	v_mfma_f32_16x16x32_bf16 v[32:35], v[228:231], v[196:199], v[32:35]
	v_mfma_f32_16x16x32_bf16 v[20:23], v[220:223], v[204:207], v[20:23]
	v_mfma_f32_16x16x32_bf16 v[16:19], v[228:231], v[204:207], v[16:19]
	v_mfma_f32_16x16x32_bf16 v[4:7], v[220:223], v[212:215], v[4:7]
	v_mfma_f32_16x16x32_bf16 v[0:3], v[228:231], v[212:215], v[0:3]
	v_mfma_f32_16x16x32_bf16 v[52:55], v[224:227], v[192:195], v[52:55]
	v_mfma_f32_16x16x32_bf16 v[48:51], v[232:235], v[192:195], v[48:51]
	v_mfma_f32_16x16x32_bf16 v[36:39], v[224:227], v[200:203], v[36:39]
	v_mfma_f32_16x16x32_bf16 v[32:35], v[232:235], v[200:203], v[32:35]
	v_mfma_f32_16x16x32_bf16 v[20:23], v[224:227], v[208:211], v[20:23]
	v_mfma_f32_16x16x32_bf16 v[16:19], v[232:235], v[208:211], v[16:19]
	v_mfma_f32_16x16x32_bf16 v[4:7], v[224:227], v[216:219], v[4:7]
	v_mfma_f32_16x16x32_bf16 v[0:3], v[232:235], v[216:219], v[0:3]
	s_add_i32 s65, s65, 2
	s_add_u32 s4, s4, 0x100
	s_addc_u32 s5, s5, 0
	s_add_u32 s62, s62, 0x100
	s_addc_u32 s63, s63, 0
	s_cmp_gt_u32 s65, 13
	s_barrier
; __device__ __forceinline__ float sigm(float x) { return __builtin_amdgcn_rcpf(1.0f + __expf(-x)); }
; __device__ __forceinline__ float lo16(unsigned w) { return __uint_as_float(w << 16); }
; __device__ __forceinline__ float hi16(unsigned w) { return __uint_as_float(w & 0xffff0000u); }
; __device__ __forceinline__ float rstd_of(const float* rowss, int row) { return rsqrtf(rowss[row] * (1.0f / 1024.0f) + 1e-6f); }
;     __device__ __forceinline__ void operator()(const f32x4 (&acc)[2][2][4][2], const pg8::Unit& u, int wr, int wc, int fr, int fq) const {
;         const int row0 = u.pm * 256 + wr * 64 + fr, col0 = u.pn * 256 + wc * 32 + 8 * fq;
; #pragma unroll
;         for (int ai = 0; ai < 2; ++ai)
; #pragma unroll
;             for (int m = 0; m < 4; ++m) {
;                 const int row = row0 + ai * 128 + m * 16;
;                 const float s = rstd_of(rowss, row);
; #pragma unroll
;                 for (int bj = 0; bj < 2; ++bj) {
;                     const size_t off = (size_t)row * 1024 + col0 + bj * 128;
;                     const u32x4 tv = *(const u32x4*)(Tm + off);
;                     u32x4 pv = (u32x4){0u, 0u, 0u, 0u};
;                     if (ACC) pv = *(const u32x4*)(M + off);
;                     const f32x4 a0 = acc[ai][bj][m][0] * s, a1 = acc[ai][bj][m][1] * s;
;                     float o[8];
;                     o[0] = sigm(a0[0]) * lo16(tv.x); o[1] = sigm(a0[1]) * hi16(tv.x); o[2] = sigm(a0[2]) * lo16(tv.y); o[3] = sigm(a0[3]) * hi16(tv.y);
;                     o[4] = sigm(a1[0]) * lo16(tv.z); o[5] = sigm(a1[1]) * hi16(tv.z); o[6] = sigm(a1[2]) * lo16(tv.w); o[7] = sigm(a1[3]) * hi16(tv.w);
	s_cbranch_scc0 .LBB0_313
	v_lshl_add_u32 v162, s2, 8, v139
	v_ashrrev_i32_e32 v163, 31, v162
	v_lshl_add_u64 v[160:161], v[162:163], 2, s[40:41]
	global_load_dword v164, v[160:161], off
	v_lshl_or_b32 v158, s46, 8, v168
	v_ashrrev_i32_e32 v159, 31, v158
	s_mov_b32 s2, 0x40000
	s_mov_b64 s[4:5], 0x40000
	s_mov_b32 s46, s6
	s_mov_b64 s[12:13], s[24:25]
	s_mov_b32 s62, 0x1800000
	s_waitcnt vmcnt(0)
	v_fmamk_f32 v164, v164, 0x3a800000, v187
	v_cmp_gt_f32_e32 vcc, s67, v164
	v_mul_f32_e32 v165, 0x4b800000, v164
	s_nop 0
	v_cndmask_b32_e32 v164, v164, v165, vcc
	v_rsq_f32_e32 v164, v164
	s_nop 0
	v_mul_f32_e32 v165, 0x45800000, v164
	v_cndmask_b32_e32 v166, v164, v165, vcc
	v_lshlrev_b64 v[164:165], 11, v[162:163]
	v_lshl_add_u64 v[170:171], s[0:1], 0, v[164:165]
	v_lshlrev_b64 v[164:165], 1, v[158:159]
	v_lshl_add_u64 v[158:159], v[170:171], 0, v[164:165]
	v_mov_b32_e32 v170, v158
	v_mov_b32_e32 v171, v159
	global_load_dwordx4 v[192:195], v[170:171], off
	global_load_dwordx4 v[196:199], v[170:171], off offset:256
	v_add_co_u32_e32 v170, vcc, 0x8000, v170
	s_nop 1
	v_addc_co_u32_e32 v171, vcc, 0, v171, vcc
	global_load_dwordx4 v[200:203], v[170:171], off
	global_load_dwordx4 v[204:207], v[170:171], off offset:256
	v_add_co_u32_e32 v170, vcc, 0x8000, v170
	s_nop 1
	v_addc_co_u32_e32 v171, vcc, 0, v171, vcc
	global_load_dwordx4 v[208:211], v[170:171], off
	global_load_dwordx4 v[212:215], v[170:171], off offset:256
	v_add_co_u32_e32 v170, vcc, 0x8000, v170
	s_nop 1
	v_addc_co_u32_e32 v171, vcc, 0, v171, vcc
	global_load_dwordx4 v[216:219], v[170:171], off
	global_load_dwordx4 v[220:223], v[170:171], off offset:256
	v_lshl_add_u64 v[170:171], v[158:159], 0, s[4:5]
	global_load_dwordx4 v[224:227], v[170:171], off
	global_load_dwordx4 v[228:231], v[170:171], off offset:256
	v_add_co_u32_e32 v170, vcc, 0x8000, v170
	s_nop 1
	v_addc_co_u32_e32 v171, vcc, 0, v171, vcc
	global_load_dwordx4 v[232:235], v[170:171], off
	global_load_dwordx4 v[236:239], v[170:171], off offset:256
	v_add_co_u32_e32 v170, vcc, 0x8000, v170
	s_nop 1
	v_addc_co_u32_e32 v171, vcc, 0, v171, vcc
	global_load_dwordx4 v[244:247], v[170:171], off
	global_load_dwordx4 v[248:251], v[170:171], off offset:256
	v_add_co_u32_e32 v170, vcc, 0x8000, v170
	s_nop 1
	v_addc_co_u32_e32 v171, vcc, 0, v171, vcc
	global_load_dwordx4 v[176:179], v[170:171], off
	global_load_dwordx4 v[252:255], v[170:171], off offset:256
	global_load_dword v180, v[160:161], off offset:64
	global_load_dword v181, v[160:161], off offset:128
	global_load_dword v182, v[160:161], off offset:192
	global_load_dword v183, v[160:161], off offset:512
	global_load_dword v240, v[160:161], off offset:576
	global_load_dword v241, v[160:161], off offset:640
	global_load_dword v169, v[160:161], off offset:704
	v_pk_mul_f32 v[126:127], v[126:127], v[166:167] op_sel_hi:[1,0]
	v_pk_mul_f32 v[120:121], v[120:121], v[166:167] op_sel_hi:[1,0]
	v_mul_f32_e32 v126, 0xbfb8aa3b, v126
	v_mul_f32_e32 v127, 0xbfb8aa3b, v127
	v_exp_f32_e32 v126, v126
	v_exp_f32_e32 v127, v127
	v_mul_f32_e32 v120, 0xbfb8aa3b, v120
	v_mul_f32_e32 v121, 0xbfb8aa3b, v121
	v_exp_f32_e32 v120, v120
	v_exp_f32_e32 v121, v121
	v_add_f32_e32 v126, 1.0, v126
	v_add_f32_e32 v127, 1.0, v127
	v_rcp_f32_e32 v126, v126
	v_rcp_f32_e32 v127, v127
	v_add_f32_e32 v120, 1.0, v120
	v_add_f32_e32 v121, 1.0, v121
	v_rcp_f32_e32 v120, v120
	v_rcp_f32_e32 v121, v121
	v_pk_mul_f32 v[124:125], v[124:125], v[166:167] op_sel_hi:[1,0]
	v_pk_mul_f32 v[122:123], v[122:123], v[166:167] op_sel_hi:[1,0]
	v_mul_f32_e32 v124, 0xbfb8aa3b, v124
	v_mul_f32_e32 v125, 0xbfb8aa3b, v125
	v_exp_f32_e32 v124, v124
	v_exp_f32_e32 v125, v125
	v_pk_mul_f32 v[118:119], v[118:119], v[166:167] op_sel_hi:[1,0]
	v_pk_mul_f32 v[112:113], v[112:113], v[166:167] op_sel_hi:[1,0]
	v_add_f32_e32 v124, 1.0, v124
	v_add_f32_e32 v125, 1.0, v125
	v_rcp_f32_e32 v124, v124
	v_rcp_f32_e32 v125, v125
	v_mul_f32_e32 v118, 0xbfb8aa3b, v118
	v_mul_f32_e32 v119, 0xbfb8aa3b, v119
	v_exp_f32_e32 v118, v118
	v_exp_f32_e32 v119, v119
	v_mul_f32_e32 v112, 0xbfb8aa3b, v112
	v_mul_f32_e32 v113, 0xbfb8aa3b, v113
	v_exp_f32_e32 v112, v112
	v_exp_f32_e32 v113, v113
	v_add_f32_e32 v118, 1.0, v118
	v_add_f32_e32 v119, 1.0, v119
	v_rcp_f32_e32 v118, v118
	v_rcp_f32_e32 v119, v119
	v_add_f32_e32 v112, 1.0, v112
	v_add_f32_e32 v113, 1.0, v113
	v_rcp_f32_e32 v112, v112
	v_rcp_f32_e32 v113, v113
	v_pk_mul_f32 v[116:117], v[116:117], v[166:167] op_sel_hi:[1,0]
	v_pk_mul_f32 v[114:115], v[114:115], v[166:167] op_sel_hi:[1,0]
	v_mul_f32_e32 v116, 0xbfb8aa3b, v116
	v_mul_f32_e32 v117, 0xbfb8aa3b, v117
	v_exp_f32_e32 v116, v116
	v_exp_f32_e32 v117, v117
	v_add_f32_e32 v116, 1.0, v116
	v_add_f32_e32 v117, 1.0, v117
	v_rcp_f32_e32 v116, v116
	v_rcp_f32_e32 v117, v117
	s_waitcnt vmcnt(0)
; __device__ __forceinline__ unsigned cvt_pk_bf16(float lo, float hi) { const f32x2_cv v = {lo, hi}; const bf16x2_cv b = __builtin_convertvector(v, bf16x2_cv); return __builtin_bit_cast(unsigned, b); }
; __device__ __forceinline__ float sigm(float x) { return __builtin_amdgcn_rcpf(1.0f + __expf(-x)); }
; __device__ __forceinline__ float lo16(unsigned w) { return __uint_as_float(w << 16); }
; __device__ __forceinline__ float hi16(unsigned w) { return __uint_as_float(w & 0xffff0000u); }
; __device__ __forceinline__ float rstd_of(const float* rowss, int row) { return rsqrtf(rowss[row] * (1.0f / 1024.0f) + 1e-6f); }
;     __device__ __forceinline__ void operator()(const f32x4 (&acc)[2][2][4][2], const pg8::Unit& u, int wr, int wc, int fr, int fq) const {
;     ...
;                 const int row = row0 + ai * 128 + m * 16;
;                 const float s = rstd_of(rowss, row);
; #pragma unroll
;                 for (int bj = 0; bj < 2; ++bj) {
;                     const size_t off = (size_t)row * 1024 + col0 + bj * 128;
;                     const u32x4 tv = *(const u32x4*)(Tm + off);
;                     u32x4 pv = (u32x4){0u, 0u, 0u, 0u};
;                     if (ACC) pv = *(const u32x4*)(M + off);
;                     const f32x4 a0 = acc[ai][bj][m][0] * s, a1 = acc[ai][bj][m][1] * s;
;                     float o[8];
;                     o[0] = sigm(a0[0]) * lo16(tv.x); o[1] = sigm(a0[1]) * hi16(tv.x); o[2] = sigm(a0[2]) * lo16(tv.y); o[3] = sigm(a0[3]) * hi16(tv.y);
;                     o[4] = sigm(a1[0]) * lo16(tv.z); o[5] = sigm(a1[1]) * hi16(tv.z); o[6] = sigm(a1[2]) * lo16(tv.w); o[7] = sigm(a1[3]) * hi16(tv.w);
;                     if (ACC) { o[0] += lo16(pv.x); o[1] += hi16(pv.x); o[2] += lo16(pv.y); o[3] += hi16(pv.y); o[4] += lo16(pv.z); o[5] += hi16(pv.z); o[6] += lo16(pv.w); o[7] += hi16(pv.w); }
;                     u32x4 w; w.x = cvt_pk_bf16(o[0], o[1]); w.y = cvt_pk_bf16(o[2], o[3]); w.z = cvt_pk_bf16(o[4], o[5]); w.w = cvt_pk_bf16(o[6], o[7]);
;                     *(u32x4*)(M + off) = w; } }
	v_mov_b32_e32 v170, v192
	v_mov_b32_e32 v171, v193
	v_mov_b32_e32 v172, v194
	v_mov_b32_e32 v173, v195
	v_lshlrev_b32_e32 v174, 16, v170
	v_and_b32_e32 v175, 0xffff0000, v170
	v_lshlrev_b32_e32 v170, 16, v171
	v_and_b32_e32 v171, 0xffff0000, v171
	v_pk_mul_f32 v[126:127], v[126:127], v[170:171]
	v_lshlrev_b32_e32 v170, 16, v172
	v_and_b32_e32 v171, 0xffff0000, v172
	v_pk_mul_f32 v[170:171], v[120:121], v[170:171]
	v_mul_f32_e32 v120, 0xbfb8aa3b, v122
	v_mul_f32_e32 v121, 0xbfb8aa3b, v123
	v_exp_f32_e32 v120, v120
	v_exp_f32_e32 v121, v121
	v_lshlrev_b32_e32 v122, 16, v173
	v_and_b32_e32 v123, 0xffff0000, v173
	v_add_f32_e32 v120, 1.0, v120
	v_add_f32_e32 v121, 1.0, v121
	v_rcp_f32_e32 v120, v120
	v_rcp_f32_e32 v121, v121
	v_pk_mul_f32 v[124:125], v[124:125], v[174:175]
	v_pk_mul_f32 v[172:173], v[120:121], v[122:123]
	v_cvt_pk_bf16_f32 v120, v124, v125
	v_cvt_pk_bf16_f32 v121, v126, v127
	v_cvt_pk_bf16_f32 v122, v170, v171
	v_cvt_pk_bf16_f32 v123, v172, v173
	global_store_dwordx4 v[158:159], v[120:123], off
	s_nop 1
	v_mov_b32_e32 v120, v196
	v_mov_b32_e32 v121, v197
	v_mov_b32_e32 v122, v198
	v_mov_b32_e32 v123, v199
	v_lshlrev_b32_e32 v124, 16, v120
	v_and_b32_e32 v125, 0xffff0000, v120
	v_lshlrev_b32_e32 v120, 16, v121
	v_and_b32_e32 v121, 0xffff0000, v121
	v_pk_mul_f32 v[118:119], v[118:119], v[120:121]
	v_lshlrev_b32_e32 v120, 16, v122
	v_and_b32_e32 v121, 0xffff0000, v122
	v_pk_mul_f32 v[120:121], v[112:113], v[120:121]
	v_mul_f32_e32 v112, 0xbfb8aa3b, v114
	v_mul_f32_e32 v113, 0xbfb8aa3b, v115
	v_exp_f32_e32 v112, v112
	v_exp_f32_e32 v113, v113
	v_lshlrev_b32_e32 v114, 16, v123
	v_and_b32_e32 v115, 0xffff0000, v123
	v_add_f32_e32 v112, 1.0, v112
	v_add_f32_e32 v113, 1.0, v113
	v_rcp_f32_e32 v112, v112
	v_rcp_f32_e32 v113, v113
	v_pk_mul_f32 v[116:117], v[116:117], v[124:125]
	v_pk_mul_f32 v[122:123], v[112:113], v[114:115]
	v_cvt_pk_bf16_f32 v112, v116, v117
	v_cvt_pk_bf16_f32 v113, v118, v119
	v_cvt_pk_bf16_f32 v114, v120, v121
	v_cvt_pk_bf16_f32 v115, v122, v123
	global_store_dwordx4 v[158:159], v[112:115], off offset:256
	s_nop 1
	v_mov_b32_e32 v114, v180
	s_nop 0
	v_or_b32_e32 v112, 16, v162
	v_ashrrev_i32_e32 v113, 31, v112
	v_lshlrev_b64 v[112:113], 11, v[112:113]
	v_lshl_add_u64 v[112:113], s[0:1], 0, v[112:113]
	v_lshl_add_u64 v[112:113], v[112:113], 0, v[164:165]
	s_nop 1
	v_mov_b32_e32 v116, v200
	v_mov_b32_e32 v117, v201
	v_mov_b32_e32 v118, v202
	v_mov_b32_e32 v119, v203
	v_fmamk_f32 v114, v114, 0x3a800000, v187
	v_cmp_gt_f32_e32 vcc, s67, v114
	v_mul_f32_e32 v115, 0x4b800000, v114
	v_lshlrev_b32_e32 v120, 16, v116
	v_cndmask_b32_e32 v114, v114, v115, vcc
	v_rsq_f32_e32 v114, v114
	v_and_b32_e32 v121, 0xffff0000, v116
	v_lshlrev_b32_e32 v116, 16, v117
	v_and_b32_e32 v117, 0xffff0000, v117
	v_mul_f32_e32 v115, 0x45800000, v114
	v_cndmask_b32_e32 v114, v114, v115, vcc
	v_pk_mul_f32 v[110:111], v[110:111], v[114:115] op_sel_hi:[1,0]
	v_pk_mul_f32 v[104:105], v[104:105], v[114:115] op_sel_hi:[1,0]
	v_mul_f32_e32 v110, 0xbfb8aa3b, v110
	v_mul_f32_e32 v111, 0xbfb8aa3b, v111
	v_exp_f32_e32 v110, v110
	v_exp_f32_e32 v111, v111
	v_mul_f32_e32 v104, 0xbfb8aa3b, v104
	v_mul_f32_e32 v105, 0xbfb8aa3b, v105
	v_exp_f32_e32 v104, v104
	v_exp_f32_e32 v105, v105
	v_add_f32_e32 v110, 1.0, v110
	v_add_f32_e32 v111, 1.0, v111
	v_rcp_f32_e32 v110, v110
	v_rcp_f32_e32 v111, v111
	v_add_f32_e32 v104, 1.0, v104
	v_add_f32_e32 v105, 1.0, v105
	v_rcp_f32_e32 v104, v104
	v_rcp_f32_e32 v105, v105
	v_pk_mul_f32 v[108:109], v[108:109], v[114:115] op_sel_hi:[1,0]
	v_pk_mul_f32 v[106:107], v[106:107], v[114:115] op_sel_hi:[1,0]
	v_pk_mul_f32 v[110:111], v[110:111], v[116:117]
	v_lshlrev_b32_e32 v116, 16, v118
	v_and_b32_e32 v117, 0xffff0000, v118
	v_mul_f32_e32 v108, 0xbfb8aa3b, v108
	v_mul_f32_e32 v109, 0xbfb8aa3b, v109
	v_pk_mul_f32 v[116:117], v[104:105], v[116:117]
	v_mul_f32_e32 v104, 0xbfb8aa3b, v106
	v_mul_f32_e32 v105, 0xbfb8aa3b, v107
	v_exp_f32_e32 v108, v108
	v_exp_f32_e32 v109, v109
	v_exp_f32_e32 v104, v104
	v_exp_f32_e32 v105, v105
	v_add_f32_e32 v108, 1.0, v108
	v_add_f32_e32 v109, 1.0, v109
	v_add_f32_e32 v104, 1.0, v104
	v_add_f32_e32 v105, 1.0, v105
	v_rcp_f32_e32 v108, v108
	v_rcp_f32_e32 v109, v109
	v_rcp_f32_e32 v104, v104
	v_rcp_f32_e32 v105, v105
	v_lshlrev_b32_e32 v106, 16, v119
	v_and_b32_e32 v107, 0xffff0000, v119
	v_pk_mul_f32 v[108:109], v[108:109], v[120:121]
	v_pk_mul_f32 v[118:119], v[104:105], v[106:107]
	v_cvt_pk_bf16_f32 v104, v108, v109
	v_cvt_pk_bf16_f32 v105, v110, v111
	v_cvt_pk_bf16_f32 v106, v116, v117
	v_cvt_pk_bf16_f32 v107, v118, v119
	global_store_dwordx4 v[112:113], v[104:107], off
	s_nop 1
	v_mov_b32_e32 v104, v204
	v_mov_b32_e32 v105, v205
	v_mov_b32_e32 v106, v206
	v_mov_b32_e32 v107, v207
	v_pk_mul_f32 v[102:103], v[102:103], v[114:115] op_sel_hi:[1,0]
	v_pk_mul_f32 v[96:97], v[96:97], v[114:115] op_sel_hi:[1,0]
	v_mul_f32_e32 v102, 0xbfb8aa3b, v102
	v_mul_f32_e32 v103, 0xbfb8aa3b, v103
	v_exp_f32_e32 v102, v102
	v_exp_f32_e32 v103, v103
	v_mul_f32_e32 v96, 0xbfb8aa3b, v96
	v_mul_f32_e32 v97, 0xbfb8aa3b, v97
	v_exp_f32_e32 v96, v96
	v_exp_f32_e32 v97, v97
	v_add_f32_e32 v102, 1.0, v102
	v_add_f32_e32 v103, 1.0, v103
	v_rcp_f32_e32 v102, v102
	v_rcp_f32_e32 v103, v103
	v_add_f32_e32 v96, 1.0, v96
	v_add_f32_e32 v97, 1.0, v97
	v_rcp_f32_e32 v96, v96
	v_rcp_f32_e32 v97, v97
	v_pk_mul_f32 v[100:101], v[100:101], v[114:115] op_sel_hi:[1,0]
	v_pk_mul_f32 v[98:99], v[98:99], v[114:115] op_sel_hi:[1,0]
	v_mul_f32_e32 v100, 0xbfb8aa3b, v100
	v_mul_f32_e32 v101, 0xbfb8aa3b, v101
	v_exp_f32_e32 v100, v100
	v_exp_f32_e32 v101, v101
	v_add_f32_e32 v100, 1.0, v100
	v_add_f32_e32 v101, 1.0, v101
	v_rcp_f32_e32 v100, v100
; __device__ __forceinline__ unsigned cvt_pk_bf16(float lo, float hi) { const f32x2_cv v = {lo, hi}; const bf16x2_cv b = __builtin_convertvector(v, bf16x2_cv); return __builtin_bit_cast(unsigned, b); }
; __device__ __forceinline__ float sigm(float x) { return __builtin_amdgcn_rcpf(1.0f + __expf(-x)); }
; __device__ __forceinline__ float lo16(unsigned w) { return __uint_as_float(w << 16); }
; __device__ __forceinline__ float hi16(unsigned w) { return __uint_as_float(w & 0xffff0000u); }
; __device__ __forceinline__ float rstd_of(const float* rowss, int row) { return rsqrtf(rowss[row] * (1.0f / 1024.0f) + 1e-6f); }
;     __device__ __forceinline__ void operator()(const f32x4 (&acc)[2][2][4][2], const pg8::Unit& u, int wr, int wc, int fr, int fq) const {
;     ...
;                 const int row = row0 + ai * 128 + m * 16;
;                 const float s = rstd_of(rowss, row);
; #pragma unroll
;                 for (int bj = 0; bj < 2; ++bj) {
;                     const size_t off = (size_t)row * 1024 + col0 + bj * 128;
;                     const u32x4 tv = *(const u32x4*)(Tm + off);
;                     u32x4 pv = (u32x4){0u, 0u, 0u, 0u};
;                     if (ACC) pv = *(const u32x4*)(M + off);
;                     const f32x4 a0 = acc[ai][bj][m][0] * s, a1 = acc[ai][bj][m][1] * s;
;                     float o[8];
;                     o[0] = sigm(a0[0]) * lo16(tv.x); o[1] = sigm(a0[1]) * hi16(tv.x); o[2] = sigm(a0[2]) * lo16(tv.y); o[3] = sigm(a0[3]) * hi16(tv.y);
;                     o[4] = sigm(a1[0]) * lo16(tv.z); o[5] = sigm(a1[1]) * hi16(tv.z); o[6] = sigm(a1[2]) * lo16(tv.w); o[7] = sigm(a1[3]) * hi16(tv.w);
;                     if (ACC) { o[0] += lo16(pv.x); o[1] += hi16(pv.x); o[2] += lo16(pv.y); o[3] += hi16(pv.y); o[4] += lo16(pv.z); o[5] += hi16(pv.z); o[6] += lo16(pv.w); o[7] += hi16(pv.w); }
;                     u32x4 w; w.x = cvt_pk_bf16(o[0], o[1]); w.y = cvt_pk_bf16(o[2], o[3]); w.z = cvt_pk_bf16(o[4], o[5]); w.w = cvt_pk_bf16(o[6], o[7]);
;                     *(u32x4*)(M + off) = w; } }
	v_rcp_f32_e32 v101, v101
	v_lshlrev_b32_e32 v108, 16, v104
	v_and_b32_e32 v109, 0xffff0000, v104
	v_lshlrev_b32_e32 v104, 16, v105
	v_and_b32_e32 v105, 0xffff0000, v105
	v_pk_mul_f32 v[102:103], v[102:103], v[104:105]
	v_lshlrev_b32_e32 v104, 16, v106
	v_and_b32_e32 v105, 0xffff0000, v106
	v_pk_mul_f32 v[104:105], v[96:97], v[104:105]
	v_mul_f32_e32 v96, 0xbfb8aa3b, v98
	v_mul_f32_e32 v97, 0xbfb8aa3b, v99
	v_exp_f32_e32 v96, v96
	v_exp_f32_e32 v97, v97
	v_lshlrev_b32_e32 v98, 16, v107
	v_and_b32_e32 v99, 0xffff0000, v107
	v_add_f32_e32 v96, 1.0, v96
	v_add_f32_e32 v97, 1.0, v97
	v_rcp_f32_e32 v96, v96
	v_rcp_f32_e32 v97, v97
	v_pk_mul_f32 v[100:101], v[100:101], v[108:109]
	v_pk_mul_f32 v[106:107], v[96:97], v[98:99]
	v_cvt_pk_bf16_f32 v96, v100, v101
	v_cvt_pk_bf16_f32 v97, v102, v103
	v_cvt_pk_bf16_f32 v98, v104, v105
	v_cvt_pk_bf16_f32 v99, v106, v107
	global_store_dwordx4 v[112:113], v[96:99], off offset:256
	s_nop 1
	v_mov_b32_e32 v98, v181
	s_nop 0
	v_or_b32_e32 v96, 32, v162
	v_ashrrev_i32_e32 v97, 31, v96
	v_lshlrev_b64 v[96:97], 11, v[96:97]
	v_lshl_add_u64 v[96:97], s[0:1], 0, v[96:97]
	v_lshl_add_u64 v[96:97], v[96:97], 0, v[164:165]
	s_nop 1
	v_mov_b32_e32 v100, v208
	v_mov_b32_e32 v101, v209
	v_mov_b32_e32 v102, v210
	v_mov_b32_e32 v103, v211
	v_fmamk_f32 v98, v98, 0x3a800000, v187
	v_cmp_gt_f32_e32 vcc, s67, v98
	v_mul_f32_e32 v99, 0x4b800000, v98
	v_lshlrev_b32_e32 v104, 16, v100
	v_cndmask_b32_e32 v98, v98, v99, vcc
	v_rsq_f32_e32 v98, v98
	v_and_b32_e32 v105, 0xffff0000, v100
	v_lshlrev_b32_e32 v100, 16, v101
	v_and_b32_e32 v101, 0xffff0000, v101
	v_mul_f32_e32 v99, 0x45800000, v98
	v_cndmask_b32_e32 v98, v98, v99, vcc
	v_pk_mul_f32 v[94:95], v[94:95], v[98:99] op_sel_hi:[1,0]
	v_pk_mul_f32 v[88:89], v[88:89], v[98:99] op_sel_hi:[1,0]
	v_mul_f32_e32 v94, 0xbfb8aa3b, v94
	v_mul_f32_e32 v95, 0xbfb8aa3b, v95
	v_exp_f32_e32 v94, v94
	v_exp_f32_e32 v95, v95
	v_mul_f32_e32 v88, 0xbfb8aa3b, v88
	v_mul_f32_e32 v89, 0xbfb8aa3b, v89
	v_exp_f32_e32 v88, v88
	v_exp_f32_e32 v89, v89
	v_add_f32_e32 v94, 1.0, v94
	v_add_f32_e32 v95, 1.0, v95
	v_rcp_f32_e32 v94, v94
	v_rcp_f32_e32 v95, v95
	v_add_f32_e32 v88, 1.0, v88
	v_add_f32_e32 v89, 1.0, v89
	v_rcp_f32_e32 v88, v88
	v_rcp_f32_e32 v89, v89
	v_pk_mul_f32 v[92:93], v[92:93], v[98:99] op_sel_hi:[1,0]
	v_pk_mul_f32 v[90:91], v[90:91], v[98:99] op_sel_hi:[1,0]
	v_pk_mul_f32 v[94:95], v[94:95], v[100:101]
	v_lshlrev_b32_e32 v100, 16, v102
	v_and_b32_e32 v101, 0xffff0000, v102
	v_mul_f32_e32 v92, 0xbfb8aa3b, v92
	v_mul_f32_e32 v93, 0xbfb8aa3b, v93
	v_pk_mul_f32 v[100:101], v[88:89], v[100:101]
	v_mul_f32_e32 v88, 0xbfb8aa3b, v90
	v_mul_f32_e32 v89, 0xbfb8aa3b, v91
	v_exp_f32_e32 v92, v92
	v_exp_f32_e32 v93, v93
	v_exp_f32_e32 v88, v88
	v_exp_f32_e32 v89, v89
	v_add_f32_e32 v92, 1.0, v92
	v_add_f32_e32 v93, 1.0, v93
	v_add_f32_e32 v88, 1.0, v88
	v_add_f32_e32 v89, 1.0, v89
	v_rcp_f32_e32 v92, v92
	v_rcp_f32_e32 v93, v93
	v_rcp_f32_e32 v88, v88
	v_rcp_f32_e32 v89, v89
	v_lshlrev_b32_e32 v90, 16, v103
	v_and_b32_e32 v91, 0xffff0000, v103
	v_pk_mul_f32 v[92:93], v[92:93], v[104:105]
	v_pk_mul_f32 v[102:103], v[88:89], v[90:91]
	v_cvt_pk_bf16_f32 v88, v92, v93
	v_cvt_pk_bf16_f32 v89, v94, v95
	v_cvt_pk_bf16_f32 v90, v100, v101
	v_cvt_pk_bf16_f32 v91, v102, v103
	global_store_dwordx4 v[96:97], v[88:91], off
	s_nop 1
	v_mov_b32_e32 v88, v212
	v_mov_b32_e32 v89, v213
	v_mov_b32_e32 v90, v214
	v_mov_b32_e32 v91, v215
	v_pk_mul_f32 v[86:87], v[86:87], v[98:99] op_sel_hi:[1,0]
	v_pk_mul_f32 v[80:81], v[80:81], v[98:99] op_sel_hi:[1,0]
	v_mul_f32_e32 v86, 0xbfb8aa3b, v86
	v_mul_f32_e32 v87, 0xbfb8aa3b, v87
	v_exp_f32_e32 v86, v86
	v_exp_f32_e32 v87, v87
	v_mul_f32_e32 v80, 0xbfb8aa3b, v80
	v_mul_f32_e32 v81, 0xbfb8aa3b, v81
	v_exp_f32_e32 v80, v80
	v_exp_f32_e32 v81, v81
	v_add_f32_e32 v86, 1.0, v86
	v_add_f32_e32 v87, 1.0, v87
	v_rcp_f32_e32 v86, v86
	v_rcp_f32_e32 v87, v87
	v_add_f32_e32 v80, 1.0, v80
	v_add_f32_e32 v81, 1.0, v81
	v_rcp_f32_e32 v80, v80
	v_rcp_f32_e32 v81, v81
	v_pk_mul_f32 v[84:85], v[84:85], v[98:99] op_sel_hi:[1,0]
	v_pk_mul_f32 v[82:83], v[82:83], v[98:99] op_sel_hi:[1,0]
	v_mul_f32_e32 v84, 0xbfb8aa3b, v84
	v_mul_f32_e32 v85, 0xbfb8aa3b, v85
	v_exp_f32_e32 v84, v84
	v_exp_f32_e32 v85, v85
	v_add_f32_e32 v84, 1.0, v84
	v_add_f32_e32 v85, 1.0, v85
	v_rcp_f32_e32 v84, v84
	v_rcp_f32_e32 v85, v85
	v_lshlrev_b32_e32 v92, 16, v88
	v_and_b32_e32 v93, 0xffff0000, v88
	v_lshlrev_b32_e32 v88, 16, v89
	v_and_b32_e32 v89, 0xffff0000, v89
	v_pk_mul_f32 v[86:87], v[86:87], v[88:89]
	v_lshlrev_b32_e32 v88, 16, v90
	v_and_b32_e32 v89, 0xffff0000, v90
	v_pk_mul_f32 v[88:89], v[80:81], v[88:89]
	v_mul_f32_e32 v80, 0xbfb8aa3b, v82
	v_mul_f32_e32 v81, 0xbfb8aa3b, v83
	v_exp_f32_e32 v80, v80
	v_exp_f32_e32 v81, v81
	v_lshlrev_b32_e32 v82, 16, v91
	v_and_b32_e32 v83, 0xffff0000, v91
	v_add_f32_e32 v80, 1.0, v80
	v_add_f32_e32 v81, 1.0, v81
	v_rcp_f32_e32 v80, v80
	v_rcp_f32_e32 v81, v81
	v_pk_mul_f32 v[84:85], v[84:85], v[92:93]
	v_pk_mul_f32 v[90:91], v[80:81], v[82:83]
	v_cvt_pk_bf16_f32 v80, v84, v85
	v_cvt_pk_bf16_f32 v81, v86, v87
	v_cvt_pk_bf16_f32 v82, v88, v89
	v_cvt_pk_bf16_f32 v83, v90, v91
	global_store_dwordx4 v[96:97], v[80:83], off offset:256
	s_nop 1
	v_mov_b32_e32 v82, v182
	s_nop 0
	v_or_b32_e32 v80, 48, v162
	v_ashrrev_i32_e32 v81, 31, v80
	v_lshlrev_b64 v[80:81], 11, v[80:81]
	v_lshl_add_u64 v[80:81], s[0:1], 0, v[80:81]
	v_lshl_add_u64 v[80:81], v[80:81], 0, v[164:165]
	s_nop 1
	v_mov_b32_e32 v84, v216
	v_mov_b32_e32 v85, v217
	v_mov_b32_e32 v86, v218
	v_mov_b32_e32 v87, v219
	v_fmamk_f32 v82, v82, 0x3a800000, v187
	v_cmp_gt_f32_e32 vcc, s67, v82
	v_mul_f32_e32 v83, 0x4b800000, v82
; __device__ __forceinline__ unsigned cvt_pk_bf16(float lo, float hi) { const f32x2_cv v = {lo, hi}; const bf16x2_cv b = __builtin_convertvector(v, bf16x2_cv); return __builtin_bit_cast(unsigned, b); }
; __device__ __forceinline__ float sigm(float x) { return __builtin_amdgcn_rcpf(1.0f + __expf(-x)); }
; __device__ __forceinline__ float lo16(unsigned w) { return __uint_as_float(w << 16); }
; __device__ __forceinline__ float hi16(unsigned w) { return __uint_as_float(w & 0xffff0000u); }
; __device__ __forceinline__ float rstd_of(const float* rowss, int row) { return rsqrtf(rowss[row] * (1.0f / 1024.0f) + 1e-6f); }
;     __device__ __forceinline__ void operator()(const f32x4 (&acc)[2][2][4][2], const pg8::Unit& u, int wr, int wc, int fr, int fq) const {
;     ...
;                 const int row = row0 + ai * 128 + m * 16;
;                 const float s = rstd_of(rowss, row);
; #pragma unroll
;                 for (int bj = 0; bj < 2; ++bj) {
;                     const size_t off = (size_t)row * 1024 + col0 + bj * 128;
;                     const u32x4 tv = *(const u32x4*)(Tm + off);
;                     u32x4 pv = (u32x4){0u, 0u, 0u, 0u};
;                     if (ACC) pv = *(const u32x4*)(M + off);
;                     const f32x4 a0 = acc[ai][bj][m][0] * s, a1 = acc[ai][bj][m][1] * s;
;                     float o[8];
;                     o[0] = sigm(a0[0]) * lo16(tv.x); o[1] = sigm(a0[1]) * hi16(tv.x); o[2] = sigm(a0[2]) * lo16(tv.y); o[3] = sigm(a0[3]) * hi16(tv.y);
;                     o[4] = sigm(a1[0]) * lo16(tv.z); o[5] = sigm(a1[1]) * hi16(tv.z); o[6] = sigm(a1[2]) * lo16(tv.w); o[7] = sigm(a1[3]) * hi16(tv.w);
;                     if (ACC) { o[0] += lo16(pv.x); o[1] += hi16(pv.x); o[2] += lo16(pv.y); o[3] += hi16(pv.y); o[4] += lo16(pv.z); o[5] += hi16(pv.z); o[6] += lo16(pv.w); o[7] += hi16(pv.w); }
;                     u32x4 w; w.x = cvt_pk_bf16(o[0], o[1]); w.y = cvt_pk_bf16(o[2], o[3]); w.z = cvt_pk_bf16(o[4], o[5]); w.w = cvt_pk_bf16(o[6], o[7]);
;                     *(u32x4*)(M + off) = w; } }
	v_lshlrev_b32_e32 v88, 16, v84
	v_cndmask_b32_e32 v82, v82, v83, vcc
	v_rsq_f32_e32 v82, v82
	v_and_b32_e32 v89, 0xffff0000, v84
	v_lshlrev_b32_e32 v84, 16, v85
	v_and_b32_e32 v85, 0xffff0000, v85
	v_mul_f32_e32 v83, 0x45800000, v82
	v_cndmask_b32_e32 v82, v82, v83, vcc
	v_pk_mul_f32 v[78:79], v[78:79], v[82:83] op_sel_hi:[1,0]
	v_pk_mul_f32 v[72:73], v[72:73], v[82:83] op_sel_hi:[1,0]
	v_mul_f32_e32 v78, 0xbfb8aa3b, v78
	v_mul_f32_e32 v79, 0xbfb8aa3b, v79
	v_exp_f32_e32 v78, v78
	v_exp_f32_e32 v79, v79
	v_mul_f32_e32 v72, 0xbfb8aa3b, v72
	v_mul_f32_e32 v73, 0xbfb8aa3b, v73
	v_exp_f32_e32 v72, v72
	v_exp_f32_e32 v73, v73
	v_add_f32_e32 v78, 1.0, v78
	v_add_f32_e32 v79, 1.0, v79
	v_rcp_f32_e32 v78, v78
	v_rcp_f32_e32 v79, v79
	v_add_f32_e32 v72, 1.0, v72
	v_add_f32_e32 v73, 1.0, v73
	v_rcp_f32_e32 v72, v72
	v_rcp_f32_e32 v73, v73
	v_pk_mul_f32 v[76:77], v[76:77], v[82:83] op_sel_hi:[1,0]
	v_pk_mul_f32 v[74:75], v[74:75], v[82:83] op_sel_hi:[1,0]
	v_pk_mul_f32 v[78:79], v[78:79], v[84:85]
	v_lshlrev_b32_e32 v84, 16, v86
	v_and_b32_e32 v85, 0xffff0000, v86
	v_mul_f32_e32 v76, 0xbfb8aa3b, v76
	v_mul_f32_e32 v77, 0xbfb8aa3b, v77
	v_pk_mul_f32 v[84:85], v[72:73], v[84:85]
	v_mul_f32_e32 v72, 0xbfb8aa3b, v74
	v_mul_f32_e32 v73, 0xbfb8aa3b, v75
	v_exp_f32_e32 v76, v76
	v_exp_f32_e32 v77, v77
	v_exp_f32_e32 v72, v72
	v_exp_f32_e32 v73, v73
	v_add_f32_e32 v76, 1.0, v76
	v_add_f32_e32 v77, 1.0, v77
	v_add_f32_e32 v72, 1.0, v72
	v_add_f32_e32 v73, 1.0, v73
	v_rcp_f32_e32 v76, v76
	v_rcp_f32_e32 v77, v77
	v_rcp_f32_e32 v72, v72
	v_rcp_f32_e32 v73, v73
	v_lshlrev_b32_e32 v74, 16, v87
	v_and_b32_e32 v75, 0xffff0000, v87
	v_pk_mul_f32 v[76:77], v[76:77], v[88:89]
	v_pk_mul_f32 v[86:87], v[72:73], v[74:75]
	v_cvt_pk_bf16_f32 v72, v76, v77
	v_cvt_pk_bf16_f32 v73, v78, v79
	v_cvt_pk_bf16_f32 v74, v84, v85
	v_cvt_pk_bf16_f32 v75, v86, v87
	global_store_dwordx4 v[80:81], v[72:75], off
	s_nop 1
	v_mov_b32_e32 v72, v220
	v_mov_b32_e32 v73, v221
	v_mov_b32_e32 v74, v222
	v_mov_b32_e32 v75, v223
	v_pk_mul_f32 v[70:71], v[70:71], v[82:83] op_sel_hi:[1,0]
	v_pk_mul_f32 v[64:65], v[64:65], v[82:83] op_sel_hi:[1,0]
	v_mul_f32_e32 v70, 0xbfb8aa3b, v70
	v_mul_f32_e32 v71, 0xbfb8aa3b, v71
	v_exp_f32_e32 v70, v70
	v_exp_f32_e32 v71, v71
	v_mul_f32_e32 v64, 0xbfb8aa3b, v64
	v_mul_f32_e32 v65, 0xbfb8aa3b, v65
	v_exp_f32_e32 v64, v64
	v_exp_f32_e32 v65, v65
	v_add_f32_e32 v70, 1.0, v70
	v_add_f32_e32 v71, 1.0, v71
	v_rcp_f32_e32 v70, v70
	v_rcp_f32_e32 v71, v71
	v_add_f32_e32 v64, 1.0, v64
	v_add_f32_e32 v65, 1.0, v65
	v_rcp_f32_e32 v64, v64
	v_rcp_f32_e32 v65, v65
	v_pk_mul_f32 v[68:69], v[68:69], v[82:83] op_sel_hi:[1,0]
	v_pk_mul_f32 v[66:67], v[66:67], v[82:83] op_sel_hi:[1,0]
	v_mul_f32_e32 v68, 0xbfb8aa3b, v68
	v_mul_f32_e32 v69, 0xbfb8aa3b, v69
	v_exp_f32_e32 v68, v68
	v_exp_f32_e32 v69, v69
	v_add_f32_e32 v68, 1.0, v68
	v_add_f32_e32 v69, 1.0, v69
	v_rcp_f32_e32 v68, v68
	v_rcp_f32_e32 v69, v69
	v_lshlrev_b32_e32 v76, 16, v72
	v_and_b32_e32 v77, 0xffff0000, v72
	v_lshlrev_b32_e32 v72, 16, v73
	v_and_b32_e32 v73, 0xffff0000, v73
	v_pk_mul_f32 v[70:71], v[70:71], v[72:73]
	v_lshlrev_b32_e32 v72, 16, v74
	v_and_b32_e32 v73, 0xffff0000, v74
	v_pk_mul_f32 v[72:73], v[64:65], v[72:73]
	v_mul_f32_e32 v64, 0xbfb8aa3b, v66
	v_mul_f32_e32 v65, 0xbfb8aa3b, v67
	v_exp_f32_e32 v64, v64
	v_exp_f32_e32 v65, v65
	v_lshlrev_b32_e32 v66, 16, v75
	v_and_b32_e32 v67, 0xffff0000, v75
	v_add_f32_e32 v64, 1.0, v64
	v_add_f32_e32 v65, 1.0, v65
	v_rcp_f32_e32 v64, v64
	v_rcp_f32_e32 v65, v65
	v_pk_mul_f32 v[68:69], v[68:69], v[76:77]
	v_pk_mul_f32 v[74:75], v[64:65], v[66:67]
	v_cvt_pk_bf16_f32 v64, v68, v69
	v_cvt_pk_bf16_f32 v65, v70, v71
	v_cvt_pk_bf16_f32 v66, v72, v73
	v_cvt_pk_bf16_f32 v67, v74, v75
	global_store_dwordx4 v[80:81], v[64:67], off offset:256
	s_nop 1
	v_mov_b32_e32 v64, v183
	v_fmamk_f32 v64, v64, 0x3a800000, v187
	v_cmp_gt_f32_e32 vcc, s67, v64
	v_mul_f32_e32 v65, 0x4b800000, v64
	s_nop 0
	v_cndmask_b32_e32 v64, v64, v65, vcc
	v_rsq_f32_e32 v64, v64
	s_nop 0
	v_mul_f32_e32 v65, 0x45800000, v64
	v_cndmask_b32_e32 v66, v64, v65, vcc
	v_add_co_u32_e32 v72, vcc, s2, v158
	v_pk_mul_f32 v[62:63], v[62:63], v[66:67] op_sel_hi:[1,0]
	s_nop 0
	v_addc_co_u32_e32 v73, vcc, 0, v159, vcc
	s_nop 1
	v_mov_b32_e32 v68, v224
	v_mov_b32_e32 v69, v225
	v_mov_b32_e32 v70, v226
	v_mov_b32_e32 v71, v227
	v_pk_mul_f32 v[56:57], v[56:57], v[66:67] op_sel_hi:[1,0]
	v_mul_f32_e32 v62, 0xbfb8aa3b, v62
	v_mul_f32_e32 v63, 0xbfb8aa3b, v63
	v_exp_f32_e32 v62, v62
	v_exp_f32_e32 v63, v63
	v_mul_f32_e32 v56, 0xbfb8aa3b, v56
	v_mul_f32_e32 v57, 0xbfb8aa3b, v57
	v_exp_f32_e32 v56, v56
	v_exp_f32_e32 v57, v57
	v_add_f32_e32 v62, 1.0, v62
	v_add_f32_e32 v63, 1.0, v63
	v_rcp_f32_e32 v62, v62
	v_rcp_f32_e32 v63, v63
	v_add_f32_e32 v56, 1.0, v56
	v_add_f32_e32 v57, 1.0, v57
	v_rcp_f32_e32 v56, v56
	v_rcp_f32_e32 v57, v57
	v_pk_mul_f32 v[60:61], v[60:61], v[66:67] op_sel_hi:[1,0]
	v_pk_mul_f32 v[58:59], v[58:59], v[66:67] op_sel_hi:[1,0]
	v_mul_f32_e32 v60, 0xbfb8aa3b, v60
	v_mul_f32_e32 v61, 0xbfb8aa3b, v61
	v_exp_f32_e32 v60, v60
	v_exp_f32_e32 v61, v61
	v_lshl_add_u64 v[64:65], v[158:159], 0, s[4:5]
	v_pk_mul_f32 v[54:55], v[54:55], v[66:67] op_sel_hi:[1,0]
	v_add_f32_e32 v60, 1.0, v60
	v_add_f32_e32 v61, 1.0, v61
	v_rcp_f32_e32 v60, v60
	v_rcp_f32_e32 v61, v61
	v_pk_mul_f32 v[48:49], v[48:49], v[66:67] op_sel_hi:[1,0]
	v_mul_f32_e32 v54, 0xbfb8aa3b, v54
	v_mul_f32_e32 v55, 0xbfb8aa3b, v55
	v_exp_f32_e32 v54, v54
	v_exp_f32_e32 v55, v55
	v_mul_f32_e32 v48, 0xbfb8aa3b, v48
	v_mul_f32_e32 v49, 0xbfb8aa3b, v49
	v_exp_f32_e32 v48, v48
	v_exp_f32_e32 v49, v49
	v_add_f32_e32 v54, 1.0, v54
	v_add_f32_e32 v55, 1.0, v55
; __device__ __forceinline__ unsigned cvt_pk_bf16(float lo, float hi) { const f32x2_cv v = {lo, hi}; const bf16x2_cv b = __builtin_convertvector(v, bf16x2_cv); return __builtin_bit_cast(unsigned, b); }
; __device__ __forceinline__ float sigm(float x) { return __builtin_amdgcn_rcpf(1.0f + __expf(-x)); }
; __device__ __forceinline__ float lo16(unsigned w) { return __uint_as_float(w << 16); }
; __device__ __forceinline__ float hi16(unsigned w) { return __uint_as_float(w & 0xffff0000u); }
; __device__ __forceinline__ float rstd_of(const float* rowss, int row) { return rsqrtf(rowss[row] * (1.0f / 1024.0f) + 1e-6f); }
;     __device__ __forceinline__ void operator()(const f32x4 (&acc)[2][2][4][2], const pg8::Unit& u, int wr, int wc, int fr, int fq) const {
;     ...
;                 const int row = row0 + ai * 128 + m * 16;
;                 const float s = rstd_of(rowss, row);
; #pragma unroll
;                 for (int bj = 0; bj < 2; ++bj) {
;                     const size_t off = (size_t)row * 1024 + col0 + bj * 128;
;                     const u32x4 tv = *(const u32x4*)(Tm + off);
;                     u32x4 pv = (u32x4){0u, 0u, 0u, 0u};
;                     if (ACC) pv = *(const u32x4*)(M + off);
;                     const f32x4 a0 = acc[ai][bj][m][0] * s, a1 = acc[ai][bj][m][1] * s;
;                     float o[8];
;                     o[0] = sigm(a0[0]) * lo16(tv.x); o[1] = sigm(a0[1]) * hi16(tv.x); o[2] = sigm(a0[2]) * lo16(tv.y); o[3] = sigm(a0[3]) * hi16(tv.y);
;                     o[4] = sigm(a1[0]) * lo16(tv.z); o[5] = sigm(a1[1]) * hi16(tv.z); o[6] = sigm(a1[2]) * lo16(tv.w); o[7] = sigm(a1[3]) * hi16(tv.w);
;                     if (ACC) { o[0] += lo16(pv.x); o[1] += hi16(pv.x); o[2] += lo16(pv.y); o[3] += hi16(pv.y); o[4] += lo16(pv.z); o[5] += hi16(pv.z); o[6] += lo16(pv.w); o[7] += hi16(pv.w); }
;                     u32x4 w; w.x = cvt_pk_bf16(o[0], o[1]); w.y = cvt_pk_bf16(o[2], o[3]); w.z = cvt_pk_bf16(o[4], o[5]); w.w = cvt_pk_bf16(o[6], o[7]);
;                     *(u32x4*)(M + off) = w; } }
	v_rcp_f32_e32 v54, v54
	v_rcp_f32_e32 v55, v55
	v_add_f32_e32 v48, 1.0, v48
	v_add_f32_e32 v49, 1.0, v49
	v_rcp_f32_e32 v48, v48
	v_rcp_f32_e32 v49, v49
	v_pk_mul_f32 v[52:53], v[52:53], v[66:67] op_sel_hi:[1,0]
	v_pk_mul_f32 v[50:51], v[50:51], v[66:67] op_sel_hi:[1,0]
	v_mul_f32_e32 v52, 0xbfb8aa3b, v52
	v_mul_f32_e32 v53, 0xbfb8aa3b, v53
	v_exp_f32_e32 v52, v52
	v_exp_f32_e32 v53, v53
	s_mov_b32 s2, 0x48000
	s_mov_b64 s[4:5], 0x48000
	v_add_f32_e32 v52, 1.0, v52
	v_add_f32_e32 v53, 1.0, v53
	v_rcp_f32_e32 v52, v52
	v_rcp_f32_e32 v53, v53
	v_lshlrev_b32_e32 v74, 16, v68
	v_and_b32_e32 v75, 0xffff0000, v68
	v_lshlrev_b32_e32 v68, 16, v69
	v_and_b32_e32 v69, 0xffff0000, v69
	v_pk_mul_f32 v[62:63], v[62:63], v[68:69]
	v_lshlrev_b32_e32 v68, 16, v70
	v_and_b32_e32 v69, 0xffff0000, v70
	v_pk_mul_f32 v[68:69], v[56:57], v[68:69]
	v_mul_f32_e32 v56, 0xbfb8aa3b, v58
	v_mul_f32_e32 v57, 0xbfb8aa3b, v59
	v_exp_f32_e32 v56, v56
	v_exp_f32_e32 v57, v57
	v_lshlrev_b32_e32 v58, 16, v71
	v_and_b32_e32 v59, 0xffff0000, v71
	v_add_f32_e32 v56, 1.0, v56
	v_add_f32_e32 v57, 1.0, v57
	v_rcp_f32_e32 v56, v56
	v_rcp_f32_e32 v57, v57
	v_pk_mul_f32 v[60:61], v[60:61], v[74:75]
	v_pk_mul_f32 v[70:71], v[56:57], v[58:59]
	v_cvt_pk_bf16_f32 v56, v60, v61
	v_cvt_pk_bf16_f32 v57, v62, v63
	v_cvt_pk_bf16_f32 v58, v68, v69
	v_cvt_pk_bf16_f32 v59, v70, v71
	global_store_dwordx4 v[72:73], v[56:59], off
	s_nop 1
	v_mov_b32_e32 v56, v228
	v_mov_b32_e32 v57, v229
	v_mov_b32_e32 v58, v230
	v_mov_b32_e32 v59, v231
	v_lshlrev_b32_e32 v60, 16, v56
	v_and_b32_e32 v61, 0xffff0000, v56
	v_lshlrev_b32_e32 v56, 16, v57
	v_and_b32_e32 v57, 0xffff0000, v57
	v_pk_mul_f32 v[54:55], v[54:55], v[56:57]
	v_lshlrev_b32_e32 v56, 16, v58
	v_and_b32_e32 v57, 0xffff0000, v58
	v_pk_mul_f32 v[56:57], v[48:49], v[56:57]
	v_mul_f32_e32 v48, 0xbfb8aa3b, v50
	v_mul_f32_e32 v49, 0xbfb8aa3b, v51
	v_exp_f32_e32 v48, v48
	v_exp_f32_e32 v49, v49
	v_lshlrev_b32_e32 v50, 16, v59
	v_and_b32_e32 v51, 0xffff0000, v59
	v_add_f32_e32 v48, 1.0, v48
	v_add_f32_e32 v49, 1.0, v49
	v_rcp_f32_e32 v48, v48
	v_rcp_f32_e32 v49, v49
	v_pk_mul_f32 v[52:53], v[52:53], v[60:61]
	v_pk_mul_f32 v[58:59], v[48:49], v[50:51]
	v_cvt_pk_bf16_f32 v48, v52, v53
	v_cvt_pk_bf16_f32 v49, v54, v55
	v_cvt_pk_bf16_f32 v50, v56, v57
	v_cvt_pk_bf16_f32 v51, v58, v59
	global_store_dwordx4 v[64:65], v[48:51], off offset:256
	s_nop 1
	v_mov_b32_e32 v48, v240
	v_fmamk_f32 v48, v48, 0x3a800000, v187
	v_cmp_gt_f32_e32 vcc, s67, v48
	v_mul_f32_e32 v49, 0x4b800000, v48
	s_nop 0
	v_cndmask_b32_e32 v48, v48, v49, vcc
	v_rsq_f32_e32 v48, v48
	s_nop 0
	v_mul_f32_e32 v49, 0x45800000, v48
	v_cndmask_b32_e32 v50, v48, v49, vcc
	v_add_co_u32_e32 v56, vcc, s2, v158
	v_pk_mul_f32 v[46:47], v[46:47], v[50:51] op_sel_hi:[1,0]
	s_nop 0
	v_addc_co_u32_e32 v57, vcc, 0, v159, vcc
	s_nop 1
	v_mov_b32_e32 v52, v232
	v_mov_b32_e32 v53, v233
	v_mov_b32_e32 v54, v234
	v_mov_b32_e32 v55, v235
	v_pk_mul_f32 v[40:41], v[40:41], v[50:51] op_sel_hi:[1,0]
	v_mul_f32_e32 v46, 0xbfb8aa3b, v46
	v_mul_f32_e32 v47, 0xbfb8aa3b, v47
	v_exp_f32_e32 v46, v46
	v_exp_f32_e32 v47, v47
	v_mul_f32_e32 v40, 0xbfb8aa3b, v40
	v_mul_f32_e32 v41, 0xbfb8aa3b, v41
	v_exp_f32_e32 v40, v40
	v_exp_f32_e32 v41, v41
	v_add_f32_e32 v46, 1.0, v46
	v_add_f32_e32 v47, 1.0, v47
	v_rcp_f32_e32 v46, v46
	v_rcp_f32_e32 v47, v47
	v_add_f32_e32 v40, 1.0, v40
	v_add_f32_e32 v41, 1.0, v41
	v_rcp_f32_e32 v40, v40
	v_rcp_f32_e32 v41, v41
	v_pk_mul_f32 v[44:45], v[44:45], v[50:51] op_sel_hi:[1,0]
	v_pk_mul_f32 v[42:43], v[42:43], v[50:51] op_sel_hi:[1,0]
	v_mul_f32_e32 v44, 0xbfb8aa3b, v44
	v_mul_f32_e32 v45, 0xbfb8aa3b, v45
	v_exp_f32_e32 v44, v44
	v_exp_f32_e32 v45, v45
	v_lshl_add_u64 v[48:49], v[158:159], 0, s[4:5]
	v_pk_mul_f32 v[38:39], v[38:39], v[50:51] op_sel_hi:[1,0]
	v_add_f32_e32 v44, 1.0, v44
	v_add_f32_e32 v45, 1.0, v45
	v_rcp_f32_e32 v44, v44
	v_rcp_f32_e32 v45, v45
	v_pk_mul_f32 v[32:33], v[32:33], v[50:51] op_sel_hi:[1,0]
	v_mul_f32_e32 v38, 0xbfb8aa3b, v38
	v_mul_f32_e32 v39, 0xbfb8aa3b, v39
	v_exp_f32_e32 v38, v38
	v_exp_f32_e32 v39, v39
	v_mul_f32_e32 v32, 0xbfb8aa3b, v32
	v_mul_f32_e32 v33, 0xbfb8aa3b, v33
	v_exp_f32_e32 v32, v32
	v_exp_f32_e32 v33, v33
	v_add_f32_e32 v38, 1.0, v38
	v_add_f32_e32 v39, 1.0, v39
	v_rcp_f32_e32 v38, v38
	v_rcp_f32_e32 v39, v39
	v_add_f32_e32 v32, 1.0, v32
	v_add_f32_e32 v33, 1.0, v33
	v_rcp_f32_e32 v32, v32
	v_rcp_f32_e32 v33, v33
	v_pk_mul_f32 v[36:37], v[36:37], v[50:51] op_sel_hi:[1,0]
	v_pk_mul_f32 v[34:35], v[34:35], v[50:51] op_sel_hi:[1,0]
	v_mul_f32_e32 v36, 0xbfb8aa3b, v36
	v_mul_f32_e32 v37, 0xbfb8aa3b, v37
	v_exp_f32_e32 v36, v36
	v_exp_f32_e32 v37, v37
	s_mov_b32 s2, 0x50000
	s_mov_b64 s[4:5], 0x50000
	v_add_f32_e32 v36, 1.0, v36
	v_add_f32_e32 v37, 1.0, v37
	v_rcp_f32_e32 v36, v36
	v_rcp_f32_e32 v37, v37
	v_lshlrev_b32_e32 v58, 16, v52
	v_and_b32_e32 v59, 0xffff0000, v52
	v_lshlrev_b32_e32 v52, 16, v53
	v_and_b32_e32 v53, 0xffff0000, v53
	v_pk_mul_f32 v[46:47], v[46:47], v[52:53]
	v_lshlrev_b32_e32 v52, 16, v54
	v_and_b32_e32 v53, 0xffff0000, v54
	v_pk_mul_f32 v[52:53], v[40:41], v[52:53]
	v_mul_f32_e32 v40, 0xbfb8aa3b, v42
	v_mul_f32_e32 v41, 0xbfb8aa3b, v43
	v_exp_f32_e32 v40, v40
	v_exp_f32_e32 v41, v41
	v_lshlrev_b32_e32 v42, 16, v55
	v_and_b32_e32 v43, 0xffff0000, v55
	v_add_f32_e32 v40, 1.0, v40
	v_add_f32_e32 v41, 1.0, v41
	v_rcp_f32_e32 v40, v40
	v_rcp_f32_e32 v41, v41
	v_pk_mul_f32 v[44:45], v[44:45], v[58:59]
	v_pk_mul_f32 v[54:55], v[40:41], v[42:43]
	v_cvt_pk_bf16_f32 v40, v44, v45
	v_cvt_pk_bf16_f32 v41, v46, v47
	v_cvt_pk_bf16_f32 v42, v52, v53
	v_cvt_pk_bf16_f32 v43, v54, v55
	global_store_dwordx4 v[56:57], v[40:43], off
	s_nop 1
; __device__ __forceinline__ unsigned cvt_pk_bf16(float lo, float hi) { const f32x2_cv v = {lo, hi}; const bf16x2_cv b = __builtin_convertvector(v, bf16x2_cv); return __builtin_bit_cast(unsigned, b); }
; __device__ __forceinline__ float sigm(float x) { return __builtin_amdgcn_rcpf(1.0f + __expf(-x)); }
; __device__ __forceinline__ float lo16(unsigned w) { return __uint_as_float(w << 16); }
; __device__ __forceinline__ float hi16(unsigned w) { return __uint_as_float(w & 0xffff0000u); }
; __device__ __forceinline__ float rstd_of(const float* rowss, int row) { return rsqrtf(rowss[row] * (1.0f / 1024.0f) + 1e-6f); }
;     __device__ __forceinline__ void operator()(const f32x4 (&acc)[2][2][4][2], const pg8::Unit& u, int wr, int wc, int fr, int fq) const {
;     ...
;                 const int row = row0 + ai * 128 + m * 16;
;                 const float s = rstd_of(rowss, row);
; #pragma unroll
;                 for (int bj = 0; bj < 2; ++bj) {
;                     const size_t off = (size_t)row * 1024 + col0 + bj * 128;
;                     const u32x4 tv = *(const u32x4*)(Tm + off);
;                     u32x4 pv = (u32x4){0u, 0u, 0u, 0u};
;                     if (ACC) pv = *(const u32x4*)(M + off);
;                     const f32x4 a0 = acc[ai][bj][m][0] * s, a1 = acc[ai][bj][m][1] * s;
;                     float o[8];
;                     o[0] = sigm(a0[0]) * lo16(tv.x); o[1] = sigm(a0[1]) * hi16(tv.x); o[2] = sigm(a0[2]) * lo16(tv.y); o[3] = sigm(a0[3]) * hi16(tv.y);
;                     o[4] = sigm(a1[0]) * lo16(tv.z); o[5] = sigm(a1[1]) * hi16(tv.z); o[6] = sigm(a1[2]) * lo16(tv.w); o[7] = sigm(a1[3]) * hi16(tv.w);
;                     if (ACC) { o[0] += lo16(pv.x); o[1] += hi16(pv.x); o[2] += lo16(pv.y); o[3] += hi16(pv.y); o[4] += lo16(pv.z); o[5] += hi16(pv.z); o[6] += lo16(pv.w); o[7] += hi16(pv.w); }
;                     u32x4 w; w.x = cvt_pk_bf16(o[0], o[1]); w.y = cvt_pk_bf16(o[2], o[3]); w.z = cvt_pk_bf16(o[4], o[5]); w.w = cvt_pk_bf16(o[6], o[7]);
;                     *(u32x4*)(M + off) = w; } }
	v_mov_b32_e32 v40, v236
	v_mov_b32_e32 v41, v237
	v_mov_b32_e32 v42, v238
	v_mov_b32_e32 v43, v239
	v_lshlrev_b32_e32 v44, 16, v40
	v_and_b32_e32 v45, 0xffff0000, v40
	v_lshlrev_b32_e32 v40, 16, v41
	v_and_b32_e32 v41, 0xffff0000, v41
	v_pk_mul_f32 v[38:39], v[38:39], v[40:41]
	v_lshlrev_b32_e32 v40, 16, v42
	v_and_b32_e32 v41, 0xffff0000, v42
	v_pk_mul_f32 v[40:41], v[32:33], v[40:41]
	v_mul_f32_e32 v32, 0xbfb8aa3b, v34
	v_mul_f32_e32 v33, 0xbfb8aa3b, v35
	v_exp_f32_e32 v32, v32
	v_exp_f32_e32 v33, v33
	v_lshlrev_b32_e32 v34, 16, v43
	v_and_b32_e32 v35, 0xffff0000, v43
	v_add_f32_e32 v32, 1.0, v32
	v_add_f32_e32 v33, 1.0, v33
	v_rcp_f32_e32 v32, v32
	v_rcp_f32_e32 v33, v33
	v_pk_mul_f32 v[36:37], v[36:37], v[44:45]
	v_pk_mul_f32 v[42:43], v[32:33], v[34:35]
	v_cvt_pk_bf16_f32 v32, v36, v37
	v_cvt_pk_bf16_f32 v33, v38, v39
	v_cvt_pk_bf16_f32 v34, v40, v41
	v_cvt_pk_bf16_f32 v35, v42, v43
	global_store_dwordx4 v[48:49], v[32:35], off offset:256
	s_nop 1
	v_mov_b32_e32 v32, v241
	v_fmamk_f32 v32, v32, 0x3a800000, v187
	v_cmp_gt_f32_e32 vcc, s67, v32
	v_mul_f32_e32 v33, 0x4b800000, v32
	s_nop 0
	v_cndmask_b32_e32 v32, v32, v33, vcc
	v_rsq_f32_e32 v32, v32
	s_nop 0
	v_mul_f32_e32 v33, 0x45800000, v32
	v_cndmask_b32_e32 v34, v32, v33, vcc
	v_add_co_u32_e32 v40, vcc, s2, v158
	v_pk_mul_f32 v[30:31], v[30:31], v[34:35] op_sel_hi:[1,0]
	s_nop 0
	v_addc_co_u32_e32 v41, vcc, 0, v159, vcc
	s_nop 1
	v_mov_b32_e32 v36, v244
	v_mov_b32_e32 v37, v245
	v_mov_b32_e32 v38, v246
	v_mov_b32_e32 v39, v247
	v_pk_mul_f32 v[24:25], v[24:25], v[34:35] op_sel_hi:[1,0]
	v_mul_f32_e32 v30, 0xbfb8aa3b, v30
	v_mul_f32_e32 v31, 0xbfb8aa3b, v31
	v_exp_f32_e32 v30, v30
	v_exp_f32_e32 v31, v31
	v_mul_f32_e32 v24, 0xbfb8aa3b, v24
	v_mul_f32_e32 v25, 0xbfb8aa3b, v25
	v_exp_f32_e32 v24, v24
	v_exp_f32_e32 v25, v25
	v_add_f32_e32 v30, 1.0, v30
	v_add_f32_e32 v31, 1.0, v31
	v_rcp_f32_e32 v30, v30
	v_rcp_f32_e32 v31, v31
	v_add_f32_e32 v24, 1.0, v24
	v_add_f32_e32 v25, 1.0, v25
	v_rcp_f32_e32 v24, v24
	v_rcp_f32_e32 v25, v25
	v_pk_mul_f32 v[28:29], v[28:29], v[34:35] op_sel_hi:[1,0]
	v_pk_mul_f32 v[26:27], v[26:27], v[34:35] op_sel_hi:[1,0]
	v_mul_f32_e32 v28, 0xbfb8aa3b, v28
	v_mul_f32_e32 v29, 0xbfb8aa3b, v29
	v_exp_f32_e32 v28, v28
	v_exp_f32_e32 v29, v29
	v_lshl_add_u64 v[32:33], v[158:159], 0, s[4:5]
	v_pk_mul_f32 v[22:23], v[22:23], v[34:35] op_sel_hi:[1,0]
	v_add_f32_e32 v28, 1.0, v28
	v_add_f32_e32 v29, 1.0, v29
	v_rcp_f32_e32 v28, v28
	v_rcp_f32_e32 v29, v29
	v_pk_mul_f32 v[16:17], v[16:17], v[34:35] op_sel_hi:[1,0]
	v_mul_f32_e32 v22, 0xbfb8aa3b, v22
	v_mul_f32_e32 v23, 0xbfb8aa3b, v23
	v_exp_f32_e32 v22, v22
	v_exp_f32_e32 v23, v23
	v_mul_f32_e32 v16, 0xbfb8aa3b, v16
	v_mul_f32_e32 v17, 0xbfb8aa3b, v17
	v_exp_f32_e32 v16, v16
	v_exp_f32_e32 v17, v17
	v_add_f32_e32 v22, 1.0, v22
	v_add_f32_e32 v23, 1.0, v23
	v_rcp_f32_e32 v22, v22
	v_rcp_f32_e32 v23, v23
	v_add_f32_e32 v16, 1.0, v16
	v_add_f32_e32 v17, 1.0, v17
	v_rcp_f32_e32 v16, v16
	v_rcp_f32_e32 v17, v17
	v_pk_mul_f32 v[20:21], v[20:21], v[34:35] op_sel_hi:[1,0]
	v_pk_mul_f32 v[18:19], v[18:19], v[34:35] op_sel_hi:[1,0]
	v_mul_f32_e32 v20, 0xbfb8aa3b, v20
	v_mul_f32_e32 v21, 0xbfb8aa3b, v21
	v_exp_f32_e32 v20, v20
	v_exp_f32_e32 v21, v21
	s_mov_b32 s2, 0x58000
	s_mov_b64 s[4:5], 0x58000
	v_add_f32_e32 v20, 1.0, v20
	v_add_f32_e32 v21, 1.0, v21
	v_rcp_f32_e32 v20, v20
	v_rcp_f32_e32 v21, v21
	v_lshlrev_b32_e32 v42, 16, v36
	v_and_b32_e32 v43, 0xffff0000, v36
	v_lshlrev_b32_e32 v36, 16, v37
	v_and_b32_e32 v37, 0xffff0000, v37
	v_pk_mul_f32 v[30:31], v[30:31], v[36:37]
	v_lshlrev_b32_e32 v36, 16, v38
	v_and_b32_e32 v37, 0xffff0000, v38
	v_pk_mul_f32 v[36:37], v[24:25], v[36:37]
	v_mul_f32_e32 v24, 0xbfb8aa3b, v26
	v_mul_f32_e32 v25, 0xbfb8aa3b, v27
	v_exp_f32_e32 v24, v24
	v_exp_f32_e32 v25, v25
	v_lshlrev_b32_e32 v26, 16, v39
	v_and_b32_e32 v27, 0xffff0000, v39
	v_add_f32_e32 v24, 1.0, v24
	v_add_f32_e32 v25, 1.0, v25
	v_rcp_f32_e32 v24, v24
	v_rcp_f32_e32 v25, v25
	v_pk_mul_f32 v[28:29], v[28:29], v[42:43]
	v_pk_mul_f32 v[38:39], v[24:25], v[26:27]
	v_cvt_pk_bf16_f32 v24, v28, v29
	v_cvt_pk_bf16_f32 v25, v30, v31
	v_cvt_pk_bf16_f32 v26, v36, v37
	v_cvt_pk_bf16_f32 v27, v38, v39
	global_store_dwordx4 v[40:41], v[24:27], off
	s_nop 1
	v_mov_b32_e32 v24, v248
	v_mov_b32_e32 v25, v249
	v_mov_b32_e32 v26, v250
	v_mov_b32_e32 v27, v251
	v_lshlrev_b32_e32 v28, 16, v24
	v_and_b32_e32 v29, 0xffff0000, v24
	v_lshlrev_b32_e32 v24, 16, v25
	v_and_b32_e32 v25, 0xffff0000, v25
	v_pk_mul_f32 v[22:23], v[22:23], v[24:25]
	v_lshlrev_b32_e32 v24, 16, v26
	v_and_b32_e32 v25, 0xffff0000, v26
	v_pk_mul_f32 v[24:25], v[16:17], v[24:25]
	v_mul_f32_e32 v16, 0xbfb8aa3b, v18
	v_mul_f32_e32 v17, 0xbfb8aa3b, v19
; __device__ __forceinline__ unsigned cvt_pk_bf16(float lo, float hi) { const f32x2_cv v = {lo, hi}; const bf16x2_cv b = __builtin_convertvector(v, bf16x2_cv); return __builtin_bit_cast(unsigned, b); }
; __device__ __forceinline__ float sigm(float x) { return __builtin_amdgcn_rcpf(1.0f + __expf(-x)); }
; __device__ __forceinline__ float lo16(unsigned w) { return __uint_as_float(w << 16); }
; __device__ __forceinline__ float hi16(unsigned w) { return __uint_as_float(w & 0xffff0000u); }
; __device__ __forceinline__ float rstd_of(const float* rowss, int row) { return rsqrtf(rowss[row] * (1.0f / 1024.0f) + 1e-6f); }
;     __device__ __forceinline__ void operator()(const f32x4 (&acc)[2][2][4][2], const pg8::Unit& u, int wr, int wc, int fr, int fq) const {
;     ...
;                 const int row = row0 + ai * 128 + m * 16;
;                 const float s = rstd_of(rowss, row);
; #pragma unroll
;                 for (int bj = 0; bj < 2; ++bj) {
;                     const size_t off = (size_t)row * 1024 + col0 + bj * 128;
;                     const u32x4 tv = *(const u32x4*)(Tm + off);
;                     u32x4 pv = (u32x4){0u, 0u, 0u, 0u};
;                     if (ACC) pv = *(const u32x4*)(M + off);
;                     const f32x4 a0 = acc[ai][bj][m][0] * s, a1 = acc[ai][bj][m][1] * s;
;                     float o[8];
;                     o[0] = sigm(a0[0]) * lo16(tv.x); o[1] = sigm(a0[1]) * hi16(tv.x); o[2] = sigm(a0[2]) * lo16(tv.y); o[3] = sigm(a0[3]) * hi16(tv.y);
;                     o[4] = sigm(a1[0]) * lo16(tv.z); o[5] = sigm(a1[1]) * hi16(tv.z); o[6] = sigm(a1[2]) * lo16(tv.w); o[7] = sigm(a1[3]) * hi16(tv.w);
;                     if (ACC) { o[0] += lo16(pv.x); o[1] += hi16(pv.x); o[2] += lo16(pv.y); o[3] += hi16(pv.y); o[4] += lo16(pv.z); o[5] += hi16(pv.z); o[6] += lo16(pv.w); o[7] += hi16(pv.w); }
;                     u32x4 w; w.x = cvt_pk_bf16(o[0], o[1]); w.y = cvt_pk_bf16(o[2], o[3]); w.z = cvt_pk_bf16(o[4], o[5]); w.w = cvt_pk_bf16(o[6], o[7]);
;                     *(u32x4*)(M + off) = w; } }
	v_exp_f32_e32 v16, v16
	v_exp_f32_e32 v17, v17
	v_lshlrev_b32_e32 v18, 16, v27
	v_and_b32_e32 v19, 0xffff0000, v27
	v_add_f32_e32 v16, 1.0, v16
	v_add_f32_e32 v17, 1.0, v17
	v_rcp_f32_e32 v16, v16
	v_rcp_f32_e32 v17, v17
	v_pk_mul_f32 v[20:21], v[20:21], v[28:29]
	v_pk_mul_f32 v[26:27], v[16:17], v[18:19]
	v_cvt_pk_bf16_f32 v16, v20, v21
	v_cvt_pk_bf16_f32 v17, v22, v23
	v_cvt_pk_bf16_f32 v18, v24, v25
	v_cvt_pk_bf16_f32 v19, v26, v27
	global_store_dwordx4 v[32:33], v[16:19], off offset:256
	s_nop 1
	v_mov_b32_e32 v16, v169
	v_fmamk_f32 v16, v16, 0x3a800000, v187
	v_cmp_gt_f32_e32 vcc, s67, v16
	v_mul_f32_e32 v17, 0x4b800000, v16
	s_nop 0
	v_cndmask_b32_e32 v16, v16, v17, vcc
	v_rsq_f32_e32 v16, v16
	s_nop 0
	v_mul_f32_e32 v17, 0x45800000, v16
	v_cndmask_b32_e32 v18, v16, v17, vcc
	v_add_co_u32_e32 v24, vcc, s2, v158
	v_pk_mul_f32 v[14:15], v[14:15], v[18:19] op_sel_hi:[1,0]
	s_nop 0
	v_addc_co_u32_e32 v25, vcc, 0, v159, vcc
	s_nop 1
	v_mov_b32_e32 v20, v176
	v_mov_b32_e32 v21, v177
	v_mov_b32_e32 v22, v178
	v_mov_b32_e32 v23, v179
	v_pk_mul_f32 v[8:9], v[8:9], v[18:19] op_sel_hi:[1,0]
	v_mul_f32_e32 v14, 0xbfb8aa3b, v14
	v_mul_f32_e32 v15, 0xbfb8aa3b, v15
	v_exp_f32_e32 v14, v14
	v_exp_f32_e32 v15, v15
	v_mul_f32_e32 v8, 0xbfb8aa3b, v8
	v_mul_f32_e32 v9, 0xbfb8aa3b, v9
	v_exp_f32_e32 v8, v8
	v_exp_f32_e32 v9, v9
	v_add_f32_e32 v14, 1.0, v14
	v_add_f32_e32 v15, 1.0, v15
	v_rcp_f32_e32 v14, v14
	v_rcp_f32_e32 v15, v15
	v_add_f32_e32 v8, 1.0, v8
	v_add_f32_e32 v9, 1.0, v9
	v_rcp_f32_e32 v8, v8
	v_rcp_f32_e32 v9, v9
	v_pk_mul_f32 v[12:13], v[12:13], v[18:19] op_sel_hi:[1,0]
	v_pk_mul_f32 v[10:11], v[10:11], v[18:19] op_sel_hi:[1,0]
	v_mul_f32_e32 v12, 0xbfb8aa3b, v12
	v_mul_f32_e32 v13, 0xbfb8aa3b, v13
	v_exp_f32_e32 v12, v12
	v_exp_f32_e32 v13, v13
	v_lshl_add_u64 v[16:17], v[158:159], 0, s[4:5]
	v_pk_mul_f32 v[6:7], v[6:7], v[18:19] op_sel_hi:[1,0]
	v_add_f32_e32 v12, 1.0, v12
	v_add_f32_e32 v13, 1.0, v13
	v_rcp_f32_e32 v12, v12
	v_rcp_f32_e32 v13, v13
	v_pk_mul_f32 v[0:1], v[0:1], v[18:19] op_sel_hi:[1,0]
	v_mul_f32_e32 v6, 0xbfb8aa3b, v6
	v_mul_f32_e32 v7, 0xbfb8aa3b, v7
	v_exp_f32_e32 v6, v6
	v_exp_f32_e32 v7, v7
	v_mul_f32_e32 v0, 0xbfb8aa3b, v0
	v_mul_f32_e32 v1, 0xbfb8aa3b, v1
	v_exp_f32_e32 v0, v0
	v_exp_f32_e32 v1, v1
	v_add_f32_e32 v6, 1.0, v6
	v_add_f32_e32 v7, 1.0, v7
	v_rcp_f32_e32 v6, v6
	v_rcp_f32_e32 v7, v7
	v_add_f32_e32 v0, 1.0, v0
	v_add_f32_e32 v1, 1.0, v1
	v_rcp_f32_e32 v0, v0
	v_rcp_f32_e32 v1, v1
	v_pk_mul_f32 v[4:5], v[4:5], v[18:19] op_sel_hi:[1,0]
	v_pk_mul_f32 v[2:3], v[2:3], v[18:19] op_sel_hi:[1,0]
	v_mul_f32_e32 v4, 0xbfb8aa3b, v4
	v_mul_f32_e32 v5, 0xbfb8aa3b, v5
	v_exp_f32_e32 v4, v4
	v_exp_f32_e32 v5, v5
	s_and_b64 vcc, exec, s[38:39]
	s_mov_b32 s2, s30
	v_add_f32_e32 v4, 1.0, v4
	v_add_f32_e32 v5, 1.0, v5
	v_rcp_f32_e32 v4, v4
	v_rcp_f32_e32 v5, v5
	s_mov_b64 s[4:5], s[48:49]
	v_lshlrev_b32_e32 v26, 16, v20
	v_and_b32_e32 v27, 0xffff0000, v20
	v_lshlrev_b32_e32 v20, 16, v21
	v_and_b32_e32 v21, 0xffff0000, v21
	v_pk_mul_f32 v[14:15], v[14:15], v[20:21]
	v_lshlrev_b32_e32 v20, 16, v22
	v_and_b32_e32 v21, 0xffff0000, v22
	v_pk_mul_f32 v[20:21], v[8:9], v[20:21]
	v_mul_f32_e32 v8, 0xbfb8aa3b, v10
	v_mul_f32_e32 v9, 0xbfb8aa3b, v11
	v_exp_f32_e32 v8, v8
	v_exp_f32_e32 v9, v9
	v_lshlrev_b32_e32 v10, 16, v23
	v_and_b32_e32 v11, 0xffff0000, v23
	v_add_f32_e32 v8, 1.0, v8
	v_add_f32_e32 v9, 1.0, v9
	v_rcp_f32_e32 v8, v8
	v_rcp_f32_e32 v9, v9
	v_pk_mul_f32 v[12:13], v[12:13], v[26:27]
	v_pk_mul_f32 v[22:23], v[8:9], v[10:11]
	v_cvt_pk_bf16_f32 v8, v12, v13
	v_cvt_pk_bf16_f32 v9, v14, v15
	v_cvt_pk_bf16_f32 v10, v20, v21
	v_cvt_pk_bf16_f32 v11, v22, v23
	global_store_dwordx4 v[24:25], v[8:11], off
	s_nop 1
	v_mov_b32_e32 v8, v252
	v_mov_b32_e32 v9, v253
	v_mov_b32_e32 v10, v254
	v_mov_b32_e32 v11, v255
	v_lshlrev_b32_e32 v12, 16, v8
	v_and_b32_e32 v13, 0xffff0000, v8
	v_lshlrev_b32_e32 v8, 16, v9
	v_and_b32_e32 v9, 0xffff0000, v9
	v_pk_mul_f32 v[6:7], v[6:7], v[8:9]
	v_lshlrev_b32_e32 v8, 16, v10
	v_and_b32_e32 v9, 0xffff0000, v10
	v_pk_mul_f32 v[8:9], v[0:1], v[8:9]
	v_mul_f32_e32 v0, 0xbfb8aa3b, v2
	v_mul_f32_e32 v1, 0xbfb8aa3b, v3
	v_exp_f32_e32 v0, v0
	v_exp_f32_e32 v1, v1
	v_lshlrev_b32_e32 v2, 16, v11
	v_and_b32_e32 v3, 0xffff0000, v11
	v_add_f32_e32 v0, 1.0, v0
	v_add_f32_e32 v1, 1.0, v1
	v_rcp_f32_e32 v0, v0
	v_rcp_f32_e32 v1, v1
	v_pk_mul_f32 v[4:5], v[4:5], v[12:13]
	v_pk_mul_f32 v[10:11], v[0:1], v[2:3]
	v_cvt_pk_bf16_f32 v0, v4, v5
	v_cvt_pk_bf16_f32 v1, v6, v7
	v_cvt_pk_bf16_f32 v2, v8, v9
	v_cvt_pk_bf16_f32 v3, v10, v11
	global_store_dwordx4 v[16:17], v[0:3], off offset:256
	s_cbranch_vccz .LBB0_306
	s_cmpk_gt_u32 s36, 0xff
	s_cbranch_scc1 .LBB0_317
	s_barrier

; #define PG8_STAGE(bufoff, gbase, voff) do { _Pragma("unroll") for (int _i = 0; _i < 2; ++_i) \
;         __builtin_amdgcn_global_load_lds((const unsigned*)((const char*)(gbase) + (voff)[_i]), (PG8_LAS unsigned*)(lds + (bufoff) + ldsw + _i * 8192), 16, 0, 0); } while (0)
; #define PG8_LDA(dst, b, h) do { _Pragma("unroll") for (int m = 0; m < 4; ++m) _Pragma("unroll") for (int k = 0; k < 2; ++k) dst[m][k] = *(const PG8_LAS bf16x8*)(lds + PG8_SA(b, h) + aoff + m * 2048 + k * 1024); } while (0)
; #define PG8_LDB(dst, b, h) do { _Pragma("unroll") for (int n = 0; n < 2; ++n) _Pragma("unroll") for (int k = 0; k < 2; ++k) dst[n][k] = *(const PG8_LAS bf16x8*)(lds + PG8_SB(b, h) + boff + n * 2048 + k * 1024); } while (0)
; #define PG8_WAIT_L(n) asm volatile("s_waitcnt lgkmcnt(" #n ")" ::: "memory")
; #define PG8_BAR __builtin_amdgcn_s_barrier()
; #define PG8_SCHED __builtin_amdgcn_sched_barrier(0)
;     __device__ bool next(int i, pg8::Unit& u) const { if (i != 0 || !valid) return false; u.pm = pm; u.pn = pn; return true; }
; template <class Epi, class Sched, bool STAMP = false>
; __device__ __forceinline__ void gemm_phase(PG8_LAS unsigned char* lds, const Gemm g, const Sched& S, const Epi& E, unsigned long long* stamps) {
;     ...
;         const bool has_next = S.next(ui + 1, nxt);
;         const char* nA = has_next ? (const char*)g.A + (size_t)nxt.pm * tstep : cA; const char* nB = has_next ? (const char*)g.Bt + (size_t)nxt.pn * tstep : cB;
;         for (int t = 0; t < nt; t += 2) {
;             const bool last = (t == nt - 2);
;             const char* a1 = cA + (size_t)(t + 1) * kstep;
;             const char* a2 = last ? nA : cA + (size_t)(t + 2) * kstep; const char* b2 = last ? nB : cB + (size_t)(t + 2) * kstep;
;             const char* a3 = a2 + kstep; const char* b3 = b2 + kstep;
;             if (last && has_next) S.a_ready(nxt);
;             PG8_LDB(B0, 0, 0); PG8_SCHED; PG8_LDA(At, 0, 0); PG8_STAGE(PG8_SA(1, 1), a1 + hstep, voffA);
;             PG8_WAIT_L(8); PG8_BAR; PG8_WAIT_L(0); PG8_MMA(0, 0, At, B0); PG8_BAR; PG8_SCHED;
;     ...
; #pragma unroll
;         for (int a = 0; a < 2; ++a)
; #pragma unroll
;             for (int b = 0; b < 2; ++b)
; #pragma unroll
;                 for (int m = 0; m < 4; ++m)
; #pragma unroll
;                     for (int n = 0; n < 2; ++n) acc[a][b][m][n] = (f32x4){0.f, 0.f, 0.f, 0.f};
;         cur = nxt; cA = nA; cB = nB; ++ui;
.LBB0_332:
	s_ashr_i32 s13, s12, 31
	s_lshl_b64 s[14:15], s[12:13], 18
	v_cmp_lt_i64_e32 vcc, s[24:25], v[136:137]
	s_add_u32 s24, s48, s14
	s_addc_u32 s25, s49, s15
	s_and_b64 s[14:15], vcc, exec
	s_cselect_b32 s13, s25, s37
	s_cselect_b32 s77, s24, s36
	s_ashr_i32 s5, s4, 31
	s_lshl_b64 s[14:15], s[4:5], 18
	s_add_u32 s26, s6, s14
	s_addc_u32 s27, s7, s15
	s_and_b64 s[14:15], vcc, exec
	s_cselect_b32 s5, s27, s57
	s_cselect_b32 s88, s26, s56
	s_add_u32 s36, s36, 0x20080
	s_addc_u32 s37, s37, 0
	s_add_u32 s89, s56, 0x100
	v_mov_b32_e32 v0, 0
	s_addc_u32 s96, s57, 0
	s_mov_b32 s97, -2
	v_mov_b32_e32 v1, v0
	v_mov_b32_e32 v2, v0
	v_mov_b32_e32 v3, v0
	v_mov_b32_e32 v4, v0
	v_mov_b32_e32 v5, v0
	v_mov_b32_e32 v6, v0
	v_mov_b32_e32 v7, v0
	v_mov_b32_e32 v8, v0
	v_mov_b32_e32 v9, v0
	v_mov_b32_e32 v10, v0
	v_mov_b32_e32 v11, v0
	v_mov_b32_e32 v12, v0
	v_mov_b32_e32 v13, v0
	v_mov_b32_e32 v14, v0
	v_mov_b32_e32 v15, v0
	v_mov_b32_e32 v24, v0
	v_mov_b32_e32 v25, v0
	v_mov_b32_e32 v26, v0
	v_mov_b32_e32 v27, v0
	v_mov_b32_e32 v28, v0
	v_mov_b32_e32 v29, v0
	v_mov_b32_e32 v30, v0
	v_mov_b32_e32 v31, v0
	v_mov_b32_e32 v40, v0
	v_mov_b32_e32 v41, v0
	v_mov_b32_e32 v42, v0
	v_mov_b32_e32 v43, v0
	v_mov_b32_e32 v44, v0
	v_mov_b32_e32 v45, v0
	v_mov_b32_e32 v46, v0
	v_mov_b32_e32 v47, v0
	v_mov_b32_e32 v16, v0
	v_mov_b32_e32 v17, v0
	v_mov_b32_e32 v18, v0
	v_mov_b32_e32 v19, v0
	v_mov_b32_e32 v20, v0
	v_mov_b32_e32 v21, v0
	v_mov_b32_e32 v22, v0
	v_mov_b32_e32 v23, v0
	v_mov_b32_e32 v32, v0
	v_mov_b32_e32 v33, v0
	v_mov_b32_e32 v34, v0
	v_mov_b32_e32 v35, v0
	v_mov_b32_e32 v36, v0
	v_mov_b32_e32 v37, v0
	v_mov_b32_e32 v38, v0
	v_mov_b32_e32 v39, v0
	v_mov_b32_e32 v48, v0
	v_mov_b32_e32 v49, v0
	v_mov_b32_e32 v50, v0
	v_mov_b32_e32 v51, v0
	v_mov_b32_e32 v52, v0
	v_mov_b32_e32 v53, v0
	v_mov_b32_e32 v54, v0
	v_mov_b32_e32 v55, v0
	v_mov_b32_e32 v56, v0
	v_mov_b32_e32 v57, v0
	v_mov_b32_e32 v58, v0
	v_mov_b32_e32 v59, v0
	v_mov_b32_e32 v60, v0
	v_mov_b32_e32 v61, v0
	v_mov_b32_e32 v62, v0
	v_mov_b32_e32 v63, v0
	v_mov_b32_e32 v64, v0
	v_mov_b32_e32 v65, v0
	v_mov_b32_e32 v66, v0
	v_mov_b32_e32 v67, v0
	v_mov_b32_e32 v68, v0
	v_mov_b32_e32 v69, v0
	v_mov_b32_e32 v70, v0
	v_mov_b32_e32 v71, v0
	v_mov_b32_e32 v72, v0
	v_mov_b32_e32 v73, v0
	v_mov_b32_e32 v74, v0
	v_mov_b32_e32 v75, v0
	v_mov_b32_e32 v76, v0
	v_mov_b32_e32 v77, v0
	v_mov_b32_e32 v78, v0
	v_mov_b32_e32 v79, v0
	v_mov_b32_e32 v88, v0
	v_mov_b32_e32 v89, v0
	v_mov_b32_e32 v90, v0
	v_mov_b32_e32 v91, v0
	v_mov_b32_e32 v92, v0
	v_mov_b32_e32 v93, v0
	v_mov_b32_e32 v94, v0
	v_mov_b32_e32 v95, v0
	v_mov_b32_e32 v104, v0
	v_mov_b32_e32 v105, v0
	v_mov_b32_e32 v106, v0
	v_mov_b32_e32 v107, v0
	v_mov_b32_e32 v108, v0
	v_mov_b32_e32 v109, v0
	v_mov_b32_e32 v110, v0
	v_mov_b32_e32 v111, v0
	v_mov_b32_e32 v80, v0
	v_mov_b32_e32 v81, v0
	v_mov_b32_e32 v82, v0
	v_mov_b32_e32 v83, v0
	v_mov_b32_e32 v84, v0
	v_mov_b32_e32 v85, v0
	v_mov_b32_e32 v86, v0
	v_mov_b32_e32 v87, v0
	v_mov_b32_e32 v96, v0
	v_mov_b32_e32 v97, v0
	v_mov_b32_e32 v98, v0
	v_mov_b32_e32 v99, v0
	v_mov_b32_e32 v100, v0
	v_mov_b32_e32 v101, v0
	v_mov_b32_e32 v102, v0
	v_mov_b32_e32 v103, v0
	v_mov_b32_e32 v112, v0
	v_mov_b32_e32 v113, v0
	v_mov_b32_e32 v114, v0
	v_mov_b32_e32 v115, v0
	v_mov_b32_e32 v116, v0
	v_mov_b32_e32 v117, v0
	v_mov_b32_e32 v118, v0
	v_mov_b32_e32 v119, v0
	v_mov_b32_e32 v120, v0
	v_mov_b32_e32 v121, v0
	v_mov_b32_e32 v122, v0
	v_mov_b32_e32 v123, v0
	v_mov_b32_e32 v124, v0
	v_mov_b32_e32 v125, v0
	v_mov_b32_e32 v126, v0
	v_mov_b32_e32 v127, v0
	v_add_u32_e32 v244, 0x80, v128
	v_add_u32_e32 v245, 0x80, v152
	v_add_u32_e32 v246, 0x80, v148
	v_add_u32_e32 v247, 0x80, v150
	v_add_u32_e32 v248, 0x10000, v158
	v_add_u32_e32 v249, 0x14000, v158
	v_add_u32_e32 v250, 0x18000, v158
	v_add_u32_e32 v251, 0x1c000, v158
.LBB0_333:
	s_add_u32 s14, s36, 0xfffe0080
	s_addc_u32 s15, s37, -1
	s_add_i32 s16, 0, 0x10000
	ds_read_b128 v[162:165], v248
	ds_read_b128 v[166:169], v248 offset:1024
	ds_read_b128 v[170:173], v248 offset:2048
	ds_read_b128 v[174:177], v248 offset:3072
	s_cmp_eq_u32 s97, 4
	s_cselect_b32 s59, s13, s15
	s_cselect_b32 s58, s77, s14
	s_cselect_b32 s57, s5, s96
	s_cselect_b32 s56, s88, s89
	s_add_i32 m0, s3, 0xc000
	ds_read_b128 v[178:181], v160
	ds_read_b128 v[192:195], v160 offset:1024
	ds_read_b128 v[196:199], v160 offset:2048
	ds_read_b128 v[200:203], v160 offset:3072
	ds_read_b128 v[204:207], v160 offset:4096
	ds_read_b128 v[208:211], v160 offset:5120
	ds_read_b128 v[212:215], v160 offset:6144
	ds_read_b128 v[216:219], v160 offset:7168
	global_load_lds_dwordx4 v154, s[36:37]
	s_add_i32 m0, s3, 0xe000
	s_nop 0
	global_load_lds_dwordx4 v156, s[36:37]
	s_waitcnt lgkmcnt(8)
	s_barrier
	s_waitcnt lgkmcnt(0)
	v_mfma_f32_16x16x32_bf16 v[124:127], v[162:165], v[178:181], v[124:127]
	v_mfma_f32_16x16x32_bf16 v[120:123], v[170:173], v[178:181], v[120:123]
	v_mfma_f32_16x16x32_bf16 v[116:119], v[162:165], v[196:199], v[116:119]
	v_mfma_f32_16x16x32_bf16 v[112:115], v[170:173], v[196:199], v[112:115]
	v_mfma_f32_16x16x32_bf16 v[100:103], v[162:165], v[204:207], v[100:103]
	v_mfma_f32_16x16x32_bf16 v[96:99], v[170:173], v[204:207], v[96:99]
	v_mfma_f32_16x16x32_bf16 v[84:87], v[162:165], v[212:215], v[84:87]
	v_mfma_f32_16x16x32_bf16 v[80:83], v[170:173], v[212:215], v[80:83]
	v_mfma_f32_16x16x32_bf16 v[124:127], v[166:169], v[192:195], v[124:127]
	v_mfma_f32_16x16x32_bf16 v[120:123], v[174:177], v[192:195], v[120:123]
	v_mfma_f32_16x16x32_bf16 v[116:119], v[166:169], v[200:203], v[116:119]
	v_mfma_f32_16x16x32_bf16 v[112:115], v[174:177], v[200:203], v[112:115]
	v_mfma_f32_16x16x32_bf16 v[100:103], v[166:169], v[208:211], v[100:103]
	v_mfma_f32_16x16x32_bf16 v[96:99], v[174:177], v[208:211], v[96:99]
	v_mfma_f32_16x16x32_bf16 v[84:87], v[166:169], v[216:219], v[84:87]
	v_mfma_f32_16x16x32_bf16 v[80:83], v[174:177], v[216:219], v[80:83]
	s_barrier
; #define PG8_STAGE(bufoff, gbase, voff) do { _Pragma("unroll") for (int _i = 0; _i < 2; ++_i) \
;         __builtin_amdgcn_global_load_lds((const unsigned*)((const char*)(gbase) + (voff)[_i]), (PG8_LAS unsigned*)(lds + (bufoff) + ldsw + _i * 8192), 16, 0, 0); } while (0)
; #define PG8_LDA(dst, b, h) do { _Pragma("unroll") for (int m = 0; m < 4; ++m) _Pragma("unroll") for (int k = 0; k < 2; ++k) dst[m][k] = *(const PG8_LAS bf16x8*)(lds + PG8_SA(b, h) + aoff + m * 2048 + k * 1024); } while (0)
; #define PG8_LDB(dst, b, h) do { _Pragma("unroll") for (int n = 0; n < 2; ++n) _Pragma("unroll") for (int k = 0; k < 2; ++k) dst[n][k] = *(const PG8_LAS bf16x8*)(lds + PG8_SB(b, h) + boff + n * 2048 + k * 1024); } while (0)
; #define PG8_MMA(ai, bj, At, Bt) do { __builtin_amdgcn_s_setprio(1); _Pragma("unroll") for (int m = 0; m < 4; ++m) _Pragma("unroll") for (int n = 0; n < 2; ++n) _Pragma("unroll") for (int k = 0; k < 2; ++k) \
;         acc[ai][bj][m][n] = __builtin_amdgcn_mfma_f32_16x16x32_bf16(Bt[n][k], At[m][k], acc[ai][bj][m][n], 0, 0, 0); __builtin_amdgcn_s_setprio(0); } while (0)
; #define PG8_WAIT_V(n) asm volatile("s_waitcnt vmcnt(" #n ")" ::: "memory")
; #define PG8_WAIT_L(n) asm volatile("s_waitcnt lgkmcnt(" #n ")" ::: "memory")
; #define PG8_BAR __builtin_amdgcn_s_barrier()
; #define PG8_SCHED __builtin_amdgcn_sched_barrier(0)
; template <class Epi, class Sched, bool STAMP = false>
; __device__ __forceinline__ void gemm_phase(PG8_LAS unsigned char* lds, const Gemm g, const Sched& S, const Epi& E, unsigned long long* stamps) {
;     ...
;             PG8_LDB(B1, 0, 1); PG8_STAGE(PG8_SB(0, 0), b2, voffB);
;             PG8_BAR; PG8_WAIT_L(0); PG8_MMA(0, 1, At, B1); PG8_BAR;
;             PG8_LDA(At, 0, 1); PG8_STAGE(PG8_SA(0, 0), a2, voffA);
;             PG8_BAR; PG8_WAIT_L(0); PG8_MMA(1, 0, At, B0); PG8_BAR; PG8_SCHED;
;             PG8_STAGE(PG8_SB(0, 1), b2 + hstep, voffB);
;             PG8_WAIT_V(6); PG8_BAR; PG8_MMA(1, 1, At, B1); PG8_BAR;
;             PG8_LDB(B0, 1, 0); PG8_SCHED; PG8_LDA(At, 1, 0); PG8_STAGE(PG8_SA(0, 1), a2 + hstep, voffA);
;             PG8_WAIT_L(8); PG8_BAR; PG8_WAIT_L(0); PG8_MMA(0, 0, At, B0); PG8_BAR; PG8_SCHED;
	s_add_i32 s17, 0, 0x14000
	s_add_i32 s14, s16, s53
	s_mov_b32 m0, s14
	ds_read_b128 v[220:223], v249
	ds_read_b128 v[224:227], v249 offset:1024
	ds_read_b128 v[228:231], v249 offset:2048
	ds_read_b128 v[232:235], v249 offset:3072
	global_load_lds_dwordx4 v128, s[56:57]
	s_add_i32 m0, s14, 0x2000
	s_nop 0
	global_load_lds_dwordx4 v152, s[56:57]
	s_barrier
	s_waitcnt lgkmcnt(0)
	v_mfma_f32_16x16x32_bf16 v[108:111], v[220:223], v[178:181], v[108:111]
	v_mfma_f32_16x16x32_bf16 v[104:107], v[228:231], v[178:181], v[104:107]
	v_mfma_f32_16x16x32_bf16 v[92:95], v[220:223], v[196:199], v[92:95]
	v_mfma_f32_16x16x32_bf16 v[88:91], v[228:231], v[196:199], v[88:91]
	v_mfma_f32_16x16x32_bf16 v[76:79], v[220:223], v[204:207], v[76:79]
	v_mfma_f32_16x16x32_bf16 v[72:75], v[228:231], v[204:207], v[72:75]
	v_mfma_f32_16x16x32_bf16 v[68:71], v[220:223], v[212:215], v[68:71]
	v_mfma_f32_16x16x32_bf16 v[64:67], v[228:231], v[212:215], v[64:67]
	v_mfma_f32_16x16x32_bf16 v[108:111], v[224:227], v[192:195], v[108:111]
	v_mfma_f32_16x16x32_bf16 v[104:107], v[232:235], v[192:195], v[104:107]
	v_mfma_f32_16x16x32_bf16 v[92:95], v[224:227], v[200:203], v[92:95]
	v_mfma_f32_16x16x32_bf16 v[88:91], v[232:235], v[200:203], v[88:91]
	v_mfma_f32_16x16x32_bf16 v[76:79], v[224:227], v[208:211], v[76:79]
	v_mfma_f32_16x16x32_bf16 v[72:75], v[232:235], v[208:211], v[72:75]
	v_mfma_f32_16x16x32_bf16 v[68:71], v[224:227], v[216:219], v[68:71]
	v_mfma_f32_16x16x32_bf16 v[64:67], v[232:235], v[216:219], v[64:67]
	s_mov_b32 m0, s3
	s_barrier
	ds_read_b128 v[178:181], v160 offset:16384
	ds_read_b128 v[192:195], v160 offset:17408
	ds_read_b128 v[196:199], v160 offset:18432
	ds_read_b128 v[200:203], v160 offset:19456
	ds_read_b128 v[204:207], v160 offset:20480
	ds_read_b128 v[208:211], v160 offset:21504
	ds_read_b128 v[212:215], v160 offset:22528
	ds_read_b128 v[216:219], v160 offset:23552
	global_load_lds_dwordx4 v148, s[58:59]
	s_mov_b32 m0, s60
	s_nop 0
	global_load_lds_dwordx4 v150, s[58:59]
	s_barrier
	s_waitcnt lgkmcnt(0)
	v_mfma_f32_16x16x32_bf16 v[60:63], v[162:165], v[178:181], v[60:63]
	v_mfma_f32_16x16x32_bf16 v[56:59], v[170:173], v[178:181], v[56:59]
	v_mfma_f32_16x16x32_bf16 v[52:55], v[162:165], v[196:199], v[52:55]
	v_mfma_f32_16x16x32_bf16 v[48:51], v[170:173], v[196:199], v[48:51]
	v_mfma_f32_16x16x32_bf16 v[36:39], v[162:165], v[204:207], v[36:39]
	v_mfma_f32_16x16x32_bf16 v[32:35], v[170:173], v[204:207], v[32:35]
	v_mfma_f32_16x16x32_bf16 v[20:23], v[162:165], v[212:215], v[20:23]
	v_mfma_f32_16x16x32_bf16 v[16:19], v[170:173], v[212:215], v[16:19]
	v_mfma_f32_16x16x32_bf16 v[60:63], v[166:169], v[192:195], v[60:63]
	v_mfma_f32_16x16x32_bf16 v[56:59], v[174:177], v[192:195], v[56:59]
	v_mfma_f32_16x16x32_bf16 v[52:55], v[166:169], v[200:203], v[52:55]
	v_mfma_f32_16x16x32_bf16 v[48:51], v[174:177], v[200:203], v[48:51]
	v_mfma_f32_16x16x32_bf16 v[36:39], v[166:169], v[208:211], v[36:39]
	v_mfma_f32_16x16x32_bf16 v[32:35], v[174:177], v[208:211], v[32:35]
	v_mfma_f32_16x16x32_bf16 v[20:23], v[166:169], v[216:219], v[20:23]
	v_mfma_f32_16x16x32_bf16 v[16:19], v[174:177], v[216:219], v[16:19]
	s_barrier
	s_add_u32 s14, s56, 0x20000
	s_addc_u32 s15, s57, 0
	s_add_i32 s16, s17, s53
	s_mov_b32 m0, s16
	s_nop 0
	global_load_lds_dwordx4 v128, s[14:15]
	s_add_i32 m0, s16, 0x2000
	s_nop 0
	global_load_lds_dwordx4 v152, s[14:15]
	s_waitcnt vmcnt(6)
	s_barrier
	v_mfma_f32_16x16x32_bf16 v[44:47], v[220:223], v[178:181], v[44:47]
	v_mfma_f32_16x16x32_bf16 v[40:43], v[228:231], v[178:181], v[40:43]
	v_mfma_f32_16x16x32_bf16 v[28:31], v[220:223], v[196:199], v[28:31]
	v_mfma_f32_16x16x32_bf16 v[24:27], v[228:231], v[196:199], v[24:27]
	v_mfma_f32_16x16x32_bf16 v[12:15], v[220:223], v[204:207], v[12:15]
	v_mfma_f32_16x16x32_bf16 v[8:11], v[228:231], v[204:207], v[8:11]
	v_mfma_f32_16x16x32_bf16 v[4:7], v[220:223], v[212:215], v[4:7]
	v_mfma_f32_16x16x32_bf16 v[0:3], v[228:231], v[212:215], v[0:3]
	v_mfma_f32_16x16x32_bf16 v[44:47], v[224:227], v[192:195], v[44:47]
	v_mfma_f32_16x16x32_bf16 v[40:43], v[232:235], v[192:195], v[40:43]
	v_mfma_f32_16x16x32_bf16 v[28:31], v[224:227], v[200:203], v[28:31]
	v_mfma_f32_16x16x32_bf16 v[24:27], v[232:235], v[200:203], v[24:27]
	v_mfma_f32_16x16x32_bf16 v[12:15], v[224:227], v[208:211], v[12:15]
	v_mfma_f32_16x16x32_bf16 v[8:11], v[232:235], v[208:211], v[8:11]
	v_mfma_f32_16x16x32_bf16 v[4:7], v[224:227], v[216:219], v[4:7]
	v_mfma_f32_16x16x32_bf16 v[0:3], v[232:235], v[216:219], v[0:3]
	s_add_i32 s16, 0, 0x18000
	s_barrier
	ds_read_b128 v[162:165], v250
	ds_read_b128 v[166:169], v250 offset:1024
	ds_read_b128 v[170:173], v250 offset:2048
	ds_read_b128 v[174:177], v250 offset:3072
	s_add_u32 s14, s58, 0x20000
	s_addc_u32 s15, s59, 0
	s_mov_b32 m0, s61
	ds_read_b128 v[178:181], v160 offset:32768
	ds_read_b128 v[192:195], v160 offset:33792
	ds_read_b128 v[196:199], v160 offset:34816
	ds_read_b128 v[200:203], v160 offset:35840
	ds_read_b128 v[204:207], v160 offset:36864
	ds_read_b128 v[208:211], v160 offset:37888
	ds_read_b128 v[212:215], v160 offset:38912
	ds_read_b128 v[216:219], v160 offset:39936
	global_load_lds_dwordx4 v148, s[14:15]
	s_mov_b32 m0, s62
	s_nop 0
	global_load_lds_dwordx4 v150, s[14:15]
	s_waitcnt lgkmcnt(8)
	s_barrier
; #define PG8_STAGE(bufoff, gbase, voff) do { _Pragma("unroll") for (int _i = 0; _i < 2; ++_i) \
;         __builtin_amdgcn_global_load_lds((const unsigned*)((const char*)(gbase) + (voff)[_i]), (PG8_LAS unsigned*)(lds + (bufoff) + ldsw + _i * 8192), 16, 0, 0); } while (0)
; #define PG8_LDA(dst, b, h) do { _Pragma("unroll") for (int m = 0; m < 4; ++m) _Pragma("unroll") for (int k = 0; k < 2; ++k) dst[m][k] = *(const PG8_LAS bf16x8*)(lds + PG8_SA(b, h) + aoff + m * 2048 + k * 1024); } while (0)
; #define PG8_LDB(dst, b, h) do { _Pragma("unroll") for (int n = 0; n < 2; ++n) _Pragma("unroll") for (int k = 0; k < 2; ++k) dst[n][k] = *(const PG8_LAS bf16x8*)(lds + PG8_SB(b, h) + boff + n * 2048 + k * 1024); } while (0)
; #define PG8_MMA(ai, bj, At, Bt) do { __builtin_amdgcn_s_setprio(1); _Pragma("unroll") for (int m = 0; m < 4; ++m) _Pragma("unroll") for (int n = 0; n < 2; ++n) _Pragma("unroll") for (int k = 0; k < 2; ++k) \
;         acc[ai][bj][m][n] = __builtin_amdgcn_mfma_f32_16x16x32_bf16(Bt[n][k], At[m][k], acc[ai][bj][m][n], 0, 0, 0); __builtin_amdgcn_s_setprio(0); } while (0)
; #define PG8_WAIT_V(n) asm volatile("s_waitcnt vmcnt(" #n ")" ::: "memory")
; #define PG8_WAIT_L(n) asm volatile("s_waitcnt lgkmcnt(" #n ")" ::: "memory")
; #define PG8_BAR __builtin_amdgcn_s_barrier()
; #define PG8_SCHED __builtin_amdgcn_sched_barrier(0)
; template <class Epi, class Sched, bool STAMP = false>
; __device__ __forceinline__ void gemm_phase(PG8_LAS unsigned char* lds, const Gemm g, const Sched& S, const Epi& E, unsigned long long* stamps) {
;     ...
;             PG8_WAIT_L(8); PG8_BAR; PG8_WAIT_L(0); PG8_MMA(0, 0, At, B0); PG8_BAR; PG8_SCHED;
;             PG8_LDB(B1, 1, 1); PG8_STAGE(PG8_SB(1, 0), b3, voffB);
;             PG8_BAR; PG8_WAIT_L(0); PG8_MMA(0, 1, At, B1); PG8_BAR;
;             PG8_LDA(At, 1, 1); PG8_STAGE(PG8_SA(1, 0), a3, voffA);
;             PG8_BAR; PG8_WAIT_L(0); PG8_MMA(1, 0, At, B0); PG8_BAR; PG8_SCHED;
;             PG8_STAGE(PG8_SB(1, 1), b3 + hstep, voffB);
;             PG8_WAIT_V(6); PG8_BAR; PG8_MMA(1, 1, At, B1); PG8_BAR;
	s_waitcnt lgkmcnt(0)
	v_mfma_f32_16x16x32_bf16 v[124:127], v[162:165], v[178:181], v[124:127]
	v_mfma_f32_16x16x32_bf16 v[120:123], v[170:173], v[178:181], v[120:123]
	v_mfma_f32_16x16x32_bf16 v[116:119], v[162:165], v[196:199], v[116:119]
	v_mfma_f32_16x16x32_bf16 v[112:115], v[170:173], v[196:199], v[112:115]
	v_mfma_f32_16x16x32_bf16 v[100:103], v[162:165], v[204:207], v[100:103]
	v_mfma_f32_16x16x32_bf16 v[96:99], v[170:173], v[204:207], v[96:99]
	v_mfma_f32_16x16x32_bf16 v[84:87], v[162:165], v[212:215], v[84:87]
	v_mfma_f32_16x16x32_bf16 v[80:83], v[170:173], v[212:215], v[80:83]
	v_mfma_f32_16x16x32_bf16 v[124:127], v[166:169], v[192:195], v[124:127]
	v_mfma_f32_16x16x32_bf16 v[120:123], v[174:177], v[192:195], v[120:123]
	v_mfma_f32_16x16x32_bf16 v[116:119], v[166:169], v[200:203], v[116:119]
	v_mfma_f32_16x16x32_bf16 v[112:115], v[174:177], v[200:203], v[112:115]
	v_mfma_f32_16x16x32_bf16 v[100:103], v[166:169], v[208:211], v[100:103]
	v_mfma_f32_16x16x32_bf16 v[96:99], v[174:177], v[208:211], v[96:99]
	v_mfma_f32_16x16x32_bf16 v[84:87], v[166:169], v[216:219], v[84:87]
	v_mfma_f32_16x16x32_bf16 v[80:83], v[174:177], v[216:219], v[80:83]
	s_barrier
	s_add_i32 s17, 0, 0x1c000
	s_add_i32 s14, s16, s53
	s_mov_b32 m0, s14
	ds_read_b128 v[220:223], v251
	ds_read_b128 v[224:227], v251 offset:1024
	ds_read_b128 v[228:231], v251 offset:2048
	ds_read_b128 v[232:235], v251 offset:3072
	global_load_lds_dwordx4 v244, s[56:57]
	s_add_i32 m0, s14, 0x2000
	s_nop 0
	global_load_lds_dwordx4 v245, s[56:57]
	s_barrier
	s_waitcnt lgkmcnt(0)
	v_mfma_f32_16x16x32_bf16 v[108:111], v[220:223], v[178:181], v[108:111]
	v_mfma_f32_16x16x32_bf16 v[104:107], v[228:231], v[178:181], v[104:107]
	v_mfma_f32_16x16x32_bf16 v[92:95], v[220:223], v[196:199], v[92:95]
	v_mfma_f32_16x16x32_bf16 v[88:91], v[228:231], v[196:199], v[88:91]
	v_mfma_f32_16x16x32_bf16 v[76:79], v[220:223], v[204:207], v[76:79]
	v_mfma_f32_16x16x32_bf16 v[72:75], v[228:231], v[204:207], v[72:75]
	v_mfma_f32_16x16x32_bf16 v[68:71], v[220:223], v[212:215], v[68:71]
	v_mfma_f32_16x16x32_bf16 v[64:67], v[228:231], v[212:215], v[64:67]
	v_mfma_f32_16x16x32_bf16 v[108:111], v[224:227], v[192:195], v[108:111]
	v_mfma_f32_16x16x32_bf16 v[104:107], v[232:235], v[192:195], v[104:107]
	v_mfma_f32_16x16x32_bf16 v[92:95], v[224:227], v[200:203], v[92:95]
	v_mfma_f32_16x16x32_bf16 v[88:91], v[232:235], v[200:203], v[88:91]
	v_mfma_f32_16x16x32_bf16 v[76:79], v[224:227], v[208:211], v[76:79]
	v_mfma_f32_16x16x32_bf16 v[72:75], v[232:235], v[208:211], v[72:75]
	v_mfma_f32_16x16x32_bf16 v[68:71], v[224:227], v[216:219], v[68:71]
	v_mfma_f32_16x16x32_bf16 v[64:67], v[232:235], v[216:219], v[64:67]
	s_mov_b32 m0, s63
	s_barrier
	ds_read_b128 v[178:181], v160 offset:49152
	ds_read_b128 v[192:195], v160 offset:50176
	ds_read_b128 v[196:199], v160 offset:51200
	ds_read_b128 v[200:203], v160 offset:52224
	ds_read_b128 v[204:207], v160 offset:53248
	ds_read_b128 v[208:211], v160 offset:54272
	ds_read_b128 v[212:215], v160 offset:55296
	ds_read_b128 v[216:219], v160 offset:56320
	global_load_lds_dwordx4 v246, s[58:59]
	s_mov_b32 m0, s64
	s_nop 0
	global_load_lds_dwordx4 v247, s[58:59]
	s_barrier
	s_waitcnt lgkmcnt(0)
	v_mfma_f32_16x16x32_bf16 v[60:63], v[162:165], v[178:181], v[60:63]
	v_mfma_f32_16x16x32_bf16 v[56:59], v[170:173], v[178:181], v[56:59]
	v_mfma_f32_16x16x32_bf16 v[52:55], v[162:165], v[196:199], v[52:55]
	v_mfma_f32_16x16x32_bf16 v[48:51], v[170:173], v[196:199], v[48:51]
	v_mfma_f32_16x16x32_bf16 v[36:39], v[162:165], v[204:207], v[36:39]
	v_mfma_f32_16x16x32_bf16 v[32:35], v[170:173], v[204:207], v[32:35]
	v_mfma_f32_16x16x32_bf16 v[20:23], v[162:165], v[212:215], v[20:23]
	v_mfma_f32_16x16x32_bf16 v[16:19], v[170:173], v[212:215], v[16:19]
	v_mfma_f32_16x16x32_bf16 v[60:63], v[166:169], v[192:195], v[60:63]
	v_mfma_f32_16x16x32_bf16 v[56:59], v[174:177], v[192:195], v[56:59]
	v_mfma_f32_16x16x32_bf16 v[52:55], v[166:169], v[200:203], v[52:55]
	v_mfma_f32_16x16x32_bf16 v[48:51], v[174:177], v[200:203], v[48:51]
	v_mfma_f32_16x16x32_bf16 v[36:39], v[166:169], v[208:211], v[36:39]
	v_mfma_f32_16x16x32_bf16 v[32:35], v[174:177], v[208:211], v[32:35]
	v_mfma_f32_16x16x32_bf16 v[20:23], v[166:169], v[216:219], v[20:23]
	v_mfma_f32_16x16x32_bf16 v[16:19], v[174:177], v[216:219], v[16:19]
	s_barrier
	s_add_u32 s14, s56, 0x20080
	s_addc_u32 s15, s57, 0
	s_add_i32 s16, s17, s53
	s_mov_b32 m0, s16
	s_nop 0
	global_load_lds_dwordx4 v128, s[14:15]
	s_add_i32 m0, s16, 0x2000
	s_nop 0
	global_load_lds_dwordx4 v152, s[14:15]
	s_waitcnt vmcnt(6)
	s_barrier
	v_mfma_f32_16x16x32_bf16 v[44:47], v[220:223], v[178:181], v[44:47]
	v_mfma_f32_16x16x32_bf16 v[40:43], v[228:231], v[178:181], v[40:43]
	v_mfma_f32_16x16x32_bf16 v[28:31], v[220:223], v[196:199], v[28:31]
	v_mfma_f32_16x16x32_bf16 v[24:27], v[228:231], v[196:199], v[24:27]
	v_mfma_f32_16x16x32_bf16 v[12:15], v[220:223], v[204:207], v[12:15]
	v_mfma_f32_16x16x32_bf16 v[8:11], v[228:231], v[204:207], v[8:11]
	v_mfma_f32_16x16x32_bf16 v[4:7], v[220:223], v[212:215], v[4:7]
	v_mfma_f32_16x16x32_bf16 v[0:3], v[228:231], v[212:215], v[0:3]
	v_mfma_f32_16x16x32_bf16 v[44:47], v[224:227], v[192:195], v[44:47]
	v_mfma_f32_16x16x32_bf16 v[40:43], v[232:235], v[192:195], v[40:43]
	v_mfma_f32_16x16x32_bf16 v[28:31], v[224:227], v[200:203], v[28:31]
	v_mfma_f32_16x16x32_bf16 v[24:27], v[232:235], v[200:203], v[24:27]
	v_mfma_f32_16x16x32_bf16 v[12:15], v[224:227], v[208:211], v[12:15]
	v_mfma_f32_16x16x32_bf16 v[8:11], v[232:235], v[208:211], v[8:11]
	v_mfma_f32_16x16x32_bf16 v[4:7], v[224:227], v[216:219], v[4:7]
	v_mfma_f32_16x16x32_bf16 v[0:3], v[232:235], v[216:219], v[0:3]
	s_add_i32 s97, s97, 2
	s_add_u32 s36, s36, 0x100
	s_addc_u32 s37, s37, 0
	s_add_u32 s89, s89, 0x100
	s_addc_u32 s96, s96, 0
	s_cmp_gt_u32 s97, 5
	s_barrier
; __device__ __forceinline__ unsigned cvt_pk_bf16(float lo, float hi) { const f32x2_cv v = {lo, hi}; const bf16x2_cv b = __builtin_convertvector(v, bf16x2_cv); return __builtin_bit_cast(unsigned, b); }
; __device__ __forceinline__ float rstd_of(const float* rowss, int row) { return rsqrtf(rowss[row] * (1.0f / 1024.0f) + 1e-6f); }
;     __device__ __forceinline__ void operator()(const f32x4 (&acc)[2][2][4][2], const pg8::Unit& u, int wr, int wc, int fr, int fq) const {
;         const int row0 = u.pm * 256 + wr * 64 + fr, col0 = u.pn * 256 + wc * 32 + 8 * fq;
; #pragma unroll
;         for (int ai = 0; ai < 2; ++ai)
; #pragma unroll
;             for (int m = 0; m < 4; ++m) {
;                 const int row = row0 + ai * 128 + m * 16;
;                 const float s = (MODE == 2) ? 1.0f : rstd_of(rowss, row);
;                 bf16_t* rowp = O + (size_t)row * ldc + col0;
; #pragma unroll
;                 for (int bj = 0; bj < 2; ++bj) {
;                     f32x4 v0 = acc[ai][bj][m][0] * s, v1 = acc[ai][bj][m][1] * s;
;                     if (MODE == 1) {
; #pragma unroll
;                         for (int j = 0; j < 4; ++j) { const float a = fmaxf(v0[j], 0.f), b = fmaxf(v1[j], 0.f); v0[j] = a * a; v1[j] = b * b; } }
;                     u32x4 w; w.x = cvt_pk_bf16(v0[0], v0[1]); w.y = cvt_pk_bf16(v0[2], v0[3]); w.z = cvt_pk_bf16(v1[0], v1[1]); w.w = cvt_pk_bf16(v1[2], v1[3]);
;                     *(u32x4*)(rowp + bj * 128) = w; } }
;     }
	s_cbranch_scc0 .LBB0_333
	v_lshl_add_u32 v162, s2, 8, v139
	v_lshl_or_b32 v164, s76, 8, v159
	v_ashrrev_i32_e32 v163, 31, v162
	v_ashrrev_i32_e32 v165, 31, v164
	v_lshlrev_b64 v[166:167], 11, v[162:163]
	v_lshl_add_u64 v[166:167], s[30:31], 0, v[166:167]
	v_lshlrev_b64 v[164:165], 1, v[164:165]
	v_lshl_add_u64 v[166:167], v[166:167], 0, v[164:165]
	s_mov_b32 s2, 0x40000
	s_mov_b64 s[14:15], 0x40000
	v_cvt_pk_bf16_f32 v60, v60, v61
	v_cvt_pk_bf16_f32 v61, v62, v63
	v_cvt_pk_bf16_f32 v62, v56, v57
	v_add_co_u32_e32 v56, vcc, s2, v166
	v_cvt_pk_bf16_f32 v68, v68, v69
	v_cvt_pk_bf16_f32 v69, v70, v71
	v_cvt_pk_bf16_f32 v70, v64, v65
	v_lshl_add_u64 v[64:65], v[166:167], 0, s[14:15]
	v_addc_co_u32_e32 v57, vcc, 0, v167, vcc
	v_cvt_pk_bf16_f32 v44, v44, v45
	v_cvt_pk_bf16_f32 v45, v46, v47
	v_cvt_pk_bf16_f32 v46, v40, v41
	v_cvt_pk_bf16_f32 v47, v42, v43
	s_mov_b32 s2, 0x48000
	v_cvt_pk_bf16_f32 v108, v108, v109
	v_cvt_pk_bf16_f32 v109, v110, v111
	v_cvt_pk_bf16_f32 v110, v104, v105
	v_or_b32_e32 v104, 16, v162
	global_store_dwordx4 v[64:65], v[44:47], off offset:256
	s_mov_b64 s[14:15], 0x48000
	v_ashrrev_i32_e32 v105, 31, v104
	v_add_co_u32_e32 v46, vcc, s2, v166
	v_cvt_pk_bf16_f32 v92, v92, v93
	v_cvt_pk_bf16_f32 v93, v94, v95
	v_cvt_pk_bf16_f32 v94, v88, v89
	v_or_b32_e32 v88, 32, v162
	v_lshl_add_u64 v[44:45], v[166:167], 0, s[14:15]
	v_addc_co_u32_e32 v47, vcc, 0, v167, vcc
	v_cvt_pk_bf16_f32 v28, v28, v29
	v_cvt_pk_bf16_f32 v29, v30, v31
	v_cvt_pk_bf16_f32 v30, v24, v25
	v_cvt_pk_bf16_f32 v31, v26, v27
	s_mov_b32 s2, 0x50000
	v_lshlrev_b64 v[104:105], 11, v[104:105]
	v_ashrrev_i32_e32 v89, 31, v88
	v_cvt_pk_bf16_f32 v76, v76, v77
	v_cvt_pk_bf16_f32 v77, v78, v79
	v_cvt_pk_bf16_f32 v78, v72, v73
	v_or_b32_e32 v72, 48, v162
	global_store_dwordx4 v[44:45], v[28:31], off offset:256
	s_mov_b64 s[14:15], 0x50000
	v_cvt_pk_bf16_f32 v111, v106, v107
	v_add_co_u32_e32 v30, vcc, s2, v166
	v_lshl_add_u64 v[104:105], s[30:31], 0, v[104:105]
	v_lshlrev_b64 v[88:89], 11, v[88:89]
	v_ashrrev_i32_e32 v73, 31, v72
	v_lshl_add_u64 v[28:29], v[166:167], 0, s[14:15]
	v_addc_co_u32_e32 v31, vcc, 0, v167, vcc
	v_cvt_pk_bf16_f32 v12, v12, v13
	v_cvt_pk_bf16_f32 v13, v14, v15
	v_cvt_pk_bf16_f32 v14, v8, v9
	v_cvt_pk_bf16_f32 v15, v10, v11
	s_mov_b32 s2, 0x58000
	global_store_dwordx4 v[166:167], v[108:111], off offset:256
	v_cvt_pk_bf16_f32 v95, v90, v91
	v_lshl_add_u64 v[88:89], s[30:31], 0, v[88:89]
	v_lshl_add_u64 v[108:109], v[104:105], 0, v[164:165]
	v_lshlrev_b64 v[72:73], 11, v[72:73]
	global_store_dwordx4 v[28:29], v[12:15], off offset:256
	global_store_dwordx4 v[108:109], v[92:95], off offset:256
	v_cvt_pk_bf16_f32 v79, v74, v75
	v_add_co_u32_e32 v14, vcc, s2, v166
	v_lshl_add_u64 v[92:93], v[88:89], 0, v[164:165]
	v_lshl_add_u64 v[72:73], s[30:31], 0, v[72:73]
	s_mov_b64 s[14:15], 0x58000
	v_addc_co_u32_e32 v15, vcc, 0, v167, vcc
	v_readlane_b32 s88, v242, 39
	v_cvt_pk_bf16_f32 v124, v124, v125
	v_cvt_pk_bf16_f32 v125, v126, v127
	v_cvt_pk_bf16_f32 v126, v120, v121
	v_cvt_pk_bf16_f32 v127, v122, v123
	v_cvt_pk_bf16_f32 v104, v116, v117
	v_cvt_pk_bf16_f32 v105, v118, v119
	v_cvt_pk_bf16_f32 v106, v112, v113
	v_cvt_pk_bf16_f32 v107, v114, v115
	v_cvt_pk_bf16_f32 v88, v100, v101
	v_cvt_pk_bf16_f32 v89, v102, v103
	v_cvt_pk_bf16_f32 v90, v96, v97
	v_cvt_pk_bf16_f32 v91, v98, v99
	global_store_dwordx4 v[92:93], v[76:79], off offset:256
	v_cvt_pk_bf16_f32 v74, v80, v81
	v_cvt_pk_bf16_f32 v75, v82, v83
	v_lshl_add_u64 v[76:77], v[72:73], 0, v[164:165]
	v_cvt_pk_bf16_f32 v72, v84, v85
	v_cvt_pk_bf16_f32 v73, v86, v87
	v_cvt_pk_bf16_f32 v71, v66, v67
	v_cvt_pk_bf16_f32 v63, v58, v59
	v_cvt_pk_bf16_f32 v40, v52, v53
	v_cvt_pk_bf16_f32 v41, v54, v55
	v_cvt_pk_bf16_f32 v42, v48, v49
	v_cvt_pk_bf16_f32 v43, v50, v51
	v_cvt_pk_bf16_f32 v24, v36, v37
	v_cvt_pk_bf16_f32 v25, v38, v39
	v_cvt_pk_bf16_f32 v26, v32, v33
	v_cvt_pk_bf16_f32 v27, v34, v35
	v_lshl_add_u64 v[12:13], v[166:167], 0, s[14:15]
	v_cvt_pk_bf16_f32 v8, v20, v21
	v_cvt_pk_bf16_f32 v9, v22, v23
	v_cvt_pk_bf16_f32 v10, v16, v17
	v_cvt_pk_bf16_f32 v11, v18, v19
	v_cvt_pk_bf16_f32 v4, v4, v5
	v_cvt_pk_bf16_f32 v5, v6, v7
	v_cvt_pk_bf16_f32 v6, v0, v1
	v_cvt_pk_bf16_f32 v7, v2, v3
	s_and_b64 vcc, exec, s[38:39]
	s_mov_b32 s76, s4
	s_mov_b32 s2, s12
	s_mov_b64 s[56:57], s[26:27]
	s_mov_b64 s[36:37], s[24:25]
	s_movk_i32 s77, 0xa0
	s_movk_i32 s58, 0xff60
	v_readlane_b32 s89, v242, 40
	global_store_dwordx4 v[166:167], v[124:127], off
	global_store_dwordx4 v[108:109], v[104:107], off
	global_store_dwordx4 v[92:93], v[88:91], off
	global_store_dwordx4 v[76:77], v[72:75], off
	global_store_dwordx4 v[76:77], v[68:71], off offset:256
	global_store_dwordx4 v[56:57], v[60:63], off
	global_store_dwordx4 v[46:47], v[40:43], off
	global_store_dwordx4 v[30:31], v[24:27], off
	global_store_dwordx4 v[14:15], v[8:11], off
	global_store_dwordx4 v[12:13], v[4:7], off offset:256
	s_cbranch_vccz .LBB0_326
	s_cmpk_gt_u32 s46, 0xff
	s_cbranch_scc1 .LBB0_337
	s_barrier

; #define PG8_STAGE(bufoff, gbase, voff) do { _Pragma("unroll") for (int _i = 0; _i < 2; ++_i) \
;         __builtin_amdgcn_global_load_lds((const unsigned*)((const char*)(gbase) + (voff)[_i]), (PG8_LAS unsigned*)(lds + (bufoff) + ldsw + _i * 8192), 16, 0, 0); } while (0)
; #define PG8_LDA(dst, b, h) do { _Pragma("unroll") for (int m = 0; m < 4; ++m) _Pragma("unroll") for (int k = 0; k < 2; ++k) dst[m][k] = *(const PG8_LAS bf16x8*)(lds + PG8_SA(b, h) + aoff + m * 2048 + k * 1024); } while (0)
; #define PG8_LDB(dst, b, h) do { _Pragma("unroll") for (int n = 0; n < 2; ++n) _Pragma("unroll") for (int k = 0; k < 2; ++k) dst[n][k] = *(const PG8_LAS bf16x8*)(lds + PG8_SB(b, h) + boff + n * 2048 + k * 1024); } while (0)
; #define PG8_WAIT_L(n) asm volatile("s_waitcnt lgkmcnt(" #n ")" ::: "memory")
; #define PG8_BAR __builtin_amdgcn_s_barrier()
; #define PG8_SCHED __builtin_amdgcn_sched_barrier(0)
;     __device__ bool next(int i, pg8::Unit& u) const { if (i != 0 || !valid) return false; u.pm = pm; u.pn = pn; return true; }
; template <class Epi, class Sched, bool STAMP = false>
; __device__ __forceinline__ void gemm_phase(PG8_LAS unsigned char* lds, const Gemm g, const Sched& S, const Epi& E, unsigned long long* stamps) {
;     ...
;         const bool has_next = S.next(ui + 1, nxt);
;         const char* nA = has_next ? (const char*)g.A + (size_t)nxt.pm * tstep : cA; const char* nB = has_next ? (const char*)g.Bt + (size_t)nxt.pn * tstep : cB;
;         for (int t = 0; t < nt; t += 2) {
;             const bool last = (t == nt - 2);
;             const char* a1 = cA + (size_t)(t + 1) * kstep;
;             const char* a2 = last ? nA : cA + (size_t)(t + 2) * kstep; const char* b2 = last ? nB : cB + (size_t)(t + 2) * kstep;
;             const char* a3 = a2 + kstep; const char* b3 = b2 + kstep;
;             if (last && has_next) S.a_ready(nxt);
;             PG8_LDB(B0, 0, 0); PG8_SCHED; PG8_LDA(At, 0, 0); PG8_STAGE(PG8_SA(1, 1), a1 + hstep, voffA);
;             PG8_WAIT_L(8); PG8_BAR; PG8_WAIT_L(0); PG8_MMA(0, 0, At, B0); PG8_BAR; PG8_SCHED;
;     ...
; #pragma unroll
;         for (int a = 0; a < 2; ++a)
; #pragma unroll
;             for (int b = 0; b < 2; ++b)
; #pragma unroll
;                 for (int m = 0; m < 4; ++m)
; #pragma unroll
;                     for (int n = 0; n < 2; ++n) acc[a][b][m][n] = (f32x4){0.f, 0.f, 0.f, 0.f};
;         cur = nxt; cA = nA; cB = nB; ++ui;
.LBB0_352:
	s_ashr_i32 s13, s12, 31
	v_cmp_lt_i64_e32 vcc, s[4:5], v[136:137]
	s_lshl_b64 s[4:5], s[12:13], 19
	s_add_u32 s4, s42, s4
	s_addc_u32 s5, s43, s5
	s_and_b64 s[14:15], vcc, exec
	s_cselect_b32 s13, s5, s57
	s_cselect_b32 s47, s4, s56
	s_ashr_i32 s27, s26, 31
	s_lshl_b64 s[14:15], s[26:27], 19
	s_add_u32 s36, s24, s14
	s_addc_u32 s37, s25, s15
	s_and_b64 s[14:15], vcc, exec
	s_cselect_b32 s27, s37, s59
	s_cselect_b32 s53, s36, s58
	s_add_u32 s56, s56, 0x40080
	s_addc_u32 s57, s57, 0
	s_add_u32 s76, s58, 0x100
	v_mov_b32_e32 v0, 0
	s_addc_u32 s77, s59, 0
	s_mov_b32 vcc_lo, -2
	v_mov_b32_e32 v1, v0
	v_mov_b32_e32 v2, v0
	v_mov_b32_e32 v3, v0
	v_mov_b32_e32 v4, v0
	v_mov_b32_e32 v5, v0
	v_mov_b32_e32 v6, v0
	v_mov_b32_e32 v7, v0
	v_mov_b32_e32 v16, v0
	v_mov_b32_e32 v17, v0
	v_mov_b32_e32 v18, v0
	v_mov_b32_e32 v19, v0
	v_mov_b32_e32 v20, v0
	v_mov_b32_e32 v21, v0
	v_mov_b32_e32 v22, v0
	v_mov_b32_e32 v23, v0
	v_mov_b32_e32 v32, v0
	v_mov_b32_e32 v33, v0
	v_mov_b32_e32 v34, v0
	v_mov_b32_e32 v35, v0
	v_mov_b32_e32 v36, v0
	v_mov_b32_e32 v37, v0
	v_mov_b32_e32 v38, v0
	v_mov_b32_e32 v39, v0
	v_mov_b32_e32 v48, v0
	v_mov_b32_e32 v49, v0
	v_mov_b32_e32 v50, v0
	v_mov_b32_e32 v51, v0
	v_mov_b32_e32 v52, v0
	v_mov_b32_e32 v53, v0
	v_mov_b32_e32 v54, v0
	v_mov_b32_e32 v55, v0
	v_mov_b32_e32 v8, v0
	v_mov_b32_e32 v9, v0
	v_mov_b32_e32 v10, v0
	v_mov_b32_e32 v11, v0
	v_mov_b32_e32 v12, v0
	v_mov_b32_e32 v13, v0
	v_mov_b32_e32 v14, v0
	v_mov_b32_e32 v15, v0
	v_mov_b32_e32 v24, v0
	v_mov_b32_e32 v25, v0
	v_mov_b32_e32 v26, v0
	v_mov_b32_e32 v27, v0
	v_mov_b32_e32 v28, v0
	v_mov_b32_e32 v29, v0
	v_mov_b32_e32 v30, v0
	v_mov_b32_e32 v31, v0
	v_mov_b32_e32 v40, v0
	v_mov_b32_e32 v41, v0
	v_mov_b32_e32 v42, v0
	v_mov_b32_e32 v43, v0
	v_mov_b32_e32 v44, v0
	v_mov_b32_e32 v45, v0
	v_mov_b32_e32 v46, v0
	v_mov_b32_e32 v47, v0
	v_mov_b32_e32 v56, v0
	v_mov_b32_e32 v57, v0
	v_mov_b32_e32 v58, v0
	v_mov_b32_e32 v59, v0
	v_mov_b32_e32 v60, v0
	v_mov_b32_e32 v61, v0
	v_mov_b32_e32 v62, v0
	v_mov_b32_e32 v63, v0
	v_mov_b32_e32 v64, v0
	v_mov_b32_e32 v65, v0
	v_mov_b32_e32 v66, v0
	v_mov_b32_e32 v67, v0
	v_mov_b32_e32 v68, v0
	v_mov_b32_e32 v69, v0
	v_mov_b32_e32 v70, v0
	v_mov_b32_e32 v71, v0
	v_mov_b32_e32 v80, v0
	v_mov_b32_e32 v81, v0
	v_mov_b32_e32 v82, v0
	v_mov_b32_e32 v83, v0
	v_mov_b32_e32 v84, v0
	v_mov_b32_e32 v85, v0
	v_mov_b32_e32 v86, v0
	v_mov_b32_e32 v87, v0
	v_mov_b32_e32 v96, v0
	v_mov_b32_e32 v97, v0
	v_mov_b32_e32 v98, v0
	v_mov_b32_e32 v99, v0
	v_mov_b32_e32 v100, v0
	v_mov_b32_e32 v101, v0
	v_mov_b32_e32 v102, v0
	v_mov_b32_e32 v103, v0
	v_mov_b32_e32 v112, v0
	v_mov_b32_e32 v113, v0
	v_mov_b32_e32 v114, v0
	v_mov_b32_e32 v115, v0
	v_mov_b32_e32 v116, v0
	v_mov_b32_e32 v117, v0
	v_mov_b32_e32 v118, v0
	v_mov_b32_e32 v119, v0
	v_mov_b32_e32 v72, v0
	v_mov_b32_e32 v73, v0
	v_mov_b32_e32 v74, v0
	v_mov_b32_e32 v75, v0
	v_mov_b32_e32 v76, v0
	v_mov_b32_e32 v77, v0
	v_mov_b32_e32 v78, v0
	v_mov_b32_e32 v79, v0
	v_mov_b32_e32 v88, v0
	v_mov_b32_e32 v89, v0
	v_mov_b32_e32 v90, v0
	v_mov_b32_e32 v91, v0
	v_mov_b32_e32 v92, v0
	v_mov_b32_e32 v93, v0
	v_mov_b32_e32 v94, v0
	v_mov_b32_e32 v95, v0
	v_mov_b32_e32 v104, v0
	v_mov_b32_e32 v105, v0
	v_mov_b32_e32 v106, v0
	v_mov_b32_e32 v107, v0
	v_mov_b32_e32 v108, v0
	v_mov_b32_e32 v109, v0
	v_mov_b32_e32 v110, v0
	v_mov_b32_e32 v111, v0
	v_mov_b32_e32 v120, v0
	v_mov_b32_e32 v121, v0
	v_mov_b32_e32 v122, v0
	v_mov_b32_e32 v123, v0
	v_mov_b32_e32 v124, v0
	v_mov_b32_e32 v125, v0
	v_mov_b32_e32 v126, v0
	v_mov_b32_e32 v127, v0
	v_add_u32_e32 v244, 0x80, v128
	v_add_u32_e32 v245, 0x80, v152
	v_add_u32_e32 v246, 0x80, v148
	v_add_u32_e32 v247, 0x80, v150
	v_add_u32_e32 v248, 0x10000, v167
	v_add_u32_e32 v249, 0x14000, v167
	v_add_u32_e32 v250, 0x18000, v167
	v_add_u32_e32 v251, 0x1c000, v167
.LBB0_353:
	s_add_u32 s14, s56, 0xfffc0080
	s_addc_u32 s15, s57, -1
	s_add_i32 s16, 0, 0x10000
	ds_read_b128 v[158:161], v248
	ds_read_b128 v[162:165], v248 offset:1024
	ds_read_b128 v[172:175], v248 offset:2048
	ds_read_b128 v[176:179], v248 offset:3072
	s_cmp_eq_u32 vcc_lo, 12
	s_cselect_b32 s61, s13, s15
	s_cselect_b32 s60, s47, s14
	s_cselect_b32 s59, s27, s77
	s_cselect_b32 s58, s53, s76
	s_add_i32 m0, s89, 0xc000
	ds_read_b128 v[180:183], v171
	ds_read_b128 v[192:195], v171 offset:1024
	ds_read_b128 v[196:199], v171 offset:2048
	ds_read_b128 v[200:203], v171 offset:3072
	ds_read_b128 v[204:207], v171 offset:4096
	ds_read_b128 v[208:211], v171 offset:5120
	ds_read_b128 v[212:215], v171 offset:6144
	ds_read_b128 v[216:219], v171 offset:7168
	global_load_lds_dwordx4 v154, s[56:57]
	s_add_i32 m0, s89, 0xe000
	s_nop 0
	global_load_lds_dwordx4 v156, s[56:57]
	s_waitcnt lgkmcnt(8)
	s_barrier
	s_waitcnt lgkmcnt(0)
	v_mfma_f32_16x16x32_bf16 v[124:127], v[158:161], v[180:183], v[124:127]
	v_mfma_f32_16x16x32_bf16 v[120:123], v[172:175], v[180:183], v[120:123]
	v_mfma_f32_16x16x32_bf16 v[108:111], v[158:161], v[196:199], v[108:111]
	v_mfma_f32_16x16x32_bf16 v[104:107], v[172:175], v[196:199], v[104:107]
	v_mfma_f32_16x16x32_bf16 v[92:95], v[158:161], v[204:207], v[92:95]
	v_mfma_f32_16x16x32_bf16 v[88:91], v[172:175], v[204:207], v[88:91]
	v_mfma_f32_16x16x32_bf16 v[76:79], v[158:161], v[212:215], v[76:79]
	v_mfma_f32_16x16x32_bf16 v[72:75], v[172:175], v[212:215], v[72:75]
	v_mfma_f32_16x16x32_bf16 v[124:127], v[162:165], v[192:195], v[124:127]
	v_mfma_f32_16x16x32_bf16 v[120:123], v[176:179], v[192:195], v[120:123]
	v_mfma_f32_16x16x32_bf16 v[108:111], v[162:165], v[200:203], v[108:111]
	v_mfma_f32_16x16x32_bf16 v[104:107], v[176:179], v[200:203], v[104:107]
	v_mfma_f32_16x16x32_bf16 v[92:95], v[162:165], v[208:211], v[92:95]
	v_mfma_f32_16x16x32_bf16 v[88:91], v[176:179], v[208:211], v[88:91]
	v_mfma_f32_16x16x32_bf16 v[76:79], v[162:165], v[216:219], v[76:79]
	v_mfma_f32_16x16x32_bf16 v[72:75], v[176:179], v[216:219], v[72:75]
	s_barrier
; #define PG8_STAGE(bufoff, gbase, voff) do { _Pragma("unroll") for (int _i = 0; _i < 2; ++_i) \
;         __builtin_amdgcn_global_load_lds((const unsigned*)((const char*)(gbase) + (voff)[_i]), (PG8_LAS unsigned*)(lds + (bufoff) + ldsw + _i * 8192), 16, 0, 0); } while (0)
; #define PG8_LDA(dst, b, h) do { _Pragma("unroll") for (int m = 0; m < 4; ++m) _Pragma("unroll") for (int k = 0; k < 2; ++k) dst[m][k] = *(const PG8_LAS bf16x8*)(lds + PG8_SA(b, h) + aoff + m * 2048 + k * 1024); } while (0)
; #define PG8_LDB(dst, b, h) do { _Pragma("unroll") for (int n = 0; n < 2; ++n) _Pragma("unroll") for (int k = 0; k < 2; ++k) dst[n][k] = *(const PG8_LAS bf16x8*)(lds + PG8_SB(b, h) + boff + n * 2048 + k * 1024); } while (0)
; #define PG8_MMA(ai, bj, At, Bt) do { __builtin_amdgcn_s_setprio(1); _Pragma("unroll") for (int m = 0; m < 4; ++m) _Pragma("unroll") for (int n = 0; n < 2; ++n) _Pragma("unroll") for (int k = 0; k < 2; ++k) \
;         acc[ai][bj][m][n] = __builtin_amdgcn_mfma_f32_16x16x32_bf16(Bt[n][k], At[m][k], acc[ai][bj][m][n], 0, 0, 0); __builtin_amdgcn_s_setprio(0); } while (0)
; #define PG8_WAIT_V(n) asm volatile("s_waitcnt vmcnt(" #n ")" ::: "memory")
; #define PG8_WAIT_L(n) asm volatile("s_waitcnt lgkmcnt(" #n ")" ::: "memory")
; #define PG8_BAR __builtin_amdgcn_s_barrier()
; #define PG8_SCHED __builtin_amdgcn_sched_barrier(0)
; template <class Epi, class Sched, bool STAMP = false>
; __device__ __forceinline__ void gemm_phase(PG8_LAS unsigned char* lds, const Gemm g, const Sched& S, const Epi& E, unsigned long long* stamps) {
;     ...
;             PG8_LDB(B1, 0, 1); PG8_STAGE(PG8_SB(0, 0), b2, voffB);
;             PG8_BAR; PG8_WAIT_L(0); PG8_MMA(0, 1, At, B1); PG8_BAR;
;             PG8_LDA(At, 0, 1); PG8_STAGE(PG8_SA(0, 0), a2, voffA);
;             PG8_BAR; PG8_WAIT_L(0); PG8_MMA(1, 0, At, B0); PG8_BAR; PG8_SCHED;
;             PG8_STAGE(PG8_SB(0, 1), b2 + hstep, voffB);
;             PG8_WAIT_V(6); PG8_BAR; PG8_MMA(1, 1, At, B1); PG8_BAR;
;             PG8_LDB(B0, 1, 0); PG8_SCHED; PG8_LDA(At, 1, 0); PG8_STAGE(PG8_SA(0, 1), a2 + hstep, voffA);
;             PG8_WAIT_L(8); PG8_BAR; PG8_WAIT_L(0); PG8_MMA(0, 0, At, B0); PG8_BAR; PG8_SCHED;
	s_add_i32 s17, 0, 0x14000
	s_add_i32 s14, s16, s88
	s_mov_b32 m0, s14
	ds_read_b128 v[220:223], v249
	ds_read_b128 v[224:227], v249 offset:1024
	ds_read_b128 v[228:231], v249 offset:2048
	ds_read_b128 v[232:235], v249 offset:3072
	global_load_lds_dwordx4 v128, s[58:59]
	s_add_i32 m0, s14, 0x2000
	s_nop 0
	global_load_lds_dwordx4 v152, s[58:59]
	s_barrier
	s_waitcnt lgkmcnt(0)
	v_mfma_f32_16x16x32_bf16 v[116:119], v[220:223], v[180:183], v[116:119]
	v_mfma_f32_16x16x32_bf16 v[112:115], v[228:231], v[180:183], v[112:115]
	v_mfma_f32_16x16x32_bf16 v[100:103], v[220:223], v[196:199], v[100:103]
	v_mfma_f32_16x16x32_bf16 v[96:99], v[228:231], v[196:199], v[96:99]
	v_mfma_f32_16x16x32_bf16 v[84:87], v[220:223], v[204:207], v[84:87]
	v_mfma_f32_16x16x32_bf16 v[80:83], v[228:231], v[204:207], v[80:83]
	v_mfma_f32_16x16x32_bf16 v[68:71], v[220:223], v[212:215], v[68:71]
	v_mfma_f32_16x16x32_bf16 v[64:67], v[228:231], v[212:215], v[64:67]
	v_mfma_f32_16x16x32_bf16 v[116:119], v[224:227], v[192:195], v[116:119]
	v_mfma_f32_16x16x32_bf16 v[112:115], v[232:235], v[192:195], v[112:115]
	v_mfma_f32_16x16x32_bf16 v[100:103], v[224:227], v[200:203], v[100:103]
	v_mfma_f32_16x16x32_bf16 v[96:99], v[232:235], v[200:203], v[96:99]
	v_mfma_f32_16x16x32_bf16 v[84:87], v[224:227], v[208:211], v[84:87]
	v_mfma_f32_16x16x32_bf16 v[80:83], v[232:235], v[208:211], v[80:83]
	v_mfma_f32_16x16x32_bf16 v[68:71], v[224:227], v[216:219], v[68:71]
	v_mfma_f32_16x16x32_bf16 v[64:67], v[232:235], v[216:219], v[64:67]
	s_mov_b32 m0, s89
	s_barrier
	ds_read_b128 v[180:183], v171 offset:16384
	ds_read_b128 v[192:195], v171 offset:17408
	ds_read_b128 v[196:199], v171 offset:18432
	ds_read_b128 v[200:203], v171 offset:19456
	ds_read_b128 v[204:207], v171 offset:20480
	ds_read_b128 v[208:211], v171 offset:21504
	ds_read_b128 v[212:215], v171 offset:22528
	ds_read_b128 v[216:219], v171 offset:23552
	global_load_lds_dwordx4 v148, s[60:61]
	s_mov_b32 m0, s96
	s_nop 0
	global_load_lds_dwordx4 v150, s[60:61]
	s_barrier
	s_waitcnt lgkmcnt(0)
	v_mfma_f32_16x16x32_bf16 v[60:63], v[158:161], v[180:183], v[60:63]
	v_mfma_f32_16x16x32_bf16 v[56:59], v[172:175], v[180:183], v[56:59]
	v_mfma_f32_16x16x32_bf16 v[44:47], v[158:161], v[196:199], v[44:47]
	v_mfma_f32_16x16x32_bf16 v[40:43], v[172:175], v[196:199], v[40:43]
	v_mfma_f32_16x16x32_bf16 v[28:31], v[158:161], v[204:207], v[28:31]
	v_mfma_f32_16x16x32_bf16 v[24:27], v[172:175], v[204:207], v[24:27]
	v_mfma_f32_16x16x32_bf16 v[12:15], v[158:161], v[212:215], v[12:15]
	v_mfma_f32_16x16x32_bf16 v[8:11], v[172:175], v[212:215], v[8:11]
	v_mfma_f32_16x16x32_bf16 v[60:63], v[162:165], v[192:195], v[60:63]
	v_mfma_f32_16x16x32_bf16 v[56:59], v[176:179], v[192:195], v[56:59]
	v_mfma_f32_16x16x32_bf16 v[44:47], v[162:165], v[200:203], v[44:47]
	v_mfma_f32_16x16x32_bf16 v[40:43], v[176:179], v[200:203], v[40:43]
	v_mfma_f32_16x16x32_bf16 v[28:31], v[162:165], v[208:211], v[28:31]
	v_mfma_f32_16x16x32_bf16 v[24:27], v[176:179], v[208:211], v[24:27]
	v_mfma_f32_16x16x32_bf16 v[12:15], v[162:165], v[216:219], v[12:15]
	v_mfma_f32_16x16x32_bf16 v[8:11], v[176:179], v[216:219], v[8:11]
	s_barrier
	s_add_u32 s14, s58, 0x40000
	s_addc_u32 s15, s59, 0
	s_add_i32 s16, s17, s88
	s_mov_b32 m0, s16
	s_nop 0
	global_load_lds_dwordx4 v128, s[14:15]
	s_add_i32 m0, s16, 0x2000
	s_nop 0
	global_load_lds_dwordx4 v152, s[14:15]
	s_waitcnt vmcnt(6)
	s_barrier
	v_mfma_f32_16x16x32_bf16 v[52:55], v[220:223], v[180:183], v[52:55]
	v_mfma_f32_16x16x32_bf16 v[48:51], v[228:231], v[180:183], v[48:51]
	v_mfma_f32_16x16x32_bf16 v[36:39], v[220:223], v[196:199], v[36:39]
	v_mfma_f32_16x16x32_bf16 v[32:35], v[228:231], v[196:199], v[32:35]
	v_mfma_f32_16x16x32_bf16 v[20:23], v[220:223], v[204:207], v[20:23]
	v_mfma_f32_16x16x32_bf16 v[16:19], v[228:231], v[204:207], v[16:19]
	v_mfma_f32_16x16x32_bf16 v[4:7], v[220:223], v[212:215], v[4:7]
	v_mfma_f32_16x16x32_bf16 v[0:3], v[228:231], v[212:215], v[0:3]
	v_mfma_f32_16x16x32_bf16 v[52:55], v[224:227], v[192:195], v[52:55]
	v_mfma_f32_16x16x32_bf16 v[48:51], v[232:235], v[192:195], v[48:51]
	v_mfma_f32_16x16x32_bf16 v[36:39], v[224:227], v[200:203], v[36:39]
	v_mfma_f32_16x16x32_bf16 v[32:35], v[232:235], v[200:203], v[32:35]
	v_mfma_f32_16x16x32_bf16 v[20:23], v[224:227], v[208:211], v[20:23]
	v_mfma_f32_16x16x32_bf16 v[16:19], v[232:235], v[208:211], v[16:19]
	v_mfma_f32_16x16x32_bf16 v[4:7], v[224:227], v[216:219], v[4:7]
	v_mfma_f32_16x16x32_bf16 v[0:3], v[232:235], v[216:219], v[0:3]
	s_add_i32 s16, 0, 0x18000
	s_barrier
	ds_read_b128 v[158:161], v250
	ds_read_b128 v[162:165], v250 offset:1024
	ds_read_b128 v[172:175], v250 offset:2048
	ds_read_b128 v[176:179], v250 offset:3072
	s_add_u32 s14, s60, 0x40000
	s_addc_u32 s15, s61, 0
	s_mov_b32 m0, s97
	ds_read_b128 v[180:183], v171 offset:32768
	ds_read_b128 v[192:195], v171 offset:33792
	ds_read_b128 v[196:199], v171 offset:34816
	ds_read_b128 v[200:203], v171 offset:35840
	ds_read_b128 v[204:207], v171 offset:36864
	ds_read_b128 v[208:211], v171 offset:37888
	ds_read_b128 v[212:215], v171 offset:38912
	ds_read_b128 v[216:219], v171 offset:39936
	global_load_lds_dwordx4 v148, s[14:15]
	s_mov_b32 m0, s64
	s_nop 0
	global_load_lds_dwordx4 v150, s[14:15]
	s_waitcnt lgkmcnt(8)
	s_barrier
; #define PG8_STAGE(bufoff, gbase, voff) do { _Pragma("unroll") for (int _i = 0; _i < 2; ++_i) \
;         __builtin_amdgcn_global_load_lds((const unsigned*)((const char*)(gbase) + (voff)[_i]), (PG8_LAS unsigned*)(lds + (bufoff) + ldsw + _i * 8192), 16, 0, 0); } while (0)
; #define PG8_LDA(dst, b, h) do { _Pragma("unroll") for (int m = 0; m < 4; ++m) _Pragma("unroll") for (int k = 0; k < 2; ++k) dst[m][k] = *(const PG8_LAS bf16x8*)(lds + PG8_SA(b, h) + aoff + m * 2048 + k * 1024); } while (0)
; #define PG8_LDB(dst, b, h) do { _Pragma("unroll") for (int n = 0; n < 2; ++n) _Pragma("unroll") for (int k = 0; k < 2; ++k) dst[n][k] = *(const PG8_LAS bf16x8*)(lds + PG8_SB(b, h) + boff + n * 2048 + k * 1024); } while (0)
; #define PG8_MMA(ai, bj, At, Bt) do { __builtin_amdgcn_s_setprio(1); _Pragma("unroll") for (int m = 0; m < 4; ++m) _Pragma("unroll") for (int n = 0; n < 2; ++n) _Pragma("unroll") for (int k = 0; k < 2; ++k) \
;         acc[ai][bj][m][n] = __builtin_amdgcn_mfma_f32_16x16x32_bf16(Bt[n][k], At[m][k], acc[ai][bj][m][n], 0, 0, 0); __builtin_amdgcn_s_setprio(0); } while (0)
; #define PG8_WAIT_V(n) asm volatile("s_waitcnt vmcnt(" #n ")" ::: "memory")
; #define PG8_WAIT_L(n) asm volatile("s_waitcnt lgkmcnt(" #n ")" ::: "memory")
; #define PG8_BAR __builtin_amdgcn_s_barrier()
; #define PG8_SCHED __builtin_amdgcn_sched_barrier(0)
; template <class Epi, class Sched, bool STAMP = false>
; __device__ __forceinline__ void gemm_phase(PG8_LAS unsigned char* lds, const Gemm g, const Sched& S, const Epi& E, unsigned long long* stamps) {
;     ...
;             PG8_WAIT_L(8); PG8_BAR; PG8_WAIT_L(0); PG8_MMA(0, 0, At, B0); PG8_BAR; PG8_SCHED;
;             PG8_LDB(B1, 1, 1); PG8_STAGE(PG8_SB(1, 0), b3, voffB);
;             PG8_BAR; PG8_WAIT_L(0); PG8_MMA(0, 1, At, B1); PG8_BAR;
;             PG8_LDA(At, 1, 1); PG8_STAGE(PG8_SA(1, 0), a3, voffA);
;             PG8_BAR; PG8_WAIT_L(0); PG8_MMA(1, 0, At, B0); PG8_BAR; PG8_SCHED;
;             PG8_STAGE(PG8_SB(1, 1), b3 + hstep, voffB);
;             PG8_WAIT_V(6); PG8_BAR; PG8_MMA(1, 1, At, B1); PG8_BAR;
	s_waitcnt lgkmcnt(0)
	v_mfma_f32_16x16x32_bf16 v[124:127], v[158:161], v[180:183], v[124:127]
	v_mfma_f32_16x16x32_bf16 v[120:123], v[172:175], v[180:183], v[120:123]
	v_mfma_f32_16x16x32_bf16 v[108:111], v[158:161], v[196:199], v[108:111]
	v_mfma_f32_16x16x32_bf16 v[104:107], v[172:175], v[196:199], v[104:107]
	v_mfma_f32_16x16x32_bf16 v[92:95], v[158:161], v[204:207], v[92:95]
	v_mfma_f32_16x16x32_bf16 v[88:91], v[172:175], v[204:207], v[88:91]
	v_mfma_f32_16x16x32_bf16 v[76:79], v[158:161], v[212:215], v[76:79]
	v_mfma_f32_16x16x32_bf16 v[72:75], v[172:175], v[212:215], v[72:75]
	v_mfma_f32_16x16x32_bf16 v[124:127], v[162:165], v[192:195], v[124:127]
	v_mfma_f32_16x16x32_bf16 v[120:123], v[176:179], v[192:195], v[120:123]
	v_mfma_f32_16x16x32_bf16 v[108:111], v[162:165], v[200:203], v[108:111]
	v_mfma_f32_16x16x32_bf16 v[104:107], v[176:179], v[200:203], v[104:107]
	v_mfma_f32_16x16x32_bf16 v[92:95], v[162:165], v[208:211], v[92:95]
	v_mfma_f32_16x16x32_bf16 v[88:91], v[176:179], v[208:211], v[88:91]
	v_mfma_f32_16x16x32_bf16 v[76:79], v[162:165], v[216:219], v[76:79]
	v_mfma_f32_16x16x32_bf16 v[72:75], v[176:179], v[216:219], v[72:75]
	s_barrier
	s_add_i32 s17, 0, 0x1c000
	s_add_i32 s14, s16, s88
	s_mov_b32 m0, s14
	ds_read_b128 v[220:223], v251
	ds_read_b128 v[224:227], v251 offset:1024
	ds_read_b128 v[228:231], v251 offset:2048
	ds_read_b128 v[232:235], v251 offset:3072
	global_load_lds_dwordx4 v244, s[58:59]
	s_add_i32 m0, s14, 0x2000
	s_nop 0
	global_load_lds_dwordx4 v245, s[58:59]
	s_barrier
	s_waitcnt lgkmcnt(0)
	v_mfma_f32_16x16x32_bf16 v[116:119], v[220:223], v[180:183], v[116:119]
	v_mfma_f32_16x16x32_bf16 v[112:115], v[228:231], v[180:183], v[112:115]
	v_mfma_f32_16x16x32_bf16 v[100:103], v[220:223], v[196:199], v[100:103]
	v_mfma_f32_16x16x32_bf16 v[96:99], v[228:231], v[196:199], v[96:99]
	v_mfma_f32_16x16x32_bf16 v[84:87], v[220:223], v[204:207], v[84:87]
	v_mfma_f32_16x16x32_bf16 v[80:83], v[228:231], v[204:207], v[80:83]
	v_mfma_f32_16x16x32_bf16 v[68:71], v[220:223], v[212:215], v[68:71]
	v_mfma_f32_16x16x32_bf16 v[64:67], v[228:231], v[212:215], v[64:67]
	v_mfma_f32_16x16x32_bf16 v[116:119], v[224:227], v[192:195], v[116:119]
	v_mfma_f32_16x16x32_bf16 v[112:115], v[232:235], v[192:195], v[112:115]
	v_mfma_f32_16x16x32_bf16 v[100:103], v[224:227], v[200:203], v[100:103]
	v_mfma_f32_16x16x32_bf16 v[96:99], v[232:235], v[200:203], v[96:99]
	v_mfma_f32_16x16x32_bf16 v[84:87], v[224:227], v[208:211], v[84:87]
	v_mfma_f32_16x16x32_bf16 v[80:83], v[232:235], v[208:211], v[80:83]
	v_mfma_f32_16x16x32_bf16 v[68:71], v[224:227], v[216:219], v[68:71]
	v_mfma_f32_16x16x32_bf16 v[64:67], v[232:235], v[216:219], v[64:67]
	s_mov_b32 m0, s62
	s_barrier
	ds_read_b128 v[180:183], v171 offset:49152
	ds_read_b128 v[192:195], v171 offset:50176
	ds_read_b128 v[196:199], v171 offset:51200
	ds_read_b128 v[200:203], v171 offset:52224
	ds_read_b128 v[204:207], v171 offset:53248
	ds_read_b128 v[208:211], v171 offset:54272
	ds_read_b128 v[212:215], v171 offset:55296
	ds_read_b128 v[216:219], v171 offset:56320
	global_load_lds_dwordx4 v246, s[60:61]
	s_mov_b32 m0, s63
	s_nop 0
	global_load_lds_dwordx4 v247, s[60:61]
	s_barrier
	s_waitcnt lgkmcnt(0)
	v_mfma_f32_16x16x32_bf16 v[60:63], v[158:161], v[180:183], v[60:63]
	v_mfma_f32_16x16x32_bf16 v[56:59], v[172:175], v[180:183], v[56:59]
	v_mfma_f32_16x16x32_bf16 v[44:47], v[158:161], v[196:199], v[44:47]
	v_mfma_f32_16x16x32_bf16 v[40:43], v[172:175], v[196:199], v[40:43]
	v_mfma_f32_16x16x32_bf16 v[28:31], v[158:161], v[204:207], v[28:31]
	v_mfma_f32_16x16x32_bf16 v[24:27], v[172:175], v[204:207], v[24:27]
	v_mfma_f32_16x16x32_bf16 v[12:15], v[158:161], v[212:215], v[12:15]
	v_mfma_f32_16x16x32_bf16 v[8:11], v[172:175], v[212:215], v[8:11]
	v_mfma_f32_16x16x32_bf16 v[60:63], v[162:165], v[192:195], v[60:63]
	v_mfma_f32_16x16x32_bf16 v[56:59], v[176:179], v[192:195], v[56:59]
	v_mfma_f32_16x16x32_bf16 v[44:47], v[162:165], v[200:203], v[44:47]
	v_mfma_f32_16x16x32_bf16 v[40:43], v[176:179], v[200:203], v[40:43]
	v_mfma_f32_16x16x32_bf16 v[28:31], v[162:165], v[208:211], v[28:31]
	v_mfma_f32_16x16x32_bf16 v[24:27], v[176:179], v[208:211], v[24:27]
	v_mfma_f32_16x16x32_bf16 v[12:15], v[162:165], v[216:219], v[12:15]
	v_mfma_f32_16x16x32_bf16 v[8:11], v[176:179], v[216:219], v[8:11]
	s_barrier
	s_add_u32 s14, s58, 0x40080
	s_addc_u32 s15, s59, 0
	s_add_i32 s16, s17, s88
	s_mov_b32 m0, s16
	s_nop 0
	global_load_lds_dwordx4 v128, s[14:15]
	s_add_i32 m0, s16, 0x2000
	s_nop 0
	global_load_lds_dwordx4 v152, s[14:15]
	s_waitcnt vmcnt(6)
	s_barrier
	v_mfma_f32_16x16x32_bf16 v[52:55], v[220:223], v[180:183], v[52:55]
	v_mfma_f32_16x16x32_bf16 v[48:51], v[228:231], v[180:183], v[48:51]
	v_mfma_f32_16x16x32_bf16 v[36:39], v[220:223], v[196:199], v[36:39]
	v_mfma_f32_16x16x32_bf16 v[32:35], v[228:231], v[196:199], v[32:35]
	v_mfma_f32_16x16x32_bf16 v[20:23], v[220:223], v[204:207], v[20:23]
	v_mfma_f32_16x16x32_bf16 v[16:19], v[228:231], v[204:207], v[16:19]
	v_mfma_f32_16x16x32_bf16 v[4:7], v[220:223], v[212:215], v[4:7]
	v_mfma_f32_16x16x32_bf16 v[0:3], v[228:231], v[212:215], v[0:3]
	v_mfma_f32_16x16x32_bf16 v[52:55], v[224:227], v[192:195], v[52:55]
	v_mfma_f32_16x16x32_bf16 v[48:51], v[232:235], v[192:195], v[48:51]
	v_mfma_f32_16x16x32_bf16 v[36:39], v[224:227], v[200:203], v[36:39]
	v_mfma_f32_16x16x32_bf16 v[32:35], v[232:235], v[200:203], v[32:35]
	v_mfma_f32_16x16x32_bf16 v[20:23], v[224:227], v[208:211], v[20:23]
	v_mfma_f32_16x16x32_bf16 v[16:19], v[232:235], v[208:211], v[16:19]
	v_mfma_f32_16x16x32_bf16 v[4:7], v[224:227], v[216:219], v[4:7]
	v_mfma_f32_16x16x32_bf16 v[0:3], v[232:235], v[216:219], v[0:3]
	s_add_i32 vcc_lo, vcc_lo, 2
	s_add_u32 s56, s56, 0x100
	s_addc_u32 s57, s57, 0
	s_add_u32 s76, s76, 0x100
	s_addc_u32 s77, s77, 0
	s_cmp_gt_u32 vcc_lo, 13
	s_barrier
; __device__ __forceinline__ unsigned cvt_pk_bf16(float lo, float hi) { const f32x2_cv v = {lo, hi}; const bf16x2_cv b = __builtin_convertvector(v, bf16x2_cv); return __builtin_bit_cast(unsigned, b); }
; __device__ __forceinline__ float sigm(float x) { return __builtin_amdgcn_rcpf(1.0f + __expf(-x)); }
; __device__ __forceinline__ float lo16(unsigned w) { return __uint_as_float(w << 16); }
; __device__ __forceinline__ float hi16(unsigned w) { return __uint_as_float(w & 0xffff0000u); }
; __device__ __forceinline__ float rstd_of(const float* rowss, int row) { return rsqrtf(rowss[row] * (1.0f / 1024.0f) + 1e-6f); }
;     __device__ __forceinline__ void operator()(const f32x4 (&acc)[2][2][4][2], const pg8::Unit& u, int wr, int wc, int fr, int fq) const {
;         const int row0 = u.pm * 256 + wr * 64 + fr, col0 = u.pn * 256 + wc * 32 + 8 * fq;
; #pragma unroll
;         for (int ai = 0; ai < 2; ++ai)
; #pragma unroll
;             for (int m = 0; m < 4; ++m) {
;                 const int row = row0 + ai * 128 + m * 16;
;                 const float s = rstd_of(rowss, row);
; #pragma unroll
;                 for (int bj = 0; bj < 2; ++bj) {
;                     const size_t off = (size_t)row * 1024 + col0 + bj * 128;
;                     const u32x4 tv = *(const u32x4*)(Tm + off);
;                     u32x4 pv = (u32x4){0u, 0u, 0u, 0u};
;                     if (ACC) pv = *(const u32x4*)(M + off);
;                     const f32x4 a0 = acc[ai][bj][m][0] * s, a1 = acc[ai][bj][m][1] * s;
;                     float o[8];
;                     o[0] = sigm(a0[0]) * lo16(tv.x); o[1] = sigm(a0[1]) * hi16(tv.x); o[2] = sigm(a0[2]) * lo16(tv.y); o[3] = sigm(a0[3]) * hi16(tv.y);
;                     o[4] = sigm(a1[0]) * lo16(tv.z); o[5] = sigm(a1[1]) * hi16(tv.z); o[6] = sigm(a1[2]) * lo16(tv.w); o[7] = sigm(a1[3]) * hi16(tv.w);
;                     if (ACC) { o[0] += lo16(pv.x); o[1] += hi16(pv.x); o[2] += lo16(pv.y); o[3] += hi16(pv.y); o[4] += lo16(pv.z); o[5] += hi16(pv.z); o[6] += lo16(pv.w); o[7] += hi16(pv.w); }
;                     u32x4 w; w.x = cvt_pk_bf16(o[0], o[1]); w.y = cvt_pk_bf16(o[2], o[3]); w.z = cvt_pk_bf16(o[4], o[5]); w.w = cvt_pk_bf16(o[6], o[7]);
;                     *(u32x4*)(M + off) = w; } }
;     }
	s_cbranch_scc0 .LBB0_353
	v_lshl_add_u32 v164, s2, 8, v139
	v_ashrrev_i32_e32 v165, 31, v164
	v_lshl_add_u64 v[160:161], v[164:165], 2, s[40:41]
	global_load_dword v158, v[160:161], off
	v_lshl_or_b32 v162, s3, 8, v170
	v_ashrrev_i32_e32 v163, 31, v162
	s_mov_b64 s[2:3], 0x40000
	s_mov_b64 s[58:59], s[36:37]
	s_mov_b64 s[56:57], s[4:5]
	s_waitcnt vmcnt(0)
	v_fmamk_f32 v158, v158, 0x3a800000, v187
	v_cmp_gt_f32_e32 vcc, s67, v158
	v_mul_f32_e32 v159, 0x4b800000, v158
	s_nop 0
	v_cndmask_b32_e32 v158, v158, v159, vcc
	v_rsq_f32_e32 v158, v158
	s_nop 0
	v_mul_f32_e32 v159, 0x45800000, v158
	v_cndmask_b32_e32 v166, v158, v159, vcc
	v_lshlrev_b64 v[158:159], 10, v[164:165]
	v_lshl_add_u64 v[158:159], v[158:159], 0, v[162:163]
	v_lshlrev_b64 v[158:159], 1, v[158:159]
	v_lshl_add_u64 v[168:169], s[30:31], 0, v[158:159]
	v_mov_b32_e32 v249, v158
	v_mov_b32_e32 v250, v249
	global_load_dwordx4 v[192:195], v250, s[30:31]
	global_load_dwordx4 v[196:199], v250, s[0:1]
	global_load_dwordx4 v[200:203], v250, s[30:31] offset:256
	global_load_dwordx4 v[204:207], v250, s[0:1] offset:256
	v_add_u32_e32 v250, 0x8000, v249
	global_load_dwordx4 v[208:211], v250, s[30:31]
	global_load_dwordx4 v[212:215], v250, s[0:1]
	global_load_dwordx4 v[216:219], v250, s[30:31] offset:256
	global_load_dwordx4 v[220:223], v250, s[0:1] offset:256
	v_add_u32_e32 v250, 0x10000, v249
	global_load_dwordx4 v[224:227], v250, s[30:31]
	global_load_dwordx4 v[228:231], v250, s[0:1]
	global_load_dwordx4 v[232:235], v250, s[30:31] offset:256
	global_load_dwordx4 v[236:239], v250, s[0:1] offset:256
	global_load_dword v240, v[160:161], off offset:64
	global_load_dword v241, v[160:161], off offset:128
	global_load_dword v244, v[160:161], off offset:192
	global_load_dword v245, v[160:161], off offset:512
	global_load_dword v246, v[160:161], off offset:576
	global_load_dword v247, v[160:161], off offset:640
	global_load_dword v248, v[160:161], off offset:704
	v_lshl_add_u64 v[168:169], s[0:1], 0, v[158:159]
	v_pk_mul_f32 v[126:127], v[126:127], v[166:167] op_sel_hi:[1,0]
	v_pk_mul_f32 v[120:121], v[120:121], v[166:167] op_sel_hi:[1,0]
	v_mul_f32_e32 v126, 0xbfb8aa3b, v126
	v_mul_f32_e32 v127, 0xbfb8aa3b, v127
	v_pk_mul_f32 v[124:125], v[124:125], v[166:167] op_sel_hi:[1,0]
	v_pk_mul_f32 v[122:123], v[122:123], v[166:167] op_sel_hi:[1,0]
	v_exp_f32_e32 v126, v126
	v_exp_f32_e32 v127, v127
	v_mul_f32_e32 v120, 0xbfb8aa3b, v120
	v_mul_f32_e32 v121, 0xbfb8aa3b, v121
	v_mul_f32_e32 v124, 0xbfb8aa3b, v124
	v_mul_f32_e32 v125, 0xbfb8aa3b, v125
	v_exp_f32_e32 v120, v120
	v_exp_f32_e32 v121, v121
	v_mul_f32_e32 v122, 0xbfb8aa3b, v122
	v_mul_f32_e32 v123, 0xbfb8aa3b, v123
	v_exp_f32_e32 v124, v124
	v_exp_f32_e32 v125, v125
	v_exp_f32_e32 v122, v122
	v_exp_f32_e32 v123, v123
	v_add_f32_e32 v126, 1.0, v126
	v_add_f32_e32 v127, 1.0, v127
	v_rcp_f32_e32 v126, v126
	v_rcp_f32_e32 v127, v127
	v_add_f32_e32 v120, 1.0, v120
	v_add_f32_e32 v121, 1.0, v121
	v_add_f32_e32 v124, 1.0, v124
	v_add_f32_e32 v125, 1.0, v125
	v_rcp_f32_e32 v120, v120
	v_rcp_f32_e32 v121, v121
	v_add_f32_e32 v122, 1.0, v122
	v_add_f32_e32 v123, 1.0, v123
	v_rcp_f32_e32 v124, v124
	v_rcp_f32_e32 v125, v125
	v_rcp_f32_e32 v122, v122
	v_rcp_f32_e32 v123, v123
	v_pk_mul_f32 v[116:117], v[116:117], v[166:167] op_sel_hi:[1,0]
	v_pk_mul_f32 v[114:115], v[114:115], v[166:167] op_sel_hi:[1,0]
	s_waitcnt vmcnt(0)
	v_mov_b32_e32 v172, v192
	v_mov_b32_e32 v173, v193
	v_mov_b32_e32 v174, v194
	v_mov_b32_e32 v175, v195
	v_mov_b32_e32 v176, v196
	v_mov_b32_e32 v177, v197
	v_mov_b32_e32 v178, v198
	v_mov_b32_e32 v179, v199
	v_lshlrev_b32_e32 v180, 16, v172
	v_and_b32_e32 v181, 0xffff0000, v172
	v_lshlrev_b32_e32 v182, 16, v176
	v_and_b32_e32 v183, 0xffff0000, v176
	v_lshlrev_b32_e32 v172, 16, v173
	v_and_b32_e32 v173, 0xffff0000, v173
	v_lshlrev_b32_e32 v176, 16, v177
	v_and_b32_e32 v177, 0xffff0000, v177
	v_pk_fma_f32 v[126:127], v[126:127], v[172:173], v[176:177]
	v_lshlrev_b32_e32 v172, 16, v174
	v_and_b32_e32 v173, 0xffff0000, v174
	v_lshlrev_b32_e32 v176, 16, v178
	v_and_b32_e32 v177, 0xffff0000, v178
	v_pk_fma_f32 v[172:173], v[120:121], v[172:173], v[176:177]
	v_lshlrev_b32_e32 v120, 16, v175
	v_and_b32_e32 v121, 0xffff0000, v175
	v_lshlrev_b32_e32 v174, 16, v179
	v_and_b32_e32 v175, 0xffff0000, v179
	v_pk_fma_f32 v[124:125], v[124:125], v[180:181], v[182:183]
	v_pk_fma_f32 v[174:175], v[122:123], v[120:121], v[174:175]
	v_cvt_pk_bf16_f32 v120, v124, v125
	v_cvt_pk_bf16_f32 v121, v126, v127
	v_cvt_pk_bf16_f32 v122, v172, v173
	v_cvt_pk_bf16_f32 v123, v174, v175
	v_or_b32_e32 v124, 0x100, v158
	v_mov_b32_e32 v125, v159
	global_store_dwordx4 v[168:169], v[120:123], off
	v_lshl_add_u64 v[168:169], s[0:1], 0, v[124:125]
	v_pk_mul_f32 v[172:173], v[118:119], v[166:167] op_sel_hi:[1,0]
	v_lshl_add_u64 v[120:121], s[30:31], 0, v[124:125]
	s_nop 1
	v_mov_b32_e32 v120, v200
	v_mov_b32_e32 v121, v201
	v_mov_b32_e32 v122, v202
	v_mov_b32_e32 v123, v203
	v_pk_mul_f32 v[118:119], v[112:113], v[166:167] op_sel_hi:[1,0]
	s_nop 1
	v_mov_b32_e32 v124, v204
	v_mov_b32_e32 v125, v205
	v_mov_b32_e32 v126, v206
	v_mov_b32_e32 v127, v207
	v_add_u32_e32 v250, 0x18000, v249
	global_load_dwordx4 v[192:195], v250, s[30:31]
	global_load_dwordx4 v[196:199], v250, s[0:1]
	global_load_dwordx4 v[200:203], v250, s[30:31] offset:256
	global_load_dwordx4 v[204:207], v250, s[0:1] offset:256
	v_mul_f32_e32 v112, 0xbfb8aa3b, v116
	v_mul_f32_e32 v113, 0xbfb8aa3b, v117
	v_mul_f32_e32 v116, 0xbfb8aa3b, v172
	v_mul_f32_e32 v117, 0xbfb8aa3b, v173
	v_exp_f32_e32 v116, v116
	v_exp_f32_e32 v117, v117
	v_mul_f32_e32 v118, 0xbfb8aa3b, v118
	v_mul_f32_e32 v119, 0xbfb8aa3b, v119
; __device__ __forceinline__ unsigned cvt_pk_bf16(float lo, float hi) { const f32x2_cv v = {lo, hi}; const bf16x2_cv b = __builtin_convertvector(v, bf16x2_cv); return __builtin_bit_cast(unsigned, b); }
; __device__ __forceinline__ float sigm(float x) { return __builtin_amdgcn_rcpf(1.0f + __expf(-x)); }
; __device__ __forceinline__ float lo16(unsigned w) { return __uint_as_float(w << 16); }
; __device__ __forceinline__ float hi16(unsigned w) { return __uint_as_float(w & 0xffff0000u); }
; __device__ __forceinline__ float rstd_of(const float* rowss, int row) { return rsqrtf(rowss[row] * (1.0f / 1024.0f) + 1e-6f); }
;     __device__ __forceinline__ void operator()(const f32x4 (&acc)[2][2][4][2], const pg8::Unit& u, int wr, int wc, int fr, int fq) const {
;         const int row0 = u.pm * 256 + wr * 64 + fr, col0 = u.pn * 256 + wc * 32 + 8 * fq;
; #pragma unroll
;         for (int ai = 0; ai < 2; ++ai)
; #pragma unroll
;             for (int m = 0; m < 4; ++m) {
;                 const int row = row0 + ai * 128 + m * 16;
;                 const float s = rstd_of(rowss, row);
; #pragma unroll
;                 for (int bj = 0; bj < 2; ++bj) {
;                     const size_t off = (size_t)row * 1024 + col0 + bj * 128;
;                     const u32x4 tv = *(const u32x4*)(Tm + off);
;                     u32x4 pv = (u32x4){0u, 0u, 0u, 0u};
;                     if (ACC) pv = *(const u32x4*)(M + off);
;                     const f32x4 a0 = acc[ai][bj][m][0] * s, a1 = acc[ai][bj][m][1] * s;
;                     float o[8];
;                     o[0] = sigm(a0[0]) * lo16(tv.x); o[1] = sigm(a0[1]) * hi16(tv.x); o[2] = sigm(a0[2]) * lo16(tv.y); o[3] = sigm(a0[3]) * hi16(tv.y);
;                     o[4] = sigm(a1[0]) * lo16(tv.z); o[5] = sigm(a1[1]) * hi16(tv.z); o[6] = sigm(a1[2]) * lo16(tv.w); o[7] = sigm(a1[3]) * hi16(tv.w);
;                     if (ACC) { o[0] += lo16(pv.x); o[1] += hi16(pv.x); o[2] += lo16(pv.y); o[3] += hi16(pv.y); o[4] += lo16(pv.z); o[5] += hi16(pv.z); o[6] += lo16(pv.w); o[7] += hi16(pv.w); }
;                     u32x4 w; w.x = cvt_pk_bf16(o[0], o[1]); w.y = cvt_pk_bf16(o[2], o[3]); w.z = cvt_pk_bf16(o[4], o[5]); w.w = cvt_pk_bf16(o[6], o[7]);
;                     *(u32x4*)(M + off) = w; } }
;     }
	v_exp_f32_e32 v118, v118
	v_exp_f32_e32 v119, v119
	v_mul_f32_e32 v114, 0xbfb8aa3b, v114
	v_mul_f32_e32 v115, 0xbfb8aa3b, v115
	v_exp_f32_e32 v112, v112
	v_exp_f32_e32 v113, v113
	v_exp_f32_e32 v114, v114
	v_exp_f32_e32 v115, v115
	v_add_f32_e32 v116, 1.0, v116
	v_add_f32_e32 v117, 1.0, v117
	v_rcp_f32_e32 v116, v116
	v_rcp_f32_e32 v117, v117
	v_add_f32_e32 v118, 1.0, v118
	v_add_f32_e32 v119, 1.0, v119
	v_add_f32_e32 v112, 1.0, v112
	v_add_f32_e32 v113, 1.0, v113
	v_rcp_f32_e32 v118, v118
	v_rcp_f32_e32 v119, v119
	v_add_f32_e32 v114, 1.0, v114
	v_add_f32_e32 v115, 1.0, v115
	v_rcp_f32_e32 v112, v112
	v_rcp_f32_e32 v113, v113
	v_rcp_f32_e32 v114, v114
	v_rcp_f32_e32 v115, v115
	v_lshlrev_b32_e32 v172, 16, v120
	v_and_b32_e32 v173, 0xffff0000, v120
	v_lshlrev_b32_e32 v174, 16, v124
	v_and_b32_e32 v175, 0xffff0000, v124
	v_lshlrev_b32_e32 v120, 16, v121
	v_and_b32_e32 v121, 0xffff0000, v121
	v_lshlrev_b32_e32 v124, 16, v125
	v_and_b32_e32 v125, 0xffff0000, v125
	v_pk_fma_f32 v[116:117], v[116:117], v[120:121], v[124:125]
	v_lshlrev_b32_e32 v120, 16, v122
	v_and_b32_e32 v121, 0xffff0000, v122
	v_lshlrev_b32_e32 v124, 16, v126
	v_and_b32_e32 v125, 0xffff0000, v126
	v_pk_fma_f32 v[118:119], v[118:119], v[120:121], v[124:125]
	v_lshlrev_b32_e32 v120, 16, v123
	v_and_b32_e32 v121, 0xffff0000, v123
	v_lshlrev_b32_e32 v122, 16, v127
	v_and_b32_e32 v123, 0xffff0000, v127
	v_pk_fma_f32 v[112:113], v[112:113], v[172:173], v[174:175]
	v_pk_fma_f32 v[120:121], v[114:115], v[120:121], v[122:123]
	v_cvt_pk_bf16_f32 v112, v112, v113
	v_cvt_pk_bf16_f32 v113, v116, v117
	v_cvt_pk_bf16_f32 v114, v118, v119
	v_cvt_pk_bf16_f32 v115, v120, v121
	global_store_dwordx4 v[168:169], v[112:115], off
	s_nop 1
	v_mov_b32_e32 v112, v240
	s_nop 0
	v_or_b32_e32 v114, 16, v164
	v_ashrrev_i32_e32 v115, 31, v114
	v_lshlrev_b64 v[114:115], 10, v[114:115]
	v_lshl_add_u64 v[114:115], v[114:115], 0, v[162:163]
	v_lshlrev_b64 v[114:115], 1, v[114:115]
	v_lshl_add_u64 v[116:117], s[30:31], 0, v[114:115]
	v_lshl_add_u64 v[124:125], s[0:1], 0, v[114:115]
	s_nop 1
	v_mov_b32_e32 v116, v208
	v_mov_b32_e32 v117, v209
	v_mov_b32_e32 v118, v210
	v_mov_b32_e32 v119, v211
	v_or_b32_e32 v114, 0x100, v114
	s_nop 1
	v_mov_b32_e32 v120, v212
	v_mov_b32_e32 v121, v213
	v_mov_b32_e32 v122, v214
	v_mov_b32_e32 v123, v215
	v_fmamk_f32 v112, v112, 0x3a800000, v187
	v_cmp_gt_f32_e32 vcc, s67, v112
	v_mul_f32_e32 v113, 0x4b800000, v112
	v_lshlrev_b32_e32 v126, 16, v116
	v_cndmask_b32_e32 v112, v112, v113, vcc
	v_rsq_f32_e32 v112, v112
	v_and_b32_e32 v127, 0xffff0000, v116
	v_lshlrev_b32_e32 v168, 16, v120
	v_and_b32_e32 v169, 0xffff0000, v120
	v_mul_f32_e32 v113, 0x45800000, v112
	v_cndmask_b32_e32 v112, v112, v113, vcc
	v_pk_mul_f32 v[110:111], v[110:111], v[112:113] op_sel_hi:[1,0]
	v_pk_mul_f32 v[104:105], v[104:105], v[112:113] op_sel_hi:[1,0]
	v_mul_f32_e32 v110, 0xbfb8aa3b, v110
	v_mul_f32_e32 v111, 0xbfb8aa3b, v111
	v_pk_mul_f32 v[108:109], v[108:109], v[112:113] op_sel_hi:[1,0]
	v_pk_mul_f32 v[106:107], v[106:107], v[112:113] op_sel_hi:[1,0]
	v_exp_f32_e32 v110, v110
	v_exp_f32_e32 v111, v111
	v_mul_f32_e32 v104, 0xbfb8aa3b, v104
	v_mul_f32_e32 v105, 0xbfb8aa3b, v105
	v_mul_f32_e32 v108, 0xbfb8aa3b, v108
	v_mul_f32_e32 v109, 0xbfb8aa3b, v109
	v_exp_f32_e32 v104, v104
	v_exp_f32_e32 v105, v105
	v_mul_f32_e32 v106, 0xbfb8aa3b, v106
	v_mul_f32_e32 v107, 0xbfb8aa3b, v107
	v_exp_f32_e32 v108, v108
	v_exp_f32_e32 v109, v109
	v_exp_f32_e32 v106, v106
	v_exp_f32_e32 v107, v107
	v_add_f32_e32 v110, 1.0, v110
	v_add_f32_e32 v111, 1.0, v111
	v_rcp_f32_e32 v110, v110
	v_rcp_f32_e32 v111, v111
	v_add_f32_e32 v104, 1.0, v104
	v_add_f32_e32 v105, 1.0, v105
	v_add_f32_e32 v108, 1.0, v108
	v_add_f32_e32 v109, 1.0, v109
	v_rcp_f32_e32 v104, v104
	v_rcp_f32_e32 v105, v105
	v_add_f32_e32 v106, 1.0, v106
	v_add_f32_e32 v107, 1.0, v107
	v_rcp_f32_e32 v108, v108
	v_rcp_f32_e32 v109, v109
	v_rcp_f32_e32 v106, v106
	v_rcp_f32_e32 v107, v107
	v_lshlrev_b32_e32 v116, 16, v117
	v_and_b32_e32 v117, 0xffff0000, v117
	v_lshlrev_b32_e32 v120, 16, v121
	v_and_b32_e32 v121, 0xffff0000, v121
	v_pk_fma_f32 v[110:111], v[110:111], v[116:117], v[120:121]
	v_lshlrev_b32_e32 v116, 16, v118
	v_and_b32_e32 v117, 0xffff0000, v118
	v_lshlrev_b32_e32 v120, 16, v122
	v_and_b32_e32 v121, 0xffff0000, v122
	v_pk_fma_f32 v[116:117], v[104:105], v[116:117], v[120:121]
	v_lshlrev_b32_e32 v104, 16, v119
	v_and_b32_e32 v105, 0xffff0000, v119
	v_lshlrev_b32_e32 v118, 16, v123
	v_and_b32_e32 v119, 0xffff0000, v123
	v_pk_fma_f32 v[108:109], v[108:109], v[126:127], v[168:169]
	v_pk_fma_f32 v[118:119], v[106:107], v[104:105], v[118:119]
	v_cvt_pk_bf16_f32 v104, v108, v109
	v_cvt_pk_bf16_f32 v105, v110, v111
	v_cvt_pk_bf16_f32 v106, v116, v117
	v_cvt_pk_bf16_f32 v107, v118, v119
	global_store_dwordx4 v[124:125], v[104:107], off
	v_pk_mul_f32 v[102:103], v[102:103], v[112:113] op_sel_hi:[1,0]
	v_pk_mul_f32 v[96:97], v[96:97], v[112:113] op_sel_hi:[1,0]
	v_lshl_add_u64 v[104:105], s[30:31], 0, v[114:115]
	v_lshl_add_u64 v[114:115], s[0:1], 0, v[114:115]
	s_nop 1
	v_mov_b32_e32 v104, v216
	v_mov_b32_e32 v105, v217
	v_mov_b32_e32 v106, v218
	v_mov_b32_e32 v107, v219
	v_mul_f32_e32 v102, 0xbfb8aa3b, v102
	s_nop 1
	v_mov_b32_e32 v108, v220
	v_mov_b32_e32 v109, v221
	v_mov_b32_e32 v110, v222
	v_mov_b32_e32 v111, v223
	v_add_u32_e32 v250, 0x40000, v249
	global_load_dwordx4 v[208:211], v250, s[30:31]
	global_load_dwordx4 v[212:215], v250, s[0:1]
	global_load_dwordx4 v[216:219], v250, s[30:31] offset:256
	global_load_dwordx4 v[220:223], v250, s[0:1] offset:256
	v_mul_f32_e32 v103, 0xbfb8aa3b, v103
	v_pk_mul_f32 v[100:101], v[100:101], v[112:113] op_sel_hi:[1,0]
; __device__ __forceinline__ unsigned cvt_pk_bf16(float lo, float hi) { const f32x2_cv v = {lo, hi}; const bf16x2_cv b = __builtin_convertvector(v, bf16x2_cv); return __builtin_bit_cast(unsigned, b); }
; __device__ __forceinline__ float sigm(float x) { return __builtin_amdgcn_rcpf(1.0f + __expf(-x)); }
; __device__ __forceinline__ float lo16(unsigned w) { return __uint_as_float(w << 16); }
; __device__ __forceinline__ float hi16(unsigned w) { return __uint_as_float(w & 0xffff0000u); }
; __device__ __forceinline__ float rstd_of(const float* rowss, int row) { return rsqrtf(rowss[row] * (1.0f / 1024.0f) + 1e-6f); }
;     __device__ __forceinline__ void operator()(const f32x4 (&acc)[2][2][4][2], const pg8::Unit& u, int wr, int wc, int fr, int fq) const {
;         const int row0 = u.pm * 256 + wr * 64 + fr, col0 = u.pn * 256 + wc * 32 + 8 * fq;
; #pragma unroll
;         for (int ai = 0; ai < 2; ++ai)
; #pragma unroll
;             for (int m = 0; m < 4; ++m) {
;                 const int row = row0 + ai * 128 + m * 16;
;                 const float s = rstd_of(rowss, row);
; #pragma unroll
;                 for (int bj = 0; bj < 2; ++bj) {
;                     const size_t off = (size_t)row * 1024 + col0 + bj * 128;
;                     const u32x4 tv = *(const u32x4*)(Tm + off);
;                     u32x4 pv = (u32x4){0u, 0u, 0u, 0u};
;                     if (ACC) pv = *(const u32x4*)(M + off);
;                     const f32x4 a0 = acc[ai][bj][m][0] * s, a1 = acc[ai][bj][m][1] * s;
;                     float o[8];
;                     o[0] = sigm(a0[0]) * lo16(tv.x); o[1] = sigm(a0[1]) * hi16(tv.x); o[2] = sigm(a0[2]) * lo16(tv.y); o[3] = sigm(a0[3]) * hi16(tv.y);
;                     o[4] = sigm(a1[0]) * lo16(tv.z); o[5] = sigm(a1[1]) * hi16(tv.z); o[6] = sigm(a1[2]) * lo16(tv.w); o[7] = sigm(a1[3]) * hi16(tv.w);
;                     if (ACC) { o[0] += lo16(pv.x); o[1] += hi16(pv.x); o[2] += lo16(pv.y); o[3] += hi16(pv.y); o[4] += lo16(pv.z); o[5] += hi16(pv.z); o[6] += lo16(pv.w); o[7] += hi16(pv.w); }
;                     u32x4 w; w.x = cvt_pk_bf16(o[0], o[1]); w.y = cvt_pk_bf16(o[2], o[3]); w.z = cvt_pk_bf16(o[4], o[5]); w.w = cvt_pk_bf16(o[6], o[7]);
;                     *(u32x4*)(M + off) = w; } }
;     }
	v_pk_mul_f32 v[98:99], v[98:99], v[112:113] op_sel_hi:[1,0]
	v_exp_f32_e32 v102, v102
	v_exp_f32_e32 v103, v103
	v_mul_f32_e32 v96, 0xbfb8aa3b, v96
	v_mul_f32_e32 v97, 0xbfb8aa3b, v97
	v_mul_f32_e32 v100, 0xbfb8aa3b, v100
	v_mul_f32_e32 v101, 0xbfb8aa3b, v101
	v_exp_f32_e32 v96, v96
	v_exp_f32_e32 v97, v97
	v_mul_f32_e32 v98, 0xbfb8aa3b, v98
	v_mul_f32_e32 v99, 0xbfb8aa3b, v99
	v_exp_f32_e32 v100, v100
	v_exp_f32_e32 v101, v101
	v_exp_f32_e32 v98, v98
	v_exp_f32_e32 v99, v99
	v_add_f32_e32 v102, 1.0, v102
	v_add_f32_e32 v103, 1.0, v103
	v_rcp_f32_e32 v102, v102
	v_rcp_f32_e32 v103, v103
	v_add_f32_e32 v96, 1.0, v96
	v_add_f32_e32 v97, 1.0, v97
	v_add_f32_e32 v100, 1.0, v100
	v_add_f32_e32 v101, 1.0, v101
	v_rcp_f32_e32 v96, v96
	v_rcp_f32_e32 v97, v97
	v_add_f32_e32 v98, 1.0, v98
	v_add_f32_e32 v99, 1.0, v99
	v_rcp_f32_e32 v100, v100
	v_rcp_f32_e32 v101, v101
	v_rcp_f32_e32 v98, v98
	v_rcp_f32_e32 v99, v99
	v_lshlrev_b32_e32 v112, 16, v104
	v_and_b32_e32 v113, 0xffff0000, v104
	v_lshlrev_b32_e32 v116, 16, v108
	v_and_b32_e32 v117, 0xffff0000, v108
	v_lshlrev_b32_e32 v104, 16, v105
	v_and_b32_e32 v105, 0xffff0000, v105
	v_lshlrev_b32_e32 v108, 16, v109
	v_and_b32_e32 v109, 0xffff0000, v109
	v_pk_fma_f32 v[102:103], v[102:103], v[104:105], v[108:109]
	v_lshlrev_b32_e32 v104, 16, v106
	v_and_b32_e32 v105, 0xffff0000, v106
	v_lshlrev_b32_e32 v108, 16, v110
	v_and_b32_e32 v109, 0xffff0000, v110
	v_pk_fma_f32 v[104:105], v[96:97], v[104:105], v[108:109]
	v_lshlrev_b32_e32 v96, 16, v107
	v_and_b32_e32 v97, 0xffff0000, v107
	v_lshlrev_b32_e32 v106, 16, v111
	v_and_b32_e32 v107, 0xffff0000, v111
	v_pk_fma_f32 v[100:101], v[100:101], v[112:113], v[116:117]
	v_pk_fma_f32 v[106:107], v[98:99], v[96:97], v[106:107]
	v_cvt_pk_bf16_f32 v96, v100, v101
	v_cvt_pk_bf16_f32 v97, v102, v103
	v_cvt_pk_bf16_f32 v98, v104, v105
	v_cvt_pk_bf16_f32 v99, v106, v107
	global_store_dwordx4 v[114:115], v[96:99], off
	s_nop 1
	v_mov_b32_e32 v96, v241
	s_nop 0
	v_or_b32_e32 v98, 32, v164
	v_ashrrev_i32_e32 v99, 31, v98
	v_lshlrev_b64 v[98:99], 10, v[98:99]
	v_lshl_add_u64 v[98:99], v[98:99], 0, v[162:163]
	v_lshlrev_b64 v[98:99], 1, v[98:99]
	v_lshl_add_u64 v[100:101], s[30:31], 0, v[98:99]
	v_lshl_add_u64 v[108:109], s[0:1], 0, v[98:99]
	s_nop 1
	v_mov_b32_e32 v100, v224
	v_mov_b32_e32 v101, v225
	v_mov_b32_e32 v102, v226
	v_mov_b32_e32 v103, v227
	v_or_b32_e32 v98, 0x100, v98
	s_nop 1
	v_mov_b32_e32 v104, v228
	v_mov_b32_e32 v105, v229
	v_mov_b32_e32 v106, v230
	v_mov_b32_e32 v107, v231
	v_fmamk_f32 v96, v96, 0x3a800000, v187
	v_cmp_gt_f32_e32 vcc, s67, v96
	v_mul_f32_e32 v97, 0x4b800000, v96
	v_lshlrev_b32_e32 v110, 16, v100
	v_cndmask_b32_e32 v96, v96, v97, vcc
	v_rsq_f32_e32 v96, v96
	v_and_b32_e32 v111, 0xffff0000, v100
	v_lshlrev_b32_e32 v112, 16, v104
	v_and_b32_e32 v113, 0xffff0000, v104
	v_mul_f32_e32 v97, 0x45800000, v96
	v_cndmask_b32_e32 v96, v96, v97, vcc
	v_pk_mul_f32 v[94:95], v[94:95], v[96:97] op_sel_hi:[1,0]
	v_pk_mul_f32 v[88:89], v[88:89], v[96:97] op_sel_hi:[1,0]
	v_mul_f32_e32 v94, 0xbfb8aa3b, v94
	v_mul_f32_e32 v95, 0xbfb8aa3b, v95
	v_pk_mul_f32 v[92:93], v[92:93], v[96:97] op_sel_hi:[1,0]
	v_pk_mul_f32 v[90:91], v[90:91], v[96:97] op_sel_hi:[1,0]
	v_exp_f32_e32 v94, v94
	v_exp_f32_e32 v95, v95
	v_mul_f32_e32 v88, 0xbfb8aa3b, v88
	v_mul_f32_e32 v89, 0xbfb8aa3b, v89
	v_mul_f32_e32 v92, 0xbfb8aa3b, v92
	v_mul_f32_e32 v93, 0xbfb8aa3b, v93
	v_exp_f32_e32 v88, v88
	v_exp_f32_e32 v89, v89
	v_mul_f32_e32 v90, 0xbfb8aa3b, v90
	v_mul_f32_e32 v91, 0xbfb8aa3b, v91
	v_exp_f32_e32 v92, v92
	v_exp_f32_e32 v93, v93
	v_exp_f32_e32 v90, v90
	v_exp_f32_e32 v91, v91
	v_add_f32_e32 v94, 1.0, v94
	v_add_f32_e32 v95, 1.0, v95
	v_rcp_f32_e32 v94, v94
	v_rcp_f32_e32 v95, v95
	v_add_f32_e32 v88, 1.0, v88
	v_add_f32_e32 v89, 1.0, v89
	v_add_f32_e32 v92, 1.0, v92
	v_add_f32_e32 v93, 1.0, v93
	v_rcp_f32_e32 v88, v88
	v_rcp_f32_e32 v89, v89
	v_add_f32_e32 v90, 1.0, v90
	v_add_f32_e32 v91, 1.0, v91
	v_rcp_f32_e32 v92, v92
	v_rcp_f32_e32 v93, v93
	v_rcp_f32_e32 v90, v90
	v_rcp_f32_e32 v91, v91
	v_lshlrev_b32_e32 v100, 16, v101
	v_and_b32_e32 v101, 0xffff0000, v101
	v_lshlrev_b32_e32 v104, 16, v105
	v_and_b32_e32 v105, 0xffff0000, v105
	v_pk_fma_f32 v[94:95], v[94:95], v[100:101], v[104:105]
	v_lshlrev_b32_e32 v100, 16, v102
	v_and_b32_e32 v101, 0xffff0000, v102
	v_lshlrev_b32_e32 v104, 16, v106
	v_and_b32_e32 v105, 0xffff0000, v106
	v_pk_fma_f32 v[100:101], v[88:89], v[100:101], v[104:105]
	v_lshlrev_b32_e32 v88, 16, v103
	v_and_b32_e32 v89, 0xffff0000, v103
	v_lshlrev_b32_e32 v102, 16, v107
	v_and_b32_e32 v103, 0xffff0000, v107
	v_pk_fma_f32 v[92:93], v[92:93], v[110:111], v[112:113]
	v_pk_fma_f32 v[102:103], v[90:91], v[88:89], v[102:103]
	v_cvt_pk_bf16_f32 v88, v92, v93
	v_cvt_pk_bf16_f32 v89, v94, v95
	v_cvt_pk_bf16_f32 v90, v100, v101
	v_cvt_pk_bf16_f32 v91, v102, v103
	global_store_dwordx4 v[108:109], v[88:91], off
	v_pk_mul_f32 v[86:87], v[86:87], v[96:97] op_sel_hi:[1,0]
	v_pk_mul_f32 v[80:81], v[80:81], v[96:97] op_sel_hi:[1,0]
	v_lshl_add_u64 v[88:89], s[30:31], 0, v[98:99]
	v_lshl_add_u64 v[98:99], s[0:1], 0, v[98:99]
	s_nop 1
	v_mov_b32_e32 v92, v232
	v_mov_b32_e32 v93, v233
	v_mov_b32_e32 v94, v234
	v_mov_b32_e32 v95, v235
	v_mul_f32_e32 v86, 0xbfb8aa3b, v86
	s_nop 1
	v_mov_b32_e32 v88, v236
	v_mov_b32_e32 v89, v237
	v_mov_b32_e32 v90, v238
	v_mov_b32_e32 v91, v239
	v_add_u32_e32 v250, 0x48000, v249
	global_load_dwordx4 v[224:227], v250, s[30:31]
	global_load_dwordx4 v[228:231], v250, s[0:1]
	global_load_dwordx4 v[232:235], v250, s[30:31] offset:256
	global_load_dwordx4 v[236:239], v250, s[0:1] offset:256
	v_mul_f32_e32 v87, 0xbfb8aa3b, v87
; __device__ __forceinline__ unsigned cvt_pk_bf16(float lo, float hi) { const f32x2_cv v = {lo, hi}; const bf16x2_cv b = __builtin_convertvector(v, bf16x2_cv); return __builtin_bit_cast(unsigned, b); }
; __device__ __forceinline__ float sigm(float x) { return __builtin_amdgcn_rcpf(1.0f + __expf(-x)); }
; __device__ __forceinline__ float lo16(unsigned w) { return __uint_as_float(w << 16); }
; __device__ __forceinline__ float hi16(unsigned w) { return __uint_as_float(w & 0xffff0000u); }
; __device__ __forceinline__ float rstd_of(const float* rowss, int row) { return rsqrtf(rowss[row] * (1.0f / 1024.0f) + 1e-6f); }
;     __device__ __forceinline__ void operator()(const f32x4 (&acc)[2][2][4][2], const pg8::Unit& u, int wr, int wc, int fr, int fq) const {
;         const int row0 = u.pm * 256 + wr * 64 + fr, col0 = u.pn * 256 + wc * 32 + 8 * fq;
; #pragma unroll
;         for (int ai = 0; ai < 2; ++ai)
; #pragma unroll
;             for (int m = 0; m < 4; ++m) {
;                 const int row = row0 + ai * 128 + m * 16;
;                 const float s = rstd_of(rowss, row);
; #pragma unroll
;                 for (int bj = 0; bj < 2; ++bj) {
;                     const size_t off = (size_t)row * 1024 + col0 + bj * 128;
;                     const u32x4 tv = *(const u32x4*)(Tm + off);
;                     u32x4 pv = (u32x4){0u, 0u, 0u, 0u};
;                     if (ACC) pv = *(const u32x4*)(M + off);
;                     const f32x4 a0 = acc[ai][bj][m][0] * s, a1 = acc[ai][bj][m][1] * s;
;                     float o[8];
;                     o[0] = sigm(a0[0]) * lo16(tv.x); o[1] = sigm(a0[1]) * hi16(tv.x); o[2] = sigm(a0[2]) * lo16(tv.y); o[3] = sigm(a0[3]) * hi16(tv.y);
;                     o[4] = sigm(a1[0]) * lo16(tv.z); o[5] = sigm(a1[1]) * hi16(tv.z); o[6] = sigm(a1[2]) * lo16(tv.w); o[7] = sigm(a1[3]) * hi16(tv.w);
;                     if (ACC) { o[0] += lo16(pv.x); o[1] += hi16(pv.x); o[2] += lo16(pv.y); o[3] += hi16(pv.y); o[4] += lo16(pv.z); o[5] += hi16(pv.z); o[6] += lo16(pv.w); o[7] += hi16(pv.w); }
;                     u32x4 w; w.x = cvt_pk_bf16(o[0], o[1]); w.y = cvt_pk_bf16(o[2], o[3]); w.z = cvt_pk_bf16(o[4], o[5]); w.w = cvt_pk_bf16(o[6], o[7]);
;                     *(u32x4*)(M + off) = w; } }
;     }
	v_pk_mul_f32 v[84:85], v[84:85], v[96:97] op_sel_hi:[1,0]
	v_pk_mul_f32 v[82:83], v[82:83], v[96:97] op_sel_hi:[1,0]
	v_exp_f32_e32 v86, v86
	v_exp_f32_e32 v87, v87
	v_mul_f32_e32 v80, 0xbfb8aa3b, v80
	v_mul_f32_e32 v81, 0xbfb8aa3b, v81
	v_mul_f32_e32 v84, 0xbfb8aa3b, v84
	v_mul_f32_e32 v85, 0xbfb8aa3b, v85
	v_exp_f32_e32 v80, v80
	v_exp_f32_e32 v81, v81
	v_mul_f32_e32 v82, 0xbfb8aa3b, v82
	v_mul_f32_e32 v83, 0xbfb8aa3b, v83
	v_exp_f32_e32 v84, v84
	v_exp_f32_e32 v85, v85
	v_exp_f32_e32 v82, v82
	v_exp_f32_e32 v83, v83
	v_add_f32_e32 v86, 1.0, v86
	v_add_f32_e32 v87, 1.0, v87
	v_rcp_f32_e32 v86, v86
	v_rcp_f32_e32 v87, v87
	v_add_f32_e32 v80, 1.0, v80
	v_add_f32_e32 v81, 1.0, v81
	v_add_f32_e32 v84, 1.0, v84
	v_add_f32_e32 v85, 1.0, v85
	v_rcp_f32_e32 v80, v80
	v_rcp_f32_e32 v81, v81
	v_add_f32_e32 v82, 1.0, v82
	v_add_f32_e32 v83, 1.0, v83
	v_rcp_f32_e32 v84, v84
	v_rcp_f32_e32 v85, v85
	v_rcp_f32_e32 v82, v82
	v_rcp_f32_e32 v83, v83
	v_lshlrev_b32_e32 v96, 16, v92
	v_and_b32_e32 v97, 0xffff0000, v92
	v_lshlrev_b32_e32 v100, 16, v88
	v_and_b32_e32 v101, 0xffff0000, v88
	v_lshlrev_b32_e32 v92, 16, v93
	v_and_b32_e32 v93, 0xffff0000, v93
	v_lshlrev_b32_e32 v88, 16, v89
	v_and_b32_e32 v89, 0xffff0000, v89
	v_pk_fma_f32 v[86:87], v[86:87], v[92:93], v[88:89]
	v_lshlrev_b32_e32 v88, 16, v94
	v_and_b32_e32 v89, 0xffff0000, v94
	v_lshlrev_b32_e32 v92, 16, v90
	v_and_b32_e32 v93, 0xffff0000, v90
	v_pk_fma_f32 v[88:89], v[80:81], v[88:89], v[92:93]
	v_lshlrev_b32_e32 v80, 16, v95
	v_and_b32_e32 v81, 0xffff0000, v95
	v_lshlrev_b32_e32 v90, 16, v91
	v_and_b32_e32 v91, 0xffff0000, v91
	v_pk_fma_f32 v[84:85], v[84:85], v[96:97], v[100:101]
	v_pk_fma_f32 v[90:91], v[82:83], v[80:81], v[90:91]
	v_cvt_pk_bf16_f32 v80, v84, v85
	v_cvt_pk_bf16_f32 v81, v86, v87
	v_cvt_pk_bf16_f32 v82, v88, v89
	v_cvt_pk_bf16_f32 v83, v90, v91
	global_store_dwordx4 v[98:99], v[80:83], off
	s_nop 1
	v_mov_b32_e32 v80, v244
	s_nop 0
	v_or_b32_e32 v82, 48, v164
	v_ashrrev_i32_e32 v83, 31, v82
	v_lshlrev_b64 v[82:83], 10, v[82:83]
	v_lshl_add_u64 v[82:83], v[82:83], 0, v[162:163]
	v_lshlrev_b64 v[82:83], 1, v[82:83]
	v_lshl_add_u64 v[84:85], s[30:31], 0, v[82:83]
	v_lshl_add_u64 v[92:93], s[0:1], 0, v[82:83]
	s_waitcnt vmcnt(13)
	s_nop 1
	v_mov_b32_e32 v84, v192
	v_mov_b32_e32 v85, v193
	v_mov_b32_e32 v86, v194
	v_mov_b32_e32 v87, v195
	v_or_b32_e32 v82, 0x100, v82
	s_nop 1
	v_mov_b32_e32 v88, v196
	v_mov_b32_e32 v89, v197
	v_mov_b32_e32 v90, v198
	v_mov_b32_e32 v91, v199
	v_fmamk_f32 v80, v80, 0x3a800000, v187
	v_cmp_gt_f32_e32 vcc, s67, v80
	v_mul_f32_e32 v81, 0x4b800000, v80
	v_lshlrev_b32_e32 v94, 16, v84
	v_cndmask_b32_e32 v80, v80, v81, vcc
	v_rsq_f32_e32 v80, v80
	v_and_b32_e32 v95, 0xffff0000, v84
	v_lshlrev_b32_e32 v96, 16, v88
	v_and_b32_e32 v97, 0xffff0000, v88
	v_mul_f32_e32 v81, 0x45800000, v80
	v_cndmask_b32_e32 v80, v80, v81, vcc
	v_pk_mul_f32 v[78:79], v[78:79], v[80:81] op_sel_hi:[1,0]
	v_pk_mul_f32 v[72:73], v[72:73], v[80:81] op_sel_hi:[1,0]
	v_mul_f32_e32 v78, 0xbfb8aa3b, v78
	v_mul_f32_e32 v79, 0xbfb8aa3b, v79
	v_pk_mul_f32 v[76:77], v[76:77], v[80:81] op_sel_hi:[1,0]
	v_pk_mul_f32 v[74:75], v[74:75], v[80:81] op_sel_hi:[1,0]
	v_exp_f32_e32 v78, v78
	v_exp_f32_e32 v79, v79
	v_mul_f32_e32 v72, 0xbfb8aa3b, v72
	v_mul_f32_e32 v73, 0xbfb8aa3b, v73
	v_mul_f32_e32 v76, 0xbfb8aa3b, v76
	v_mul_f32_e32 v77, 0xbfb8aa3b, v77
	v_exp_f32_e32 v72, v72
	v_exp_f32_e32 v73, v73
	v_mul_f32_e32 v74, 0xbfb8aa3b, v74
	v_mul_f32_e32 v75, 0xbfb8aa3b, v75
	v_exp_f32_e32 v76, v76
	v_exp_f32_e32 v77, v77
	v_exp_f32_e32 v74, v74
	v_exp_f32_e32 v75, v75
	v_add_f32_e32 v78, 1.0, v78
	v_add_f32_e32 v79, 1.0, v79
	v_rcp_f32_e32 v78, v78
	v_rcp_f32_e32 v79, v79
	v_add_f32_e32 v72, 1.0, v72
	v_add_f32_e32 v73, 1.0, v73
	v_add_f32_e32 v76, 1.0, v76
	v_add_f32_e32 v77, 1.0, v77
	v_rcp_f32_e32 v72, v72
	v_rcp_f32_e32 v73, v73
	v_add_f32_e32 v74, 1.0, v74
	v_add_f32_e32 v75, 1.0, v75
	v_rcp_f32_e32 v76, v76
	v_rcp_f32_e32 v77, v77
	v_rcp_f32_e32 v74, v74
	v_rcp_f32_e32 v75, v75
	v_lshlrev_b32_e32 v84, 16, v85
	v_and_b32_e32 v85, 0xffff0000, v85
	v_lshlrev_b32_e32 v88, 16, v89
	v_and_b32_e32 v89, 0xffff0000, v89
	v_pk_fma_f32 v[78:79], v[78:79], v[84:85], v[88:89]
	v_lshlrev_b32_e32 v84, 16, v86
	v_and_b32_e32 v85, 0xffff0000, v86
	v_lshlrev_b32_e32 v88, 16, v90
	v_and_b32_e32 v89, 0xffff0000, v90
	v_pk_fma_f32 v[84:85], v[72:73], v[84:85], v[88:89]
	v_lshlrev_b32_e32 v72, 16, v87
	v_and_b32_e32 v73, 0xffff0000, v87
	v_lshlrev_b32_e32 v86, 16, v91
	v_and_b32_e32 v87, 0xffff0000, v91
	v_pk_fma_f32 v[76:77], v[76:77], v[94:95], v[96:97]
	v_pk_fma_f32 v[86:87], v[74:75], v[72:73], v[86:87]
	v_cvt_pk_bf16_f32 v72, v76, v77
	v_cvt_pk_bf16_f32 v73, v78, v79
	v_cvt_pk_bf16_f32 v74, v84, v85
	v_cvt_pk_bf16_f32 v75, v86, v87
	global_store_dwordx4 v[92:93], v[72:75], off
	v_pk_mul_f32 v[70:71], v[70:71], v[80:81] op_sel_hi:[1,0]
	v_pk_mul_f32 v[64:65], v[64:65], v[80:81] op_sel_hi:[1,0]
	v_lshl_add_u64 v[72:73], s[30:31], 0, v[82:83]
	v_lshl_add_u64 v[82:83], s[0:1], 0, v[82:83]
	s_nop 1
	v_mov_b32_e32 v76, v200
	v_mov_b32_e32 v77, v201
	v_mov_b32_e32 v78, v202
	v_mov_b32_e32 v79, v203
	v_mul_f32_e32 v70, 0xbfb8aa3b, v70
	s_nop 1
	v_mov_b32_e32 v72, v204
	v_mov_b32_e32 v73, v205
	v_mov_b32_e32 v74, v206
	v_mov_b32_e32 v75, v207
	v_add_u32_e32 v250, 0x50000, v249
	global_load_dwordx4 v[192:195], v250, s[30:31]
	global_load_dwordx4 v[196:199], v250, s[0:1]
	global_load_dwordx4 v[200:203], v250, s[30:31] offset:256
	global_load_dwordx4 v[204:207], v250, s[0:1] offset:256
	v_mul_f32_e32 v71, 0xbfb8aa3b, v71
	v_pk_mul_f32 v[68:69], v[68:69], v[80:81] op_sel_hi:[1,0]
	v_pk_mul_f32 v[66:67], v[66:67], v[80:81] op_sel_hi:[1,0]
; __device__ __forceinline__ unsigned cvt_pk_bf16(float lo, float hi) { const f32x2_cv v = {lo, hi}; const bf16x2_cv b = __builtin_convertvector(v, bf16x2_cv); return __builtin_bit_cast(unsigned, b); }
; __device__ __forceinline__ float sigm(float x) { return __builtin_amdgcn_rcpf(1.0f + __expf(-x)); }
; __device__ __forceinline__ float lo16(unsigned w) { return __uint_as_float(w << 16); }
; __device__ __forceinline__ float hi16(unsigned w) { return __uint_as_float(w & 0xffff0000u); }
; __device__ __forceinline__ float rstd_of(const float* rowss, int row) { return rsqrtf(rowss[row] * (1.0f / 1024.0f) + 1e-6f); }
;     __device__ __forceinline__ void operator()(const f32x4 (&acc)[2][2][4][2], const pg8::Unit& u, int wr, int wc, int fr, int fq) const {
;         const int row0 = u.pm * 256 + wr * 64 + fr, col0 = u.pn * 256 + wc * 32 + 8 * fq;
; #pragma unroll
;         for (int ai = 0; ai < 2; ++ai)
; #pragma unroll
;             for (int m = 0; m < 4; ++m) {
;                 const int row = row0 + ai * 128 + m * 16;
;                 const float s = rstd_of(rowss, row);
; #pragma unroll
;                 for (int bj = 0; bj < 2; ++bj) {
;                     const size_t off = (size_t)row * 1024 + col0 + bj * 128;
;                     const u32x4 tv = *(const u32x4*)(Tm + off);
;                     u32x4 pv = (u32x4){0u, 0u, 0u, 0u};
;                     if (ACC) pv = *(const u32x4*)(M + off);
;                     const f32x4 a0 = acc[ai][bj][m][0] * s, a1 = acc[ai][bj][m][1] * s;
;                     float o[8];
;                     o[0] = sigm(a0[0]) * lo16(tv.x); o[1] = sigm(a0[1]) * hi16(tv.x); o[2] = sigm(a0[2]) * lo16(tv.y); o[3] = sigm(a0[3]) * hi16(tv.y);
;                     o[4] = sigm(a1[0]) * lo16(tv.z); o[5] = sigm(a1[1]) * hi16(tv.z); o[6] = sigm(a1[2]) * lo16(tv.w); o[7] = sigm(a1[3]) * hi16(tv.w);
;                     if (ACC) { o[0] += lo16(pv.x); o[1] += hi16(pv.x); o[2] += lo16(pv.y); o[3] += hi16(pv.y); o[4] += lo16(pv.z); o[5] += hi16(pv.z); o[6] += lo16(pv.w); o[7] += hi16(pv.w); }
;                     u32x4 w; w.x = cvt_pk_bf16(o[0], o[1]); w.y = cvt_pk_bf16(o[2], o[3]); w.z = cvt_pk_bf16(o[4], o[5]); w.w = cvt_pk_bf16(o[6], o[7]);
;                     *(u32x4*)(M + off) = w; } }
;     }
	v_exp_f32_e32 v70, v70
	v_exp_f32_e32 v71, v71
	v_mul_f32_e32 v64, 0xbfb8aa3b, v64
	v_mul_f32_e32 v65, 0xbfb8aa3b, v65
	v_mul_f32_e32 v68, 0xbfb8aa3b, v68
	v_mul_f32_e32 v69, 0xbfb8aa3b, v69
	v_exp_f32_e32 v64, v64
	v_exp_f32_e32 v65, v65
	v_mul_f32_e32 v66, 0xbfb8aa3b, v66
	v_mul_f32_e32 v67, 0xbfb8aa3b, v67
	v_exp_f32_e32 v68, v68
	v_exp_f32_e32 v69, v69
	v_exp_f32_e32 v66, v66
	v_exp_f32_e32 v67, v67
	v_add_f32_e32 v70, 1.0, v70
	v_add_f32_e32 v71, 1.0, v71
	v_rcp_f32_e32 v70, v70
	v_rcp_f32_e32 v71, v71
	v_add_f32_e32 v64, 1.0, v64
	v_add_f32_e32 v65, 1.0, v65
	v_add_f32_e32 v68, 1.0, v68
	v_add_f32_e32 v69, 1.0, v69
	v_rcp_f32_e32 v64, v64
	v_rcp_f32_e32 v65, v65
	v_add_f32_e32 v66, 1.0, v66
	v_add_f32_e32 v67, 1.0, v67
	v_rcp_f32_e32 v68, v68
	v_rcp_f32_e32 v69, v69
	v_rcp_f32_e32 v66, v66
	v_rcp_f32_e32 v67, v67
	v_lshlrev_b32_e32 v80, 16, v76
	v_and_b32_e32 v81, 0xffff0000, v76
	v_lshlrev_b32_e32 v84, 16, v72
	v_and_b32_e32 v85, 0xffff0000, v72
	v_lshlrev_b32_e32 v76, 16, v77
	v_and_b32_e32 v77, 0xffff0000, v77
	v_lshlrev_b32_e32 v72, 16, v73
	v_and_b32_e32 v73, 0xffff0000, v73
	v_pk_fma_f32 v[70:71], v[70:71], v[76:77], v[72:73]
	v_lshlrev_b32_e32 v72, 16, v78
	v_and_b32_e32 v73, 0xffff0000, v78
	v_lshlrev_b32_e32 v76, 16, v74
	v_and_b32_e32 v77, 0xffff0000, v74
	v_pk_fma_f32 v[72:73], v[64:65], v[72:73], v[76:77]
	v_lshlrev_b32_e32 v64, 16, v79
	v_and_b32_e32 v65, 0xffff0000, v79
	v_lshlrev_b32_e32 v74, 16, v75
	v_and_b32_e32 v75, 0xffff0000, v75
	v_pk_fma_f32 v[68:69], v[68:69], v[80:81], v[84:85]
	v_pk_fma_f32 v[74:75], v[66:67], v[64:65], v[74:75]
	v_cvt_pk_bf16_f32 v64, v68, v69
	v_cvt_pk_bf16_f32 v65, v70, v71
	v_cvt_pk_bf16_f32 v66, v72, v73
	v_cvt_pk_bf16_f32 v67, v74, v75
	global_store_dwordx4 v[82:83], v[64:67], off
	s_nop 1
	v_mov_b32_e32 v64, v245
	v_lshl_add_u64 v[70:71], v[158:159], 0, s[2:3]
	v_lshl_add_u64 v[66:67], s[30:31], 0, v[70:71]
	v_lshl_add_u64 v[74:75], s[0:1], 0, v[70:71]
	s_waitcnt vmcnt(13)
	s_nop 1
	v_mov_b32_e32 v66, v208
	v_mov_b32_e32 v67, v209
	v_mov_b32_e32 v68, v210
	v_mov_b32_e32 v69, v211
	s_mov_b64 s[2:3], 0x40100
	s_nop 1
	v_mov_b32_e32 v70, v212
	v_mov_b32_e32 v71, v213
	v_mov_b32_e32 v72, v214
	v_mov_b32_e32 v73, v215
	v_fmamk_f32 v64, v64, 0x3a800000, v187
	v_cmp_gt_f32_e32 vcc, s67, v64
	v_mul_f32_e32 v65, 0x4b800000, v64
	v_lshlrev_b32_e32 v76, 16, v66
	v_cndmask_b32_e32 v64, v64, v65, vcc
	v_rsq_f32_e32 v64, v64
	v_and_b32_e32 v77, 0xffff0000, v66
	v_lshlrev_b32_e32 v78, 16, v70
	v_and_b32_e32 v79, 0xffff0000, v70
	v_mul_f32_e32 v65, 0x45800000, v64
	v_cndmask_b32_e32 v64, v64, v65, vcc
	v_pk_mul_f32 v[62:63], v[62:63], v[64:65] op_sel_hi:[1,0]
	v_pk_mul_f32 v[56:57], v[56:57], v[64:65] op_sel_hi:[1,0]
	v_mul_f32_e32 v62, 0xbfb8aa3b, v62
	v_mul_f32_e32 v63, 0xbfb8aa3b, v63
	v_pk_mul_f32 v[60:61], v[60:61], v[64:65] op_sel_hi:[1,0]
	v_pk_mul_f32 v[58:59], v[58:59], v[64:65] op_sel_hi:[1,0]
	v_exp_f32_e32 v62, v62
	v_exp_f32_e32 v63, v63
	v_mul_f32_e32 v56, 0xbfb8aa3b, v56
	v_mul_f32_e32 v57, 0xbfb8aa3b, v57
	v_mul_f32_e32 v60, 0xbfb8aa3b, v60
	v_mul_f32_e32 v61, 0xbfb8aa3b, v61
	v_exp_f32_e32 v56, v56
	v_exp_f32_e32 v57, v57
	v_mul_f32_e32 v58, 0xbfb8aa3b, v58
	v_mul_f32_e32 v59, 0xbfb8aa3b, v59
	v_exp_f32_e32 v60, v60
	v_exp_f32_e32 v61, v61
	v_exp_f32_e32 v58, v58
	v_exp_f32_e32 v59, v59
	v_add_f32_e32 v62, 1.0, v62
	v_add_f32_e32 v63, 1.0, v63
	v_rcp_f32_e32 v62, v62
	v_rcp_f32_e32 v63, v63
	v_add_f32_e32 v56, 1.0, v56
	v_add_f32_e32 v57, 1.0, v57
	v_add_f32_e32 v60, 1.0, v60
	v_add_f32_e32 v61, 1.0, v61
	v_rcp_f32_e32 v56, v56
	v_rcp_f32_e32 v57, v57
	v_add_f32_e32 v58, 1.0, v58
	v_add_f32_e32 v59, 1.0, v59
	v_rcp_f32_e32 v60, v60
	v_rcp_f32_e32 v61, v61
	v_rcp_f32_e32 v58, v58
	v_rcp_f32_e32 v59, v59
	v_lshlrev_b32_e32 v66, 16, v67
	v_and_b32_e32 v67, 0xffff0000, v67
	v_lshlrev_b32_e32 v70, 16, v71
	v_and_b32_e32 v71, 0xffff0000, v71
	v_pk_fma_f32 v[62:63], v[62:63], v[66:67], v[70:71]
	v_lshlrev_b32_e32 v66, 16, v68
	v_and_b32_e32 v67, 0xffff0000, v68
	v_lshlrev_b32_e32 v70, 16, v72
	v_and_b32_e32 v71, 0xffff0000, v72
	v_pk_fma_f32 v[66:67], v[56:57], v[66:67], v[70:71]
	v_lshlrev_b32_e32 v56, 16, v69
	v_and_b32_e32 v57, 0xffff0000, v69
	v_lshlrev_b32_e32 v68, 16, v73
	v_and_b32_e32 v69, 0xffff0000, v73
	v_pk_fma_f32 v[60:61], v[60:61], v[76:77], v[78:79]
	v_pk_fma_f32 v[68:69], v[58:59], v[56:57], v[68:69]
	v_cvt_pk_bf16_f32 v56, v60, v61
	v_cvt_pk_bf16_f32 v57, v62, v63
	v_cvt_pk_bf16_f32 v58, v66, v67
	v_cvt_pk_bf16_f32 v59, v68, v69
	global_store_dwordx4 v[74:75], v[56:59], off
	v_pk_mul_f32 v[54:55], v[54:55], v[64:65] op_sel_hi:[1,0]
	v_pk_mul_f32 v[48:49], v[48:49], v[64:65] op_sel_hi:[1,0]
	v_lshl_add_u64 v[56:57], v[158:159], 0, s[2:3]
	v_lshl_add_u64 v[58:59], s[30:31], 0, v[56:57]
	v_lshl_add_u64 v[66:67], s[0:1], 0, v[56:57]
	s_nop 1
	v_mov_b32_e32 v60, v216
	v_mov_b32_e32 v61, v217
	v_mov_b32_e32 v62, v218
	v_mov_b32_e32 v63, v219
	v_mul_f32_e32 v54, 0xbfb8aa3b, v54
	s_nop 1
	v_mov_b32_e32 v56, v220
	v_mov_b32_e32 v57, v221
	v_mov_b32_e32 v58, v222
	v_mov_b32_e32 v59, v223
	v_add_u32_e32 v250, 0x58000, v249
	global_load_dwordx4 v[208:211], v250, s[30:31]
	global_load_dwordx4 v[212:215], v250, s[0:1]
	global_load_dwordx4 v[216:219], v250, s[30:31] offset:256
	global_load_dwordx4 v[220:223], v250, s[0:1] offset:256
	v_mul_f32_e32 v55, 0xbfb8aa3b, v55
	v_pk_mul_f32 v[52:53], v[52:53], v[64:65] op_sel_hi:[1,0]
	v_pk_mul_f32 v[50:51], v[50:51], v[64:65] op_sel_hi:[1,0]
	v_exp_f32_e32 v54, v54
	v_exp_f32_e32 v55, v55
	v_mul_f32_e32 v48, 0xbfb8aa3b, v48
	v_mul_f32_e32 v49, 0xbfb8aa3b, v49
	v_mul_f32_e32 v52, 0xbfb8aa3b, v52
	v_mul_f32_e32 v53, 0xbfb8aa3b, v53
; __device__ __forceinline__ unsigned cvt_pk_bf16(float lo, float hi) { const f32x2_cv v = {lo, hi}; const bf16x2_cv b = __builtin_convertvector(v, bf16x2_cv); return __builtin_bit_cast(unsigned, b); }
; __device__ __forceinline__ float sigm(float x) { return __builtin_amdgcn_rcpf(1.0f + __expf(-x)); }
; __device__ __forceinline__ float lo16(unsigned w) { return __uint_as_float(w << 16); }
; __device__ __forceinline__ float hi16(unsigned w) { return __uint_as_float(w & 0xffff0000u); }
; __device__ __forceinline__ float rstd_of(const float* rowss, int row) { return rsqrtf(rowss[row] * (1.0f / 1024.0f) + 1e-6f); }
;     __device__ __forceinline__ void operator()(const f32x4 (&acc)[2][2][4][2], const pg8::Unit& u, int wr, int wc, int fr, int fq) const {
;         const int row0 = u.pm * 256 + wr * 64 + fr, col0 = u.pn * 256 + wc * 32 + 8 * fq;
; #pragma unroll
;         for (int ai = 0; ai < 2; ++ai)
; #pragma unroll
;             for (int m = 0; m < 4; ++m) {
;                 const int row = row0 + ai * 128 + m * 16;
;                 const float s = rstd_of(rowss, row);
; #pragma unroll
;                 for (int bj = 0; bj < 2; ++bj) {
;                     const size_t off = (size_t)row * 1024 + col0 + bj * 128;
;                     const u32x4 tv = *(const u32x4*)(Tm + off);
;                     u32x4 pv = (u32x4){0u, 0u, 0u, 0u};
;                     if (ACC) pv = *(const u32x4*)(M + off);
;                     const f32x4 a0 = acc[ai][bj][m][0] * s, a1 = acc[ai][bj][m][1] * s;
;                     float o[8];
;                     o[0] = sigm(a0[0]) * lo16(tv.x); o[1] = sigm(a0[1]) * hi16(tv.x); o[2] = sigm(a0[2]) * lo16(tv.y); o[3] = sigm(a0[3]) * hi16(tv.y);
;                     o[4] = sigm(a1[0]) * lo16(tv.z); o[5] = sigm(a1[1]) * hi16(tv.z); o[6] = sigm(a1[2]) * lo16(tv.w); o[7] = sigm(a1[3]) * hi16(tv.w);
;                     if (ACC) { o[0] += lo16(pv.x); o[1] += hi16(pv.x); o[2] += lo16(pv.y); o[3] += hi16(pv.y); o[4] += lo16(pv.z); o[5] += hi16(pv.z); o[6] += lo16(pv.w); o[7] += hi16(pv.w); }
;                     u32x4 w; w.x = cvt_pk_bf16(o[0], o[1]); w.y = cvt_pk_bf16(o[2], o[3]); w.z = cvt_pk_bf16(o[4], o[5]); w.w = cvt_pk_bf16(o[6], o[7]);
;                     *(u32x4*)(M + off) = w; } }
;     }
	v_exp_f32_e32 v48, v48
	v_exp_f32_e32 v49, v49
	v_mul_f32_e32 v50, 0xbfb8aa3b, v50
	v_mul_f32_e32 v51, 0xbfb8aa3b, v51
	v_exp_f32_e32 v52, v52
	v_exp_f32_e32 v53, v53
	v_exp_f32_e32 v50, v50
	v_exp_f32_e32 v51, v51
	v_add_f32_e32 v54, 1.0, v54
	v_add_f32_e32 v55, 1.0, v55
	v_rcp_f32_e32 v54, v54
	v_rcp_f32_e32 v55, v55
	v_add_f32_e32 v48, 1.0, v48
	v_add_f32_e32 v49, 1.0, v49
	v_add_f32_e32 v52, 1.0, v52
	v_add_f32_e32 v53, 1.0, v53
	v_rcp_f32_e32 v48, v48
	v_rcp_f32_e32 v49, v49
	v_add_f32_e32 v50, 1.0, v50
	v_add_f32_e32 v51, 1.0, v51
	v_rcp_f32_e32 v52, v52
	v_rcp_f32_e32 v53, v53
	v_rcp_f32_e32 v50, v50
	v_rcp_f32_e32 v51, v51
	s_mov_b64 s[2:3], 0x48000
	v_lshlrev_b32_e32 v64, 16, v60
	v_and_b32_e32 v65, 0xffff0000, v60
	v_lshlrev_b32_e32 v68, 16, v56
	v_and_b32_e32 v69, 0xffff0000, v56
	v_lshlrev_b32_e32 v60, 16, v61
	v_and_b32_e32 v61, 0xffff0000, v61
	v_lshlrev_b32_e32 v56, 16, v57
	v_and_b32_e32 v57, 0xffff0000, v57
	v_pk_fma_f32 v[54:55], v[54:55], v[60:61], v[56:57]
	v_lshlrev_b32_e32 v56, 16, v62
	v_and_b32_e32 v57, 0xffff0000, v62
	v_lshlrev_b32_e32 v60, 16, v58
	v_and_b32_e32 v61, 0xffff0000, v58
	v_pk_fma_f32 v[56:57], v[48:49], v[56:57], v[60:61]
	v_lshlrev_b32_e32 v48, 16, v63
	v_and_b32_e32 v49, 0xffff0000, v63
	v_lshlrev_b32_e32 v58, 16, v59
	v_and_b32_e32 v59, 0xffff0000, v59
	v_pk_fma_f32 v[52:53], v[52:53], v[64:65], v[68:69]
	v_pk_fma_f32 v[58:59], v[50:51], v[48:49], v[58:59]
	v_cvt_pk_bf16_f32 v48, v52, v53
	v_cvt_pk_bf16_f32 v49, v54, v55
	v_cvt_pk_bf16_f32 v50, v56, v57
	v_cvt_pk_bf16_f32 v51, v58, v59
	global_store_dwordx4 v[66:67], v[48:51], off
	s_nop 1
	v_mov_b32_e32 v48, v246
	v_lshl_add_u64 v[54:55], v[158:159], 0, s[2:3]
	v_lshl_add_u64 v[50:51], s[30:31], 0, v[54:55]
	v_lshl_add_u64 v[58:59], s[0:1], 0, v[54:55]
	s_waitcnt vmcnt(13)
	s_nop 1
	v_mov_b32_e32 v50, v224
	v_mov_b32_e32 v51, v225
	v_mov_b32_e32 v52, v226
	v_mov_b32_e32 v53, v227
	s_mov_b64 s[2:3], 0x48100
	s_nop 1
	v_mov_b32_e32 v54, v228
	v_mov_b32_e32 v55, v229
	v_mov_b32_e32 v56, v230
	v_mov_b32_e32 v57, v231
	v_fmamk_f32 v48, v48, 0x3a800000, v187
	v_cmp_gt_f32_e32 vcc, s67, v48
	v_mul_f32_e32 v49, 0x4b800000, v48
	v_lshlrev_b32_e32 v60, 16, v50
	v_cndmask_b32_e32 v48, v48, v49, vcc
	v_rsq_f32_e32 v48, v48
	v_and_b32_e32 v61, 0xffff0000, v50
	v_lshlrev_b32_e32 v62, 16, v54
	v_and_b32_e32 v63, 0xffff0000, v54
	v_mul_f32_e32 v49, 0x45800000, v48
	v_cndmask_b32_e32 v48, v48, v49, vcc
	v_pk_mul_f32 v[46:47], v[46:47], v[48:49] op_sel_hi:[1,0]
	v_pk_mul_f32 v[40:41], v[40:41], v[48:49] op_sel_hi:[1,0]
	v_mul_f32_e32 v46, 0xbfb8aa3b, v46
	v_mul_f32_e32 v47, 0xbfb8aa3b, v47
	v_pk_mul_f32 v[44:45], v[44:45], v[48:49] op_sel_hi:[1,0]
	v_pk_mul_f32 v[42:43], v[42:43], v[48:49] op_sel_hi:[1,0]
	v_exp_f32_e32 v46, v46
	v_exp_f32_e32 v47, v47
	v_mul_f32_e32 v40, 0xbfb8aa3b, v40
	v_mul_f32_e32 v41, 0xbfb8aa3b, v41
	v_mul_f32_e32 v44, 0xbfb8aa3b, v44
	v_mul_f32_e32 v45, 0xbfb8aa3b, v45
	v_exp_f32_e32 v40, v40
	v_exp_f32_e32 v41, v41
	v_mul_f32_e32 v42, 0xbfb8aa3b, v42
	v_mul_f32_e32 v43, 0xbfb8aa3b, v43
	v_exp_f32_e32 v44, v44
	v_exp_f32_e32 v45, v45
	v_exp_f32_e32 v42, v42
	v_exp_f32_e32 v43, v43
	v_add_f32_e32 v46, 1.0, v46
	v_add_f32_e32 v47, 1.0, v47
	v_rcp_f32_e32 v46, v46
	v_rcp_f32_e32 v47, v47
	v_add_f32_e32 v40, 1.0, v40
	v_add_f32_e32 v41, 1.0, v41
	v_add_f32_e32 v44, 1.0, v44
	v_add_f32_e32 v45, 1.0, v45
	v_rcp_f32_e32 v40, v40
	v_rcp_f32_e32 v41, v41
	v_add_f32_e32 v42, 1.0, v42
	v_add_f32_e32 v43, 1.0, v43
	v_rcp_f32_e32 v44, v44
	v_rcp_f32_e32 v45, v45
	v_rcp_f32_e32 v42, v42
	v_rcp_f32_e32 v43, v43
	v_lshlrev_b32_e32 v50, 16, v51
	v_and_b32_e32 v51, 0xffff0000, v51
	v_lshlrev_b32_e32 v54, 16, v55
	v_and_b32_e32 v55, 0xffff0000, v55
	v_pk_fma_f32 v[46:47], v[46:47], v[50:51], v[54:55]
	v_lshlrev_b32_e32 v50, 16, v52
	v_and_b32_e32 v51, 0xffff0000, v52
	v_lshlrev_b32_e32 v54, 16, v56
	v_and_b32_e32 v55, 0xffff0000, v56
	v_pk_fma_f32 v[50:51], v[40:41], v[50:51], v[54:55]
	v_lshlrev_b32_e32 v40, 16, v53
	v_and_b32_e32 v41, 0xffff0000, v53
	v_lshlrev_b32_e32 v52, 16, v57
	v_and_b32_e32 v53, 0xffff0000, v57
	v_pk_fma_f32 v[44:45], v[44:45], v[60:61], v[62:63]
	v_pk_fma_f32 v[52:53], v[42:43], v[40:41], v[52:53]
	v_cvt_pk_bf16_f32 v40, v44, v45
	v_cvt_pk_bf16_f32 v41, v46, v47
	v_cvt_pk_bf16_f32 v42, v50, v51
	v_cvt_pk_bf16_f32 v43, v52, v53
	global_store_dwordx4 v[58:59], v[40:43], off
	v_pk_mul_f32 v[38:39], v[38:39], v[48:49] op_sel_hi:[1,0]
	v_pk_mul_f32 v[32:33], v[32:33], v[48:49] op_sel_hi:[1,0]
	v_lshl_add_u64 v[40:41], v[158:159], 0, s[2:3]
	v_lshl_add_u64 v[42:43], s[30:31], 0, v[40:41]
	v_lshl_add_u64 v[50:51], s[0:1], 0, v[40:41]
	s_nop 1
	v_mov_b32_e32 v44, v232
	v_mov_b32_e32 v45, v233
	v_mov_b32_e32 v46, v234
	v_mov_b32_e32 v47, v235
	v_mul_f32_e32 v38, 0xbfb8aa3b, v38
	s_nop 1
	v_mov_b32_e32 v40, v236
	v_mov_b32_e32 v41, v237
	v_mov_b32_e32 v42, v238
	v_mov_b32_e32 v43, v239
	v_mul_f32_e32 v39, 0xbfb8aa3b, v39
	v_pk_mul_f32 v[36:37], v[36:37], v[48:49] op_sel_hi:[1,0]
	v_pk_mul_f32 v[34:35], v[34:35], v[48:49] op_sel_hi:[1,0]
	v_exp_f32_e32 v38, v38
	v_exp_f32_e32 v39, v39
	v_mul_f32_e32 v32, 0xbfb8aa3b, v32
	v_mul_f32_e32 v33, 0xbfb8aa3b, v33
	v_mul_f32_e32 v36, 0xbfb8aa3b, v36
	v_mul_f32_e32 v37, 0xbfb8aa3b, v37
	v_exp_f32_e32 v32, v32
	v_exp_f32_e32 v33, v33
	v_mul_f32_e32 v34, 0xbfb8aa3b, v34
	v_mul_f32_e32 v35, 0xbfb8aa3b, v35
	v_exp_f32_e32 v36, v36
	v_exp_f32_e32 v37, v37
	v_exp_f32_e32 v34, v34
	v_exp_f32_e32 v35, v35
	v_add_f32_e32 v38, 1.0, v38
	v_add_f32_e32 v39, 1.0, v39
	v_rcp_f32_e32 v38, v38
	v_rcp_f32_e32 v39, v39
	v_add_f32_e32 v32, 1.0, v32
	v_add_f32_e32 v33, 1.0, v33
	v_add_f32_e32 v36, 1.0, v36
	v_add_f32_e32 v37, 1.0, v37
	v_rcp_f32_e32 v32, v32
	v_rcp_f32_e32 v33, v33
	v_add_f32_e32 v34, 1.0, v34
	v_add_f32_e32 v35, 1.0, v35
	v_rcp_f32_e32 v36, v36
	v_rcp_f32_e32 v37, v37
	v_rcp_f32_e32 v34, v34
	v_rcp_f32_e32 v35, v35
	s_mov_b64 s[2:3], 0x50000
	v_lshlrev_b32_e32 v48, 16, v44
	v_and_b32_e32 v49, 0xffff0000, v44
	v_lshlrev_b32_e32 v52, 16, v40
	v_and_b32_e32 v53, 0xffff0000, v40
	v_lshlrev_b32_e32 v44, 16, v45
	v_and_b32_e32 v45, 0xffff0000, v45
	v_lshlrev_b32_e32 v40, 16, v41
	v_and_b32_e32 v41, 0xffff0000, v41
	v_pk_fma_f32 v[38:39], v[38:39], v[44:45], v[40:41]
	v_lshlrev_b32_e32 v40, 16, v46
	v_and_b32_e32 v41, 0xffff0000, v46
	v_lshlrev_b32_e32 v44, 16, v42
	v_and_b32_e32 v45, 0xffff0000, v42
	v_pk_fma_f32 v[40:41], v[32:33], v[40:41], v[44:45]
	v_lshlrev_b32_e32 v32, 16, v47
	v_and_b32_e32 v33, 0xffff0000, v47
	v_lshlrev_b32_e32 v42, 16, v43
	v_and_b32_e32 v43, 0xffff0000, v43
	v_pk_fma_f32 v[36:37], v[36:37], v[48:49], v[52:53]
	v_pk_fma_f32 v[42:43], v[34:35], v[32:33], v[42:43]
	v_cvt_pk_bf16_f32 v32, v36, v37
	v_cvt_pk_bf16_f32 v33, v38, v39
	v_cvt_pk_bf16_f32 v34, v40, v41
	v_cvt_pk_bf16_f32 v35, v42, v43
	global_store_dwordx4 v[50:51], v[32:35], off
	s_nop 1
	v_mov_b32_e32 v32, v247
	v_lshl_add_u64 v[38:39], v[158:159], 0, s[2:3]
	v_lshl_add_u64 v[34:35], s[30:31], 0, v[38:39]
	v_lshl_add_u64 v[42:43], s[0:1], 0, v[38:39]
	s_waitcnt vmcnt(9)
; __device__ __forceinline__ unsigned cvt_pk_bf16(float lo, float hi) { const f32x2_cv v = {lo, hi}; const bf16x2_cv b = __builtin_convertvector(v, bf16x2_cv); return __builtin_bit_cast(unsigned, b); }
; __device__ __forceinline__ float sigm(float x) { return __builtin_amdgcn_rcpf(1.0f + __expf(-x)); }
; __device__ __forceinline__ float lo16(unsigned w) { return __uint_as_float(w << 16); }
; __device__ __forceinline__ float hi16(unsigned w) { return __uint_as_float(w & 0xffff0000u); }
; __device__ __forceinline__ float rstd_of(const float* rowss, int row) { return rsqrtf(rowss[row] * (1.0f / 1024.0f) + 1e-6f); }
;     __device__ __forceinline__ void operator()(const f32x4 (&acc)[2][2][4][2], const pg8::Unit& u, int wr, int wc, int fr, int fq) const {
;         const int row0 = u.pm * 256 + wr * 64 + fr, col0 = u.pn * 256 + wc * 32 + 8 * fq;
; #pragma unroll
;         for (int ai = 0; ai < 2; ++ai)
; #pragma unroll
;             for (int m = 0; m < 4; ++m) {
;                 const int row = row0 + ai * 128 + m * 16;
;                 const float s = rstd_of(rowss, row);
; #pragma unroll
;                 for (int bj = 0; bj < 2; ++bj) {
;                     const size_t off = (size_t)row * 1024 + col0 + bj * 128;
;                     const u32x4 tv = *(const u32x4*)(Tm + off);
;                     u32x4 pv = (u32x4){0u, 0u, 0u, 0u};
;                     if (ACC) pv = *(const u32x4*)(M + off);
;                     const f32x4 a0 = acc[ai][bj][m][0] * s, a1 = acc[ai][bj][m][1] * s;
;                     float o[8];
;                     o[0] = sigm(a0[0]) * lo16(tv.x); o[1] = sigm(a0[1]) * hi16(tv.x); o[2] = sigm(a0[2]) * lo16(tv.y); o[3] = sigm(a0[3]) * hi16(tv.y);
;                     o[4] = sigm(a1[0]) * lo16(tv.z); o[5] = sigm(a1[1]) * hi16(tv.z); o[6] = sigm(a1[2]) * lo16(tv.w); o[7] = sigm(a1[3]) * hi16(tv.w);
;                     if (ACC) { o[0] += lo16(pv.x); o[1] += hi16(pv.x); o[2] += lo16(pv.y); o[3] += hi16(pv.y); o[4] += lo16(pv.z); o[5] += hi16(pv.z); o[6] += lo16(pv.w); o[7] += hi16(pv.w); }
;                     u32x4 w; w.x = cvt_pk_bf16(o[0], o[1]); w.y = cvt_pk_bf16(o[2], o[3]); w.z = cvt_pk_bf16(o[4], o[5]); w.w = cvt_pk_bf16(o[6], o[7]);
;                     *(u32x4*)(M + off) = w; } }
;     }
	s_nop 1
	v_mov_b32_e32 v34, v192
	v_mov_b32_e32 v35, v193
	v_mov_b32_e32 v36, v194
	v_mov_b32_e32 v37, v195
	s_mov_b64 s[2:3], 0x50100
	s_nop 1
	v_mov_b32_e32 v38, v196
	v_mov_b32_e32 v39, v197
	v_mov_b32_e32 v40, v198
	v_mov_b32_e32 v41, v199
	v_fmamk_f32 v32, v32, 0x3a800000, v187
	v_cmp_gt_f32_e32 vcc, s67, v32
	v_mul_f32_e32 v33, 0x4b800000, v32
	v_lshlrev_b32_e32 v44, 16, v34
	v_cndmask_b32_e32 v32, v32, v33, vcc
	v_rsq_f32_e32 v32, v32
	v_and_b32_e32 v45, 0xffff0000, v34
	v_lshlrev_b32_e32 v46, 16, v38
	v_and_b32_e32 v47, 0xffff0000, v38
	v_mul_f32_e32 v33, 0x45800000, v32
	v_cndmask_b32_e32 v32, v32, v33, vcc
	v_pk_mul_f32 v[30:31], v[30:31], v[32:33] op_sel_hi:[1,0]
	v_pk_mul_f32 v[24:25], v[24:25], v[32:33] op_sel_hi:[1,0]
	v_mul_f32_e32 v30, 0xbfb8aa3b, v30
	v_mul_f32_e32 v31, 0xbfb8aa3b, v31
	v_pk_mul_f32 v[28:29], v[28:29], v[32:33] op_sel_hi:[1,0]
	v_pk_mul_f32 v[26:27], v[26:27], v[32:33] op_sel_hi:[1,0]
	v_exp_f32_e32 v30, v30
	v_exp_f32_e32 v31, v31
	v_mul_f32_e32 v24, 0xbfb8aa3b, v24
	v_mul_f32_e32 v25, 0xbfb8aa3b, v25
	v_mul_f32_e32 v28, 0xbfb8aa3b, v28
	v_mul_f32_e32 v29, 0xbfb8aa3b, v29
	v_exp_f32_e32 v24, v24
	v_exp_f32_e32 v25, v25
	v_mul_f32_e32 v26, 0xbfb8aa3b, v26
	v_mul_f32_e32 v27, 0xbfb8aa3b, v27
	v_exp_f32_e32 v28, v28
	v_exp_f32_e32 v29, v29
	v_exp_f32_e32 v26, v26
	v_exp_f32_e32 v27, v27
	v_add_f32_e32 v30, 1.0, v30
	v_add_f32_e32 v31, 1.0, v31
	v_rcp_f32_e32 v30, v30
	v_rcp_f32_e32 v31, v31
	v_add_f32_e32 v24, 1.0, v24
	v_add_f32_e32 v25, 1.0, v25
	v_add_f32_e32 v28, 1.0, v28
	v_add_f32_e32 v29, 1.0, v29
	v_rcp_f32_e32 v24, v24
	v_rcp_f32_e32 v25, v25
	v_add_f32_e32 v26, 1.0, v26
	v_add_f32_e32 v27, 1.0, v27
	v_rcp_f32_e32 v28, v28
	v_rcp_f32_e32 v29, v29
	v_rcp_f32_e32 v26, v26
	v_rcp_f32_e32 v27, v27
	v_lshlrev_b32_e32 v34, 16, v35
	v_and_b32_e32 v35, 0xffff0000, v35
	v_lshlrev_b32_e32 v38, 16, v39
	v_and_b32_e32 v39, 0xffff0000, v39
	v_pk_fma_f32 v[30:31], v[30:31], v[34:35], v[38:39]
	v_lshlrev_b32_e32 v34, 16, v36
	v_and_b32_e32 v35, 0xffff0000, v36
	v_lshlrev_b32_e32 v38, 16, v40
	v_and_b32_e32 v39, 0xffff0000, v40
	v_pk_fma_f32 v[34:35], v[24:25], v[34:35], v[38:39]
	v_lshlrev_b32_e32 v24, 16, v37
	v_and_b32_e32 v25, 0xffff0000, v37
	v_lshlrev_b32_e32 v36, 16, v41
	v_and_b32_e32 v37, 0xffff0000, v41
	v_pk_fma_f32 v[28:29], v[28:29], v[44:45], v[46:47]
	v_pk_fma_f32 v[36:37], v[26:27], v[24:25], v[36:37]
	v_cvt_pk_bf16_f32 v24, v28, v29
	v_cvt_pk_bf16_f32 v25, v30, v31
	v_cvt_pk_bf16_f32 v26, v34, v35
	v_cvt_pk_bf16_f32 v27, v36, v37
	global_store_dwordx4 v[42:43], v[24:27], off
	v_pk_mul_f32 v[22:23], v[22:23], v[32:33] op_sel_hi:[1,0]
	v_pk_mul_f32 v[16:17], v[16:17], v[32:33] op_sel_hi:[1,0]
	v_lshl_add_u64 v[24:25], v[158:159], 0, s[2:3]
	v_lshl_add_u64 v[26:27], s[30:31], 0, v[24:25]
	v_lshl_add_u64 v[34:35], s[0:1], 0, v[24:25]
	s_nop 1
	v_mov_b32_e32 v28, v200
	v_mov_b32_e32 v29, v201
	v_mov_b32_e32 v30, v202
	v_mov_b32_e32 v31, v203
	v_mul_f32_e32 v22, 0xbfb8aa3b, v22
	s_nop 1
	v_mov_b32_e32 v24, v204
	v_mov_b32_e32 v25, v205
	v_mov_b32_e32 v26, v206
	v_mov_b32_e32 v27, v207
	v_mul_f32_e32 v23, 0xbfb8aa3b, v23
	v_pk_mul_f32 v[20:21], v[20:21], v[32:33] op_sel_hi:[1,0]
	v_pk_mul_f32 v[18:19], v[18:19], v[32:33] op_sel_hi:[1,0]
	v_exp_f32_e32 v22, v22
	v_exp_f32_e32 v23, v23
	v_mul_f32_e32 v16, 0xbfb8aa3b, v16
	v_mul_f32_e32 v17, 0xbfb8aa3b, v17
	v_mul_f32_e32 v20, 0xbfb8aa3b, v20
	v_mul_f32_e32 v21, 0xbfb8aa3b, v21
	v_exp_f32_e32 v16, v16
	v_exp_f32_e32 v17, v17
	v_mul_f32_e32 v18, 0xbfb8aa3b, v18
	v_mul_f32_e32 v19, 0xbfb8aa3b, v19
	v_exp_f32_e32 v20, v20
	v_exp_f32_e32 v21, v21
	v_exp_f32_e32 v18, v18
	v_exp_f32_e32 v19, v19
	v_add_f32_e32 v22, 1.0, v22
	v_add_f32_e32 v23, 1.0, v23
	v_rcp_f32_e32 v22, v22
	v_rcp_f32_e32 v23, v23
	v_add_f32_e32 v16, 1.0, v16
	v_add_f32_e32 v17, 1.0, v17
	v_add_f32_e32 v20, 1.0, v20
	v_add_f32_e32 v21, 1.0, v21
	v_rcp_f32_e32 v16, v16
	v_rcp_f32_e32 v17, v17
	v_add_f32_e32 v18, 1.0, v18
	v_add_f32_e32 v19, 1.0, v19
	v_rcp_f32_e32 v20, v20
	v_rcp_f32_e32 v21, v21
	v_rcp_f32_e32 v18, v18
	v_rcp_f32_e32 v19, v19
	s_mov_b64 s[2:3], 0x58000
	v_lshlrev_b32_e32 v32, 16, v28
	v_and_b32_e32 v33, 0xffff0000, v28
	v_lshlrev_b32_e32 v36, 16, v24
	v_and_b32_e32 v37, 0xffff0000, v24
	v_lshlrev_b32_e32 v28, 16, v29
	v_and_b32_e32 v29, 0xffff0000, v29
	v_lshlrev_b32_e32 v24, 16, v25
	v_and_b32_e32 v25, 0xffff0000, v25
	v_pk_fma_f32 v[22:23], v[22:23], v[28:29], v[24:25]
	v_lshlrev_b32_e32 v24, 16, v30
	v_and_b32_e32 v25, 0xffff0000, v30
	v_lshlrev_b32_e32 v28, 16, v26
	v_and_b32_e32 v29, 0xffff0000, v26
	v_pk_fma_f32 v[24:25], v[16:17], v[24:25], v[28:29]
	v_lshlrev_b32_e32 v16, 16, v31
	v_and_b32_e32 v17, 0xffff0000, v31
	v_lshlrev_b32_e32 v26, 16, v27
	v_and_b32_e32 v27, 0xffff0000, v27
	v_pk_fma_f32 v[20:21], v[20:21], v[32:33], v[36:37]
	v_pk_fma_f32 v[26:27], v[18:19], v[16:17], v[26:27]
	v_cvt_pk_bf16_f32 v16, v20, v21
	v_cvt_pk_bf16_f32 v17, v22, v23
	v_cvt_pk_bf16_f32 v18, v24, v25
	v_cvt_pk_bf16_f32 v19, v26, v27
	global_store_dwordx4 v[34:35], v[16:19], off
	s_nop 1
	v_mov_b32_e32 v16, v248
	v_lshl_add_u64 v[22:23], v[158:159], 0, s[2:3]
	v_lshl_add_u64 v[18:19], s[30:31], 0, v[22:23]
	v_lshl_add_u64 v[26:27], s[0:1], 0, v[22:23]
	s_waitcnt vmcnt(5)
; __device__ __forceinline__ unsigned cvt_pk_bf16(float lo, float hi) { const f32x2_cv v = {lo, hi}; const bf16x2_cv b = __builtin_convertvector(v, bf16x2_cv); return __builtin_bit_cast(unsigned, b); }
; __device__ __forceinline__ float sigm(float x) { return __builtin_amdgcn_rcpf(1.0f + __expf(-x)); }
; __device__ __forceinline__ float lo16(unsigned w) { return __uint_as_float(w << 16); }
; __device__ __forceinline__ float hi16(unsigned w) { return __uint_as_float(w & 0xffff0000u); }
; __device__ __forceinline__ float rstd_of(const float* rowss, int row) { return rsqrtf(rowss[row] * (1.0f / 1024.0f) + 1e-6f); }
;     __device__ __forceinline__ void operator()(const f32x4 (&acc)[2][2][4][2], const pg8::Unit& u, int wr, int wc, int fr, int fq) const {
;         const int row0 = u.pm * 256 + wr * 64 + fr, col0 = u.pn * 256 + wc * 32 + 8 * fq;
; #pragma unroll
;         for (int ai = 0; ai < 2; ++ai)
; #pragma unroll
;             for (int m = 0; m < 4; ++m) {
;                 const int row = row0 + ai * 128 + m * 16;
;                 const float s = rstd_of(rowss, row);
; #pragma unroll
;                 for (int bj = 0; bj < 2; ++bj) {
;                     const size_t off = (size_t)row * 1024 + col0 + bj * 128;
;                     const u32x4 tv = *(const u32x4*)(Tm + off);
;                     u32x4 pv = (u32x4){0u, 0u, 0u, 0u};
;                     if (ACC) pv = *(const u32x4*)(M + off);
;                     const f32x4 a0 = acc[ai][bj][m][0] * s, a1 = acc[ai][bj][m][1] * s;
;                     float o[8];
;                     o[0] = sigm(a0[0]) * lo16(tv.x); o[1] = sigm(a0[1]) * hi16(tv.x); o[2] = sigm(a0[2]) * lo16(tv.y); o[3] = sigm(a0[3]) * hi16(tv.y);
;                     o[4] = sigm(a1[0]) * lo16(tv.z); o[5] = sigm(a1[1]) * hi16(tv.z); o[6] = sigm(a1[2]) * lo16(tv.w); o[7] = sigm(a1[3]) * hi16(tv.w);
;                     if (ACC) { o[0] += lo16(pv.x); o[1] += hi16(pv.x); o[2] += lo16(pv.y); o[3] += hi16(pv.y); o[4] += lo16(pv.z); o[5] += hi16(pv.z); o[6] += lo16(pv.w); o[7] += hi16(pv.w); }
;                     u32x4 w; w.x = cvt_pk_bf16(o[0], o[1]); w.y = cvt_pk_bf16(o[2], o[3]); w.z = cvt_pk_bf16(o[4], o[5]); w.w = cvt_pk_bf16(o[6], o[7]);
;                     *(u32x4*)(M + off) = w; } }
;     }
	s_nop 1
	v_mov_b32_e32 v18, v208
	v_mov_b32_e32 v19, v209
	v_mov_b32_e32 v20, v210
	v_mov_b32_e32 v21, v211
	s_mov_b64 s[2:3], 0x58100
	s_nop 1
	v_mov_b32_e32 v22, v212
	v_mov_b32_e32 v23, v213
	v_mov_b32_e32 v24, v214
	v_mov_b32_e32 v25, v215
	v_fmamk_f32 v16, v16, 0x3a800000, v187
	v_cmp_gt_f32_e32 vcc, s67, v16
	v_mul_f32_e32 v17, 0x4b800000, v16
	v_lshlrev_b32_e32 v28, 16, v18
	v_cndmask_b32_e32 v16, v16, v17, vcc
	v_rsq_f32_e32 v16, v16
	v_and_b32_e32 v29, 0xffff0000, v18
	v_lshlrev_b32_e32 v30, 16, v22
	v_and_b32_e32 v31, 0xffff0000, v22
	v_mul_f32_e32 v17, 0x45800000, v16
	v_cndmask_b32_e32 v16, v16, v17, vcc
	v_pk_mul_f32 v[14:15], v[14:15], v[16:17] op_sel_hi:[1,0]
	v_pk_mul_f32 v[8:9], v[8:9], v[16:17] op_sel_hi:[1,0]
	v_mul_f32_e32 v14, 0xbfb8aa3b, v14
	v_mul_f32_e32 v15, 0xbfb8aa3b, v15
	v_pk_mul_f32 v[12:13], v[12:13], v[16:17] op_sel_hi:[1,0]
	v_pk_mul_f32 v[10:11], v[10:11], v[16:17] op_sel_hi:[1,0]
	v_exp_f32_e32 v14, v14
	v_exp_f32_e32 v15, v15
	v_mul_f32_e32 v8, 0xbfb8aa3b, v8
	v_mul_f32_e32 v9, 0xbfb8aa3b, v9
	v_mul_f32_e32 v12, 0xbfb8aa3b, v12
	v_mul_f32_e32 v13, 0xbfb8aa3b, v13
	v_exp_f32_e32 v8, v8
	v_exp_f32_e32 v9, v9
	v_mul_f32_e32 v10, 0xbfb8aa3b, v10
	v_mul_f32_e32 v11, 0xbfb8aa3b, v11
	v_exp_f32_e32 v12, v12
	v_exp_f32_e32 v13, v13
	v_exp_f32_e32 v10, v10
	v_exp_f32_e32 v11, v11
	v_add_f32_e32 v14, 1.0, v14
	v_add_f32_e32 v15, 1.0, v15
	v_rcp_f32_e32 v14, v14
	v_rcp_f32_e32 v15, v15
	v_add_f32_e32 v8, 1.0, v8
	v_add_f32_e32 v9, 1.0, v9
	v_add_f32_e32 v12, 1.0, v12
	v_add_f32_e32 v13, 1.0, v13
	v_rcp_f32_e32 v8, v8
	v_rcp_f32_e32 v9, v9
	v_add_f32_e32 v10, 1.0, v10
	v_add_f32_e32 v11, 1.0, v11
	v_rcp_f32_e32 v12, v12
	v_rcp_f32_e32 v13, v13
	v_rcp_f32_e32 v10, v10
	v_rcp_f32_e32 v11, v11
	v_lshlrev_b32_e32 v18, 16, v19
	v_and_b32_e32 v19, 0xffff0000, v19
	v_lshlrev_b32_e32 v22, 16, v23
	v_and_b32_e32 v23, 0xffff0000, v23
	v_pk_fma_f32 v[14:15], v[14:15], v[18:19], v[22:23]
	v_lshlrev_b32_e32 v18, 16, v20
	v_and_b32_e32 v19, 0xffff0000, v20
	v_lshlrev_b32_e32 v22, 16, v24
	v_and_b32_e32 v23, 0xffff0000, v24
	v_pk_fma_f32 v[18:19], v[8:9], v[18:19], v[22:23]
	v_lshlrev_b32_e32 v8, 16, v21
	v_and_b32_e32 v9, 0xffff0000, v21
	v_lshlrev_b32_e32 v20, 16, v25
	v_and_b32_e32 v21, 0xffff0000, v25
	v_pk_fma_f32 v[12:13], v[12:13], v[28:29], v[30:31]
	v_pk_fma_f32 v[20:21], v[10:11], v[8:9], v[20:21]
	v_cvt_pk_bf16_f32 v8, v12, v13
	v_cvt_pk_bf16_f32 v9, v14, v15
	v_cvt_pk_bf16_f32 v10, v18, v19
	v_cvt_pk_bf16_f32 v11, v20, v21
	global_store_dwordx4 v[26:27], v[8:11], off
	v_pk_mul_f32 v[6:7], v[6:7], v[16:17] op_sel_hi:[1,0]
	v_pk_mul_f32 v[0:1], v[0:1], v[16:17] op_sel_hi:[1,0]
	v_lshl_add_u64 v[8:9], v[158:159], 0, s[2:3]
	v_lshl_add_u64 v[10:11], s[30:31], 0, v[8:9]
	v_lshl_add_u64 v[18:19], s[0:1], 0, v[8:9]
	s_nop 1
	v_mov_b32_e32 v12, v216
	v_mov_b32_e32 v13, v217
	v_mov_b32_e32 v14, v218
	v_mov_b32_e32 v15, v219
	v_mul_f32_e32 v6, 0xbfb8aa3b, v6
	s_nop 1
	v_mov_b32_e32 v8, v220
	v_mov_b32_e32 v9, v221
	v_mov_b32_e32 v10, v222
	v_mov_b32_e32 v11, v223
	v_mul_f32_e32 v7, 0xbfb8aa3b, v7
	v_pk_mul_f32 v[4:5], v[4:5], v[16:17] op_sel_hi:[1,0]
	v_pk_mul_f32 v[2:3], v[2:3], v[16:17] op_sel_hi:[1,0]
	v_exp_f32_e32 v6, v6
	v_exp_f32_e32 v7, v7
	v_mul_f32_e32 v0, 0xbfb8aa3b, v0
	v_mul_f32_e32 v1, 0xbfb8aa3b, v1
	v_mul_f32_e32 v4, 0xbfb8aa3b, v4
	v_mul_f32_e32 v5, 0xbfb8aa3b, v5
	v_exp_f32_e32 v0, v0
	v_exp_f32_e32 v1, v1
	v_mul_f32_e32 v2, 0xbfb8aa3b, v2
	v_mul_f32_e32 v3, 0xbfb8aa3b, v3
	v_exp_f32_e32 v4, v4
	v_exp_f32_e32 v5, v5
	v_exp_f32_e32 v2, v2
	v_exp_f32_e32 v3, v3
	v_add_f32_e32 v6, 1.0, v6
	v_add_f32_e32 v7, 1.0, v7
	v_rcp_f32_e32 v6, v6
	v_rcp_f32_e32 v7, v7
	v_add_f32_e32 v0, 1.0, v0
	v_add_f32_e32 v1, 1.0, v1
	v_add_f32_e32 v4, 1.0, v4
	v_add_f32_e32 v5, 1.0, v5
	v_rcp_f32_e32 v0, v0
	v_rcp_f32_e32 v1, v1
	v_add_f32_e32 v2, 1.0, v2
	v_add_f32_e32 v3, 1.0, v3
	v_rcp_f32_e32 v4, v4
	v_rcp_f32_e32 v5, v5
	v_rcp_f32_e32 v2, v2
	v_rcp_f32_e32 v3, v3
	s_and_b64 vcc, exec, s[38:39]
	s_mov_b32 s3, s26
	s_mov_b32 s2, s12
	v_lshlrev_b32_e32 v16, 16, v12
	v_and_b32_e32 v17, 0xffff0000, v12
	v_lshlrev_b32_e32 v20, 16, v8
	v_and_b32_e32 v21, 0xffff0000, v8
	v_lshlrev_b32_e32 v12, 16, v13
	v_and_b32_e32 v13, 0xffff0000, v13
	v_lshlrev_b32_e32 v8, 16, v9
	v_and_b32_e32 v9, 0xffff0000, v9
	v_pk_fma_f32 v[6:7], v[6:7], v[12:13], v[8:9]
	v_lshlrev_b32_e32 v8, 16, v14
	v_and_b32_e32 v9, 0xffff0000, v14
	v_lshlrev_b32_e32 v12, 16, v10
	v_and_b32_e32 v13, 0xffff0000, v10
	v_pk_fma_f32 v[8:9], v[0:1], v[8:9], v[12:13]
	v_lshlrev_b32_e32 v0, 16, v15
	v_and_b32_e32 v1, 0xffff0000, v15
	v_lshlrev_b32_e32 v10, 16, v11
	v_and_b32_e32 v11, 0xffff0000, v11
	v_pk_fma_f32 v[4:5], v[4:5], v[16:17], v[20:21]
	v_pk_fma_f32 v[10:11], v[2:3], v[0:1], v[10:11]
	v_cvt_pk_bf16_f32 v0, v4, v5
	v_cvt_pk_bf16_f32 v1, v6, v7
	v_cvt_pk_bf16_f32 v2, v8, v9
	v_cvt_pk_bf16_f32 v3, v10, v11
	global_store_dwordx4 v[18:19], v[0:3], off
	s_cbranch_vccz .LBB0_346
	s_cmpk_gt_u32 s70, 0xff
	s_cbranch_scc1 .LBB0_357
	s_barrier

; #define PG8_STAGE(bufoff, gbase, voff) do { _Pragma("unroll") for (int _i = 0; _i < 2; ++_i) \
;         __builtin_amdgcn_global_load_lds((const unsigned*)((const char*)(gbase) + (voff)[_i]), (PG8_LAS unsigned*)(lds + (bufoff) + ldsw + _i * 8192), 16, 0, 0); } while (0)
; #define PG8_WAIT_V(n) asm volatile("s_waitcnt vmcnt(" #n ")" ::: "memory")
; #define PG8_BAR __builtin_amdgcn_s_barrier()
; template <class Epi, class Sched, bool STAMP = false>
; __device__ __forceinline__ void gemm_phase(PG8_LAS unsigned char* lds, const Gemm g, const Sched& S, const Epi& E, unsigned long long* stamps) {
;     ...
;     f32x4 acc[2][2][4][2];
; #pragma unroll
;     for (int a = 0; a < 2; ++a)
; #pragma unroll
;         for (int b = 0; b < 2; ++b)
; #pragma unroll
;             for (int m = 0; m < 4; ++m)
; #pragma unroll
;                 for (int n = 0; n < 2; ++n) acc[a][b][m][n] = (f32x4){0.f, 0.f, 0.f, 0.f};
;     bf16x8 At[4][2], B0[2][2], B1[2][2];
;     const char* cA = (const char*)g.A + (size_t)cur.pm * tstep; const char* cB = (const char*)g.Bt + (size_t)cur.pn * tstep;
;     S.a_ready(cur);
;     PG8_STAGE(PG8_SB(0, 0), cB, voffB); PG8_STAGE(PG8_SA(0, 0), cA, voffA); PG8_STAGE(PG8_SB(0, 1), cB + hstep, voffB); PG8_STAGE(PG8_SA(0, 1), cA + hstep, voffA);
;     if (wr == 1) PG8_BAR;
;     PG8_WAIT_V(4); PG8_BAR;
;     PG8_STAGE(PG8_SB(1, 0), cB + kstep, voffB); PG8_STAGE(PG8_SA(1, 0), cA + kstep, voffA); PG8_STAGE(PG8_SB(1, 1), cB + hstep + kstep, voffB);
;     PG8_WAIT_V(6); PG8_BAR;
.LBB0_373:
	v_bfe_u32 v139, v0, 4, 2
	s_lshl_b32 s14, s14, 5
	v_and_b32_e32 v150, 15, v0
	v_lshlrev_b32_e32 v1, 4, v139
	v_lshlrev_b32_e32 v0, 2, v0
	s_and_b32 s53, s14, 0x60
	v_lshl_add_u64 v[2:3], s[4:5], 0, v[128:129]
	v_mov_b32_e32 v149, v129
	s_lshl_b32 s49, s15, 6
	v_lshl_or_b32 v1, v150, 6, v1
	s_lshl_b32 s15, s15, 13
	v_and_b32_e32 v0, 32, v0
	s_lshl_b32 s14, s53, 7
	v_lshl_add_u64 v[4:5], s[4:5], 0, v[148:149]
	v_bitop3_b32 v14, v1, s15, v0 bitop3:0xde
	v_bitop3_b32 v151, v1, s14, v0 bitop3:0xde
	s_add_i32 m0, s42, 0x18000
	v_lshl_add_u64 v[0:1], v[2:3], 0, s[18:19]
	v_lshl_add_u64 v[6:7], s[6:7], 0, v[128:129]
	s_waitcnt vmcnt(4)
	s_barrier
	global_load_lds_dwordx4 v[0:1], off
	v_lshl_add_u64 v[0:1], v[4:5], 0, s[18:19]
	s_add_i32 m0, s42, 0x1a000
	s_add_i32 s56, s42, 0x8000
	v_lshl_add_u64 v[8:9], s[6:7], 0, v[148:149]
	global_load_lds_dwordx4 v[0:1], off
	v_lshl_add_u64 v[0:1], v[6:7], 0, s[18:19]
	s_mov_b32 m0, s56
	s_add_i32 s57, s42, 0xa000
	v_lshl_add_u64 v[10:11], s[20:21], 0, v[128:129]
	global_load_lds_dwordx4 v[0:1], off
	v_lshl_add_u64 v[0:1], v[8:9], 0, s[18:19]
	s_mov_b32 m0, s57
	v_lshl_add_u64 v[12:13], s[20:21], 0, v[148:149]
	global_load_lds_dwordx4 v[0:1], off
	s_add_i32 m0, s42, 0x1c000
	v_lshl_add_u64 v[0:1], v[10:11], 0, s[18:19]
	global_load_lds_dwordx4 v[0:1], off
	v_lshl_add_u64 v[0:1], v[12:13], 0, s[18:19]
	s_add_i32 m0, s42, 0x1e000
	s_mov_b32 s14, 0
	global_load_lds_dwordx4 v[0:1], off
	s_waitcnt vmcnt(6)
	v_mov_b32_e32 v0, 0
	s_mov_b64 s[20:21], -1
	s_mov_b64 s[22:23], 0
	v_add_u32_e32 v152, 0, v14
	v_mov_b32_e32 v1, v0
	v_mov_b32_e32 v2, v0
	v_mov_b32_e32 v3, v0
	v_mov_b32_e32 v4, v0
	v_mov_b32_e32 v5, v0
	v_mov_b32_e32 v6, v0
	v_mov_b32_e32 v7, v0
	v_mov_b32_e32 v8, v0
	v_mov_b32_e32 v9, v0
	v_mov_b32_e32 v10, v0
	v_mov_b32_e32 v11, v0
	v_mov_b32_e32 v12, v0
	v_mov_b32_e32 v13, v0
	v_mov_b32_e32 v14, v0
	v_mov_b32_e32 v15, v0
	v_mov_b32_e32 v24, v0
	v_mov_b32_e32 v25, v0
	v_mov_b32_e32 v26, v0
	v_mov_b32_e32 v27, v0
	v_mov_b32_e32 v28, v0
	v_mov_b32_e32 v29, v0
	v_mov_b32_e32 v30, v0
	v_mov_b32_e32 v31, v0
	v_mov_b32_e32 v40, v0
	v_mov_b32_e32 v41, v0
	v_mov_b32_e32 v42, v0
	v_mov_b32_e32 v43, v0
	v_mov_b32_e32 v44, v0
	v_mov_b32_e32 v45, v0
	v_mov_b32_e32 v46, v0
	v_mov_b32_e32 v47, v0
	v_mov_b32_e32 v16, v0
	v_mov_b32_e32 v17, v0
	v_mov_b32_e32 v18, v0
	v_mov_b32_e32 v19, v0
	v_mov_b32_e32 v20, v0
	v_mov_b32_e32 v21, v0
	v_mov_b32_e32 v22, v0
	v_mov_b32_e32 v23, v0
	v_mov_b32_e32 v32, v0
	v_mov_b32_e32 v33, v0
	v_mov_b32_e32 v34, v0
	v_mov_b32_e32 v35, v0
	v_mov_b32_e32 v36, v0
	v_mov_b32_e32 v37, v0
	v_mov_b32_e32 v38, v0
	v_mov_b32_e32 v39, v0
	v_mov_b32_e32 v48, v0
	v_mov_b32_e32 v49, v0
	v_mov_b32_e32 v50, v0
	v_mov_b32_e32 v51, v0
	v_mov_b32_e32 v52, v0
	v_mov_b32_e32 v53, v0
	v_mov_b32_e32 v54, v0
	v_mov_b32_e32 v55, v0
	v_mov_b32_e32 v56, v0
	v_mov_b32_e32 v57, v0
	v_mov_b32_e32 v58, v0
	v_mov_b32_e32 v59, v0
	v_mov_b32_e32 v60, v0
	v_mov_b32_e32 v61, v0
	v_mov_b32_e32 v62, v0
	v_mov_b32_e32 v63, v0
	v_mov_b32_e32 v64, v0
	v_mov_b32_e32 v65, v0
	v_mov_b32_e32 v66, v0
	v_mov_b32_e32 v67, v0
	v_mov_b32_e32 v68, v0
	v_mov_b32_e32 v69, v0
	v_mov_b32_e32 v70, v0
	v_mov_b32_e32 v71, v0
	v_mov_b32_e32 v72, v0
	v_mov_b32_e32 v73, v0
	v_mov_b32_e32 v74, v0
	v_mov_b32_e32 v75, v0
	v_mov_b32_e32 v76, v0
	v_mov_b32_e32 v77, v0
	v_mov_b32_e32 v78, v0
	v_mov_b32_e32 v79, v0
	v_mov_b32_e32 v84, v0
	v_mov_b32_e32 v85, v0
	v_mov_b32_e32 v86, v0
	v_mov_b32_e32 v87, v0
	v_mov_b32_e32 v92, v0
	v_mov_b32_e32 v93, v0
	v_mov_b32_e32 v94, v0
	v_mov_b32_e32 v95, v0
	v_mov_b32_e32 v100, v0
	v_mov_b32_e32 v101, v0
	v_mov_b32_e32 v102, v0
	v_mov_b32_e32 v103, v0
	v_mov_b32_e32 v108, v0
	v_mov_b32_e32 v109, v0
	v_mov_b32_e32 v110, v0
	v_mov_b32_e32 v111, v0
	v_mov_b32_e32 v80, v0
	v_mov_b32_e32 v81, v0
	v_mov_b32_e32 v82, v0
	v_mov_b32_e32 v83, v0
	v_mov_b32_e32 v88, v0
	v_mov_b32_e32 v89, v0
	v_mov_b32_e32 v90, v0
	v_mov_b32_e32 v91, v0
	v_mov_b32_e32 v96, v0
	v_mov_b32_e32 v97, v0
	v_mov_b32_e32 v98, v0
	v_mov_b32_e32 v99, v0
	v_mov_b32_e32 v104, v0
	v_mov_b32_e32 v105, v0
	v_mov_b32_e32 v106, v0
	v_mov_b32_e32 v107, v0
	v_mov_b32_e32 v112, v0
	v_mov_b32_e32 v113, v0
	v_mov_b32_e32 v114, v0
	v_mov_b32_e32 v115, v0
	v_mov_b32_e32 v116, v0
	v_mov_b32_e32 v117, v0
	v_mov_b32_e32 v118, v0
	v_mov_b32_e32 v119, v0
	v_mov_b32_e32 v120, v0
	v_mov_b32_e32 v121, v0
	v_mov_b32_e32 v122, v0
	v_mov_b32_e32 v123, v0
	v_mov_b32_e32 v124, v0
	v_mov_b32_e32 v125, v0
	v_mov_b32_e32 v126, v0
	v_mov_b32_e32 v127, v0
	s_barrier
	v_add_u32_e32 v244, 0x80, v128
	v_add_u32_e32 v245, 0x80, v148
	v_add_u32_e32 v248, 0x10000, v151
	v_add_u32_e32 v249, 0x14000, v151
	v_add_u32_e32 v250, 0x18000, v151
	v_add_u32_e32 v251, 0x1c000, v151
; #define PG8_STAGE(bufoff, gbase, voff) do { _Pragma("unroll") for (int _i = 0; _i < 2; ++_i) \
;         __builtin_amdgcn_global_load_lds((const unsigned*)((const char*)(gbase) + (voff)[_i]), (PG8_LAS unsigned*)(lds + (bufoff) + ldsw + _i * 8192), 16, 0, 0); } while (0)
; #define PG8_LDA(dst, b, h) do { _Pragma("unroll") for (int m = 0; m < 4; ++m) _Pragma("unroll") for (int k = 0; k < 2; ++k) dst[m][k] = *(const PG8_LAS bf16x8*)(lds + PG8_SA(b, h) + aoff + m * 2048 + k * 1024); } while (0)
; #define PG8_LDB(dst, b, h) do { _Pragma("unroll") for (int n = 0; n < 2; ++n) _Pragma("unroll") for (int k = 0; k < 2; ++k) dst[n][k] = *(const PG8_LAS bf16x8*)(lds + PG8_SB(b, h) + boff + n * 2048 + k * 1024); } while (0)
; #define PG8_MMA(ai, bj, At, Bt) do { __builtin_amdgcn_s_setprio(1); _Pragma("unroll") for (int m = 0; m < 4; ++m) _Pragma("unroll") for (int n = 0; n < 2; ++n) _Pragma("unroll") for (int k = 0; k < 2; ++k) \
;         acc[ai][bj][m][n] = __builtin_amdgcn_mfma_f32_16x16x32_bf16(Bt[n][k], At[m][k], acc[ai][bj][m][n], 0, 0, 0); __builtin_amdgcn_s_setprio(0); } while (0)
; #define PG8_WAIT_L(n) asm volatile("s_waitcnt lgkmcnt(" #n ")" ::: "memory")
; #define PG8_BAR __builtin_amdgcn_s_barrier()
; #define PG8_SCHED __builtin_amdgcn_sched_barrier(0)
; template <class Epi, class Sched, bool STAMP = false>
; __device__ __forceinline__ void gemm_phase(PG8_LAS unsigned char* lds, const Gemm g, const Sched& S, const Epi& E, unsigned long long* stamps) {
;     ...
;         for (int t = 0; t < nt; t += 2) {
;             const bool last = (t == nt - 2);
;             const char* a1 = cA + (size_t)(t + 1) * kstep;
;             const char* a2 = last ? nA : cA + (size_t)(t + 2) * kstep; const char* b2 = last ? nB : cB + (size_t)(t + 2) * kstep;
;             const char* a3 = a2 + kstep; const char* b3 = b2 + kstep;
;             if (last && has_next) S.a_ready(nxt);
;             PG8_LDB(B0, 0, 0); PG8_SCHED; PG8_LDA(At, 0, 0); PG8_STAGE(PG8_SA(1, 1), a1 + hstep, voffA);
;             PG8_WAIT_L(8); PG8_BAR; PG8_WAIT_L(0); PG8_MMA(0, 0, At, B0); PG8_BAR; PG8_SCHED;
;             PG8_LDB(B1, 0, 1); PG8_STAGE(PG8_SB(0, 0), b2, voffB);
;             PG8_BAR; PG8_WAIT_L(0); PG8_MMA(0, 1, At, B1); PG8_BAR;
;             PG8_LDA(At, 0, 1); PG8_STAGE(PG8_SA(0, 0), a2, voffA);
;             PG8_BAR; PG8_WAIT_L(0); PG8_MMA(1, 0, At, B0); PG8_BAR; PG8_SCHED;
.LBB0_374:
	s_add_i32 s15, s14, 0x100
	s_and_b64 s[16:17], s[22:23], exec
	s_cselect_b32 s15, 0, s15
	s_cselect_b32 s16, 0, 0
	s_add_u32 s26, s6, s15
	s_addc_u32 s27, s7, s16
	s_add_i32 s52, 0, 0x10000
	s_add_u32 s30, s4, s15
	s_addc_u32 s31, s5, s16
	s_add_u32 s36, s12, s14
	s_addc_u32 s37, s13, 0
	s_add_i32 s62, s52, s46
	s_add_i32 m0, s42, 0xc000
	s_add_i32 s61, s42, 0xe000
	s_add_i32 s60, 0, 0x14000
	s_add_i32 s59, s62, 0x2000
	ds_read_b128 v[154:157], v248
	ds_read_b128 v[158:161], v248 offset:1024
	ds_read_b128 v[162:165], v248 offset:2048
	ds_read_b128 v[166:169], v248 offset:3072
	s_add_u32 s24, s30, s45
	s_addc_u32 s25, s31, 0
	s_add_i32 s29, s60, s46
	s_add_i32 s17, s29, 0x2000
	s_add_i32 s16, 0, 0x18000
	s_add_u32 s22, s26, s45
	s_addc_u32 s23, s27, 0
	s_add_i32 s14, 0, 0x1c000
	s_add_i32 s15, s16, s46
	s_add_i32 s58, s14, s46
	s_add_i32 s63, s15, 0x2000
	s_add_i32 s52, s58, 0x2000
	v_lshl_add_u64 v[182:183], s[36:37], 0, v[128:129]
	v_lshl_add_u64 v[182:183], v[182:183], 0, s[18:19]
	ds_read_b128 v[170:173], v152
	ds_read_b128 v[174:177], v152 offset:1024
	ds_read_b128 v[178:181], v152 offset:2048
	ds_read_b128 v[192:195], v152 offset:3072
	ds_read_b128 v[196:199], v152 offset:4096
	ds_read_b128 v[200:203], v152 offset:5120
	ds_read_b128 v[204:207], v152 offset:6144
	ds_read_b128 v[208:211], v152 offset:7168
	global_load_lds_dwordx4 v244, s[36:37]
	v_lshl_add_u64 v[182:183], s[36:37], 0, v[148:149]
	v_lshl_add_u64 v[182:183], v[182:183], 0, s[18:19]
	s_mov_b32 m0, s61
	s_nop 0
	global_load_lds_dwordx4 v245, s[36:37]
	s_waitcnt lgkmcnt(8)
	s_barrier
	s_waitcnt lgkmcnt(0)
	v_mfma_f32_16x16x32_bf16 v[124:127], v[154:157], v[170:173], v[124:127]
	v_mfma_f32_16x16x32_bf16 v[120:123], v[162:165], v[170:173], v[120:123]
	v_mfma_f32_16x16x32_bf16 v[116:119], v[154:157], v[178:181], v[116:119]
	v_mfma_f32_16x16x32_bf16 v[112:115], v[162:165], v[178:181], v[112:115]
	v_mfma_f32_16x16x32_bf16 v[104:107], v[154:157], v[196:199], v[104:107]
	v_mfma_f32_16x16x32_bf16 v[96:99], v[162:165], v[196:199], v[96:99]
	v_mfma_f32_16x16x32_bf16 v[88:91], v[154:157], v[204:207], v[88:91]
	v_mfma_f32_16x16x32_bf16 v[80:83], v[162:165], v[204:207], v[80:83]
	v_mfma_f32_16x16x32_bf16 v[124:127], v[158:161], v[174:177], v[124:127]
	v_mfma_f32_16x16x32_bf16 v[120:123], v[166:169], v[174:177], v[120:123]
	v_mfma_f32_16x16x32_bf16 v[116:119], v[158:161], v[192:195], v[116:119]
	v_mfma_f32_16x16x32_bf16 v[112:115], v[166:169], v[192:195], v[112:115]
	v_mfma_f32_16x16x32_bf16 v[104:107], v[158:161], v[200:203], v[104:107]
	v_mfma_f32_16x16x32_bf16 v[96:99], v[166:169], v[200:203], v[96:99]
	v_mfma_f32_16x16x32_bf16 v[88:91], v[158:161], v[208:211], v[88:91]
	v_mfma_f32_16x16x32_bf16 v[80:83], v[166:169], v[208:211], v[80:83]
	s_barrier
	s_mov_b32 m0, s62
	v_lshl_add_u64 v[182:183], s[30:31], 0, v[128:129]
	ds_read_b128 v[212:215], v249
	ds_read_b128 v[216:219], v249 offset:1024
	ds_read_b128 v[220:223], v249 offset:2048
	ds_read_b128 v[224:227], v249 offset:3072
	global_load_lds_dwordx4 v128, s[30:31]
	v_lshl_add_u64 v[228:229], s[30:31], 0, v[148:149]
	s_mov_b32 m0, s59
	s_nop 0
	global_load_lds_dwordx4 v148, s[30:31]
	s_barrier
	s_waitcnt lgkmcnt(0)
	v_mfma_f32_16x16x32_bf16 v[108:111], v[212:215], v[170:173], v[108:111]
	v_mfma_f32_16x16x32_bf16 v[100:103], v[220:223], v[170:173], v[100:103]
	v_mfma_f32_16x16x32_bf16 v[92:95], v[212:215], v[178:181], v[92:95]
	v_mfma_f32_16x16x32_bf16 v[84:87], v[220:223], v[178:181], v[84:87]
	v_mfma_f32_16x16x32_bf16 v[76:79], v[212:215], v[196:199], v[76:79]
	v_mfma_f32_16x16x32_bf16 v[72:75], v[220:223], v[196:199], v[72:75]
	v_mfma_f32_16x16x32_bf16 v[68:71], v[212:215], v[204:207], v[68:71]
	v_mfma_f32_16x16x32_bf16 v[64:67], v[220:223], v[204:207], v[64:67]
	v_mfma_f32_16x16x32_bf16 v[108:111], v[216:219], v[174:177], v[108:111]
	v_mfma_f32_16x16x32_bf16 v[100:103], v[224:227], v[174:177], v[100:103]
	v_mfma_f32_16x16x32_bf16 v[92:95], v[216:219], v[192:195], v[92:95]
	v_mfma_f32_16x16x32_bf16 v[84:87], v[224:227], v[192:195], v[84:87]
	v_mfma_f32_16x16x32_bf16 v[76:79], v[216:219], v[200:203], v[76:79]
	v_mfma_f32_16x16x32_bf16 v[72:75], v[224:227], v[200:203], v[72:75]
	v_mfma_f32_16x16x32_bf16 v[68:71], v[216:219], v[208:211], v[68:71]
	v_mfma_f32_16x16x32_bf16 v[64:67], v[224:227], v[208:211], v[64:67]
	s_mov_b32 m0, s42
	v_lshl_add_u64 v[230:231], s[26:27], 0, v[128:129]
	s_barrier
	ds_read_b128 v[170:173], v152 offset:16384
	ds_read_b128 v[174:177], v152 offset:17408
	ds_read_b128 v[178:181], v152 offset:18432
	ds_read_b128 v[192:195], v152 offset:19456
	ds_read_b128 v[196:199], v152 offset:20480
	ds_read_b128 v[200:203], v152 offset:21504
	ds_read_b128 v[204:207], v152 offset:22528
	ds_read_b128 v[208:211], v152 offset:23552
	global_load_lds_dwordx4 v128, s[26:27]
	v_lshl_add_u64 v[232:233], s[26:27], 0, v[148:149]
	s_mov_b32 m0, s43
	s_nop 0
	global_load_lds_dwordx4 v148, s[26:27]
	s_barrier
	s_waitcnt lgkmcnt(0)
	v_mfma_f32_16x16x32_bf16 v[60:63], v[154:157], v[170:173], v[60:63]
	v_mfma_f32_16x16x32_bf16 v[56:59], v[162:165], v[170:173], v[56:59]
	v_mfma_f32_16x16x32_bf16 v[52:55], v[154:157], v[178:181], v[52:55]
	v_mfma_f32_16x16x32_bf16 v[48:51], v[162:165], v[178:181], v[48:51]
	v_mfma_f32_16x16x32_bf16 v[36:39], v[154:157], v[196:199], v[36:39]
	v_mfma_f32_16x16x32_bf16 v[32:35], v[162:165], v[196:199], v[32:35]
	v_mfma_f32_16x16x32_bf16 v[20:23], v[154:157], v[204:207], v[20:23]
	v_mfma_f32_16x16x32_bf16 v[16:19], v[162:165], v[204:207], v[16:19]
	v_mfma_f32_16x16x32_bf16 v[60:63], v[158:161], v[174:177], v[60:63]
	v_mfma_f32_16x16x32_bf16 v[56:59], v[166:169], v[174:177], v[56:59]
	v_mfma_f32_16x16x32_bf16 v[52:55], v[158:161], v[192:195], v[52:55]
	v_mfma_f32_16x16x32_bf16 v[48:51], v[166:169], v[192:195], v[48:51]
	v_mfma_f32_16x16x32_bf16 v[36:39], v[158:161], v[200:203], v[36:39]
	v_mfma_f32_16x16x32_bf16 v[32:35], v[166:169], v[200:203], v[32:35]
	v_mfma_f32_16x16x32_bf16 v[20:23], v[158:161], v[208:211], v[20:23]
	v_mfma_f32_16x16x32_bf16 v[16:19], v[166:169], v[208:211], v[16:19]
	s_barrier
; #define PG8_STAGE(bufoff, gbase, voff) do { _Pragma("unroll") for (int _i = 0; _i < 2; ++_i) \
;         __builtin_amdgcn_global_load_lds((const unsigned*)((const char*)(gbase) + (voff)[_i]), (PG8_LAS unsigned*)(lds + (bufoff) + ldsw + _i * 8192), 16, 0, 0); } while (0)
; #define PG8_LDA(dst, b, h) do { _Pragma("unroll") for (int m = 0; m < 4; ++m) _Pragma("unroll") for (int k = 0; k < 2; ++k) dst[m][k] = *(const PG8_LAS bf16x8*)(lds + PG8_SA(b, h) + aoff + m * 2048 + k * 1024); } while (0)
; #define PG8_LDB(dst, b, h) do { _Pragma("unroll") for (int n = 0; n < 2; ++n) _Pragma("unroll") for (int k = 0; k < 2; ++k) dst[n][k] = *(const PG8_LAS bf16x8*)(lds + PG8_SB(b, h) + boff + n * 2048 + k * 1024); } while (0)
; #define PG8_MMA(ai, bj, At, Bt) do { __builtin_amdgcn_s_setprio(1); _Pragma("unroll") for (int m = 0; m < 4; ++m) _Pragma("unroll") for (int n = 0; n < 2; ++n) _Pragma("unroll") for (int k = 0; k < 2; ++k) \
;         acc[ai][bj][m][n] = __builtin_amdgcn_mfma_f32_16x16x32_bf16(Bt[n][k], At[m][k], acc[ai][bj][m][n], 0, 0, 0); __builtin_amdgcn_s_setprio(0); } while (0)
; #define PG8_WAIT_V(n) asm volatile("s_waitcnt vmcnt(" #n ")" ::: "memory")
; #define PG8_WAIT_L(n) asm volatile("s_waitcnt lgkmcnt(" #n ")" ::: "memory")
; #define PG8_BAR __builtin_amdgcn_s_barrier()
; #define PG8_SCHED __builtin_amdgcn_sched_barrier(0)
; template <class Epi, class Sched, bool STAMP = false>
; __device__ __forceinline__ void gemm_phase(PG8_LAS unsigned char* lds, const Gemm g, const Sched& S, const Epi& E, unsigned long long* stamps) {
;     ...
;             PG8_BAR; PG8_WAIT_L(0); PG8_MMA(1, 0, At, B0); PG8_BAR; PG8_SCHED;
;             PG8_STAGE(PG8_SB(0, 1), b2 + hstep, voffB);
;             PG8_WAIT_V(6); PG8_BAR; PG8_MMA(1, 1, At, B1); PG8_BAR;
;             PG8_LDB(B0, 1, 0); PG8_SCHED; PG8_LDA(At, 1, 0); PG8_STAGE(PG8_SA(0, 1), a2 + hstep, voffA);
;             PG8_WAIT_L(8); PG8_BAR; PG8_WAIT_L(0); PG8_MMA(0, 0, At, B0); PG8_BAR; PG8_SCHED;
;             PG8_LDB(B1, 1, 1); PG8_STAGE(PG8_SB(1, 0), b3, voffB);
;             PG8_BAR; PG8_WAIT_L(0); PG8_MMA(0, 1, At, B1); PG8_BAR;
;             PG8_LDA(At, 1, 1); PG8_STAGE(PG8_SA(1, 0), a3, voffA);
;             PG8_BAR; PG8_WAIT_L(0); PG8_MMA(1, 0, At, B0); PG8_BAR; PG8_SCHED;
	s_mov_b32 m0, s29
	s_nop 0
	global_load_lds_dwordx4 v128, s[24:25]
	s_mov_b32 m0, s17
	s_nop 0
	global_load_lds_dwordx4 v148, s[24:25]
	s_waitcnt vmcnt(6)
	s_barrier
	v_mfma_f32_16x16x32_bf16 v[44:47], v[212:215], v[170:173], v[44:47]
	v_mfma_f32_16x16x32_bf16 v[40:43], v[220:223], v[170:173], v[40:43]
	v_mfma_f32_16x16x32_bf16 v[28:31], v[212:215], v[178:181], v[28:31]
	v_mfma_f32_16x16x32_bf16 v[24:27], v[220:223], v[178:181], v[24:27]
	v_mfma_f32_16x16x32_bf16 v[12:15], v[212:215], v[196:199], v[12:15]
	v_mfma_f32_16x16x32_bf16 v[8:11], v[220:223], v[196:199], v[8:11]
	v_mfma_f32_16x16x32_bf16 v[4:7], v[212:215], v[204:207], v[4:7]
	v_mfma_f32_16x16x32_bf16 v[0:3], v[220:223], v[204:207], v[0:3]
	v_mfma_f32_16x16x32_bf16 v[44:47], v[216:219], v[174:177], v[44:47]
	v_mfma_f32_16x16x32_bf16 v[40:43], v[224:227], v[174:177], v[40:43]
	v_mfma_f32_16x16x32_bf16 v[28:31], v[216:219], v[192:195], v[28:31]
	v_mfma_f32_16x16x32_bf16 v[24:27], v[224:227], v[192:195], v[24:27]
	v_mfma_f32_16x16x32_bf16 v[12:15], v[216:219], v[200:203], v[12:15]
	v_mfma_f32_16x16x32_bf16 v[8:11], v[224:227], v[200:203], v[8:11]
	v_mfma_f32_16x16x32_bf16 v[4:7], v[216:219], v[208:211], v[4:7]
	v_mfma_f32_16x16x32_bf16 v[0:3], v[224:227], v[208:211], v[0:3]
	s_barrier
	ds_read_b128 v[154:157], v250
	ds_read_b128 v[158:161], v250 offset:1024
	ds_read_b128 v[162:165], v250 offset:2048
	ds_read_b128 v[166:169], v250 offset:3072
	s_mov_b32 m0, s47
	ds_read_b128 v[170:173], v152 offset:32768
	ds_read_b128 v[174:177], v152 offset:33792
	ds_read_b128 v[178:181], v152 offset:34816
	ds_read_b128 v[192:195], v152 offset:35840
	ds_read_b128 v[196:199], v152 offset:36864
	ds_read_b128 v[200:203], v152 offset:37888
	ds_read_b128 v[204:207], v152 offset:38912
	ds_read_b128 v[208:211], v152 offset:39936
	global_load_lds_dwordx4 v128, s[22:23]
	s_mov_b32 m0, s48
	s_nop 0
	global_load_lds_dwordx4 v148, s[22:23]
	s_waitcnt lgkmcnt(8)
	s_barrier
	s_waitcnt lgkmcnt(0)
	v_mfma_f32_16x16x32_bf16 v[124:127], v[154:157], v[170:173], v[124:127]
	v_mfma_f32_16x16x32_bf16 v[120:123], v[162:165], v[170:173], v[120:123]
	v_mfma_f32_16x16x32_bf16 v[116:119], v[154:157], v[178:181], v[116:119]
	v_mfma_f32_16x16x32_bf16 v[112:115], v[162:165], v[178:181], v[112:115]
	v_mfma_f32_16x16x32_bf16 v[104:107], v[154:157], v[196:199], v[104:107]
	v_mfma_f32_16x16x32_bf16 v[96:99], v[162:165], v[196:199], v[96:99]
	v_mfma_f32_16x16x32_bf16 v[88:91], v[154:157], v[204:207], v[88:91]
	v_mfma_f32_16x16x32_bf16 v[80:83], v[162:165], v[204:207], v[80:83]
	v_mfma_f32_16x16x32_bf16 v[124:127], v[158:161], v[174:177], v[124:127]
	v_mfma_f32_16x16x32_bf16 v[120:123], v[166:169], v[174:177], v[120:123]
	v_mfma_f32_16x16x32_bf16 v[116:119], v[158:161], v[192:195], v[116:119]
	v_mfma_f32_16x16x32_bf16 v[112:115], v[166:169], v[192:195], v[112:115]
	v_mfma_f32_16x16x32_bf16 v[104:107], v[158:161], v[200:203], v[104:107]
	v_mfma_f32_16x16x32_bf16 v[96:99], v[166:169], v[200:203], v[96:99]
	v_mfma_f32_16x16x32_bf16 v[88:91], v[158:161], v[208:211], v[88:91]
	v_mfma_f32_16x16x32_bf16 v[80:83], v[166:169], v[208:211], v[80:83]
	s_barrier
	s_mov_b32 m0, s15
	v_lshl_add_u64 v[182:183], v[182:183], 0, s[18:19]
	ds_read_b128 v[212:215], v251
	ds_read_b128 v[216:219], v251 offset:1024
	ds_read_b128 v[220:223], v251 offset:2048
	ds_read_b128 v[224:227], v251 offset:3072
	global_load_lds_dwordx4 v244, s[30:31]
	v_lshl_add_u64 v[182:183], v[228:229], 0, s[18:19]
	s_mov_b32 m0, s63
	s_nop 0
	global_load_lds_dwordx4 v245, s[30:31]
	s_barrier
	s_waitcnt lgkmcnt(0)
	v_mfma_f32_16x16x32_bf16 v[108:111], v[212:215], v[170:173], v[108:111]
	v_mfma_f32_16x16x32_bf16 v[100:103], v[220:223], v[170:173], v[100:103]
	v_mfma_f32_16x16x32_bf16 v[92:95], v[212:215], v[178:181], v[92:95]
	v_mfma_f32_16x16x32_bf16 v[84:87], v[220:223], v[178:181], v[84:87]
	v_mfma_f32_16x16x32_bf16 v[76:79], v[212:215], v[196:199], v[76:79]
	v_mfma_f32_16x16x32_bf16 v[72:75], v[220:223], v[196:199], v[72:75]
	v_mfma_f32_16x16x32_bf16 v[68:71], v[212:215], v[204:207], v[68:71]
	v_mfma_f32_16x16x32_bf16 v[64:67], v[220:223], v[204:207], v[64:67]
	v_mfma_f32_16x16x32_bf16 v[108:111], v[216:219], v[174:177], v[108:111]
	v_mfma_f32_16x16x32_bf16 v[100:103], v[224:227], v[174:177], v[100:103]
	v_mfma_f32_16x16x32_bf16 v[92:95], v[216:219], v[192:195], v[92:95]
	v_mfma_f32_16x16x32_bf16 v[84:87], v[224:227], v[192:195], v[84:87]
	v_mfma_f32_16x16x32_bf16 v[76:79], v[216:219], v[200:203], v[76:79]
	v_mfma_f32_16x16x32_bf16 v[72:75], v[224:227], v[200:203], v[72:75]
	v_mfma_f32_16x16x32_bf16 v[68:71], v[216:219], v[208:211], v[68:71]
	v_mfma_f32_16x16x32_bf16 v[64:67], v[224:227], v[208:211], v[64:67]
	s_mov_b32 m0, s56
	v_lshl_add_u64 v[182:183], v[230:231], 0, s[18:19]
	s_barrier
	ds_read_b128 v[170:173], v152 offset:49152
	ds_read_b128 v[174:177], v152 offset:50176
	ds_read_b128 v[178:181], v152 offset:51200
	ds_read_b128 v[192:195], v152 offset:52224
	ds_read_b128 v[196:199], v152 offset:53248
	ds_read_b128 v[200:203], v152 offset:54272
	ds_read_b128 v[204:207], v152 offset:55296
	ds_read_b128 v[208:211], v152 offset:56320
	global_load_lds_dwordx4 v244, s[26:27]
	v_lshl_add_u64 v[182:183], v[232:233], 0, s[18:19]
	s_mov_b32 m0, s57
	s_nop 0
	global_load_lds_dwordx4 v245, s[26:27]
	s_barrier
; #define PG8_STAGE(bufoff, gbase, voff) do { _Pragma("unroll") for (int _i = 0; _i < 2; ++_i) \
;         __builtin_amdgcn_global_load_lds((const unsigned*)((const char*)(gbase) + (voff)[_i]), (PG8_LAS unsigned*)(lds + (bufoff) + ldsw + _i * 8192), 16, 0, 0); } while (0)
; #define PG8_MMA(ai, bj, At, Bt) do { __builtin_amdgcn_s_setprio(1); _Pragma("unroll") for (int m = 0; m < 4; ++m) _Pragma("unroll") for (int n = 0; n < 2; ++n) _Pragma("unroll") for (int k = 0; k < 2; ++k) \
;         acc[ai][bj][m][n] = __builtin_amdgcn_mfma_f32_16x16x32_bf16(Bt[n][k], At[m][k], acc[ai][bj][m][n], 0, 0, 0); __builtin_amdgcn_s_setprio(0); } while (0)
; #define PG8_WAIT_V(n) asm volatile("s_waitcnt vmcnt(" #n ")" ::: "memory")
; #define PG8_WAIT_L(n) asm volatile("s_waitcnt lgkmcnt(" #n ")" ::: "memory")
; #define PG8_BAR __builtin_amdgcn_s_barrier()
; #define PG8_SCHED __builtin_amdgcn_sched_barrier(0)
; template <class Epi, class Sched, bool STAMP = false>
; __device__ __forceinline__ void gemm_phase(PG8_LAS unsigned char* lds, const Gemm g, const Sched& S, const Epi& E, unsigned long long* stamps) {
;     ...
;             PG8_BAR; PG8_WAIT_L(0); PG8_MMA(1, 0, At, B0); PG8_BAR; PG8_SCHED;
;             PG8_STAGE(PG8_SB(1, 1), b3 + hstep, voffB);
;             PG8_WAIT_V(6); PG8_BAR; PG8_MMA(1, 1, At, B1); PG8_BAR;
;         }
;         if constexpr (!Epi::AFTER_DRAIN) { E(acc, cur, wr, wc, fr, fq); S.done(cur); }
;     __device__ __forceinline__ void operator()(const f32x4 (&acc)[2][2][4][2], const pg8::Unit& u, int wr, int wc, int fr, int fq) const {
;         const int row0 = (u.pm - 64) * 256 + wr * 64 + fr, col0 = u.pn * 256 + wc * 32 + 4 * fq;
; #pragma unroll
;         for (int ai = 0; ai < 2; ++ai)
; #pragma unroll
;             for (int m = 0; m < 4; ++m) { float* xp = PART + (size_t)(row0 + ai * 128 + m * 16) * ldp + col0;
; #pragma unroll
;                 for (int bj = 0; bj < 2; ++bj)
; #pragma unroll
;                     for (int n = 0; n < 2; ++n) *(f32x4*)(xp + bj * 128 + n * 16) = acc[ai][bj][m][n]; }
;     }
	s_waitcnt lgkmcnt(0)
	v_mfma_f32_16x16x32_bf16 v[60:63], v[154:157], v[170:173], v[60:63]
	v_mfma_f32_16x16x32_bf16 v[56:59], v[162:165], v[170:173], v[56:59]
	v_mfma_f32_16x16x32_bf16 v[52:55], v[154:157], v[178:181], v[52:55]
	v_mfma_f32_16x16x32_bf16 v[48:51], v[162:165], v[178:181], v[48:51]
	v_mfma_f32_16x16x32_bf16 v[36:39], v[154:157], v[196:199], v[36:39]
	v_mfma_f32_16x16x32_bf16 v[32:35], v[162:165], v[196:199], v[32:35]
	v_mfma_f32_16x16x32_bf16 v[20:23], v[154:157], v[204:207], v[20:23]
	v_mfma_f32_16x16x32_bf16 v[16:19], v[162:165], v[204:207], v[16:19]
	v_mfma_f32_16x16x32_bf16 v[60:63], v[158:161], v[174:177], v[60:63]
	v_mfma_f32_16x16x32_bf16 v[56:59], v[166:169], v[174:177], v[56:59]
	v_mfma_f32_16x16x32_bf16 v[52:55], v[158:161], v[192:195], v[52:55]
	v_mfma_f32_16x16x32_bf16 v[48:51], v[166:169], v[192:195], v[48:51]
	v_mfma_f32_16x16x32_bf16 v[36:39], v[158:161], v[200:203], v[36:39]
	v_mfma_f32_16x16x32_bf16 v[32:35], v[166:169], v[200:203], v[32:35]
	v_mfma_f32_16x16x32_bf16 v[20:23], v[158:161], v[208:211], v[20:23]
	v_mfma_f32_16x16x32_bf16 v[16:19], v[166:169], v[208:211], v[16:19]
	s_barrier
	s_mov_b32 m0, s58
	s_nop 0
	global_load_lds_dwordx4 v244, s[24:25]
	s_mov_b32 m0, s52
	s_nop 0
	global_load_lds_dwordx4 v245, s[24:25]
	s_waitcnt vmcnt(6)
	s_barrier
	v_mfma_f32_16x16x32_bf16 v[44:47], v[212:215], v[170:173], v[44:47]
	v_mfma_f32_16x16x32_bf16 v[40:43], v[220:223], v[170:173], v[40:43]
	v_mfma_f32_16x16x32_bf16 v[28:31], v[212:215], v[178:181], v[28:31]
	v_mfma_f32_16x16x32_bf16 v[24:27], v[220:223], v[178:181], v[24:27]
	v_mfma_f32_16x16x32_bf16 v[12:15], v[212:215], v[196:199], v[12:15]
	v_mfma_f32_16x16x32_bf16 v[8:11], v[220:223], v[196:199], v[8:11]
	v_mfma_f32_16x16x32_bf16 v[4:7], v[212:215], v[204:207], v[4:7]
	v_mfma_f32_16x16x32_bf16 v[0:3], v[220:223], v[204:207], v[0:3]
	v_mfma_f32_16x16x32_bf16 v[44:47], v[216:219], v[174:177], v[44:47]
	v_mfma_f32_16x16x32_bf16 v[40:43], v[224:227], v[174:177], v[40:43]
	v_mfma_f32_16x16x32_bf16 v[28:31], v[216:219], v[192:195], v[28:31]
	v_mfma_f32_16x16x32_bf16 v[24:27], v[224:227], v[192:195], v[24:27]
	v_mfma_f32_16x16x32_bf16 v[12:15], v[216:219], v[200:203], v[12:15]
	v_mfma_f32_16x16x32_bf16 v[8:11], v[224:227], v[200:203], v[8:11]
	v_mfma_f32_16x16x32_bf16 v[4:7], v[216:219], v[208:211], v[4:7]
	v_mfma_f32_16x16x32_bf16 v[0:3], v[224:227], v[208:211], v[0:3]
	s_andn2_b64 vcc, exec, s[20:21]
	s_mov_b64 s[22:23], -1
	s_mov_b64 s[20:21], 0
	s_movk_i32 s14, 0x100
	s_barrier
	s_cbranch_vccz .LBB0_374
	s_lshl_b64 s[4:5], s[10:11], 22
	s_add_u32 s4, s2, s4
	s_addc_u32 s5, s3, s5
	s_lshl_b32 s6, s44, 8
	s_addk_i32 s6, 0xc000
	v_or_b32_e32 v128, s6, v150
	v_add_u32_e32 v148, s49, v128
	s_lshl_b32 s6, s39, 8
	v_lshl_or_b32 v128, v139, 2, s6
	v_ashrrev_i32_e32 v149, 31, v148
	v_or_b32_e32 v128, s53, v128
	v_lshlrev_b64 v[150:151], 12, v[148:149]
	v_lshl_add_u64 v[150:151], s[4:5], 0, v[150:151]
	v_lshlrev_b32_e32 v128, 2, v128
	v_lshl_add_u64 v[150:151], v[150:151], 0, v[128:129]
	global_store_dwordx4 v[150:151], v[124:127], off
	global_store_dwordx4 v[150:151], v[120:123], off offset:64
	global_store_dwordx4 v[150:151], v[108:111], off offset:512
	global_store_dwordx4 v[150:151], v[100:103], off offset:576
	s_cmpk_lt_u32 s38, 0x100
	s_nop 0
	v_or_b32_e32 v100, 16, v148
	v_ashrrev_i32_e32 v101, 31, v100
	v_lshlrev_b64 v[100:101], 12, v[100:101]
	v_lshl_add_u64 v[100:101], s[4:5], 0, v[100:101]
	v_lshl_add_u64 v[100:101], v[100:101], 0, v[128:129]
	global_store_dwordx4 v[100:101], v[116:119], off
	global_store_dwordx4 v[100:101], v[112:115], off offset:64
	global_store_dwordx4 v[100:101], v[92:95], off offset:512
	global_store_dwordx4 v[100:101], v[84:87], off offset:576
	s_nop 1
	v_or_b32_e32 v84, 32, v148
	v_ashrrev_i32_e32 v85, 31, v84
	v_lshlrev_b64 v[84:85], 12, v[84:85]
	v_lshl_add_u64 v[84:85], s[4:5], 0, v[84:85]
	v_lshl_add_u64 v[84:85], v[84:85], 0, v[128:129]
	global_store_dwordx4 v[84:85], v[104:107], off
	global_store_dwordx4 v[84:85], v[96:99], off offset:64
	global_store_dwordx4 v[84:85], v[76:79], off offset:512
	global_store_dwordx4 v[84:85], v[72:75], off offset:576
	s_nop 1
	v_or_b32_e32 v72, 48, v148
	v_ashrrev_i32_e32 v73, 31, v72
	v_lshlrev_b64 v[72:73], 12, v[72:73]
	v_lshl_add_u64 v[72:73], s[4:5], 0, v[72:73]
	v_lshl_add_u64 v[72:73], v[72:73], 0, v[128:129]
	s_mov_b64 s[4:5], 0x80000
	global_store_dwordx4 v[72:73], v[88:91], off
	global_store_dwordx4 v[72:73], v[80:83], off offset:64
	global_store_dwordx4 v[72:73], v[68:71], off offset:512
	global_store_dwordx4 v[72:73], v[64:67], off offset:576
	s_nop 1
	v_lshl_add_u64 v[64:65], v[150:151], 0, s[4:5]
	s_mov_b32 s4, 0x80000
	v_add_co_u32_e32 v66, vcc, s4, v150
	s_mov_b64 s[4:5], 0x90000
	s_nop 0
	v_addc_co_u32_e32 v67, vcc, 0, v151, vcc
	global_store_dwordx4 v[66:67], v[60:63], off
	global_store_dwordx4 v[64:65], v[56:59], off offset:64
	global_store_dwordx4 v[64:65], v[44:47], off offset:512
	global_store_dwordx4 v[64:65], v[40:43], off offset:576
	s_nop 1
	v_lshl_add_u64 v[40:41], v[150:151], 0, s[4:5]
	s_mov_b32 s4, 0x90000
	v_add_co_u32_e32 v42, vcc, s4, v150
	s_mov_b64 s[4:5], 0xa0000
	s_nop 0
	v_addc_co_u32_e32 v43, vcc, 0, v151, vcc
	global_store_dwordx4 v[42:43], v[52:55], off
	global_store_dwordx4 v[40:41], v[48:51], off offset:64
	global_store_dwordx4 v[40:41], v[28:31], off offset:512
	global_store_dwordx4 v[40:41], v[24:27], off offset:576
	s_nop 1
	v_lshl_add_u64 v[24:25], v[150:151], 0, s[4:5]
	s_mov_b32 s4, 0xa0000
	v_add_co_u32_e32 v26, vcc, s4, v150
	s_mov_b64 s[4:5], 0xb0000
	s_nop 0
	v_addc_co_u32_e32 v27, vcc, 0, v151, vcc
	global_store_dwordx4 v[26:27], v[36:39], off
	global_store_dwordx4 v[24:25], v[32:35], off offset:64
	global_store_dwordx4 v[24:25], v[12:15], off offset:512
	global_store_dwordx4 v[24:25], v[8:11], off offset:576
	s_nop 1
	v_add_co_u32_e32 v10, vcc, 0xb0000, v150
	v_lshl_add_u64 v[8:9], v[150:151], 0, s[4:5]
	s_nop 0
	v_addc_co_u32_e32 v11, vcc, 0, v151, vcc
	global_store_dwordx4 v[10:11], v[20:23], off
	global_store_dwordx4 v[8:9], v[16:19], off offset:64
	global_store_dwordx4 v[8:9], v[4:7], off offset:512
	global_store_dwordx4 v[8:9], v[0:3], off offset:576
	s_waitcnt vmcnt(0)
	s_cbranch_scc0 .LBB0_377
	s_barrier

; #define PG8_STAGE(bufoff, gbase, voff) do { _Pragma("unroll") for (int _i = 0; _i < 2; ++_i) \
;         __builtin_amdgcn_global_load_lds((const unsigned*)((const char*)(gbase) + (voff)[_i]), (PG8_LAS unsigned*)(lds + (bufoff) + ldsw + _i * 8192), 16, 0, 0); } while (0)
; #define PG8_LDA(dst, b, h) do { _Pragma("unroll") for (int m = 0; m < 4; ++m) _Pragma("unroll") for (int k = 0; k < 2; ++k) dst[m][k] = *(const PG8_LAS bf16x8*)(lds + PG8_SA(b, h) + aoff + m * 2048 + k * 1024); } while (0)
; #define PG8_LDB(dst, b, h) do { _Pragma("unroll") for (int n = 0; n < 2; ++n) _Pragma("unroll") for (int k = 0; k < 2; ++k) dst[n][k] = *(const PG8_LAS bf16x8*)(lds + PG8_SB(b, h) + boff + n * 2048 + k * 1024); } while (0)
; #define PG8_WAIT_L(n) asm volatile("s_waitcnt lgkmcnt(" #n ")" ::: "memory")
; #define PG8_BAR __builtin_amdgcn_s_barrier()
; #define PG8_SCHED __builtin_amdgcn_sched_barrier(0)
;     __device__ bool next(int i, pg8::Unit& u) const { if (i != 0 || !valid) return false; u.pm = pm; u.pn = pn; return true; }
; template <class Epi, class Sched, bool STAMP = false>
; __device__ __forceinline__ void gemm_phase(PG8_LAS unsigned char* lds, const Gemm g, const Sched& S, const Epi& E, unsigned long long* stamps) {
;     ...
;         const bool has_next = S.next(ui + 1, nxt);
;         const char* nA = has_next ? (const char*)g.A + (size_t)nxt.pm * tstep : cA; const char* nB = has_next ? (const char*)g.Bt + (size_t)nxt.pn * tstep : cB;
;         for (int t = 0; t < nt; t += 2) {
;             const bool last = (t == nt - 2);
;             const char* a1 = cA + (size_t)(t + 1) * kstep;
;             const char* a2 = last ? nA : cA + (size_t)(t + 2) * kstep; const char* b2 = last ? nB : cB + (size_t)(t + 2) * kstep;
;             const char* a3 = a2 + kstep; const char* b3 = b2 + kstep;
;             if (last && has_next) S.a_ready(nxt);
;             PG8_LDB(B0, 0, 0); PG8_SCHED; PG8_LDA(At, 0, 0); PG8_STAGE(PG8_SA(1, 1), a1 + hstep, voffA);
;             PG8_WAIT_L(8); PG8_BAR; PG8_WAIT_L(0); PG8_MMA(0, 0, At, B0); PG8_BAR; PG8_SCHED;
;     ...
; #pragma unroll
;         for (int a = 0; a < 2; ++a)
; #pragma unroll
;             for (int b = 0; b < 2; ++b)
; #pragma unroll
;                 for (int m = 0; m < 4; ++m)
; #pragma unroll
;                     for (int n = 0; n < 2; ++n) acc[a][b][m][n] = (f32x4){0.f, 0.f, 0.f, 0.f};
;         cur = nxt; cA = nA; cB = nB; ++ui;
.LBB0_494:
	s_ashr_i32 s7, s6, 31
	v_cmp_lt_i64_e32 vcc, s[12:13], v[142:143]
	s_lshl_b64 s[12:13], s[6:7], 19
	s_add_u32 s12, s37, s12
	s_addc_u32 s13, s40, s13
	s_and_b64 s[14:15], vcc, exec
	s_cselect_b32 s7, s13, s25
	s_cselect_b32 s57, s12, s24
	s_ashr_i32 s5, s4, 31
	s_lshl_b64 s[14:15], s[4:5], 19
	s_add_u32 s20, s41, s14
	s_addc_u32 s21, s42, s15
	s_and_b64 s[14:15], vcc, exec
	s_cselect_b32 s5, s21, s27
	s_cselect_b32 s58, s20, s26
	s_add_u32 s24, s24, 0x40080
	s_addc_u32 s25, s25, 0
	s_add_u32 s59, s26, 0x100
	v_mov_b32_e32 v0, 0
	s_addc_u32 s60, s27, 0
	s_mov_b32 s61, -2
	v_mov_b32_e32 v1, v0
	v_mov_b32_e32 v2, v0
	v_mov_b32_e32 v3, v0
	v_mov_b32_e32 v4, v0
	v_mov_b32_e32 v5, v0
	v_mov_b32_e32 v6, v0
	v_mov_b32_e32 v7, v0
	v_mov_b32_e32 v16, v0
	v_mov_b32_e32 v17, v0
	v_mov_b32_e32 v18, v0
	v_mov_b32_e32 v19, v0
	v_mov_b32_e32 v20, v0
	v_mov_b32_e32 v21, v0
	v_mov_b32_e32 v22, v0
	v_mov_b32_e32 v23, v0
	v_mov_b32_e32 v32, v0
	v_mov_b32_e32 v33, v0
	v_mov_b32_e32 v34, v0
	v_mov_b32_e32 v35, v0
	v_mov_b32_e32 v36, v0
	v_mov_b32_e32 v37, v0
	v_mov_b32_e32 v38, v0
	v_mov_b32_e32 v39, v0
	v_mov_b32_e32 v48, v0
	v_mov_b32_e32 v49, v0
	v_mov_b32_e32 v50, v0
	v_mov_b32_e32 v51, v0
	v_mov_b32_e32 v52, v0
	v_mov_b32_e32 v53, v0
	v_mov_b32_e32 v54, v0
	v_mov_b32_e32 v55, v0
	v_mov_b32_e32 v8, v0
	v_mov_b32_e32 v9, v0
	v_mov_b32_e32 v10, v0
	v_mov_b32_e32 v11, v0
	v_mov_b32_e32 v12, v0
	v_mov_b32_e32 v13, v0
	v_mov_b32_e32 v14, v0
	v_mov_b32_e32 v15, v0
	v_mov_b32_e32 v24, v0
	v_mov_b32_e32 v25, v0
	v_mov_b32_e32 v26, v0
	v_mov_b32_e32 v27, v0
	v_mov_b32_e32 v28, v0
	v_mov_b32_e32 v29, v0
	v_mov_b32_e32 v30, v0
	v_mov_b32_e32 v31, v0
	v_mov_b32_e32 v40, v0
	v_mov_b32_e32 v41, v0
	v_mov_b32_e32 v42, v0
	v_mov_b32_e32 v43, v0
	v_mov_b32_e32 v44, v0
	v_mov_b32_e32 v45, v0
	v_mov_b32_e32 v46, v0
	v_mov_b32_e32 v47, v0
	v_mov_b32_e32 v56, v0
	v_mov_b32_e32 v57, v0
	v_mov_b32_e32 v58, v0
	v_mov_b32_e32 v59, v0
	v_mov_b32_e32 v60, v0
	v_mov_b32_e32 v61, v0
	v_mov_b32_e32 v62, v0
	v_mov_b32_e32 v63, v0
	v_mov_b32_e32 v64, v0
	v_mov_b32_e32 v65, v0
	v_mov_b32_e32 v66, v0
	v_mov_b32_e32 v67, v0
	v_mov_b32_e32 v68, v0
	v_mov_b32_e32 v69, v0
	v_mov_b32_e32 v70, v0
	v_mov_b32_e32 v71, v0
	v_mov_b32_e32 v80, v0
	v_mov_b32_e32 v81, v0
	v_mov_b32_e32 v82, v0
	v_mov_b32_e32 v83, v0
	v_mov_b32_e32 v84, v0
	v_mov_b32_e32 v85, v0
	v_mov_b32_e32 v86, v0
	v_mov_b32_e32 v87, v0
	v_mov_b32_e32 v96, v0
	v_mov_b32_e32 v97, v0
	v_mov_b32_e32 v98, v0
	v_mov_b32_e32 v99, v0
	v_mov_b32_e32 v100, v0
	v_mov_b32_e32 v101, v0
	v_mov_b32_e32 v102, v0
	v_mov_b32_e32 v103, v0
	v_mov_b32_e32 v112, v0
	v_mov_b32_e32 v113, v0
	v_mov_b32_e32 v114, v0
	v_mov_b32_e32 v115, v0
	v_mov_b32_e32 v116, v0
	v_mov_b32_e32 v117, v0
	v_mov_b32_e32 v118, v0
	v_mov_b32_e32 v119, v0
	v_mov_b32_e32 v72, v0
	v_mov_b32_e32 v73, v0
	v_mov_b32_e32 v74, v0
	v_mov_b32_e32 v75, v0
	v_mov_b32_e32 v76, v0
	v_mov_b32_e32 v77, v0
	v_mov_b32_e32 v78, v0
	s_waitcnt vmcnt(0)
	v_mov_b32_e32 v79, v0
	v_mov_b32_e32 v88, v0
	v_mov_b32_e32 v89, v0
	v_mov_b32_e32 v90, v0
	v_mov_b32_e32 v91, v0
	v_mov_b32_e32 v92, v0
	v_mov_b32_e32 v93, v0
	v_mov_b32_e32 v94, v0
	v_mov_b32_e32 v95, v0
	v_mov_b32_e32 v104, v0
	v_mov_b32_e32 v105, v0
	v_mov_b32_e32 v106, v0
	v_mov_b32_e32 v107, v0
	v_mov_b32_e32 v108, v0
	v_mov_b32_e32 v109, v0
	v_mov_b32_e32 v110, v0
	v_mov_b32_e32 v111, v0
	v_mov_b32_e32 v120, v0
	v_mov_b32_e32 v121, v0
	v_mov_b32_e32 v122, v0
	v_mov_b32_e32 v123, v0
	v_mov_b32_e32 v124, v0
	v_mov_b32_e32 v125, v0
	v_mov_b32_e32 v126, v0
	v_mov_b32_e32 v127, v0
	v_add_u32_e32 v244, 0x80, v128
	v_add_u32_e32 v245, 0x80, v148
	v_add_u32_e32 v246, 0x80, v152
	v_add_u32_e32 v247, 0x80, v150
	v_add_u32_e32 v248, 0x10000, v166
	v_add_u32_e32 v249, 0x14000, v166
	v_add_u32_e32 v250, 0x18000, v166
	v_add_u32_e32 v251, 0x1c000, v166
.LBB0_495:
	s_add_u32 s14, s24, 0xfffc0080
	s_addc_u32 s15, s25, -1
	s_add_i32 s16, 0, 0x10000
	ds_read_b128 v[158:161], v248
	ds_read_b128 v[162:165], v248 offset:1024
	ds_read_b128 v[170:173], v248 offset:2048
	ds_read_b128 v[174:177], v248 offset:3072
	s_cmp_eq_u32 s61, 12
	s_cselect_b32 s31, s7, s15
	s_cselect_b32 s30, s57, s14
	s_cselect_b32 s27, s5, s60
	s_cselect_b32 s26, s58, s59
	s_add_i32 m0, s23, 0xc000
	ds_read_b128 v[178:181], v168
	ds_read_b128 v[192:195], v168 offset:1024
	ds_read_b128 v[196:199], v168 offset:2048
	ds_read_b128 v[200:203], v168 offset:3072
	ds_read_b128 v[204:207], v168 offset:4096
	ds_read_b128 v[208:211], v168 offset:5120
	ds_read_b128 v[212:215], v168 offset:6144
	ds_read_b128 v[216:219], v168 offset:7168
	global_load_lds_dwordx4 v154, s[24:25]
	s_add_i32 m0, s23, 0xe000
	s_nop 0
	global_load_lds_dwordx4 v156, s[24:25]
	s_waitcnt lgkmcnt(8)
	s_barrier
	s_waitcnt lgkmcnt(0)
	v_mfma_f32_16x16x32_bf16 v[124:127], v[158:161], v[178:181], v[124:127]
	v_mfma_f32_16x16x32_bf16 v[120:123], v[170:173], v[178:181], v[120:123]
	v_mfma_f32_16x16x32_bf16 v[108:111], v[158:161], v[196:199], v[108:111]
	v_mfma_f32_16x16x32_bf16 v[104:107], v[170:173], v[196:199], v[104:107]
	v_mfma_f32_16x16x32_bf16 v[92:95], v[158:161], v[204:207], v[92:95]
	v_mfma_f32_16x16x32_bf16 v[88:91], v[170:173], v[204:207], v[88:91]
	v_mfma_f32_16x16x32_bf16 v[76:79], v[158:161], v[212:215], v[76:79]
	v_mfma_f32_16x16x32_bf16 v[72:75], v[170:173], v[212:215], v[72:75]
	v_mfma_f32_16x16x32_bf16 v[124:127], v[162:165], v[192:195], v[124:127]
	v_mfma_f32_16x16x32_bf16 v[120:123], v[174:177], v[192:195], v[120:123]
	v_mfma_f32_16x16x32_bf16 v[108:111], v[162:165], v[200:203], v[108:111]
	v_mfma_f32_16x16x32_bf16 v[104:107], v[174:177], v[200:203], v[104:107]
	v_mfma_f32_16x16x32_bf16 v[92:95], v[162:165], v[208:211], v[92:95]
	v_mfma_f32_16x16x32_bf16 v[88:91], v[174:177], v[208:211], v[88:91]
	v_mfma_f32_16x16x32_bf16 v[76:79], v[162:165], v[216:219], v[76:79]
	v_mfma_f32_16x16x32_bf16 v[72:75], v[174:177], v[216:219], v[72:75]
	s_barrier
; #define PG8_STAGE(bufoff, gbase, voff) do { _Pragma("unroll") for (int _i = 0; _i < 2; ++_i) \
;         __builtin_amdgcn_global_load_lds((const unsigned*)((const char*)(gbase) + (voff)[_i]), (PG8_LAS unsigned*)(lds + (bufoff) + ldsw + _i * 8192), 16, 0, 0); } while (0)
; #define PG8_LDA(dst, b, h) do { _Pragma("unroll") for (int m = 0; m < 4; ++m) _Pragma("unroll") for (int k = 0; k < 2; ++k) dst[m][k] = *(const PG8_LAS bf16x8*)(lds + PG8_SA(b, h) + aoff + m * 2048 + k * 1024); } while (0)
; #define PG8_LDB(dst, b, h) do { _Pragma("unroll") for (int n = 0; n < 2; ++n) _Pragma("unroll") for (int k = 0; k < 2; ++k) dst[n][k] = *(const PG8_LAS bf16x8*)(lds + PG8_SB(b, h) + boff + n * 2048 + k * 1024); } while (0)
; #define PG8_MMA(ai, bj, At, Bt) do { __builtin_amdgcn_s_setprio(1); _Pragma("unroll") for (int m = 0; m < 4; ++m) _Pragma("unroll") for (int n = 0; n < 2; ++n) _Pragma("unroll") for (int k = 0; k < 2; ++k) \
;         acc[ai][bj][m][n] = __builtin_amdgcn_mfma_f32_16x16x32_bf16(Bt[n][k], At[m][k], acc[ai][bj][m][n], 0, 0, 0); __builtin_amdgcn_s_setprio(0); } while (0)
; #define PG8_WAIT_V(n) asm volatile("s_waitcnt vmcnt(" #n ")" ::: "memory")
; #define PG8_WAIT_L(n) asm volatile("s_waitcnt lgkmcnt(" #n ")" ::: "memory")
; #define PG8_BAR __builtin_amdgcn_s_barrier()
; #define PG8_SCHED __builtin_amdgcn_sched_barrier(0)
; template <class Epi, class Sched, bool STAMP = false>
; __device__ __forceinline__ void gemm_phase(PG8_LAS unsigned char* lds, const Gemm g, const Sched& S, const Epi& E, unsigned long long* stamps) {
;     ...
;             PG8_LDB(B1, 0, 1); PG8_STAGE(PG8_SB(0, 0), b2, voffB);
;             PG8_BAR; PG8_WAIT_L(0); PG8_MMA(0, 1, At, B1); PG8_BAR;
;             PG8_LDA(At, 0, 1); PG8_STAGE(PG8_SA(0, 0), a2, voffA);
;             PG8_BAR; PG8_WAIT_L(0); PG8_MMA(1, 0, At, B0); PG8_BAR; PG8_SCHED;
;             PG8_STAGE(PG8_SB(0, 1), b2 + hstep, voffB);
;             PG8_WAIT_V(6); PG8_BAR; PG8_MMA(1, 1, At, B1); PG8_BAR;
;             PG8_LDB(B0, 1, 0); PG8_SCHED; PG8_LDA(At, 1, 0); PG8_STAGE(PG8_SA(0, 1), a2 + hstep, voffA);
;             PG8_WAIT_L(8); PG8_BAR; PG8_WAIT_L(0); PG8_MMA(0, 0, At, B0); PG8_BAR; PG8_SCHED;
	s_add_i32 s17, 0, 0x14000
	s_add_i32 s14, s16, s43
	s_mov_b32 m0, s14
	ds_read_b128 v[220:223], v249
	ds_read_b128 v[224:227], v249 offset:1024
	ds_read_b128 v[228:231], v249 offset:2048
	ds_read_b128 v[232:235], v249 offset:3072
	global_load_lds_dwordx4 v128, s[26:27]
	s_add_i32 m0, s14, 0x2000
	s_nop 0
	global_load_lds_dwordx4 v148, s[26:27]
	s_barrier
	s_waitcnt lgkmcnt(0)
	v_mfma_f32_16x16x32_bf16 v[116:119], v[220:223], v[178:181], v[116:119]
	v_mfma_f32_16x16x32_bf16 v[112:115], v[228:231], v[178:181], v[112:115]
	v_mfma_f32_16x16x32_bf16 v[100:103], v[220:223], v[196:199], v[100:103]
	v_mfma_f32_16x16x32_bf16 v[96:99], v[228:231], v[196:199], v[96:99]
	v_mfma_f32_16x16x32_bf16 v[84:87], v[220:223], v[204:207], v[84:87]
	v_mfma_f32_16x16x32_bf16 v[80:83], v[228:231], v[204:207], v[80:83]
	v_mfma_f32_16x16x32_bf16 v[68:71], v[220:223], v[212:215], v[68:71]
	v_mfma_f32_16x16x32_bf16 v[64:67], v[228:231], v[212:215], v[64:67]
	v_mfma_f32_16x16x32_bf16 v[116:119], v[224:227], v[192:195], v[116:119]
	v_mfma_f32_16x16x32_bf16 v[112:115], v[232:235], v[192:195], v[112:115]
	v_mfma_f32_16x16x32_bf16 v[100:103], v[224:227], v[200:203], v[100:103]
	v_mfma_f32_16x16x32_bf16 v[96:99], v[232:235], v[200:203], v[96:99]
	v_mfma_f32_16x16x32_bf16 v[84:87], v[224:227], v[208:211], v[84:87]
	v_mfma_f32_16x16x32_bf16 v[80:83], v[232:235], v[208:211], v[80:83]
	v_mfma_f32_16x16x32_bf16 v[68:71], v[224:227], v[216:219], v[68:71]
	v_mfma_f32_16x16x32_bf16 v[64:67], v[232:235], v[216:219], v[64:67]
	s_mov_b32 m0, s23
	s_barrier
	ds_read_b128 v[178:181], v168 offset:16384
	ds_read_b128 v[192:195], v168 offset:17408
	ds_read_b128 v[196:199], v168 offset:18432
	ds_read_b128 v[200:203], v168 offset:19456
	ds_read_b128 v[204:207], v168 offset:20480
	ds_read_b128 v[208:211], v168 offset:21504
	ds_read_b128 v[212:215], v168 offset:22528
	ds_read_b128 v[216:219], v168 offset:23552
	global_load_lds_dwordx4 v152, s[30:31]
	s_mov_b32 m0, s45
	s_nop 0
	global_load_lds_dwordx4 v150, s[30:31]
	s_barrier
	s_waitcnt lgkmcnt(0)
	v_mfma_f32_16x16x32_bf16 v[60:63], v[158:161], v[178:181], v[60:63]
	v_mfma_f32_16x16x32_bf16 v[56:59], v[170:173], v[178:181], v[56:59]
	v_mfma_f32_16x16x32_bf16 v[44:47], v[158:161], v[196:199], v[44:47]
	v_mfma_f32_16x16x32_bf16 v[40:43], v[170:173], v[196:199], v[40:43]
	v_mfma_f32_16x16x32_bf16 v[28:31], v[158:161], v[204:207], v[28:31]
	v_mfma_f32_16x16x32_bf16 v[24:27], v[170:173], v[204:207], v[24:27]
	v_mfma_f32_16x16x32_bf16 v[12:15], v[158:161], v[212:215], v[12:15]
	v_mfma_f32_16x16x32_bf16 v[8:11], v[170:173], v[212:215], v[8:11]
	v_mfma_f32_16x16x32_bf16 v[60:63], v[162:165], v[192:195], v[60:63]
	v_mfma_f32_16x16x32_bf16 v[56:59], v[174:177], v[192:195], v[56:59]
	v_mfma_f32_16x16x32_bf16 v[44:47], v[162:165], v[200:203], v[44:47]
	v_mfma_f32_16x16x32_bf16 v[40:43], v[174:177], v[200:203], v[40:43]
	v_mfma_f32_16x16x32_bf16 v[28:31], v[162:165], v[208:211], v[28:31]
	v_mfma_f32_16x16x32_bf16 v[24:27], v[174:177], v[208:211], v[24:27]
	v_mfma_f32_16x16x32_bf16 v[12:15], v[162:165], v[216:219], v[12:15]
	v_mfma_f32_16x16x32_bf16 v[8:11], v[174:177], v[216:219], v[8:11]
	s_barrier
	s_add_u32 s14, s26, 0x40000
	s_addc_u32 s15, s27, 0
	s_add_i32 s16, s17, s43
	s_mov_b32 m0, s16
	s_nop 0
	global_load_lds_dwordx4 v128, s[14:15]
	s_add_i32 m0, s16, 0x2000
	s_nop 0
	global_load_lds_dwordx4 v148, s[14:15]
	s_waitcnt vmcnt(6)
	s_barrier
	v_mfma_f32_16x16x32_bf16 v[52:55], v[220:223], v[178:181], v[52:55]
	v_mfma_f32_16x16x32_bf16 v[48:51], v[228:231], v[178:181], v[48:51]
	v_mfma_f32_16x16x32_bf16 v[36:39], v[220:223], v[196:199], v[36:39]
	v_mfma_f32_16x16x32_bf16 v[32:35], v[228:231], v[196:199], v[32:35]
	v_mfma_f32_16x16x32_bf16 v[20:23], v[220:223], v[204:207], v[20:23]
	v_mfma_f32_16x16x32_bf16 v[16:19], v[228:231], v[204:207], v[16:19]
	v_mfma_f32_16x16x32_bf16 v[4:7], v[220:223], v[212:215], v[4:7]
	v_mfma_f32_16x16x32_bf16 v[0:3], v[228:231], v[212:215], v[0:3]
	v_mfma_f32_16x16x32_bf16 v[52:55], v[224:227], v[192:195], v[52:55]
	v_mfma_f32_16x16x32_bf16 v[48:51], v[232:235], v[192:195], v[48:51]
	v_mfma_f32_16x16x32_bf16 v[36:39], v[224:227], v[200:203], v[36:39]
	v_mfma_f32_16x16x32_bf16 v[32:35], v[232:235], v[200:203], v[32:35]
	v_mfma_f32_16x16x32_bf16 v[20:23], v[224:227], v[208:211], v[20:23]
	v_mfma_f32_16x16x32_bf16 v[16:19], v[232:235], v[208:211], v[16:19]
	v_mfma_f32_16x16x32_bf16 v[4:7], v[224:227], v[216:219], v[4:7]
	v_mfma_f32_16x16x32_bf16 v[0:3], v[232:235], v[216:219], v[0:3]
	s_add_i32 s16, 0, 0x18000
	s_barrier
	ds_read_b128 v[158:161], v250
	ds_read_b128 v[162:165], v250 offset:1024
	ds_read_b128 v[170:173], v250 offset:2048
	ds_read_b128 v[174:177], v250 offset:3072
	s_add_u32 s14, s30, 0x40000
	s_addc_u32 s15, s31, 0
	s_mov_b32 m0, s46
	ds_read_b128 v[178:181], v168 offset:32768
	ds_read_b128 v[192:195], v168 offset:33792
	ds_read_b128 v[196:199], v168 offset:34816
	ds_read_b128 v[200:203], v168 offset:35840
	ds_read_b128 v[204:207], v168 offset:36864
	ds_read_b128 v[208:211], v168 offset:37888
	ds_read_b128 v[212:215], v168 offset:38912
	ds_read_b128 v[216:219], v168 offset:39936
	global_load_lds_dwordx4 v152, s[14:15]
	s_mov_b32 m0, s47
	s_nop 0
	global_load_lds_dwordx4 v150, s[14:15]
	s_waitcnt lgkmcnt(8)
	s_barrier
; #define PG8_STAGE(bufoff, gbase, voff) do { _Pragma("unroll") for (int _i = 0; _i < 2; ++_i) \
;         __builtin_amdgcn_global_load_lds((const unsigned*)((const char*)(gbase) + (voff)[_i]), (PG8_LAS unsigned*)(lds + (bufoff) + ldsw + _i * 8192), 16, 0, 0); } while (0)
; #define PG8_LDA(dst, b, h) do { _Pragma("unroll") for (int m = 0; m < 4; ++m) _Pragma("unroll") for (int k = 0; k < 2; ++k) dst[m][k] = *(const PG8_LAS bf16x8*)(lds + PG8_SA(b, h) + aoff + m * 2048 + k * 1024); } while (0)
; #define PG8_LDB(dst, b, h) do { _Pragma("unroll") for (int n = 0; n < 2; ++n) _Pragma("unroll") for (int k = 0; k < 2; ++k) dst[n][k] = *(const PG8_LAS bf16x8*)(lds + PG8_SB(b, h) + boff + n * 2048 + k * 1024); } while (0)
; #define PG8_MMA(ai, bj, At, Bt) do { __builtin_amdgcn_s_setprio(1); _Pragma("unroll") for (int m = 0; m < 4; ++m) _Pragma("unroll") for (int n = 0; n < 2; ++n) _Pragma("unroll") for (int k = 0; k < 2; ++k) \
;         acc[ai][bj][m][n] = __builtin_amdgcn_mfma_f32_16x16x32_bf16(Bt[n][k], At[m][k], acc[ai][bj][m][n], 0, 0, 0); __builtin_amdgcn_s_setprio(0); } while (0)
; #define PG8_WAIT_V(n) asm volatile("s_waitcnt vmcnt(" #n ")" ::: "memory")
; #define PG8_WAIT_L(n) asm volatile("s_waitcnt lgkmcnt(" #n ")" ::: "memory")
; #define PG8_BAR __builtin_amdgcn_s_barrier()
; #define PG8_SCHED __builtin_amdgcn_sched_barrier(0)
; template <class Epi, class Sched, bool STAMP = false>
; __device__ __forceinline__ void gemm_phase(PG8_LAS unsigned char* lds, const Gemm g, const Sched& S, const Epi& E, unsigned long long* stamps) {
;     ...
;             PG8_WAIT_L(8); PG8_BAR; PG8_WAIT_L(0); PG8_MMA(0, 0, At, B0); PG8_BAR; PG8_SCHED;
;             PG8_LDB(B1, 1, 1); PG8_STAGE(PG8_SB(1, 0), b3, voffB);
;             PG8_BAR; PG8_WAIT_L(0); PG8_MMA(0, 1, At, B1); PG8_BAR;
;             PG8_LDA(At, 1, 1); PG8_STAGE(PG8_SA(1, 0), a3, voffA);
;             PG8_BAR; PG8_WAIT_L(0); PG8_MMA(1, 0, At, B0); PG8_BAR; PG8_SCHED;
;             PG8_STAGE(PG8_SB(1, 1), b3 + hstep, voffB);
;             PG8_WAIT_V(6); PG8_BAR; PG8_MMA(1, 1, At, B1); PG8_BAR;
	s_waitcnt lgkmcnt(0)
	v_mfma_f32_16x16x32_bf16 v[124:127], v[158:161], v[178:181], v[124:127]
	v_mfma_f32_16x16x32_bf16 v[120:123], v[170:173], v[178:181], v[120:123]
	v_mfma_f32_16x16x32_bf16 v[108:111], v[158:161], v[196:199], v[108:111]
	v_mfma_f32_16x16x32_bf16 v[104:107], v[170:173], v[196:199], v[104:107]
	v_mfma_f32_16x16x32_bf16 v[92:95], v[158:161], v[204:207], v[92:95]
	v_mfma_f32_16x16x32_bf16 v[88:91], v[170:173], v[204:207], v[88:91]
	v_mfma_f32_16x16x32_bf16 v[76:79], v[158:161], v[212:215], v[76:79]
	v_mfma_f32_16x16x32_bf16 v[72:75], v[170:173], v[212:215], v[72:75]
	v_mfma_f32_16x16x32_bf16 v[124:127], v[162:165], v[192:195], v[124:127]
	v_mfma_f32_16x16x32_bf16 v[120:123], v[174:177], v[192:195], v[120:123]
	v_mfma_f32_16x16x32_bf16 v[108:111], v[162:165], v[200:203], v[108:111]
	v_mfma_f32_16x16x32_bf16 v[104:107], v[174:177], v[200:203], v[104:107]
	v_mfma_f32_16x16x32_bf16 v[92:95], v[162:165], v[208:211], v[92:95]
	v_mfma_f32_16x16x32_bf16 v[88:91], v[174:177], v[208:211], v[88:91]
	v_mfma_f32_16x16x32_bf16 v[76:79], v[162:165], v[216:219], v[76:79]
	v_mfma_f32_16x16x32_bf16 v[72:75], v[174:177], v[216:219], v[72:75]
	s_barrier
	s_add_i32 s17, 0, 0x1c000
	s_add_i32 s14, s16, s43
	s_mov_b32 m0, s14
	ds_read_b128 v[220:223], v251
	ds_read_b128 v[224:227], v251 offset:1024
	ds_read_b128 v[228:231], v251 offset:2048
	ds_read_b128 v[232:235], v251 offset:3072
	global_load_lds_dwordx4 v244, s[26:27]
	s_add_i32 m0, s14, 0x2000
	s_nop 0
	global_load_lds_dwordx4 v245, s[26:27]
	s_barrier
	s_waitcnt lgkmcnt(0)
	v_mfma_f32_16x16x32_bf16 v[116:119], v[220:223], v[178:181], v[116:119]
	v_mfma_f32_16x16x32_bf16 v[112:115], v[228:231], v[178:181], v[112:115]
	v_mfma_f32_16x16x32_bf16 v[100:103], v[220:223], v[196:199], v[100:103]
	v_mfma_f32_16x16x32_bf16 v[96:99], v[228:231], v[196:199], v[96:99]
	v_mfma_f32_16x16x32_bf16 v[84:87], v[220:223], v[204:207], v[84:87]
	v_mfma_f32_16x16x32_bf16 v[80:83], v[228:231], v[204:207], v[80:83]
	v_mfma_f32_16x16x32_bf16 v[68:71], v[220:223], v[212:215], v[68:71]
	v_mfma_f32_16x16x32_bf16 v[64:67], v[228:231], v[212:215], v[64:67]
	v_mfma_f32_16x16x32_bf16 v[116:119], v[224:227], v[192:195], v[116:119]
	v_mfma_f32_16x16x32_bf16 v[112:115], v[232:235], v[192:195], v[112:115]
	v_mfma_f32_16x16x32_bf16 v[100:103], v[224:227], v[200:203], v[100:103]
	v_mfma_f32_16x16x32_bf16 v[96:99], v[232:235], v[200:203], v[96:99]
	v_mfma_f32_16x16x32_bf16 v[84:87], v[224:227], v[208:211], v[84:87]
	v_mfma_f32_16x16x32_bf16 v[80:83], v[232:235], v[208:211], v[80:83]
	v_mfma_f32_16x16x32_bf16 v[68:71], v[224:227], v[216:219], v[68:71]
	v_mfma_f32_16x16x32_bf16 v[64:67], v[232:235], v[216:219], v[64:67]
	s_mov_b32 m0, s49
	s_barrier
	ds_read_b128 v[178:181], v168 offset:49152
	ds_read_b128 v[192:195], v168 offset:50176
	ds_read_b128 v[196:199], v168 offset:51200
	ds_read_b128 v[200:203], v168 offset:52224
	ds_read_b128 v[204:207], v168 offset:53248
	ds_read_b128 v[208:211], v168 offset:54272
	ds_read_b128 v[212:215], v168 offset:55296
	ds_read_b128 v[216:219], v168 offset:56320
	global_load_lds_dwordx4 v246, s[30:31]
	s_mov_b32 m0, s53
	s_nop 0
	global_load_lds_dwordx4 v247, s[30:31]
	s_barrier
	s_waitcnt lgkmcnt(0)
	v_mfma_f32_16x16x32_bf16 v[60:63], v[158:161], v[178:181], v[60:63]
	v_mfma_f32_16x16x32_bf16 v[56:59], v[170:173], v[178:181], v[56:59]
	v_mfma_f32_16x16x32_bf16 v[44:47], v[158:161], v[196:199], v[44:47]
	v_mfma_f32_16x16x32_bf16 v[40:43], v[170:173], v[196:199], v[40:43]
	v_mfma_f32_16x16x32_bf16 v[28:31], v[158:161], v[204:207], v[28:31]
	v_mfma_f32_16x16x32_bf16 v[24:27], v[170:173], v[204:207], v[24:27]
	v_mfma_f32_16x16x32_bf16 v[12:15], v[158:161], v[212:215], v[12:15]
	v_mfma_f32_16x16x32_bf16 v[8:11], v[170:173], v[212:215], v[8:11]
	v_mfma_f32_16x16x32_bf16 v[60:63], v[162:165], v[192:195], v[60:63]
	v_mfma_f32_16x16x32_bf16 v[56:59], v[174:177], v[192:195], v[56:59]
	v_mfma_f32_16x16x32_bf16 v[44:47], v[162:165], v[200:203], v[44:47]
	v_mfma_f32_16x16x32_bf16 v[40:43], v[174:177], v[200:203], v[40:43]
	v_mfma_f32_16x16x32_bf16 v[28:31], v[162:165], v[208:211], v[28:31]
	v_mfma_f32_16x16x32_bf16 v[24:27], v[174:177], v[208:211], v[24:27]
	v_mfma_f32_16x16x32_bf16 v[12:15], v[162:165], v[216:219], v[12:15]
	v_mfma_f32_16x16x32_bf16 v[8:11], v[174:177], v[216:219], v[8:11]
	s_barrier
	s_add_u32 s14, s26, 0x40080
	s_addc_u32 s15, s27, 0
	s_add_i32 s16, s17, s43
	s_mov_b32 m0, s16
	s_nop 0
	global_load_lds_dwordx4 v128, s[14:15]
	s_add_i32 m0, s16, 0x2000
	s_nop 0
	global_load_lds_dwordx4 v148, s[14:15]
	s_waitcnt vmcnt(6)
	s_barrier
	v_mfma_f32_16x16x32_bf16 v[52:55], v[220:223], v[178:181], v[52:55]
	v_mfma_f32_16x16x32_bf16 v[48:51], v[228:231], v[178:181], v[48:51]
	v_mfma_f32_16x16x32_bf16 v[36:39], v[220:223], v[196:199], v[36:39]
	v_mfma_f32_16x16x32_bf16 v[32:35], v[228:231], v[196:199], v[32:35]
	v_mfma_f32_16x16x32_bf16 v[20:23], v[220:223], v[204:207], v[20:23]
	v_mfma_f32_16x16x32_bf16 v[16:19], v[228:231], v[204:207], v[16:19]
	v_mfma_f32_16x16x32_bf16 v[4:7], v[220:223], v[212:215], v[4:7]
	v_mfma_f32_16x16x32_bf16 v[0:3], v[228:231], v[212:215], v[0:3]
	v_mfma_f32_16x16x32_bf16 v[52:55], v[224:227], v[192:195], v[52:55]
	v_mfma_f32_16x16x32_bf16 v[48:51], v[232:235], v[192:195], v[48:51]
	v_mfma_f32_16x16x32_bf16 v[36:39], v[224:227], v[200:203], v[36:39]
	v_mfma_f32_16x16x32_bf16 v[32:35], v[232:235], v[200:203], v[32:35]
	v_mfma_f32_16x16x32_bf16 v[20:23], v[224:227], v[208:211], v[20:23]
	v_mfma_f32_16x16x32_bf16 v[16:19], v[232:235], v[208:211], v[16:19]
	v_mfma_f32_16x16x32_bf16 v[4:7], v[224:227], v[216:219], v[4:7]
	v_mfma_f32_16x16x32_bf16 v[0:3], v[232:235], v[216:219], v[0:3]
	s_add_i32 s61, s61, 2
	s_add_u32 s24, s24, 0x100
	s_addc_u32 s25, s25, 0
	s_add_u32 s59, s59, 0x100
	s_addc_u32 s60, s60, 0
	s_cmp_gt_u32 s61, 13
	s_barrier
; __device__ __forceinline__ unsigned cvt_pk_bf16(float lo, float hi) { const f32x2_cv v = {lo, hi}; const bf16x2_cv b = __builtin_convertvector(v, bf16x2_cv); return __builtin_bit_cast(unsigned, b); }
; __device__ __forceinline__ float rstd_of(const float* rowss, int row) { return rsqrtf(rowss[row] * (1.0f / 1024.0f) + 1e-6f); }
;     __device__ __forceinline__ void operator()(const f32x4 (&acc)[2][2][4][2], const pg8::Unit& u, int wr, int wc, int fr, int fq) const {
;         const int row0 = u.pm * 256 + wr * 64 + fr, col0 = u.pn * 256 + wc * 32 + 8 * fq;
; #pragma unroll
;         for (int ai = 0; ai < 2; ++ai)
; #pragma unroll
;             for (int m = 0; m < 4; ++m) {
;                 const int row = row0 + ai * 128 + m * 16;
;                 const float s = (MODE == 2) ? 1.0f : rstd_of(rowss, row);
;                 bf16_t* rowp = O + (size_t)row * ldc + col0;
; #pragma unroll
;                 for (int bj = 0; bj < 2; ++bj) {
;                     f32x4 v0 = acc[ai][bj][m][0] * s, v1 = acc[ai][bj][m][1] * s;
;                     if (MODE == 1) {
; #pragma unroll
;                         for (int j = 0; j < 4; ++j) { const float a = fmaxf(v0[j], 0.f), b = fmaxf(v1[j], 0.f); v0[j] = a * a; v1[j] = b * b; } }
;                     u32x4 w; w.x = cvt_pk_bf16(v0[0], v0[1]); w.y = cvt_pk_bf16(v0[2], v0[3]); w.z = cvt_pk_bf16(v1[0], v1[1]); w.w = cvt_pk_bf16(v1[2], v1[3]);
;                     *(u32x4*)(rowp + bj * 128) = w; } }
	s_cbranch_scc0 .LBB0_495
	v_lshl_add_u32 v162, s22, 8, v139
	v_ashrrev_i32_e32 v163, 31, v162
	v_lshl_add_u64 v[158:159], v[162:163], 2, s[0:1]
	global_load_dword v164, v[158:159], off
	global_load_dword v193, v[158:159], off offset:64
	global_load_dword v194, v[158:159], off offset:128
	global_load_dword v195, v[158:159], off offset:192
	global_load_dword v196, v[158:159], off offset:512
	global_load_dword v197, v[158:159], off offset:576
	global_load_dword v198, v[158:159], off offset:640
	global_load_dword v199, v[158:159], off offset:704
	v_lshl_or_b32 v160, s56, 8, v167
	v_ashrrev_i32_e32 v161, 31, v160
	s_mov_b32 s5, 0x80000
	s_mov_b64 s[14:15], 0x80000
	s_mov_b32 s56, s4
	s_mov_b32 s22, s6
	s_mov_b64 s[26:27], s[20:21]
	s_mov_b64 s[24:25], s[12:13]
	s_waitcnt vmcnt(0)
	v_fmamk_f32 v164, v164, 0x3a800000, v187
	v_cmp_gt_f32_e32 vcc, s67, v164
	v_mul_f32_e32 v165, 0x4b800000, v164
	s_nop 0
	v_cndmask_b32_e32 v164, v164, v165, vcc
	v_rsq_f32_e32 v164, v164
	s_nop 0
	v_mul_f32_e32 v165, 0x45800000, v164
	v_cndmask_b32_e32 v170, v164, v165, vcc
	v_lshlrev_b64 v[164:165], 12, v[162:163]
	v_lshl_add_u64 v[172:173], s[2:3], 0, v[164:165]
	v_lshlrev_b64 v[164:165], 1, v[160:161]
	v_lshl_add_u64 v[160:161], v[172:173], 0, v[164:165]
	v_pk_mul_f32 v[126:127], v[126:127], v[170:171] op_sel_hi:[1,0]
	v_pk_mul_f32 v[124:125], v[124:125], v[170:171] op_sel_hi:[1,0]
	v_pk_mul_f32 v[172:173], v[122:123], v[170:171] op_sel_hi:[1,0]
	v_pk_mul_f32 v[122:123], v[120:121], v[170:171] op_sel_hi:[1,0]
	v_cvt_pk_bf16_f32 v120, v124, v125
	v_cvt_pk_bf16_f32 v121, v126, v127
	v_cvt_pk_bf16_f32 v122, v122, v123
	v_cvt_pk_bf16_f32 v123, v172, v173
	global_store_dwordx4 v[160:161], v[120:123], off
	v_pk_mul_f32 v[118:119], v[118:119], v[170:171] op_sel_hi:[1,0]
	v_pk_mul_f32 v[116:117], v[116:117], v[170:171] op_sel_hi:[1,0]
	v_pk_mul_f32 v[120:121], v[114:115], v[170:171] op_sel_hi:[1,0]
	v_pk_mul_f32 v[114:115], v[112:113], v[170:171] op_sel_hi:[1,0]
	v_cvt_pk_bf16_f32 v112, v116, v117
	v_cvt_pk_bf16_f32 v113, v118, v119
	v_cvt_pk_bf16_f32 v114, v114, v115
	v_cvt_pk_bf16_f32 v115, v120, v121
	global_store_dwordx4 v[160:161], v[112:115], off offset:256
	s_nop 1
	v_mov_b32_e32 v114, v193
	s_nop 0
	v_or_b32_e32 v112, 16, v162
	v_ashrrev_i32_e32 v113, 31, v112
	v_lshlrev_b64 v[112:113], 12, v[112:113]
	v_lshl_add_u64 v[112:113], s[2:3], 0, v[112:113]
	v_lshl_add_u64 v[112:113], v[112:113], 0, v[164:165]
	v_fmamk_f32 v114, v114, 0x3a800000, v187
	v_cmp_gt_f32_e32 vcc, s67, v114
	v_mul_f32_e32 v115, 0x4b800000, v114
	s_nop 0
	v_cndmask_b32_e32 v114, v114, v115, vcc
	v_rsq_f32_e32 v114, v114
	s_nop 0
	v_mul_f32_e32 v115, 0x45800000, v114
	v_cndmask_b32_e32 v114, v114, v115, vcc
	v_pk_mul_f32 v[110:111], v[110:111], v[114:115] op_sel_hi:[1,0]
	v_pk_mul_f32 v[108:109], v[108:109], v[114:115] op_sel_hi:[1,0]
	v_pk_mul_f32 v[116:117], v[106:107], v[114:115] op_sel_hi:[1,0]
	v_pk_mul_f32 v[106:107], v[104:105], v[114:115] op_sel_hi:[1,0]
	v_cvt_pk_bf16_f32 v104, v108, v109
	v_cvt_pk_bf16_f32 v105, v110, v111
	v_cvt_pk_bf16_f32 v106, v106, v107
	v_cvt_pk_bf16_f32 v107, v116, v117
	global_store_dwordx4 v[112:113], v[104:107], off
	v_pk_mul_f32 v[102:103], v[102:103], v[114:115] op_sel_hi:[1,0]
	v_pk_mul_f32 v[100:101], v[100:101], v[114:115] op_sel_hi:[1,0]
	v_pk_mul_f32 v[104:105], v[98:99], v[114:115] op_sel_hi:[1,0]
	v_pk_mul_f32 v[98:99], v[96:97], v[114:115] op_sel_hi:[1,0]
	v_cvt_pk_bf16_f32 v96, v100, v101
	v_cvt_pk_bf16_f32 v97, v102, v103
	v_cvt_pk_bf16_f32 v98, v98, v99
	v_cvt_pk_bf16_f32 v99, v104, v105
	global_store_dwordx4 v[112:113], v[96:99], off offset:256
	s_nop 1
	v_mov_b32_e32 v98, v194
	s_nop 0
	v_or_b32_e32 v96, 32, v162
	v_ashrrev_i32_e32 v97, 31, v96
	v_lshlrev_b64 v[96:97], 12, v[96:97]
	v_lshl_add_u64 v[96:97], s[2:3], 0, v[96:97]
	v_lshl_add_u64 v[96:97], v[96:97], 0, v[164:165]
	v_fmamk_f32 v98, v98, 0x3a800000, v187
	v_cmp_gt_f32_e32 vcc, s67, v98
	v_mul_f32_e32 v99, 0x4b800000, v98
	s_nop 0
	v_cndmask_b32_e32 v98, v98, v99, vcc
	v_rsq_f32_e32 v98, v98
	s_nop 0
	v_mul_f32_e32 v99, 0x45800000, v98
	v_cndmask_b32_e32 v98, v98, v99, vcc
	v_pk_mul_f32 v[94:95], v[94:95], v[98:99] op_sel_hi:[1,0]
	v_pk_mul_f32 v[92:93], v[92:93], v[98:99] op_sel_hi:[1,0]
	v_pk_mul_f32 v[100:101], v[90:91], v[98:99] op_sel_hi:[1,0]
	v_pk_mul_f32 v[90:91], v[88:89], v[98:99] op_sel_hi:[1,0]
	v_cvt_pk_bf16_f32 v88, v92, v93
	v_cvt_pk_bf16_f32 v89, v94, v95
	v_cvt_pk_bf16_f32 v90, v90, v91
	v_cvt_pk_bf16_f32 v91, v100, v101
	global_store_dwordx4 v[96:97], v[88:91], off
	v_pk_mul_f32 v[86:87], v[86:87], v[98:99] op_sel_hi:[1,0]
	v_pk_mul_f32 v[84:85], v[84:85], v[98:99] op_sel_hi:[1,0]
	v_pk_mul_f32 v[88:89], v[82:83], v[98:99] op_sel_hi:[1,0]
	v_pk_mul_f32 v[82:83], v[80:81], v[98:99] op_sel_hi:[1,0]
	v_cvt_pk_bf16_f32 v80, v84, v85
	v_cvt_pk_bf16_f32 v81, v86, v87
	v_cvt_pk_bf16_f32 v82, v82, v83
	v_cvt_pk_bf16_f32 v83, v88, v89
	global_store_dwordx4 v[96:97], v[80:83], off offset:256
	s_nop 1
	v_mov_b32_e32 v82, v195
	s_nop 0
	v_or_b32_e32 v80, 48, v162
	v_ashrrev_i32_e32 v81, 31, v80
	v_lshlrev_b64 v[80:81], 12, v[80:81]
	v_lshl_add_u64 v[80:81], s[2:3], 0, v[80:81]
	v_lshl_add_u64 v[80:81], v[80:81], 0, v[164:165]
	v_fmamk_f32 v82, v82, 0x3a800000, v187
	v_cmp_gt_f32_e32 vcc, s67, v82
	v_mul_f32_e32 v83, 0x4b800000, v82
	s_nop 0
	v_cndmask_b32_e32 v82, v82, v83, vcc
	v_rsq_f32_e32 v82, v82
	s_nop 0
	v_mul_f32_e32 v83, 0x45800000, v82
	v_cndmask_b32_e32 v82, v82, v83, vcc
	v_pk_mul_f32 v[78:79], v[78:79], v[82:83] op_sel_hi:[1,0]
	v_pk_mul_f32 v[76:77], v[76:77], v[82:83] op_sel_hi:[1,0]
	v_pk_mul_f32 v[84:85], v[74:75], v[82:83] op_sel_hi:[1,0]
; __device__ __forceinline__ unsigned cvt_pk_bf16(float lo, float hi) { const f32x2_cv v = {lo, hi}; const bf16x2_cv b = __builtin_convertvector(v, bf16x2_cv); return __builtin_bit_cast(unsigned, b); }
; #define PG8_WAIT_V(n) asm volatile("s_waitcnt vmcnt(" #n ")" ::: "memory")
; #define PG8_BAR __builtin_amdgcn_s_barrier()
; __device__ __forceinline__ float rstd_of(const float* rowss, int row) { return rsqrtf(rowss[row] * (1.0f / 1024.0f) + 1e-6f); }
; template <class Epi, class Sched, bool STAMP = false>
; __device__ __forceinline__ void gemm_phase(PG8_LAS unsigned char* lds, const Gemm g, const Sched& S, const Epi& E, unsigned long long* stamps) {
;     ...
;         if (!has_next) break;
; #pragma unroll
;         for (int a = 0; a < 2; ++a)
; #pragma unroll
;             for (int b = 0; b < 2; ++b)
; #pragma unroll
;                 for (int m = 0; m < 4; ++m)
; #pragma unroll
;                     for (int n = 0; n < 2; ++n) acc[a][b][m][n] = (f32x4){0.f, 0.f, 0.f, 0.f};
;         cur = nxt; cA = nA; cB = nB; ++ui;
;     }
;     PG8_WAIT_V(0);
;     if (wr == 0) PG8_BAR;
;     __device__ __forceinline__ void operator()(const f32x4 (&acc)[2][2][4][2], const pg8::Unit& u, int wr, int wc, int fr, int fq) const {
;         const int row0 = u.pm * 256 + wr * 64 + fr, col0 = u.pn * 256 + wc * 32 + 8 * fq;
; #pragma unroll
;         for (int ai = 0; ai < 2; ++ai)
; #pragma unroll
;             for (int m = 0; m < 4; ++m) {
;                 const int row = row0 + ai * 128 + m * 16;
;                 const float s = (MODE == 2) ? 1.0f : rstd_of(rowss, row);
;                 bf16_t* rowp = O + (size_t)row * ldc + col0;
; #pragma unroll
;                 for (int bj = 0; bj < 2; ++bj) {
;                     f32x4 v0 = acc[ai][bj][m][0] * s, v1 = acc[ai][bj][m][1] * s;
;                     if (MODE == 1) {
; #pragma unroll
;                         for (int j = 0; j < 4; ++j) { const float a = fmaxf(v0[j], 0.f), b = fmaxf(v1[j], 0.f); v0[j] = a * a; v1[j] = b * b; } }
;                     u32x4 w; w.x = cvt_pk_bf16(v0[0], v0[1]); w.y = cvt_pk_bf16(v0[2], v0[3]); w.z = cvt_pk_bf16(v1[0], v1[1]); w.w = cvt_pk_bf16(v1[2], v1[3]);
;                     *(u32x4*)(rowp + bj * 128) = w; } }
	v_pk_mul_f32 v[74:75], v[72:73], v[82:83] op_sel_hi:[1,0]
	v_cvt_pk_bf16_f32 v72, v76, v77
	v_cvt_pk_bf16_f32 v73, v78, v79
	v_cvt_pk_bf16_f32 v74, v74, v75
	v_cvt_pk_bf16_f32 v75, v84, v85
	global_store_dwordx4 v[80:81], v[72:75], off
	v_pk_mul_f32 v[70:71], v[70:71], v[82:83] op_sel_hi:[1,0]
	v_pk_mul_f32 v[68:69], v[68:69], v[82:83] op_sel_hi:[1,0]
	v_pk_mul_f32 v[72:73], v[66:67], v[82:83] op_sel_hi:[1,0]
	v_pk_mul_f32 v[66:67], v[64:65], v[82:83] op_sel_hi:[1,0]
	v_cvt_pk_bf16_f32 v64, v68, v69
	v_cvt_pk_bf16_f32 v65, v70, v71
	v_cvt_pk_bf16_f32 v66, v66, v67
	v_cvt_pk_bf16_f32 v67, v72, v73
	global_store_dwordx4 v[80:81], v[64:67], off offset:256
	s_nop 1
	v_mov_b32_e32 v64, v196
	s_nop 0
	v_lshl_add_u64 v[66:67], v[160:161], 0, s[14:15]
	s_mov_b64 s[14:15], 0x90000
	v_fmamk_f32 v64, v64, 0x3a800000, v187
	v_cmp_gt_f32_e32 vcc, s67, v64
	v_mul_f32_e32 v65, 0x4b800000, v64
	s_nop 0
	v_cndmask_b32_e32 v64, v64, v65, vcc
	v_rsq_f32_e32 v64, v64
	s_nop 0
	v_mul_f32_e32 v65, 0x45800000, v64
	v_cndmask_b32_e32 v64, v64, v65, vcc
	v_pk_mul_f32 v[60:61], v[60:61], v[64:65] op_sel_hi:[1,0]
	v_pk_mul_f32 v[62:63], v[62:63], v[64:65] op_sel_hi:[1,0]
	v_pk_mul_f32 v[68:69], v[58:59], v[64:65] op_sel_hi:[1,0]
	v_pk_mul_f32 v[58:59], v[56:57], v[64:65] op_sel_hi:[1,0]
	v_cvt_pk_bf16_f32 v56, v60, v61
	v_add_co_u32_e32 v60, vcc, s5, v160
	v_cvt_pk_bf16_f32 v57, v62, v63
	v_cvt_pk_bf16_f32 v58, v58, v59
	v_cvt_pk_bf16_f32 v59, v68, v69
	v_addc_co_u32_e32 v61, vcc, 0, v161, vcc
	global_store_dwordx4 v[60:61], v[56:59], off
	v_pk_mul_f32 v[54:55], v[54:55], v[64:65] op_sel_hi:[1,0]
	v_pk_mul_f32 v[52:53], v[52:53], v[64:65] op_sel_hi:[1,0]
	v_pk_mul_f32 v[56:57], v[50:51], v[64:65] op_sel_hi:[1,0]
	v_pk_mul_f32 v[50:51], v[48:49], v[64:65] op_sel_hi:[1,0]
	v_cvt_pk_bf16_f32 v48, v52, v53
	v_cvt_pk_bf16_f32 v49, v54, v55
	v_cvt_pk_bf16_f32 v50, v50, v51
	v_cvt_pk_bf16_f32 v51, v56, v57
	global_store_dwordx4 v[66:67], v[48:51], off offset:256
	s_nop 1
	v_mov_b32_e32 v48, v197
	s_mov_b32 s5, 0x90000
	v_lshl_add_u64 v[50:51], v[160:161], 0, s[14:15]
	s_mov_b64 s[14:15], 0xa0000
	v_fmamk_f32 v48, v48, 0x3a800000, v187
	v_cmp_gt_f32_e32 vcc, s67, v48
	v_mul_f32_e32 v49, 0x4b800000, v48
	s_nop 0
	v_cndmask_b32_e32 v48, v48, v49, vcc
	v_rsq_f32_e32 v48, v48
	s_nop 0
	v_mul_f32_e32 v49, 0x45800000, v48
	v_cndmask_b32_e32 v48, v48, v49, vcc
	v_pk_mul_f32 v[44:45], v[44:45], v[48:49] op_sel_hi:[1,0]
	v_pk_mul_f32 v[46:47], v[46:47], v[48:49] op_sel_hi:[1,0]
	v_pk_mul_f32 v[52:53], v[42:43], v[48:49] op_sel_hi:[1,0]
	v_pk_mul_f32 v[42:43], v[40:41], v[48:49] op_sel_hi:[1,0]
	v_cvt_pk_bf16_f32 v40, v44, v45
	v_add_co_u32_e32 v44, vcc, s5, v160
	v_cvt_pk_bf16_f32 v41, v46, v47
	v_cvt_pk_bf16_f32 v42, v42, v43
	v_cvt_pk_bf16_f32 v43, v52, v53
	v_addc_co_u32_e32 v45, vcc, 0, v161, vcc
	global_store_dwordx4 v[44:45], v[40:43], off
	v_pk_mul_f32 v[38:39], v[38:39], v[48:49] op_sel_hi:[1,0]
	v_pk_mul_f32 v[36:37], v[36:37], v[48:49] op_sel_hi:[1,0]
	v_pk_mul_f32 v[40:41], v[34:35], v[48:49] op_sel_hi:[1,0]
	v_pk_mul_f32 v[34:35], v[32:33], v[48:49] op_sel_hi:[1,0]
	v_cvt_pk_bf16_f32 v32, v36, v37
	v_cvt_pk_bf16_f32 v33, v38, v39
	v_cvt_pk_bf16_f32 v34, v34, v35
	v_cvt_pk_bf16_f32 v35, v40, v41
	global_store_dwordx4 v[50:51], v[32:35], off offset:256
	s_nop 1
	v_mov_b32_e32 v32, v198
	s_mov_b32 s5, 0xa0000
	v_lshl_add_u64 v[34:35], v[160:161], 0, s[14:15]
	s_mov_b64 s[14:15], 0xb0000
	v_fmamk_f32 v32, v32, 0x3a800000, v187
	v_cmp_gt_f32_e32 vcc, s67, v32
	v_mul_f32_e32 v33, 0x4b800000, v32
	s_nop 0
	v_cndmask_b32_e32 v32, v32, v33, vcc
	v_rsq_f32_e32 v32, v32
	s_nop 0
	v_mul_f32_e32 v33, 0x45800000, v32
	v_cndmask_b32_e32 v32, v32, v33, vcc
	v_pk_mul_f32 v[28:29], v[28:29], v[32:33] op_sel_hi:[1,0]
	v_pk_mul_f32 v[30:31], v[30:31], v[32:33] op_sel_hi:[1,0]
	v_pk_mul_f32 v[36:37], v[26:27], v[32:33] op_sel_hi:[1,0]
	v_pk_mul_f32 v[26:27], v[24:25], v[32:33] op_sel_hi:[1,0]
	v_cvt_pk_bf16_f32 v24, v28, v29
	v_add_co_u32_e32 v28, vcc, s5, v160
	v_cvt_pk_bf16_f32 v25, v30, v31
	v_cvt_pk_bf16_f32 v26, v26, v27
	v_cvt_pk_bf16_f32 v27, v36, v37
	v_addc_co_u32_e32 v29, vcc, 0, v161, vcc
	global_store_dwordx4 v[28:29], v[24:27], off
	v_pk_mul_f32 v[22:23], v[22:23], v[32:33] op_sel_hi:[1,0]
	v_pk_mul_f32 v[20:21], v[20:21], v[32:33] op_sel_hi:[1,0]
	v_pk_mul_f32 v[24:25], v[18:19], v[32:33] op_sel_hi:[1,0]
	v_pk_mul_f32 v[18:19], v[16:17], v[32:33] op_sel_hi:[1,0]
	v_cvt_pk_bf16_f32 v16, v20, v21
	v_cvt_pk_bf16_f32 v17, v22, v23
	v_cvt_pk_bf16_f32 v18, v18, v19
	v_cvt_pk_bf16_f32 v19, v24, v25
	global_store_dwordx4 v[34:35], v[16:19], off offset:256
	s_nop 1
	v_mov_b32_e32 v16, v199
	s_mov_b32 s5, 0xb0000
	v_lshl_add_u64 v[18:19], v[160:161], 0, s[14:15]
	v_fmamk_f32 v16, v16, 0x3a800000, v187
	v_cmp_gt_f32_e32 vcc, s67, v16
	v_mul_f32_e32 v17, 0x4b800000, v16
	s_nop 0
	v_cndmask_b32_e32 v16, v16, v17, vcc
	v_rsq_f32_e32 v16, v16
	s_nop 0
	v_mul_f32_e32 v17, 0x45800000, v16
	v_cndmask_b32_e32 v16, v16, v17, vcc
	v_pk_mul_f32 v[12:13], v[12:13], v[16:17] op_sel_hi:[1,0]
	v_pk_mul_f32 v[14:15], v[14:15], v[16:17] op_sel_hi:[1,0]
	v_pk_mul_f32 v[20:21], v[10:11], v[16:17] op_sel_hi:[1,0]
	v_pk_mul_f32 v[10:11], v[8:9], v[16:17] op_sel_hi:[1,0]
	v_cvt_pk_bf16_f32 v8, v12, v13
	v_add_co_u32_e32 v12, vcc, s5, v160
	v_cvt_pk_bf16_f32 v9, v14, v15
	v_cvt_pk_bf16_f32 v10, v10, v11
	v_cvt_pk_bf16_f32 v11, v20, v21
	v_addc_co_u32_e32 v13, vcc, 0, v161, vcc
	global_store_dwordx4 v[12:13], v[8:11], off
	v_pk_mul_f32 v[6:7], v[6:7], v[16:17] op_sel_hi:[1,0]
	v_pk_mul_f32 v[4:5], v[4:5], v[16:17] op_sel_hi:[1,0]
	v_pk_mul_f32 v[8:9], v[2:3], v[16:17] op_sel_hi:[1,0]
	v_pk_mul_f32 v[2:3], v[0:1], v[16:17] op_sel_hi:[1,0]
	v_cvt_pk_bf16_f32 v0, v4, v5
	v_cvt_pk_bf16_f32 v1, v6, v7
	v_cvt_pk_bf16_f32 v2, v2, v3
	v_cvt_pk_bf16_f32 v3, v8, v9
	s_and_b64 vcc, exec, s[38:39]
	global_store_dwordx4 v[18:19], v[0:3], off offset:256
	s_cbranch_vccz .LBB0_492
	s_waitcnt vmcnt(0)
	s_cmpk_gt_u32 s36, 0xff
	s_cbranch_scc1 .LBB0_499
	s_barrier

; #define PG8_STAGE(bufoff, gbase, voff) do { _Pragma("unroll") for (int _i = 0; _i < 2; ++_i) \
;         __builtin_amdgcn_global_load_lds((const unsigned*)((const char*)(gbase) + (voff)[_i]), (PG8_LAS unsigned*)(lds + (bufoff) + ldsw + _i * 8192), 16, 0, 0); } while (0)
; #define PG8_LDA(dst, b, h) do { _Pragma("unroll") for (int m = 0; m < 4; ++m) _Pragma("unroll") for (int k = 0; k < 2; ++k) dst[m][k] = *(const PG8_LAS bf16x8*)(lds + PG8_SA(b, h) + aoff + m * 2048 + k * 1024); } while (0)
; #define PG8_LDB(dst, b, h) do { _Pragma("unroll") for (int n = 0; n < 2; ++n) _Pragma("unroll") for (int k = 0; k < 2; ++k) dst[n][k] = *(const PG8_LAS bf16x8*)(lds + PG8_SB(b, h) + boff + n * 2048 + k * 1024); } while (0)
; #define PG8_WAIT_L(n) asm volatile("s_waitcnt lgkmcnt(" #n ")" ::: "memory")
; #define PG8_BAR __builtin_amdgcn_s_barrier()
; #define PG8_SCHED __builtin_amdgcn_sched_barrier(0)
;     __device__ bool next(int i, pg8::Unit& u) const { if (i != 0 || !valid) return false; u.pm = pm; u.pn = pn; return true; }
; template <class Epi, class Sched, bool STAMP = false>
; __device__ __forceinline__ void gemm_phase(PG8_LAS unsigned char* lds, const Gemm g, const Sched& S, const Epi& E, unsigned long long* stamps) {
;     ...
;         const bool has_next = S.next(ui + 1, nxt);
;         const char* nA = has_next ? (const char*)g.A + (size_t)nxt.pm * tstep : cA; const char* nB = has_next ? (const char*)g.Bt + (size_t)nxt.pn * tstep : cB;
;         for (int t = 0; t < nt; t += 2) {
;             const bool last = (t == nt - 2);
;             const char* a1 = cA + (size_t)(t + 1) * kstep;
;             const char* a2 = last ? nA : cA + (size_t)(t + 2) * kstep; const char* b2 = last ? nB : cB + (size_t)(t + 2) * kstep;
;             const char* a3 = a2 + kstep; const char* b3 = b2 + kstep;
;             if (last && has_next) S.a_ready(nxt);
;             PG8_LDB(B0, 0, 0); PG8_SCHED; PG8_LDA(At, 0, 0); PG8_STAGE(PG8_SA(1, 1), a1 + hstep, voffA);
;             PG8_WAIT_L(8); PG8_BAR; PG8_WAIT_L(0); PG8_MMA(0, 0, At, B0); PG8_BAR; PG8_SCHED;
;     ...
; #pragma unroll
;         for (int a = 0; a < 2; ++a)
; #pragma unroll
;             for (int b = 0; b < 2; ++b)
; #pragma unroll
;                 for (int m = 0; m < 4; ++m)
; #pragma unroll
;                     for (int n = 0; n < 2; ++n) acc[a][b][m][n] = (f32x4){0.f, 0.f, 0.f, 0.f};
;         cur = nxt; cA = nA; cB = nB; ++ui;
.LBB0_1182:
	s_ashr_i32 s7, s6, 31
	v_cmp_lt_i64_e32 vcc, s[12:13], v[136:137]
	s_lshl_b64 s[12:13], s[6:7], 21
	s_add_u32 s12, s45, s12
	s_addc_u32 s13, s46, s13
	s_and_b64 s[14:15], vcc, exec
	s_cselect_b32 s7, s13, s27
	s_cselect_b32 s23, s12, s26
	s_ashr_i32 s5, s4, 31
	s_lshl_b64 s[14:15], s[4:5], 21
	s_add_u32 s20, s47, s14
	s_addc_u32 s21, s48, s15
	s_and_b64 s[14:15], vcc, exec
	s_cselect_b32 s5, s21, s31
	s_cselect_b32 s62, s20, s30
	s_add_u32 s63, s30, 0x100
	v_mov_b32_e32 v0, 0
	s_addc_u32 s64, s31, 0
	s_mov_b32 s65, -2
	s_waitcnt lgkmcnt(0)
	v_mov_b32_e32 v1, v0
	v_mov_b32_e32 v2, v0
	v_mov_b32_e32 v3, v0
	v_mov_b32_e32 v4, v0
	v_mov_b32_e32 v5, v0
	v_mov_b32_e32 v6, v0
	v_mov_b32_e32 v7, v0
	v_mov_b32_e32 v16, v0
	v_mov_b32_e32 v17, v0
	v_mov_b32_e32 v18, v0
	v_mov_b32_e32 v19, v0
	v_mov_b32_e32 v20, v0
	v_mov_b32_e32 v21, v0
	v_mov_b32_e32 v22, v0
	v_mov_b32_e32 v23, v0
	v_mov_b32_e32 v32, v0
	v_mov_b32_e32 v33, v0
	v_mov_b32_e32 v34, v0
	v_mov_b32_e32 v35, v0
	v_mov_b32_e32 v36, v0
	v_mov_b32_e32 v37, v0
	v_mov_b32_e32 v38, v0
	v_mov_b32_e32 v39, v0
	v_mov_b32_e32 v48, v0
	v_mov_b32_e32 v49, v0
	v_mov_b32_e32 v50, v0
	v_mov_b32_e32 v51, v0
	v_mov_b32_e32 v52, v0
	v_mov_b32_e32 v53, v0
	v_mov_b32_e32 v54, v0
	v_mov_b32_e32 v55, v0
	v_mov_b32_e32 v8, v0
	v_mov_b32_e32 v9, v0
	v_mov_b32_e32 v10, v0
	v_mov_b32_e32 v11, v0
	v_mov_b32_e32 v12, v0
	v_mov_b32_e32 v13, v0
	v_mov_b32_e32 v14, v0
	v_mov_b32_e32 v15, v0
	v_mov_b32_e32 v24, v0
	v_mov_b32_e32 v25, v0
	v_mov_b32_e32 v26, v0
	v_mov_b32_e32 v27, v0
	v_mov_b32_e32 v28, v0
	v_mov_b32_e32 v29, v0
	v_mov_b32_e32 v30, v0
	v_mov_b32_e32 v31, v0
	v_mov_b32_e32 v40, v0
	v_mov_b32_e32 v41, v0
	v_mov_b32_e32 v42, v0
	v_mov_b32_e32 v43, v0
	v_mov_b32_e32 v44, v0
	v_mov_b32_e32 v45, v0
	v_mov_b32_e32 v46, v0
	v_mov_b32_e32 v47, v0
	v_mov_b32_e32 v56, v0
	v_mov_b32_e32 v57, v0
	v_mov_b32_e32 v58, v0
	v_mov_b32_e32 v59, v0
	v_mov_b32_e32 v60, v0
	v_mov_b32_e32 v61, v0
	v_mov_b32_e32 v62, v0
	v_mov_b32_e32 v63, v0
	v_mov_b32_e32 v64, v0
	v_mov_b32_e32 v65, v0
	v_mov_b32_e32 v66, v0
	v_mov_b32_e32 v67, v0
	v_mov_b32_e32 v68, v0
	v_mov_b32_e32 v69, v0
	v_mov_b32_e32 v70, v0
	v_mov_b32_e32 v71, v0
	v_mov_b32_e32 v80, v0
	v_mov_b32_e32 v81, v0
	v_mov_b32_e32 v82, v0
	v_mov_b32_e32 v83, v0
	v_mov_b32_e32 v84, v0
	v_mov_b32_e32 v85, v0
	v_mov_b32_e32 v86, v0
	v_mov_b32_e32 v87, v0
	v_mov_b32_e32 v96, v0
	v_mov_b32_e32 v97, v0
	s_waitcnt vmcnt(0)
	v_mov_b32_e32 v98, v0
	v_mov_b32_e32 v99, v0
	v_mov_b32_e32 v100, v0
	v_mov_b32_e32 v101, v0
	v_mov_b32_e32 v102, v0
	v_mov_b32_e32 v103, v0
	v_mov_b32_e32 v112, v0
	v_mov_b32_e32 v113, v0
	v_mov_b32_e32 v114, v0
	v_mov_b32_e32 v115, v0
	v_mov_b32_e32 v116, v0
	v_mov_b32_e32 v117, v0
	v_mov_b32_e32 v118, v0
	v_mov_b32_e32 v119, v0
	v_mov_b32_e32 v72, v0
	v_mov_b32_e32 v73, v0
	v_mov_b32_e32 v74, v0
	v_mov_b32_e32 v75, v0
	v_mov_b32_e32 v76, v0
	v_mov_b32_e32 v77, v0
	v_mov_b32_e32 v78, v0
	v_mov_b32_e32 v79, v0
	v_mov_b32_e32 v88, v0
	v_mov_b32_e32 v89, v0
	v_mov_b32_e32 v90, v0
	v_mov_b32_e32 v91, v0
	v_mov_b32_e32 v92, v0
	v_mov_b32_e32 v93, v0
	v_mov_b32_e32 v94, v0
	v_mov_b32_e32 v95, v0
	v_mov_b32_e32 v104, v0
	v_mov_b32_e32 v105, v0
	v_mov_b32_e32 v106, v0
	v_mov_b32_e32 v107, v0
	v_mov_b32_e32 v108, v0
	v_mov_b32_e32 v109, v0
	v_mov_b32_e32 v110, v0
	v_mov_b32_e32 v111, v0
	v_mov_b32_e32 v120, v0
	v_mov_b32_e32 v121, v0
	v_mov_b32_e32 v122, v0
	v_mov_b32_e32 v123, v0
	v_mov_b32_e32 v124, v0
	v_mov_b32_e32 v125, v0
	v_mov_b32_e32 v126, v0
	v_mov_b32_e32 v127, v0
	v_add_u32_e32 v244, 0x80, v128
	v_add_u32_e32 v245, 0x80, v148
	v_add_u32_e32 v248, 0x10000, v158
	v_add_u32_e32 v249, 0x14000, v158
	v_add_u32_e32 v250, 0x18000, v158
	v_add_u32_e32 v251, 0x1c000, v158
.LBB0_1183:
	s_add_u32 s30, s26, 0x100
	s_addc_u32 s31, s27, 0
	s_add_i32 s14, 0, 0x10000
	ds_read_b128 v[154:157], v248
	ds_read_b128 v[162:165], v248 offset:1024
	ds_read_b128 v[166:169], v248 offset:2048
	ds_read_b128 v[170:173], v248 offset:3072
	s_cmp_eq_u32 s65, 60
	s_cselect_b32 s37, s7, s31
	s_cselect_b32 s36, s23, s30
	s_cselect_b32 s35, s5, s64
	s_cselect_b32 s34, s62, s63
	s_add_i32 m0, s25, 0xc000
	ds_read_b128 v[174:177], v160
	ds_read_b128 v[178:181], v160 offset:1024
	ds_read_b128 v[192:195], v160 offset:2048
	ds_read_b128 v[196:199], v160 offset:3072
	ds_read_b128 v[200:203], v160 offset:4096
	ds_read_b128 v[204:207], v160 offset:5120
	ds_read_b128 v[208:211], v160 offset:6144
	ds_read_b128 v[212:215], v160 offset:7168
	global_load_lds_dwordx4 v150, s[26:27]
	s_add_i32 m0, s25, 0xe000
	s_nop 0
	global_load_lds_dwordx4 v152, s[26:27]
	s_waitcnt lgkmcnt(8)
	s_barrier
	s_waitcnt lgkmcnt(0)
	v_mfma_f32_16x16x32_bf16 v[124:127], v[154:157], v[174:177], v[124:127]
	v_mfma_f32_16x16x32_bf16 v[120:123], v[166:169], v[174:177], v[120:123]
	v_mfma_f32_16x16x32_bf16 v[108:111], v[154:157], v[192:195], v[108:111]
	v_mfma_f32_16x16x32_bf16 v[104:107], v[166:169], v[192:195], v[104:107]
	v_mfma_f32_16x16x32_bf16 v[92:95], v[154:157], v[200:203], v[92:95]
	v_mfma_f32_16x16x32_bf16 v[88:91], v[166:169], v[200:203], v[88:91]
	v_mfma_f32_16x16x32_bf16 v[76:79], v[154:157], v[208:211], v[76:79]
	v_mfma_f32_16x16x32_bf16 v[72:75], v[166:169], v[208:211], v[72:75]
	v_mfma_f32_16x16x32_bf16 v[124:127], v[162:165], v[178:181], v[124:127]
	v_mfma_f32_16x16x32_bf16 v[120:123], v[170:173], v[178:181], v[120:123]
	v_mfma_f32_16x16x32_bf16 v[108:111], v[162:165], v[196:199], v[108:111]
	v_mfma_f32_16x16x32_bf16 v[104:107], v[170:173], v[196:199], v[104:107]
	v_mfma_f32_16x16x32_bf16 v[92:95], v[162:165], v[204:207], v[92:95]
	v_mfma_f32_16x16x32_bf16 v[88:91], v[170:173], v[204:207], v[88:91]
	v_mfma_f32_16x16x32_bf16 v[76:79], v[162:165], v[212:215], v[76:79]
	v_mfma_f32_16x16x32_bf16 v[72:75], v[170:173], v[212:215], v[72:75]
	s_barrier
; #define PG8_STAGE(bufoff, gbase, voff) do { _Pragma("unroll") for (int _i = 0; _i < 2; ++_i) \
;         __builtin_amdgcn_global_load_lds((const unsigned*)((const char*)(gbase) + (voff)[_i]), (PG8_LAS unsigned*)(lds + (bufoff) + ldsw + _i * 8192), 16, 0, 0); } while (0)
; #define PG8_LDA(dst, b, h) do { _Pragma("unroll") for (int m = 0; m < 4; ++m) _Pragma("unroll") for (int k = 0; k < 2; ++k) dst[m][k] = *(const PG8_LAS bf16x8*)(lds + PG8_SA(b, h) + aoff + m * 2048 + k * 1024); } while (0)
; #define PG8_LDB(dst, b, h) do { _Pragma("unroll") for (int n = 0; n < 2; ++n) _Pragma("unroll") for (int k = 0; k < 2; ++k) dst[n][k] = *(const PG8_LAS bf16x8*)(lds + PG8_SB(b, h) + boff + n * 2048 + k * 1024); } while (0)
; #define PG8_MMA(ai, bj, At, Bt) do { __builtin_amdgcn_s_setprio(1); _Pragma("unroll") for (int m = 0; m < 4; ++m) _Pragma("unroll") for (int n = 0; n < 2; ++n) _Pragma("unroll") for (int k = 0; k < 2; ++k) \
;         acc[ai][bj][m][n] = __builtin_amdgcn_mfma_f32_16x16x32_bf16(Bt[n][k], At[m][k], acc[ai][bj][m][n], 0, 0, 0); __builtin_amdgcn_s_setprio(0); } while (0)
; #define PG8_WAIT_V(n) asm volatile("s_waitcnt vmcnt(" #n ")" ::: "memory")
; #define PG8_WAIT_L(n) asm volatile("s_waitcnt lgkmcnt(" #n ")" ::: "memory")
; #define PG8_BAR __builtin_amdgcn_s_barrier()
; #define PG8_SCHED __builtin_amdgcn_sched_barrier(0)
; template <class Epi, class Sched, bool STAMP = false>
; __device__ __forceinline__ void gemm_phase(PG8_LAS unsigned char* lds, const Gemm g, const Sched& S, const Epi& E, unsigned long long* stamps) {
;     ...
;             PG8_LDB(B1, 0, 1); PG8_STAGE(PG8_SB(0, 0), b2, voffB);
;             PG8_BAR; PG8_WAIT_L(0); PG8_MMA(0, 1, At, B1); PG8_BAR;
;             PG8_LDA(At, 0, 1); PG8_STAGE(PG8_SA(0, 0), a2, voffA);
;             PG8_BAR; PG8_WAIT_L(0); PG8_MMA(1, 0, At, B0); PG8_BAR; PG8_SCHED;
;             PG8_STAGE(PG8_SB(0, 1), b2 + hstep, voffB);
;             PG8_WAIT_V(6); PG8_BAR; PG8_MMA(1, 1, At, B1); PG8_BAR;
;             PG8_LDB(B0, 1, 0); PG8_SCHED; PG8_LDA(At, 1, 0); PG8_STAGE(PG8_SA(0, 1), a2 + hstep, voffA);
;             PG8_WAIT_L(8); PG8_BAR; PG8_WAIT_L(0); PG8_MMA(0, 0, At, B0); PG8_BAR; PG8_SCHED;
	s_add_i32 s16, 0, 0x14000
	s_add_i32 s14, s14, s49
	s_mov_b32 m0, s14
	ds_read_b128 v[216:219], v249
	ds_read_b128 v[220:223], v249 offset:1024
	ds_read_b128 v[224:227], v249 offset:2048
	ds_read_b128 v[228:231], v249 offset:3072
	global_load_lds_dwordx4 v128, s[34:35]
	s_add_i32 m0, s14, 0x2000
	s_nop 0
	global_load_lds_dwordx4 v148, s[34:35]
	s_barrier
	s_waitcnt lgkmcnt(0)
	v_mfma_f32_16x16x32_bf16 v[116:119], v[216:219], v[174:177], v[116:119]
	v_mfma_f32_16x16x32_bf16 v[112:115], v[224:227], v[174:177], v[112:115]
	v_mfma_f32_16x16x32_bf16 v[100:103], v[216:219], v[192:195], v[100:103]
	v_mfma_f32_16x16x32_bf16 v[96:99], v[224:227], v[192:195], v[96:99]
	v_mfma_f32_16x16x32_bf16 v[84:87], v[216:219], v[200:203], v[84:87]
	v_mfma_f32_16x16x32_bf16 v[80:83], v[224:227], v[200:203], v[80:83]
	v_mfma_f32_16x16x32_bf16 v[68:71], v[216:219], v[208:211], v[68:71]
	v_mfma_f32_16x16x32_bf16 v[64:67], v[224:227], v[208:211], v[64:67]
	v_mfma_f32_16x16x32_bf16 v[116:119], v[220:223], v[178:181], v[116:119]
	v_mfma_f32_16x16x32_bf16 v[112:115], v[228:231], v[178:181], v[112:115]
	v_mfma_f32_16x16x32_bf16 v[100:103], v[220:223], v[196:199], v[100:103]
	v_mfma_f32_16x16x32_bf16 v[96:99], v[228:231], v[196:199], v[96:99]
	v_mfma_f32_16x16x32_bf16 v[84:87], v[220:223], v[204:207], v[84:87]
	v_mfma_f32_16x16x32_bf16 v[80:83], v[228:231], v[204:207], v[80:83]
	v_mfma_f32_16x16x32_bf16 v[68:71], v[220:223], v[212:215], v[68:71]
	v_mfma_f32_16x16x32_bf16 v[64:67], v[228:231], v[212:215], v[64:67]
	s_mov_b32 m0, s25
	s_barrier
	ds_read_b128 v[174:177], v160 offset:16384
	ds_read_b128 v[178:181], v160 offset:17408
	ds_read_b128 v[192:195], v160 offset:18432
	ds_read_b128 v[196:199], v160 offset:19456
	ds_read_b128 v[200:203], v160 offset:20480
	ds_read_b128 v[204:207], v160 offset:21504
	ds_read_b128 v[208:211], v160 offset:22528
	ds_read_b128 v[212:215], v160 offset:23552
	global_load_lds_dwordx4 v128, s[36:37]
	s_mov_b32 m0, s53
	s_nop 0
	global_load_lds_dwordx4 v148, s[36:37]
	s_barrier
	s_waitcnt lgkmcnt(0)
	v_mfma_f32_16x16x32_bf16 v[60:63], v[154:157], v[174:177], v[60:63]
	v_mfma_f32_16x16x32_bf16 v[56:59], v[166:169], v[174:177], v[56:59]
	v_mfma_f32_16x16x32_bf16 v[44:47], v[154:157], v[192:195], v[44:47]
	v_mfma_f32_16x16x32_bf16 v[40:43], v[166:169], v[192:195], v[40:43]
	v_mfma_f32_16x16x32_bf16 v[28:31], v[154:157], v[200:203], v[28:31]
	v_mfma_f32_16x16x32_bf16 v[24:27], v[166:169], v[200:203], v[24:27]
	v_mfma_f32_16x16x32_bf16 v[12:15], v[154:157], v[208:211], v[12:15]
	v_mfma_f32_16x16x32_bf16 v[8:11], v[166:169], v[208:211], v[8:11]
	v_mfma_f32_16x16x32_bf16 v[60:63], v[162:165], v[178:181], v[60:63]
	v_mfma_f32_16x16x32_bf16 v[56:59], v[170:173], v[178:181], v[56:59]
	v_mfma_f32_16x16x32_bf16 v[44:47], v[162:165], v[196:199], v[44:47]
	v_mfma_f32_16x16x32_bf16 v[40:43], v[170:173], v[196:199], v[40:43]
	v_mfma_f32_16x16x32_bf16 v[28:31], v[162:165], v[204:207], v[28:31]
	v_mfma_f32_16x16x32_bf16 v[24:27], v[170:173], v[204:207], v[24:27]
	v_mfma_f32_16x16x32_bf16 v[12:15], v[162:165], v[212:215], v[12:15]
	v_mfma_f32_16x16x32_bf16 v[8:11], v[170:173], v[212:215], v[8:11]
	s_barrier
	s_add_u32 s14, s34, 0x100000
	s_addc_u32 s15, s35, 0
	s_add_i32 s16, s16, s49
	s_mov_b32 m0, s16
	s_nop 0
	global_load_lds_dwordx4 v128, s[14:15]
	s_add_i32 m0, s16, 0x2000
	s_nop 0
	global_load_lds_dwordx4 v148, s[14:15]
	s_waitcnt vmcnt(6)
	s_barrier
	v_mfma_f32_16x16x32_bf16 v[52:55], v[216:219], v[174:177], v[52:55]
	v_mfma_f32_16x16x32_bf16 v[48:51], v[224:227], v[174:177], v[48:51]
	v_mfma_f32_16x16x32_bf16 v[36:39], v[216:219], v[192:195], v[36:39]
	v_mfma_f32_16x16x32_bf16 v[32:35], v[224:227], v[192:195], v[32:35]
	v_mfma_f32_16x16x32_bf16 v[20:23], v[216:219], v[200:203], v[20:23]
	v_mfma_f32_16x16x32_bf16 v[16:19], v[224:227], v[200:203], v[16:19]
	v_mfma_f32_16x16x32_bf16 v[4:7], v[216:219], v[208:211], v[4:7]
	v_mfma_f32_16x16x32_bf16 v[0:3], v[224:227], v[208:211], v[0:3]
	v_mfma_f32_16x16x32_bf16 v[52:55], v[220:223], v[178:181], v[52:55]
	v_mfma_f32_16x16x32_bf16 v[48:51], v[228:231], v[178:181], v[48:51]
	v_mfma_f32_16x16x32_bf16 v[36:39], v[220:223], v[196:199], v[36:39]
	v_mfma_f32_16x16x32_bf16 v[32:35], v[228:231], v[196:199], v[32:35]
	v_mfma_f32_16x16x32_bf16 v[20:23], v[220:223], v[204:207], v[20:23]
	v_mfma_f32_16x16x32_bf16 v[16:19], v[228:231], v[204:207], v[16:19]
	v_mfma_f32_16x16x32_bf16 v[4:7], v[220:223], v[212:215], v[4:7]
	v_mfma_f32_16x16x32_bf16 v[0:3], v[228:231], v[212:215], v[0:3]
	s_add_i32 s16, 0, 0x18000
	s_barrier
	ds_read_b128 v[154:157], v250
	ds_read_b128 v[162:165], v250 offset:1024
	ds_read_b128 v[166:169], v250 offset:2048
	ds_read_b128 v[170:173], v250 offset:3072
	s_add_u32 s14, s36, 0x100000
	s_addc_u32 s15, s37, 0
	s_mov_b32 m0, s56
	ds_read_b128 v[174:177], v160 offset:32768
	ds_read_b128 v[178:181], v160 offset:33792
	ds_read_b128 v[192:195], v160 offset:34816
	ds_read_b128 v[196:199], v160 offset:35840
	ds_read_b128 v[200:203], v160 offset:36864
	ds_read_b128 v[204:207], v160 offset:37888
	ds_read_b128 v[208:211], v160 offset:38912
	ds_read_b128 v[212:215], v160 offset:39936
	global_load_lds_dwordx4 v128, s[14:15]
	s_mov_b32 m0, s57
	s_nop 0
	global_load_lds_dwordx4 v148, s[14:15]
	s_waitcnt lgkmcnt(8)
	s_barrier
; #define PG8_STAGE(bufoff, gbase, voff) do { _Pragma("unroll") for (int _i = 0; _i < 2; ++_i) \
;         __builtin_amdgcn_global_load_lds((const unsigned*)((const char*)(gbase) + (voff)[_i]), (PG8_LAS unsigned*)(lds + (bufoff) + ldsw + _i * 8192), 16, 0, 0); } while (0)
; #define PG8_LDA(dst, b, h) do { _Pragma("unroll") for (int m = 0; m < 4; ++m) _Pragma("unroll") for (int k = 0; k < 2; ++k) dst[m][k] = *(const PG8_LAS bf16x8*)(lds + PG8_SA(b, h) + aoff + m * 2048 + k * 1024); } while (0)
; #define PG8_LDB(dst, b, h) do { _Pragma("unroll") for (int n = 0; n < 2; ++n) _Pragma("unroll") for (int k = 0; k < 2; ++k) dst[n][k] = *(const PG8_LAS bf16x8*)(lds + PG8_SB(b, h) + boff + n * 2048 + k * 1024); } while (0)
; #define PG8_MMA(ai, bj, At, Bt) do { __builtin_amdgcn_s_setprio(1); _Pragma("unroll") for (int m = 0; m < 4; ++m) _Pragma("unroll") for (int n = 0; n < 2; ++n) _Pragma("unroll") for (int k = 0; k < 2; ++k) \
;         acc[ai][bj][m][n] = __builtin_amdgcn_mfma_f32_16x16x32_bf16(Bt[n][k], At[m][k], acc[ai][bj][m][n], 0, 0, 0); __builtin_amdgcn_s_setprio(0); } while (0)
; #define PG8_WAIT_L(n) asm volatile("s_waitcnt lgkmcnt(" #n ")" ::: "memory")
; #define PG8_BAR __builtin_amdgcn_s_barrier()
; #define PG8_SCHED __builtin_amdgcn_sched_barrier(0)
; template <class Epi, class Sched, bool STAMP = false>
; __device__ __forceinline__ void gemm_phase(PG8_LAS unsigned char* lds, const Gemm g, const Sched& S, const Epi& E, unsigned long long* stamps) {
;     ...
;             PG8_WAIT_L(8); PG8_BAR; PG8_WAIT_L(0); PG8_MMA(0, 0, At, B0); PG8_BAR; PG8_SCHED;
;             PG8_LDB(B1, 1, 1); PG8_STAGE(PG8_SB(1, 0), b3, voffB);
;             PG8_BAR; PG8_WAIT_L(0); PG8_MMA(0, 1, At, B1); PG8_BAR;
;             PG8_LDA(At, 1, 1); PG8_STAGE(PG8_SA(1, 0), a3, voffA);
;             PG8_BAR; PG8_WAIT_L(0); PG8_MMA(1, 0, At, B0); PG8_BAR; PG8_SCHED;
;             PG8_STAGE(PG8_SB(1, 1), b3 + hstep, voffB);
	s_waitcnt lgkmcnt(0)
	v_mfma_f32_16x16x32_bf16 v[124:127], v[154:157], v[174:177], v[124:127]
	v_mfma_f32_16x16x32_bf16 v[120:123], v[166:169], v[174:177], v[120:123]
	v_mfma_f32_16x16x32_bf16 v[108:111], v[154:157], v[192:195], v[108:111]
	v_mfma_f32_16x16x32_bf16 v[104:107], v[166:169], v[192:195], v[104:107]
	v_mfma_f32_16x16x32_bf16 v[92:95], v[154:157], v[200:203], v[92:95]
	v_mfma_f32_16x16x32_bf16 v[88:91], v[166:169], v[200:203], v[88:91]
	v_mfma_f32_16x16x32_bf16 v[76:79], v[154:157], v[208:211], v[76:79]
	v_mfma_f32_16x16x32_bf16 v[72:75], v[166:169], v[208:211], v[72:75]
	v_mfma_f32_16x16x32_bf16 v[124:127], v[162:165], v[178:181], v[124:127]
	v_mfma_f32_16x16x32_bf16 v[120:123], v[170:173], v[178:181], v[120:123]
	v_mfma_f32_16x16x32_bf16 v[108:111], v[162:165], v[196:199], v[108:111]
	v_mfma_f32_16x16x32_bf16 v[104:107], v[170:173], v[196:199], v[104:107]
	v_mfma_f32_16x16x32_bf16 v[92:95], v[162:165], v[204:207], v[92:95]
	v_mfma_f32_16x16x32_bf16 v[88:91], v[170:173], v[204:207], v[88:91]
	v_mfma_f32_16x16x32_bf16 v[76:79], v[162:165], v[212:215], v[76:79]
	v_mfma_f32_16x16x32_bf16 v[72:75], v[170:173], v[212:215], v[72:75]
	s_barrier
	s_add_i32 s17, 0, 0x1c000
	s_add_i32 s14, s16, s49
	s_mov_b32 m0, s14
	ds_read_b128 v[216:219], v251
	ds_read_b128 v[220:223], v251 offset:1024
	ds_read_b128 v[224:227], v251 offset:2048
	ds_read_b128 v[228:231], v251 offset:3072
	global_load_lds_dwordx4 v244, s[34:35]
	s_add_i32 m0, s14, 0x2000
	s_nop 0
	global_load_lds_dwordx4 v245, s[34:35]
	s_barrier
	s_waitcnt lgkmcnt(0)
	v_mfma_f32_16x16x32_bf16 v[116:119], v[216:219], v[174:177], v[116:119]
	v_mfma_f32_16x16x32_bf16 v[112:115], v[224:227], v[174:177], v[112:115]
	v_mfma_f32_16x16x32_bf16 v[100:103], v[216:219], v[192:195], v[100:103]
	v_mfma_f32_16x16x32_bf16 v[96:99], v[224:227], v[192:195], v[96:99]
	v_mfma_f32_16x16x32_bf16 v[84:87], v[216:219], v[200:203], v[84:87]
	v_mfma_f32_16x16x32_bf16 v[80:83], v[224:227], v[200:203], v[80:83]
	v_mfma_f32_16x16x32_bf16 v[68:71], v[216:219], v[208:211], v[68:71]
	v_mfma_f32_16x16x32_bf16 v[64:67], v[224:227], v[208:211], v[64:67]
	v_mfma_f32_16x16x32_bf16 v[116:119], v[220:223], v[178:181], v[116:119]
	v_mfma_f32_16x16x32_bf16 v[112:115], v[228:231], v[178:181], v[112:115]
	v_mfma_f32_16x16x32_bf16 v[100:103], v[220:223], v[196:199], v[100:103]
	v_mfma_f32_16x16x32_bf16 v[96:99], v[228:231], v[196:199], v[96:99]
	v_mfma_f32_16x16x32_bf16 v[84:87], v[220:223], v[204:207], v[84:87]
	v_mfma_f32_16x16x32_bf16 v[80:83], v[228:231], v[204:207], v[80:83]
	v_mfma_f32_16x16x32_bf16 v[68:71], v[220:223], v[212:215], v[68:71]
	v_mfma_f32_16x16x32_bf16 v[64:67], v[228:231], v[212:215], v[64:67]
	s_mov_b32 m0, s59
	s_barrier
	ds_read_b128 v[174:177], v160 offset:49152
	ds_read_b128 v[178:181], v160 offset:50176
	ds_read_b128 v[192:195], v160 offset:51200
	ds_read_b128 v[196:199], v160 offset:52224
	ds_read_b128 v[200:203], v160 offset:53248
	ds_read_b128 v[204:207], v160 offset:54272
	ds_read_b128 v[208:211], v160 offset:55296
	ds_read_b128 v[212:215], v160 offset:56320
	global_load_lds_dwordx4 v244, s[36:37]
	s_mov_b32 m0, s60
	s_nop 0
	global_load_lds_dwordx4 v245, s[36:37]
	s_barrier
	s_waitcnt lgkmcnt(0)
	v_mfma_f32_16x16x32_bf16 v[60:63], v[154:157], v[174:177], v[60:63]
	v_mfma_f32_16x16x32_bf16 v[56:59], v[166:169], v[174:177], v[56:59]
	v_mfma_f32_16x16x32_bf16 v[44:47], v[154:157], v[192:195], v[44:47]
	v_mfma_f32_16x16x32_bf16 v[40:43], v[166:169], v[192:195], v[40:43]
	v_mfma_f32_16x16x32_bf16 v[28:31], v[154:157], v[200:203], v[28:31]
	v_mfma_f32_16x16x32_bf16 v[24:27], v[166:169], v[200:203], v[24:27]
	v_mfma_f32_16x16x32_bf16 v[12:15], v[154:157], v[208:211], v[12:15]
	v_mfma_f32_16x16x32_bf16 v[8:11], v[166:169], v[208:211], v[8:11]
	v_mfma_f32_16x16x32_bf16 v[60:63], v[162:165], v[178:181], v[60:63]
	v_mfma_f32_16x16x32_bf16 v[56:59], v[170:173], v[178:181], v[56:59]
	v_mfma_f32_16x16x32_bf16 v[44:47], v[162:165], v[196:199], v[44:47]
	v_mfma_f32_16x16x32_bf16 v[40:43], v[170:173], v[196:199], v[40:43]
	v_mfma_f32_16x16x32_bf16 v[28:31], v[162:165], v[204:207], v[28:31]
	v_mfma_f32_16x16x32_bf16 v[24:27], v[170:173], v[204:207], v[24:27]
	v_mfma_f32_16x16x32_bf16 v[12:15], v[162:165], v[212:215], v[12:15]
	v_mfma_f32_16x16x32_bf16 v[8:11], v[170:173], v[212:215], v[8:11]
	s_barrier
	s_add_u32 s14, s34, 0x100080
	s_addc_u32 s15, s35, 0
	s_add_i32 s16, s17, s49
	s_mov_b32 m0, s16
	s_nop 0
	global_load_lds_dwordx4 v128, s[14:15]
	s_add_i32 m0, s16, 0x2000
	s_nop 0
	global_load_lds_dwordx4 v148, s[14:15]
	s_waitcnt vmcnt(6)
	s_barrier
; __device__ __forceinline__ unsigned cvt_pk_bf16(float lo, float hi) { const f32x2_cv v = {lo, hi}; const bf16x2_cv b = __builtin_convertvector(v, bf16x2_cv); return __builtin_bit_cast(unsigned, b); }
; #define PG8_MMA(ai, bj, At, Bt) do { __builtin_amdgcn_s_setprio(1); _Pragma("unroll") for (int m = 0; m < 4; ++m) _Pragma("unroll") for (int n = 0; n < 2; ++n) _Pragma("unroll") for (int k = 0; k < 2; ++k) \
;         acc[ai][bj][m][n] = __builtin_amdgcn_mfma_f32_16x16x32_bf16(Bt[n][k], At[m][k], acc[ai][bj][m][n], 0, 0, 0); __builtin_amdgcn_s_setprio(0); } while (0)
; #define PG8_WAIT_V(n) asm volatile("s_waitcnt vmcnt(" #n ")" ::: "memory")
; #define PG8_BAR __builtin_amdgcn_s_barrier()
; template <class Epi, class Sched, bool STAMP = false>
; __device__ __forceinline__ void gemm_phase(PG8_LAS unsigned char* lds, const Gemm g, const Sched& S, const Epi& E, unsigned long long* stamps) {
;     ...
;             PG8_WAIT_V(6); PG8_BAR; PG8_MMA(1, 1, At, B1); PG8_BAR;
;     __device__ __forceinline__ void operator()(const f32x4 (&acc)[2][2][4][2], const pg8::Unit& u, int wr, int wc, int fr, int fq) const {
;         const int row0 = u.pm * 256 + wr * 64 + fr, col0 = u.pn * 256 + wc * 32 + 4 * fq;
; #pragma unroll
;         for (int ai = 0; ai < 2; ++ai)
; #pragma unroll
;             for (int m = 0; m < 4; ++m) {
;                 const int row = row0 + ai * 128 + m * 16;
;                 float* xp = X + (size_t)row * 1024 + col0; bf16_t* bp = XB + (size_t)row * 1024 + col0;
;                 const float* xi = Xp0 ? (row < T_P ? Xp0 + (size_t)row * 1024 + col0 : Xs0 + (size_t)(row - T_P) * 1024 + col0) : xp;
;                 float ss = 0.f;
; #pragma unroll
;                 for (int bj = 0; bj < 2; ++bj)
; #pragma unroll
;                     for (int n = 0; n < 2; ++n) {
;                         f32x4 xv = *(const f32x4*)(xi + bj * 128 + n * 16) + acc[ai][bj][m][n];
;                         *(f32x4*)(xp + bj * 128 + n * 16) = xv;
;                         ss += (xv[0] * xv[0] + xv[1] * xv[1]) + (xv[2] * xv[2] + xv[3] * xv[3]);
;                         u32x2 w; w.x = cvt_pk_bf16(xv[0], xv[1]); w.y = cvt_pk_bf16(xv[2], xv[3]);
;                         *(u32x2*)(bp + bj * 128 + n * 16) = w; }
;                 ss += __shfl_xor(ss, 16); ss += __shfl_xor(ss, 32);
;                 if (fq == 0) atomicAdd(rowss_out + row, ss); }
	v_mfma_f32_16x16x32_bf16 v[52:55], v[216:219], v[174:177], v[52:55]
	v_mfma_f32_16x16x32_bf16 v[48:51], v[224:227], v[174:177], v[48:51]
	v_mfma_f32_16x16x32_bf16 v[36:39], v[216:219], v[192:195], v[36:39]
	v_mfma_f32_16x16x32_bf16 v[32:35], v[224:227], v[192:195], v[32:35]
	v_mfma_f32_16x16x32_bf16 v[20:23], v[216:219], v[200:203], v[20:23]
	v_mfma_f32_16x16x32_bf16 v[16:19], v[224:227], v[200:203], v[16:19]
	v_mfma_f32_16x16x32_bf16 v[4:7], v[216:219], v[208:211], v[4:7]
	v_mfma_f32_16x16x32_bf16 v[0:3], v[224:227], v[208:211], v[0:3]
	v_mfma_f32_16x16x32_bf16 v[52:55], v[220:223], v[178:181], v[52:55]
	v_mfma_f32_16x16x32_bf16 v[48:51], v[228:231], v[178:181], v[48:51]
	v_mfma_f32_16x16x32_bf16 v[36:39], v[220:223], v[196:199], v[36:39]
	v_mfma_f32_16x16x32_bf16 v[32:35], v[228:231], v[196:199], v[32:35]
	v_mfma_f32_16x16x32_bf16 v[20:23], v[220:223], v[204:207], v[20:23]
	v_mfma_f32_16x16x32_bf16 v[16:19], v[228:231], v[204:207], v[16:19]
	v_mfma_f32_16x16x32_bf16 v[4:7], v[220:223], v[212:215], v[4:7]
	v_mfma_f32_16x16x32_bf16 v[0:3], v[228:231], v[212:215], v[0:3]
	s_add_i32 s65, s65, 2
	s_add_u32 s63, s63, 0x100
	s_addc_u32 s64, s64, 0
	s_cmp_gt_u32 s65, 61
	s_mov_b64 s[26:27], s[30:31]
	s_barrier
	s_cbranch_scc0 .LBB0_1183
	v_lshl_add_u32 v156, s22, 8, v139
	v_ashrrev_i32_e32 v157, 31, v156
	v_lshl_or_b32 v154, s24, 8, v159
	v_lshlrev_b64 v[162:163], 12, v[156:157]
	v_ashrrev_i32_e32 v155, 31, v154
	v_lshl_add_u64 v[162:163], s[84:85], 0, v[162:163]
	v_lshl_add_u64 v[170:171], v[154:155], 2, v[162:163]
	global_load_dwordx4 v[192:195], v[170:171], off
	global_load_dwordx4 v[196:199], v[170:171], off offset:64
	global_load_dwordx4 v[200:203], v[170:171], off offset:512
	global_load_dwordx4 v[204:207], v[170:171], off offset:576
	v_add_co_u32_e32 v224, vcc, 0x10000, v170
	s_nop 1
	v_addc_co_u32_e32 v225, vcc, 0, v171, vcc
	global_load_dwordx4 v[208:211], v[224:225], off
	global_load_dwordx4 v[212:215], v[224:225], off offset:64
	global_load_dwordx4 v[216:219], v[224:225], off offset:512
	global_load_dwordx4 v[220:223], v[224:225], off offset:576
	v_lshlrev_b64 v[166:167], 11, v[156:157]
	v_lshl_add_u64 v[166:167], s[0:1], 0, v[166:167]
	v_lshl_add_u64 v[172:173], v[154:155], 1, v[166:167]
	v_xor_b32_e32 v161, 32, v189
	s_waitcnt vmcnt(4)
	v_mov_b32_e32 v162, v192
	v_mov_b32_e32 v163, v193
	v_mov_b32_e32 v164, v194
	v_mov_b32_e32 v165, v195
	v_pk_add_f32 v[126:127], v[126:127], v[164:165]
	v_pk_add_f32 v[124:125], v[124:125], v[162:163]
	v_cvt_pk_bf16_f32 v163, v126, v127
	v_cvt_pk_bf16_f32 v162, v124, v125
	global_store_dwordx4 v[170:171], v[124:127], off
	global_store_dwordx2 v[172:173], v[162:163], off
	s_nop 1
	v_mov_b32_e32 v162, v196
	v_mov_b32_e32 v163, v197
	v_mov_b32_e32 v164, v198
	v_mov_b32_e32 v165, v199
	v_pk_add_f32 v[122:123], v[122:123], v[164:165]
	v_pk_add_f32 v[120:121], v[120:121], v[162:163]
	v_cvt_pk_bf16_f32 v163, v122, v123
	v_cvt_pk_bf16_f32 v162, v120, v121
	global_store_dwordx4 v[170:171], v[120:123], off offset:64
	global_store_dwordx2 v[172:173], v[162:163], off offset:32
	s_nop 1
	v_mov_b32_e32 v162, v200
	v_mov_b32_e32 v163, v201
	v_mov_b32_e32 v164, v202
	v_mov_b32_e32 v165, v203
	v_pk_add_f32 v[164:165], v[118:119], v[164:165]
	v_pk_add_f32 v[162:163], v[116:117], v[162:163]
	v_cvt_pk_bf16_f32 v117, v164, v165
	v_cvt_pk_bf16_f32 v116, v162, v163
	global_store_dwordx4 v[170:171], v[162:165], off offset:512
	global_store_dwordx2 v[172:173], v[116:117], off offset:256
	s_nop 1
	v_mov_b32_e32 v166, v204
	v_mov_b32_e32 v167, v205
	v_mov_b32_e32 v168, v206
	v_mov_b32_e32 v169, v207
	v_mul_f32_e32 v118, v125, v125
	v_mul_f32_e32 v119, v127, v127
	v_fmac_f32_e32 v118, v124, v124
	v_fmac_f32_e32 v119, v126, v126
	v_add_f32_e32 v118, v118, v119
	v_mul_f32_e32 v119, v121, v121
	v_mul_f32_e32 v121, v123, v123
	v_fmac_f32_e32 v119, v120, v120
	v_fmac_f32_e32 v121, v122, v122
	v_add_f32_e32 v119, v119, v121
	v_add_f32_e32 v118, v118, v119
	v_mul_f32_e32 v119, v163, v163
	v_mul_f32_e32 v120, v165, v165
	v_fmac_f32_e32 v119, v162, v162
	v_fmac_f32_e32 v120, v164, v164
	v_add_f32_e32 v119, v119, v120
	v_and_b32_e32 v117, 64, v189
	v_add_f32_e32 v122, v118, v119
	v_xor_b32_e32 v116, 16, v189
	v_add_u32_e32 v117, 64, v117
	v_cmp_lt_i32_e32 vcc, v116, v117
	v_pk_add_f32 v[120:121], v[114:115], v[168:169]
	v_pk_add_f32 v[118:119], v[112:113], v[166:167]
	v_mul_f32_e32 v113, v121, v121
	v_mul_f32_e32 v112, v119, v119
	v_fmac_f32_e32 v112, v118, v118
	v_fmac_f32_e32 v113, v120, v120
	v_cndmask_b32_e32 v116, v189, v116, vcc
	v_add_f32_e32 v112, v112, v113
	v_lshlrev_b32_e32 v116, 2, v116
	v_add_f32_e32 v112, v122, v112
	ds_bpermute_b32 v113, v116, v112
	v_cmp_lt_i32_e32 vcc, v161, v117
	global_store_dwordx4 v[170:171], v[118:121], off offset:576
	s_waitcnt lgkmcnt(0)
	v_add_f32_e32 v115, v112, v113
	v_cndmask_b32_e32 v114, v189, v161, vcc
	v_lshlrev_b32_e32 v114, 2, v114
	ds_bpermute_b32 v117, v114, v115
	v_cvt_pk_bf16_f32 v112, v118, v119
	v_cvt_pk_bf16_f32 v113, v120, v121
	global_store_dwordx2 v[172:173], v[112:113], off offset:288
	v_lshl_add_u64 v[112:113], v[156:157], 2, s[2:3]
	s_and_saveexec_b64 s[22:23], s[38:39]
	s_cbranch_execz .LBB0_1186
	s_waitcnt lgkmcnt(0)
	v_add_f32_e32 v115, v115, v117
	global_atomic_add_f32 v[112:113], v115, off

; #define PG8_STAGE(bufoff, gbase, voff) do { _Pragma("unroll") for (int _i = 0; _i < 2; ++_i) \
;         __builtin_amdgcn_global_load_lds((const unsigned*)((const char*)(gbase) + (voff)[_i]), (PG8_LAS unsigned*)(lds + (bufoff) + ldsw + _i * 8192), 16, 0, 0); } while (0)
; #define PG8_WAIT_V(n) asm volatile("s_waitcnt vmcnt(" #n ")" ::: "memory")
; #define PG8_BAR __builtin_amdgcn_s_barrier()
;     __device__ bool next(int i, pg8::Unit& u) const { if (i != 0 || !valid) return false; u.pm = pm; u.pn = pn; return true; }
; template <class Epi, class Sched, bool STAMP = false>
; __device__ __forceinline__ void gemm_phase(PG8_LAS unsigned char* lds, const Gemm g, const Sched& S, const Epi& E, unsigned long long* stamps) {
;     ...
;     const int aoff = lds_byte(wr * 64 + fr, fq * 8), boff = lds_byte(wc * 32 + fr, fq * 8);
;     ...
;     Unit cur, nxt; int ui = 0;
;     if (!S.next(0, cur)) return;
;     f32x4 acc[2][2][4][2];
; #pragma unroll
;     for (int a = 0; a < 2; ++a)
; #pragma unroll
;         for (int b = 0; b < 2; ++b)
; #pragma unroll
;             for (int m = 0; m < 4; ++m)
; #pragma unroll
;                 for (int n = 0; n < 2; ++n) acc[a][b][m][n] = (f32x4){0.f, 0.f, 0.f, 0.f};
;     bf16x8 At[4][2], B0[2][2], B1[2][2];
;     const char* cA = (const char*)g.A + (size_t)cur.pm * tstep; const char* cB = (const char*)g.Bt + (size_t)cur.pn * tstep;
;     S.a_ready(cur);
;     PG8_STAGE(PG8_SB(0, 0), cB, voffB); PG8_STAGE(PG8_SA(0, 0), cA, voffA); PG8_STAGE(PG8_SB(0, 1), cB + hstep, voffB); PG8_STAGE(PG8_SA(0, 1), cA + hstep, voffA);
;     if (wr == 1) PG8_BAR;
;     PG8_WAIT_V(4); PG8_BAR;
;     PG8_STAGE(PG8_SB(1, 0), cB + kstep, voffB); PG8_STAGE(PG8_SA(1, 0), cA + kstep, voffA); PG8_STAGE(PG8_SB(1, 1), cB + hstep + kstep, voffB);
;     PG8_WAIT_V(6); PG8_BAR;
.LBB0_1206:
	v_bfe_u32 v139, v12, 4, 2
	s_lshl_b32 s6, s6, 5
	v_and_b32_e32 v154, 15, v12
	v_lshlrev_b32_e32 v17, 4, v139
	v_lshlrev_b32_e32 v12, 2, v12
	s_and_b32 s36, s6, 0x60
	s_add_i32 m0, s27, 0x18000
	v_lshl_add_u64 v[6:7], v[6:7], 0, s[18:19]
	s_lshl_b32 s35, s7, 6
	v_lshl_or_b32 v17, v154, 6, v17
	s_lshl_b32 s7, s7, 13
	v_and_b32_e32 v12, 32, v12
	s_lshl_b32 s6, s36, 7
	s_waitcnt vmcnt(4)
	s_barrier
	global_load_lds_dwordx4 v[6:7], off
	v_lshl_add_u64 v[4:5], v[4:5], 0, s[18:19]
	s_add_i32 m0, s27, 0x1a000
	s_add_i32 s37, s27, 0x8000
	s_add_i32 s38, s27, 0xa000
	v_bitop3_b32 v155, v17, s6, v12 bitop3:0xde
	global_load_lds_dwordx4 v[4:5], off
	v_lshl_add_u64 v[2:3], v[2:3], 0, s[18:19]
	s_mov_b32 m0, s37
	s_add_u32 s6, s0, 0x100080
	v_bitop3_b32 v18, v17, s7, v12 bitop3:0xde
	global_load_lds_dwordx4 v[2:3], off
	v_lshl_add_u64 v[0:1], v[0:1], 0, s[18:19]
	s_mov_b32 m0, s38
	s_addc_u32 s7, s1, 0
	global_load_lds_dwordx4 v[0:1], off
	s_add_i32 m0, s27, 0x1c000
	v_lshl_add_u64 v[0:1], s[6:7], 0, v[128:129]
	global_load_lds_dwordx4 v[0:1], off
	v_lshl_add_u64 v[0:1], s[6:7], 0, v[148:149]
	s_add_i32 m0, s27, 0x1e000
	s_lshl_b32 s4, s4, 16
	global_load_lds_dwordx4 v[0:1], off
	s_and_b32 s4, s4, 0x600000
	s_or_b32 s4, s4, s5
	v_lshlrev_b32_e32 v0, 15, v14
	v_and_b32_e32 v0, 0x7fff0000, v0
	s_add_u32 s4, s10, s4
	v_lshl_add_u32 v0, v13, 12, v0
	s_addc_u32 s5, s42, 0
	v_or_b32_e32 v0, v0, v15
	s_add_u32 s4, s4, 0xd600080
	v_add_lshl_u32 v0, v0, v16, 1
	v_mov_b32_e32 v1, v129
	s_addc_u32 s5, s5, 0
	v_lshl_add_u64 v[150:151], s[4:5], 0, v[0:1]
	v_lshlrev_b32_e32 v0, 15, v8
	v_and_b32_e32 v0, 0x7fff0000, v0
	v_lshl_add_u32 v0, v9, 12, v0
	v_or_b32_e32 v0, v0, v10
	s_waitcnt vmcnt(6)
	v_add_lshl_u32 v0, v0, v11, 1
	v_lshl_add_u64 v[152:153], s[4:5], 0, v[0:1]
	v_mov_b32_e32 v0, 0
	s_mov_b32 s39, -2
	s_mov_b64 s[4:5], 0
	v_add_u32_e32 v156, 0, v18
	v_mov_b32_e32 v1, v0
	v_mov_b32_e32 v2, v0
	v_mov_b32_e32 v3, v0
	v_mov_b32_e32 v4, v0
	v_mov_b32_e32 v5, v0
	v_mov_b32_e32 v6, v0
	v_mov_b32_e32 v7, v0
	v_mov_b32_e32 v8, v0
	v_mov_b32_e32 v9, v0
	v_mov_b32_e32 v10, v0
	v_mov_b32_e32 v11, v0
	v_mov_b32_e32 v12, v0
	v_mov_b32_e32 v13, v0
	v_mov_b32_e32 v14, v0
	v_mov_b32_e32 v15, v0
	v_mov_b32_e32 v24, v0
	v_mov_b32_e32 v25, v0
	v_mov_b32_e32 v26, v0
	v_mov_b32_e32 v27, v0
	v_mov_b32_e32 v28, v0
	v_mov_b32_e32 v29, v0
	v_mov_b32_e32 v30, v0
	v_mov_b32_e32 v31, v0
	v_mov_b32_e32 v40, v0
	v_mov_b32_e32 v41, v0
	v_mov_b32_e32 v42, v0
	v_mov_b32_e32 v43, v0
	v_mov_b32_e32 v44, v0
	v_mov_b32_e32 v45, v0
	v_mov_b32_e32 v46, v0
	v_mov_b32_e32 v47, v0
	v_mov_b32_e32 v16, v0
	v_mov_b32_e32 v17, v0
	v_mov_b32_e32 v18, v0
	v_mov_b32_e32 v19, v0
	v_mov_b32_e32 v20, v0
	v_mov_b32_e32 v21, v0
	v_mov_b32_e32 v22, v0
	v_mov_b32_e32 v23, v0
	v_mov_b32_e32 v32, v0
	v_mov_b32_e32 v33, v0
	v_mov_b32_e32 v34, v0
	v_mov_b32_e32 v35, v0
	v_mov_b32_e32 v36, v0
	v_mov_b32_e32 v37, v0
	v_mov_b32_e32 v38, v0
	v_mov_b32_e32 v39, v0
	v_mov_b32_e32 v48, v0
	v_mov_b32_e32 v49, v0
	v_mov_b32_e32 v50, v0
	v_mov_b32_e32 v51, v0
	v_mov_b32_e32 v52, v0
	v_mov_b32_e32 v53, v0
	v_mov_b32_e32 v54, v0
	v_mov_b32_e32 v55, v0
	v_mov_b32_e32 v56, v0
	v_mov_b32_e32 v57, v0
	v_mov_b32_e32 v58, v0
	v_mov_b32_e32 v59, v0
	v_mov_b32_e32 v60, v0
	v_mov_b32_e32 v61, v0
	v_mov_b32_e32 v62, v0
	v_mov_b32_e32 v63, v0
	v_mov_b32_e32 v64, v0
	v_mov_b32_e32 v65, v0
	v_mov_b32_e32 v66, v0
	v_mov_b32_e32 v67, v0
	v_mov_b32_e32 v68, v0
	v_mov_b32_e32 v69, v0
	v_mov_b32_e32 v70, v0
	v_mov_b32_e32 v71, v0
	v_mov_b32_e32 v72, v0
	v_mov_b32_e32 v73, v0
	v_mov_b32_e32 v74, v0
	v_mov_b32_e32 v75, v0
	v_mov_b32_e32 v76, v0
	v_mov_b32_e32 v77, v0
	v_mov_b32_e32 v78, v0
	s_waitcnt vmcnt(0)
	v_mov_b32_e32 v79, v0
	v_mov_b32_e32 v84, v0
	v_mov_b32_e32 v85, v0
	v_mov_b32_e32 v86, v0
	v_mov_b32_e32 v87, v0
	v_mov_b32_e32 v92, v0
	v_mov_b32_e32 v93, v0
	v_mov_b32_e32 v94, v0
	v_mov_b32_e32 v95, v0
	v_mov_b32_e32 v100, v0
	v_mov_b32_e32 v101, v0
	v_mov_b32_e32 v102, v0
	v_mov_b32_e32 v103, v0
	v_mov_b32_e32 v108, v0
	v_mov_b32_e32 v109, v0
	v_mov_b32_e32 v110, v0
	v_mov_b32_e32 v111, v0
	v_mov_b32_e32 v80, v0
	v_mov_b32_e32 v81, v0
	v_mov_b32_e32 v82, v0
	v_mov_b32_e32 v83, v0
	v_mov_b32_e32 v88, v0
	v_mov_b32_e32 v89, v0
	v_mov_b32_e32 v90, v0
	v_mov_b32_e32 v91, v0
	v_mov_b32_e32 v96, v0
	v_mov_b32_e32 v97, v0
	v_mov_b32_e32 v98, v0
	v_mov_b32_e32 v99, v0
	v_mov_b32_e32 v104, v0
	v_mov_b32_e32 v105, v0
	v_mov_b32_e32 v106, v0
	v_mov_b32_e32 v107, v0
	v_mov_b32_e32 v112, v0
	v_mov_b32_e32 v113, v0
	v_mov_b32_e32 v114, v0
	v_mov_b32_e32 v115, v0
	v_mov_b32_e32 v116, v0
	v_mov_b32_e32 v117, v0
	v_mov_b32_e32 v118, v0
	v_mov_b32_e32 v119, v0
	v_mov_b32_e32 v120, v0
	v_mov_b32_e32 v121, v0
	v_mov_b32_e32 v122, v0
	v_mov_b32_e32 v123, v0
	v_mov_b32_e32 v124, v0
	v_mov_b32_e32 v125, v0
	v_mov_b32_e32 v126, v0
	v_mov_b32_e32 v127, v0
	s_barrier
	v_add_u32_e32 v244, 0x80, v128
	v_add_u32_e32 v245, 0x80, v148
	v_add_u32_e32 v248, 0x10000, v155
	v_add_u32_e32 v249, 0x14000, v155
	v_add_u32_e32 v250, 0x18000, v155
	v_add_u32_e32 v251, 0x1c000, v155
; #define PG8_STAGE(bufoff, gbase, voff) do { _Pragma("unroll") for (int _i = 0; _i < 2; ++_i) \
;         __builtin_amdgcn_global_load_lds((const unsigned*)((const char*)(gbase) + (voff)[_i]), (PG8_LAS unsigned*)(lds + (bufoff) + ldsw + _i * 8192), 16, 0, 0); } while (0)
; #define PG8_LDA(dst, b, h) do { _Pragma("unroll") for (int m = 0; m < 4; ++m) _Pragma("unroll") for (int k = 0; k < 2; ++k) dst[m][k] = *(const PG8_LAS bf16x8*)(lds + PG8_SA(b, h) + aoff + m * 2048 + k * 1024); } while (0)
; #define PG8_LDB(dst, b, h) do { _Pragma("unroll") for (int n = 0; n < 2; ++n) _Pragma("unroll") for (int k = 0; k < 2; ++k) dst[n][k] = *(const PG8_LAS bf16x8*)(lds + PG8_SB(b, h) + boff + n * 2048 + k * 1024); } while (0)
; #define PG8_MMA(ai, bj, At, Bt) do { __builtin_amdgcn_s_setprio(1); _Pragma("unroll") for (int m = 0; m < 4; ++m) _Pragma("unroll") for (int n = 0; n < 2; ++n) _Pragma("unroll") for (int k = 0; k < 2; ++k) \
;         acc[ai][bj][m][n] = __builtin_amdgcn_mfma_f32_16x16x32_bf16(Bt[n][k], At[m][k], acc[ai][bj][m][n], 0, 0, 0); __builtin_amdgcn_s_setprio(0); } while (0)
; #define PG8_WAIT_L(n) asm volatile("s_waitcnt lgkmcnt(" #n ")" ::: "memory")
; #define PG8_BAR __builtin_amdgcn_s_barrier()
; #define PG8_SCHED __builtin_amdgcn_sched_barrier(0)
; template <class Epi, class Sched, bool STAMP = false>
; __device__ __forceinline__ void gemm_phase(PG8_LAS unsigned char* lds, const Gemm g, const Sched& S, const Epi& E, unsigned long long* stamps) {
;     ...
;         for (int t = 0; t < nt; t += 2) {
;             const bool last = (t == nt - 2);
;             const char* a1 = cA + (size_t)(t + 1) * kstep;
;             const char* a2 = last ? nA : cA + (size_t)(t + 2) * kstep; const char* b2 = last ? nB : cB + (size_t)(t + 2) * kstep;
;             const char* a3 = a2 + kstep; const char* b3 = b2 + kstep;
;             if (last && has_next) S.a_ready(nxt);
;             PG8_LDB(B0, 0, 0); PG8_SCHED; PG8_LDA(At, 0, 0); PG8_STAGE(PG8_SA(1, 1), a1 + hstep, voffA);
;             PG8_WAIT_L(8); PG8_BAR; PG8_WAIT_L(0); PG8_MMA(0, 0, At, B0); PG8_BAR; PG8_SCHED;
;             PG8_LDB(B1, 0, 1); PG8_STAGE(PG8_SB(0, 0), b2, voffB);
;             PG8_BAR; PG8_WAIT_L(0); PG8_MMA(0, 1, At, B1); PG8_BAR;
;             PG8_LDA(At, 0, 1); PG8_STAGE(PG8_SA(0, 0), a2, voffA);
;             PG8_BAR; PG8_WAIT_L(0); PG8_MMA(1, 0, At, B0); PG8_BAR; PG8_SCHED;
.LBB0_1207:
	s_add_u32 s6, s4, 0x100
	s_addc_u32 s7, s5, 0
	s_cmp_lg_u32 s39, 4
	s_cselect_b32 s12, s6, 0
	s_cselect_b32 s13, s7, 0
	s_add_u32 s20, s2, s12
	s_addc_u32 s21, s3, s13
	s_add_i32 s14, 0, 0x10000
	ds_read_b128 v[158:161], v248
	ds_read_b128 v[162:165], v248 offset:1024
	ds_read_b128 v[166:169], v248 offset:2048
	ds_read_b128 v[170:173], v248 offset:3072
	s_add_u32 s12, s0, s12
	s_addc_u32 s13, s1, s13
	v_lshl_add_u64 v[182:183], v[150:151], 0, s[4:5]
	s_add_i32 m0, s27, 0xc000
	ds_read_b128 v[174:177], v156
	ds_read_b128 v[178:181], v156 offset:1024
	ds_read_b128 v[192:195], v156 offset:2048
	ds_read_b128 v[196:199], v156 offset:3072
	ds_read_b128 v[200:203], v156 offset:4096
	ds_read_b128 v[204:207], v156 offset:5120
	ds_read_b128 v[208:211], v156 offset:6144
	ds_read_b128 v[212:215], v156 offset:7168
	global_load_lds_dwordx4 v[182:183], off
	v_lshl_add_u64 v[182:183], v[152:153], 0, s[4:5]
	s_add_i32 m0, s27, 0xe000
	s_nop 0
	global_load_lds_dwordx4 v[182:183], off
	s_waitcnt lgkmcnt(8)
	s_barrier
	s_waitcnt lgkmcnt(0)
	v_mfma_f32_16x16x32_bf16 v[124:127], v[158:161], v[174:177], v[124:127]
	v_mfma_f32_16x16x32_bf16 v[120:123], v[166:169], v[174:177], v[120:123]
	v_mfma_f32_16x16x32_bf16 v[116:119], v[158:161], v[192:195], v[116:119]
	v_mfma_f32_16x16x32_bf16 v[112:115], v[166:169], v[192:195], v[112:115]
	v_mfma_f32_16x16x32_bf16 v[104:107], v[158:161], v[200:203], v[104:107]
	v_mfma_f32_16x16x32_bf16 v[96:99], v[166:169], v[200:203], v[96:99]
	v_mfma_f32_16x16x32_bf16 v[88:91], v[158:161], v[208:211], v[88:91]
	v_mfma_f32_16x16x32_bf16 v[80:83], v[166:169], v[208:211], v[80:83]
	v_mfma_f32_16x16x32_bf16 v[124:127], v[162:165], v[178:181], v[124:127]
	v_mfma_f32_16x16x32_bf16 v[120:123], v[170:173], v[178:181], v[120:123]
	v_mfma_f32_16x16x32_bf16 v[116:119], v[162:165], v[196:199], v[116:119]
	v_mfma_f32_16x16x32_bf16 v[112:115], v[170:173], v[196:199], v[112:115]
	v_mfma_f32_16x16x32_bf16 v[104:107], v[162:165], v[204:207], v[104:107]
	v_mfma_f32_16x16x32_bf16 v[96:99], v[170:173], v[204:207], v[96:99]
	v_mfma_f32_16x16x32_bf16 v[88:91], v[162:165], v[212:215], v[88:91]
	v_mfma_f32_16x16x32_bf16 v[80:83], v[170:173], v[212:215], v[80:83]
	s_barrier
	s_add_i32 s15, 0, 0x14000
	s_add_i32 s4, s14, s26
	v_lshl_add_u64 v[182:183], s[12:13], 0, v[128:129]
	s_mov_b32 m0, s4
	ds_read_b128 v[216:219], v249
	ds_read_b128 v[220:223], v249 offset:1024
	ds_read_b128 v[224:227], v249 offset:2048
	ds_read_b128 v[228:231], v249 offset:3072
	global_load_lds_dwordx4 v128, s[12:13]
	v_lshl_add_u64 v[232:233], s[12:13], 0, v[148:149]
	s_add_i32 m0, s4, 0x2000
	s_nop 0
	global_load_lds_dwordx4 v148, s[12:13]
	s_barrier
	s_waitcnt lgkmcnt(0)
	v_mfma_f32_16x16x32_bf16 v[108:111], v[216:219], v[174:177], v[108:111]
	v_mfma_f32_16x16x32_bf16 v[100:103], v[224:227], v[174:177], v[100:103]
	v_mfma_f32_16x16x32_bf16 v[92:95], v[216:219], v[192:195], v[92:95]
	v_mfma_f32_16x16x32_bf16 v[84:87], v[224:227], v[192:195], v[84:87]
	v_mfma_f32_16x16x32_bf16 v[76:79], v[216:219], v[200:203], v[76:79]
	v_mfma_f32_16x16x32_bf16 v[72:75], v[224:227], v[200:203], v[72:75]
	v_mfma_f32_16x16x32_bf16 v[68:71], v[216:219], v[208:211], v[68:71]
	v_mfma_f32_16x16x32_bf16 v[64:67], v[224:227], v[208:211], v[64:67]
	v_mfma_f32_16x16x32_bf16 v[108:111], v[220:223], v[178:181], v[108:111]
	v_mfma_f32_16x16x32_bf16 v[100:103], v[228:231], v[178:181], v[100:103]
	v_mfma_f32_16x16x32_bf16 v[92:95], v[220:223], v[196:199], v[92:95]
	v_mfma_f32_16x16x32_bf16 v[84:87], v[228:231], v[196:199], v[84:87]
	v_mfma_f32_16x16x32_bf16 v[76:79], v[220:223], v[204:207], v[76:79]
	v_mfma_f32_16x16x32_bf16 v[72:75], v[228:231], v[204:207], v[72:75]
	v_mfma_f32_16x16x32_bf16 v[68:71], v[220:223], v[212:215], v[68:71]
	v_mfma_f32_16x16x32_bf16 v[64:67], v[228:231], v[212:215], v[64:67]
	s_mov_b32 m0, s27
	v_lshl_add_u64 v[234:235], s[20:21], 0, v[128:129]
	s_barrier
	ds_read_b128 v[174:177], v156 offset:16384
	ds_read_b128 v[178:181], v156 offset:17408
	ds_read_b128 v[192:195], v156 offset:18432
	ds_read_b128 v[196:199], v156 offset:19456
	ds_read_b128 v[200:203], v156 offset:20480
	ds_read_b128 v[204:207], v156 offset:21504
	ds_read_b128 v[208:211], v156 offset:22528
	ds_read_b128 v[212:215], v156 offset:23552
	global_load_lds_dwordx4 v128, s[20:21]
	v_lshl_add_u64 v[236:237], s[20:21], 0, v[148:149]
	s_mov_b32 m0, s30
	s_nop 0
	global_load_lds_dwordx4 v148, s[20:21]
	s_barrier
	s_waitcnt lgkmcnt(0)
	v_mfma_f32_16x16x32_bf16 v[60:63], v[158:161], v[174:177], v[60:63]
	v_mfma_f32_16x16x32_bf16 v[56:59], v[166:169], v[174:177], v[56:59]
	v_mfma_f32_16x16x32_bf16 v[52:55], v[158:161], v[192:195], v[52:55]
	v_mfma_f32_16x16x32_bf16 v[48:51], v[166:169], v[192:195], v[48:51]
	v_mfma_f32_16x16x32_bf16 v[36:39], v[158:161], v[200:203], v[36:39]
	v_mfma_f32_16x16x32_bf16 v[32:35], v[166:169], v[200:203], v[32:35]
	v_mfma_f32_16x16x32_bf16 v[20:23], v[158:161], v[208:211], v[20:23]
	v_mfma_f32_16x16x32_bf16 v[16:19], v[166:169], v[208:211], v[16:19]
	v_mfma_f32_16x16x32_bf16 v[60:63], v[162:165], v[178:181], v[60:63]
	v_mfma_f32_16x16x32_bf16 v[56:59], v[170:173], v[178:181], v[56:59]
	v_mfma_f32_16x16x32_bf16 v[52:55], v[162:165], v[196:199], v[52:55]
	v_mfma_f32_16x16x32_bf16 v[48:51], v[170:173], v[196:199], v[48:51]
	v_mfma_f32_16x16x32_bf16 v[36:39], v[162:165], v[204:207], v[36:39]
	v_mfma_f32_16x16x32_bf16 v[32:35], v[170:173], v[204:207], v[32:35]
	v_mfma_f32_16x16x32_bf16 v[20:23], v[162:165], v[212:215], v[20:23]
	v_mfma_f32_16x16x32_bf16 v[16:19], v[170:173], v[212:215], v[16:19]
	s_barrier
; #define PG8_STAGE(bufoff, gbase, voff) do { _Pragma("unroll") for (int _i = 0; _i < 2; ++_i) \
;         __builtin_amdgcn_global_load_lds((const unsigned*)((const char*)(gbase) + (voff)[_i]), (PG8_LAS unsigned*)(lds + (bufoff) + ldsw + _i * 8192), 16, 0, 0); } while (0)
; #define PG8_LDA(dst, b, h) do { _Pragma("unroll") for (int m = 0; m < 4; ++m) _Pragma("unroll") for (int k = 0; k < 2; ++k) dst[m][k] = *(const PG8_LAS bf16x8*)(lds + PG8_SA(b, h) + aoff + m * 2048 + k * 1024); } while (0)
; #define PG8_LDB(dst, b, h) do { _Pragma("unroll") for (int n = 0; n < 2; ++n) _Pragma("unroll") for (int k = 0; k < 2; ++k) dst[n][k] = *(const PG8_LAS bf16x8*)(lds + PG8_SB(b, h) + boff + n * 2048 + k * 1024); } while (0)
; #define PG8_MMA(ai, bj, At, Bt) do { __builtin_amdgcn_s_setprio(1); _Pragma("unroll") for (int m = 0; m < 4; ++m) _Pragma("unroll") for (int n = 0; n < 2; ++n) _Pragma("unroll") for (int k = 0; k < 2; ++k) \
;         acc[ai][bj][m][n] = __builtin_amdgcn_mfma_f32_16x16x32_bf16(Bt[n][k], At[m][k], acc[ai][bj][m][n], 0, 0, 0); __builtin_amdgcn_s_setprio(0); } while (0)
; #define PG8_WAIT_V(n) asm volatile("s_waitcnt vmcnt(" #n ")" ::: "memory")
; #define PG8_WAIT_L(n) asm volatile("s_waitcnt lgkmcnt(" #n ")" ::: "memory")
; #define PG8_BAR __builtin_amdgcn_s_barrier()
; #define PG8_SCHED __builtin_amdgcn_sched_barrier(0)
; template <class Epi, class Sched, bool STAMP = false>
; __device__ __forceinline__ void gemm_phase(PG8_LAS unsigned char* lds, const Gemm g, const Sched& S, const Epi& E, unsigned long long* stamps) {
;     ...
;             PG8_STAGE(PG8_SB(0, 1), b2 + hstep, voffB);
;             PG8_WAIT_V(6); PG8_BAR; PG8_MMA(1, 1, At, B1); PG8_BAR;
;             PG8_LDB(B0, 1, 0); PG8_SCHED; PG8_LDA(At, 1, 0); PG8_STAGE(PG8_SA(0, 1), a2 + hstep, voffA);
;             PG8_WAIT_L(8); PG8_BAR; PG8_WAIT_L(0); PG8_MMA(0, 0, At, B0); PG8_BAR; PG8_SCHED;
;             PG8_LDB(B1, 1, 1); PG8_STAGE(PG8_SB(1, 0), b3, voffB);
;             PG8_BAR; PG8_WAIT_L(0); PG8_MMA(0, 1, At, B1); PG8_BAR;
;             PG8_LDA(At, 1, 1); PG8_STAGE(PG8_SA(1, 0), a3, voffA);
	s_add_u32 s4, s12, 0x100000
	s_addc_u32 s5, s13, 0
	s_add_i32 s14, s15, s26
	s_mov_b32 m0, s14
	s_nop 0
	global_load_lds_dwordx4 v128, s[4:5]
	s_add_i32 m0, s14, 0x2000
	s_nop 0
	global_load_lds_dwordx4 v148, s[4:5]
	s_waitcnt vmcnt(6)
	s_barrier
	v_mfma_f32_16x16x32_bf16 v[44:47], v[216:219], v[174:177], v[44:47]
	v_mfma_f32_16x16x32_bf16 v[40:43], v[224:227], v[174:177], v[40:43]
	v_mfma_f32_16x16x32_bf16 v[28:31], v[216:219], v[192:195], v[28:31]
	v_mfma_f32_16x16x32_bf16 v[24:27], v[224:227], v[192:195], v[24:27]
	v_mfma_f32_16x16x32_bf16 v[12:15], v[216:219], v[200:203], v[12:15]
	v_mfma_f32_16x16x32_bf16 v[8:11], v[224:227], v[200:203], v[8:11]
	v_mfma_f32_16x16x32_bf16 v[4:7], v[216:219], v[208:211], v[4:7]
	v_mfma_f32_16x16x32_bf16 v[0:3], v[224:227], v[208:211], v[0:3]
	v_mfma_f32_16x16x32_bf16 v[44:47], v[220:223], v[178:181], v[44:47]
	v_mfma_f32_16x16x32_bf16 v[40:43], v[228:231], v[178:181], v[40:43]
	v_mfma_f32_16x16x32_bf16 v[28:31], v[220:223], v[196:199], v[28:31]
	v_mfma_f32_16x16x32_bf16 v[24:27], v[228:231], v[196:199], v[24:27]
	v_mfma_f32_16x16x32_bf16 v[12:15], v[220:223], v[204:207], v[12:15]
	v_mfma_f32_16x16x32_bf16 v[8:11], v[228:231], v[204:207], v[8:11]
	v_mfma_f32_16x16x32_bf16 v[4:7], v[220:223], v[212:215], v[4:7]
	v_mfma_f32_16x16x32_bf16 v[0:3], v[228:231], v[212:215], v[0:3]
	s_add_i32 s14, 0, 0x18000
	s_barrier
	ds_read_b128 v[158:161], v250
	ds_read_b128 v[162:165], v250 offset:1024
	ds_read_b128 v[166:169], v250 offset:2048
	ds_read_b128 v[170:173], v250 offset:3072
	s_add_u32 s4, s20, 0x100000
	s_addc_u32 s5, s21, 0
	s_mov_b32 m0, s31
	ds_read_b128 v[174:177], v156 offset:32768
	ds_read_b128 v[178:181], v156 offset:33792
	ds_read_b128 v[192:195], v156 offset:34816
	ds_read_b128 v[196:199], v156 offset:35840
	ds_read_b128 v[200:203], v156 offset:36864
	ds_read_b128 v[204:207], v156 offset:37888
	ds_read_b128 v[208:211], v156 offset:38912
	ds_read_b128 v[212:215], v156 offset:39936
	global_load_lds_dwordx4 v128, s[4:5]
	s_mov_b32 m0, s34
	s_nop 0
	global_load_lds_dwordx4 v148, s[4:5]
	s_waitcnt lgkmcnt(8)
	s_barrier
	s_waitcnt lgkmcnt(0)
	v_mfma_f32_16x16x32_bf16 v[124:127], v[158:161], v[174:177], v[124:127]
	v_mfma_f32_16x16x32_bf16 v[120:123], v[166:169], v[174:177], v[120:123]
	v_mfma_f32_16x16x32_bf16 v[116:119], v[158:161], v[192:195], v[116:119]
	v_mfma_f32_16x16x32_bf16 v[112:115], v[166:169], v[192:195], v[112:115]
	v_mfma_f32_16x16x32_bf16 v[104:107], v[158:161], v[200:203], v[104:107]
	v_mfma_f32_16x16x32_bf16 v[96:99], v[166:169], v[200:203], v[96:99]
	v_mfma_f32_16x16x32_bf16 v[88:91], v[158:161], v[208:211], v[88:91]
	v_mfma_f32_16x16x32_bf16 v[80:83], v[166:169], v[208:211], v[80:83]
	v_mfma_f32_16x16x32_bf16 v[124:127], v[162:165], v[178:181], v[124:127]
	v_mfma_f32_16x16x32_bf16 v[120:123], v[170:173], v[178:181], v[120:123]
	v_mfma_f32_16x16x32_bf16 v[116:119], v[162:165], v[196:199], v[116:119]
	v_mfma_f32_16x16x32_bf16 v[112:115], v[170:173], v[196:199], v[112:115]
	v_mfma_f32_16x16x32_bf16 v[104:107], v[162:165], v[204:207], v[104:107]
	v_mfma_f32_16x16x32_bf16 v[96:99], v[170:173], v[204:207], v[96:99]
	v_mfma_f32_16x16x32_bf16 v[88:91], v[162:165], v[212:215], v[88:91]
	v_mfma_f32_16x16x32_bf16 v[80:83], v[170:173], v[212:215], v[80:83]
	s_barrier
	s_add_i32 s15, 0, 0x1c000
	s_add_i32 s4, s14, s26
	v_lshl_add_u64 v[182:183], v[182:183], 0, s[18:19]
	s_mov_b32 m0, s4
	ds_read_b128 v[216:219], v251
	ds_read_b128 v[220:223], v251 offset:1024
	ds_read_b128 v[224:227], v251 offset:2048
	ds_read_b128 v[228:231], v251 offset:3072
	global_load_lds_dwordx4 v244, s[12:13]
	v_lshl_add_u64 v[182:183], v[232:233], 0, s[18:19]
	s_add_i32 m0, s4, 0x2000
	s_nop 0
	global_load_lds_dwordx4 v245, s[12:13]
	s_barrier
	s_waitcnt lgkmcnt(0)
	v_mfma_f32_16x16x32_bf16 v[108:111], v[216:219], v[174:177], v[108:111]
	v_mfma_f32_16x16x32_bf16 v[100:103], v[224:227], v[174:177], v[100:103]
	v_mfma_f32_16x16x32_bf16 v[92:95], v[216:219], v[192:195], v[92:95]
	v_mfma_f32_16x16x32_bf16 v[84:87], v[224:227], v[192:195], v[84:87]
	v_mfma_f32_16x16x32_bf16 v[76:79], v[216:219], v[200:203], v[76:79]
	v_mfma_f32_16x16x32_bf16 v[72:75], v[224:227], v[200:203], v[72:75]
	v_mfma_f32_16x16x32_bf16 v[68:71], v[216:219], v[208:211], v[68:71]
	v_mfma_f32_16x16x32_bf16 v[64:67], v[224:227], v[208:211], v[64:67]
	v_mfma_f32_16x16x32_bf16 v[108:111], v[220:223], v[178:181], v[108:111]
	v_mfma_f32_16x16x32_bf16 v[100:103], v[228:231], v[178:181], v[100:103]
	v_mfma_f32_16x16x32_bf16 v[92:95], v[220:223], v[196:199], v[92:95]
	v_mfma_f32_16x16x32_bf16 v[84:87], v[228:231], v[196:199], v[84:87]
	v_mfma_f32_16x16x32_bf16 v[76:79], v[220:223], v[204:207], v[76:79]
	v_mfma_f32_16x16x32_bf16 v[72:75], v[228:231], v[204:207], v[72:75]
	v_mfma_f32_16x16x32_bf16 v[68:71], v[220:223], v[212:215], v[68:71]
	v_mfma_f32_16x16x32_bf16 v[64:67], v[228:231], v[212:215], v[64:67]
	s_mov_b32 m0, s37
	v_lshl_add_u64 v[182:183], v[234:235], 0, s[18:19]
	s_barrier
	ds_read_b128 v[174:177], v156 offset:49152
	ds_read_b128 v[178:181], v156 offset:50176
	ds_read_b128 v[192:195], v156 offset:51200
	ds_read_b128 v[196:199], v156 offset:52224
	ds_read_b128 v[200:203], v156 offset:53248
	ds_read_b128 v[204:207], v156 offset:54272
	ds_read_b128 v[208:211], v156 offset:55296
	ds_read_b128 v[212:215], v156 offset:56320
	global_load_lds_dwordx4 v244, s[20:21]
	v_lshl_add_u64 v[182:183], v[236:237], 0, s[18:19]
	s_mov_b32 m0, s38
	s_nop 0
	global_load_lds_dwordx4 v245, s[20:21]
	s_barrier
; #define PG8_STAGE(bufoff, gbase, voff) do { _Pragma("unroll") for (int _i = 0; _i < 2; ++_i) \
;         __builtin_amdgcn_global_load_lds((const unsigned*)((const char*)(gbase) + (voff)[_i]), (PG8_LAS unsigned*)(lds + (bufoff) + ldsw + _i * 8192), 16, 0, 0); } while (0)
; #define PG8_MMA(ai, bj, At, Bt) do { __builtin_amdgcn_s_setprio(1); _Pragma("unroll") for (int m = 0; m < 4; ++m) _Pragma("unroll") for (int n = 0; n < 2; ++n) _Pragma("unroll") for (int k = 0; k < 2; ++k) \
;         acc[ai][bj][m][n] = __builtin_amdgcn_mfma_f32_16x16x32_bf16(Bt[n][k], At[m][k], acc[ai][bj][m][n], 0, 0, 0); __builtin_amdgcn_s_setprio(0); } while (0)
; #define PG8_WAIT_V(n) asm volatile("s_waitcnt vmcnt(" #n ")" ::: "memory")
; #define PG8_WAIT_L(n) asm volatile("s_waitcnt lgkmcnt(" #n ")" ::: "memory")
; #define PG8_BAR __builtin_amdgcn_s_barrier()
; #define PG8_SCHED __builtin_amdgcn_sched_barrier(0)
; template <class Epi, class Sched, bool STAMP = false>
; __device__ __forceinline__ void gemm_phase(PG8_LAS unsigned char* lds, const Gemm g, const Sched& S, const Epi& E, unsigned long long* stamps) {
;     ...
;             PG8_BAR; PG8_WAIT_L(0); PG8_MMA(1, 0, At, B0); PG8_BAR; PG8_SCHED;
;             PG8_STAGE(PG8_SB(1, 1), b3 + hstep, voffB);
;             PG8_WAIT_V(6); PG8_BAR; PG8_MMA(1, 1, At, B1); PG8_BAR;
;     __device__ __forceinline__ void operator()(const f32x4 (&acc)[2][2][4][2], const pg8::Unit& u, int wr, int wc, int fr, int fq) const {
;         const int row0 = (u.pm - 64) * 256 + wr * 64 + fr, col0 = u.pn * 256 + wc * 32 + 4 * fq;
; #pragma unroll
;         for (int ai = 0; ai < 2; ++ai)
; #pragma unroll
;             for (int m = 0; m < 4; ++m) { float* xp = PART + (size_t)(row0 + ai * 128 + m * 16) * ldp + col0;
; #pragma unroll
;                 for (int bj = 0; bj < 2; ++bj)
; #pragma unroll
;                     for (int n = 0; n < 2; ++n) *(f32x4*)(xp + bj * 128 + n * 16) = acc[ai][bj][m][n]; }
	s_waitcnt lgkmcnt(0)
	v_mfma_f32_16x16x32_bf16 v[60:63], v[158:161], v[174:177], v[60:63]
	v_mfma_f32_16x16x32_bf16 v[56:59], v[166:169], v[174:177], v[56:59]
	v_mfma_f32_16x16x32_bf16 v[52:55], v[158:161], v[192:195], v[52:55]
	v_mfma_f32_16x16x32_bf16 v[48:51], v[166:169], v[192:195], v[48:51]
	v_mfma_f32_16x16x32_bf16 v[36:39], v[158:161], v[200:203], v[36:39]
	v_mfma_f32_16x16x32_bf16 v[32:35], v[166:169], v[200:203], v[32:35]
	v_mfma_f32_16x16x32_bf16 v[20:23], v[158:161], v[208:211], v[20:23]
	v_mfma_f32_16x16x32_bf16 v[16:19], v[166:169], v[208:211], v[16:19]
	v_mfma_f32_16x16x32_bf16 v[60:63], v[162:165], v[178:181], v[60:63]
	v_mfma_f32_16x16x32_bf16 v[56:59], v[170:173], v[178:181], v[56:59]
	v_mfma_f32_16x16x32_bf16 v[52:55], v[162:165], v[196:199], v[52:55]
	v_mfma_f32_16x16x32_bf16 v[48:51], v[170:173], v[196:199], v[48:51]
	v_mfma_f32_16x16x32_bf16 v[36:39], v[162:165], v[204:207], v[36:39]
	v_mfma_f32_16x16x32_bf16 v[32:35], v[170:173], v[204:207], v[32:35]
	v_mfma_f32_16x16x32_bf16 v[20:23], v[162:165], v[212:215], v[20:23]
	v_mfma_f32_16x16x32_bf16 v[16:19], v[170:173], v[212:215], v[16:19]
	s_barrier
	s_add_u32 s4, s12, 0x100080
	s_addc_u32 s5, s13, 0
	s_add_i32 s12, s15, s26
	s_mov_b32 m0, s12
	s_nop 0
	global_load_lds_dwordx4 v128, s[4:5]
	s_add_i32 m0, s12, 0x2000
	s_nop 0
	global_load_lds_dwordx4 v148, s[4:5]
	s_waitcnt vmcnt(6)
	s_barrier
	v_mfma_f32_16x16x32_bf16 v[44:47], v[216:219], v[174:177], v[44:47]
	v_mfma_f32_16x16x32_bf16 v[40:43], v[224:227], v[174:177], v[40:43]
	v_mfma_f32_16x16x32_bf16 v[28:31], v[216:219], v[192:195], v[28:31]
	v_mfma_f32_16x16x32_bf16 v[24:27], v[224:227], v[192:195], v[24:27]
	v_mfma_f32_16x16x32_bf16 v[12:15], v[216:219], v[200:203], v[12:15]
	v_mfma_f32_16x16x32_bf16 v[8:11], v[224:227], v[200:203], v[8:11]
	v_mfma_f32_16x16x32_bf16 v[4:7], v[216:219], v[208:211], v[4:7]
	v_mfma_f32_16x16x32_bf16 v[0:3], v[224:227], v[208:211], v[0:3]
	v_mfma_f32_16x16x32_bf16 v[44:47], v[220:223], v[178:181], v[44:47]
	v_mfma_f32_16x16x32_bf16 v[40:43], v[228:231], v[178:181], v[40:43]
	v_mfma_f32_16x16x32_bf16 v[28:31], v[220:223], v[196:199], v[28:31]
	v_mfma_f32_16x16x32_bf16 v[24:27], v[228:231], v[196:199], v[24:27]
	v_mfma_f32_16x16x32_bf16 v[12:15], v[220:223], v[204:207], v[12:15]
	v_mfma_f32_16x16x32_bf16 v[8:11], v[228:231], v[204:207], v[8:11]
	v_mfma_f32_16x16x32_bf16 v[4:7], v[220:223], v[212:215], v[4:7]
	v_mfma_f32_16x16x32_bf16 v[0:3], v[228:231], v[212:215], v[0:3]
	s_add_i32 s39, s39, 2
	s_cmp_gt_u32 s39, 5
	s_mov_b64 s[4:5], s[6:7]
	s_barrier
	s_cbranch_scc0 .LBB0_1207
	s_lshl_b32 s0, s25, 22
	s_add_u32 s0, s10, s0
	s_addc_u32 s1, s42, 0
	s_add_u32 s0, s0, 0xdd00000
	s_addc_u32 s1, s1, 0
	s_lshl_b32 s2, s24, 8
	s_add_i32 s2, s2, s35
	v_add_u32_e32 v150, s2, v154
	v_add_u32_e32 v148, 0xffffc000, v150
	s_lshl_b32 s2, s23, 8
	v_lshl_or_b32 v128, v139, 2, s2
	v_ashrrev_i32_e32 v149, 31, v148
	v_or_b32_e32 v128, s36, v128
	v_lshlrev_b64 v[148:149], 12, v[148:149]
	v_lshl_add_u64 v[148:149], s[0:1], 0, v[148:149]
	v_lshlrev_b32_e32 v128, 2, v128
	v_lshl_add_u64 v[148:149], v[148:149], 0, v[128:129]
	global_store_dwordx4 v[148:149], v[124:127], off
	global_store_dwordx4 v[148:149], v[120:123], off offset:64
	global_store_dwordx4 v[148:149], v[108:111], off offset:512
	global_store_dwordx4 v[148:149], v[100:103], off offset:576
	s_cmpk_lt_u32 s22, 0x100
	v_readlane_b32 s39, v242, 28
	v_add_u32_e32 v100, 0xffffc010, v150
	v_ashrrev_i32_e32 v101, 31, v100
	v_lshlrev_b64 v[100:101], 12, v[100:101]
	v_lshl_add_u64 v[100:101], s[0:1], 0, v[100:101]
	v_lshl_add_u64 v[100:101], v[100:101], 0, v[128:129]
	global_store_dwordx4 v[100:101], v[116:119], off
	global_store_dwordx4 v[100:101], v[112:115], off offset:64
	global_store_dwordx4 v[100:101], v[92:95], off offset:512
	global_store_dwordx4 v[100:101], v[84:87], off offset:576
	s_mov_b32 s38, 0x1ffff
	s_nop 0
	v_add_u32_e32 v84, 0xffffc020, v150
	v_ashrrev_i32_e32 v85, 31, v84
	v_lshlrev_b64 v[84:85], 12, v[84:85]
	v_lshl_add_u64 v[84:85], s[0:1], 0, v[84:85]
	v_lshl_add_u64 v[84:85], v[84:85], 0, v[128:129]
	global_store_dwordx4 v[84:85], v[104:107], off
	global_store_dwordx4 v[84:85], v[96:99], off offset:64
	global_store_dwordx4 v[84:85], v[76:79], off offset:512
	global_store_dwordx4 v[84:85], v[72:75], off offset:576
	s_nop 1
	v_add_u32_e32 v72, 0xffffc030, v150
	v_ashrrev_i32_e32 v73, 31, v72
	v_lshlrev_b64 v[72:73], 12, v[72:73]
	v_lshl_add_u64 v[72:73], s[0:1], 0, v[72:73]
	v_lshl_add_u64 v[72:73], v[72:73], 0, v[128:129]
	s_mov_b64 s[0:1], 0x80000
	global_store_dwordx4 v[72:73], v[88:91], off
	global_store_dwordx4 v[72:73], v[80:83], off offset:64
	global_store_dwordx4 v[72:73], v[68:71], off offset:512
	global_store_dwordx4 v[72:73], v[64:67], off offset:576
	s_nop 1
	v_lshl_add_u64 v[64:65], v[148:149], 0, s[0:1]
	s_mov_b32 s0, 0x80000
	v_add_co_u32_e32 v66, vcc, s0, v148
	s_mov_b64 s[0:1], 0x90000
	s_nop 0
	v_addc_co_u32_e32 v67, vcc, 0, v149, vcc
	global_store_dwordx4 v[66:67], v[60:63], off
	global_store_dwordx4 v[64:65], v[56:59], off offset:64
	global_store_dwordx4 v[64:65], v[44:47], off offset:512
	global_store_dwordx4 v[64:65], v[40:43], off offset:576
	s_nop 1
	v_lshl_add_u64 v[40:41], v[148:149], 0, s[0:1]
	s_mov_b32 s0, 0x90000
	v_add_co_u32_e32 v42, vcc, s0, v148
	s_mov_b64 s[0:1], 0xa0000
	s_nop 0
	v_addc_co_u32_e32 v43, vcc, 0, v149, vcc
	global_store_dwordx4 v[42:43], v[52:55], off
	global_store_dwordx4 v[40:41], v[48:51], off offset:64
	global_store_dwordx4 v[40:41], v[28:31], off offset:512
	global_store_dwordx4 v[40:41], v[24:27], off offset:576
	s_nop 1
	v_lshl_add_u64 v[24:25], v[148:149], 0, s[0:1]
	s_mov_b32 s0, 0xa0000
	v_add_co_u32_e32 v26, vcc, s0, v148
	s_mov_b64 s[0:1], 0xb0000
	s_nop 0
	v_addc_co_u32_e32 v27, vcc, 0, v149, vcc
	global_store_dwordx4 v[26:27], v[36:39], off
	global_store_dwordx4 v[24:25], v[32:35], off offset:64
	global_store_dwordx4 v[24:25], v[12:15], off offset:512
	global_store_dwordx4 v[24:25], v[8:11], off offset:576
	s_nop 1
	v_add_co_u32_e32 v10, vcc, 0xb0000, v148
	v_lshl_add_u64 v[8:9], v[148:149], 0, s[0:1]
	s_nop 0
	v_addc_co_u32_e32 v11, vcc, 0, v149, vcc
	global_store_dwordx4 v[10:11], v[20:23], off
	global_store_dwordx4 v[8:9], v[16:19], off offset:64
	global_store_dwordx4 v[8:9], v[4:7], off offset:512
	global_store_dwordx4 v[8:9], v[0:3], off offset:576
	s_waitcnt vmcnt(0)
	s_cbranch_scc0 .LBB0_1210
	s_barrier

; #define PG8_STAGE(bufoff, gbase, voff) do { _Pragma("unroll") for (int _i = 0; _i < 2; ++_i) \
;         __builtin_amdgcn_global_load_lds((const unsigned*)((const char*)(gbase) + (voff)[_i]), (PG8_LAS unsigned*)(lds + (bufoff) + ldsw + _i * 8192), 16, 0, 0); } while (0)
; #define PG8_LDA(dst, b, h) do { _Pragma("unroll") for (int m = 0; m < 4; ++m) _Pragma("unroll") for (int k = 0; k < 2; ++k) dst[m][k] = *(const PG8_LAS bf16x8*)(lds + PG8_SA(b, h) + aoff + m * 2048 + k * 1024); } while (0)
; #define PG8_LDB(dst, b, h) do { _Pragma("unroll") for (int n = 0; n < 2; ++n) _Pragma("unroll") for (int k = 0; k < 2; ++k) dst[n][k] = *(const PG8_LAS bf16x8*)(lds + PG8_SB(b, h) + boff + n * 2048 + k * 1024); } while (0)
; #define PG8_WAIT_L(n) asm volatile("s_waitcnt lgkmcnt(" #n ")" ::: "memory")
; #define PG8_BAR __builtin_amdgcn_s_barrier()
; #define PG8_SCHED __builtin_amdgcn_sched_barrier(0)
;     __device__ bool next(int i, pg8::Unit& u) const { if (i != 0 || !valid) return false; u.pm = pm; u.pn = pn; return true; }
; template <class Epi, class Sched, bool STAMP = false>
; __device__ __forceinline__ void gemm_phase(PG8_LAS unsigned char* lds, const Gemm g, const Sched& S, const Epi& E, unsigned long long* stamps) {
;     ...
;         const bool has_next = S.next(ui + 1, nxt);
;         const char* nA = has_next ? (const char*)g.A + (size_t)nxt.pm * tstep : cA; const char* nB = has_next ? (const char*)g.Bt + (size_t)nxt.pn * tstep : cB;
;         for (int t = 0; t < nt; t += 2) {
;             const bool last = (t == nt - 2);
;             const char* a1 = cA + (size_t)(t + 1) * kstep;
;             const char* a2 = last ? nA : cA + (size_t)(t + 2) * kstep; const char* b2 = last ? nB : cB + (size_t)(t + 2) * kstep;
;             const char* a3 = a2 + kstep; const char* b3 = b2 + kstep;
;             if (last && has_next) S.a_ready(nxt);
;             PG8_LDB(B0, 0, 0); PG8_SCHED; PG8_LDA(At, 0, 0); PG8_STAGE(PG8_SA(1, 1), a1 + hstep, voffA);
;             PG8_WAIT_L(8); PG8_BAR; PG8_WAIT_L(0); PG8_MMA(0, 0, At, B0); PG8_BAR; PG8_SCHED;
;     ...
; #pragma unroll
;         for (int a = 0; a < 2; ++a)
; #pragma unroll
;             for (int b = 0; b < 2; ++b)
; #pragma unroll
;                 for (int m = 0; m < 4; ++m)
; #pragma unroll
;                     for (int n = 0; n < 2; ++n) acc[a][b][m][n] = (f32x4){0.f, 0.f, 0.f, 0.f};
;         cur = nxt; cA = nA; cB = nB; ++ui;
.LBB0_1339:
	s_ashr_i32 s7, s6, 31
	v_cmp_lt_i64_e32 vcc, s[12:13], v[146:147]
	s_lshl_b64 s[12:13], s[6:7], 19
	s_add_u32 s12, s37, s12
	s_addc_u32 s13, s40, s13
	s_and_b64 s[14:15], vcc, exec
	s_cselect_b32 s7, s13, s25
	s_cselect_b32 s57, s12, s24
	s_ashr_i32 s5, s4, 31
	s_lshl_b64 s[14:15], s[4:5], 19
	s_add_u32 s20, s36, s14
	s_addc_u32 s21, s10, s15
	s_and_b64 s[14:15], vcc, exec
	s_cselect_b32 s5, s21, s27
	s_cselect_b32 s58, s20, s26
	s_add_u32 s24, s24, 0x40080
	s_addc_u32 s25, s25, 0
	s_add_u32 s59, s26, 0x100
	v_mov_b32_e32 v0, 0
	s_addc_u32 s60, s27, 0
	s_mov_b32 s61, -2
	v_mov_b32_e32 v1, v0
	v_mov_b32_e32 v2, v0
	v_mov_b32_e32 v3, v0
	v_mov_b32_e32 v4, v0
	v_mov_b32_e32 v5, v0
	v_mov_b32_e32 v6, v0
	v_mov_b32_e32 v7, v0
	v_mov_b32_e32 v16, v0
	v_mov_b32_e32 v17, v0
	v_mov_b32_e32 v18, v0
	v_mov_b32_e32 v19, v0
	v_mov_b32_e32 v20, v0
	v_mov_b32_e32 v21, v0
	v_mov_b32_e32 v22, v0
	v_mov_b32_e32 v23, v0
	v_mov_b32_e32 v32, v0
	v_mov_b32_e32 v33, v0
	v_mov_b32_e32 v34, v0
	v_mov_b32_e32 v35, v0
	v_mov_b32_e32 v36, v0
	v_mov_b32_e32 v37, v0
	v_mov_b32_e32 v38, v0
	v_mov_b32_e32 v39, v0
	v_mov_b32_e32 v48, v0
	v_mov_b32_e32 v49, v0
	v_mov_b32_e32 v50, v0
	v_mov_b32_e32 v51, v0
	v_mov_b32_e32 v52, v0
	v_mov_b32_e32 v53, v0
	v_mov_b32_e32 v54, v0
	v_mov_b32_e32 v55, v0
	v_mov_b32_e32 v8, v0
	v_mov_b32_e32 v9, v0
	v_mov_b32_e32 v10, v0
	v_mov_b32_e32 v11, v0
	v_mov_b32_e32 v12, v0
	v_mov_b32_e32 v13, v0
	v_mov_b32_e32 v14, v0
	v_mov_b32_e32 v15, v0
	v_mov_b32_e32 v24, v0
	v_mov_b32_e32 v25, v0
	v_mov_b32_e32 v26, v0
	v_mov_b32_e32 v27, v0
	v_mov_b32_e32 v28, v0
	v_mov_b32_e32 v29, v0
	v_mov_b32_e32 v30, v0
	v_mov_b32_e32 v31, v0
	v_mov_b32_e32 v40, v0
	v_mov_b32_e32 v41, v0
	v_mov_b32_e32 v42, v0
	v_mov_b32_e32 v43, v0
	v_mov_b32_e32 v44, v0
	v_mov_b32_e32 v45, v0
	v_mov_b32_e32 v46, v0
	v_mov_b32_e32 v47, v0
	v_mov_b32_e32 v56, v0
	v_mov_b32_e32 v57, v0
	v_mov_b32_e32 v58, v0
	v_mov_b32_e32 v59, v0
	v_mov_b32_e32 v60, v0
	v_mov_b32_e32 v61, v0
	v_mov_b32_e32 v62, v0
	v_mov_b32_e32 v63, v0
	v_mov_b32_e32 v64, v0
	v_mov_b32_e32 v65, v0
	v_mov_b32_e32 v66, v0
	v_mov_b32_e32 v67, v0
	v_mov_b32_e32 v68, v0
	v_mov_b32_e32 v69, v0
	v_mov_b32_e32 v70, v0
	v_mov_b32_e32 v71, v0
	v_mov_b32_e32 v80, v0
	v_mov_b32_e32 v81, v0
	v_mov_b32_e32 v82, v0
	v_mov_b32_e32 v83, v0
	v_mov_b32_e32 v84, v0
	v_mov_b32_e32 v85, v0
	v_mov_b32_e32 v86, v0
	v_mov_b32_e32 v87, v0
	v_mov_b32_e32 v96, v0
	v_mov_b32_e32 v97, v0
	s_waitcnt vmcnt(0)
	v_mov_b32_e32 v98, v0
	v_mov_b32_e32 v99, v0
	v_mov_b32_e32 v100, v0
	v_mov_b32_e32 v101, v0
	v_mov_b32_e32 v102, v0
	v_mov_b32_e32 v103, v0
	v_mov_b32_e32 v112, v0
	v_mov_b32_e32 v113, v0
	v_mov_b32_e32 v114, v0
	v_mov_b32_e32 v115, v0
	v_mov_b32_e32 v116, v0
	v_mov_b32_e32 v117, v0
	v_mov_b32_e32 v118, v0
	v_mov_b32_e32 v119, v0
	v_mov_b32_e32 v72, v0
	v_mov_b32_e32 v73, v0
	v_mov_b32_e32 v74, v0
	v_mov_b32_e32 v75, v0
	v_mov_b32_e32 v76, v0
	v_mov_b32_e32 v77, v0
	v_mov_b32_e32 v78, v0
	v_mov_b32_e32 v79, v0
	v_mov_b32_e32 v88, v0
	v_mov_b32_e32 v89, v0
	v_mov_b32_e32 v90, v0
	v_mov_b32_e32 v91, v0
	v_mov_b32_e32 v92, v0
	v_mov_b32_e32 v93, v0
	v_mov_b32_e32 v94, v0
	v_mov_b32_e32 v95, v0
	v_mov_b32_e32 v104, v0
	v_mov_b32_e32 v105, v0
	v_mov_b32_e32 v106, v0
	v_mov_b32_e32 v107, v0
	v_mov_b32_e32 v108, v0
	v_mov_b32_e32 v109, v0
	v_mov_b32_e32 v110, v0
	v_mov_b32_e32 v111, v0
	v_mov_b32_e32 v120, v0
	v_mov_b32_e32 v121, v0
	v_mov_b32_e32 v122, v0
	v_mov_b32_e32 v123, v0
	v_mov_b32_e32 v124, v0
	v_mov_b32_e32 v125, v0
	v_mov_b32_e32 v126, v0
	v_mov_b32_e32 v127, v0
	v_add_u32_e32 v244, 0x80, v128
	v_add_u32_e32 v245, 0x80, v148
	v_add_u32_e32 v246, 0x80, v152
	v_add_u32_e32 v247, 0x80, v150
	v_add_u32_e32 v248, 0x10000, v166
	v_add_u32_e32 v249, 0x14000, v166
	v_add_u32_e32 v250, 0x18000, v166
	v_add_u32_e32 v251, 0x1c000, v166
.LBB0_1340:
	s_add_u32 s14, s24, 0xfffc0080
	s_addc_u32 s15, s25, -1
	s_add_i32 s16, 0, 0x10000
	ds_read_b128 v[158:161], v248
	ds_read_b128 v[162:165], v248 offset:1024
	ds_read_b128 v[170:173], v248 offset:2048
	ds_read_b128 v[174:177], v248 offset:3072
	s_cmp_eq_u32 s61, 12
	s_cselect_b32 s31, s7, s15
	s_cselect_b32 s30, s57, s14
	s_cselect_b32 s27, s5, s60
	s_cselect_b32 s26, s58, s59
	s_add_i32 m0, s23, 0xc000
	ds_read_b128 v[178:181], v168
	ds_read_b128 v[192:195], v168 offset:1024
	ds_read_b128 v[196:199], v168 offset:2048
	ds_read_b128 v[200:203], v168 offset:3072
	ds_read_b128 v[204:207], v168 offset:4096
	ds_read_b128 v[208:211], v168 offset:5120
	ds_read_b128 v[212:215], v168 offset:6144
	ds_read_b128 v[216:219], v168 offset:7168
	global_load_lds_dwordx4 v154, s[24:25]
	s_add_i32 m0, s23, 0xe000
	s_nop 0
	global_load_lds_dwordx4 v156, s[24:25]
	s_waitcnt lgkmcnt(8)
	s_barrier
	s_waitcnt lgkmcnt(0)
	v_mfma_f32_16x16x32_bf16 v[124:127], v[158:161], v[178:181], v[124:127]
	v_mfma_f32_16x16x32_bf16 v[120:123], v[170:173], v[178:181], v[120:123]
	v_mfma_f32_16x16x32_bf16 v[108:111], v[158:161], v[196:199], v[108:111]
	v_mfma_f32_16x16x32_bf16 v[104:107], v[170:173], v[196:199], v[104:107]
	v_mfma_f32_16x16x32_bf16 v[92:95], v[158:161], v[204:207], v[92:95]
	v_mfma_f32_16x16x32_bf16 v[88:91], v[170:173], v[204:207], v[88:91]
	v_mfma_f32_16x16x32_bf16 v[76:79], v[158:161], v[212:215], v[76:79]
	v_mfma_f32_16x16x32_bf16 v[72:75], v[170:173], v[212:215], v[72:75]
	v_mfma_f32_16x16x32_bf16 v[124:127], v[162:165], v[192:195], v[124:127]
	v_mfma_f32_16x16x32_bf16 v[120:123], v[174:177], v[192:195], v[120:123]
	v_mfma_f32_16x16x32_bf16 v[108:111], v[162:165], v[200:203], v[108:111]
	v_mfma_f32_16x16x32_bf16 v[104:107], v[174:177], v[200:203], v[104:107]
	v_mfma_f32_16x16x32_bf16 v[92:95], v[162:165], v[208:211], v[92:95]
	v_mfma_f32_16x16x32_bf16 v[88:91], v[174:177], v[208:211], v[88:91]
	v_mfma_f32_16x16x32_bf16 v[76:79], v[162:165], v[216:219], v[76:79]
	v_mfma_f32_16x16x32_bf16 v[72:75], v[174:177], v[216:219], v[72:75]
	s_barrier
; #define PG8_STAGE(bufoff, gbase, voff) do { _Pragma("unroll") for (int _i = 0; _i < 2; ++_i) \
;         __builtin_amdgcn_global_load_lds((const unsigned*)((const char*)(gbase) + (voff)[_i]), (PG8_LAS unsigned*)(lds + (bufoff) + ldsw + _i * 8192), 16, 0, 0); } while (0)
; #define PG8_LDA(dst, b, h) do { _Pragma("unroll") for (int m = 0; m < 4; ++m) _Pragma("unroll") for (int k = 0; k < 2; ++k) dst[m][k] = *(const PG8_LAS bf16x8*)(lds + PG8_SA(b, h) + aoff + m * 2048 + k * 1024); } while (0)
; #define PG8_LDB(dst, b, h) do { _Pragma("unroll") for (int n = 0; n < 2; ++n) _Pragma("unroll") for (int k = 0; k < 2; ++k) dst[n][k] = *(const PG8_LAS bf16x8*)(lds + PG8_SB(b, h) + boff + n * 2048 + k * 1024); } while (0)
; #define PG8_MMA(ai, bj, At, Bt) do { __builtin_amdgcn_s_setprio(1); _Pragma("unroll") for (int m = 0; m < 4; ++m) _Pragma("unroll") for (int n = 0; n < 2; ++n) _Pragma("unroll") for (int k = 0; k < 2; ++k) \
;         acc[ai][bj][m][n] = __builtin_amdgcn_mfma_f32_16x16x32_bf16(Bt[n][k], At[m][k], acc[ai][bj][m][n], 0, 0, 0); __builtin_amdgcn_s_setprio(0); } while (0)
; #define PG8_WAIT_V(n) asm volatile("s_waitcnt vmcnt(" #n ")" ::: "memory")
; #define PG8_WAIT_L(n) asm volatile("s_waitcnt lgkmcnt(" #n ")" ::: "memory")
; #define PG8_BAR __builtin_amdgcn_s_barrier()
; #define PG8_SCHED __builtin_amdgcn_sched_barrier(0)
; template <class Epi, class Sched, bool STAMP = false>
; __device__ __forceinline__ void gemm_phase(PG8_LAS unsigned char* lds, const Gemm g, const Sched& S, const Epi& E, unsigned long long* stamps) {
;     ...
;             PG8_LDB(B1, 0, 1); PG8_STAGE(PG8_SB(0, 0), b2, voffB);
;             PG8_BAR; PG8_WAIT_L(0); PG8_MMA(0, 1, At, B1); PG8_BAR;
;             PG8_LDA(At, 0, 1); PG8_STAGE(PG8_SA(0, 0), a2, voffA);
;             PG8_BAR; PG8_WAIT_L(0); PG8_MMA(1, 0, At, B0); PG8_BAR; PG8_SCHED;
;             PG8_STAGE(PG8_SB(0, 1), b2 + hstep, voffB);
;             PG8_WAIT_V(6); PG8_BAR; PG8_MMA(1, 1, At, B1); PG8_BAR;
;             PG8_LDB(B0, 1, 0); PG8_SCHED; PG8_LDA(At, 1, 0); PG8_STAGE(PG8_SA(0, 1), a2 + hstep, voffA);
;             PG8_WAIT_L(8); PG8_BAR; PG8_WAIT_L(0); PG8_MMA(0, 0, At, B0); PG8_BAR; PG8_SCHED;
	s_add_i32 s17, 0, 0x14000
	s_add_i32 s14, s16, s43
	s_mov_b32 m0, s14
	ds_read_b128 v[220:223], v249
	ds_read_b128 v[224:227], v249 offset:1024
	ds_read_b128 v[228:231], v249 offset:2048
	ds_read_b128 v[232:235], v249 offset:3072
	global_load_lds_dwordx4 v128, s[26:27]
	s_add_i32 m0, s14, 0x2000
	s_nop 0
	global_load_lds_dwordx4 v148, s[26:27]
	s_barrier
	s_waitcnt lgkmcnt(0)
	v_mfma_f32_16x16x32_bf16 v[116:119], v[220:223], v[178:181], v[116:119]
	v_mfma_f32_16x16x32_bf16 v[112:115], v[228:231], v[178:181], v[112:115]
	v_mfma_f32_16x16x32_bf16 v[100:103], v[220:223], v[196:199], v[100:103]
	v_mfma_f32_16x16x32_bf16 v[96:99], v[228:231], v[196:199], v[96:99]
	v_mfma_f32_16x16x32_bf16 v[84:87], v[220:223], v[204:207], v[84:87]
	v_mfma_f32_16x16x32_bf16 v[80:83], v[228:231], v[204:207], v[80:83]
	v_mfma_f32_16x16x32_bf16 v[68:71], v[220:223], v[212:215], v[68:71]
	v_mfma_f32_16x16x32_bf16 v[64:67], v[228:231], v[212:215], v[64:67]
	v_mfma_f32_16x16x32_bf16 v[116:119], v[224:227], v[192:195], v[116:119]
	v_mfma_f32_16x16x32_bf16 v[112:115], v[232:235], v[192:195], v[112:115]
	v_mfma_f32_16x16x32_bf16 v[100:103], v[224:227], v[200:203], v[100:103]
	v_mfma_f32_16x16x32_bf16 v[96:99], v[232:235], v[200:203], v[96:99]
	v_mfma_f32_16x16x32_bf16 v[84:87], v[224:227], v[208:211], v[84:87]
	v_mfma_f32_16x16x32_bf16 v[80:83], v[232:235], v[208:211], v[80:83]
	v_mfma_f32_16x16x32_bf16 v[68:71], v[224:227], v[216:219], v[68:71]
	v_mfma_f32_16x16x32_bf16 v[64:67], v[232:235], v[216:219], v[64:67]
	s_mov_b32 m0, s23
	s_barrier
	ds_read_b128 v[178:181], v168 offset:16384
	ds_read_b128 v[192:195], v168 offset:17408
	ds_read_b128 v[196:199], v168 offset:18432
	ds_read_b128 v[200:203], v168 offset:19456
	ds_read_b128 v[204:207], v168 offset:20480
	ds_read_b128 v[208:211], v168 offset:21504
	ds_read_b128 v[212:215], v168 offset:22528
	ds_read_b128 v[216:219], v168 offset:23552
	global_load_lds_dwordx4 v152, s[30:31]
	s_mov_b32 m0, s45
	s_nop 0
	global_load_lds_dwordx4 v150, s[30:31]
	s_barrier
	s_waitcnt lgkmcnt(0)
	v_mfma_f32_16x16x32_bf16 v[60:63], v[158:161], v[178:181], v[60:63]
	v_mfma_f32_16x16x32_bf16 v[56:59], v[170:173], v[178:181], v[56:59]
	v_mfma_f32_16x16x32_bf16 v[44:47], v[158:161], v[196:199], v[44:47]
	v_mfma_f32_16x16x32_bf16 v[40:43], v[170:173], v[196:199], v[40:43]
	v_mfma_f32_16x16x32_bf16 v[28:31], v[158:161], v[204:207], v[28:31]
	v_mfma_f32_16x16x32_bf16 v[24:27], v[170:173], v[204:207], v[24:27]
	v_mfma_f32_16x16x32_bf16 v[12:15], v[158:161], v[212:215], v[12:15]
	v_mfma_f32_16x16x32_bf16 v[8:11], v[170:173], v[212:215], v[8:11]
	v_mfma_f32_16x16x32_bf16 v[60:63], v[162:165], v[192:195], v[60:63]
	v_mfma_f32_16x16x32_bf16 v[56:59], v[174:177], v[192:195], v[56:59]
	v_mfma_f32_16x16x32_bf16 v[44:47], v[162:165], v[200:203], v[44:47]
	v_mfma_f32_16x16x32_bf16 v[40:43], v[174:177], v[200:203], v[40:43]
	v_mfma_f32_16x16x32_bf16 v[28:31], v[162:165], v[208:211], v[28:31]
	v_mfma_f32_16x16x32_bf16 v[24:27], v[174:177], v[208:211], v[24:27]
	v_mfma_f32_16x16x32_bf16 v[12:15], v[162:165], v[216:219], v[12:15]
	v_mfma_f32_16x16x32_bf16 v[8:11], v[174:177], v[216:219], v[8:11]
	s_barrier
	s_add_u32 s14, s26, 0x40000
	s_addc_u32 s15, s27, 0
	s_add_i32 s16, s17, s43
	s_mov_b32 m0, s16
	s_nop 0
	global_load_lds_dwordx4 v128, s[14:15]
	s_add_i32 m0, s16, 0x2000
	s_nop 0
	global_load_lds_dwordx4 v148, s[14:15]
	s_waitcnt vmcnt(6)
	s_barrier
	v_mfma_f32_16x16x32_bf16 v[52:55], v[220:223], v[178:181], v[52:55]
	v_mfma_f32_16x16x32_bf16 v[48:51], v[228:231], v[178:181], v[48:51]
	v_mfma_f32_16x16x32_bf16 v[36:39], v[220:223], v[196:199], v[36:39]
	v_mfma_f32_16x16x32_bf16 v[32:35], v[228:231], v[196:199], v[32:35]
	v_mfma_f32_16x16x32_bf16 v[20:23], v[220:223], v[204:207], v[20:23]
	v_mfma_f32_16x16x32_bf16 v[16:19], v[228:231], v[204:207], v[16:19]
	v_mfma_f32_16x16x32_bf16 v[4:7], v[220:223], v[212:215], v[4:7]
	v_mfma_f32_16x16x32_bf16 v[0:3], v[228:231], v[212:215], v[0:3]
	v_mfma_f32_16x16x32_bf16 v[52:55], v[224:227], v[192:195], v[52:55]
	v_mfma_f32_16x16x32_bf16 v[48:51], v[232:235], v[192:195], v[48:51]
	v_mfma_f32_16x16x32_bf16 v[36:39], v[224:227], v[200:203], v[36:39]
	v_mfma_f32_16x16x32_bf16 v[32:35], v[232:235], v[200:203], v[32:35]
	v_mfma_f32_16x16x32_bf16 v[20:23], v[224:227], v[208:211], v[20:23]
	v_mfma_f32_16x16x32_bf16 v[16:19], v[232:235], v[208:211], v[16:19]
	v_mfma_f32_16x16x32_bf16 v[4:7], v[224:227], v[216:219], v[4:7]
	v_mfma_f32_16x16x32_bf16 v[0:3], v[232:235], v[216:219], v[0:3]
	s_add_i32 s16, 0, 0x18000
	s_barrier
	ds_read_b128 v[158:161], v250
	ds_read_b128 v[162:165], v250 offset:1024
	ds_read_b128 v[170:173], v250 offset:2048
	ds_read_b128 v[174:177], v250 offset:3072
	s_add_u32 s14, s30, 0x40000
	s_addc_u32 s15, s31, 0
	s_mov_b32 m0, s46
	ds_read_b128 v[178:181], v168 offset:32768
	ds_read_b128 v[192:195], v168 offset:33792
	ds_read_b128 v[196:199], v168 offset:34816
	ds_read_b128 v[200:203], v168 offset:35840
	ds_read_b128 v[204:207], v168 offset:36864
	ds_read_b128 v[208:211], v168 offset:37888
	ds_read_b128 v[212:215], v168 offset:38912
	ds_read_b128 v[216:219], v168 offset:39936
	global_load_lds_dwordx4 v152, s[14:15]
	s_mov_b32 m0, s47
	s_nop 0
	global_load_lds_dwordx4 v150, s[14:15]
	s_waitcnt lgkmcnt(8)
	s_barrier
; #define PG8_STAGE(bufoff, gbase, voff) do { _Pragma("unroll") for (int _i = 0; _i < 2; ++_i) \
;         __builtin_amdgcn_global_load_lds((const unsigned*)((const char*)(gbase) + (voff)[_i]), (PG8_LAS unsigned*)(lds + (bufoff) + ldsw + _i * 8192), 16, 0, 0); } while (0)
; #define PG8_LDA(dst, b, h) do { _Pragma("unroll") for (int m = 0; m < 4; ++m) _Pragma("unroll") for (int k = 0; k < 2; ++k) dst[m][k] = *(const PG8_LAS bf16x8*)(lds + PG8_SA(b, h) + aoff + m * 2048 + k * 1024); } while (0)
; #define PG8_LDB(dst, b, h) do { _Pragma("unroll") for (int n = 0; n < 2; ++n) _Pragma("unroll") for (int k = 0; k < 2; ++k) dst[n][k] = *(const PG8_LAS bf16x8*)(lds + PG8_SB(b, h) + boff + n * 2048 + k * 1024); } while (0)
; #define PG8_MMA(ai, bj, At, Bt) do { __builtin_amdgcn_s_setprio(1); _Pragma("unroll") for (int m = 0; m < 4; ++m) _Pragma("unroll") for (int n = 0; n < 2; ++n) _Pragma("unroll") for (int k = 0; k < 2; ++k) \
;         acc[ai][bj][m][n] = __builtin_amdgcn_mfma_f32_16x16x32_bf16(Bt[n][k], At[m][k], acc[ai][bj][m][n], 0, 0, 0); __builtin_amdgcn_s_setprio(0); } while (0)
; #define PG8_WAIT_V(n) asm volatile("s_waitcnt vmcnt(" #n ")" ::: "memory")
; #define PG8_WAIT_L(n) asm volatile("s_waitcnt lgkmcnt(" #n ")" ::: "memory")
; #define PG8_BAR __builtin_amdgcn_s_barrier()
; #define PG8_SCHED __builtin_amdgcn_sched_barrier(0)
; template <class Epi, class Sched, bool STAMP = false>
; __device__ __forceinline__ void gemm_phase(PG8_LAS unsigned char* lds, const Gemm g, const Sched& S, const Epi& E, unsigned long long* stamps) {
;     ...
;             PG8_WAIT_L(8); PG8_BAR; PG8_WAIT_L(0); PG8_MMA(0, 0, At, B0); PG8_BAR; PG8_SCHED;
;             PG8_LDB(B1, 1, 1); PG8_STAGE(PG8_SB(1, 0), b3, voffB);
;             PG8_BAR; PG8_WAIT_L(0); PG8_MMA(0, 1, At, B1); PG8_BAR;
;             PG8_LDA(At, 1, 1); PG8_STAGE(PG8_SA(1, 0), a3, voffA);
;             PG8_BAR; PG8_WAIT_L(0); PG8_MMA(1, 0, At, B0); PG8_BAR; PG8_SCHED;
;             PG8_STAGE(PG8_SB(1, 1), b3 + hstep, voffB);
;             PG8_WAIT_V(6); PG8_BAR; PG8_MMA(1, 1, At, B1); PG8_BAR;
	s_waitcnt lgkmcnt(0)
	v_mfma_f32_16x16x32_bf16 v[124:127], v[158:161], v[178:181], v[124:127]
	v_mfma_f32_16x16x32_bf16 v[120:123], v[170:173], v[178:181], v[120:123]
	v_mfma_f32_16x16x32_bf16 v[108:111], v[158:161], v[196:199], v[108:111]
	v_mfma_f32_16x16x32_bf16 v[104:107], v[170:173], v[196:199], v[104:107]
	v_mfma_f32_16x16x32_bf16 v[92:95], v[158:161], v[204:207], v[92:95]
	v_mfma_f32_16x16x32_bf16 v[88:91], v[170:173], v[204:207], v[88:91]
	v_mfma_f32_16x16x32_bf16 v[76:79], v[158:161], v[212:215], v[76:79]
	v_mfma_f32_16x16x32_bf16 v[72:75], v[170:173], v[212:215], v[72:75]
	v_mfma_f32_16x16x32_bf16 v[124:127], v[162:165], v[192:195], v[124:127]
	v_mfma_f32_16x16x32_bf16 v[120:123], v[174:177], v[192:195], v[120:123]
	v_mfma_f32_16x16x32_bf16 v[108:111], v[162:165], v[200:203], v[108:111]
	v_mfma_f32_16x16x32_bf16 v[104:107], v[174:177], v[200:203], v[104:107]
	v_mfma_f32_16x16x32_bf16 v[92:95], v[162:165], v[208:211], v[92:95]
	v_mfma_f32_16x16x32_bf16 v[88:91], v[174:177], v[208:211], v[88:91]
	v_mfma_f32_16x16x32_bf16 v[76:79], v[162:165], v[216:219], v[76:79]
	v_mfma_f32_16x16x32_bf16 v[72:75], v[174:177], v[216:219], v[72:75]
	s_barrier
	s_add_i32 s17, 0, 0x1c000
	s_add_i32 s14, s16, s43
	s_mov_b32 m0, s14
	ds_read_b128 v[220:223], v251
	ds_read_b128 v[224:227], v251 offset:1024
	ds_read_b128 v[228:231], v251 offset:2048
	ds_read_b128 v[232:235], v251 offset:3072
	global_load_lds_dwordx4 v244, s[26:27]
	s_add_i32 m0, s14, 0x2000
	s_nop 0
	global_load_lds_dwordx4 v245, s[26:27]
	s_barrier
	s_waitcnt lgkmcnt(0)
	v_mfma_f32_16x16x32_bf16 v[116:119], v[220:223], v[178:181], v[116:119]
	v_mfma_f32_16x16x32_bf16 v[112:115], v[228:231], v[178:181], v[112:115]
	v_mfma_f32_16x16x32_bf16 v[100:103], v[220:223], v[196:199], v[100:103]
	v_mfma_f32_16x16x32_bf16 v[96:99], v[228:231], v[196:199], v[96:99]
	v_mfma_f32_16x16x32_bf16 v[84:87], v[220:223], v[204:207], v[84:87]
	v_mfma_f32_16x16x32_bf16 v[80:83], v[228:231], v[204:207], v[80:83]
	v_mfma_f32_16x16x32_bf16 v[68:71], v[220:223], v[212:215], v[68:71]
	v_mfma_f32_16x16x32_bf16 v[64:67], v[228:231], v[212:215], v[64:67]
	v_mfma_f32_16x16x32_bf16 v[116:119], v[224:227], v[192:195], v[116:119]
	v_mfma_f32_16x16x32_bf16 v[112:115], v[232:235], v[192:195], v[112:115]
	v_mfma_f32_16x16x32_bf16 v[100:103], v[224:227], v[200:203], v[100:103]
	v_mfma_f32_16x16x32_bf16 v[96:99], v[232:235], v[200:203], v[96:99]
	v_mfma_f32_16x16x32_bf16 v[84:87], v[224:227], v[208:211], v[84:87]
	v_mfma_f32_16x16x32_bf16 v[80:83], v[232:235], v[208:211], v[80:83]
	v_mfma_f32_16x16x32_bf16 v[68:71], v[224:227], v[216:219], v[68:71]
	v_mfma_f32_16x16x32_bf16 v[64:67], v[232:235], v[216:219], v[64:67]
	s_mov_b32 m0, s48
	s_barrier
	ds_read_b128 v[178:181], v168 offset:49152
	ds_read_b128 v[192:195], v168 offset:50176
	ds_read_b128 v[196:199], v168 offset:51200
	ds_read_b128 v[200:203], v168 offset:52224
	ds_read_b128 v[204:207], v168 offset:53248
	ds_read_b128 v[208:211], v168 offset:54272
	ds_read_b128 v[212:215], v168 offset:55296
	ds_read_b128 v[216:219], v168 offset:56320
	global_load_lds_dwordx4 v246, s[30:31]
	s_mov_b32 m0, s49
	s_nop 0
	global_load_lds_dwordx4 v247, s[30:31]
	s_barrier
	s_waitcnt lgkmcnt(0)
	v_mfma_f32_16x16x32_bf16 v[60:63], v[158:161], v[178:181], v[60:63]
	v_mfma_f32_16x16x32_bf16 v[56:59], v[170:173], v[178:181], v[56:59]
	v_mfma_f32_16x16x32_bf16 v[44:47], v[158:161], v[196:199], v[44:47]
	v_mfma_f32_16x16x32_bf16 v[40:43], v[170:173], v[196:199], v[40:43]
	v_mfma_f32_16x16x32_bf16 v[28:31], v[158:161], v[204:207], v[28:31]
	v_mfma_f32_16x16x32_bf16 v[24:27], v[170:173], v[204:207], v[24:27]
	v_mfma_f32_16x16x32_bf16 v[12:15], v[158:161], v[212:215], v[12:15]
	v_mfma_f32_16x16x32_bf16 v[8:11], v[170:173], v[212:215], v[8:11]
	v_mfma_f32_16x16x32_bf16 v[60:63], v[162:165], v[192:195], v[60:63]
	v_mfma_f32_16x16x32_bf16 v[56:59], v[174:177], v[192:195], v[56:59]
	v_mfma_f32_16x16x32_bf16 v[44:47], v[162:165], v[200:203], v[44:47]
	v_mfma_f32_16x16x32_bf16 v[40:43], v[174:177], v[200:203], v[40:43]
	v_mfma_f32_16x16x32_bf16 v[28:31], v[162:165], v[208:211], v[28:31]
	v_mfma_f32_16x16x32_bf16 v[24:27], v[174:177], v[208:211], v[24:27]
	v_mfma_f32_16x16x32_bf16 v[12:15], v[162:165], v[216:219], v[12:15]
	v_mfma_f32_16x16x32_bf16 v[8:11], v[174:177], v[216:219], v[8:11]
	s_barrier
	s_add_u32 s14, s26, 0x40080
	s_addc_u32 s15, s27, 0
	s_add_i32 s16, s17, s43
	s_mov_b32 m0, s16
	s_nop 0
	global_load_lds_dwordx4 v128, s[14:15]
	s_add_i32 m0, s16, 0x2000
	s_nop 0
	global_load_lds_dwordx4 v148, s[14:15]
	s_waitcnt vmcnt(6)
	s_barrier
	v_mfma_f32_16x16x32_bf16 v[52:55], v[220:223], v[178:181], v[52:55]
	v_mfma_f32_16x16x32_bf16 v[48:51], v[228:231], v[178:181], v[48:51]
	v_mfma_f32_16x16x32_bf16 v[36:39], v[220:223], v[196:199], v[36:39]
	v_mfma_f32_16x16x32_bf16 v[32:35], v[228:231], v[196:199], v[32:35]
	v_mfma_f32_16x16x32_bf16 v[20:23], v[220:223], v[204:207], v[20:23]
	v_mfma_f32_16x16x32_bf16 v[16:19], v[228:231], v[204:207], v[16:19]
	v_mfma_f32_16x16x32_bf16 v[4:7], v[220:223], v[212:215], v[4:7]
	v_mfma_f32_16x16x32_bf16 v[0:3], v[228:231], v[212:215], v[0:3]
	v_mfma_f32_16x16x32_bf16 v[52:55], v[224:227], v[192:195], v[52:55]
	v_mfma_f32_16x16x32_bf16 v[48:51], v[232:235], v[192:195], v[48:51]
	v_mfma_f32_16x16x32_bf16 v[36:39], v[224:227], v[200:203], v[36:39]
	v_mfma_f32_16x16x32_bf16 v[32:35], v[232:235], v[200:203], v[32:35]
	v_mfma_f32_16x16x32_bf16 v[20:23], v[224:227], v[208:211], v[20:23]
	v_mfma_f32_16x16x32_bf16 v[16:19], v[232:235], v[208:211], v[16:19]
	v_mfma_f32_16x16x32_bf16 v[4:7], v[224:227], v[216:219], v[4:7]
	v_mfma_f32_16x16x32_bf16 v[0:3], v[232:235], v[216:219], v[0:3]
	s_add_i32 s61, s61, 2
	s_add_u32 s24, s24, 0x100
	s_addc_u32 s25, s25, 0
	s_add_u32 s59, s59, 0x100
	s_addc_u32 s60, s60, 0
	s_cmp_gt_u32 s61, 13
	s_barrier
; __device__ __forceinline__ unsigned cvt_pk_bf16(float lo, float hi) { const f32x2_cv v = {lo, hi}; const bf16x2_cv b = __builtin_convertvector(v, bf16x2_cv); return __builtin_bit_cast(unsigned, b); }
; __device__ __forceinline__ float rstd_of(const float* rowss, int row) { return rsqrtf(rowss[row] * (1.0f / 1024.0f) + 1e-6f); }
;     __device__ __forceinline__ void operator()(const f32x4 (&acc)[2][2][4][2], const pg8::Unit& u, int wr, int wc, int fr, int fq) const {
;         const int row0 = u.pm * 256 + wr * 64 + fr, col0 = u.pn * 256 + wc * 32 + 8 * fq;
; #pragma unroll
;         for (int ai = 0; ai < 2; ++ai)
; #pragma unroll
;             for (int m = 0; m < 4; ++m) {
;                 const int row = row0 + ai * 128 + m * 16;
;                 const float s = (MODE == 2) ? 1.0f : rstd_of(rowss, row);
;                 bf16_t* rowp = O + (size_t)row * ldc + col0;
; #pragma unroll
;                 for (int bj = 0; bj < 2; ++bj) {
;                     f32x4 v0 = acc[ai][bj][m][0] * s, v1 = acc[ai][bj][m][1] * s;
;                     if (MODE == 1) {
; #pragma unroll
;                         for (int j = 0; j < 4; ++j) { const float a = fmaxf(v0[j], 0.f), b = fmaxf(v1[j], 0.f); v0[j] = a * a; v1[j] = b * b; } }
;                     u32x4 w; w.x = cvt_pk_bf16(v0[0], v0[1]); w.y = cvt_pk_bf16(v0[2], v0[3]); w.z = cvt_pk_bf16(v1[0], v1[1]); w.w = cvt_pk_bf16(v1[2], v1[3]);
;                     *(u32x4*)(rowp + bj * 128) = w; } }
	s_cbranch_scc0 .LBB0_1340
	v_lshl_add_u32 v162, s22, 8, v139
	v_ashrrev_i32_e32 v163, 31, v162
	v_lshl_add_u64 v[158:159], v[162:163], 2, s[0:1]
	global_load_dword v164, v[158:159], off
	global_load_dword v231, v[158:159], off offset:64
	global_load_dword v232, v[158:159], off offset:128
	global_load_dword v233, v[158:159], off offset:192
	global_load_dword v234, v[158:159], off offset:512
	global_load_dword v235, v[158:159], off offset:576
	global_load_dword v236, v[158:159], off offset:640
	global_load_dword v237, v[158:159], off offset:704
	v_lshl_or_b32 v160, s56, 8, v167
	v_ashrrev_i32_e32 v161, 31, v160
	s_mov_b32 s5, 0x80000
	s_mov_b64 s[14:15], 0x80000
	s_mov_b32 s56, s4
	s_mov_b32 s22, s6
	s_mov_b64 s[26:27], s[20:21]
	s_mov_b64 s[24:25], s[12:13]
	s_waitcnt vmcnt(0)
	v_fmamk_f32 v164, v164, 0x3a800000, v187
	v_cmp_gt_f32_e32 vcc, s67, v164
	v_mul_f32_e32 v165, 0x4b800000, v164
	s_nop 0
	v_cndmask_b32_e32 v164, v164, v165, vcc
	v_rsq_f32_e32 v164, v164
	s_nop 0
	v_mul_f32_e32 v165, 0x45800000, v164
	v_cndmask_b32_e32 v170, v164, v165, vcc
	v_lshlrev_b64 v[164:165], 12, v[162:163]
	v_lshl_add_u64 v[172:173], s[2:3], 0, v[164:165]
	v_lshlrev_b64 v[164:165], 1, v[160:161]
	v_lshl_add_u64 v[160:161], v[172:173], 0, v[164:165]
	v_pk_mul_f32 v[126:127], v[126:127], v[170:171] op_sel_hi:[1,0]
	v_pk_mul_f32 v[124:125], v[124:125], v[170:171] op_sel_hi:[1,0]
	v_pk_mul_f32 v[172:173], v[122:123], v[170:171] op_sel_hi:[1,0]
	v_pk_mul_f32 v[122:123], v[120:121], v[170:171] op_sel_hi:[1,0]
	v_cvt_pk_bf16_f32 v120, v124, v125
	v_cvt_pk_bf16_f32 v121, v126, v127
	v_cvt_pk_bf16_f32 v122, v122, v123
	v_cvt_pk_bf16_f32 v123, v172, v173
	global_store_dwordx4 v[160:161], v[120:123], off
	v_pk_mul_f32 v[118:119], v[118:119], v[170:171] op_sel_hi:[1,0]
	v_pk_mul_f32 v[116:117], v[116:117], v[170:171] op_sel_hi:[1,0]
	v_pk_mul_f32 v[120:121], v[114:115], v[170:171] op_sel_hi:[1,0]
	v_pk_mul_f32 v[114:115], v[112:113], v[170:171] op_sel_hi:[1,0]
	v_cvt_pk_bf16_f32 v112, v116, v117
	v_cvt_pk_bf16_f32 v113, v118, v119
	v_cvt_pk_bf16_f32 v114, v114, v115
	v_cvt_pk_bf16_f32 v115, v120, v121
	global_store_dwordx4 v[160:161], v[112:115], off offset:256
	s_nop 1
	v_mov_b32_e32 v114, v231
	s_nop 0
	v_or_b32_e32 v112, 16, v162
	v_ashrrev_i32_e32 v113, 31, v112
	v_lshlrev_b64 v[112:113], 12, v[112:113]
	v_lshl_add_u64 v[112:113], s[2:3], 0, v[112:113]
	v_lshl_add_u64 v[112:113], v[112:113], 0, v[164:165]
	v_fmamk_f32 v114, v114, 0x3a800000, v187
	v_cmp_gt_f32_e32 vcc, s67, v114
	v_mul_f32_e32 v115, 0x4b800000, v114
	s_nop 0
	v_cndmask_b32_e32 v114, v114, v115, vcc
	v_rsq_f32_e32 v114, v114
	s_nop 0
	v_mul_f32_e32 v115, 0x45800000, v114
	v_cndmask_b32_e32 v114, v114, v115, vcc
	v_pk_mul_f32 v[110:111], v[110:111], v[114:115] op_sel_hi:[1,0]
	v_pk_mul_f32 v[108:109], v[108:109], v[114:115] op_sel_hi:[1,0]
	v_pk_mul_f32 v[116:117], v[106:107], v[114:115] op_sel_hi:[1,0]
	v_pk_mul_f32 v[106:107], v[104:105], v[114:115] op_sel_hi:[1,0]
	v_cvt_pk_bf16_f32 v104, v108, v109
	v_cvt_pk_bf16_f32 v105, v110, v111
	v_cvt_pk_bf16_f32 v106, v106, v107
	v_cvt_pk_bf16_f32 v107, v116, v117
	global_store_dwordx4 v[112:113], v[104:107], off
	v_pk_mul_f32 v[102:103], v[102:103], v[114:115] op_sel_hi:[1,0]
	v_pk_mul_f32 v[100:101], v[100:101], v[114:115] op_sel_hi:[1,0]
	v_pk_mul_f32 v[104:105], v[98:99], v[114:115] op_sel_hi:[1,0]
	v_pk_mul_f32 v[98:99], v[96:97], v[114:115] op_sel_hi:[1,0]
	v_cvt_pk_bf16_f32 v96, v100, v101
	v_cvt_pk_bf16_f32 v97, v102, v103
	v_cvt_pk_bf16_f32 v98, v98, v99
	v_cvt_pk_bf16_f32 v99, v104, v105
	global_store_dwordx4 v[112:113], v[96:99], off offset:256
	s_nop 1
	v_mov_b32_e32 v98, v232
	s_nop 0
	v_or_b32_e32 v96, 32, v162
	v_ashrrev_i32_e32 v97, 31, v96
	v_lshlrev_b64 v[96:97], 12, v[96:97]
	v_lshl_add_u64 v[96:97], s[2:3], 0, v[96:97]
	v_lshl_add_u64 v[96:97], v[96:97], 0, v[164:165]
	v_fmamk_f32 v98, v98, 0x3a800000, v187
	v_cmp_gt_f32_e32 vcc, s67, v98
	v_mul_f32_e32 v99, 0x4b800000, v98
	s_nop 0
	v_cndmask_b32_e32 v98, v98, v99, vcc
	v_rsq_f32_e32 v98, v98
	s_nop 0
	v_mul_f32_e32 v99, 0x45800000, v98
	v_cndmask_b32_e32 v98, v98, v99, vcc
	v_pk_mul_f32 v[94:95], v[94:95], v[98:99] op_sel_hi:[1,0]
	v_pk_mul_f32 v[92:93], v[92:93], v[98:99] op_sel_hi:[1,0]
	v_pk_mul_f32 v[100:101], v[90:91], v[98:99] op_sel_hi:[1,0]
	v_pk_mul_f32 v[90:91], v[88:89], v[98:99] op_sel_hi:[1,0]
	v_cvt_pk_bf16_f32 v88, v92, v93
	v_cvt_pk_bf16_f32 v89, v94, v95
	v_cvt_pk_bf16_f32 v90, v90, v91
	v_cvt_pk_bf16_f32 v91, v100, v101
	global_store_dwordx4 v[96:97], v[88:91], off
	v_pk_mul_f32 v[86:87], v[86:87], v[98:99] op_sel_hi:[1,0]
	v_pk_mul_f32 v[84:85], v[84:85], v[98:99] op_sel_hi:[1,0]
	v_pk_mul_f32 v[88:89], v[82:83], v[98:99] op_sel_hi:[1,0]
	v_pk_mul_f32 v[82:83], v[80:81], v[98:99] op_sel_hi:[1,0]
	v_cvt_pk_bf16_f32 v80, v84, v85
	v_cvt_pk_bf16_f32 v81, v86, v87
	v_cvt_pk_bf16_f32 v82, v82, v83
	v_cvt_pk_bf16_f32 v83, v88, v89
	global_store_dwordx4 v[96:97], v[80:83], off offset:256
	s_nop 1
	v_mov_b32_e32 v82, v233
	s_nop 0
	v_or_b32_e32 v80, 48, v162
	v_ashrrev_i32_e32 v81, 31, v80
	v_lshlrev_b64 v[80:81], 12, v[80:81]
	v_lshl_add_u64 v[80:81], s[2:3], 0, v[80:81]
	v_lshl_add_u64 v[80:81], v[80:81], 0, v[164:165]
	v_fmamk_f32 v82, v82, 0x3a800000, v187
	v_cmp_gt_f32_e32 vcc, s67, v82
	v_mul_f32_e32 v83, 0x4b800000, v82
	s_nop 0
	v_cndmask_b32_e32 v82, v82, v83, vcc
	v_rsq_f32_e32 v82, v82
	s_nop 0
	v_mul_f32_e32 v83, 0x45800000, v82
	v_cndmask_b32_e32 v82, v82, v83, vcc
	v_pk_mul_f32 v[78:79], v[78:79], v[82:83] op_sel_hi:[1,0]
	v_pk_mul_f32 v[76:77], v[76:77], v[82:83] op_sel_hi:[1,0]
	v_pk_mul_f32 v[84:85], v[74:75], v[82:83] op_sel_hi:[1,0]
; __device__ __forceinline__ unsigned cvt_pk_bf16(float lo, float hi) { const f32x2_cv v = {lo, hi}; const bf16x2_cv b = __builtin_convertvector(v, bf16x2_cv); return __builtin_bit_cast(unsigned, b); }
; #define PG8_WAIT_V(n) asm volatile("s_waitcnt vmcnt(" #n ")" ::: "memory")
; #define PG8_BAR __builtin_amdgcn_s_barrier()
; __device__ __forceinline__ float rstd_of(const float* rowss, int row) { return rsqrtf(rowss[row] * (1.0f / 1024.0f) + 1e-6f); }
; template <class Epi, class Sched, bool STAMP = false>
; __device__ __forceinline__ void gemm_phase(PG8_LAS unsigned char* lds, const Gemm g, const Sched& S, const Epi& E, unsigned long long* stamps) {
;     ...
;         if (!has_next) break;
; #pragma unroll
;         for (int a = 0; a < 2; ++a)
; #pragma unroll
;             for (int b = 0; b < 2; ++b)
; #pragma unroll
;                 for (int m = 0; m < 4; ++m)
; #pragma unroll
;                     for (int n = 0; n < 2; ++n) acc[a][b][m][n] = (f32x4){0.f, 0.f, 0.f, 0.f};
;         cur = nxt; cA = nA; cB = nB; ++ui;
;     }
;     PG8_WAIT_V(0);
;     if (wr == 0) PG8_BAR;
;     __device__ __forceinline__ void operator()(const f32x4 (&acc)[2][2][4][2], const pg8::Unit& u, int wr, int wc, int fr, int fq) const {
;         const int row0 = u.pm * 256 + wr * 64 + fr, col0 = u.pn * 256 + wc * 32 + 8 * fq;
; #pragma unroll
;         for (int ai = 0; ai < 2; ++ai)
; #pragma unroll
;             for (int m = 0; m < 4; ++m) {
;                 const int row = row0 + ai * 128 + m * 16;
;                 const float s = (MODE == 2) ? 1.0f : rstd_of(rowss, row);
;                 bf16_t* rowp = O + (size_t)row * ldc + col0;
; #pragma unroll
;                 for (int bj = 0; bj < 2; ++bj) {
;                     f32x4 v0 = acc[ai][bj][m][0] * s, v1 = acc[ai][bj][m][1] * s;
;                     if (MODE == 1) {
; #pragma unroll
;                         for (int j = 0; j < 4; ++j) { const float a = fmaxf(v0[j], 0.f), b = fmaxf(v1[j], 0.f); v0[j] = a * a; v1[j] = b * b; } }
;                     u32x4 w; w.x = cvt_pk_bf16(v0[0], v0[1]); w.y = cvt_pk_bf16(v0[2], v0[3]); w.z = cvt_pk_bf16(v1[0], v1[1]); w.w = cvt_pk_bf16(v1[2], v1[3]);
;                     *(u32x4*)(rowp + bj * 128) = w; } }
	v_pk_mul_f32 v[74:75], v[72:73], v[82:83] op_sel_hi:[1,0]
	v_cvt_pk_bf16_f32 v72, v76, v77
	v_cvt_pk_bf16_f32 v73, v78, v79
	v_cvt_pk_bf16_f32 v74, v74, v75
	v_cvt_pk_bf16_f32 v75, v84, v85
	global_store_dwordx4 v[80:81], v[72:75], off
	v_pk_mul_f32 v[70:71], v[70:71], v[82:83] op_sel_hi:[1,0]
	v_pk_mul_f32 v[68:69], v[68:69], v[82:83] op_sel_hi:[1,0]
	v_pk_mul_f32 v[72:73], v[66:67], v[82:83] op_sel_hi:[1,0]
	v_pk_mul_f32 v[66:67], v[64:65], v[82:83] op_sel_hi:[1,0]
	v_cvt_pk_bf16_f32 v64, v68, v69
	v_cvt_pk_bf16_f32 v65, v70, v71
	v_cvt_pk_bf16_f32 v66, v66, v67
	v_cvt_pk_bf16_f32 v67, v72, v73
	global_store_dwordx4 v[80:81], v[64:67], off offset:256
	s_nop 1
	v_mov_b32_e32 v64, v234
	s_nop 0
	v_lshl_add_u64 v[66:67], v[160:161], 0, s[14:15]
	s_mov_b64 s[14:15], 0x90000
	v_fmamk_f32 v64, v64, 0x3a800000, v187
	v_cmp_gt_f32_e32 vcc, s67, v64
	v_mul_f32_e32 v65, 0x4b800000, v64
	s_nop 0
	v_cndmask_b32_e32 v64, v64, v65, vcc
	v_rsq_f32_e32 v64, v64
	s_nop 0
	v_mul_f32_e32 v65, 0x45800000, v64
	v_cndmask_b32_e32 v64, v64, v65, vcc
	v_pk_mul_f32 v[60:61], v[60:61], v[64:65] op_sel_hi:[1,0]
	v_pk_mul_f32 v[62:63], v[62:63], v[64:65] op_sel_hi:[1,0]
	v_pk_mul_f32 v[68:69], v[58:59], v[64:65] op_sel_hi:[1,0]
	v_pk_mul_f32 v[58:59], v[56:57], v[64:65] op_sel_hi:[1,0]
	v_cvt_pk_bf16_f32 v56, v60, v61
	v_add_co_u32_e32 v60, vcc, s5, v160
	v_cvt_pk_bf16_f32 v57, v62, v63
	v_cvt_pk_bf16_f32 v58, v58, v59
	v_cvt_pk_bf16_f32 v59, v68, v69
	v_addc_co_u32_e32 v61, vcc, 0, v161, vcc
	global_store_dwordx4 v[60:61], v[56:59], off
	v_pk_mul_f32 v[54:55], v[54:55], v[64:65] op_sel_hi:[1,0]
	v_pk_mul_f32 v[52:53], v[52:53], v[64:65] op_sel_hi:[1,0]
	v_pk_mul_f32 v[56:57], v[50:51], v[64:65] op_sel_hi:[1,0]
	v_pk_mul_f32 v[50:51], v[48:49], v[64:65] op_sel_hi:[1,0]
	v_cvt_pk_bf16_f32 v48, v52, v53
	v_cvt_pk_bf16_f32 v49, v54, v55
	v_cvt_pk_bf16_f32 v50, v50, v51
	v_cvt_pk_bf16_f32 v51, v56, v57
	global_store_dwordx4 v[66:67], v[48:51], off offset:256
	s_nop 1
	v_mov_b32_e32 v48, v235
	s_mov_b32 s5, 0x90000
	v_lshl_add_u64 v[50:51], v[160:161], 0, s[14:15]
	s_mov_b64 s[14:15], 0xa0000
	v_fmamk_f32 v48, v48, 0x3a800000, v187
	v_cmp_gt_f32_e32 vcc, s67, v48
	v_mul_f32_e32 v49, 0x4b800000, v48
	s_nop 0
	v_cndmask_b32_e32 v48, v48, v49, vcc
	v_rsq_f32_e32 v48, v48
	s_nop 0
	v_mul_f32_e32 v49, 0x45800000, v48
	v_cndmask_b32_e32 v48, v48, v49, vcc
	v_pk_mul_f32 v[44:45], v[44:45], v[48:49] op_sel_hi:[1,0]
	v_pk_mul_f32 v[46:47], v[46:47], v[48:49] op_sel_hi:[1,0]
	v_pk_mul_f32 v[52:53], v[42:43], v[48:49] op_sel_hi:[1,0]
	v_pk_mul_f32 v[42:43], v[40:41], v[48:49] op_sel_hi:[1,0]
	v_cvt_pk_bf16_f32 v40, v44, v45
	v_add_co_u32_e32 v44, vcc, s5, v160
	v_cvt_pk_bf16_f32 v41, v46, v47
	v_cvt_pk_bf16_f32 v42, v42, v43
	v_cvt_pk_bf16_f32 v43, v52, v53
	v_addc_co_u32_e32 v45, vcc, 0, v161, vcc
	global_store_dwordx4 v[44:45], v[40:43], off
	v_pk_mul_f32 v[38:39], v[38:39], v[48:49] op_sel_hi:[1,0]
	v_pk_mul_f32 v[36:37], v[36:37], v[48:49] op_sel_hi:[1,0]
	v_pk_mul_f32 v[40:41], v[34:35], v[48:49] op_sel_hi:[1,0]
	v_pk_mul_f32 v[34:35], v[32:33], v[48:49] op_sel_hi:[1,0]
	v_cvt_pk_bf16_f32 v32, v36, v37
	v_cvt_pk_bf16_f32 v33, v38, v39
	v_cvt_pk_bf16_f32 v34, v34, v35
	v_cvt_pk_bf16_f32 v35, v40, v41
	global_store_dwordx4 v[50:51], v[32:35], off offset:256
	s_nop 1
	v_mov_b32_e32 v32, v236
	s_mov_b32 s5, 0xa0000
	v_lshl_add_u64 v[34:35], v[160:161], 0, s[14:15]
	s_mov_b64 s[14:15], 0xb0000
	v_fmamk_f32 v32, v32, 0x3a800000, v187
	v_cmp_gt_f32_e32 vcc, s67, v32
	v_mul_f32_e32 v33, 0x4b800000, v32
	s_nop 0
	v_cndmask_b32_e32 v32, v32, v33, vcc
	v_rsq_f32_e32 v32, v32
	s_nop 0
	v_mul_f32_e32 v33, 0x45800000, v32
	v_cndmask_b32_e32 v32, v32, v33, vcc
	v_pk_mul_f32 v[28:29], v[28:29], v[32:33] op_sel_hi:[1,0]
	v_pk_mul_f32 v[30:31], v[30:31], v[32:33] op_sel_hi:[1,0]
	v_pk_mul_f32 v[36:37], v[26:27], v[32:33] op_sel_hi:[1,0]
	v_pk_mul_f32 v[26:27], v[24:25], v[32:33] op_sel_hi:[1,0]
	v_cvt_pk_bf16_f32 v24, v28, v29
	v_add_co_u32_e32 v28, vcc, s5, v160
	v_cvt_pk_bf16_f32 v25, v30, v31
	v_cvt_pk_bf16_f32 v26, v26, v27
	v_cvt_pk_bf16_f32 v27, v36, v37
	v_addc_co_u32_e32 v29, vcc, 0, v161, vcc
	global_store_dwordx4 v[28:29], v[24:27], off
	v_pk_mul_f32 v[22:23], v[22:23], v[32:33] op_sel_hi:[1,0]
	v_pk_mul_f32 v[20:21], v[20:21], v[32:33] op_sel_hi:[1,0]
	v_pk_mul_f32 v[24:25], v[18:19], v[32:33] op_sel_hi:[1,0]
	v_pk_mul_f32 v[18:19], v[16:17], v[32:33] op_sel_hi:[1,0]
	v_cvt_pk_bf16_f32 v16, v20, v21
	v_cvt_pk_bf16_f32 v17, v22, v23
	v_cvt_pk_bf16_f32 v18, v18, v19
	v_cvt_pk_bf16_f32 v19, v24, v25
	global_store_dwordx4 v[34:35], v[16:19], off offset:256
	s_nop 1
	v_mov_b32_e32 v16, v237
	s_mov_b32 s5, 0xb0000
	v_lshl_add_u64 v[18:19], v[160:161], 0, s[14:15]
	v_fmamk_f32 v16, v16, 0x3a800000, v187
	v_cmp_gt_f32_e32 vcc, s67, v16
	v_mul_f32_e32 v17, 0x4b800000, v16
	s_nop 0
	v_cndmask_b32_e32 v16, v16, v17, vcc
	v_rsq_f32_e32 v16, v16
	s_nop 0
	v_mul_f32_e32 v17, 0x45800000, v16
	v_cndmask_b32_e32 v16, v16, v17, vcc
	v_pk_mul_f32 v[12:13], v[12:13], v[16:17] op_sel_hi:[1,0]
	v_pk_mul_f32 v[14:15], v[14:15], v[16:17] op_sel_hi:[1,0]
	v_pk_mul_f32 v[20:21], v[10:11], v[16:17] op_sel_hi:[1,0]
	v_pk_mul_f32 v[10:11], v[8:9], v[16:17] op_sel_hi:[1,0]
	v_cvt_pk_bf16_f32 v8, v12, v13
	v_add_co_u32_e32 v12, vcc, s5, v160
	v_cvt_pk_bf16_f32 v9, v14, v15
	v_cvt_pk_bf16_f32 v10, v10, v11
	v_cvt_pk_bf16_f32 v11, v20, v21
	v_addc_co_u32_e32 v13, vcc, 0, v161, vcc
	global_store_dwordx4 v[12:13], v[8:11], off
	v_pk_mul_f32 v[6:7], v[6:7], v[16:17] op_sel_hi:[1,0]
	v_pk_mul_f32 v[4:5], v[4:5], v[16:17] op_sel_hi:[1,0]
	v_pk_mul_f32 v[8:9], v[2:3], v[16:17] op_sel_hi:[1,0]
	v_pk_mul_f32 v[2:3], v[0:1], v[16:17] op_sel_hi:[1,0]
	v_cvt_pk_bf16_f32 v0, v4, v5
	v_cvt_pk_bf16_f32 v1, v6, v7
	v_cvt_pk_bf16_f32 v2, v2, v3
	v_cvt_pk_bf16_f32 v3, v8, v9
	s_and_b64 vcc, exec, s[38:39]
	global_store_dwordx4 v[18:19], v[0:3], off offset:256
	s_cbranch_vccz .LBB0_1337
	s_waitcnt vmcnt(0)
	s_cmpk_gt_u32 s42, 0xff
	s_cbranch_scc1 .LBB0_1344
	s_barrier

; #define PG8_STAGE(bufoff, gbase, voff) do { _Pragma("unroll") for (int _i = 0; _i < 2; ++_i) \
;         __builtin_amdgcn_global_load_lds((const unsigned*)((const char*)(gbase) + (voff)[_i]), (PG8_LAS unsigned*)(lds + (bufoff) + ldsw + _i * 8192), 16, 0, 0); } while (0)
; #define PG8_WAIT_V(n) asm volatile("s_waitcnt vmcnt(" #n ")" ::: "memory")
; #define PG8_BAR __builtin_amdgcn_s_barrier()
;     __device__ bool next(int i, pg8::Unit& u) const { if (i != 0 || !valid) return false; u.pm = pm; u.pn = pn; return true; }
; template <class Epi, class Sched, bool STAMP = false>
; __device__ __forceinline__ void gemm_phase(PG8_LAS unsigned char* lds, const Gemm g, const Sched& S, const Epi& E, unsigned long long* stamps) {
;     ...
;     const int aoff = lds_byte(wr * 64 + fr, fq * 8), boff = lds_byte(wc * 32 + fr, fq * 8);
;     ...
;     Unit cur, nxt; int ui = 0;
;     if (!S.next(0, cur)) return;
;     f32x4 acc[2][2][4][2];
; #pragma unroll
;     for (int a = 0; a < 2; ++a)
; #pragma unroll
;         for (int b = 0; b < 2; ++b)
; #pragma unroll
;             for (int m = 0; m < 4; ++m)
; #pragma unroll
;                 for (int n = 0; n < 2; ++n) acc[a][b][m][n] = (f32x4){0.f, 0.f, 0.f, 0.f};
;     bf16x8 At[4][2], B0[2][2], B1[2][2];
;     const char* cA = (const char*)g.A + (size_t)cur.pm * tstep; const char* cB = (const char*)g.Bt + (size_t)cur.pn * tstep;
;     S.a_ready(cur);
;     PG8_STAGE(PG8_SB(0, 0), cB, voffB); PG8_STAGE(PG8_SA(0, 0), cA, voffA); PG8_STAGE(PG8_SB(0, 1), cB + hstep, voffB); PG8_STAGE(PG8_SA(0, 1), cA + hstep, voffA);
;     if (wr == 1) PG8_BAR;
;     PG8_WAIT_V(4); PG8_BAR;
;     PG8_STAGE(PG8_SB(1, 0), cB + kstep, voffB); PG8_STAGE(PG8_SA(1, 0), cA + kstep, voffA); PG8_STAGE(PG8_SB(1, 1), cB + hstep + kstep, voffB);
;     PG8_WAIT_V(6); PG8_BAR;
.LBB0_1348:
	v_bfe_u32 v139, v0, 4, 2
	s_lshl_b32 s14, s14, 5
	v_and_b32_e32 v150, 15, v0
	v_lshlrev_b32_e32 v1, 4, v139
	v_lshlrev_b32_e32 v0, 2, v0
	s_and_b32 s56, s14, 0x60
	v_lshl_add_u64 v[2:3], s[6:7], 0, v[128:129]
	v_mov_b32_e32 v149, v129
	s_lshl_b32 s53, s15, 6
	v_lshl_or_b32 v1, v150, 6, v1
	s_lshl_b32 s15, s15, 13
	v_and_b32_e32 v0, 32, v0
	s_lshl_b32 s14, s56, 7
	v_lshl_add_u64 v[4:5], s[6:7], 0, v[148:149]
	v_bitop3_b32 v10, v1, s15, v0 bitop3:0xde
	v_bitop3_b32 v151, v1, s14, v0 bitop3:0xde
	s_add_i32 m0, s10, 0x18000
	v_lshl_add_u64 v[0:1], v[2:3], 0, s[18:19]
	v_lshl_add_u64 v[6:7], s[12:13], 0, v[128:129]
	s_waitcnt vmcnt(4)
	s_barrier
	global_load_lds_dwordx4 v[0:1], off
	v_lshl_add_u64 v[0:1], v[4:5], 0, s[18:19]
	s_add_i32 m0, s10, 0x1a000
	s_add_i32 s57, s10, 0x8000
	s_add_i32 s58, s10, 0xa000
	v_lshl_add_u64 v[8:9], s[12:13], 0, v[148:149]
	global_load_lds_dwordx4 v[0:1], off
	v_lshl_add_u64 v[0:1], v[6:7], 0, s[18:19]
	s_mov_b32 m0, s57
	s_add_u32 s14, s6, 0x40080
	global_load_lds_dwordx4 v[0:1], off
	v_lshl_add_u64 v[0:1], v[8:9], 0, s[18:19]
	s_mov_b32 m0, s58
	s_addc_u32 s15, s7, 0
	global_load_lds_dwordx4 v[0:1], off
	s_add_i32 m0, s10, 0x1c000
	v_lshl_add_u64 v[0:1], s[14:15], 0, v[128:129]
	global_load_lds_dwordx4 v[0:1], off
	v_lshl_add_u64 v[0:1], s[14:15], 0, v[148:149]
	s_add_i32 m0, s10, 0x1e000
	s_mov_b32 s14, 0
	global_load_lds_dwordx4 v[0:1], off
	s_waitcnt vmcnt(6)
	v_mov_b32_e32 v0, 0
	s_mov_b64 s[22:23], -1
	s_mov_b64 s[24:25], 0
	v_add_u32_e32 v152, 0, v10
	v_mov_b32_e32 v1, v0
	v_mov_b32_e32 v2, v0
	v_mov_b32_e32 v3, v0
	v_mov_b32_e32 v4, v0
	v_mov_b32_e32 v5, v0
	v_mov_b32_e32 v6, v0
	v_mov_b32_e32 v7, v0
	v_mov_b32_e32 v8, v0
	v_mov_b32_e32 v9, v0
	v_mov_b32_e32 v10, v0
	v_mov_b32_e32 v11, v0
	v_mov_b32_e32 v12, v0
	v_mov_b32_e32 v13, v0
	v_mov_b32_e32 v14, v0
	v_mov_b32_e32 v15, v0
	v_mov_b32_e32 v24, v0
	v_mov_b32_e32 v25, v0
	v_mov_b32_e32 v26, v0
	v_mov_b32_e32 v27, v0
	v_mov_b32_e32 v28, v0
	v_mov_b32_e32 v29, v0
	v_mov_b32_e32 v30, v0
	v_mov_b32_e32 v31, v0
	v_mov_b32_e32 v40, v0
	v_mov_b32_e32 v41, v0
	v_mov_b32_e32 v42, v0
	v_mov_b32_e32 v43, v0
	v_mov_b32_e32 v44, v0
	v_mov_b32_e32 v45, v0
	v_mov_b32_e32 v46, v0
	v_mov_b32_e32 v47, v0
	v_mov_b32_e32 v16, v0
	v_mov_b32_e32 v17, v0
	v_mov_b32_e32 v18, v0
	v_mov_b32_e32 v19, v0
	v_mov_b32_e32 v20, v0
	v_mov_b32_e32 v21, v0
	v_mov_b32_e32 v22, v0
	v_mov_b32_e32 v23, v0
	v_mov_b32_e32 v32, v0
	v_mov_b32_e32 v33, v0
	v_mov_b32_e32 v34, v0
	v_mov_b32_e32 v35, v0
	v_mov_b32_e32 v36, v0
	v_mov_b32_e32 v37, v0
	v_mov_b32_e32 v38, v0
	v_mov_b32_e32 v39, v0
	v_mov_b32_e32 v48, v0
	v_mov_b32_e32 v49, v0
	v_mov_b32_e32 v50, v0
	v_mov_b32_e32 v51, v0
	v_mov_b32_e32 v52, v0
	v_mov_b32_e32 v53, v0
	v_mov_b32_e32 v54, v0
	v_mov_b32_e32 v55, v0
	v_mov_b32_e32 v56, v0
	v_mov_b32_e32 v57, v0
	v_mov_b32_e32 v58, v0
	v_mov_b32_e32 v59, v0
	v_mov_b32_e32 v60, v0
	v_mov_b32_e32 v61, v0
	v_mov_b32_e32 v62, v0
	v_mov_b32_e32 v63, v0
	v_mov_b32_e32 v64, v0
	v_mov_b32_e32 v65, v0
	v_mov_b32_e32 v66, v0
	v_mov_b32_e32 v67, v0
	v_mov_b32_e32 v68, v0
	v_mov_b32_e32 v69, v0
	v_mov_b32_e32 v70, v0
	v_mov_b32_e32 v71, v0
	v_mov_b32_e32 v72, v0
	v_mov_b32_e32 v73, v0
	v_mov_b32_e32 v74, v0
	v_mov_b32_e32 v75, v0
	v_mov_b32_e32 v76, v0
	v_mov_b32_e32 v77, v0
	v_mov_b32_e32 v78, v0
	s_waitcnt vmcnt(0)
	v_mov_b32_e32 v79, v0
	v_mov_b32_e32 v84, v0
	v_mov_b32_e32 v85, v0
	v_mov_b32_e32 v86, v0
	v_mov_b32_e32 v87, v0
	v_mov_b32_e32 v92, v0
	v_mov_b32_e32 v93, v0
	v_mov_b32_e32 v94, v0
	v_mov_b32_e32 v95, v0
	v_mov_b32_e32 v100, v0
	v_mov_b32_e32 v101, v0
	v_mov_b32_e32 v102, v0
	v_mov_b32_e32 v103, v0
	v_mov_b32_e32 v108, v0
	v_mov_b32_e32 v109, v0
	v_mov_b32_e32 v110, v0
	v_mov_b32_e32 v111, v0
	v_mov_b32_e32 v80, v0
	v_mov_b32_e32 v81, v0
	v_mov_b32_e32 v82, v0
	v_mov_b32_e32 v83, v0
	v_mov_b32_e32 v88, v0
	v_mov_b32_e32 v89, v0
	v_mov_b32_e32 v90, v0
	v_mov_b32_e32 v91, v0
	v_mov_b32_e32 v96, v0
	v_mov_b32_e32 v97, v0
	v_mov_b32_e32 v98, v0
	v_mov_b32_e32 v99, v0
	v_mov_b32_e32 v104, v0
	v_mov_b32_e32 v105, v0
	v_mov_b32_e32 v106, v0
	v_mov_b32_e32 v107, v0
	v_mov_b32_e32 v112, v0
	v_mov_b32_e32 v113, v0
	v_mov_b32_e32 v114, v0
	v_mov_b32_e32 v115, v0
	v_mov_b32_e32 v116, v0
	v_mov_b32_e32 v117, v0
	v_mov_b32_e32 v118, v0
	v_mov_b32_e32 v119, v0
	v_mov_b32_e32 v120, v0
	v_mov_b32_e32 v121, v0
	v_mov_b32_e32 v122, v0
	v_mov_b32_e32 v123, v0
	v_mov_b32_e32 v124, v0
	v_mov_b32_e32 v125, v0
	v_mov_b32_e32 v126, v0
	v_mov_b32_e32 v127, v0
	s_barrier
	v_add_u32_e32 v244, 0x80, v128
	v_add_u32_e32 v245, 0x80, v148
	v_add_u32_e32 v248, 0x10000, v151
	v_add_u32_e32 v249, 0x14000, v151
	v_add_u32_e32 v250, 0x18000, v151
	v_add_u32_e32 v251, 0x1c000, v151
; #define PG8_STAGE(bufoff, gbase, voff) do { _Pragma("unroll") for (int _i = 0; _i < 2; ++_i) \
;         __builtin_amdgcn_global_load_lds((const unsigned*)((const char*)(gbase) + (voff)[_i]), (PG8_LAS unsigned*)(lds + (bufoff) + ldsw + _i * 8192), 16, 0, 0); } while (0)
; #define PG8_LDA(dst, b, h) do { _Pragma("unroll") for (int m = 0; m < 4; ++m) _Pragma("unroll") for (int k = 0; k < 2; ++k) dst[m][k] = *(const PG8_LAS bf16x8*)(lds + PG8_SA(b, h) + aoff + m * 2048 + k * 1024); } while (0)
; #define PG8_LDB(dst, b, h) do { _Pragma("unroll") for (int n = 0; n < 2; ++n) _Pragma("unroll") for (int k = 0; k < 2; ++k) dst[n][k] = *(const PG8_LAS bf16x8*)(lds + PG8_SB(b, h) + boff + n * 2048 + k * 1024); } while (0)
; #define PG8_MMA(ai, bj, At, Bt) do { __builtin_amdgcn_s_setprio(1); _Pragma("unroll") for (int m = 0; m < 4; ++m) _Pragma("unroll") for (int n = 0; n < 2; ++n) _Pragma("unroll") for (int k = 0; k < 2; ++k) \
;         acc[ai][bj][m][n] = __builtin_amdgcn_mfma_f32_16x16x32_bf16(Bt[n][k], At[m][k], acc[ai][bj][m][n], 0, 0, 0); __builtin_amdgcn_s_setprio(0); } while (0)
; #define PG8_WAIT_L(n) asm volatile("s_waitcnt lgkmcnt(" #n ")" ::: "memory")
; #define PG8_BAR __builtin_amdgcn_s_barrier()
; #define PG8_SCHED __builtin_amdgcn_sched_barrier(0)
; template <class Epi, class Sched, bool STAMP = false>
; __device__ __forceinline__ void gemm_phase(PG8_LAS unsigned char* lds, const Gemm g, const Sched& S, const Epi& E, unsigned long long* stamps) {
;     ...
;         for (int t = 0; t < nt; t += 2) {
;             const bool last = (t == nt - 2);
;             const char* a1 = cA + (size_t)(t + 1) * kstep;
;             const char* a2 = last ? nA : cA + (size_t)(t + 2) * kstep; const char* b2 = last ? nB : cB + (size_t)(t + 2) * kstep;
;             const char* a3 = a2 + kstep; const char* b3 = b2 + kstep;
;             if (last && has_next) S.a_ready(nxt);
;             PG8_LDB(B0, 0, 0); PG8_SCHED; PG8_LDA(At, 0, 0); PG8_STAGE(PG8_SA(1, 1), a1 + hstep, voffA);
;             PG8_WAIT_L(8); PG8_BAR; PG8_WAIT_L(0); PG8_MMA(0, 0, At, B0); PG8_BAR; PG8_SCHED;
;             PG8_LDB(B1, 0, 1); PG8_STAGE(PG8_SB(0, 0), b2, voffB);
;             PG8_BAR; PG8_WAIT_L(0); PG8_MMA(0, 1, At, B1); PG8_BAR;
;             PG8_LDA(At, 0, 1); PG8_STAGE(PG8_SA(0, 0), a2, voffA);
;             PG8_BAR; PG8_WAIT_L(0); PG8_MMA(1, 0, At, B0); PG8_BAR; PG8_SCHED;
.LBB0_1349:
	s_add_i32 s15, s14, 0x100
	s_and_b64 s[16:17], s[24:25], exec
	s_cselect_b32 s15, 0, s15
	s_cselect_b32 s16, 0, 0
	s_add_u32 s36, s12, s15
	s_addc_u32 s37, s13, s16
	s_add_i32 s25, 0, 0x10000
	s_add_u32 s38, s6, s15
	s_addc_u32 s39, s7, s16
	s_add_u32 s40, s20, s14
	s_addc_u32 s41, s21, 0
	s_add_i32 s63, s25, s46
	s_add_i32 m0, s10, 0xc000
	s_add_i32 s64, s10, 0xe000
	s_add_i32 s62, 0, 0x14000
	s_add_i32 s61, s63, 0x2000
	s_add_u32 s30, s38, 0x40000
	s_addc_u32 s31, s39, 0
	s_add_i32 s52, s62, s46
	ds_read_b128 v[154:157], v248
	ds_read_b128 v[158:161], v248 offset:1024
	ds_read_b128 v[162:165], v248 offset:2048
	ds_read_b128 v[166:169], v248 offset:3072
	s_add_i32 s29, s52, 0x2000
	s_add_i32 s17, 0, 0x18000
	s_add_u32 s26, s36, 0x40000
	s_addc_u32 s27, s37, 0
	s_add_i32 s16, s17, s46
	s_add_i32 s15, 0, 0x1c000
	s_add_i32 s14, s16, 0x2000
	s_add_u32 s24, s38, 0x40080
	s_addc_u32 s25, s39, 0
	s_add_i32 s60, s15, s46
	s_add_i32 s59, s60, 0x2000
	v_lshl_add_u64 v[182:183], s[40:41], 0, v[128:129]
	v_lshl_add_u64 v[182:183], v[182:183], 0, s[18:19]
	ds_read_b128 v[170:173], v152
	ds_read_b128 v[174:177], v152 offset:1024
	ds_read_b128 v[178:181], v152 offset:2048
	ds_read_b128 v[192:195], v152 offset:3072
	ds_read_b128 v[196:199], v152 offset:4096
	ds_read_b128 v[200:203], v152 offset:5120
	ds_read_b128 v[204:207], v152 offset:6144
	ds_read_b128 v[208:211], v152 offset:7168
	global_load_lds_dwordx4 v244, s[40:41]
	v_lshl_add_u64 v[182:183], s[40:41], 0, v[148:149]
	v_lshl_add_u64 v[182:183], v[182:183], 0, s[18:19]
	s_mov_b32 m0, s64
	s_nop 0
	global_load_lds_dwordx4 v245, s[40:41]
	s_waitcnt lgkmcnt(8)
	s_barrier
	s_waitcnt lgkmcnt(0)
	v_mfma_f32_16x16x32_bf16 v[124:127], v[154:157], v[170:173], v[124:127]
	v_mfma_f32_16x16x32_bf16 v[120:123], v[162:165], v[170:173], v[120:123]
	v_mfma_f32_16x16x32_bf16 v[116:119], v[154:157], v[178:181], v[116:119]
	v_mfma_f32_16x16x32_bf16 v[112:115], v[162:165], v[178:181], v[112:115]
	v_mfma_f32_16x16x32_bf16 v[104:107], v[154:157], v[196:199], v[104:107]
	v_mfma_f32_16x16x32_bf16 v[96:99], v[162:165], v[196:199], v[96:99]
	v_mfma_f32_16x16x32_bf16 v[88:91], v[154:157], v[204:207], v[88:91]
	v_mfma_f32_16x16x32_bf16 v[80:83], v[162:165], v[204:207], v[80:83]
	v_mfma_f32_16x16x32_bf16 v[124:127], v[158:161], v[174:177], v[124:127]
	v_mfma_f32_16x16x32_bf16 v[120:123], v[166:169], v[174:177], v[120:123]
	v_mfma_f32_16x16x32_bf16 v[116:119], v[158:161], v[192:195], v[116:119]
	v_mfma_f32_16x16x32_bf16 v[112:115], v[166:169], v[192:195], v[112:115]
	v_mfma_f32_16x16x32_bf16 v[104:107], v[158:161], v[200:203], v[104:107]
	v_mfma_f32_16x16x32_bf16 v[96:99], v[166:169], v[200:203], v[96:99]
	v_mfma_f32_16x16x32_bf16 v[88:91], v[158:161], v[208:211], v[88:91]
	v_mfma_f32_16x16x32_bf16 v[80:83], v[166:169], v[208:211], v[80:83]
	s_barrier
	s_mov_b32 m0, s63
	v_lshl_add_u64 v[182:183], s[38:39], 0, v[128:129]
	ds_read_b128 v[212:215], v249
	ds_read_b128 v[216:219], v249 offset:1024
	ds_read_b128 v[220:223], v249 offset:2048
	ds_read_b128 v[224:227], v249 offset:3072
	global_load_lds_dwordx4 v128, s[38:39]
	v_lshl_add_u64 v[228:229], s[38:39], 0, v[148:149]
	s_mov_b32 m0, s61
	s_nop 0
	global_load_lds_dwordx4 v148, s[38:39]
	s_barrier
	s_waitcnt lgkmcnt(0)
	v_mfma_f32_16x16x32_bf16 v[108:111], v[212:215], v[170:173], v[108:111]
	v_mfma_f32_16x16x32_bf16 v[100:103], v[220:223], v[170:173], v[100:103]
	v_mfma_f32_16x16x32_bf16 v[92:95], v[212:215], v[178:181], v[92:95]
	v_mfma_f32_16x16x32_bf16 v[84:87], v[220:223], v[178:181], v[84:87]
	v_mfma_f32_16x16x32_bf16 v[76:79], v[212:215], v[196:199], v[76:79]
	v_mfma_f32_16x16x32_bf16 v[72:75], v[220:223], v[196:199], v[72:75]
	v_mfma_f32_16x16x32_bf16 v[68:71], v[212:215], v[204:207], v[68:71]
	v_mfma_f32_16x16x32_bf16 v[64:67], v[220:223], v[204:207], v[64:67]
	v_mfma_f32_16x16x32_bf16 v[108:111], v[216:219], v[174:177], v[108:111]
	v_mfma_f32_16x16x32_bf16 v[100:103], v[224:227], v[174:177], v[100:103]
	v_mfma_f32_16x16x32_bf16 v[92:95], v[216:219], v[192:195], v[92:95]
	v_mfma_f32_16x16x32_bf16 v[84:87], v[224:227], v[192:195], v[84:87]
	v_mfma_f32_16x16x32_bf16 v[76:79], v[216:219], v[200:203], v[76:79]
	v_mfma_f32_16x16x32_bf16 v[72:75], v[224:227], v[200:203], v[72:75]
	v_mfma_f32_16x16x32_bf16 v[68:71], v[216:219], v[208:211], v[68:71]
	v_mfma_f32_16x16x32_bf16 v[64:67], v[224:227], v[208:211], v[64:67]
	s_mov_b32 m0, s10
	v_lshl_add_u64 v[230:231], s[36:37], 0, v[128:129]
	s_barrier
	ds_read_b128 v[170:173], v152 offset:16384
	ds_read_b128 v[174:177], v152 offset:17408
	ds_read_b128 v[178:181], v152 offset:18432
	ds_read_b128 v[192:195], v152 offset:19456
	ds_read_b128 v[196:199], v152 offset:20480
	ds_read_b128 v[200:203], v152 offset:21504
	ds_read_b128 v[204:207], v152 offset:22528
	ds_read_b128 v[208:211], v152 offset:23552
	global_load_lds_dwordx4 v128, s[36:37]
	v_lshl_add_u64 v[232:233], s[36:37], 0, v[148:149]
	s_mov_b32 m0, s47
	s_nop 0
	global_load_lds_dwordx4 v148, s[36:37]
	s_barrier
	s_waitcnt lgkmcnt(0)
	v_mfma_f32_16x16x32_bf16 v[60:63], v[154:157], v[170:173], v[60:63]
	v_mfma_f32_16x16x32_bf16 v[56:59], v[162:165], v[170:173], v[56:59]
	v_mfma_f32_16x16x32_bf16 v[52:55], v[154:157], v[178:181], v[52:55]
	v_mfma_f32_16x16x32_bf16 v[48:51], v[162:165], v[178:181], v[48:51]
	v_mfma_f32_16x16x32_bf16 v[36:39], v[154:157], v[196:199], v[36:39]
	v_mfma_f32_16x16x32_bf16 v[32:35], v[162:165], v[196:199], v[32:35]
	v_mfma_f32_16x16x32_bf16 v[20:23], v[154:157], v[204:207], v[20:23]
	v_mfma_f32_16x16x32_bf16 v[16:19], v[162:165], v[204:207], v[16:19]
	v_mfma_f32_16x16x32_bf16 v[60:63], v[158:161], v[174:177], v[60:63]
	v_mfma_f32_16x16x32_bf16 v[56:59], v[166:169], v[174:177], v[56:59]
	v_mfma_f32_16x16x32_bf16 v[52:55], v[158:161], v[192:195], v[52:55]
	v_mfma_f32_16x16x32_bf16 v[48:51], v[166:169], v[192:195], v[48:51]
	v_mfma_f32_16x16x32_bf16 v[36:39], v[158:161], v[200:203], v[36:39]
	v_mfma_f32_16x16x32_bf16 v[32:35], v[166:169], v[200:203], v[32:35]
	v_mfma_f32_16x16x32_bf16 v[20:23], v[158:161], v[208:211], v[20:23]
	v_mfma_f32_16x16x32_bf16 v[16:19], v[166:169], v[208:211], v[16:19]
	s_barrier
; #define PG8_STAGE(bufoff, gbase, voff) do { _Pragma("unroll") for (int _i = 0; _i < 2; ++_i) \
;         __builtin_amdgcn_global_load_lds((const unsigned*)((const char*)(gbase) + (voff)[_i]), (PG8_LAS unsigned*)(lds + (bufoff) + ldsw + _i * 8192), 16, 0, 0); } while (0)
; #define PG8_LDA(dst, b, h) do { _Pragma("unroll") for (int m = 0; m < 4; ++m) _Pragma("unroll") for (int k = 0; k < 2; ++k) dst[m][k] = *(const PG8_LAS bf16x8*)(lds + PG8_SA(b, h) + aoff + m * 2048 + k * 1024); } while (0)
; #define PG8_LDB(dst, b, h) do { _Pragma("unroll") for (int n = 0; n < 2; ++n) _Pragma("unroll") for (int k = 0; k < 2; ++k) dst[n][k] = *(const PG8_LAS bf16x8*)(lds + PG8_SB(b, h) + boff + n * 2048 + k * 1024); } while (0)
; #define PG8_MMA(ai, bj, At, Bt) do { __builtin_amdgcn_s_setprio(1); _Pragma("unroll") for (int m = 0; m < 4; ++m) _Pragma("unroll") for (int n = 0; n < 2; ++n) _Pragma("unroll") for (int k = 0; k < 2; ++k) \
;         acc[ai][bj][m][n] = __builtin_amdgcn_mfma_f32_16x16x32_bf16(Bt[n][k], At[m][k], acc[ai][bj][m][n], 0, 0, 0); __builtin_amdgcn_s_setprio(0); } while (0)
; #define PG8_WAIT_V(n) asm volatile("s_waitcnt vmcnt(" #n ")" ::: "memory")
; #define PG8_WAIT_L(n) asm volatile("s_waitcnt lgkmcnt(" #n ")" ::: "memory")
; #define PG8_BAR __builtin_amdgcn_s_barrier()
; #define PG8_SCHED __builtin_amdgcn_sched_barrier(0)
; template <class Epi, class Sched, bool STAMP = false>
; __device__ __forceinline__ void gemm_phase(PG8_LAS unsigned char* lds, const Gemm g, const Sched& S, const Epi& E, unsigned long long* stamps) {
;     ...
;             PG8_STAGE(PG8_SB(0, 1), b2 + hstep, voffB);
;             PG8_WAIT_V(6); PG8_BAR; PG8_MMA(1, 1, At, B1); PG8_BAR;
;             PG8_LDB(B0, 1, 0); PG8_SCHED; PG8_LDA(At, 1, 0); PG8_STAGE(PG8_SA(0, 1), a2 + hstep, voffA);
;             PG8_WAIT_L(8); PG8_BAR; PG8_WAIT_L(0); PG8_MMA(0, 0, At, B0); PG8_BAR; PG8_SCHED;
;             PG8_LDB(B1, 1, 1); PG8_STAGE(PG8_SB(1, 0), b3, voffB);
;             PG8_BAR; PG8_WAIT_L(0); PG8_MMA(0, 1, At, B1); PG8_BAR;
;             PG8_LDA(At, 1, 1); PG8_STAGE(PG8_SA(1, 0), a3, voffA);
	s_mov_b32 m0, s52
	s_nop 0
	global_load_lds_dwordx4 v128, s[30:31]
	s_mov_b32 m0, s29
	s_nop 0
	global_load_lds_dwordx4 v148, s[30:31]
	s_waitcnt vmcnt(6)
	s_barrier
	v_mfma_f32_16x16x32_bf16 v[44:47], v[212:215], v[170:173], v[44:47]
	v_mfma_f32_16x16x32_bf16 v[40:43], v[220:223], v[170:173], v[40:43]
	v_mfma_f32_16x16x32_bf16 v[28:31], v[212:215], v[178:181], v[28:31]
	v_mfma_f32_16x16x32_bf16 v[24:27], v[220:223], v[178:181], v[24:27]
	v_mfma_f32_16x16x32_bf16 v[12:15], v[212:215], v[196:199], v[12:15]
	v_mfma_f32_16x16x32_bf16 v[8:11], v[220:223], v[196:199], v[8:11]
	v_mfma_f32_16x16x32_bf16 v[4:7], v[212:215], v[204:207], v[4:7]
	v_mfma_f32_16x16x32_bf16 v[0:3], v[220:223], v[204:207], v[0:3]
	v_mfma_f32_16x16x32_bf16 v[44:47], v[216:219], v[174:177], v[44:47]
	v_mfma_f32_16x16x32_bf16 v[40:43], v[224:227], v[174:177], v[40:43]
	v_mfma_f32_16x16x32_bf16 v[28:31], v[216:219], v[192:195], v[28:31]
	v_mfma_f32_16x16x32_bf16 v[24:27], v[224:227], v[192:195], v[24:27]
	v_mfma_f32_16x16x32_bf16 v[12:15], v[216:219], v[200:203], v[12:15]
	v_mfma_f32_16x16x32_bf16 v[8:11], v[224:227], v[200:203], v[8:11]
	v_mfma_f32_16x16x32_bf16 v[4:7], v[216:219], v[208:211], v[4:7]
	v_mfma_f32_16x16x32_bf16 v[0:3], v[224:227], v[208:211], v[0:3]
	s_barrier
	ds_read_b128 v[154:157], v250
	ds_read_b128 v[158:161], v250 offset:1024
	ds_read_b128 v[162:165], v250 offset:2048
	ds_read_b128 v[166:169], v250 offset:3072
	s_mov_b32 m0, s48
	ds_read_b128 v[170:173], v152 offset:32768
	ds_read_b128 v[174:177], v152 offset:33792
	ds_read_b128 v[178:181], v152 offset:34816
	ds_read_b128 v[192:195], v152 offset:35840
	ds_read_b128 v[196:199], v152 offset:36864
	ds_read_b128 v[200:203], v152 offset:37888
	ds_read_b128 v[204:207], v152 offset:38912
	ds_read_b128 v[208:211], v152 offset:39936
	global_load_lds_dwordx4 v128, s[26:27]
	s_mov_b32 m0, s49
	s_nop 0
	global_load_lds_dwordx4 v148, s[26:27]
	s_waitcnt lgkmcnt(8)
	s_barrier
	s_waitcnt lgkmcnt(0)
	v_mfma_f32_16x16x32_bf16 v[124:127], v[154:157], v[170:173], v[124:127]
	v_mfma_f32_16x16x32_bf16 v[120:123], v[162:165], v[170:173], v[120:123]
	v_mfma_f32_16x16x32_bf16 v[116:119], v[154:157], v[178:181], v[116:119]
	v_mfma_f32_16x16x32_bf16 v[112:115], v[162:165], v[178:181], v[112:115]
	v_mfma_f32_16x16x32_bf16 v[104:107], v[154:157], v[196:199], v[104:107]
	v_mfma_f32_16x16x32_bf16 v[96:99], v[162:165], v[196:199], v[96:99]
	v_mfma_f32_16x16x32_bf16 v[88:91], v[154:157], v[204:207], v[88:91]
	v_mfma_f32_16x16x32_bf16 v[80:83], v[162:165], v[204:207], v[80:83]
	v_mfma_f32_16x16x32_bf16 v[124:127], v[158:161], v[174:177], v[124:127]
	v_mfma_f32_16x16x32_bf16 v[120:123], v[166:169], v[174:177], v[120:123]
	v_mfma_f32_16x16x32_bf16 v[116:119], v[158:161], v[192:195], v[116:119]
	v_mfma_f32_16x16x32_bf16 v[112:115], v[166:169], v[192:195], v[112:115]
	v_mfma_f32_16x16x32_bf16 v[104:107], v[158:161], v[200:203], v[104:107]
	v_mfma_f32_16x16x32_bf16 v[96:99], v[166:169], v[200:203], v[96:99]
	v_mfma_f32_16x16x32_bf16 v[88:91], v[158:161], v[208:211], v[88:91]
	v_mfma_f32_16x16x32_bf16 v[80:83], v[166:169], v[208:211], v[80:83]
	s_barrier
	s_mov_b32 m0, s16
	v_lshl_add_u64 v[182:183], v[182:183], 0, s[18:19]
	ds_read_b128 v[212:215], v251
	ds_read_b128 v[216:219], v251 offset:1024
	ds_read_b128 v[220:223], v251 offset:2048
	ds_read_b128 v[224:227], v251 offset:3072
	global_load_lds_dwordx4 v244, s[38:39]
	v_lshl_add_u64 v[182:183], v[228:229], 0, s[18:19]
	s_mov_b32 m0, s14
	s_nop 0
	global_load_lds_dwordx4 v245, s[38:39]
	s_barrier
	s_waitcnt lgkmcnt(0)
	v_mfma_f32_16x16x32_bf16 v[108:111], v[212:215], v[170:173], v[108:111]
	v_mfma_f32_16x16x32_bf16 v[100:103], v[220:223], v[170:173], v[100:103]
	v_mfma_f32_16x16x32_bf16 v[92:95], v[212:215], v[178:181], v[92:95]
	v_mfma_f32_16x16x32_bf16 v[84:87], v[220:223], v[178:181], v[84:87]
	v_mfma_f32_16x16x32_bf16 v[76:79], v[212:215], v[196:199], v[76:79]
	v_mfma_f32_16x16x32_bf16 v[72:75], v[220:223], v[196:199], v[72:75]
	v_mfma_f32_16x16x32_bf16 v[68:71], v[212:215], v[204:207], v[68:71]
	v_mfma_f32_16x16x32_bf16 v[64:67], v[220:223], v[204:207], v[64:67]
	v_mfma_f32_16x16x32_bf16 v[108:111], v[216:219], v[174:177], v[108:111]
	v_mfma_f32_16x16x32_bf16 v[100:103], v[224:227], v[174:177], v[100:103]
	v_mfma_f32_16x16x32_bf16 v[92:95], v[216:219], v[192:195], v[92:95]
	v_mfma_f32_16x16x32_bf16 v[84:87], v[224:227], v[192:195], v[84:87]
	v_mfma_f32_16x16x32_bf16 v[76:79], v[216:219], v[200:203], v[76:79]
	v_mfma_f32_16x16x32_bf16 v[72:75], v[224:227], v[200:203], v[72:75]
	v_mfma_f32_16x16x32_bf16 v[68:71], v[216:219], v[208:211], v[68:71]
	v_mfma_f32_16x16x32_bf16 v[64:67], v[224:227], v[208:211], v[64:67]
	s_mov_b32 m0, s57
	v_lshl_add_u64 v[182:183], v[230:231], 0, s[18:19]
	s_barrier
	ds_read_b128 v[170:173], v152 offset:49152
	ds_read_b128 v[174:177], v152 offset:50176
	ds_read_b128 v[178:181], v152 offset:51200
	ds_read_b128 v[192:195], v152 offset:52224
	ds_read_b128 v[196:199], v152 offset:53248
	ds_read_b128 v[200:203], v152 offset:54272
	ds_read_b128 v[204:207], v152 offset:55296
	ds_read_b128 v[208:211], v152 offset:56320
	global_load_lds_dwordx4 v244, s[36:37]
	v_lshl_add_u64 v[182:183], v[232:233], 0, s[18:19]
	s_mov_b32 m0, s58
	s_nop 0
	global_load_lds_dwordx4 v245, s[36:37]
	s_barrier
; #define PG8_STAGE(bufoff, gbase, voff) do { _Pragma("unroll") for (int _i = 0; _i < 2; ++_i) \
;         __builtin_amdgcn_global_load_lds((const unsigned*)((const char*)(gbase) + (voff)[_i]), (PG8_LAS unsigned*)(lds + (bufoff) + ldsw + _i * 8192), 16, 0, 0); } while (0)
; #define PG8_MMA(ai, bj, At, Bt) do { __builtin_amdgcn_s_setprio(1); _Pragma("unroll") for (int m = 0; m < 4; ++m) _Pragma("unroll") for (int n = 0; n < 2; ++n) _Pragma("unroll") for (int k = 0; k < 2; ++k) \
;         acc[ai][bj][m][n] = __builtin_amdgcn_mfma_f32_16x16x32_bf16(Bt[n][k], At[m][k], acc[ai][bj][m][n], 0, 0, 0); __builtin_amdgcn_s_setprio(0); } while (0)
; #define PG8_WAIT_V(n) asm volatile("s_waitcnt vmcnt(" #n ")" ::: "memory")
; #define PG8_WAIT_L(n) asm volatile("s_waitcnt lgkmcnt(" #n ")" ::: "memory")
; #define PG8_BAR __builtin_amdgcn_s_barrier()
; #define PG8_SCHED __builtin_amdgcn_sched_barrier(0)
; template <class Epi, class Sched, bool STAMP = false>
; __device__ __forceinline__ void gemm_phase(PG8_LAS unsigned char* lds, const Gemm g, const Sched& S, const Epi& E, unsigned long long* stamps) {
;     ...
;             PG8_BAR; PG8_WAIT_L(0); PG8_MMA(1, 0, At, B0); PG8_BAR; PG8_SCHED;
;             PG8_STAGE(PG8_SB(1, 1), b3 + hstep, voffB);
;             PG8_WAIT_V(6); PG8_BAR; PG8_MMA(1, 1, At, B1); PG8_BAR;
;     __device__ __forceinline__ void operator()(const f32x4 (&acc)[2][2][4][2], const pg8::Unit& u, int wr, int wc, int fr, int fq) const {
;         const int row0 = (u.pm - 64) * 256 + wr * 64 + fr, col0 = u.pn * 256 + wc * 32 + 4 * fq;
; #pragma unroll
;         for (int ai = 0; ai < 2; ++ai)
; #pragma unroll
;             for (int m = 0; m < 4; ++m) { float* xp = PART + (size_t)(row0 + ai * 128 + m * 16) * ldp + col0;
; #pragma unroll
;                 for (int bj = 0; bj < 2; ++bj)
; #pragma unroll
;                     for (int n = 0; n < 2; ++n) *(f32x4*)(xp + bj * 128 + n * 16) = acc[ai][bj][m][n]; }
	s_waitcnt lgkmcnt(0)
	v_mfma_f32_16x16x32_bf16 v[60:63], v[154:157], v[170:173], v[60:63]
	v_mfma_f32_16x16x32_bf16 v[56:59], v[162:165], v[170:173], v[56:59]
	v_mfma_f32_16x16x32_bf16 v[52:55], v[154:157], v[178:181], v[52:55]
	v_mfma_f32_16x16x32_bf16 v[48:51], v[162:165], v[178:181], v[48:51]
	v_mfma_f32_16x16x32_bf16 v[36:39], v[154:157], v[196:199], v[36:39]
	v_mfma_f32_16x16x32_bf16 v[32:35], v[162:165], v[196:199], v[32:35]
	v_mfma_f32_16x16x32_bf16 v[20:23], v[154:157], v[204:207], v[20:23]
	v_mfma_f32_16x16x32_bf16 v[16:19], v[162:165], v[204:207], v[16:19]
	v_mfma_f32_16x16x32_bf16 v[60:63], v[158:161], v[174:177], v[60:63]
	v_mfma_f32_16x16x32_bf16 v[56:59], v[166:169], v[174:177], v[56:59]
	v_mfma_f32_16x16x32_bf16 v[52:55], v[158:161], v[192:195], v[52:55]
	v_mfma_f32_16x16x32_bf16 v[48:51], v[166:169], v[192:195], v[48:51]
	v_mfma_f32_16x16x32_bf16 v[36:39], v[158:161], v[200:203], v[36:39]
	v_mfma_f32_16x16x32_bf16 v[32:35], v[166:169], v[200:203], v[32:35]
	v_mfma_f32_16x16x32_bf16 v[20:23], v[158:161], v[208:211], v[20:23]
	v_mfma_f32_16x16x32_bf16 v[16:19], v[166:169], v[208:211], v[16:19]
	s_barrier
	s_mov_b32 m0, s60
	s_nop 0
	global_load_lds_dwordx4 v128, s[24:25]
	s_mov_b32 m0, s59
	s_nop 0
	global_load_lds_dwordx4 v148, s[24:25]
	s_waitcnt vmcnt(6)
	s_barrier
	v_mfma_f32_16x16x32_bf16 v[44:47], v[212:215], v[170:173], v[44:47]
	v_mfma_f32_16x16x32_bf16 v[40:43], v[220:223], v[170:173], v[40:43]
	v_mfma_f32_16x16x32_bf16 v[28:31], v[212:215], v[178:181], v[28:31]
	v_mfma_f32_16x16x32_bf16 v[24:27], v[220:223], v[178:181], v[24:27]
	v_mfma_f32_16x16x32_bf16 v[12:15], v[212:215], v[196:199], v[12:15]
	v_mfma_f32_16x16x32_bf16 v[8:11], v[220:223], v[196:199], v[8:11]
	v_mfma_f32_16x16x32_bf16 v[4:7], v[212:215], v[204:207], v[4:7]
	v_mfma_f32_16x16x32_bf16 v[0:3], v[220:223], v[204:207], v[0:3]
	v_mfma_f32_16x16x32_bf16 v[44:47], v[216:219], v[174:177], v[44:47]
	v_mfma_f32_16x16x32_bf16 v[40:43], v[224:227], v[174:177], v[40:43]
	v_mfma_f32_16x16x32_bf16 v[28:31], v[216:219], v[192:195], v[28:31]
	v_mfma_f32_16x16x32_bf16 v[24:27], v[224:227], v[192:195], v[24:27]
	v_mfma_f32_16x16x32_bf16 v[12:15], v[216:219], v[200:203], v[12:15]
	v_mfma_f32_16x16x32_bf16 v[8:11], v[224:227], v[200:203], v[8:11]
	v_mfma_f32_16x16x32_bf16 v[4:7], v[216:219], v[208:211], v[4:7]
	v_mfma_f32_16x16x32_bf16 v[0:3], v[224:227], v[208:211], v[0:3]
	s_andn2_b64 vcc, exec, s[22:23]
	s_mov_b64 s[24:25], -1
	s_mov_b64 s[22:23], 0
	s_movk_i32 s14, 0x100
	s_barrier
	s_cbranch_vccz .LBB0_1349
	s_lshl_b32 s6, s45, 23
	s_add_u32 s6, s4, s6
	s_addc_u32 s7, s5, 0
	s_lshl_b32 s10, s44, 8
	s_add_i32 s10, s10, s53
	v_add_u32_e32 v150, s10, v150
	v_add_u32_e32 v148, 0xffffc000, v150
	s_lshl_b32 s10, s43, 8
	v_lshl_or_b32 v128, v139, 2, s10
	v_ashrrev_i32_e32 v149, 31, v148
	v_or_b32_e32 v128, s56, v128
	v_lshlrev_b64 v[148:149], 13, v[148:149]
	v_lshl_add_u64 v[148:149], s[6:7], 0, v[148:149]
	v_lshlrev_b32_e32 v128, 2, v128
	v_lshl_add_u64 v[148:149], v[148:149], 0, v[128:129]
	global_store_dwordx4 v[148:149], v[124:127], off
	global_store_dwordx4 v[148:149], v[120:123], off offset:64
	global_store_dwordx4 v[148:149], v[108:111], off offset:512
	global_store_dwordx4 v[148:149], v[100:103], off offset:576
	s_cmpk_lt_u32 s42, 0x100
	s_movk_i32 s58, 0xff60
	v_add_u32_e32 v100, 0xffffc010, v150
	v_ashrrev_i32_e32 v101, 31, v100
	v_lshlrev_b64 v[100:101], 13, v[100:101]
	v_lshl_add_u64 v[100:101], s[6:7], 0, v[100:101]
	v_lshl_add_u64 v[100:101], v[100:101], 0, v[128:129]
	global_store_dwordx4 v[100:101], v[116:119], off
	global_store_dwordx4 v[100:101], v[112:115], off offset:64
	global_store_dwordx4 v[100:101], v[92:95], off offset:512
	global_store_dwordx4 v[100:101], v[84:87], off offset:576
	s_nop 1
	v_add_u32_e32 v84, 0xffffc020, v150
	v_ashrrev_i32_e32 v85, 31, v84
	v_lshlrev_b64 v[84:85], 13, v[84:85]
	v_lshl_add_u64 v[84:85], s[6:7], 0, v[84:85]
	v_lshl_add_u64 v[84:85], v[84:85], 0, v[128:129]
	global_store_dwordx4 v[84:85], v[104:107], off
	global_store_dwordx4 v[84:85], v[96:99], off offset:64
	global_store_dwordx4 v[84:85], v[76:79], off offset:512
	global_store_dwordx4 v[84:85], v[72:75], off offset:576
	s_nop 1
	v_add_u32_e32 v72, 0xffffc030, v150
	v_ashrrev_i32_e32 v73, 31, v72
	v_lshlrev_b64 v[72:73], 13, v[72:73]
	v_lshl_add_u64 v[72:73], s[6:7], 0, v[72:73]
	v_lshl_add_u64 v[72:73], v[72:73], 0, v[128:129]
	s_mov_b64 s[6:7], 0x100000
	global_store_dwordx4 v[72:73], v[88:91], off
	global_store_dwordx4 v[72:73], v[80:83], off offset:64
	global_store_dwordx4 v[72:73], v[68:71], off offset:512
	global_store_dwordx4 v[72:73], v[64:67], off offset:576
	s_nop 1
	v_lshl_add_u64 v[64:65], v[148:149], 0, s[6:7]
	s_mov_b32 s6, 0x100000
	v_add_co_u32_e32 v66, vcc, s6, v148
	s_mov_b64 s[6:7], 0x120000
	s_nop 0
	v_addc_co_u32_e32 v67, vcc, 0, v149, vcc
	global_store_dwordx4 v[66:67], v[60:63], off
	global_store_dwordx4 v[64:65], v[56:59], off offset:64
	global_store_dwordx4 v[64:65], v[44:47], off offset:512
	global_store_dwordx4 v[64:65], v[40:43], off offset:576
	s_nop 1
	v_lshl_add_u64 v[40:41], v[148:149], 0, s[6:7]
	s_mov_b32 s6, 0x120000
	v_add_co_u32_e32 v42, vcc, s6, v148
	s_mov_b64 s[6:7], 0x140000
	s_nop 0
	v_addc_co_u32_e32 v43, vcc, 0, v149, vcc
	global_store_dwordx4 v[42:43], v[52:55], off
	global_store_dwordx4 v[40:41], v[48:51], off offset:64
	global_store_dwordx4 v[40:41], v[28:31], off offset:512
	global_store_dwordx4 v[40:41], v[24:27], off offset:576
	s_nop 1
	v_lshl_add_u64 v[24:25], v[148:149], 0, s[6:7]
	s_mov_b32 s6, 0x140000
	v_add_co_u32_e32 v26, vcc, s6, v148
	s_mov_b64 s[6:7], 0x160000
	s_nop 0
	v_addc_co_u32_e32 v27, vcc, 0, v149, vcc
	global_store_dwordx4 v[26:27], v[36:39], off
	global_store_dwordx4 v[24:25], v[32:35], off offset:64
	global_store_dwordx4 v[24:25], v[12:15], off offset:512
	global_store_dwordx4 v[24:25], v[8:11], off offset:576
	s_nop 1
	v_add_co_u32_e32 v10, vcc, 0x160000, v148
	v_lshl_add_u64 v[8:9], v[148:149], 0, s[6:7]
	s_nop 0
	v_addc_co_u32_e32 v11, vcc, 0, v149, vcc
	global_store_dwordx4 v[10:11], v[20:23], off
	global_store_dwordx4 v[8:9], v[16:19], off offset:64
	global_store_dwordx4 v[8:9], v[4:7], off offset:512
	global_store_dwordx4 v[8:9], v[0:3], off offset:576
	s_waitcnt vmcnt(0)
	s_cbranch_scc0 .LBB0_1352
	s_barrier
